# hyena epilogues of both orders: all two-byte loads issued before any arithmetic/stores into registers dead after the inverse FFT; order-0 epilogue rewritten (was four dependent load groups)
# speedup vs baseline: 1.1580x; 1.0005x over previous
.LBB0_538:
	s_lshl_b32 s98, s16, 16
	s_mov_b32 s99, 0
	v_lshl_add_u64 v[196:197], s[98:99], 0, v[28:29]
	global_load_dwordx4 v[164:167], v[196:197], off offset:-4096
	global_load_dwordx4 v[168:171], v[196:197], off offset:-3072
	global_load_dwordx4 v[172:175], v[196:197], off offset:-2048
	global_load_dwordx4 v[176:179], v[196:197], off offset:-1024
	global_load_dwordx4 v[180:183], v[196:197], off
	global_load_dwordx4 v[184:187], v[196:197], off offset:1024
	global_load_dwordx4 v[188:191], v[196:197], off offset:2048
	global_load_dwordx4 v[192:195], v[196:197], off offset:3072
	v_mov_b32_e32 v20, v46
	v_mov_b32_e32 v21, v48
	v_mov_b32_e32 v22, v51
	v_mov_b32_e32 v23, v53
	v_pk_add_f32 v[88:89], v[20:21], 0 op_sel_hi:[1,0]
	v_pk_mul_f32 v[20:21], v[20:21], s[58:59] op_sel_hi:[1,0]
	v_xor_b32_e32 v91, 0x80000000, v46
	v_mov_b32_e32 v90, v48
	v_pk_add_f32 v[92:93], v[50:51], 0 neg_lo:[1,1] neg_hi:[1,1]
	v_mov_b32_e32 v24, v50
	v_mov_b32_e32 v25, v52
	v_pk_fma_f32 v[20:21], v[90:91], s[46:47], v[20:21] op_sel_hi:[1,0,1] neg_lo:[0,0,1] neg_hi:[0,0,1]
	v_pk_add_f32 v[90:91], v[22:23], 0 op_sel_hi:[1,0]
	v_pk_mul_f32 v[22:23], v[22:23], s[62:63] op_sel_hi:[1,0]
	v_mov_b32_e32 v92, v53
	v_mov_b32_e32 v26, v55
	v_mov_b32_e32 v27, v57
	v_pk_fma_f32 v[22:23], v[92:93], s[60:61], v[22:23] op_sel_hi:[1,0,1] neg_lo:[0,0,1] neg_hi:[0,0,1]
	v_pk_add_f32 v[92:93], v[24:25], 0 op_sel_hi:[1,0]
	v_pk_mul_f32 v[24:25], v[24:25], s[66:67] op_sel_hi:[1,0]
	v_xor_b32_e32 v95, 0x80000000, v50
	v_mov_b32_e32 v94, v52
	v_pk_add_f32 v[96:97], v[54:55], 0 neg_lo:[1,1] neg_hi:[1,1]
	v_mov_b32_e32 v64, v54
	v_mov_b32_e32 v65, v56
	v_pk_fma_f32 v[24:25], v[94:95], s[64:65], v[24:25] op_sel_hi:[1,0,1] neg_lo:[0,0,1] neg_hi:[0,0,1]
	v_pk_add_f32 v[94:95], v[26:27], 0 op_sel_hi:[1,0]
	v_pk_mul_f32 v[26:27], v[26:27], s[70:71] op_sel_hi:[1,0]
	v_mov_b32_e32 v96, v57
	v_mov_b32_e32 v66, v59
	v_mov_b32_e32 v67, v61
	v_pk_fma_f32 v[26:27], v[96:97], s[70:71], v[26:27] op_sel_hi:[1,0,1] neg_lo:[0,0,1] neg_hi:[0,0,1]
	v_pk_add_f32 v[96:97], v[64:65], 0 op_sel_hi:[1,0]
	v_pk_mul_f32 v[64:65], v[64:65], s[64:65] op_sel_hi:[1,0]
	v_xor_b32_e32 v99, 0x80000000, v54
	v_mov_b32_e32 v98, v56
	v_pk_add_f32 v[100:101], v[58:59], 0 neg_lo:[1,1] neg_hi:[1,1]
	v_mov_b32_e32 v2, v32
	v_mov_b32_e32 v3, v34
	v_mov_b32_e32 v4, v33
	v_mov_b32_e32 v5, v35
	v_mov_b32_e32 v18, v47
	v_mov_b32_e32 v19, v49
	v_mov_b32_e32 v68, v58
	v_mov_b32_e32 v69, v60
	v_pk_fma_f32 v[64:65], v[98:99], s[66:67], v[64:65] op_sel_hi:[1,0,1] neg_lo:[0,0,1] neg_hi:[0,0,1]
	v_pk_add_f32 v[98:99], v[66:67], 0 op_sel_hi:[1,0]
	v_pk_mul_f32 v[66:67], v[66:67], s[60:61] op_sel_hi:[1,0]
	v_mov_b32_e32 v100, v61
	v_pk_add_f32 v[70:71], v[2:3], 0 op_sel_hi:[1,0]
	v_pk_add_f32 v[72:73], v[4:5], 0 op_sel_hi:[1,0]
	v_pk_add_f32 v[74:75], v[32:33], 0 neg_lo:[1,1] neg_hi:[1,1]
	v_pk_add_f32 v[18:19], v[18:19], 0 op_sel_hi:[1,0]
	v_pk_fma_f32 v[66:67], v[100:101], s[62:63], v[66:67] op_sel_hi:[1,0,1] neg_lo:[0,0,1] neg_hi:[0,0,1]
	v_pk_add_f32 v[100:101], v[68:69], 0 op_sel_hi:[1,0]
	v_pk_mul_f32 v[68:69], v[68:69], s[46:47] op_sel_hi:[1,0]
	v_xor_b32_e32 v103, 0x80000000, v58
	v_mov_b32_e32 v102, v60
	v_mov_b32_e32 v74, v35
	v_pk_fma_f32 v[68:69], v[102:103], s[58:59], v[68:69] op_sel_hi:[1,0,1] neg_lo:[0,0,1] neg_hi:[0,0,1]
	v_pk_add_f32 v[102:103], v[18:19], v[70:71]
	v_pk_add_f32 v[18:19], v[70:71], v[18:19] neg_lo:[0,1] neg_hi:[0,1]
	v_pk_add_f32 v[70:71], v[88:89], v[72:73]
	v_pk_add_f32 v[72:73], v[72:73], v[88:89] neg_lo:[0,1] neg_hi:[0,1]
	v_mov_b32_e32 v6, v37
	v_mov_b32_e32 v7, v31
	v_pk_mul_f32 v[74:75], v[74:75], s[58:59] op_sel_hi:[1,0]
	s_nop 0
	v_pk_fma_f32 v[4:5], v[4:5], s[46:47], v[74:75] op_sel_hi:[1,0,1]
	v_pk_add_f32 v[74:75], v[6:7], 0 op_sel_hi:[1,0]
	v_pk_add_f32 v[76:77], v[36:37], 0 neg_lo:[1,1] neg_hi:[1,1]
	v_pk_mul_f32 v[88:89], v[72:73], s[62:63] op_sel:[1,0] op_sel_hi:[0,0] neg_hi:[1,0]
	v_mov_b32_e32 v76, v31
	v_pk_fma_f32 v[72:73], v[72:73], s[60:61], v[88:89] op_sel_hi:[1,0,1]
	v_pk_add_f32 v[88:89], v[90:91], v[74:75]
	v_pk_add_f32 v[74:75], v[74:75], v[90:91] neg_lo:[0,1] neg_hi:[0,1]
	v_mov_b32_e32 v8, v36
	v_mov_b32_e32 v9, v30
	v_pk_mul_f32 v[76:77], v[76:77], s[62:63] op_sel_hi:[1,0]
	s_nop 0
	v_pk_fma_f32 v[6:7], v[6:7], s[60:61], v[76:77] op_sel_hi:[1,0,1]
	v_pk_add_f32 v[76:77], v[8:9], 0 op_sel_hi:[1,0]
	v_pk_mul_f32 v[90:91], v[74:75], s[70:71] op_sel:[1,0] op_sel_hi:[0,0] neg_hi:[1,0]
	v_xor_b32_e32 v79, 0x80000000, v36
	v_mov_b32_e32 v78, v30
	v_pk_add_f32 v[80:81], v[38:39], 0 neg_lo:[1,1] neg_hi:[1,1]
	v_pk_fma_f32 v[74:75], v[74:75], s[70:71], v[90:91] op_sel_hi:[1,0,1]
	v_pk_add_f32 v[90:91], v[92:93], v[76:77]
	v_pk_add_f32 v[76:77], v[76:77], v[92:93] neg_lo:[0,1] neg_hi:[0,1]
	v_mov_b32_e32 v10, v39
	v_mov_b32_e32 v11, v41
	v_pk_mul_f32 v[78:79], v[78:79], s[66:67] op_sel_hi:[1,0]
	v_mov_b32_e32 v80, v41
	v_mov_b32_e32 v12, v38
	v_mov_b32_e32 v13, v40
	v_pk_fma_f32 v[8:9], v[8:9], s[64:65], v[78:79] op_sel_hi:[1,0,1]
	v_pk_add_f32 v[78:79], v[10:11], 0 op_sel_hi:[1,0]
	v_pk_mul_f32 v[80:81], v[80:81], s[70:71] op_sel_hi:[1,0]
	v_pk_mul_f32 v[92:93], v[76:77], s[60:61] op_sel:[1,0] op_sel_hi:[0,0] neg_hi:[1,0]
	v_pk_fma_f32 v[10:11], v[10:11], s[70:71], v[80:81] op_sel_hi:[1,0,1]
	v_pk_add_f32 v[80:81], v[12:13], 0 op_sel_hi:[1,0]
	v_xor_b32_e32 v83, 0x80000000, v38
	v_mov_b32_e32 v82, v40
	v_pk_fma_f32 v[76:77], v[76:77], s[62:63], v[92:93] op_sel_hi:[1,0,1]
	v_pk_add_f32 v[92:93], v[94:95], v[78:79]
	v_pk_add_f32 v[78:79], v[78:79], v[94:95] neg_lo:[0,1] neg_hi:[0,1]
	v_mov_b32_e32 v14, v43
	v_mov_b32_e32 v15, v45
	v_pk_mul_f32 v[82:83], v[82:83], s[64:65] op_sel_hi:[1,0]
	v_pk_add_f32 v[84:85], v[42:43], 0 neg_lo:[1,1] neg_hi:[1,1]
	v_xor_b32_e32 v95, 0x80000000, v78
	v_mov_b32_e32 v94, v79
	v_pk_add_f32 v[78:79], v[96:97], v[80:81]
	v_pk_add_f32 v[80:81], v[80:81], v[96:97] neg_lo:[0,1] neg_hi:[0,1]
	v_pk_fma_f32 v[12:13], v[12:13], s[66:67], v[82:83] op_sel_hi:[1,0,1]
	v_pk_add_f32 v[82:83], v[14:15], 0 op_sel_hi:[1,0]
	v_mov_b32_e32 v84, v45
	v_pk_mul_f32 v[96:97], v[80:81], s[62:63] op_sel_hi:[1,0]
	v_xor_b32_e32 v105, 0x80000000, v80
	v_mov_b32_e32 v104, v81
	v_mov_b32_e32 v16, v42
	v_mov_b32_e32 v17, v44
	v_pk_mul_f32 v[84:85], v[84:85], s[60:61] op_sel_hi:[1,0]
	v_xor_b32_e32 v87, 0x80000000, v42
	v_mov_b32_e32 v86, v44
	v_pk_fma_f32 v[80:81], v[104:105], s[60:61], v[96:97] op_sel_hi:[1,0,1] neg_lo:[0,0,1] neg_hi:[0,0,1]
	v_pk_add_f32 v[96:97], v[98:99], v[82:83]
	v_pk_add_f32 v[82:83], v[82:83], v[98:99] neg_lo:[0,1] neg_hi:[0,1]
	v_pk_fma_f32 v[14:15], v[14:15], s[62:63], v[84:85] op_sel_hi:[1,0,1]
	v_pk_add_f32 v[84:85], v[16:17], 0 op_sel_hi:[1,0]
	v_pk_mul_f32 v[86:87], v[86:87], s[46:47] op_sel_hi:[1,0]
	v_pk_mul_f32 v[98:99], v[82:83], s[70:71] op_sel_hi:[1,0]
	v_xor_b32_e32 v105, 0x80000000, v82
	v_mov_b32_e32 v104, v83
	v_pk_fma_f32 v[16:17], v[16:17], s[58:59], v[86:87] op_sel_hi:[1,0,1]
	v_pk_add_f32 v[86:87], v[46:47], 0 neg_lo:[1,1] neg_hi:[1,1]
	v_pk_fma_f32 v[82:83], v[104:105], s[70:71], v[98:99] op_sel_hi:[1,0,1] neg_lo:[0,0,1] neg_hi:[0,0,1]
	v_pk_add_f32 v[98:99], v[100:101], v[84:85]
	v_pk_add_f32 v[84:85], v[84:85], v[100:101] neg_lo:[0,1] neg_hi:[0,1]
	v_mov_b32_e32 v86, v49
	v_pk_mul_f32 v[100:101], v[84:85], s[60:61] op_sel_hi:[1,0]
	v_xor_b32_e32 v105, 0x80000000, v84
	v_mov_b32_e32 v104, v85
	v_pk_fma_f32 v[84:85], v[104:105], s[62:63], v[100:101] op_sel_hi:[1,0,1] neg_lo:[0,0,1] neg_hi:[0,0,1]
	v_pk_add_f32 v[100:101], v[86:87], v[2:3]
	v_pk_add_f32 v[2:3], v[2:3], v[86:87] neg_lo:[0,1] neg_hi:[0,1]
	v_pk_add_f32 v[86:87], v[20:21], v[4:5]
	v_pk_add_f32 v[4:5], v[4:5], v[20:21] neg_lo:[0,1] neg_hi:[0,1]
	v_mov_b32_e32 v63, v146
	v_pk_mul_f32 v[20:21], v[4:5], s[62:63] op_sel:[1,0] op_sel_hi:[0,0] neg_hi:[1,0]
	s_nop 0
	v_pk_fma_f32 v[4:5], v[4:5], s[60:61], v[20:21] op_sel_hi:[1,0,1]
	v_pk_add_f32 v[20:21], v[22:23], v[6:7]
	v_pk_add_f32 v[6:7], v[6:7], v[22:23] neg_lo:[0,1] neg_hi:[0,1]
	s_barrier
	v_pk_mul_f32 v[22:23], v[6:7], s[70:71] op_sel:[1,0] op_sel_hi:[0,0] neg_hi:[1,0]
	s_nop 0
	v_pk_fma_f32 v[6:7], v[6:7], s[70:71], v[22:23] op_sel_hi:[1,0,1]
	v_pk_add_f32 v[22:23], v[24:25], v[8:9]
	v_pk_add_f32 v[8:9], v[8:9], v[24:25] neg_lo:[0,1] neg_hi:[0,1]
	s_add_i32 s19, 16, 0x11000
	v_pk_mul_f32 v[24:25], v[8:9], s[60:61] op_sel:[1,0] op_sel_hi:[0,0] neg_hi:[1,0]
	s_add_i32 s18, 16, 0x12000
	v_pk_fma_f32 v[8:9], v[8:9], s[62:63], v[24:25] op_sel_hi:[1,0,1]
	v_pk_add_f32 v[24:25], v[26:27], v[10:11]
	v_pk_add_f32 v[10:11], v[10:11], v[26:27] neg_lo:[0,1] neg_hi:[0,1]
	s_add_i32 s17, 16, 0x13000
	v_xor_b32_e32 v27, 0x80000000, v10
	v_mov_b32_e32 v26, v11
	v_pk_add_f32 v[10:11], v[64:65], v[12:13]
	v_pk_add_f32 v[12:13], v[12:13], v[64:65] neg_lo:[0,1] neg_hi:[0,1]
	s_add_i32 s13, 16, 0x14000
	v_pk_mul_f32 v[64:65], v[12:13], s[62:63] op_sel_hi:[1,0]
	v_xor_b32_e32 v105, 0x80000000, v12
	v_mov_b32_e32 v104, v13
	v_pk_fma_f32 v[12:13], v[104:105], s[60:61], v[64:65] op_sel_hi:[1,0,1] neg_lo:[0,0,1] neg_hi:[0,0,1]
	v_pk_add_f32 v[64:65], v[66:67], v[14:15]
	v_pk_add_f32 v[14:15], v[14:15], v[66:67] neg_lo:[0,1] neg_hi:[0,1]
	s_add_i32 s12, 16, 0x15000
	v_pk_mul_f32 v[66:67], v[14:15], s[70:71] op_sel_hi:[1,0]
	v_xor_b32_e32 v105, 0x80000000, v14
	v_mov_b32_e32 v104, v15
	v_pk_fma_f32 v[14:15], v[104:105], s[70:71], v[66:67] op_sel_hi:[1,0,1] neg_lo:[0,0,1] neg_hi:[0,0,1]
	v_pk_add_f32 v[66:67], v[68:69], v[16:17]
	v_pk_add_f32 v[16:17], v[16:17], v[68:69] neg_lo:[0,1] neg_hi:[0,1]
	s_add_i32 s11, 16, 0x16000
	v_pk_mul_f32 v[68:69], v[16:17], s[60:61] op_sel_hi:[1,0]
	v_xor_b32_e32 v105, 0x80000000, v16
	v_mov_b32_e32 v104, v17
	v_pk_fma_f32 v[16:17], v[104:105], s[62:63], v[68:69] op_sel_hi:[1,0,1] neg_lo:[0,0,1] neg_hi:[0,0,1]
	v_pk_add_f32 v[68:69], v[92:93], v[102:103]
	v_pk_add_f32 v[92:93], v[102:103], v[92:93] neg_lo:[0,1] neg_hi:[0,1]
	v_pk_add_f32 v[102:103], v[78:79], v[70:71]
	v_pk_add_f32 v[70:71], v[70:71], v[78:79] neg_lo:[0,1] neg_hi:[0,1]
	s_add_i32 s10, 16, 0x17000
	v_pk_mul_f32 v[78:79], v[70:71], s[70:71] op_sel:[1,0] op_sel_hi:[0,0] neg_hi:[1,0]
	s_add_i32 s9, 16, 0x18000
	v_pk_fma_f32 v[70:71], v[70:71], s[70:71], v[78:79] op_sel_hi:[1,0,1]
	v_pk_add_f32 v[78:79], v[96:97], v[88:89]
	v_pk_add_f32 v[88:89], v[88:89], v[96:97] neg_lo:[0,1] neg_hi:[0,1]
	s_add_i32 s8, 16, 0x19000
	v_xor_b32_e32 v97, 0x80000000, v88
	v_mov_b32_e32 v96, v89
	v_pk_add_f32 v[88:89], v[98:99], v[90:91]
	v_pk_add_f32 v[90:91], v[90:91], v[98:99] neg_lo:[0,1] neg_hi:[0,1]
	s_add_i32 s7, 16, 0x1a000
	v_pk_mul_f32 v[98:99], v[90:91], s[70:71] op_sel_hi:[1,0]
	v_xor_b32_e32 v105, 0x80000000, v90
	v_mov_b32_e32 v104, v91
	v_pk_fma_f32 v[90:91], v[104:105], s[70:71], v[98:99] op_sel_hi:[1,0,1] neg_lo:[0,0,1] neg_hi:[0,0,1]
	v_pk_add_f32 v[98:99], v[94:95], v[18:19]
	v_pk_add_f32 v[18:19], v[18:19], v[94:95] neg_lo:[0,1] neg_hi:[0,1]
	v_pk_add_f32 v[94:95], v[80:81], v[72:73]
	v_pk_add_f32 v[72:73], v[72:73], v[80:81] neg_lo:[0,1] neg_hi:[0,1]
	s_add_i32 s6, 16, 0x1b000
	v_pk_mul_f32 v[80:81], v[72:73], s[70:71] op_sel:[1,0] op_sel_hi:[0,0] neg_hi:[1,0]
	s_add_i32 s5, 16, 0x1c000
	v_pk_fma_f32 v[72:73], v[72:73], s[70:71], v[80:81] op_sel_hi:[1,0,1]
	v_pk_add_f32 v[80:81], v[82:83], v[74:75]
	v_pk_add_f32 v[74:75], v[74:75], v[82:83] neg_lo:[0,1] neg_hi:[0,1]
	s_add_i32 s4, 16, 0x1d000
	v_xor_b32_e32 v83, 0x80000000, v74
	v_mov_b32_e32 v82, v75
	v_pk_add_f32 v[74:75], v[84:85], v[76:77]
	v_pk_add_f32 v[76:77], v[76:77], v[84:85] neg_lo:[0,1] neg_hi:[0,1]
	v_pk_add_f32 v[106:107], v[18:19], v[82:83]
	v_pk_mul_f32 v[84:85], v[76:77], s[70:71] op_sel_hi:[1,0]
	v_xor_b32_e32 v105, 0x80000000, v76
	v_mov_b32_e32 v104, v77
	v_pk_fma_f32 v[76:77], v[104:105], s[70:71], v[84:85] op_sel_hi:[1,0,1] neg_lo:[0,0,1] neg_hi:[0,0,1]
	v_pk_add_f32 v[84:85], v[24:25], v[100:101]
	v_pk_add_f32 v[24:25], v[100:101], v[24:25] neg_lo:[0,1] neg_hi:[0,1]
	v_pk_add_f32 v[100:101], v[10:11], v[86:87]
	v_pk_add_f32 v[10:11], v[86:87], v[10:11] neg_lo:[0,1] neg_hi:[0,1]
	v_pk_add_f32 v[18:19], v[18:19], v[82:83] neg_lo:[0,1] neg_hi:[0,1]
	v_pk_mul_f32 v[86:87], v[10:11], s[70:71] op_sel:[1,0] op_sel_hi:[0,0] neg_hi:[1,0]
	v_pk_add_f32 v[82:83], v[76:77], v[72:73]
	v_pk_fma_f32 v[10:11], v[10:11], s[70:71], v[86:87] op_sel_hi:[1,0,1]
	v_pk_add_f32 v[86:87], v[64:65], v[20:21]
	v_pk_add_f32 v[20:21], v[20:21], v[64:65] neg_lo:[0,1] neg_hi:[0,1]
	v_pk_add_f32 v[72:73], v[72:73], v[76:77] neg_lo:[0,1] neg_hi:[0,1]
	v_xor_b32_e32 v65, 0x80000000, v20
	v_mov_b32_e32 v64, v21
	v_pk_add_f32 v[20:21], v[66:67], v[22:23]
	v_pk_add_f32 v[22:23], v[22:23], v[66:67] neg_lo:[0,1] neg_hi:[0,1]
	v_xor_b32_e32 v77, 0x80000000, v72
	v_pk_mul_f32 v[66:67], v[22:23], s[70:71] op_sel_hi:[1,0]
	v_xor_b32_e32 v105, 0x80000000, v22
	v_mov_b32_e32 v104, v23
	v_pk_fma_f32 v[22:23], v[104:105], s[70:71], v[66:67] op_sel_hi:[1,0,1] neg_lo:[0,0,1] neg_hi:[0,0,1]
	v_pk_add_f32 v[66:67], v[2:3], v[26:27]
	v_pk_add_f32 v[2:3], v[2:3], v[26:27] neg_lo:[0,1] neg_hi:[0,1]
	v_pk_add_f32 v[26:27], v[12:13], v[4:5]
	v_pk_add_f32 v[4:5], v[4:5], v[12:13] neg_lo:[0,1] neg_hi:[0,1]
	v_mov_b32_e32 v76, v73
	v_pk_mul_f32 v[12:13], v[4:5], s[70:71] op_sel:[1,0] op_sel_hi:[0,0] neg_hi:[1,0]
	v_pk_add_f32 v[72:73], v[84:85], v[86:87]
	v_pk_fma_f32 v[4:5], v[4:5], s[70:71], v[12:13] op_sel_hi:[1,0,1]
	v_pk_add_f32 v[12:13], v[14:15], v[6:7]
	v_pk_add_f32 v[6:7], v[6:7], v[14:15] neg_lo:[0,1] neg_hi:[0,1]
	v_pk_add_f32 v[84:85], v[84:85], v[86:87] neg_lo:[0,1] neg_hi:[0,1]
	v_xor_b32_e32 v15, 0x80000000, v6
	v_mov_b32_e32 v14, v7
	v_pk_add_f32 v[6:7], v[16:17], v[8:9]
	v_pk_add_f32 v[8:9], v[8:9], v[16:17] neg_lo:[0,1] neg_hi:[0,1]
	v_pk_add_f32 v[86:87], v[20:21], v[100:101]
	v_pk_mul_f32 v[16:17], v[8:9], s[70:71] op_sel_hi:[1,0]
	s_nop 0
	v_pk_fma_f32 v[8:9], v[8:9], s[70:71], v[16:17] op_sel:[1,0,0] op_sel_hi:[0,0,1] neg_lo:[0,0,1] neg_hi:[1,0,1]
	v_pk_add_f32 v[104:105], v[92:93], v[96:97]
	v_pk_add_f32 v[92:93], v[92:93], v[96:97] neg_lo:[0,1] neg_hi:[0,1]
	v_pk_add_f32 v[96:97], v[90:91], v[70:71]
	v_pk_add_f32 v[70:71], v[70:71], v[90:91] neg_lo:[0,1] neg_hi:[0,1]
	v_pk_add_f32 v[16:17], v[78:79], v[68:69]
	v_pk_add_f32 v[68:69], v[68:69], v[78:79] neg_lo:[0,1] neg_hi:[0,1]
	v_pk_add_f32 v[78:79], v[88:89], v[102:103]
	v_pk_add_f32 v[88:89], v[102:103], v[88:89] neg_lo:[0,1] neg_hi:[0,1]
	v_xor_b32_e32 v91, 0x80000000, v70
	v_mov_b32_e32 v90, v71
	v_pk_add_f32 v[70:71], v[98:99], v[80:81]
	v_pk_add_f32 v[98:99], v[98:99], v[80:81] neg_lo:[0,1] neg_hi:[0,1]
	v_pk_add_f32 v[80:81], v[74:75], v[94:95]
	v_pk_add_f32 v[74:75], v[94:95], v[74:75] neg_lo:[0,1] neg_hi:[0,1]
	v_pk_add_f32 v[20:21], v[100:101], v[20:21] neg_lo:[0,1] neg_hi:[0,1]
	v_pk_add_f32 v[108:109], v[24:25], v[64:65]
	v_pk_add_f32 v[24:25], v[24:25], v[64:65] neg_lo:[0,1] neg_hi:[0,1]
	v_pk_add_f32 v[64:65], v[22:23], v[10:11]
	v_pk_add_f32 v[10:11], v[10:11], v[22:23] neg_lo:[0,1] neg_hi:[0,1]
	v_pk_add_f32 v[114:115], v[6:7], v[26:27]
	v_pk_add_f32 v[6:7], v[26:27], v[6:7] neg_lo:[0,1] neg_hi:[0,1]
	v_xor_b32_e32 v103, 0x80000000, v88
	v_mov_b32_e32 v102, v89
	v_xor_b32_e32 v95, 0x80000000, v74
	v_mov_b32_e32 v94, v75
	v_xor_b32_e32 v101, 0x80000000, v20
	v_mov_b32_e32 v100, v21
	v_xor_b32_e32 v27, 0x80000000, v6
	v_mov_b32_e32 v26, v7
	v_pk_add_f32 v[6:7], v[2:3], v[14:15]
	v_pk_add_f32 v[116:117], v[2:3], v[14:15] neg_lo:[0,1] neg_hi:[0,1]
	v_pk_add_f32 v[2:3], v[4:5], v[8:9] neg_lo:[0,1] neg_hi:[0,1]
	v_pk_add_f32 v[112:113], v[66:67], v[12:13]
	v_pk_add_f32 v[66:67], v[66:67], v[12:13] neg_lo:[0,1] neg_hi:[0,1]
	v_pk_add_f32 v[118:119], v[8:9], v[4:5]
	v_xor_b32_e32 v121, 0x80000000, v2
	v_mov_b32_e32 v120, v3
	v_pk_add_f32 v[2:3], v[78:79], v[16:17]
	v_pk_add_f32 v[88:89], v[16:17], v[78:79] neg_lo:[0,1] neg_hi:[0,1]
	v_pk_add_f32 v[122:123], v[68:69], v[102:103]
	v_pk_add_f32 v[20:21], v[68:69], v[102:103] neg_lo:[0,1] neg_hi:[0,1]
	v_pk_add_f32 v[78:79], v[104:105], v[96:97]
	v_pk_add_f32 v[74:75], v[104:105], v[96:97] neg_lo:[0,1] neg_hi:[0,1]
	v_pk_add_f32 v[96:97], v[92:93], v[90:91]
	v_pk_add_f32 v[8:9], v[92:93], v[90:91] neg_lo:[0,1] neg_hi:[0,1]
	v_pk_add_f32 v[102:103], v[98:99], v[94:95]
	v_pk_add_f32 v[12:13], v[98:99], v[94:95] neg_lo:[0,1] neg_hi:[0,1]
	v_pk_add_f32 v[98:99], v[18:19], v[76:77]
	v_pk_add_f32 v[4:5], v[18:19], v[76:77] neg_lo:[0,1] neg_hi:[0,1]
	v_pk_add_f32 v[18:19], v[72:73], v[86:87]
	v_pk_add_f32 v[92:93], v[72:73], v[86:87] neg_lo:[0,1] neg_hi:[0,1]
	v_pk_add_f32 v[86:87], v[84:85], v[100:101]
	v_pk_add_f32 v[22:23], v[84:85], v[100:101] neg_lo:[0,1] neg_hi:[0,1]
	v_pk_add_f32 v[100:101], v[24:25], v[10:11] op_sel:[0,1] op_sel_hi:[1,0] neg_hi:[0,1]
	v_pk_add_f32 v[10:11], v[24:25], v[10:11] op_sel:[0,1] op_sel_hi:[1,0] neg_lo:[0,1]
	v_mov_b32_e32 v24, v63
	v_pk_add_f32 v[84:85], v[108:109], v[64:65]
	v_cvt_f32_i32_e32 v24, v24
	v_pk_add_f32 v[76:77], v[108:109], v[64:65] neg_lo:[0,1] neg_hi:[0,1]
	v_pk_add_f32 v[104:105], v[66:67], v[26:27]
	v_pk_add_f32 v[14:15], v[66:67], v[26:27] neg_lo:[0,1] neg_hi:[0,1]
	v_mul_f32_e32 v25, 0x38800000, v24
	v_cos_f32_e32 v24, v25
	v_sin_f32_e32 v25, v25
	s_nop 0
	s_nop 0
	v_add_f32_e32 v62, v24, v24
	v_pk_mul_f32 v[26:27], v[24:25], v[24:25]
	v_mul_f32_e32 v62, v25, v62
	s_nop 0
	s_nop 0
	v_mov_b32_e32 v108, v25
	v_pk_add_f32 v[26:27], v[26:27], v[26:27] op_sel:[0,1] op_sel_hi:[0,1] neg_lo:[0,1] neg_hi:[0,1]
	v_pk_mul_f32 v[72:73], v[24:25], v[62:63] op_sel:[1,0] op_sel_hi:[0,0] neg_lo:[1,0]
	v_pk_mul_f32 v[94:95], v[18:19], v[108:109] op_sel:[1,0] op_sel_hi:[0,0] neg_hi:[1,0]
	v_pk_add_f32 v[16:17], v[70:71], v[80:81]
	v_pk_fma_f32 v[72:73], v[24:25], v[26:27], v[72:73]
	v_pk_fma_f32 v[18:19], v[18:19], v[24:25], v[94:95] op_sel_hi:[1,0,1]
	v_pk_mul_f32 v[24:25], v[62:63], s[48:49] op_sel_hi:[0,1]
	v_pk_fma_f32 v[94:95], v[26:27], s[40:41], v[24:25]
	s_nop 0
	v_pk_mul_f32 v[24:25], v[16:17], v[94:95] op_sel:[1,1] op_sel_hi:[0,1] neg_hi:[1,0]
	v_pk_add_f32 v[64:65], v[112:113], v[114:115]
	v_pk_fma_f32 v[24:25], v[16:17], v[94:95], v[24:25] op_sel_hi:[1,0,1]
	v_pk_mul_f32 v[16:17], v[62:63], v[72:73] op_sel:[0,1] op_sel_hi:[0,0] neg_lo:[0,1]
	v_pk_fma_f32 v[108:109], v[26:27], v[72:73], v[16:17]
	v_pk_mul_f32 v[16:17], v[64:65], v[72:73] op_sel:[1,1] op_sel_hi:[0,1] neg_hi:[1,0]
	v_pk_add_f32 v[90:91], v[106:107], v[82:83]
	v_pk_fma_f32 v[16:17], v[64:65], v[72:73], v[16:17] op_sel_hi:[1,0,1]
	v_pk_mul_f32 v[64:65], v[62:63], v[94:95] op_sel:[0,1] op_sel_hi:[0,0] neg_lo:[0,1]
	v_pk_fma_f32 v[94:95], v[26:27], v[94:95], v[64:65]
	s_nop 0
	v_pk_mul_f32 v[64:65], v[78:79], v[94:95] op_sel:[1,1] op_sel_hi:[0,1] neg_hi:[1,0]
	v_pk_add_f32 v[66:67], v[6:7], v[118:119]
	v_pk_fma_f32 v[72:73], v[78:79], v[94:95], v[64:65] op_sel_hi:[1,0,1]
	v_pk_mul_f32 v[64:65], v[62:63], v[108:109] op_sel:[0,1] op_sel_hi:[0,0] neg_lo:[0,1]
	v_pk_fma_f32 v[110:111], v[26:27], v[108:109], v[64:65]
	v_pk_mul_f32 v[64:65], v[84:85], v[108:109] op_sel:[1,1] op_sel_hi:[0,1] neg_hi:[1,0]
	v_pk_mul_f32 v[78:79], v[62:63], v[94:95] op_sel:[0,1] op_sel_hi:[0,0] neg_lo:[0,1]
	v_pk_fma_f32 v[64:65], v[84:85], v[108:109], v[64:65] op_sel_hi:[1,0,1]
	v_pk_fma_f32 v[84:85], v[26:27], v[94:95], v[78:79]
	s_nop 0
	v_pk_mul_f32 v[78:79], v[90:91], v[84:85] op_sel:[1,1] op_sel_hi:[0,1] neg_hi:[1,0]
	v_pk_add_f32 v[68:69], v[106:107], v[82:83] neg_lo:[0,1] neg_hi:[0,1]
	v_pk_fma_f32 v[78:79], v[90:91], v[84:85], v[78:79] op_sel_hi:[1,0,1]
	v_pk_mul_f32 v[90:91], v[62:63], v[110:111] op_sel:[0,1] op_sel_hi:[0,0] neg_lo:[0,1]
	v_pk_fma_f32 v[94:95], v[26:27], v[110:111], v[90:91]
	v_pk_mul_f32 v[90:91], v[66:67], v[110:111] op_sel:[1,1] op_sel_hi:[0,1] neg_hi:[1,0]
	v_pk_add_f32 v[106:107], v[116:117], v[120:121]
	v_pk_fma_f32 v[66:67], v[66:67], v[110:111], v[90:91] op_sel_hi:[1,0,1]
	v_pk_mul_f32 v[90:91], v[62:63], v[84:85] op_sel:[0,1] op_sel_hi:[0,0] neg_lo:[0,1]
	v_pk_fma_f32 v[108:109], v[26:27], v[84:85], v[90:91]
	s_nop 0
	v_pk_mul_f32 v[84:85], v[122:123], v[108:109] op_sel:[1,1] op_sel_hi:[0,1] neg_hi:[1,0]
	v_pk_add_f32 v[80:81], v[70:71], v[80:81] neg_lo:[0,1] neg_hi:[0,1]
	v_pk_fma_f32 v[90:91], v[122:123], v[108:109], v[84:85] op_sel_hi:[1,0,1]
	v_pk_mul_f32 v[84:85], v[62:63], v[94:95] op_sel:[0,1] op_sel_hi:[0,0] neg_lo:[0,1]
	v_pk_fma_f32 v[110:111], v[26:27], v[94:95], v[84:85]
	v_pk_mul_f32 v[84:85], v[86:87], v[94:95] op_sel:[1,1] op_sel_hi:[0,1] neg_hi:[1,0]
	v_pk_add_f32 v[82:83], v[112:113], v[114:115] neg_lo:[0,1] neg_hi:[0,1]
	v_pk_fma_f32 v[84:85], v[86:87], v[94:95], v[84:85] op_sel_hi:[1,0,1]
	v_pk_mul_f32 v[86:87], v[62:63], v[108:109] op_sel:[0,1] op_sel_hi:[0,0] neg_lo:[0,1]
	v_pk_fma_f32 v[108:109], v[26:27], v[108:109], v[86:87]
	s_nop 0
	v_pk_mul_f32 v[86:87], v[102:103], v[108:109] op_sel:[1,1] op_sel_hi:[0,1] neg_hi:[1,0]
	v_pk_add_f32 v[70:71], v[6:7], v[118:119] neg_lo:[0,1] neg_hi:[0,1]
	v_pk_fma_f32 v[94:95], v[102:103], v[108:109], v[86:87] op_sel_hi:[1,0,1]
	v_pk_mul_f32 v[86:87], v[62:63], v[110:111] op_sel:[0,1] op_sel_hi:[0,0] neg_lo:[0,1]
	v_pk_fma_f32 v[102:103], v[26:27], v[110:111], v[86:87]
	v_pk_mul_f32 v[86:87], v[104:105], v[110:111] op_sel:[1,1] op_sel_hi:[0,1] neg_hi:[1,0]
	v_pk_add_f32 v[6:7], v[116:117], v[120:121] neg_lo:[0,1] neg_hi:[0,1]
	v_pk_fma_f32 v[86:87], v[104:105], v[110:111], v[86:87] op_sel_hi:[1,0,1]
	v_pk_mul_f32 v[104:105], v[62:63], v[108:109] op_sel:[0,1] op_sel_hi:[0,0] neg_lo:[0,1]
	v_pk_fma_f32 v[104:105], v[26:27], v[108:109], v[104:105]
	s_nop 0
	v_pk_mul_f32 v[108:109], v[96:97], v[104:105] op_sel:[1,1] op_sel_hi:[0,1] neg_hi:[1,0]
	s_nop 0
	v_pk_fma_f32 v[96:97], v[96:97], v[104:105], v[108:109] op_sel_hi:[1,0,1]
	v_pk_mul_f32 v[108:109], v[62:63], v[102:103] op_sel:[0,1] op_sel_hi:[0,0] neg_lo:[0,1]
	v_pk_mul_f32 v[110:111], v[100:101], v[102:103] op_sel:[1,1] op_sel_hi:[0,1] neg_hi:[1,0]
	v_pk_fma_f32 v[108:109], v[26:27], v[102:103], v[108:109]
	v_pk_fma_f32 v[100:101], v[100:101], v[102:103], v[110:111] op_sel_hi:[1,0,1]
	v_pk_mul_f32 v[102:103], v[62:63], v[104:105] op_sel:[0,1] op_sel_hi:[0,0] neg_lo:[0,1]
	v_pk_fma_f32 v[102:103], v[26:27], v[104:105], v[102:103]
	s_nop 0
	v_pk_mul_f32 v[104:105], v[98:99], v[102:103] op_sel:[1,1] op_sel_hi:[0,1] neg_hi:[1,0]
	s_nop 0
	v_pk_fma_f32 v[98:99], v[98:99], v[102:103], v[104:105] op_sel_hi:[1,0,1]
	v_pk_mul_f32 v[104:105], v[62:63], v[108:109] op_sel:[0,1] op_sel_hi:[0,0] neg_lo:[0,1]
	v_pk_mul_f32 v[110:111], v[106:107], v[108:109] op_sel:[1,1] op_sel_hi:[0,1] neg_hi:[1,0]
	v_pk_fma_f32 v[104:105], v[26:27], v[108:109], v[104:105]
	v_pk_fma_f32 v[106:107], v[106:107], v[108:109], v[110:111] op_sel_hi:[1,0,1]
	v_pk_mul_f32 v[108:109], v[62:63], v[102:103] op_sel:[0,1] op_sel_hi:[0,0] neg_lo:[0,1]
	v_pk_fma_f32 v[102:103], v[26:27], v[102:103], v[108:109]
	s_nop 0
	v_pk_mul_f32 v[108:109], v[88:89], v[102:103] op_sel:[1,1] op_sel_hi:[0,1] neg_hi:[1,0]
	s_nop 0
	v_pk_fma_f32 v[88:89], v[88:89], v[102:103], v[108:109] op_sel_hi:[1,0,1]
	v_pk_mul_f32 v[108:109], v[62:63], v[104:105] op_sel:[0,1] op_sel_hi:[0,0] neg_lo:[0,1]
	v_pk_mul_f32 v[110:111], v[92:93], v[104:105] op_sel:[1,1] op_sel_hi:[0,1] neg_hi:[1,0]
	v_pk_fma_f32 v[108:109], v[26:27], v[104:105], v[108:109]
	v_pk_fma_f32 v[92:93], v[92:93], v[104:105], v[110:111] op_sel_hi:[1,0,1]
	v_pk_mul_f32 v[104:105], v[62:63], v[102:103] op_sel:[0,1] op_sel_hi:[0,0] neg_lo:[0,1]
	v_pk_fma_f32 v[102:103], v[26:27], v[102:103], v[104:105]
	s_nop 0
	v_pk_mul_f32 v[104:105], v[80:81], v[102:103] op_sel:[1,1] op_sel_hi:[0,1] neg_hi:[1,0]
	s_nop 0
	v_pk_fma_f32 v[80:81], v[80:81], v[102:103], v[104:105] op_sel_hi:[1,0,1]
	v_pk_mul_f32 v[104:105], v[62:63], v[108:109] op_sel:[0,1] op_sel_hi:[0,0] neg_lo:[0,1]
	v_pk_mul_f32 v[110:111], v[82:83], v[108:109] op_sel:[1,1] op_sel_hi:[0,1] neg_hi:[1,0]
	v_pk_fma_f32 v[104:105], v[26:27], v[108:109], v[104:105]
	v_pk_fma_f32 v[82:83], v[82:83], v[108:109], v[110:111] op_sel_hi:[1,0,1]
	v_pk_mul_f32 v[108:109], v[62:63], v[102:103] op_sel:[0,1] op_sel_hi:[0,0] neg_lo:[0,1]
	v_pk_fma_f32 v[102:103], v[26:27], v[102:103], v[108:109]
	s_nop 0
	v_pk_mul_f32 v[108:109], v[74:75], v[102:103] op_sel:[1,1] op_sel_hi:[0,1] neg_hi:[1,0]
	s_nop 0
	v_pk_fma_f32 v[74:75], v[74:75], v[102:103], v[108:109] op_sel_hi:[1,0,1]
	v_pk_mul_f32 v[108:109], v[62:63], v[104:105] op_sel:[0,1] op_sel_hi:[0,0] neg_lo:[0,1]
	v_pk_mul_f32 v[110:111], v[76:77], v[104:105] op_sel:[1,1] op_sel_hi:[0,1] neg_hi:[1,0]
	v_pk_fma_f32 v[108:109], v[26:27], v[104:105], v[108:109]
	v_pk_fma_f32 v[76:77], v[76:77], v[104:105], v[110:111] op_sel_hi:[1,0,1]
	v_pk_mul_f32 v[104:105], v[62:63], v[102:103] op_sel:[0,1] op_sel_hi:[0,0] neg_lo:[0,1]
	v_pk_fma_f32 v[102:103], v[26:27], v[102:103], v[104:105]
	s_nop 0
	v_pk_mul_f32 v[104:105], v[68:69], v[102:103] op_sel:[1,1] op_sel_hi:[0,1] neg_hi:[1,0]
	s_nop 0
	v_pk_fma_f32 v[68:69], v[68:69], v[102:103], v[104:105] op_sel_hi:[1,0,1]
	v_pk_mul_f32 v[104:105], v[62:63], v[108:109] op_sel:[0,1] op_sel_hi:[0,0] neg_lo:[0,1]
	v_pk_mul_f32 v[110:111], v[70:71], v[108:109] op_sel:[1,1] op_sel_hi:[0,1] neg_hi:[1,0]
	v_pk_fma_f32 v[104:105], v[26:27], v[108:109], v[104:105]
	v_pk_fma_f32 v[70:71], v[70:71], v[108:109], v[110:111] op_sel_hi:[1,0,1]
	v_pk_mul_f32 v[108:109], v[62:63], v[102:103] op_sel:[0,1] op_sel_hi:[0,0] neg_lo:[0,1]
	v_pk_fma_f32 v[102:103], v[26:27], v[102:103], v[108:109]
	s_nop 0
	v_pk_mul_f32 v[108:109], v[20:21], v[102:103] op_sel:[1,1] op_sel_hi:[0,1] neg_hi:[1,0]
	s_nop 0
	v_pk_fma_f32 v[20:21], v[20:21], v[102:103], v[108:109] op_sel_hi:[1,0,1]
	v_pk_mul_f32 v[108:109], v[62:63], v[104:105] op_sel:[0,1] op_sel_hi:[0,0] neg_lo:[0,1]
	v_pk_mul_f32 v[110:111], v[22:23], v[104:105] op_sel:[1,1] op_sel_hi:[0,1] neg_hi:[1,0]
	v_pk_fma_f32 v[108:109], v[26:27], v[104:105], v[108:109]
	v_pk_fma_f32 v[22:23], v[22:23], v[104:105], v[110:111] op_sel_hi:[1,0,1]
	v_pk_mul_f32 v[104:105], v[62:63], v[102:103] op_sel:[0,1] op_sel_hi:[0,0] neg_lo:[0,1]
	v_pk_fma_f32 v[102:103], v[26:27], v[102:103], v[104:105]
	s_nop 0
	v_pk_mul_f32 v[104:105], v[12:13], v[102:103] op_sel:[1,1] op_sel_hi:[0,1] neg_hi:[1,0]
	s_nop 0
	v_pk_fma_f32 v[12:13], v[12:13], v[102:103], v[104:105] op_sel_hi:[1,0,1]
	v_pk_mul_f32 v[104:105], v[62:63], v[108:109] op_sel:[0,1] op_sel_hi:[0,0] neg_lo:[0,1]
	v_pk_mul_f32 v[110:111], v[14:15], v[108:109] op_sel:[1,1] op_sel_hi:[0,1] neg_hi:[1,0]
	v_pk_fma_f32 v[104:105], v[26:27], v[108:109], v[104:105]
	v_pk_fma_f32 v[14:15], v[14:15], v[108:109], v[110:111] op_sel_hi:[1,0,1]
	v_pk_mul_f32 v[108:109], v[62:63], v[102:103] op_sel:[0,1] op_sel_hi:[0,0] neg_lo:[0,1]
	v_pk_fma_f32 v[102:103], v[26:27], v[102:103], v[108:109]
	s_nop 0
	v_pk_mul_f32 v[108:109], v[8:9], v[102:103] op_sel:[1,1] op_sel_hi:[0,1] neg_hi:[1,0]
	s_nop 0
	v_pk_fma_f32 v[8:9], v[8:9], v[102:103], v[108:109] op_sel_hi:[1,0,1]
	v_pk_mul_f32 v[108:109], v[62:63], v[104:105] op_sel:[0,1] op_sel_hi:[0,0] neg_lo:[0,1]
	v_pk_mul_f32 v[110:111], v[10:11], v[104:105] op_sel:[1,1] op_sel_hi:[0,1] neg_hi:[1,0]
	v_pk_fma_f32 v[108:109], v[26:27], v[104:105], v[108:109]
	v_pk_fma_f32 v[10:11], v[10:11], v[104:105], v[110:111] op_sel_hi:[1,0,1]
	v_pk_mul_f32 v[104:105], v[62:63], v[102:103] op_sel:[0,1] op_sel_hi:[0,0] neg_lo:[0,1]
	v_pk_fma_f32 v[26:27], v[26:27], v[102:103], v[104:105]
	s_nop 0
	v_pk_mul_f32 v[102:103], v[4:5], v[26:27] op_sel:[1,1] op_sel_hi:[0,1] neg_hi:[1,0]
	s_add_i32 s1, 16, 0x1e000
	v_pk_fma_f32 v[4:5], v[4:5], v[26:27], v[102:103] op_sel_hi:[1,0,1]
	s_nop 0
	s_nop 0
	v_pk_mul_f32 v[26:27], v[6:7], v[108:109] op_sel:[1,1] op_sel_hi:[0,1] neg_hi:[1,0]
	s_add_i32 s0, 16, 0x1f000
	v_pk_fma_f32 v[6:7], v[6:7], v[108:109], v[26:27] op_sel_hi:[1,0,1]
	v_lshrrev_b32_e32 v26, 5, v63
	v_bitop3_b32 v26, v26, v63, 15 bitop3:0x6c
	v_lshlrev_b32_e32 v26, 3, v26
	v_bfe_u32 v27, v63, 5, 4
	v_add_u32_e32 v62, 16, v26
	ds_write_b64 v62, v[2:3]
	v_bitop3_b32 v2, v27, v63, 16 bitop3:0x36
	v_lshlrev_b32_e32 v2, 3, v2
	v_add_u32_e32 v3, 16, v2
	ds_write_b64 v3, v[88:89] offset:4096
	ds_write_b64 v62, v[90:91] offset:8192
	ds_write_b64 v3, v[20:21] offset:12288
	ds_write_b64 v62, v[72:73] offset:16384
	ds_write_b64 v3, v[74:75] offset:20480
	ds_write_b64 v62, v[96:97] offset:24576
	ds_write_b64 v3, v[8:9] offset:28672
	ds_write_b64 v62, v[24:25] offset:32768
	ds_write_b64 v3, v[80:81] offset:36864
	ds_write_b64 v62, v[94:95] offset:40960
	ds_write_b64 v3, v[12:13] offset:45056
	ds_write_b64 v62, v[78:79] offset:49152
	ds_write_b64 v3, v[68:69] offset:53248
	ds_write_b64 v62, v[98:99] offset:57344
	ds_write_b64 v3, v[4:5] offset:61440
	v_add_u32_e32 v3, s47, v26
	ds_write_b64 v3, v[18:19]
	v_add_u32_e32 v3, s19, v2
	ds_write_b64 v3, v[92:93]
	v_add_u32_e32 v3, s18, v26
	ds_write_b64 v3, v[84:85]
	v_add_u32_e32 v3, s17, v2
	ds_write_b64 v3, v[22:23]
	v_add_u32_e32 v3, s13, v26
	ds_write_b64 v3, v[64:65]
	v_add_u32_e32 v3, s12, v2
	ds_write_b64 v3, v[76:77]
	v_add_u32_e32 v3, s11, v26
	ds_write_b64 v3, v[100:101]
	v_add_u32_e32 v3, s10, v2
	ds_write_b64 v3, v[10:11]
	v_add_u32_e32 v3, s9, v26
	ds_write_b64 v3, v[16:17]
	v_add_u32_e32 v3, s8, v2
	ds_write_b64 v3, v[82:83]
	v_add_u32_e32 v3, s7, v26
	ds_write_b64 v3, v[86:87]
	v_add_u32_e32 v3, s6, v2
	ds_write_b64 v3, v[14:15]
	v_add_u32_e32 v3, s5, v26
	ds_write_b64 v3, v[66:67]
	v_add_u32_e32 v3, s4, v2
	ds_write_b64 v3, v[70:71]
	v_add_u32_e32 v3, s1, v26
	v_add_u32_e32 v2, s0, v2
	v_mov_b32_e32 v21, v146
	ds_write_b64 v3, v[106:107]
	ds_write_b64 v2, v[6:7]
	s_waitcnt lgkmcnt(0)
	s_barrier
	s_lshl_b32 s44, s16, 14
	v_lshlrev_b32_e32 v2, 5, v21
	v_and_b32_e32 v4, 0xfffffe00, v2
	v_and_b32_e32 v20, 15, v21
	v_and_or_b32 v2, v21, 16, v4
	v_bitop3_b32 v4, v4, 16, v21 bitop3:0x34
	v_bitop3_b32 v72, v21, 8, 15 bitop3:0x6c
	v_lshl_add_u32 v26, v2, 3, 16
	v_lshlrev_b32_e32 v5, 3, v20
	v_lshl_add_u32 v126, v4, 3, 16
	v_lshlrev_b32_e32 v74, 3, v72
	v_add_u32_e32 v27, v26, v5
	v_add_u32_e32 v96, v126, v5
	v_add_u32_e32 v111, v26, v74
	v_add_u32_e32 v112, v126, v74
	ds_read_b64 v[2:3], v27
	ds_read_b64 v[4:5], v96
	v_bitop3_b32 v6, v21, 1, 15 bitop3:0x6c
	ds_read_b64 v[72:73], v111 offset:2048
	ds_read_b64 v[74:75], v112 offset:2048
	v_bitop3_b32 v76, v21, 9, 15 bitop3:0x6c
	v_lshlrev_b32_e32 v8, 3, v6
	v_lshlrev_b32_e32 v78, 3, v76
	v_add_u32_e32 v97, v26, v8
	v_add_u32_e32 v113, v26, v78
	ds_read_b64 v[6:7], v97 offset:256
	ds_read_b64 v[76:77], v113 offset:2304
	v_add_u32_e32 v98, v126, v8
	v_add_u32_e32 v114, v126, v78
	ds_read_b64 v[8:9], v98 offset:256
	ds_read_b64 v[78:79], v114 offset:2304
	s_waitcnt lgkmcnt(5)
	v_pk_add_f32 v[136:137], v[2:3], v[72:73]
	v_pk_add_f32 v[2:3], v[2:3], v[72:73] neg_lo:[0,1] neg_hi:[0,1]
	s_waitcnt lgkmcnt(4)
	v_pk_add_f32 v[72:73], v[4:5], v[74:75]
	v_pk_add_f32 v[4:5], v[4:5], v[74:75] neg_lo:[0,1] neg_hi:[0,1]
	v_bitop3_b32 v10, v21, 2, 15 bitop3:0x6c
	v_bitop3_b32 v80, v21, 10, 15 bitop3:0x6c
	v_lshlrev_b32_e32 v12, 3, v10
	v_lshlrev_b32_e32 v82, 3, v80
	v_pk_mul_f32 v[74:75], v[4:5], s[58:59] op_sel:[1,0] op_sel_hi:[0,0] neg_hi:[1,0]
	v_add_u32_e32 v99, v26, v12
	v_add_u32_e32 v115, v26, v82
	v_pk_fma_f32 v[4:5], v[4:5], s[46:47], v[74:75] op_sel_hi:[1,0,1]
	s_waitcnt lgkmcnt(2)
	v_pk_add_f32 v[74:75], v[6:7], v[76:77]
	v_pk_add_f32 v[6:7], v[6:7], v[76:77] neg_lo:[0,1] neg_hi:[0,1]
	ds_read_b64 v[10:11], v99 offset:512
	ds_read_b64 v[80:81], v115 offset:2560
	v_pk_mul_f32 v[76:77], v[6:7], s[62:63] op_sel:[1,0] op_sel_hi:[0,0] neg_hi:[1,0]
	v_add_u32_e32 v100, v126, v12
	v_bitop3_b32 v14, v21, 3, 15 bitop3:0x6c
	v_add_u32_e32 v116, v126, v82
	v_bitop3_b32 v84, v21, 11, 15 bitop3:0x6c
	v_pk_fma_f32 v[6:7], v[6:7], s[60:61], v[76:77] op_sel_hi:[1,0,1]
	s_waitcnt lgkmcnt(2)
	v_pk_add_f32 v[76:77], v[8:9], v[78:79]
	v_pk_add_f32 v[8:9], v[8:9], v[78:79] neg_lo:[0,1] neg_hi:[0,1]
	ds_read_b64 v[12:13], v100 offset:512
	v_lshlrev_b32_e32 v16, 3, v14
	ds_read_b64 v[82:83], v116 offset:2560
	v_lshlrev_b32_e32 v86, 3, v84
	v_add_u32_e32 v101, v26, v16
	v_add_u32_e32 v102, v126, v16
	v_add_u32_e32 v117, v26, v86
	v_add_u32_e32 v118, v126, v86
	v_pk_mul_f32 v[78:79], v[8:9], s[66:67] op_sel:[1,0] op_sel_hi:[0,0] neg_hi:[1,0]
	ds_read_b64 v[14:15], v101 offset:768
	ds_read_b64 v[16:17], v102 offset:768
	ds_read_b64 v[84:85], v117 offset:2816
	ds_read_b64 v[86:87], v118 offset:2816
	v_pk_fma_f32 v[8:9], v[8:9], s[64:65], v[78:79] op_sel_hi:[1,0,1]
	s_waitcnt lgkmcnt(6)
	v_pk_add_f32 v[78:79], v[10:11], v[80:81]
	v_pk_add_f32 v[10:11], v[10:11], v[80:81] neg_lo:[0,1] neg_hi:[0,1]
	v_bitop3_b32 v18, v21, 4, 15 bitop3:0x6c
	v_pk_mul_f32 v[80:81], v[10:11], s[70:71] op_sel:[1,0] op_sel_hi:[0,0] neg_hi:[1,0]
	v_bitop3_b32 v88, v21, 12, 15 bitop3:0x6c
	v_pk_fma_f32 v[10:11], v[10:11], s[70:71], v[80:81] op_sel_hi:[1,0,1]
	s_waitcnt lgkmcnt(4)
	v_pk_add_f32 v[80:81], v[12:13], v[82:83]
	v_pk_add_f32 v[12:13], v[12:13], v[82:83] neg_lo:[0,1] neg_hi:[0,1]
	v_lshlrev_b32_e32 v22, 3, v18
	v_lshlrev_b32_e32 v90, 3, v88
	v_pk_mul_f32 v[82:83], v[12:13], s[64:65] op_sel:[1,0] op_sel_hi:[0,0] neg_hi:[1,0]
	v_add_u32_e32 v103, v26, v22
	v_add_u32_e32 v119, v26, v90
	v_pk_fma_f32 v[12:13], v[12:13], s[66:67], v[82:83] op_sel_hi:[1,0,1]
	s_waitcnt lgkmcnt(1)
	v_pk_add_f32 v[82:83], v[14:15], v[84:85]
	v_pk_add_f32 v[14:15], v[14:15], v[84:85] neg_lo:[0,1] neg_hi:[0,1]
	ds_read_b64 v[18:19], v103 offset:1024
	v_add_u32_e32 v104, v126, v22
	v_bitop3_b32 v24, v21, 5, 15 bitop3:0x6c
	ds_read_b64 v[88:89], v119 offset:3072
	v_add_u32_e32 v120, v126, v90
	v_bitop3_b32 v92, v21, 13, 15 bitop3:0x6c
	ds_read_b64 v[22:23], v104 offset:1024
	v_lshlrev_b32_e32 v62, 3, v24
	ds_read_b64 v[90:91], v120 offset:3072
	v_lshlrev_b32_e32 v94, 3, v92
	v_pk_mul_f32 v[84:85], v[14:15], s[60:61] op_sel:[1,0] op_sel_hi:[0,0] neg_hi:[1,0]
	v_add_u32_e32 v105, v26, v62
	v_add_u32_e32 v121, v26, v94
	v_pk_fma_f32 v[14:15], v[14:15], s[62:63], v[84:85] op_sel_hi:[1,0,1]
	s_waitcnt lgkmcnt(4)
	v_pk_add_f32 v[84:85], v[16:17], v[86:87]
	v_pk_add_f32 v[16:17], v[16:17], v[86:87] neg_lo:[0,1] neg_hi:[0,1]
	ds_read_b64 v[24:25], v105 offset:1280
	ds_read_b64 v[92:93], v121 offset:3328
	v_add_u32_e32 v106, v126, v62
	v_bitop3_b32 v64, v21, 6, 15 bitop3:0x6c
	v_add_u32_e32 v122, v126, v94
	v_bitop3_b32 v123, v21, 14, 15 bitop3:0x6c
	v_pk_mul_f32 v[86:87], v[16:17], s[46:47] op_sel:[1,0] op_sel_hi:[0,0] neg_hi:[1,0]
	ds_read_b64 v[62:63], v106 offset:1280
	v_lshlrev_b32_e32 v66, 3, v64
	ds_read_b64 v[94:95], v122 offset:3328
	v_lshlrev_b32_e32 v124, 3, v123
	v_pk_fma_f32 v[16:17], v[16:17], s[58:59], v[86:87] op_sel_hi:[1,0,1]
	s_waitcnt lgkmcnt(6)
	v_pk_add_f32 v[86:87], v[18:19], v[88:89]
	v_pk_add_f32 v[18:19], v[18:19], v[88:89] neg_lo:[0,1] neg_hi:[0,1]
	v_add_u32_e32 v107, v26, v66
	v_add_u32_e32 v123, v26, v124
	v_xor_b32_e32 v89, 0x80000000, v18
	v_mov_b32_e32 v88, v19
	s_waitcnt lgkmcnt(4)
	v_pk_add_f32 v[18:19], v[22:23], v[90:91]
	v_pk_add_f32 v[22:23], v[22:23], v[90:91] neg_lo:[0,1] neg_hi:[0,1]
	ds_read_b64 v[64:65], v107 offset:1536
	ds_read_b64 v[128:129], v123 offset:3584
	v_pk_mul_f32 v[90:91], v[22:23], s[58:59] op_sel_hi:[1,0]
	v_xor_b32_e32 v139, 0x80000000, v22
	v_mov_b32_e32 v138, v23
	v_add_u32_e32 v108, v126, v66
	v_bitop3_b32 v68, v21, 7, 15 bitop3:0x6c
	v_add_u32_e32 v124, v126, v124
	v_bitop3_b32 v21, v21, 15, v21 bitop3:0xc
	v_pk_fma_f32 v[22:23], v[138:139], s[46:47], v[90:91] op_sel_hi:[1,0,1] neg_lo:[0,0,1] neg_hi:[0,0,1]
	s_waitcnt lgkmcnt(4)
	v_pk_add_f32 v[90:91], v[24:25], v[92:93]
	v_pk_add_f32 v[24:25], v[24:25], v[92:93] neg_lo:[0,1] neg_hi:[0,1]
	ds_read_b64 v[66:67], v108 offset:1536
	v_lshlrev_b32_e32 v70, 3, v68
	ds_read_b64 v[130:131], v124 offset:3584
	v_lshlrev_b32_e32 v21, 3, v21
	v_pk_mul_f32 v[92:93], v[24:25], s[62:63] op_sel_hi:[1,0]
	v_xor_b32_e32 v139, 0x80000000, v24
	v_mov_b32_e32 v138, v25
	v_add_u32_e32 v109, v26, v70
	v_add_u32_e32 v125, v26, v21
	v_pk_fma_f32 v[24:25], v[138:139], s[60:61], v[92:93] op_sel_hi:[1,0,1] neg_lo:[0,0,1] neg_hi:[0,0,1]
	s_waitcnt lgkmcnt(4)
	v_pk_add_f32 v[92:93], v[62:63], v[94:95]
	v_pk_add_f32 v[62:63], v[62:63], v[94:95] neg_lo:[0,1] neg_hi:[0,1]
	ds_read_b64 v[68:69], v109 offset:1792
	v_add_u32_e32 v110, v126, v70
	ds_read_b64 v[132:133], v125 offset:3840
	v_add_u32_e32 v126, v126, v21
	v_pk_mul_f32 v[94:95], v[62:63], s[66:67] op_sel_hi:[1,0]
	v_xor_b32_e32 v139, 0x80000000, v62
	v_mov_b32_e32 v138, v63
	ds_read_b64 v[70:71], v110 offset:1792
	ds_read_b64 v[134:135], v126 offset:3840
	v_pk_fma_f32 v[62:63], v[138:139], s[64:65], v[94:95] op_sel_hi:[1,0,1] neg_lo:[0,0,1] neg_hi:[0,0,1]
	s_waitcnt lgkmcnt(6)
	v_pk_add_f32 v[94:95], v[64:65], v[128:129]
	v_pk_add_f32 v[64:65], v[64:65], v[128:129] neg_lo:[0,1] neg_hi:[0,1]
	v_lshl_add_u64 v[0:1], s[44:45], 2, v[28:29]
	v_pk_mul_f32 v[128:129], v[64:65], s[70:71] op_sel_hi:[1,0]
	v_xor_b32_e32 v139, 0x80000000, v64
	v_mov_b32_e32 v138, v65
	v_pk_fma_f32 v[64:65], v[138:139], s[70:71], v[128:129] op_sel_hi:[1,0,1] neg_lo:[0,0,1] neg_hi:[0,0,1]
	s_waitcnt lgkmcnt(4)
	v_pk_add_f32 v[128:129], v[66:67], v[130:131]
	v_pk_add_f32 v[66:67], v[66:67], v[130:131] neg_lo:[0,1] neg_hi:[0,1]
	v_cvt_f32_i32_e32 v20, v20
	v_pk_mul_f32 v[130:131], v[66:67], s[64:65] op_sel_hi:[1,0]
	v_xor_b32_e32 v139, 0x80000000, v66
	v_mov_b32_e32 v138, v67
	v_pk_fma_f32 v[66:67], v[138:139], s[66:67], v[130:131] op_sel_hi:[1,0,1] neg_lo:[0,0,1] neg_hi:[0,0,1]
	s_waitcnt lgkmcnt(2)
	v_pk_add_f32 v[130:131], v[68:69], v[132:133]
	v_pk_add_f32 v[68:69], v[68:69], v[132:133] neg_lo:[0,1] neg_hi:[0,1]
	v_mul_f32_e32 v21, 0x3b000000, v20
	v_pk_mul_f32 v[132:133], v[68:69], s[60:61] op_sel_hi:[1,0]
	v_xor_b32_e32 v139, 0x80000000, v68
	v_mov_b32_e32 v138, v69
	v_pk_fma_f32 v[68:69], v[138:139], s[62:63], v[132:133] op_sel_hi:[1,0,1] neg_lo:[0,0,1] neg_hi:[0,0,1]
	s_waitcnt lgkmcnt(0)
	v_pk_add_f32 v[132:133], v[70:71], v[134:135]
	v_pk_add_f32 v[70:71], v[70:71], v[134:135] neg_lo:[0,1] neg_hi:[0,1]
	v_cos_f32_e32 v20, v21
	v_pk_mul_f32 v[134:135], v[70:71], s[46:47] op_sel_hi:[1,0]
	v_xor_b32_e32 v139, 0x80000000, v70
	v_mov_b32_e32 v138, v71
	v_pk_fma_f32 v[70:71], v[138:139], s[58:59], v[134:135] op_sel_hi:[1,0,1] neg_lo:[0,0,1] neg_hi:[0,0,1]
	v_pk_add_f32 v[134:135], v[136:137], v[86:87]
	v_pk_add_f32 v[86:87], v[136:137], v[86:87] neg_lo:[0,1] neg_hi:[0,1]
	v_pk_add_f32 v[136:137], v[72:73], v[18:19]
	v_pk_add_f32 v[18:19], v[72:73], v[18:19] neg_lo:[0,1] neg_hi:[0,1]
	v_sin_f32_e32 v21, v21
	s_nop 0
	s_nop 0
	v_pk_mul_f32 v[72:73], v[18:19], s[62:63] op_sel:[1,0] op_sel_hi:[0,0] neg_hi:[1,0]
	v_add_f32_e32 v26, v20, v20
	v_pk_fma_f32 v[18:19], v[18:19], s[60:61], v[72:73] op_sel_hi:[1,0,1]
	v_pk_add_f32 v[72:73], v[74:75], v[90:91]
	v_pk_add_f32 v[74:75], v[74:75], v[90:91] neg_lo:[0,1] neg_hi:[0,1]
	v_mul_f32_e32 v26, v21, v26
	s_nop 0
	s_nop 0
	v_pk_mul_f32 v[90:91], v[74:75], s[70:71] op_sel:[1,0] op_sel_hi:[0,0] neg_hi:[1,0]
	s_lshl_b32 s44, s16, 9
	v_pk_fma_f32 v[74:75], v[74:75], s[70:71], v[90:91] op_sel_hi:[1,0,1]
	v_pk_add_f32 v[90:91], v[76:77], v[92:93]
	v_pk_add_f32 v[76:77], v[76:77], v[92:93] neg_lo:[0,1] neg_hi:[0,1]
	s_mov_b64 s[28:29], -1
	s_nop 0
	s_nop 0
	v_pk_mul_f32 v[92:93], v[76:77], s[60:61] op_sel:[1,0] op_sel_hi:[0,0] neg_hi:[1,0]
	s_nop 0
	v_pk_fma_f32 v[76:77], v[76:77], s[62:63], v[92:93] op_sel_hi:[1,0,1]
	v_pk_add_f32 v[92:93], v[78:79], v[94:95]
	v_pk_add_f32 v[78:79], v[78:79], v[94:95] neg_lo:[0,1] neg_hi:[0,1]
	s_nop 0
	v_xor_b32_e32 v95, 0x80000000, v78
	v_mov_b32_e32 v94, v79
	v_pk_add_f32 v[78:79], v[80:81], v[128:129]
	v_pk_add_f32 v[80:81], v[80:81], v[128:129] neg_lo:[0,1] neg_hi:[0,1]
	s_nop 0
	v_pk_mul_f32 v[128:129], v[80:81], s[62:63] op_sel_hi:[1,0]
	v_xor_b32_e32 v139, 0x80000000, v80
	v_mov_b32_e32 v138, v81
	v_pk_fma_f32 v[80:81], v[138:139], s[60:61], v[128:129] op_sel_hi:[1,0,1] neg_lo:[0,0,1] neg_hi:[0,0,1]
	v_pk_add_f32 v[128:129], v[82:83], v[130:131]
	v_pk_add_f32 v[82:83], v[82:83], v[130:131] neg_lo:[0,1] neg_hi:[0,1]
	s_nop 0
	v_pk_mul_f32 v[130:131], v[82:83], s[70:71] op_sel_hi:[1,0]
	v_xor_b32_e32 v139, 0x80000000, v82
	v_mov_b32_e32 v138, v83
	v_pk_fma_f32 v[82:83], v[138:139], s[70:71], v[130:131] op_sel_hi:[1,0,1] neg_lo:[0,0,1] neg_hi:[0,0,1]
	v_pk_add_f32 v[130:131], v[84:85], v[132:133]
	v_pk_add_f32 v[84:85], v[84:85], v[132:133] neg_lo:[0,1] neg_hi:[0,1]
	s_nop 0
	v_pk_mul_f32 v[132:133], v[84:85], s[60:61] op_sel_hi:[1,0]
	v_xor_b32_e32 v139, 0x80000000, v84
	v_mov_b32_e32 v138, v85
	v_pk_fma_f32 v[84:85], v[138:139], s[62:63], v[132:133] op_sel_hi:[1,0,1] neg_lo:[0,0,1] neg_hi:[0,0,1]
	v_pk_add_f32 v[132:133], v[2:3], v[88:89]
	v_pk_add_f32 v[2:3], v[2:3], v[88:89] neg_lo:[0,1] neg_hi:[0,1]
	v_pk_add_f32 v[88:89], v[4:5], v[22:23]
	v_pk_add_f32 v[4:5], v[4:5], v[22:23] neg_lo:[0,1] neg_hi:[0,1]
	s_nop 0
	v_pk_mul_f32 v[22:23], v[4:5], s[62:63] op_sel:[1,0] op_sel_hi:[0,0] neg_hi:[1,0]
	s_nop 0
	v_pk_fma_f32 v[4:5], v[4:5], s[60:61], v[22:23] op_sel_hi:[1,0,1]
	v_pk_add_f32 v[22:23], v[6:7], v[24:25]
	v_pk_add_f32 v[6:7], v[6:7], v[24:25] neg_lo:[0,1] neg_hi:[0,1]
	s_nop 0
	v_pk_mul_f32 v[24:25], v[6:7], s[70:71] op_sel:[1,0] op_sel_hi:[0,0] neg_hi:[1,0]
	s_nop 0
	v_pk_fma_f32 v[6:7], v[6:7], s[70:71], v[24:25] op_sel_hi:[1,0,1]
	v_pk_add_f32 v[24:25], v[8:9], v[62:63]
	v_pk_add_f32 v[8:9], v[8:9], v[62:63] neg_lo:[0,1] neg_hi:[0,1]
	s_nop 0
	v_pk_mul_f32 v[62:63], v[8:9], s[60:61] op_sel:[1,0] op_sel_hi:[0,0] neg_hi:[1,0]
	s_nop 0
	v_pk_fma_f32 v[8:9], v[8:9], s[62:63], v[62:63] op_sel_hi:[1,0,1]
	v_pk_add_f32 v[62:63], v[10:11], v[64:65]
	v_pk_add_f32 v[10:11], v[10:11], v[64:65] neg_lo:[0,1] neg_hi:[0,1]
	s_nop 0
	v_xor_b32_e32 v65, 0x80000000, v10
	v_mov_b32_e32 v64, v11
	v_pk_add_f32 v[10:11], v[12:13], v[66:67]
	v_pk_add_f32 v[12:13], v[12:13], v[66:67] neg_lo:[0,1] neg_hi:[0,1]
	s_nop 0
	v_pk_mul_f32 v[66:67], v[12:13], s[62:63] op_sel_hi:[1,0]
	v_xor_b32_e32 v139, 0x80000000, v12
	v_mov_b32_e32 v138, v13
	v_pk_fma_f32 v[12:13], v[138:139], s[60:61], v[66:67] op_sel_hi:[1,0,1] neg_lo:[0,0,1] neg_hi:[0,0,1]
	v_pk_add_f32 v[66:67], v[14:15], v[68:69]
	v_pk_add_f32 v[14:15], v[14:15], v[68:69] neg_lo:[0,1] neg_hi:[0,1]
	s_nop 0
	v_pk_mul_f32 v[68:69], v[14:15], s[70:71] op_sel_hi:[1,0]
	v_xor_b32_e32 v139, 0x80000000, v14
	v_mov_b32_e32 v138, v15
	v_pk_fma_f32 v[14:15], v[138:139], s[70:71], v[68:69] op_sel_hi:[1,0,1] neg_lo:[0,0,1] neg_hi:[0,0,1]
	v_pk_add_f32 v[68:69], v[16:17], v[70:71]
	v_pk_add_f32 v[16:17], v[16:17], v[70:71] neg_lo:[0,1] neg_hi:[0,1]
	s_nop 0
	v_pk_mul_f32 v[70:71], v[16:17], s[60:61] op_sel_hi:[1,0]
	v_xor_b32_e32 v139, 0x80000000, v16
	v_mov_b32_e32 v138, v17
	v_pk_fma_f32 v[16:17], v[138:139], s[62:63], v[70:71] op_sel_hi:[1,0,1] neg_lo:[0,0,1] neg_hi:[0,0,1]
	v_pk_add_f32 v[70:71], v[134:135], v[92:93]
	v_pk_add_f32 v[92:93], v[134:135], v[92:93] neg_lo:[0,1] neg_hi:[0,1]
	v_pk_add_f32 v[134:135], v[136:137], v[78:79]
	v_pk_add_f32 v[78:79], v[136:137], v[78:79] neg_lo:[0,1] neg_hi:[0,1]
	s_nop 0
	v_pk_mul_f32 v[136:137], v[78:79], s[70:71] op_sel:[1,0] op_sel_hi:[0,0] neg_hi:[1,0]
	s_nop 0
	v_pk_fma_f32 v[78:79], v[78:79], s[70:71], v[136:137] op_sel_hi:[1,0,1]
	v_pk_add_f32 v[136:137], v[72:73], v[128:129]
	v_pk_add_f32 v[72:73], v[72:73], v[128:129] neg_lo:[0,1] neg_hi:[0,1]
	s_nop 0
	v_xor_b32_e32 v129, 0x80000000, v72
	v_mov_b32_e32 v128, v73
	v_pk_add_f32 v[72:73], v[90:91], v[130:131]
	v_pk_add_f32 v[90:91], v[90:91], v[130:131] neg_lo:[0,1] neg_hi:[0,1]
	s_nop 0
	v_pk_mul_f32 v[130:131], v[90:91], s[70:71] op_sel_hi:[1,0]
	v_xor_b32_e32 v139, 0x80000000, v90
	v_mov_b32_e32 v138, v91
	v_pk_fma_f32 v[90:91], v[138:139], s[70:71], v[130:131] op_sel_hi:[1,0,1] neg_lo:[0,0,1] neg_hi:[0,0,1]
	v_pk_add_f32 v[130:131], v[86:87], v[94:95]
	v_pk_add_f32 v[86:87], v[86:87], v[94:95] neg_lo:[0,1] neg_hi:[0,1]
	v_pk_add_f32 v[94:95], v[18:19], v[80:81]
	v_pk_add_f32 v[18:19], v[18:19], v[80:81] neg_lo:[0,1] neg_hi:[0,1]
	s_nop 0
	v_pk_mul_f32 v[80:81], v[18:19], s[70:71] op_sel:[1,0] op_sel_hi:[0,0] neg_hi:[1,0]
	s_nop 0
	v_pk_fma_f32 v[18:19], v[18:19], s[70:71], v[80:81] op_sel_hi:[1,0,1]
	v_pk_add_f32 v[80:81], v[74:75], v[82:83]
	v_pk_add_f32 v[74:75], v[74:75], v[82:83] neg_lo:[0,1] neg_hi:[0,1]
	s_nop 0
	v_xor_b32_e32 v83, 0x80000000, v74
	v_mov_b32_e32 v82, v75
	v_pk_add_f32 v[74:75], v[76:77], v[84:85]
	v_pk_add_f32 v[76:77], v[76:77], v[84:85] neg_lo:[0,1] neg_hi:[0,1]
	s_nop 0
	v_pk_mul_f32 v[84:85], v[76:77], s[70:71] op_sel_hi:[1,0]
	v_xor_b32_e32 v139, 0x80000000, v76
	v_mov_b32_e32 v138, v77
	v_pk_fma_f32 v[76:77], v[138:139], s[70:71], v[84:85] op_sel_hi:[1,0,1] neg_lo:[0,0,1] neg_hi:[0,0,1]
	v_pk_add_f32 v[84:85], v[132:133], v[62:63]
	v_pk_add_f32 v[62:63], v[132:133], v[62:63] neg_lo:[0,1] neg_hi:[0,1]
	v_pk_add_f32 v[132:133], v[88:89], v[10:11]
	v_pk_add_f32 v[10:11], v[88:89], v[10:11] neg_lo:[0,1] neg_hi:[0,1]
	s_nop 0
	v_pk_mul_f32 v[88:89], v[10:11], s[70:71] op_sel:[1,0] op_sel_hi:[0,0] neg_hi:[1,0]
	s_nop 0
	v_pk_fma_f32 v[10:11], v[10:11], s[70:71], v[88:89] op_sel_hi:[1,0,1]
	v_pk_add_f32 v[88:89], v[22:23], v[66:67]
	v_pk_add_f32 v[22:23], v[22:23], v[66:67] neg_lo:[0,1] neg_hi:[0,1]
	s_nop 0
	v_xor_b32_e32 v67, 0x80000000, v22
	v_mov_b32_e32 v66, v23
	v_pk_add_f32 v[22:23], v[24:25], v[68:69]
	v_pk_add_f32 v[24:25], v[24:25], v[68:69] neg_lo:[0,1] neg_hi:[0,1]
	s_nop 0
	v_pk_mul_f32 v[68:69], v[24:25], s[70:71] op_sel_hi:[1,0]
	v_xor_b32_e32 v139, 0x80000000, v24
	v_mov_b32_e32 v138, v25
	v_pk_fma_f32 v[24:25], v[138:139], s[70:71], v[68:69] op_sel_hi:[1,0,1] neg_lo:[0,0,1] neg_hi:[0,0,1]
	v_pk_add_f32 v[68:69], v[2:3], v[64:65]
	v_pk_add_f32 v[2:3], v[2:3], v[64:65] neg_lo:[0,1] neg_hi:[0,1]
	v_pk_add_f32 v[64:65], v[4:5], v[12:13]
	v_pk_add_f32 v[4:5], v[4:5], v[12:13] neg_lo:[0,1] neg_hi:[0,1]
	s_nop 0
	v_pk_mul_f32 v[12:13], v[4:5], s[70:71] op_sel:[1,0] op_sel_hi:[0,0] neg_hi:[1,0]
	s_nop 0
	v_pk_fma_f32 v[4:5], v[4:5], s[70:71], v[12:13] op_sel_hi:[1,0,1]
	v_pk_add_f32 v[12:13], v[6:7], v[14:15]
	v_pk_add_f32 v[6:7], v[6:7], v[14:15] neg_lo:[0,1] neg_hi:[0,1]
	v_pk_add_f32 v[140:141], v[68:69], v[12:13]
	v_xor_b32_e32 v15, 0x80000000, v6
	v_mov_b32_e32 v14, v7
	v_pk_add_f32 v[6:7], v[8:9], v[16:17]
	v_pk_add_f32 v[8:9], v[8:9], v[16:17] neg_lo:[0,1] neg_hi:[0,1]
	v_pk_add_f32 v[142:143], v[64:65], v[6:7]
	v_pk_mul_f32 v[16:17], v[8:9], s[70:71] op_sel_hi:[1,0]
	s_nop 0
	v_pk_fma_f32 v[8:9], v[8:9], s[70:71], v[16:17] op_sel:[1,0,0] op_sel_hi:[0,0,1] neg_lo:[0,0,1] neg_hi:[1,0,1]
	v_pk_add_f32 v[16:17], v[70:71], v[136:137]
	v_pk_add_f32 v[70:71], v[70:71], v[136:137] neg_lo:[0,1] neg_hi:[0,1]
	v_pk_add_f32 v[136:137], v[134:135], v[72:73]
	v_pk_add_f32 v[72:73], v[134:135], v[72:73] neg_lo:[0,1] neg_hi:[0,1]
	v_pk_add_f32 v[138:139], v[84:85], v[88:89] neg_lo:[0,1] neg_hi:[0,1]
	v_xor_b32_e32 v135, 0x80000000, v72
	v_mov_b32_e32 v134, v73
	v_pk_add_f32 v[72:73], v[92:93], v[128:129]
	v_pk_add_f32 v[92:93], v[92:93], v[128:129] neg_lo:[0,1] neg_hi:[0,1]
	v_pk_add_f32 v[128:129], v[78:79], v[90:91]
	v_pk_add_f32 v[78:79], v[78:79], v[90:91] neg_lo:[0,1] neg_hi:[0,1]
	v_pk_add_f32 v[6:7], v[64:65], v[6:7] neg_lo:[0,1] neg_hi:[0,1]
	v_xor_b32_e32 v91, 0x80000000, v78
	v_mov_b32_e32 v90, v79
	v_pk_add_f32 v[78:79], v[130:131], v[80:81]
	v_pk_add_f32 v[130:131], v[130:131], v[80:81] neg_lo:[0,1] neg_hi:[0,1]
	v_pk_add_f32 v[80:81], v[94:95], v[74:75]
	v_pk_add_f32 v[74:75], v[94:95], v[74:75] neg_lo:[0,1] neg_hi:[0,1]
	v_xor_b32_e32 v149, 0x80000000, v6
	v_xor_b32_e32 v95, 0x80000000, v74
	v_mov_b32_e32 v94, v75
	v_pk_add_f32 v[74:75], v[86:87], v[82:83]
	v_pk_add_f32 v[82:83], v[86:87], v[82:83] neg_lo:[0,1] neg_hi:[0,1]
	v_pk_add_f32 v[86:87], v[18:19], v[76:77]
	v_pk_add_f32 v[18:19], v[18:19], v[76:77] neg_lo:[0,1] neg_hi:[0,1]
	v_mov_b32_e32 v148, v7
	v_xor_b32_e32 v77, 0x80000000, v18
	v_mov_b32_e32 v76, v19
	v_pk_add_f32 v[18:19], v[84:85], v[88:89]
	v_pk_add_f32 v[88:89], v[132:133], v[22:23]
	v_pk_add_f32 v[22:23], v[132:133], v[22:23] neg_lo:[0,1] neg_hi:[0,1]
	v_pk_add_f32 v[6:7], v[2:3], v[14:15]
	v_xor_b32_e32 v133, 0x80000000, v22
	v_mov_b32_e32 v132, v23
	v_pk_add_f32 v[22:23], v[62:63], v[66:67]
	v_pk_add_f32 v[62:63], v[62:63], v[66:67] neg_lo:[0,1] neg_hi:[0,1]
	v_pk_add_f32 v[66:67], v[10:11], v[24:25]
	v_pk_add_f32 v[10:11], v[10:11], v[24:25] neg_lo:[0,1] neg_hi:[0,1]
	v_pk_add_f32 v[150:151], v[2:3], v[14:15] neg_lo:[0,1] neg_hi:[0,1]
	v_pk_add_f32 v[2:3], v[4:5], v[8:9] neg_lo:[0,1] neg_hi:[0,1]
	v_pk_add_f32 v[68:69], v[68:69], v[12:13] neg_lo:[0,1] neg_hi:[0,1]
	v_pk_add_f32 v[156:157], v[4:5], v[8:9]
	v_xor_b32_e32 v159, 0x80000000, v2
	v_mov_b32_e32 v158, v3
	v_pk_add_f32 v[2:3], v[16:17], v[136:137]
	v_pk_add_f32 v[84:85], v[16:17], v[136:137] neg_lo:[0,1] neg_hi:[0,1]
	v_pk_add_f32 v[136:137], v[70:71], v[134:135]
	v_pk_add_f32 v[16:17], v[70:71], v[134:135] neg_lo:[0,1] neg_hi:[0,1]
	v_pk_add_f32 v[134:135], v[72:73], v[128:129]
	v_pk_add_f32 v[70:71], v[72:73], v[128:129] neg_lo:[0,1] neg_hi:[0,1]
	v_pk_add_f32 v[128:129], v[92:93], v[90:91]
	v_pk_add_f32 v[8:9], v[92:93], v[90:91] neg_lo:[0,1] neg_hi:[0,1]
	v_pk_add_f32 v[72:73], v[78:79], v[80:81]
	v_pk_add_f32 v[80:81], v[78:79], v[80:81] neg_lo:[0,1] neg_hi:[0,1]
	v_pk_add_f32 v[92:93], v[130:131], v[94:95]
	v_pk_add_f32 v[12:13], v[130:131], v[94:95] neg_lo:[0,1] neg_hi:[0,1]
	v_pk_add_f32 v[78:79], v[74:75], v[86:87]
	v_pk_add_f32 v[64:65], v[74:75], v[86:87] neg_lo:[0,1] neg_hi:[0,1]
	v_pk_add_f32 v[130:131], v[82:83], v[76:77]
	v_pk_add_f32 v[4:5], v[82:83], v[76:77] neg_lo:[0,1] neg_hi:[0,1]
	v_pk_add_f32 v[76:77], v[18:19], v[88:89]
	v_pk_add_f32 v[88:89], v[18:19], v[88:89] neg_lo:[0,1] neg_hi:[0,1]
	v_pk_add_f32 v[86:87], v[138:139], v[132:133]
	v_pk_add_f32 v[18:19], v[138:139], v[132:133] neg_lo:[0,1] neg_hi:[0,1]
	v_pk_add_f32 v[132:133], v[62:63], v[10:11] op_sel:[0,1] op_sel_hi:[1,0] neg_hi:[0,1]
	v_pk_add_f32 v[10:11], v[62:63], v[10:11] op_sel:[0,1] op_sel_hi:[1,0] neg_lo:[0,1]
	v_pk_mul_f32 v[24:25], v[20:21], v[20:21]
	s_nop 0
	v_pk_add_f32 v[24:25], v[24:25], v[24:25] op_sel:[0,1] op_sel_hi:[0,1] neg_lo:[0,1] neg_hi:[0,1]
	v_pk_mul_f32 v[62:63], v[20:21], v[26:27] op_sel:[1,0] op_sel_hi:[0,0] neg_lo:[1,0]
	v_pk_add_f32 v[90:91], v[22:23], v[66:67]
	v_pk_add_f32 v[74:75], v[22:23], v[66:67] neg_lo:[0,1] neg_hi:[0,1]
	v_pk_add_f32 v[22:23], v[140:141], v[142:143]
	v_pk_add_f32 v[82:83], v[140:141], v[142:143] neg_lo:[0,1] neg_hi:[0,1]
	v_pk_add_f32 v[138:139], v[68:69], v[148:149]
	v_pk_add_f32 v[14:15], v[68:69], v[148:149] neg_lo:[0,1] neg_hi:[0,1]
	v_pk_fma_f32 v[68:69], v[20:21], v[24:25], v[62:63]
	v_mov_b32_e32 v142, v21
	s_nop 0
	v_pk_mul_f32 v[62:63], v[142:143], v[76:77] op_sel:[0,1] op_sel_hi:[0,0] neg_hi:[0,1]
	v_pk_fma_f32 v[20:21], v[20:21], v[76:77], v[62:63] op_sel_hi:[0,1,1]
	v_pk_mul_f32 v[62:63], v[26:27], s[48:49] op_sel_hi:[0,1]
	v_pk_fma_f32 v[76:77], v[24:25], s[40:41], v[62:63]
	s_nop 0
	v_pk_mul_f32 v[62:63], v[76:77], v[72:73] op_sel:[1,1] op_sel_hi:[1,0] neg_hi:[0,1]
	v_pk_add_f32 v[94:95], v[6:7], v[156:157]
	v_pk_fma_f32 v[62:63], v[72:73], v[76:77], v[62:63] op_sel_hi:[1,0,1]
	v_pk_mul_f32 v[72:73], v[26:27], v[68:69] op_sel:[0,1] op_sel_hi:[0,0] neg_lo:[0,1]
	v_pk_fma_f32 v[142:143], v[24:25], v[68:69], v[72:73]
	v_pk_mul_f32 v[72:73], v[68:69], v[22:23] op_sel:[1,1] op_sel_hi:[1,0] neg_hi:[0,1]
	v_pk_add_f32 v[140:141], v[150:151], v[158:159]
	v_pk_fma_f32 v[22:23], v[68:69], v[22:23], v[72:73] op_sel_hi:[0,1,1]
	v_pk_mul_f32 v[68:69], v[26:27], v[76:77] op_sel:[0,1] op_sel_hi:[0,0] neg_lo:[0,1]
	v_pk_fma_f32 v[76:77], v[24:25], v[76:77], v[68:69]
	s_nop 0
	v_pk_mul_f32 v[68:69], v[134:135], v[76:77] op_sel:[1,1] op_sel_hi:[0,1] neg_hi:[1,0]
	v_pk_add_f32 v[66:67], v[6:7], v[156:157] neg_lo:[0,1] neg_hi:[0,1]
	v_pk_fma_f32 v[72:73], v[134:135], v[76:77], v[68:69] op_sel_hi:[1,0,1]
	v_pk_mul_f32 v[68:69], v[26:27], v[142:143] op_sel:[0,1] op_sel_hi:[0,0] neg_lo:[0,1]
	v_pk_fma_f32 v[134:135], v[24:25], v[142:143], v[68:69]
	v_pk_mul_f32 v[68:69], v[142:143], v[90:91] op_sel:[1,1] op_sel_hi:[1,0] neg_hi:[0,1]
	v_pk_add_f32 v[6:7], v[150:151], v[158:159] neg_lo:[0,1] neg_hi:[0,1]
	v_pk_fma_f32 v[68:69], v[90:91], v[142:143], v[68:69] op_sel_hi:[1,0,1]
	v_pk_mul_f32 v[90:91], v[26:27], v[76:77] op_sel:[0,1] op_sel_hi:[0,0] neg_lo:[0,1]
	v_pk_fma_f32 v[90:91], v[24:25], v[76:77], v[90:91]
	s_nop 0
	v_pk_mul_f32 v[76:77], v[78:79], v[90:91] op_sel:[1,1] op_sel_hi:[0,1] neg_hi:[1,0]
	s_nop 0
	v_pk_fma_f32 v[78:79], v[78:79], v[90:91], v[76:77] op_sel_hi:[1,0,1]
	v_pk_mul_f32 v[76:77], v[26:27], v[134:135] op_sel:[0,1] op_sel_hi:[0,0] neg_lo:[0,1]
	v_pk_fma_f32 v[142:143], v[24:25], v[134:135], v[76:77]
	v_pk_mul_f32 v[76:77], v[134:135], v[94:95] op_sel:[1,1] op_sel_hi:[1,0] neg_hi:[0,1]
	s_nop 0
	v_pk_fma_f32 v[76:77], v[94:95], v[134:135], v[76:77] op_sel_hi:[1,0,1]
	v_pk_mul_f32 v[94:95], v[26:27], v[90:91] op_sel:[0,1] op_sel_hi:[0,0] neg_lo:[0,1]
	v_pk_fma_f32 v[94:95], v[24:25], v[90:91], v[94:95]
	s_nop 0
	v_pk_mul_f32 v[90:91], v[136:137], v[94:95] op_sel:[1,1] op_sel_hi:[0,1] neg_hi:[1,0]
	v_xor_b32_e32 v134, 0x80000000, v143
	v_pk_fma_f32 v[90:91], v[136:137], v[94:95], v[90:91] op_sel_hi:[1,0,1]
	v_pk_mul_f32 v[136:137], v[86:87], v[142:143] op_sel:[1,1] op_sel_hi:[0,1] neg_hi:[1,0]
	v_mov_b32_e32 v135, v142
	v_pk_fma_f32 v[86:87], v[86:87], v[142:143], v[136:137] op_sel_hi:[1,0,1]
	v_pk_mul_f32 v[136:137], v[26:27], v[94:95] op_sel:[0,1] op_sel_hi:[0,0] neg_lo:[0,1]
	v_pk_mul_f32 v[134:135], v[26:27], v[134:135] op_sel_hi:[0,1]
	v_pk_fma_f32 v[136:137], v[24:25], v[94:95], v[136:137]
	v_pk_fma_f32 v[134:135], v[24:25], v[142:143], v[134:135]
	v_pk_mul_f32 v[94:95], v[92:93], v[136:137] op_sel:[1,1] op_sel_hi:[0,1] neg_hi:[1,0]
	s_nop 0
	v_pk_fma_f32 v[94:95], v[92:93], v[136:137], v[94:95] op_sel_hi:[1,0,1]
	v_pk_mul_f32 v[92:93], v[26:27], v[134:135] op_sel:[0,1] op_sel_hi:[0,0] neg_lo:[0,1]
	v_pk_fma_f32 v[142:143], v[24:25], v[134:135], v[92:93]
	v_pk_mul_f32 v[92:93], v[138:139], v[134:135] op_sel:[1,1] op_sel_hi:[0,1] neg_hi:[1,0]
	s_nop 0
	v_pk_fma_f32 v[92:93], v[138:139], v[134:135], v[92:93] op_sel_hi:[1,0,1]
	v_pk_mul_f32 v[134:135], v[26:27], v[136:137] op_sel:[0,1] op_sel_hi:[0,0] neg_lo:[0,1]
	s_nop 0
	v_pk_fma_f32 v[134:135], v[24:25], v[136:137], v[134:135]
	v_pk_mul_f32 v[138:139], v[132:133], v[142:143] op_sel:[1,1] op_sel_hi:[0,1] neg_hi:[1,0]
	v_pk_mul_f32 v[136:137], v[128:129], v[134:135] op_sel:[1,1] op_sel_hi:[0,1] neg_hi:[1,0]
	v_pk_fma_f32 v[132:133], v[132:133], v[142:143], v[138:139] op_sel_hi:[1,0,1]
	v_pk_fma_f32 v[128:129], v[128:129], v[134:135], v[136:137] op_sel_hi:[1,0,1]
	v_pk_mul_f32 v[138:139], v[26:27], v[134:135] op_sel:[0,1] op_sel_hi:[0,0] neg_lo:[0,1]
	v_pk_mul_f32 v[136:137], v[26:27], v[142:143] op_sel:[0,1] op_sel_hi:[0,0] neg_lo:[0,1]
	v_pk_fma_f32 v[134:135], v[24:25], v[134:135], v[138:139]
	v_pk_fma_f32 v[136:137], v[24:25], v[142:143], v[136:137]
	v_pk_mul_f32 v[138:139], v[130:131], v[134:135] op_sel:[1,1] op_sel_hi:[0,1] neg_hi:[1,0]
	s_nop 0
	v_pk_fma_f32 v[130:131], v[130:131], v[134:135], v[138:139] op_sel_hi:[1,0,1]
	v_pk_mul_f32 v[138:139], v[26:27], v[136:137] op_sel:[0,1] op_sel_hi:[0,0] neg_lo:[0,1]
	v_pk_mul_f32 v[142:143], v[140:141], v[136:137] op_sel:[1,1] op_sel_hi:[0,1] neg_hi:[1,0]
	v_pk_fma_f32 v[138:139], v[24:25], v[136:137], v[138:139]
	v_pk_fma_f32 v[136:137], v[140:141], v[136:137], v[142:143] op_sel_hi:[1,0,1]
	v_pk_mul_f32 v[140:141], v[26:27], v[134:135] op_sel:[0,1] op_sel_hi:[0,0] neg_lo:[0,1]
	v_pk_fma_f32 v[134:135], v[24:25], v[134:135], v[140:141]
	s_nop 0
	v_pk_mul_f32 v[140:141], v[84:85], v[134:135] op_sel:[1,1] op_sel_hi:[0,1] neg_hi:[1,0]
	s_nop 0
	v_pk_fma_f32 v[84:85], v[84:85], v[134:135], v[140:141] op_sel_hi:[1,0,1]
	v_pk_mul_f32 v[140:141], v[26:27], v[138:139] op_sel:[0,1] op_sel_hi:[0,0] neg_lo:[0,1]
	v_pk_mul_f32 v[142:143], v[88:89], v[138:139] op_sel:[1,1] op_sel_hi:[0,1] neg_hi:[1,0]
	v_pk_fma_f32 v[140:141], v[24:25], v[138:139], v[140:141]
	v_pk_fma_f32 v[88:89], v[88:89], v[138:139], v[142:143] op_sel_hi:[1,0,1]
	v_pk_mul_f32 v[138:139], v[26:27], v[134:135] op_sel:[0,1] op_sel_hi:[0,0] neg_lo:[0,1]
	v_pk_fma_f32 v[134:135], v[24:25], v[134:135], v[138:139]
	s_nop 0
	v_pk_mul_f32 v[138:139], v[80:81], v[134:135] op_sel:[1,1] op_sel_hi:[0,1] neg_hi:[1,0]
	s_nop 0
	v_pk_fma_f32 v[80:81], v[80:81], v[134:135], v[138:139] op_sel_hi:[1,0,1]
	v_pk_mul_f32 v[138:139], v[26:27], v[140:141] op_sel:[0,1] op_sel_hi:[0,0] neg_lo:[0,1]
	v_pk_mul_f32 v[142:143], v[82:83], v[140:141] op_sel:[1,1] op_sel_hi:[0,1] neg_hi:[1,0]
	v_pk_fma_f32 v[138:139], v[24:25], v[140:141], v[138:139]
	v_pk_fma_f32 v[82:83], v[82:83], v[140:141], v[142:143] op_sel_hi:[1,0,1]
	v_pk_mul_f32 v[140:141], v[26:27], v[134:135] op_sel:[0,1] op_sel_hi:[0,0] neg_lo:[0,1]
	v_pk_fma_f32 v[134:135], v[24:25], v[134:135], v[140:141]
	s_nop 0
	v_pk_mul_f32 v[140:141], v[70:71], v[134:135] op_sel:[1,1] op_sel_hi:[0,1] neg_hi:[1,0]
	s_nop 0
	v_pk_fma_f32 v[70:71], v[70:71], v[134:135], v[140:141] op_sel_hi:[1,0,1]
	v_pk_mul_f32 v[140:141], v[26:27], v[138:139] op_sel:[0,1] op_sel_hi:[0,0] neg_lo:[0,1]
	v_pk_mul_f32 v[142:143], v[74:75], v[138:139] op_sel:[1,1] op_sel_hi:[0,1] neg_hi:[1,0]
	v_pk_fma_f32 v[140:141], v[24:25], v[138:139], v[140:141]
	v_pk_fma_f32 v[74:75], v[74:75], v[138:139], v[142:143] op_sel_hi:[1,0,1]
	v_pk_mul_f32 v[138:139], v[26:27], v[134:135] op_sel:[0,1] op_sel_hi:[0,0] neg_lo:[0,1]
	v_pk_fma_f32 v[134:135], v[24:25], v[134:135], v[138:139]
	s_nop 0
	v_pk_mul_f32 v[138:139], v[64:65], v[134:135] op_sel:[1,1] op_sel_hi:[0,1] neg_hi:[1,0]
	s_nop 0
	v_pk_fma_f32 v[64:65], v[64:65], v[134:135], v[138:139] op_sel_hi:[1,0,1]
	v_pk_mul_f32 v[138:139], v[26:27], v[140:141] op_sel:[0,1] op_sel_hi:[0,0] neg_lo:[0,1]
	v_pk_mul_f32 v[142:143], v[66:67], v[140:141] op_sel:[1,1] op_sel_hi:[0,1] neg_hi:[1,0]
	v_pk_fma_f32 v[138:139], v[24:25], v[140:141], v[138:139]
	v_pk_fma_f32 v[66:67], v[66:67], v[140:141], v[142:143] op_sel_hi:[1,0,1]
	v_pk_mul_f32 v[140:141], v[26:27], v[134:135] op_sel:[0,1] op_sel_hi:[0,0] neg_lo:[0,1]
	v_pk_fma_f32 v[134:135], v[24:25], v[134:135], v[140:141]
	s_nop 0
	v_pk_mul_f32 v[140:141], v[16:17], v[134:135] op_sel:[1,1] op_sel_hi:[0,1] neg_hi:[1,0]
	s_nop 0
	v_pk_fma_f32 v[16:17], v[16:17], v[134:135], v[140:141] op_sel_hi:[1,0,1]
	v_pk_mul_f32 v[140:141], v[26:27], v[138:139] op_sel:[0,1] op_sel_hi:[0,0] neg_lo:[0,1]
	v_pk_mul_f32 v[142:143], v[18:19], v[138:139] op_sel:[1,1] op_sel_hi:[0,1] neg_hi:[1,0]
	v_pk_fma_f32 v[140:141], v[24:25], v[138:139], v[140:141]
	v_pk_fma_f32 v[18:19], v[18:19], v[138:139], v[142:143] op_sel_hi:[1,0,1]
	v_pk_mul_f32 v[138:139], v[26:27], v[134:135] op_sel:[0,1] op_sel_hi:[0,0] neg_lo:[0,1]
	v_pk_fma_f32 v[134:135], v[24:25], v[134:135], v[138:139]
	s_nop 0
	v_pk_mul_f32 v[138:139], v[12:13], v[134:135] op_sel:[1,1] op_sel_hi:[0,1] neg_hi:[1,0]
	s_nop 0
	v_pk_fma_f32 v[12:13], v[12:13], v[134:135], v[138:139] op_sel_hi:[1,0,1]
	v_pk_mul_f32 v[138:139], v[26:27], v[140:141] op_sel:[0,1] op_sel_hi:[0,0] neg_lo:[0,1]
	v_pk_mul_f32 v[142:143], v[14:15], v[140:141] op_sel:[1,1] op_sel_hi:[0,1] neg_hi:[1,0]
	v_pk_fma_f32 v[138:139], v[24:25], v[140:141], v[138:139]
	v_pk_fma_f32 v[14:15], v[14:15], v[140:141], v[142:143] op_sel_hi:[1,0,1]
	v_pk_mul_f32 v[140:141], v[26:27], v[134:135] op_sel:[0,1] op_sel_hi:[0,0] neg_lo:[0,1]
	v_pk_fma_f32 v[134:135], v[24:25], v[134:135], v[140:141]
	s_nop 0
	v_pk_mul_f32 v[140:141], v[8:9], v[134:135] op_sel:[1,1] op_sel_hi:[0,1] neg_hi:[1,0]
	s_nop 0
	v_pk_fma_f32 v[8:9], v[8:9], v[134:135], v[140:141] op_sel_hi:[1,0,1]
	v_pk_mul_f32 v[140:141], v[26:27], v[138:139] op_sel:[0,1] op_sel_hi:[0,0] neg_lo:[0,1]
	v_pk_mul_f32 v[142:143], v[10:11], v[138:139] op_sel:[1,1] op_sel_hi:[0,1] neg_hi:[1,0]
	v_pk_fma_f32 v[140:141], v[24:25], v[138:139], v[140:141]
	v_pk_fma_f32 v[10:11], v[10:11], v[138:139], v[142:143] op_sel_hi:[1,0,1]
	v_pk_mul_f32 v[138:139], v[26:27], v[134:135] op_sel:[0,1] op_sel_hi:[0,0] neg_lo:[0,1]
	v_pk_fma_f32 v[24:25], v[24:25], v[134:135], v[138:139]
	s_nop 0
	v_pk_mul_f32 v[134:135], v[4:5], v[24:25] op_sel:[1,1] op_sel_hi:[0,1] neg_hi:[1,0]
	s_nop 0
	v_pk_fma_f32 v[4:5], v[4:5], v[24:25], v[134:135] op_sel_hi:[1,0,1]
	v_pk_mul_f32 v[24:25], v[6:7], v[140:141] op_sel:[1,1] op_sel_hi:[0,1] neg_hi:[1,0]
	s_nop 0
	v_pk_fma_f32 v[6:7], v[6:7], v[140:141], v[24:25] op_sel_hi:[1,0,1]
	ds_write_b64 v27, v[2:3]
	ds_write_b64 v96, v[84:85]
	ds_write_b64 v97, v[90:91] offset:256
	ds_write_b64 v98, v[16:17] offset:256
	ds_write_b64 v99, v[72:73] offset:512
	ds_write_b64 v100, v[70:71] offset:512
	ds_write_b64 v101, v[128:129] offset:768
	ds_write_b64 v102, v[8:9] offset:768
	ds_write_b64 v103, v[62:63] offset:1024
	ds_write_b64 v104, v[80:81] offset:1024
	ds_write_b64 v105, v[94:95] offset:1280
	ds_write_b64 v106, v[12:13] offset:1280
	ds_write_b64 v107, v[78:79] offset:1536
	ds_write_b64 v108, v[64:65] offset:1536
	ds_write_b64 v109, v[130:131] offset:1792
	ds_write_b64 v110, v[4:5] offset:1792
	ds_write_b64 v111, v[20:21] offset:2048
	ds_write_b64 v112, v[88:89] offset:2048
	ds_write_b64 v113, v[86:87] offset:2304
	ds_write_b64 v114, v[18:19] offset:2304
	ds_write_b64 v115, v[68:69] offset:2560
	ds_write_b64 v116, v[74:75] offset:2560
	ds_write_b64 v117, v[132:133] offset:2816
	ds_write_b64 v118, v[10:11] offset:2816
	ds_write_b64 v119, v[22:23] offset:3072
	ds_write_b64 v120, v[82:83] offset:3072
	ds_write_b64 v121, v[92:93] offset:3328
	ds_write_b64 v122, v[14:15] offset:3328
	ds_write_b64 v123, v[76:77] offset:3584
	ds_write_b64 v124, v[66:67] offset:3584
	ds_write_b64 v125, v[136:137] offset:3840
	ds_write_b64 v126, v[6:7] offset:3840
	v_mov_b32_e32 v2, v146
	s_waitcnt lgkmcnt(0)
	s_barrier
	s_nop 0
	v_lshlrev_b32_e32 v3, 4, v2
	v_lshrrev_b32_e32 v4, 1, v2
	v_bfe_u32 v2, v2, 1, 4
	v_bitop3_b32 v5, v4, v3, 16 bitop3:0x6c
	v_lshl_add_u32 v5, v5, 3, 16
	v_lshlrev_b32_e32 v2, 3, v2
	v_add_u32_e32 v6, v5, v2
	ds_read_b64 v[12:13], v6
	v_bitop3_b32 v6, v4, 1, 15 bitop3:0x6c
	v_lshlrev_b32_e32 v8, 3, v6
	v_add_u32_e32 v6, v5, v8
	ds_read_b64 v[14:15], v6
	v_bitop3_b32 v6, v4, 2, 15 bitop3:0x6c
	v_lshlrev_b32_e32 v9, 3, v6
	v_add_u32_e32 v6, v5, v9
	ds_read_b64 v[16:17], v6
	v_bitop3_b32 v6, v4, 3, 15 bitop3:0x6c
	v_lshlrev_b32_e32 v10, 3, v6
	v_add_u32_e32 v6, v5, v10
	ds_read_b64 v[18:19], v6
	v_bitop3_b32 v6, v4, 4, 15 bitop3:0x6c
	v_lshlrev_b32_e32 v11, 3, v6
	v_add_u32_e32 v6, v5, v11
	ds_read_b64 v[20:21], v6
	v_bitop3_b32 v6, v4, 5, 15 bitop3:0x6c
	v_lshlrev_b32_e32 v82, 3, v6
	v_add_u32_e32 v6, v5, v82
	ds_read_b64 v[22:23], v6
	v_bitop3_b32 v6, v4, 6, 15 bitop3:0x6c
	v_lshlrev_b32_e32 v83, 3, v6
	v_add_u32_e32 v6, v5, v83
	ds_read_b64 v[24:25], v6
	v_bitop3_b32 v6, v4, 7, 15 bitop3:0x6c
	v_lshlrev_b32_e32 v84, 3, v6
	v_add_u32_e32 v6, v5, v84
	ds_read_b64 v[26:27], v6
	v_bitop3_b32 v6, v4, 8, 15 bitop3:0x6c
	v_lshlrev_b32_e32 v85, 3, v6
	v_add_u32_e32 v6, v5, v85
	ds_read_b64 v[62:63], v6
	v_bitop3_b32 v6, v4, 9, 15 bitop3:0x6c
	v_lshlrev_b32_e32 v86, 3, v6
	v_add_u32_e32 v6, v5, v86
	ds_read_b64 v[64:65], v6
	v_bitop3_b32 v6, v4, 10, 15 bitop3:0x6c
	v_lshlrev_b32_e32 v87, 3, v6
	v_add_u32_e32 v6, v5, v87
	ds_read_b64 v[66:67], v6
	v_bitop3_b32 v6, v4, 11, 15 bitop3:0x6c
	v_lshlrev_b32_e32 v88, 3, v6
	v_add_u32_e32 v6, v5, v88
	ds_read_b64 v[68:69], v6
	v_bitop3_b32 v6, v4, 12, 15 bitop3:0x6c
	v_lshlrev_b32_e32 v89, 3, v6
	v_add_u32_e32 v6, v5, v89
	ds_read_b64 v[70:71], v6
	v_bitop3_b32 v6, v4, 13, 15 bitop3:0x6c
	v_lshlrev_b32_e32 v90, 3, v6
	v_add_u32_e32 v6, v5, v90
	ds_read_b64 v[72:73], v6
	v_bitop3_b32 v6, v4, 14, 15 bitop3:0x6c
	v_lshlrev_b32_e32 v91, 3, v6
	v_add_u32_e32 v6, v5, v91
	v_add_u32_e32 v3, 0x2000, v3
	ds_read_b64 v[74:75], v6
	v_bitop3_b32 v6, v4, 15, v4 bitop3:0xc
	v_bitop3_b32 v3, v3, v4, 16 bitop3:0x78
	v_lshlrev_b32_e32 v106, 3, v6
	v_lshl_add_u32 v107, v3, 3, 16
	v_add_u32_e32 v5, v5, v106
	v_add_u32_e32 v2, v107, v2
	ds_read_b64 v[76:77], v5
	ds_read_b64 v[6:7], v2
	v_add_u32_e32 v2, v107, v8
	ds_read_b64 v[78:79], v2
	v_add_u32_e32 v2, v107, v9
	ds_read_b64 v[8:9], v2
	v_add_u32_e32 v2, v107, v10
	ds_read_b64 v[80:81], v2
	v_add_u32_e32 v2, v107, v11
	ds_read_b64 v[10:11], v2
	v_add_u32_e32 v2, v107, v82
	v_add_u32_e32 v82, v107, v84
	v_add_u32_e32 v84, v107, v85
	ds_read_b64 v[4:5], v2
	ds_read_b64 v[92:93], v84
	v_add_u32_e32 v2, v107, v83
	v_add_u32_e32 v84, v107, v86
	ds_read_b64 v[2:3], v2
	ds_read_b64 v[82:83], v82
	ds_read_b64 v[94:95], v84
	v_add_u32_e32 v84, v107, v87
	ds_read_b64 v[96:97], v84
	v_add_u32_e32 v84, v107, v88
	ds_read_b64 v[98:99], v84
	v_add_u32_e32 v84, v107, v89
	ds_read_b64 v[100:101], v84
	v_add_u32_e32 v84, v107, v90
	ds_read_b64 v[102:103], v84
	v_add_u32_e32 v84, v107, v91
	ds_read_b64 v[104:105], v84
	v_add_u32_e32 v84, v107, v106
	ds_read_b64 v[106:107], v84
	s_waitcnt lgkmcnt(14)
	v_pk_add_f32 v[84:85], v[12:13], v[62:63]
	v_pk_add_f32 v[12:13], v[12:13], v[62:63] neg_lo:[0,1] neg_hi:[0,1]
	v_pk_add_f32 v[62:63], v[14:15], v[64:65]
	v_pk_add_f32 v[14:15], v[14:15], v[64:65] neg_lo:[0,1] neg_hi:[0,1]
	s_nop 0
	v_pk_mul_f32 v[64:65], v[14:15], s[62:63] op_sel:[1,0] op_sel_hi:[0,0] neg_hi:[1,0]
	s_nop 0
	v_pk_fma_f32 v[14:15], v[14:15], s[60:61], v[64:65] op_sel_hi:[1,0,1]
	v_pk_add_f32 v[64:65], v[16:17], v[66:67]
	v_pk_add_f32 v[16:17], v[16:17], v[66:67] neg_lo:[0,1] neg_hi:[0,1]
	s_nop 0
	v_pk_mul_f32 v[66:67], v[16:17], s[70:71] op_sel:[1,0] op_sel_hi:[0,0] neg_hi:[1,0]
	s_nop 0
	v_pk_fma_f32 v[16:17], v[16:17], s[70:71], v[66:67] op_sel_hi:[1,0,1]
	v_pk_add_f32 v[66:67], v[18:19], v[68:69]
	v_pk_add_f32 v[18:19], v[18:19], v[68:69] neg_lo:[0,1] neg_hi:[0,1]
	s_nop 0
	v_pk_mul_f32 v[68:69], v[18:19], s[60:61] op_sel:[1,0] op_sel_hi:[0,0] neg_hi:[1,0]
	s_nop 0
	v_pk_fma_f32 v[18:19], v[18:19], s[62:63], v[68:69] op_sel_hi:[1,0,1]
	v_pk_add_f32 v[68:69], v[20:21], v[70:71]
	v_pk_add_f32 v[20:21], v[20:21], v[70:71] neg_lo:[0,1] neg_hi:[0,1]
	s_nop 0
	v_xor_b32_e32 v71, 0x80000000, v20
	v_mov_b32_e32 v70, v21
	v_pk_add_f32 v[20:21], v[22:23], v[72:73]
	v_pk_add_f32 v[22:23], v[22:23], v[72:73] neg_lo:[0,1] neg_hi:[0,1]
	s_nop 0
	v_pk_mul_f32 v[72:73], v[22:23], s[62:63] op_sel_hi:[1,0]
	v_xor_b32_e32 v87, 0x80000000, v22
	v_mov_b32_e32 v86, v23
	v_pk_fma_f32 v[22:23], v[86:87], s[60:61], v[72:73] op_sel_hi:[1,0,1] neg_lo:[0,0,1] neg_hi:[0,0,1]
	v_pk_add_f32 v[72:73], v[24:25], v[74:75]
	v_pk_add_f32 v[24:25], v[24:25], v[74:75] neg_lo:[0,1] neg_hi:[0,1]
	s_nop 0
	v_pk_mul_f32 v[74:75], v[24:25], s[70:71] op_sel_hi:[1,0]
	v_xor_b32_e32 v87, 0x80000000, v24
	v_mov_b32_e32 v86, v25
	v_pk_fma_f32 v[24:25], v[86:87], s[70:71], v[74:75] op_sel_hi:[1,0,1] neg_lo:[0,0,1] neg_hi:[0,0,1]
	v_pk_add_f32 v[74:75], v[26:27], v[76:77]
	v_pk_add_f32 v[26:27], v[26:27], v[76:77] neg_lo:[0,1] neg_hi:[0,1]
	s_nop 0
	v_pk_mul_f32 v[76:77], v[26:27], s[60:61] op_sel_hi:[1,0]
	v_xor_b32_e32 v87, 0x80000000, v26
	v_mov_b32_e32 v86, v27
	v_pk_fma_f32 v[26:27], v[86:87], s[62:63], v[76:77] op_sel_hi:[1,0,1] neg_lo:[0,0,1] neg_hi:[0,0,1]
	v_pk_add_f32 v[76:77], v[84:85], v[68:69]
	v_pk_add_f32 v[68:69], v[84:85], v[68:69] neg_lo:[0,1] neg_hi:[0,1]
	v_pk_add_f32 v[84:85], v[62:63], v[20:21]
	v_pk_add_f32 v[20:21], v[62:63], v[20:21] neg_lo:[0,1] neg_hi:[0,1]
	s_nop 0
	v_pk_mul_f32 v[62:63], v[20:21], s[70:71] op_sel:[1,0] op_sel_hi:[0,0] neg_hi:[1,0]
	s_nop 0
	v_pk_fma_f32 v[20:21], v[20:21], s[70:71], v[62:63] op_sel_hi:[1,0,1]
	v_pk_add_f32 v[62:63], v[64:65], v[72:73]
	v_pk_add_f32 v[64:65], v[64:65], v[72:73] neg_lo:[0,1] neg_hi:[0,1]
	s_nop 0
	v_xor_b32_e32 v73, 0x80000000, v64
	v_mov_b32_e32 v72, v65
	v_pk_add_f32 v[64:65], v[66:67], v[74:75]
	v_pk_add_f32 v[66:67], v[66:67], v[74:75] neg_lo:[0,1] neg_hi:[0,1]
	s_nop 0
	v_pk_mul_f32 v[74:75], v[66:67], s[70:71] op_sel_hi:[1,0]
	v_xor_b32_e32 v87, 0x80000000, v66
	v_mov_b32_e32 v86, v67
	v_pk_fma_f32 v[66:67], v[86:87], s[70:71], v[74:75] op_sel_hi:[1,0,1] neg_lo:[0,0,1] neg_hi:[0,0,1]
	v_pk_add_f32 v[74:75], v[12:13], v[70:71]
	v_pk_add_f32 v[12:13], v[12:13], v[70:71] neg_lo:[0,1] neg_hi:[0,1]
	v_pk_add_f32 v[70:71], v[14:15], v[22:23]
	v_pk_add_f32 v[14:15], v[14:15], v[22:23] neg_lo:[0,1] neg_hi:[0,1]
	s_nop 0
	v_pk_mul_f32 v[22:23], v[14:15], s[70:71] op_sel:[1,0] op_sel_hi:[0,0] neg_hi:[1,0]
	s_nop 0
	v_pk_fma_f32 v[14:15], v[14:15], s[70:71], v[22:23] op_sel_hi:[1,0,1]
	v_pk_add_f32 v[22:23], v[16:17], v[24:25]
	v_pk_add_f32 v[16:17], v[16:17], v[24:25] neg_lo:[0,1] neg_hi:[0,1]
	s_nop 0
	v_xor_b32_e32 v25, 0x80000000, v16
	v_mov_b32_e32 v24, v17
	v_pk_add_f32 v[16:17], v[18:19], v[26:27]
	v_pk_add_f32 v[18:19], v[18:19], v[26:27] neg_lo:[0,1] neg_hi:[0,1]
	v_pk_add_f32 v[108:109], v[12:13], v[24:25]
	v_pk_mul_f32 v[26:27], v[18:19], s[70:71] op_sel_hi:[1,0]
	s_nop 0
	v_pk_fma_f32 v[18:19], v[18:19], s[70:71], v[26:27] op_sel:[1,0,0] op_sel_hi:[0,0,1] neg_lo:[0,0,1] neg_hi:[1,0,1]
	v_pk_add_f32 v[26:27], v[76:77], v[62:63]
	v_pk_add_f32 v[62:63], v[76:77], v[62:63] neg_lo:[0,1] neg_hi:[0,1]
	v_pk_add_f32 v[76:77], v[84:85], v[64:65]
	v_pk_add_f32 v[64:65], v[84:85], v[64:65] neg_lo:[0,1] neg_hi:[0,1]
	v_pk_add_f32 v[110:111], v[12:13], v[24:25] neg_lo:[0,1] neg_hi:[0,1]
	v_xor_b32_e32 v85, 0x80000000, v64
	v_mov_b32_e32 v84, v65
	v_pk_add_f32 v[64:65], v[68:69], v[72:73]
	v_pk_add_f32 v[68:69], v[68:69], v[72:73] neg_lo:[0,1] neg_hi:[0,1]
	v_pk_add_f32 v[72:73], v[20:21], v[66:67]
	v_pk_add_f32 v[20:21], v[20:21], v[66:67] neg_lo:[0,1] neg_hi:[0,1]
	v_pk_add_f32 v[12:13], v[14:15], v[18:19] neg_lo:[0,1] neg_hi:[0,1]
	v_pk_add_f32 v[112:113], v[14:15], v[18:19]
	v_xor_b32_e32 v115, 0x80000000, v12
	v_mov_b32_e32 v114, v13
	v_pk_add_f32 v[12:13], v[26:27], v[76:77]
	v_pk_add_f32 v[14:15], v[26:27], v[76:77] neg_lo:[0,1] neg_hi:[0,1]
	v_pk_add_f32 v[24:25], v[68:69], v[20:21] op_sel:[0,1] op_sel_hi:[1,0] neg_hi:[0,1]
	v_pk_add_f32 v[26:27], v[68:69], v[20:21] op_sel:[0,1] op_sel_hi:[1,0] neg_lo:[0,1]
	s_waitcnt lgkmcnt(6)
	v_pk_add_f32 v[66:67], v[78:79], v[94:95] neg_lo:[0,1] neg_hi:[0,1]
	v_pk_add_f32 v[86:87], v[74:75], v[22:23]
	v_pk_mul_f32 v[76:77], v[66:67], s[62:63] op_sel:[1,0] op_sel_hi:[0,0] neg_hi:[1,0]
	v_pk_add_f32 v[74:75], v[74:75], v[22:23] neg_lo:[0,1] neg_hi:[0,1]
	v_pk_fma_f32 v[66:67], v[66:67], s[60:61], v[76:77] op_sel_hi:[1,0,1]
	s_waitcnt lgkmcnt(5)
	v_pk_add_f32 v[76:77], v[8:9], v[96:97]
	v_pk_add_f32 v[8:9], v[8:9], v[96:97] neg_lo:[0,1] neg_hi:[0,1]
	v_pk_add_f32 v[20:21], v[64:65], v[72:73]
	v_pk_add_f32 v[22:23], v[64:65], v[72:73] neg_lo:[0,1] neg_hi:[0,1]
	v_pk_add_f32 v[64:65], v[78:79], v[94:95]
	v_pk_mul_f32 v[78:79], v[8:9], s[70:71] op_sel:[1,0] op_sel_hi:[0,0] neg_hi:[1,0]
	v_pk_add_f32 v[88:89], v[70:71], v[16:17]
	v_pk_add_f32 v[16:17], v[70:71], v[16:17] neg_lo:[0,1] neg_hi:[0,1]
	v_pk_fma_f32 v[8:9], v[8:9], s[70:71], v[78:79] op_sel_hi:[1,0,1]
	s_waitcnt lgkmcnt(4)
	v_pk_add_f32 v[78:79], v[80:81], v[98:99]
	v_pk_add_f32 v[80:81], v[80:81], v[98:99] neg_lo:[0,1] neg_hi:[0,1]
	v_xor_b32_e32 v91, 0x80000000, v16
	v_mov_b32_e32 v90, v17
	v_pk_add_f32 v[16:17], v[62:63], v[84:85]
	v_pk_add_f32 v[18:19], v[62:63], v[84:85] neg_lo:[0,1] neg_hi:[0,1]
	v_pk_add_f32 v[62:63], v[6:7], v[92:93]
	v_pk_add_f32 v[6:7], v[6:7], v[92:93] neg_lo:[0,1] neg_hi:[0,1]
	v_pk_mul_f32 v[92:93], v[80:81], s[60:61] op_sel:[1,0] op_sel_hi:[0,0] neg_hi:[1,0]
	v_pk_add_f32 v[68:69], v[86:87], v[88:89]
	v_pk_fma_f32 v[80:81], v[80:81], s[62:63], v[92:93] op_sel_hi:[1,0,1]
	s_waitcnt lgkmcnt(3)
	v_pk_add_f32 v[92:93], v[10:11], v[100:101]
	v_pk_add_f32 v[10:11], v[10:11], v[100:101] neg_lo:[0,1] neg_hi:[0,1]
	v_pk_add_f32 v[70:71], v[86:87], v[88:89] neg_lo:[0,1] neg_hi:[0,1]
	v_xor_b32_e32 v95, 0x80000000, v10
	v_mov_b32_e32 v94, v11
	s_waitcnt lgkmcnt(2)
	v_pk_add_f32 v[10:11], v[4:5], v[102:103]
	v_pk_add_f32 v[4:5], v[4:5], v[102:103] neg_lo:[0,1] neg_hi:[0,1]
	v_pk_add_f32 v[84:85], v[108:109], v[112:113]
	v_pk_mul_f32 v[96:97], v[4:5], s[62:63] op_sel_hi:[1,0]
	s_nop 0
	v_pk_fma_f32 v[4:5], v[4:5], s[60:61], v[96:97] op_sel:[1,0,0] op_sel_hi:[0,0,1] neg_lo:[0,0,1] neg_hi:[1,0,1]
	s_waitcnt lgkmcnt(1)
	v_pk_add_f32 v[96:97], v[2:3], v[104:105]
	v_pk_add_f32 v[2:3], v[2:3], v[104:105] neg_lo:[0,1] neg_hi:[0,1]
	v_pk_add_f32 v[86:87], v[108:109], v[112:113] neg_lo:[0,1] neg_hi:[0,1]
	v_pk_mul_f32 v[98:99], v[2:3], s[70:71] op_sel_hi:[1,0]
	s_nop 0
	v_pk_fma_f32 v[2:3], v[2:3], s[70:71], v[98:99] op_sel:[1,0,0] op_sel_hi:[0,0,1] neg_lo:[0,0,1] neg_hi:[1,0,1]
	s_waitcnt lgkmcnt(0)
	v_pk_add_f32 v[98:99], v[82:83], v[106:107]
	v_pk_add_f32 v[82:83], v[82:83], v[106:107] neg_lo:[0,1] neg_hi:[0,1]
	v_pk_add_f32 v[72:73], v[74:75], v[90:91]
	v_pk_mul_f32 v[100:101], v[82:83], s[60:61] op_sel_hi:[1,0]
	v_xor_b32_e32 v103, 0x80000000, v82
	v_mov_b32_e32 v102, v83
	v_pk_fma_f32 v[82:83], v[102:103], s[62:63], v[100:101] op_sel_hi:[1,0,1] neg_lo:[0,0,1] neg_hi:[0,0,1]
	v_pk_add_f32 v[100:101], v[62:63], v[92:93]
	v_pk_add_f32 v[62:63], v[62:63], v[92:93] neg_lo:[0,1] neg_hi:[0,1]
	v_pk_add_f32 v[92:93], v[64:65], v[10:11]
	v_pk_add_f32 v[10:11], v[64:65], v[10:11] neg_lo:[0,1] neg_hi:[0,1]
	v_pk_add_f32 v[74:75], v[74:75], v[90:91] neg_lo:[0,1] neg_hi:[0,1]
	v_pk_mul_f32 v[64:65], v[10:11], s[70:71] op_sel:[1,0] op_sel_hi:[0,0] neg_hi:[1,0]
	v_pk_add_f32 v[88:89], v[110:111], v[114:115]
	v_pk_fma_f32 v[10:11], v[10:11], s[70:71], v[64:65] op_sel_hi:[1,0,1]
	v_pk_add_f32 v[64:65], v[76:77], v[96:97]
	v_pk_add_f32 v[76:77], v[76:77], v[96:97] neg_lo:[0,1] neg_hi:[0,1]
	v_pk_add_f32 v[90:91], v[110:111], v[114:115] neg_lo:[0,1] neg_hi:[0,1]
	v_xor_b32_e32 v97, 0x80000000, v76
	v_mov_b32_e32 v96, v77
	v_pk_add_f32 v[76:77], v[78:79], v[98:99]
	v_pk_add_f32 v[78:79], v[78:79], v[98:99] neg_lo:[0,1] neg_hi:[0,1]
	s_nop 0
	v_pk_mul_f32 v[98:99], v[78:79], s[70:71] op_sel_hi:[1,0]
	v_xor_b32_e32 v103, 0x80000000, v78
	v_mov_b32_e32 v102, v79
	v_pk_fma_f32 v[78:79], v[102:103], s[70:71], v[98:99] op_sel_hi:[1,0,1] neg_lo:[0,0,1] neg_hi:[0,0,1]
	v_pk_add_f32 v[98:99], v[6:7], v[94:95]
	v_pk_add_f32 v[6:7], v[6:7], v[94:95] neg_lo:[0,1] neg_hi:[0,1]
	v_pk_add_f32 v[94:95], v[66:67], v[4:5]
	v_pk_add_f32 v[4:5], v[66:67], v[4:5] neg_lo:[0,1] neg_hi:[0,1]
	s_nop 0
	v_pk_mul_f32 v[66:67], v[4:5], s[70:71] op_sel:[1,0] op_sel_hi:[0,0] neg_hi:[1,0]
	s_nop 0
	v_pk_fma_f32 v[4:5], v[4:5], s[70:71], v[66:67] op_sel_hi:[1,0,1]
	v_pk_add_f32 v[66:67], v[8:9], v[2:3]
	v_pk_add_f32 v[2:3], v[8:9], v[2:3] neg_lo:[0,1] neg_hi:[0,1]
	v_pk_add_f32 v[106:107], v[98:99], v[66:67] neg_lo:[0,1] neg_hi:[0,1]
	v_xor_b32_e32 v9, 0x80000000, v2
	v_mov_b32_e32 v8, v3
	v_pk_add_f32 v[2:3], v[80:81], v[82:83]
	v_pk_add_f32 v[80:81], v[80:81], v[82:83] neg_lo:[0,1] neg_hi:[0,1]
	v_pk_add_f32 v[108:109], v[94:95], v[2:3]
	v_pk_mul_f32 v[82:83], v[80:81], s[70:71] op_sel_hi:[1,0]
	s_nop 0
	v_pk_fma_f32 v[80:81], v[80:81], s[70:71], v[82:83] op_sel:[1,0,0] op_sel_hi:[0,0,1] neg_lo:[0,0,1] neg_hi:[1,0,1]
	v_pk_add_f32 v[82:83], v[100:101], v[64:65]
	v_pk_add_f32 v[64:65], v[100:101], v[64:65] neg_lo:[0,1] neg_hi:[0,1]
	v_pk_add_f32 v[100:101], v[92:93], v[76:77]
	v_pk_add_f32 v[76:77], v[92:93], v[76:77] neg_lo:[0,1] neg_hi:[0,1]
	v_pk_add_f32 v[102:103], v[10:11], v[78:79]
	v_xor_b32_e32 v93, 0x80000000, v76
	v_mov_b32_e32 v92, v77
	v_pk_add_f32 v[76:77], v[62:63], v[96:97]
	v_pk_add_f32 v[10:11], v[10:11], v[78:79] neg_lo:[0,1] neg_hi:[0,1]
	v_pk_add_f32 v[2:3], v[94:95], v[2:3] neg_lo:[0,1] neg_hi:[0,1]
	v_pk_add_f32 v[62:63], v[62:63], v[96:97] neg_lo:[0,1] neg_hi:[0,1]
	v_xor_b32_e32 v105, 0x80000000, v10
	v_mov_b32_e32 v104, v11
	v_pk_add_f32 v[10:11], v[98:99], v[66:67]
	v_xor_b32_e32 v111, 0x80000000, v2
	v_mov_b32_e32 v110, v3
	v_pk_add_f32 v[112:113], v[6:7], v[8:9]
	v_pk_add_f32 v[114:115], v[6:7], v[8:9] neg_lo:[0,1] neg_hi:[0,1]
	v_pk_add_f32 v[6:7], v[4:5], v[80:81]
	v_pk_add_f32 v[2:3], v[4:5], v[80:81] neg_lo:[0,1] neg_hi:[0,1]
	v_pk_add_f32 v[98:99], v[82:83], v[100:101]
	v_pk_add_f32 v[96:97], v[82:83], v[100:101] neg_lo:[0,1] neg_hi:[0,1]
	v_pk_add_f32 v[82:83], v[76:77], v[102:103]
	v_pk_add_f32 v[80:81], v[76:77], v[102:103] neg_lo:[0,1] neg_hi:[0,1]
	s_waitcnt vmcnt(7)
	v_mov_b64 v[100:101], v[164:165]
	v_mov_b64 v[102:103], v[166:167]
	v_pk_add_f32 v[78:79], v[62:63], v[104:105]
	v_pk_add_f32 v[76:77], v[62:63], v[104:105] neg_lo:[0,1] neg_hi:[0,1]
	v_xor_b32_e32 v5, 0x80000000, v2
	v_mov_b32_e32 v4, v3
	v_pk_add_f32 v[62:63], v[106:107], v[110:111]
	v_pk_add_f32 v[2:3], v[106:107], v[110:111] neg_lo:[0,1] neg_hi:[0,1]
	v_pk_add_f32 v[94:95], v[64:65], v[92:93]
	v_pk_add_f32 v[92:93], v[64:65], v[92:93] neg_lo:[0,1] neg_hi:[0,1]
	v_pk_add_f32 v[66:67], v[10:11], v[108:109]
	v_pk_add_f32 v[64:65], v[10:11], v[108:109] neg_lo:[0,1] neg_hi:[0,1]
	v_pk_add_f32 v[10:11], v[112:113], v[6:7]
	v_pk_add_f32 v[8:9], v[112:113], v[6:7] neg_lo:[0,1] neg_hi:[0,1]
	v_pk_add_f32 v[6:7], v[114:115], v[4:5]
	v_pk_add_f32 v[4:5], v[114:115], v[4:5] neg_lo:[0,1] neg_hi:[0,1]
	v_cvt_f32_f16_e32 v104, v100
	v_cvt_f32_f16_sdwa v100, v100 dst_sel:DWORD dst_unused:UNUSED_PAD src0_sel:WORD_1
	v_mul_f32_e32 v104, 0x38800000, v104
	v_mul_f32_e32 v100, 0x38800000, v100
	s_nop 0
	v_pk_mul_f32 v[106:107], v[12:13], v[100:101] op_sel:[1,0] op_sel_hi:[0,0] neg_lo:[1,0]
	v_cvt_f32_f16_e32 v100, v101
	v_cvt_f32_f16_sdwa v101, v101 dst_sel:DWORD dst_unused:UNUSED_PAD src0_sel:WORD_1
	v_pk_fma_f32 v[12:13], v[12:13], v[104:105], v[106:107] op_sel_hi:[1,0,1]
	v_xor_b32_e32 v106, 0x80000000, v15
	v_mov_b32_e32 v107, v14
	v_mul_f32_e32 v104, 0x38800000, v101
	v_mul_f32_e32 v100, 0x38800000, v100
	v_pk_mul_f32 v[104:105], v[106:107], v[104:105] op_sel_hi:[1,0]
	v_xor_b32_e32 v106, 0x80000000, v21
	v_pk_fma_f32 v[14:15], v[14:15], v[100:101], v[104:105] op_sel_hi:[1,0,1]
	v_cvt_f32_f16_sdwa v101, v102 dst_sel:DWORD dst_unused:UNUSED_PAD src0_sel:WORD_1
	v_cvt_f32_f16_e32 v100, v102
	s_nop 0
	s_nop 0
	v_mul_f32_e32 v102, 0x38800000, v101
	v_mul_f32_e32 v100, 0x38800000, v100
	v_pk_mul_f32 v[104:105], v[16:17], v[102:103] op_sel:[1,0] op_sel_hi:[0,0] neg_lo:[1,0]
	v_mov_b32_e32 v107, v20
	v_pk_fma_f32 v[16:17], v[16:17], v[100:101], v[104:105] op_sel_hi:[1,0,1]
	v_cvt_f32_f16_sdwa v101, v103 dst_sel:DWORD dst_unused:UNUSED_PAD src0_sel:WORD_1
	v_cvt_f32_f16_e32 v100, v103
	v_xor_b32_e32 v104, 0x80000000, v19
	v_mov_b32_e32 v105, v18
	v_mul_f32_e32 v102, 0x38800000, v101
	v_mul_f32_e32 v100, 0x38800000, v100
	v_pk_mul_f32 v[102:103], v[104:105], v[102:103] op_sel_hi:[1,0]
	s_nop 0
	v_pk_fma_f32 v[18:19], v[18:19], v[100:101], v[102:103] op_sel_hi:[1,0,1]
	s_waitcnt vmcnt(6)
	v_mov_b64 v[100:101], v[168:169]
	v_mov_b64 v[102:103], v[170:171]
	v_cvt_f32_f16_e32 v104, v100
	v_cvt_f32_f16_sdwa v100, v100 dst_sel:DWORD dst_unused:UNUSED_PAD src0_sel:WORD_1
	v_mul_f32_e32 v104, 0x38800000, v104
	v_mul_f32_e32 v100, 0x38800000, v100
	v_pk_mul_f32 v[106:107], v[106:107], v[100:101] op_sel_hi:[1,0]
	v_cvt_f32_f16_e32 v100, v101
	v_cvt_f32_f16_sdwa v101, v101 dst_sel:DWORD dst_unused:UNUSED_PAD src0_sel:WORD_1
	v_pk_fma_f32 v[20:21], v[20:21], v[104:105], v[106:107] op_sel_hi:[1,0,1]
	v_xor_b32_e32 v106, 0x80000000, v23
	v_mov_b32_e32 v107, v22
	v_mul_f32_e32 v104, 0x38800000, v101
	v_mul_f32_e32 v100, 0x38800000, v100
	v_pk_mul_f32 v[104:105], v[106:107], v[104:105] op_sel_hi:[1,0]
	v_xor_b32_e32 v106, 0x80000000, v69
	v_pk_fma_f32 v[22:23], v[22:23], v[100:101], v[104:105] op_sel_hi:[1,0,1]
	v_cvt_f32_f16_sdwa v101, v102 dst_sel:DWORD dst_unused:UNUSED_PAD src0_sel:WORD_1
	v_cvt_f32_f16_e32 v100, v102
	s_nop 0
	s_nop 0
	v_mul_f32_e32 v102, 0x38800000, v101
	v_mul_f32_e32 v100, 0x38800000, v100
	v_pk_mul_f32 v[104:105], v[24:25], v[102:103] op_sel:[1,0] op_sel_hi:[0,0] neg_lo:[1,0]
	v_mov_b32_e32 v107, v68
	v_pk_fma_f32 v[24:25], v[24:25], v[100:101], v[104:105] op_sel_hi:[1,0,1]
	v_cvt_f32_f16_sdwa v101, v103 dst_sel:DWORD dst_unused:UNUSED_PAD src0_sel:WORD_1
	v_cvt_f32_f16_e32 v100, v103
	v_xor_b32_e32 v104, 0x80000000, v27
	v_mov_b32_e32 v105, v26
	v_mul_f32_e32 v102, 0x38800000, v101
	v_mul_f32_e32 v100, 0x38800000, v100
	v_pk_mul_f32 v[102:103], v[104:105], v[102:103] op_sel_hi:[1,0]
	s_nop 0
	v_pk_fma_f32 v[26:27], v[26:27], v[100:101], v[102:103] op_sel_hi:[1,0,1]
	s_waitcnt vmcnt(5)
	v_mov_b64 v[100:101], v[172:173]
	v_mov_b64 v[102:103], v[174:175]
	v_cvt_f32_f16_e32 v104, v100
	v_cvt_f32_f16_sdwa v100, v100 dst_sel:DWORD dst_unused:UNUSED_PAD src0_sel:WORD_1
	v_mul_f32_e32 v104, 0x38800000, v104
	v_mul_f32_e32 v100, 0x38800000, v100
	v_pk_mul_f32 v[106:107], v[106:107], v[100:101] op_sel_hi:[1,0]
	v_cvt_f32_f16_e32 v100, v101
	v_cvt_f32_f16_sdwa v101, v101 dst_sel:DWORD dst_unused:UNUSED_PAD src0_sel:WORD_1
	v_pk_fma_f32 v[68:69], v[68:69], v[104:105], v[106:107] op_sel_hi:[1,0,1]
	v_xor_b32_e32 v106, 0x80000000, v71
	v_mov_b32_e32 v107, v70
	v_mul_f32_e32 v104, 0x38800000, v101
	v_mul_f32_e32 v100, 0x38800000, v100
	v_pk_mul_f32 v[104:105], v[106:107], v[104:105] op_sel_hi:[1,0]
	v_xor_b32_e32 v106, 0x80000000, v85
	v_pk_fma_f32 v[70:71], v[70:71], v[100:101], v[104:105] op_sel_hi:[1,0,1]
	v_cvt_f32_f16_sdwa v101, v102 dst_sel:DWORD dst_unused:UNUSED_PAD src0_sel:WORD_1
	v_cvt_f32_f16_e32 v100, v102
	s_nop 0
	s_nop 0
	v_mul_f32_e32 v102, 0x38800000, v101
	v_mul_f32_e32 v100, 0x38800000, v100
	v_pk_mul_f32 v[104:105], v[72:73], v[102:103] op_sel:[1,0] op_sel_hi:[0,0] neg_lo:[1,0]
	v_mov_b32_e32 v107, v84
	v_pk_fma_f32 v[72:73], v[72:73], v[100:101], v[104:105] op_sel_hi:[1,0,1]
	v_cvt_f32_f16_sdwa v101, v103 dst_sel:DWORD dst_unused:UNUSED_PAD src0_sel:WORD_1
	v_cvt_f32_f16_e32 v100, v103
	v_xor_b32_e32 v104, 0x80000000, v75
	v_mov_b32_e32 v105, v74
	v_mul_f32_e32 v102, 0x38800000, v101
	v_mul_f32_e32 v100, 0x38800000, v100
	v_pk_mul_f32 v[102:103], v[104:105], v[102:103] op_sel_hi:[1,0]
	s_nop 0
	v_pk_fma_f32 v[74:75], v[74:75], v[100:101], v[102:103] op_sel_hi:[1,0,1]
	s_waitcnt vmcnt(4)
	v_mov_b64 v[100:101], v[176:177]
	v_mov_b64 v[102:103], v[178:179]
	v_cvt_f32_f16_e32 v104, v100
	v_cvt_f32_f16_sdwa v100, v100 dst_sel:DWORD dst_unused:UNUSED_PAD src0_sel:WORD_1
	v_mul_f32_e32 v104, 0x38800000, v104
	v_mul_f32_e32 v100, 0x38800000, v100
	v_pk_mul_f32 v[106:107], v[106:107], v[100:101] op_sel_hi:[1,0]
	v_cvt_f32_f16_e32 v100, v101
	v_cvt_f32_f16_sdwa v101, v101 dst_sel:DWORD dst_unused:UNUSED_PAD src0_sel:WORD_1
	v_pk_fma_f32 v[84:85], v[84:85], v[104:105], v[106:107] op_sel_hi:[1,0,1]
	v_xor_b32_e32 v106, 0x80000000, v87
	v_mov_b32_e32 v107, v86
	v_mul_f32_e32 v104, 0x38800000, v101
	v_mul_f32_e32 v100, 0x38800000, v100
	v_pk_mul_f32 v[104:105], v[106:107], v[104:105] op_sel_hi:[1,0]
	v_xor_b32_e32 v106, 0x80000000, v99
	v_pk_fma_f32 v[86:87], v[86:87], v[100:101], v[104:105] op_sel_hi:[1,0,1]
	v_cvt_f32_f16_sdwa v101, v102 dst_sel:DWORD dst_unused:UNUSED_PAD src0_sel:WORD_1
	v_cvt_f32_f16_e32 v100, v102
	s_nop 0
	s_nop 0
	v_mul_f32_e32 v102, 0x38800000, v101
	v_mul_f32_e32 v100, 0x38800000, v100
	v_pk_mul_f32 v[104:105], v[88:89], v[102:103] op_sel:[1,0] op_sel_hi:[0,0] neg_lo:[1,0]
	v_mov_b32_e32 v107, v98
	v_pk_fma_f32 v[88:89], v[88:89], v[100:101], v[104:105] op_sel_hi:[1,0,1]
	v_cvt_f32_f16_sdwa v101, v103 dst_sel:DWORD dst_unused:UNUSED_PAD src0_sel:WORD_1
	v_cvt_f32_f16_e32 v100, v103
	v_xor_b32_e32 v104, 0x80000000, v91
	v_mov_b32_e32 v105, v90
	v_mul_f32_e32 v102, 0x38800000, v101
	v_mul_f32_e32 v100, 0x38800000, v100
	v_pk_mul_f32 v[102:103], v[104:105], v[102:103] op_sel_hi:[1,0]
	s_nop 0
	v_pk_fma_f32 v[90:91], v[90:91], v[100:101], v[102:103] op_sel_hi:[1,0,1]
	s_waitcnt vmcnt(3)
	v_mov_b64 v[100:101], v[180:181]
	v_mov_b64 v[102:103], v[182:183]
	v_cvt_f32_f16_e32 v104, v100
	v_cvt_f32_f16_sdwa v100, v100 dst_sel:DWORD dst_unused:UNUSED_PAD src0_sel:WORD_1
	v_mul_f32_e32 v104, 0x38800000, v104
	v_mul_f32_e32 v100, 0x38800000, v100
	v_pk_mul_f32 v[106:107], v[106:107], v[100:101] op_sel_hi:[1,0]
	v_cvt_f32_f16_e32 v100, v101
	v_cvt_f32_f16_sdwa v101, v101 dst_sel:DWORD dst_unused:UNUSED_PAD src0_sel:WORD_1
	v_pk_fma_f32 v[98:99], v[98:99], v[104:105], v[106:107] op_sel_hi:[1,0,1]
	v_xor_b32_e32 v106, 0x80000000, v97
	v_mov_b32_e32 v107, v96
	v_mul_f32_e32 v104, 0x38800000, v101
	v_mul_f32_e32 v100, 0x38800000, v100
	v_pk_mul_f32 v[104:105], v[106:107], v[104:105] op_sel_hi:[1,0]
	v_xor_b32_e32 v106, 0x80000000, v83
	v_pk_fma_f32 v[96:97], v[96:97], v[100:101], v[104:105] op_sel_hi:[1,0,1]
	v_cvt_f32_f16_sdwa v101, v102 dst_sel:DWORD dst_unused:UNUSED_PAD src0_sel:WORD_1
	v_cvt_f32_f16_e32 v100, v102
	s_nop 0
	s_nop 0
	v_mul_f32_e32 v102, 0x38800000, v101
	v_mul_f32_e32 v100, 0x38800000, v100
	v_pk_mul_f32 v[104:105], v[94:95], v[102:103] op_sel:[1,0] op_sel_hi:[0,0] neg_lo:[1,0]
	v_mov_b32_e32 v107, v82
	v_pk_fma_f32 v[94:95], v[94:95], v[100:101], v[104:105] op_sel_hi:[1,0,1]
	v_cvt_f32_f16_sdwa v101, v103 dst_sel:DWORD dst_unused:UNUSED_PAD src0_sel:WORD_1
	v_cvt_f32_f16_e32 v100, v103
	v_xor_b32_e32 v104, 0x80000000, v93
	v_mov_b32_e32 v105, v92
	v_mul_f32_e32 v102, 0x38800000, v101
	v_mul_f32_e32 v100, 0x38800000, v100
	v_pk_mul_f32 v[102:103], v[104:105], v[102:103] op_sel_hi:[1,0]
	s_nop 0
	v_pk_fma_f32 v[92:93], v[92:93], v[100:101], v[102:103] op_sel_hi:[1,0,1]
	s_waitcnt vmcnt(2)
	v_mov_b64 v[100:101], v[184:185]
	v_mov_b64 v[102:103], v[186:187]
	v_cvt_f32_f16_e32 v104, v100
	v_cvt_f32_f16_sdwa v100, v100 dst_sel:DWORD dst_unused:UNUSED_PAD src0_sel:WORD_1
	v_mul_f32_e32 v104, 0x38800000, v104
	v_mul_f32_e32 v100, 0x38800000, v100
	v_pk_mul_f32 v[106:107], v[106:107], v[100:101] op_sel_hi:[1,0]
	v_cvt_f32_f16_e32 v100, v101
	v_cvt_f32_f16_sdwa v101, v101 dst_sel:DWORD dst_unused:UNUSED_PAD src0_sel:WORD_1
	v_pk_fma_f32 v[82:83], v[82:83], v[104:105], v[106:107] op_sel_hi:[1,0,1]
	v_xor_b32_e32 v106, 0x80000000, v81
	v_mov_b32_e32 v107, v80
	v_mul_f32_e32 v104, 0x38800000, v101
	v_mul_f32_e32 v100, 0x38800000, v100
	v_pk_mul_f32 v[104:105], v[106:107], v[104:105] op_sel_hi:[1,0]
	v_xor_b32_e32 v106, 0x80000000, v67
	v_pk_fma_f32 v[80:81], v[80:81], v[100:101], v[104:105] op_sel_hi:[1,0,1]
	v_cvt_f32_f16_sdwa v101, v102 dst_sel:DWORD dst_unused:UNUSED_PAD src0_sel:WORD_1
	v_cvt_f32_f16_e32 v100, v102
	s_nop 0
	s_nop 0
	v_mul_f32_e32 v102, 0x38800000, v101
	v_mul_f32_e32 v100, 0x38800000, v100
	v_pk_mul_f32 v[104:105], v[78:79], v[102:103] op_sel:[1,0] op_sel_hi:[0,0] neg_lo:[1,0]
	v_mov_b32_e32 v107, v66
	v_pk_fma_f32 v[78:79], v[78:79], v[100:101], v[104:105] op_sel_hi:[1,0,1]
	v_cvt_f32_f16_sdwa v101, v103 dst_sel:DWORD dst_unused:UNUSED_PAD src0_sel:WORD_1
	v_cvt_f32_f16_e32 v100, v103
	v_xor_b32_e32 v104, 0x80000000, v77
	v_mov_b32_e32 v105, v76
	v_mul_f32_e32 v102, 0x38800000, v101
	v_mul_f32_e32 v100, 0x38800000, v100
	v_pk_mul_f32 v[102:103], v[104:105], v[102:103] op_sel_hi:[1,0]
	s_nop 0
	v_pk_fma_f32 v[76:77], v[76:77], v[100:101], v[102:103] op_sel_hi:[1,0,1]
	s_waitcnt vmcnt(1)
	v_mov_b64 v[100:101], v[188:189]
	v_mov_b64 v[102:103], v[190:191]
	v_cvt_f32_f16_e32 v104, v100
	v_cvt_f32_f16_sdwa v100, v100 dst_sel:DWORD dst_unused:UNUSED_PAD src0_sel:WORD_1
	v_mul_f32_e32 v104, 0x38800000, v104
	v_mul_f32_e32 v100, 0x38800000, v100
	v_pk_mul_f32 v[106:107], v[106:107], v[100:101] op_sel_hi:[1,0]
	v_cvt_f32_f16_e32 v100, v101
	v_cvt_f32_f16_sdwa v101, v101 dst_sel:DWORD dst_unused:UNUSED_PAD src0_sel:WORD_1
	v_pk_fma_f32 v[66:67], v[66:67], v[104:105], v[106:107] op_sel_hi:[1,0,1]
	v_xor_b32_e32 v106, 0x80000000, v65
	v_mov_b32_e32 v107, v64
	v_mul_f32_e32 v104, 0x38800000, v101
	v_mul_f32_e32 v100, 0x38800000, v100
	v_pk_mul_f32 v[104:105], v[106:107], v[104:105] op_sel_hi:[1,0]
	s_nop 0
	v_pk_fma_f32 v[64:65], v[64:65], v[100:101], v[104:105] op_sel_hi:[1,0,1]
	v_cvt_f32_f16_sdwa v101, v102 dst_sel:DWORD dst_unused:UNUSED_PAD src0_sel:WORD_1
	v_cvt_f32_f16_e32 v100, v102
	s_nop 0
	s_nop 0
	v_mul_f32_e32 v102, 0x38800000, v101
	v_mul_f32_e32 v100, 0x38800000, v100
	v_pk_mul_f32 v[104:105], v[62:63], v[102:103] op_sel:[1,0] op_sel_hi:[0,0] neg_lo:[1,0]
	s_nop 0
	v_pk_fma_f32 v[62:63], v[62:63], v[100:101], v[104:105] op_sel_hi:[1,0,1]
	v_cvt_f32_f16_sdwa v101, v103 dst_sel:DWORD dst_unused:UNUSED_PAD src0_sel:WORD_1
	v_cvt_f32_f16_e32 v100, v103
	v_xor_b32_e32 v104, 0x80000000, v3
	v_mov_b32_e32 v105, v2
	v_mul_f32_e32 v102, 0x38800000, v101
	v_mul_f32_e32 v100, 0x38800000, v100
	v_pk_mul_f32 v[102:103], v[104:105], v[102:103] op_sel_hi:[1,0]
	v_xor_b32_e32 v104, 0x80000000, v11
	v_pk_fma_f32 v[100:101], v[2:3], v[100:101], v[102:103] op_sel_hi:[1,0,1]
	s_waitcnt vmcnt(0)
	v_mov_b64 v[0:1], v[192:193]
	v_mov_b64 v[2:3], v[194:195]
	v_mov_b32_e32 v105, v10
	v_cvt_f32_f16_e32 v102, v0
	v_cvt_f32_f16_sdwa v0, v0 dst_sel:DWORD dst_unused:UNUSED_PAD src0_sel:WORD_1
	v_mul_f32_e32 v102, 0x38800000, v102
	v_mul_f32_e32 v0, 0x38800000, v0
	v_pk_mul_f32 v[104:105], v[104:105], v[0:1] op_sel_hi:[1,0]
	v_cvt_f32_f16_e32 v0, v1
	v_cvt_f32_f16_sdwa v1, v1 dst_sel:DWORD dst_unused:UNUSED_PAD src0_sel:WORD_1
	v_pk_fma_f32 v[10:11], v[10:11], v[102:103], v[104:105] op_sel_hi:[1,0,1]
	v_xor_b32_e32 v104, 0x80000000, v9
	v_mov_b32_e32 v105, v8
	v_mul_f32_e32 v102, 0x38800000, v1
	v_mul_f32_e32 v0, 0x38800000, v0
	v_pk_mul_f32 v[102:103], v[104:105], v[102:103] op_sel_hi:[1,0]
	s_nop 0
	v_pk_fma_f32 v[0:1], v[8:9], v[0:1], v[102:103] op_sel_hi:[1,0,1]
	v_cvt_f32_f16_e32 v8, v2
	v_cvt_f32_f16_sdwa v2, v2 dst_sel:DWORD dst_unused:UNUSED_PAD src0_sel:WORD_1
	s_nop 0
	s_nop 0
	v_mul_f32_e32 v8, 0x38800000, v8
	v_mul_f32_e32 v2, 0x38800000, v2
	s_nop 0
	v_pk_mul_f32 v[102:103], v[6:7], v[2:3] op_sel:[1,0] op_sel_hi:[0,0] neg_lo:[1,0]
	v_cvt_f32_f16_e32 v2, v3
	v_cvt_f32_f16_sdwa v3, v3 dst_sel:DWORD dst_unused:UNUSED_PAD src0_sel:WORD_1
	v_pk_fma_f32 v[6:7], v[6:7], v[8:9], v[102:103] op_sel_hi:[1,0,1]
	v_xor_b32_e32 v102, 0x80000000, v5
	v_mov_b32_e32 v103, v4
	v_mul_f32_e32 v8, 0x38800000, v3
	v_mul_f32_e32 v2, 0x38800000, v2
	v_pk_mul_f32 v[8:9], v[102:103], v[8:9] op_sel_hi:[1,0]
	v_mov_b32_e32 v102, v146
	v_pk_fma_f32 v[2:3], v[4:5], v[2:3], v[8:9] op_sel_hi:[1,0,1]
	v_pk_add_f32 v[4:5], v[12:13], v[14:15]
	v_pk_add_f32 v[8:9], v[12:13], v[14:15] neg_lo:[0,1] neg_hi:[0,1]
	v_pk_add_f32 v[12:13], v[16:17], v[18:19]
	v_pk_add_f32 v[14:15], v[16:17], v[18:19] neg_lo:[0,1] neg_hi:[0,1]
	v_pk_add_f32 v[16:17], v[20:21], v[22:23]
	v_pk_add_f32 v[18:19], v[20:21], v[22:23] neg_lo:[0,1] neg_hi:[0,1]
	v_pk_add_f32 v[20:21], v[24:25], v[26:27]
	v_pk_add_f32 v[22:23], v[24:25], v[26:27] neg_lo:[0,1] neg_hi:[0,1]
	v_pk_add_f32 v[24:25], v[68:69], v[70:71]
	v_pk_add_f32 v[26:27], v[68:69], v[70:71] neg_lo:[0,1] neg_hi:[0,1]
	v_pk_add_f32 v[68:69], v[72:73], v[74:75]
	v_pk_add_f32 v[70:71], v[72:73], v[74:75] neg_lo:[0,1] neg_hi:[0,1]
	v_pk_add_f32 v[72:73], v[84:85], v[86:87]
	v_pk_add_f32 v[74:75], v[84:85], v[86:87] neg_lo:[0,1] neg_hi:[0,1]
	v_pk_add_f32 v[84:85], v[88:89], v[90:91]
	v_pk_add_f32 v[86:87], v[88:89], v[90:91] neg_lo:[0,1] neg_hi:[0,1]
	v_pk_add_f32 v[88:89], v[4:5], v[12:13]
	v_pk_add_f32 v[4:5], v[4:5], v[12:13] neg_lo:[0,1] neg_hi:[0,1]
	v_xor_b32_e32 v12, 0x80000000, v15
	v_mov_b32_e32 v13, v14
	v_pk_add_f32 v[14:15], v[8:9], v[12:13]
	v_pk_add_f32 v[8:9], v[8:9], v[12:13] neg_lo:[0,1] neg_hi:[0,1]
	v_pk_add_f32 v[12:13], v[16:17], v[20:21]
	v_pk_add_f32 v[16:17], v[16:17], v[20:21] neg_lo:[0,1] neg_hi:[0,1]
	v_xor_b32_e32 v20, 0x80000000, v23
	v_mov_b32_e32 v21, v22
	v_pk_add_f32 v[22:23], v[18:19], v[20:21]
	v_pk_add_f32 v[18:19], v[18:19], v[20:21] neg_lo:[0,1] neg_hi:[0,1]
	v_pk_add_f32 v[20:21], v[24:25], v[68:69]
	v_pk_add_f32 v[24:25], v[24:25], v[68:69] neg_lo:[0,1] neg_hi:[0,1]
	v_xor_b32_e32 v68, 0x80000000, v71
	v_mov_b32_e32 v69, v70
	v_pk_add_f32 v[70:71], v[26:27], v[68:69]
	v_pk_add_f32 v[26:27], v[26:27], v[68:69] neg_lo:[0,1] neg_hi:[0,1]
	v_pk_add_f32 v[68:69], v[72:73], v[84:85]
	v_pk_add_f32 v[72:73], v[72:73], v[84:85] neg_lo:[0,1] neg_hi:[0,1]
	v_xor_b32_e32 v84, 0x80000000, v87
	v_mov_b32_e32 v85, v86
	v_pk_add_f32 v[86:87], v[74:75], v[84:85]
	v_pk_add_f32 v[74:75], v[74:75], v[84:85] neg_lo:[0,1] neg_hi:[0,1]
	v_pk_add_f32 v[84:85], v[88:89], v[12:13]
	v_pk_add_f32 v[12:13], v[88:89], v[12:13] neg_lo:[0,1] neg_hi:[0,1]
	v_pk_mul_f32 v[88:89], v[22:23], s[70:71] op_sel:[1,0] op_sel_hi:[0,0] neg_lo:[1,0]
	v_xor_b32_e32 v90, 0x80000000, v19
	v_pk_fma_f32 v[22:23], v[22:23], s[70:71], v[88:89] op_sel_hi:[1,0,1]
	v_mov_b32_e32 v91, v18
	v_pk_add_f32 v[88:89], v[14:15], v[22:23]
	v_pk_add_f32 v[14:15], v[14:15], v[22:23] neg_lo:[0,1] neg_hi:[0,1]
	v_xor_b32_e32 v22, 0x80000000, v17
	v_mov_b32_e32 v23, v16
	v_pk_add_f32 v[16:17], v[4:5], v[22:23]
	v_pk_add_f32 v[4:5], v[4:5], v[22:23] neg_lo:[0,1] neg_hi:[0,1]
	v_pk_mul_f32 v[22:23], v[18:19], s[70:71] op_sel_hi:[1,0]
	s_nop 0
	v_pk_fma_f32 v[18:19], v[90:91], s[70:71], v[22:23] op_sel_hi:[1,0,1] neg_lo:[0,0,1] neg_hi:[0,0,1]
	v_xor_b32_e32 v90, 0x80000000, v75
	v_pk_add_f32 v[22:23], v[8:9], v[18:19]
	v_pk_add_f32 v[8:9], v[8:9], v[18:19] neg_lo:[0,1] neg_hi:[0,1]
	v_pk_add_f32 v[18:19], v[20:21], v[68:69]
	v_pk_add_f32 v[20:21], v[20:21], v[68:69] neg_lo:[0,1] neg_hi:[0,1]
	v_pk_mul_f32 v[68:69], v[86:87], s[70:71] op_sel:[1,0] op_sel_hi:[0,0] neg_lo:[1,0]
	v_mov_b32_e32 v91, v74
	v_pk_fma_f32 v[68:69], v[86:87], s[70:71], v[68:69] op_sel_hi:[1,0,1]
	s_nop 0
	v_pk_add_f32 v[86:87], v[70:71], v[68:69]
	v_pk_add_f32 v[68:69], v[70:71], v[68:69] neg_lo:[0,1] neg_hi:[0,1]
	v_xor_b32_e32 v70, 0x80000000, v73
	v_mov_b32_e32 v71, v72
	v_pk_add_f32 v[72:73], v[24:25], v[70:71]
	v_pk_add_f32 v[24:25], v[24:25], v[70:71] neg_lo:[0,1] neg_hi:[0,1]
	v_pk_mul_f32 v[70:71], v[74:75], s[70:71] op_sel_hi:[1,0]
	s_nop 0
	v_pk_fma_f32 v[70:71], v[90:91], s[70:71], v[70:71] op_sel_hi:[1,0,1] neg_lo:[0,0,1] neg_hi:[0,0,1]
	v_xor_b32_e32 v90, 0x80000000, v69
	v_pk_add_f32 v[74:75], v[26:27], v[70:71]
	v_pk_add_f32 v[26:27], v[26:27], v[70:71] neg_lo:[0,1] neg_hi:[0,1]
	v_pk_add_f32 v[70:71], v[84:85], v[18:19]
	v_pk_add_f32 v[18:19], v[84:85], v[18:19] neg_lo:[0,1] neg_hi:[0,1]
	v_pk_mul_f32 v[84:85], v[86:87], s[62:63] op_sel:[1,0] op_sel_hi:[0,0] neg_lo:[1,0]
	v_mov_b32_e32 v91, v68
	v_pk_fma_f32 v[84:85], v[86:87], s[60:61], v[84:85] op_sel_hi:[1,0,1]
	s_nop 0
	v_pk_add_f32 v[86:87], v[88:89], v[84:85]
	v_pk_add_f32 v[84:85], v[88:89], v[84:85] neg_lo:[0,1] neg_hi:[0,1]
	v_pk_mul_f32 v[88:89], v[72:73], s[70:71] op_sel:[1,0] op_sel_hi:[0,0] neg_lo:[1,0]
	s_nop 0
	v_pk_fma_f32 v[72:73], v[72:73], s[70:71], v[88:89] op_sel_hi:[1,0,1]
	s_nop 0
	v_pk_add_f32 v[88:89], v[16:17], v[72:73]
	v_pk_add_f32 v[16:17], v[16:17], v[72:73] neg_lo:[0,1] neg_hi:[0,1]
	v_pk_mul_f32 v[72:73], v[74:75], s[60:61] op_sel:[1,0] op_sel_hi:[0,0] neg_lo:[1,0]
	s_nop 0
	v_pk_fma_f32 v[72:73], v[74:75], s[62:63], v[72:73] op_sel_hi:[1,0,1]
	s_nop 0
	v_pk_add_f32 v[74:75], v[22:23], v[72:73]
	v_pk_add_f32 v[22:23], v[22:23], v[72:73] neg_lo:[0,1] neg_hi:[0,1]
	v_xor_b32_e32 v72, 0x80000000, v21
	v_mov_b32_e32 v73, v20
	v_pk_add_f32 v[20:21], v[12:13], v[72:73]
	v_pk_add_f32 v[12:13], v[12:13], v[72:73] neg_lo:[0,1] neg_hi:[0,1]
	v_pk_mul_f32 v[72:73], v[68:69], s[62:63] op_sel_hi:[1,0]
	s_nop 0
	v_pk_fma_f32 v[68:69], v[90:91], s[60:61], v[72:73] op_sel_hi:[1,0,1] neg_lo:[0,0,1] neg_hi:[0,0,1]
	v_xor_b32_e32 v90, 0x80000000, v25
	v_pk_add_f32 v[72:73], v[14:15], v[68:69]
	v_pk_add_f32 v[14:15], v[14:15], v[68:69] neg_lo:[0,1] neg_hi:[0,1]
	v_pk_mul_f32 v[68:69], v[24:25], s[70:71] op_sel_hi:[1,0]
	v_mov_b32_e32 v91, v24
	v_pk_fma_f32 v[24:25], v[90:91], s[70:71], v[68:69] op_sel_hi:[1,0,1] neg_lo:[0,0,1] neg_hi:[0,0,1]
	s_nop 0
	v_pk_add_f32 v[68:69], v[4:5], v[24:25]
	v_pk_add_f32 v[4:5], v[4:5], v[24:25] neg_lo:[0,1] neg_hi:[0,1]
	v_pk_mul_f32 v[24:25], v[26:27], s[60:61] op_sel_hi:[1,0]
	s_nop 0
	v_pk_fma_f32 v[24:25], v[26:27], s[62:63], v[24:25] op_sel:[1,0,0] op_sel_hi:[0,0,1] neg_lo:[1,0,1] neg_hi:[0,0,1]
	v_pk_add_f32 v[90:91], v[98:99], v[96:97] neg_lo:[0,1] neg_hi:[0,1]
	v_pk_add_f32 v[26:27], v[8:9], v[24:25]
	v_pk_add_f32 v[8:9], v[8:9], v[24:25] neg_lo:[0,1] neg_hi:[0,1]
	v_pk_add_f32 v[24:25], v[98:99], v[96:97]
	v_pk_add_f32 v[96:97], v[94:95], v[92:93]
	v_pk_add_f32 v[92:93], v[94:95], v[92:93] neg_lo:[0,1] neg_hi:[0,1]
	v_pk_add_f32 v[94:95], v[82:83], v[80:81]
	v_pk_add_f32 v[80:81], v[82:83], v[80:81] neg_lo:[0,1] neg_hi:[0,1]
	v_pk_add_f32 v[82:83], v[78:79], v[76:77]
	v_pk_add_f32 v[76:77], v[78:79], v[76:77] neg_lo:[0,1] neg_hi:[0,1]
	v_pk_add_f32 v[98:99], v[10:11], v[0:1]
	v_pk_add_f32 v[0:1], v[10:11], v[0:1] neg_lo:[0,1] neg_hi:[0,1]
	v_pk_add_f32 v[10:11], v[6:7], v[2:3]
	v_pk_add_f32 v[2:3], v[6:7], v[2:3] neg_lo:[0,1] neg_hi:[0,1]
	v_pk_add_f32 v[6:7], v[24:25], v[96:97]
	v_pk_add_f32 v[24:25], v[24:25], v[96:97] neg_lo:[0,1] neg_hi:[0,1]
	v_xor_b32_e32 v96, 0x80000000, v93
	v_mov_b32_e32 v97, v92
	v_pk_add_f32 v[78:79], v[66:67], v[64:65]
	v_pk_add_f32 v[64:65], v[66:67], v[64:65] neg_lo:[0,1] neg_hi:[0,1]
	v_pk_add_f32 v[66:67], v[62:63], v[100:101]
	v_pk_add_f32 v[62:63], v[62:63], v[100:101] neg_lo:[0,1] neg_hi:[0,1]
	v_pk_add_f32 v[92:93], v[90:91], v[96:97]
	v_pk_add_f32 v[90:91], v[90:91], v[96:97] neg_lo:[0,1] neg_hi:[0,1]
	v_pk_add_f32 v[96:97], v[94:95], v[82:83]
	v_pk_add_f32 v[82:83], v[94:95], v[82:83] neg_lo:[0,1] neg_hi:[0,1]
	v_xor_b32_e32 v94, 0x80000000, v77
	v_mov_b32_e32 v95, v76
	v_pk_add_f32 v[76:77], v[80:81], v[94:95]
	v_pk_add_f32 v[80:81], v[80:81], v[94:95] neg_lo:[0,1] neg_hi:[0,1]
	v_pk_add_f32 v[94:95], v[78:79], v[66:67]
	v_pk_add_f32 v[66:67], v[78:79], v[66:67] neg_lo:[0,1] neg_hi:[0,1]
	v_xor_b32_e32 v78, 0x80000000, v63
	v_mov_b32_e32 v79, v62
	v_pk_add_f32 v[62:63], v[64:65], v[78:79]
	v_pk_add_f32 v[64:65], v[64:65], v[78:79] neg_lo:[0,1] neg_hi:[0,1]
	v_pk_add_f32 v[78:79], v[98:99], v[10:11]
	v_pk_add_f32 v[10:11], v[98:99], v[10:11] neg_lo:[0,1] neg_hi:[0,1]
	v_xor_b32_e32 v98, 0x80000000, v3
	v_mov_b32_e32 v99, v2
	v_pk_add_f32 v[2:3], v[0:1], v[98:99]
	v_pk_add_f32 v[0:1], v[0:1], v[98:99] neg_lo:[0,1] neg_hi:[0,1]
	v_pk_add_f32 v[98:99], v[6:7], v[96:97]
	v_pk_add_f32 v[6:7], v[6:7], v[96:97] neg_lo:[0,1] neg_hi:[0,1]
	v_pk_mul_f32 v[96:97], v[76:77], s[70:71] op_sel:[1,0] op_sel_hi:[0,0] neg_lo:[1,0]
	v_xor_b32_e32 v100, 0x80000000, v81
	v_pk_fma_f32 v[76:77], v[76:77], s[70:71], v[96:97] op_sel_hi:[1,0,1]
	v_mov_b32_e32 v101, v80
	v_pk_add_f32 v[96:97], v[92:93], v[76:77]
	v_pk_add_f32 v[76:77], v[92:93], v[76:77] neg_lo:[0,1] neg_hi:[0,1]
	v_xor_b32_e32 v92, 0x80000000, v83
	v_mov_b32_e32 v93, v82
	v_pk_add_f32 v[82:83], v[24:25], v[92:93]
	v_pk_add_f32 v[24:25], v[24:25], v[92:93] neg_lo:[0,1] neg_hi:[0,1]
	v_pk_mul_f32 v[92:93], v[80:81], s[70:71] op_sel_hi:[1,0]
	s_nop 0
	v_pk_fma_f32 v[80:81], v[100:101], s[70:71], v[92:93] op_sel_hi:[1,0,1] neg_lo:[0,0,1] neg_hi:[0,0,1]
	v_xor_b32_e32 v100, 0x80000000, v1
	v_pk_add_f32 v[92:93], v[90:91], v[80:81]
	v_pk_add_f32 v[80:81], v[90:91], v[80:81] neg_lo:[0,1] neg_hi:[0,1]
	v_pk_add_f32 v[90:91], v[94:95], v[78:79]
	v_pk_add_f32 v[78:79], v[94:95], v[78:79] neg_lo:[0,1] neg_hi:[0,1]
	v_pk_mul_f32 v[94:95], v[2:3], s[70:71] op_sel:[1,0] op_sel_hi:[0,0] neg_lo:[1,0]
	v_mov_b32_e32 v101, v0
	v_pk_fma_f32 v[2:3], v[2:3], s[70:71], v[94:95] op_sel_hi:[1,0,1]
	s_nop 0
	v_pk_add_f32 v[94:95], v[62:63], v[2:3]
	v_pk_add_f32 v[2:3], v[62:63], v[2:3] neg_lo:[0,1] neg_hi:[0,1]
	v_xor_b32_e32 v62, 0x80000000, v11
	v_mov_b32_e32 v63, v10
	v_pk_add_f32 v[10:11], v[66:67], v[62:63]
	v_pk_add_f32 v[62:63], v[66:67], v[62:63] neg_lo:[0,1] neg_hi:[0,1]
	v_pk_mul_f32 v[66:67], v[0:1], s[70:71] op_sel_hi:[1,0]
	s_nop 0
	v_pk_fma_f32 v[0:1], v[100:101], s[70:71], v[66:67] op_sel_hi:[1,0,1] neg_lo:[0,0,1] neg_hi:[0,0,1]
	v_xor_b32_e32 v100, 0x80000000, v3
	v_pk_add_f32 v[66:67], v[64:65], v[0:1]
	v_pk_add_f32 v[0:1], v[64:65], v[0:1] neg_lo:[0,1] neg_hi:[0,1]
	v_pk_add_f32 v[64:65], v[98:99], v[90:91]
	v_pk_add_f32 v[90:91], v[98:99], v[90:91] neg_lo:[0,1] neg_hi:[0,1]
	v_pk_mul_f32 v[98:99], v[94:95], s[62:63] op_sel:[1,0] op_sel_hi:[0,0] neg_lo:[1,0]
	v_mov_b32_e32 v101, v2
	v_pk_fma_f32 v[94:95], v[94:95], s[60:61], v[98:99] op_sel_hi:[1,0,1]
	s_nop 0
	v_pk_add_f32 v[98:99], v[96:97], v[94:95]
	v_pk_add_f32 v[94:95], v[96:97], v[94:95] neg_lo:[0,1] neg_hi:[0,1]
	v_pk_mul_f32 v[96:97], v[10:11], s[70:71] op_sel:[1,0] op_sel_hi:[0,0] neg_lo:[1,0]
	s_nop 0
	v_pk_fma_f32 v[10:11], v[10:11], s[70:71], v[96:97] op_sel_hi:[1,0,1]
	s_nop 0
	v_pk_add_f32 v[96:97], v[82:83], v[10:11]
	v_pk_add_f32 v[10:11], v[82:83], v[10:11] neg_lo:[0,1] neg_hi:[0,1]
	v_pk_mul_f32 v[82:83], v[66:67], s[60:61] op_sel:[1,0] op_sel_hi:[0,0] neg_lo:[1,0]
	s_nop 0
	v_pk_fma_f32 v[66:67], v[66:67], s[62:63], v[82:83] op_sel_hi:[1,0,1]
	s_nop 0
	v_pk_add_f32 v[82:83], v[92:93], v[66:67]
	v_pk_add_f32 v[66:67], v[92:93], v[66:67] neg_lo:[0,1] neg_hi:[0,1]
	v_xor_b32_e32 v92, 0x80000000, v79
	v_mov_b32_e32 v93, v78
	v_pk_add_f32 v[78:79], v[6:7], v[92:93]
	v_pk_add_f32 v[6:7], v[6:7], v[92:93] neg_lo:[0,1] neg_hi:[0,1]
	v_pk_mul_f32 v[92:93], v[2:3], s[62:63] op_sel_hi:[1,0]
	s_nop 0
	v_pk_fma_f32 v[2:3], v[100:101], s[60:61], v[92:93] op_sel_hi:[1,0,1] neg_lo:[0,0,1] neg_hi:[0,0,1]
	v_xor_b32_e32 v100, 0x80000000, v63
	v_pk_add_f32 v[92:93], v[76:77], v[2:3]
	v_pk_add_f32 v[2:3], v[76:77], v[2:3] neg_lo:[0,1] neg_hi:[0,1]
	v_pk_mul_f32 v[76:77], v[62:63], s[70:71] op_sel_hi:[1,0]
	v_mov_b32_e32 v101, v62
	v_pk_fma_f32 v[62:63], v[100:101], s[70:71], v[76:77] op_sel_hi:[1,0,1] neg_lo:[0,0,1] neg_hi:[0,0,1]
	v_xor_b32_e32 v100, 0x80000000, v1
	v_pk_add_f32 v[76:77], v[24:25], v[62:63]
	v_pk_add_f32 v[24:25], v[24:25], v[62:63] neg_lo:[0,1] neg_hi:[0,1]
	v_pk_mul_f32 v[62:63], v[0:1], s[60:61] op_sel_hi:[1,0]
	v_mov_b32_e32 v101, v0
	v_pk_fma_f32 v[0:1], v[100:101], s[62:63], v[62:63] op_sel_hi:[1,0,1] neg_lo:[0,0,1] neg_hi:[0,0,1]
	v_bfe_u32 v100, v102, 1, 4
	v_pk_add_f32 v[62:63], v[80:81], v[0:1]
	v_pk_add_f32 v[0:1], v[80:81], v[0:1] neg_lo:[0,1] neg_hi:[0,1]
	v_lshlrev_b32_e32 v80, 4, v102
	v_lshrrev_b32_e32 v81, 1, v102
	v_bitop3_b32 v101, v81, v80, 16 bitop3:0x6c
	v_lshl_add_u32 v101, v101, 3, 16
	v_lshlrev_b32_e32 v100, 3, v100
	v_add_u32_e32 v102, v101, v100
	ds_write_b64 v102, v[70:71]
	v_bitop3_b32 v70, v81, 1, 15 bitop3:0x6c
	v_lshlrev_b32_e32 v70, 3, v70
	v_add_u32_e32 v71, v101, v70
	ds_write_b64 v71, v[86:87]
	v_bitop3_b32 v71, v81, 2, 15 bitop3:0x6c
	v_lshlrev_b32_e32 v71, 3, v71
	v_add_u32_e32 v86, v101, v71
	ds_write_b64 v86, v[88:89]
	v_bitop3_b32 v86, v81, 3, 15 bitop3:0x6c
	v_lshlrev_b32_e32 v86, 3, v86
	v_add_u32_e32 v87, v101, v86
	ds_write_b64 v87, v[74:75]
	v_bitop3_b32 v74, v81, 4, 15 bitop3:0x6c
	v_lshlrev_b32_e32 v74, 3, v74
	v_add_u32_e32 v75, v101, v74
	ds_write_b64 v75, v[20:21]
	v_bitop3_b32 v20, v81, 5, 15 bitop3:0x6c
	v_lshlrev_b32_e32 v20, 3, v20
	v_add_u32_e32 v21, v101, v20
	ds_write_b64 v21, v[72:73]
	v_bitop3_b32 v21, v81, 6, 15 bitop3:0x6c
	v_lshlrev_b32_e32 v21, 3, v21
	v_add_u32_e32 v72, v101, v21
	ds_write_b64 v72, v[68:69]
	v_bitop3_b32 v68, v81, 7, 15 bitop3:0x6c
	v_lshlrev_b32_e32 v68, 3, v68
	v_add_u32_e32 v69, v101, v68
	ds_write_b64 v69, v[26:27]
	v_bitop3_b32 v26, v81, 8, 15 bitop3:0x6c
	v_lshlrev_b32_e32 v26, 3, v26
	v_add_u32_e32 v27, v101, v26
	ds_write_b64 v27, v[18:19]
	v_bitop3_b32 v18, v81, 9, 15 bitop3:0x6c
	v_lshlrev_b32_e32 v18, 3, v18
	v_add_u32_e32 v19, v101, v18
	ds_write_b64 v19, v[84:85]
	v_bitop3_b32 v19, v81, 10, 15 bitop3:0x6c
	v_lshlrev_b32_e32 v19, 3, v19
	v_add_u32_e32 v27, v101, v19
	ds_write_b64 v27, v[16:17]
	v_bitop3_b32 v16, v81, 11, 15 bitop3:0x6c
	v_lshlrev_b32_e32 v16, 3, v16
	v_add_u32_e32 v17, v101, v16
	ds_write_b64 v17, v[22:23]
	v_bitop3_b32 v17, v81, 12, 15 bitop3:0x6c
	v_lshlrev_b32_e32 v17, 3, v17
	v_add_u32_e32 v22, v101, v17
	ds_write_b64 v22, v[12:13]
	v_bitop3_b32 v12, v81, 13, 15 bitop3:0x6c
	v_lshlrev_b32_e32 v12, 3, v12
	v_add_u32_e32 v13, v101, v12
	ds_write_b64 v13, v[14:15]
	v_bitop3_b32 v13, v81, 14, 15 bitop3:0x6c
	v_lshlrev_b32_e32 v13, 3, v13
	v_add_u32_e32 v14, v101, v13
	ds_write_b64 v14, v[4:5]
	v_bitop3_b32 v4, v81, 15, v81 bitop3:0xc
	v_lshlrev_b32_e32 v4, 3, v4
	v_add_u32_e32 v5, v101, v4
	ds_write_b64 v5, v[8:9]
	v_add_u32_e32 v5, 0x2000, v80
	v_bitop3_b32 v5, v5, v81, 16 bitop3:0x78
	v_lshl_add_u32 v5, v5, 3, 16
	v_add_u32_e32 v8, v5, v100
	ds_write_b64 v8, v[64:65]
	v_add_u32_e32 v8, v5, v70
	ds_write_b64 v8, v[98:99]
	v_add_u32_e32 v8, v5, v71
	ds_write_b64 v8, v[96:97]
	v_add_u32_e32 v8, v5, v86
	ds_write_b64 v8, v[82:83]
	v_add_u32_e32 v8, v5, v74
	ds_write_b64 v8, v[78:79]
	v_add_u32_e32 v8, v5, v20
	ds_write_b64 v8, v[92:93]
	v_add_u32_e32 v8, v5, v21
	ds_write_b64 v8, v[76:77]
	v_add_u32_e32 v8, v5, v68
	ds_write_b64 v8, v[62:63]
	v_add_u32_e32 v8, v5, v26
	ds_write_b64 v8, v[90:91]
	v_add_u32_e32 v8, v5, v18
	ds_write_b64 v8, v[94:95]
	v_add_u32_e32 v8, v5, v19
	ds_write_b64 v8, v[10:11]
	v_add_u32_e32 v8, v5, v16
	ds_write_b64 v8, v[66:67]
	v_add_u32_e32 v8, v5, v17
	ds_write_b64 v8, v[6:7]
	v_add_u32_e32 v6, v5, v12
	ds_write_b64 v6, v[2:3]
	v_add_u32_e32 v2, v5, v13
	ds_write_b64 v2, v[24:25]
	v_add_u32_e32 v2, v5, v4
	v_mov_b32_e32 v22, v146
	ds_write_b64 v2, v[0:1]
	s_waitcnt lgkmcnt(0)
	s_barrier
	s_nop 0
	v_lshlrev_b32_e32 v0, 5, v22
	v_and_b32_e32 v2, 0xfffffe00, v0
	v_and_or_b32 v0, v22, 16, v2
	v_bitop3_b32 v2, v2, 16, v22 bitop3:0x34
	v_bitop3_b32 v6, v22, 4, 15 bitop3:0x6c
	v_bitop3_b32 v14, v22, 8, 15 bitop3:0x6c
	v_lshl_add_u32 v23, v0, 3, 16
	v_lshl_add_u32 v65, v2, 3, 16
	v_lshlrev_b32_e32 v6, 3, v6
	v_lshlrev_b32_e32 v14, 3, v14
	v_bitop3_b32 v2, v22, 1, 15 bitop3:0x6c
	v_add_u32_e32 v105, v23, v6
	v_add_u32_e32 v106, v65, v6
	v_bitop3_b32 v6, v22, 5, 15 bitop3:0x6c
	v_add_u32_e32 v113, v23, v14
	v_add_u32_e32 v114, v65, v14
	v_bitop3_b32 v14, v22, 9, 15 bitop3:0x6c
	v_lshlrev_b32_e32 v2, 3, v2
	v_lshlrev_b32_e32 v6, 3, v6
	v_lshlrev_b32_e32 v14, 3, v14
	v_add_u32_e32 v99, v23, v2
	v_add_u32_e32 v100, v65, v2
	v_bitop3_b32 v2, v22, 2, 15 bitop3:0x6c
	v_add_u32_e32 v107, v23, v6
	v_add_u32_e32 v108, v65, v6
	v_bitop3_b32 v6, v22, 6, 15 bitop3:0x6c
	v_add_u32_e32 v115, v23, v14
	v_add_u32_e32 v116, v65, v14
	v_bitop3_b32 v14, v22, 10, 15 bitop3:0x6c
	v_bitop3_b32 v26, v22, 12, 15 bitop3:0x6c
	v_lshlrev_b32_e32 v2, 3, v2
	v_lshlrev_b32_e32 v6, 3, v6
	v_lshlrev_b32_e32 v14, 3, v14
	v_lshlrev_b32_e32 v26, 3, v26
	v_and_b32_e32 v64, 15, v22
	v_add_u32_e32 v101, v23, v2
	v_add_u32_e32 v102, v65, v2
	v_bitop3_b32 v2, v22, 3, 15 bitop3:0x6c
	v_add_u32_e32 v109, v23, v6
	v_add_u32_e32 v110, v65, v6
	v_bitop3_b32 v6, v22, 7, 15 bitop3:0x6c
	v_add_u32_e32 v117, v23, v14
	v_add_u32_e32 v118, v65, v14
	v_bitop3_b32 v14, v22, 11, 15 bitop3:0x6c
	v_add_u32_e32 v121, v23, v26
	v_add_u32_e32 v122, v65, v26
	v_bitop3_b32 v26, v22, 13, 15 bitop3:0x6c
	v_bitop3_b32 v66, v22, 14, 15 bitop3:0x6c
	v_bitop3_b32 v22, v22, 15, v22 bitop3:0xc
	v_lshlrev_b32_e32 v3, 3, v64
	v_lshlrev_b32_e32 v2, 3, v2
	v_lshlrev_b32_e32 v6, 3, v6
	v_lshlrev_b32_e32 v14, 3, v14
	v_lshlrev_b32_e32 v26, 3, v26
	v_lshlrev_b32_e32 v66, 3, v66
	v_lshlrev_b32_e32 v22, 3, v22
	v_add_u32_e32 v67, v23, v3
	v_add_u32_e32 v98, v65, v3
	v_add_u32_e32 v103, v23, v2
	v_add_u32_e32 v104, v65, v2
	v_add_u32_e32 v111, v23, v6
	v_add_u32_e32 v112, v65, v6
	v_add_u32_e32 v119, v23, v14
	v_add_u32_e32 v120, v65, v14
	v_add_u32_e32 v123, v23, v26
	v_add_u32_e32 v124, v65, v26
	v_add_u32_e32 v125, v23, v66
	v_add_u32_e32 v126, v65, v66
	v_add_u32_e32 v127, v23, v22
	v_add_u32_e32 v128, v65, v22
	ds_read_b64 v[0:1], v67
	ds_read_b64 v[12:13], v98
	ds_read_b64 v[74:75], v99 offset:256
	ds_read_b64 v[4:5], v100 offset:256
	ds_read_b64 v[76:77], v101 offset:512
	ds_read_b64 v[10:11], v102 offset:512
	ds_read_b64 v[70:71], v103 offset:768
	ds_read_b64 v[2:3], v104 offset:768
	ds_read_b64 v[62:63], v105 offset:1024
	ds_read_b64 v[20:21], v106 offset:1024
	ds_read_b64 v[90:91], v107 offset:1280
	ds_read_b64 v[8:9], v108 offset:1280
	ds_read_b64 v[84:85], v109 offset:1536
	ds_read_b64 v[16:17], v110 offset:1536
	ds_read_b64 v[82:83], v111 offset:1792
	ds_read_b64 v[6:7], v112 offset:1792
	ds_read_b64 v[24:25], v113 offset:2048
	ds_read_b64 v[78:79], v114 offset:2048
	ds_read_b64 v[96:97], v115 offset:2304
	ds_read_b64 v[18:19], v116 offset:2304
	ds_read_b64 v[86:87], v117 offset:2560
	ds_read_b64 v[72:73], v118 offset:2560
	ds_read_b64 v[130:131], v119 offset:2816
	ds_read_b64 v[14:15], v120 offset:2816
	ds_read_b64 v[80:81], v121 offset:3072
	ds_read_b64 v[92:93], v122 offset:3072
	ds_read_b64 v[132:133], v123 offset:3328
	ds_read_b64 v[26:27], v124 offset:3328
	ds_read_b64 v[94:95], v125 offset:3584
	ds_read_b64 v[88:89], v126 offset:3584
	ds_read_b64 v[134:135], v127 offset:3840
	ds_read_b64 v[22:23], v128 offset:3840
	s_waitcnt lgkmcnt(14)
	s_nop 0
	v_cvt_f32_i32_e32 v64, v64
	s_nop 0
	v_mul_f32_e32 v64, 0x3b000000, v64
	v_cos_f32_e32 v68, v64
	v_sin_f32_e32 v69, v64
	v_add_f32_e32 v66, v68, v68
	v_pk_mul_f32 v[64:65], v[68:69], v[68:69]
	v_mul_f32_e32 v66, v69, v66
	s_nop 0
	s_nop 0
	v_mov_b32_e32 v140, v69
	v_pk_add_f32 v[64:65], v[64:65], v[64:65] op_sel:[0,1] op_sel_hi:[0,1] neg_lo:[0,1] neg_hi:[0,1]
	v_pk_mul_f32 v[136:137], v[68:69], v[66:67] op_sel:[1,0] op_sel_hi:[0,0] neg_lo:[1,0]
	v_pk_mul_f32 v[138:139], v[24:25], v[140:141] op_sel:[1,0] op_sel_hi:[0,0] neg_lo:[1,0]
	v_pk_fma_f32 v[136:137], v[68:69], v[64:65], v[136:137]
	v_pk_fma_f32 v[24:25], v[24:25], v[68:69], v[138:139] op_sel_hi:[1,0,1]
	v_pk_mul_f32 v[68:69], v[66:67], s[48:49] op_sel_hi:[0,1]
	v_pk_fma_f32 v[138:139], v[64:65], s[40:41], v[68:69]
	s_nop 0
	v_pk_mul_f32 v[68:69], v[62:63], v[138:139] op_sel:[1,1] op_sel_hi:[0,1] neg_lo:[1,0]
	s_nop 0
	v_pk_fma_f32 v[68:69], v[62:63], v[138:139], v[68:69] op_sel_hi:[1,0,1]
	v_pk_mul_f32 v[62:63], v[66:67], v[136:137] op_sel:[0,1] op_sel_hi:[0,0] neg_lo:[0,1]
	v_pk_fma_f32 v[140:141], v[64:65], v[136:137], v[62:63]
	s_waitcnt lgkmcnt(7)
	v_pk_mul_f32 v[62:63], v[80:81], v[136:137] op_sel:[1,1] op_sel_hi:[0,1] neg_lo:[1,0]
	s_nop 0
	v_pk_fma_f32 v[62:63], v[80:81], v[136:137], v[62:63] op_sel_hi:[1,0,1]
	v_pk_mul_f32 v[80:81], v[66:67], v[138:139] op_sel:[0,1] op_sel_hi:[0,0] neg_lo:[0,1]
	v_pk_fma_f32 v[136:137], v[64:65], v[138:139], v[80:81]
	s_nop 0
	v_pk_mul_f32 v[80:81], v[76:77], v[136:137] op_sel:[1,1] op_sel_hi:[0,1] neg_lo:[1,0]
	s_nop 0
	v_pk_fma_f32 v[80:81], v[76:77], v[136:137], v[80:81] op_sel_hi:[1,0,1]
	v_pk_mul_f32 v[76:77], v[66:67], v[140:141] op_sel:[0,1] op_sel_hi:[0,0] neg_lo:[0,1]
	v_pk_fma_f32 v[138:139], v[64:65], v[140:141], v[76:77]
	v_pk_mul_f32 v[76:77], v[86:87], v[140:141] op_sel:[1,1] op_sel_hi:[0,1] neg_lo:[1,0]
	s_nop 0
	v_pk_fma_f32 v[76:77], v[86:87], v[140:141], v[76:77] op_sel_hi:[1,0,1]
	v_pk_mul_f32 v[86:87], v[66:67], v[136:137] op_sel:[0,1] op_sel_hi:[0,0] neg_lo:[0,1]
	v_pk_fma_f32 v[136:137], v[64:65], v[136:137], v[86:87]
	s_nop 0
	v_pk_mul_f32 v[86:87], v[84:85], v[136:137] op_sel:[1,1] op_sel_hi:[0,1] neg_lo:[1,0]
	s_nop 0
	v_pk_fma_f32 v[86:87], v[84:85], v[136:137], v[86:87] op_sel_hi:[1,0,1]
	v_pk_mul_f32 v[84:85], v[66:67], v[138:139] op_sel:[0,1] op_sel_hi:[0,0] neg_lo:[0,1]
	v_pk_fma_f32 v[140:141], v[64:65], v[138:139], v[84:85]
	s_waitcnt lgkmcnt(3)
	v_pk_mul_f32 v[84:85], v[94:95], v[138:139] op_sel:[1,1] op_sel_hi:[0,1] neg_lo:[1,0]
	s_nop 0
	v_pk_fma_f32 v[84:85], v[94:95], v[138:139], v[84:85] op_sel_hi:[1,0,1]
	v_pk_mul_f32 v[94:95], v[66:67], v[136:137] op_sel:[0,1] op_sel_hi:[0,0] neg_lo:[0,1]
	v_pk_fma_f32 v[136:137], v[64:65], v[136:137], v[94:95]
	s_nop 0
	v_pk_mul_f32 v[94:95], v[74:75], v[136:137] op_sel:[1,1] op_sel_hi:[0,1] neg_lo:[1,0]
	s_nop 0
	v_pk_fma_f32 v[94:95], v[74:75], v[136:137], v[94:95] op_sel_hi:[1,0,1]
	v_pk_mul_f32 v[74:75], v[66:67], v[140:141] op_sel:[0,1] op_sel_hi:[0,0] neg_lo:[0,1]
	v_pk_fma_f32 v[138:139], v[64:65], v[140:141], v[74:75]
	v_pk_mul_f32 v[74:75], v[96:97], v[140:141] op_sel:[1,1] op_sel_hi:[0,1] neg_lo:[1,0]
	s_nop 0
	v_pk_fma_f32 v[74:75], v[96:97], v[140:141], v[74:75] op_sel_hi:[1,0,1]
	v_pk_mul_f32 v[96:97], v[66:67], v[136:137] op_sel:[0,1] op_sel_hi:[0,0] neg_lo:[0,1]
	v_pk_fma_f32 v[136:137], v[64:65], v[136:137], v[96:97]
	s_nop 0
	v_pk_mul_f32 v[96:97], v[90:91], v[136:137] op_sel:[1,1] op_sel_hi:[0,1] neg_lo:[1,0]
	s_nop 0
	v_pk_fma_f32 v[96:97], v[90:91], v[136:137], v[96:97] op_sel_hi:[1,0,1]
	v_pk_mul_f32 v[90:91], v[66:67], v[138:139] op_sel:[0,1] op_sel_hi:[0,0] neg_lo:[0,1]
	v_pk_fma_f32 v[140:141], v[64:65], v[138:139], v[90:91]
	v_pk_mul_f32 v[90:91], v[132:133], v[138:139] op_sel:[1,1] op_sel_hi:[0,1] neg_lo:[1,0]
	s_nop 0
	v_pk_fma_f32 v[90:91], v[132:133], v[138:139], v[90:91] op_sel_hi:[1,0,1]
	v_pk_mul_f32 v[132:133], v[66:67], v[136:137] op_sel:[0,1] op_sel_hi:[0,0] neg_lo:[0,1]
	s_nop 0
	v_pk_fma_f32 v[132:133], v[64:65], v[136:137], v[132:133]
	v_pk_mul_f32 v[138:139], v[130:131], v[140:141] op_sel:[1,1] op_sel_hi:[0,1] neg_lo:[1,0]
	v_pk_mul_f32 v[136:137], v[70:71], v[132:133] op_sel:[1,1] op_sel_hi:[0,1] neg_lo:[1,0]
	v_pk_fma_f32 v[130:131], v[130:131], v[140:141], v[138:139] op_sel_hi:[1,0,1]
	v_pk_fma_f32 v[70:71], v[70:71], v[132:133], v[136:137] op_sel_hi:[1,0,1]
	v_pk_mul_f32 v[138:139], v[66:67], v[132:133] op_sel:[0,1] op_sel_hi:[0,0] neg_lo:[0,1]
	v_pk_mul_f32 v[136:137], v[66:67], v[140:141] op_sel:[0,1] op_sel_hi:[0,0] neg_lo:[0,1]
	v_pk_fma_f32 v[132:133], v[64:65], v[132:133], v[138:139]
	v_pk_fma_f32 v[136:137], v[64:65], v[140:141], v[136:137]
	v_pk_mul_f32 v[138:139], v[82:83], v[132:133] op_sel:[1,1] op_sel_hi:[0,1] neg_lo:[1,0]
	s_waitcnt lgkmcnt(1)
	v_pk_fma_f32 v[82:83], v[82:83], v[132:133], v[138:139] op_sel_hi:[1,0,1]
	v_pk_mul_f32 v[138:139], v[66:67], v[136:137] op_sel:[0,1] op_sel_hi:[0,0] neg_lo:[0,1]
	v_pk_mul_f32 v[140:141], v[134:135], v[136:137] op_sel:[1,1] op_sel_hi:[0,1] neg_lo:[1,0]
	v_pk_fma_f32 v[138:139], v[64:65], v[136:137], v[138:139]
	v_pk_fma_f32 v[134:135], v[134:135], v[136:137], v[140:141] op_sel_hi:[1,0,1]
	v_pk_mul_f32 v[136:137], v[66:67], v[132:133] op_sel:[0,1] op_sel_hi:[0,0] neg_lo:[0,1]
	v_pk_fma_f32 v[132:133], v[64:65], v[132:133], v[136:137]
	s_nop 0
	v_pk_mul_f32 v[136:137], v[12:13], v[132:133] op_sel:[1,1] op_sel_hi:[0,1] neg_lo:[1,0]
	s_nop 0
	v_pk_fma_f32 v[12:13], v[12:13], v[132:133], v[136:137] op_sel_hi:[1,0,1]
	v_pk_mul_f32 v[136:137], v[66:67], v[138:139] op_sel:[0,1] op_sel_hi:[0,0] neg_lo:[0,1]
	v_pk_mul_f32 v[140:141], v[78:79], v[138:139] op_sel:[1,1] op_sel_hi:[0,1] neg_lo:[1,0]
	v_pk_fma_f32 v[136:137], v[64:65], v[138:139], v[136:137]
	v_pk_fma_f32 v[78:79], v[78:79], v[138:139], v[140:141] op_sel_hi:[1,0,1]
	v_pk_mul_f32 v[138:139], v[66:67], v[132:133] op_sel:[0,1] op_sel_hi:[0,0] neg_lo:[0,1]
	v_pk_fma_f32 v[132:133], v[64:65], v[132:133], v[138:139]
	s_nop 0
	v_pk_mul_f32 v[138:139], v[20:21], v[132:133] op_sel:[1,1] op_sel_hi:[0,1] neg_lo:[1,0]
	s_nop 0
	v_pk_fma_f32 v[20:21], v[20:21], v[132:133], v[138:139] op_sel_hi:[1,0,1]
	v_pk_mul_f32 v[138:139], v[66:67], v[136:137] op_sel:[0,1] op_sel_hi:[0,0] neg_lo:[0,1]
	v_pk_mul_f32 v[140:141], v[92:93], v[136:137] op_sel:[1,1] op_sel_hi:[0,1] neg_lo:[1,0]
	v_pk_fma_f32 v[138:139], v[64:65], v[136:137], v[138:139]
	v_pk_fma_f32 v[92:93], v[92:93], v[136:137], v[140:141] op_sel_hi:[1,0,1]
	v_pk_mul_f32 v[136:137], v[66:67], v[132:133] op_sel:[0,1] op_sel_hi:[0,0] neg_lo:[0,1]
	v_pk_fma_f32 v[132:133], v[64:65], v[132:133], v[136:137]
	s_nop 0
	v_pk_mul_f32 v[136:137], v[10:11], v[132:133] op_sel:[1,1] op_sel_hi:[0,1] neg_lo:[1,0]
	s_nop 0
	v_pk_fma_f32 v[10:11], v[10:11], v[132:133], v[136:137] op_sel_hi:[1,0,1]
	v_pk_mul_f32 v[136:137], v[66:67], v[138:139] op_sel:[0,1] op_sel_hi:[0,0] neg_lo:[0,1]
	v_pk_mul_f32 v[140:141], v[72:73], v[138:139] op_sel:[1,1] op_sel_hi:[0,1] neg_lo:[1,0]
	v_pk_fma_f32 v[136:137], v[64:65], v[138:139], v[136:137]
	v_pk_fma_f32 v[72:73], v[72:73], v[138:139], v[140:141] op_sel_hi:[1,0,1]
	v_pk_mul_f32 v[138:139], v[66:67], v[132:133] op_sel:[0,1] op_sel_hi:[0,0] neg_lo:[0,1]
	v_pk_fma_f32 v[132:133], v[64:65], v[132:133], v[138:139]
	s_nop 0
	v_pk_mul_f32 v[138:139], v[16:17], v[132:133] op_sel:[1,1] op_sel_hi:[0,1] neg_lo:[1,0]
	s_nop 0
	v_pk_fma_f32 v[16:17], v[16:17], v[132:133], v[138:139] op_sel_hi:[1,0,1]
	v_pk_mul_f32 v[138:139], v[66:67], v[136:137] op_sel:[0,1] op_sel_hi:[0,0] neg_lo:[0,1]
	v_pk_mul_f32 v[140:141], v[88:89], v[136:137] op_sel:[1,1] op_sel_hi:[0,1] neg_lo:[1,0]
	v_pk_fma_f32 v[138:139], v[64:65], v[136:137], v[138:139]
	v_pk_fma_f32 v[88:89], v[88:89], v[136:137], v[140:141] op_sel_hi:[1,0,1]
	v_pk_mul_f32 v[136:137], v[66:67], v[132:133] op_sel:[0,1] op_sel_hi:[0,0] neg_lo:[0,1]
	v_pk_fma_f32 v[132:133], v[64:65], v[132:133], v[136:137]
	s_nop 0
	v_pk_mul_f32 v[136:137], v[4:5], v[132:133] op_sel:[1,1] op_sel_hi:[0,1] neg_lo:[1,0]
	s_nop 0
	v_pk_fma_f32 v[4:5], v[4:5], v[132:133], v[136:137] op_sel_hi:[1,0,1]
	v_pk_mul_f32 v[136:137], v[66:67], v[138:139] op_sel:[0,1] op_sel_hi:[0,0] neg_lo:[0,1]
	v_pk_mul_f32 v[140:141], v[18:19], v[138:139] op_sel:[1,1] op_sel_hi:[0,1] neg_lo:[1,0]
	v_pk_fma_f32 v[136:137], v[64:65], v[138:139], v[136:137]
	v_pk_fma_f32 v[18:19], v[18:19], v[138:139], v[140:141] op_sel_hi:[1,0,1]
	v_pk_mul_f32 v[138:139], v[66:67], v[132:133] op_sel:[0,1] op_sel_hi:[0,0] neg_lo:[0,1]
	v_pk_fma_f32 v[132:133], v[64:65], v[132:133], v[138:139]
	s_nop 0
	v_pk_mul_f32 v[138:139], v[8:9], v[132:133] op_sel:[1,1] op_sel_hi:[0,1] neg_lo:[1,0]
	s_nop 0
	v_pk_fma_f32 v[8:9], v[8:9], v[132:133], v[138:139] op_sel_hi:[1,0,1]
	v_pk_mul_f32 v[138:139], v[66:67], v[136:137] op_sel:[0,1] op_sel_hi:[0,0] neg_lo:[0,1]
	v_pk_mul_f32 v[140:141], v[26:27], v[136:137] op_sel:[1,1] op_sel_hi:[0,1] neg_lo:[1,0]
	v_pk_fma_f32 v[138:139], v[64:65], v[136:137], v[138:139]
	v_pk_fma_f32 v[26:27], v[26:27], v[136:137], v[140:141] op_sel_hi:[1,0,1]
	v_pk_mul_f32 v[136:137], v[66:67], v[132:133] op_sel:[0,1] op_sel_hi:[0,0] neg_lo:[0,1]
	v_pk_fma_f32 v[132:133], v[64:65], v[132:133], v[136:137]
	s_nop 0
	v_pk_mul_f32 v[136:137], v[2:3], v[132:133] op_sel:[1,1] op_sel_hi:[0,1] neg_lo:[1,0]
	s_nop 0
	v_pk_fma_f32 v[2:3], v[2:3], v[132:133], v[136:137] op_sel_hi:[1,0,1]
	v_pk_mul_f32 v[136:137], v[66:67], v[138:139] op_sel:[0,1] op_sel_hi:[0,0] neg_lo:[0,1]
	v_pk_mul_f32 v[140:141], v[14:15], v[138:139] op_sel:[1,1] op_sel_hi:[0,1] neg_lo:[1,0]
	v_pk_fma_f32 v[136:137], v[64:65], v[138:139], v[136:137]
	v_pk_fma_f32 v[14:15], v[14:15], v[138:139], v[140:141] op_sel_hi:[1,0,1]
	v_pk_mul_f32 v[138:139], v[66:67], v[132:133] op_sel:[0,1] op_sel_hi:[0,0] neg_lo:[0,1]
	v_pk_fma_f32 v[64:65], v[64:65], v[132:133], v[138:139]
	s_nop 0
	v_pk_mul_f32 v[132:133], v[6:7], v[64:65] op_sel:[1,1] op_sel_hi:[0,1] neg_lo:[1,0]
	s_nop 0
	v_pk_fma_f32 v[6:7], v[6:7], v[64:65], v[132:133] op_sel_hi:[1,0,1]
	s_waitcnt lgkmcnt(0)
	v_pk_mul_f32 v[64:65], v[22:23], v[136:137] op_sel:[1,1] op_sel_hi:[0,1] neg_lo:[1,0]
	s_nop 0
	v_pk_fma_f32 v[22:23], v[22:23], v[136:137], v[64:65] op_sel_hi:[1,0,1]
	v_pk_add_f32 v[64:65], v[0:1], v[12:13]
	v_pk_add_f32 v[0:1], v[0:1], v[12:13] neg_lo:[0,1] neg_hi:[0,1]
	v_pk_add_f32 v[12:13], v[94:95], v[4:5]
	v_pk_add_f32 v[4:5], v[94:95], v[4:5] neg_lo:[0,1] neg_hi:[0,1]
	v_pk_add_f32 v[94:95], v[80:81], v[10:11]
	v_pk_add_f32 v[10:11], v[80:81], v[10:11] neg_lo:[0,1] neg_hi:[0,1]
	v_pk_add_f32 v[80:81], v[70:71], v[2:3]
	v_pk_add_f32 v[2:3], v[70:71], v[2:3] neg_lo:[0,1] neg_hi:[0,1]
	v_pk_add_f32 v[132:133], v[64:65], v[12:13]
	v_pk_add_f32 v[12:13], v[64:65], v[12:13] neg_lo:[0,1] neg_hi:[0,1]
	v_xor_b32_e32 v64, 0x80000000, v5
	v_mov_b32_e32 v65, v4
	v_pk_add_f32 v[70:71], v[68:69], v[20:21]
	v_pk_add_f32 v[20:21], v[68:69], v[20:21] neg_lo:[0,1] neg_hi:[0,1]
	v_pk_add_f32 v[68:69], v[96:97], v[8:9]
	v_pk_add_f32 v[8:9], v[96:97], v[8:9] neg_lo:[0,1] neg_hi:[0,1]
	v_pk_add_f32 v[4:5], v[0:1], v[64:65]
	v_pk_add_f32 v[0:1], v[0:1], v[64:65] neg_lo:[0,1] neg_hi:[0,1]
	v_pk_add_f32 v[64:65], v[94:95], v[80:81]
	v_pk_add_f32 v[80:81], v[94:95], v[80:81] neg_lo:[0,1] neg_hi:[0,1]
	v_xor_b32_e32 v94, 0x80000000, v3
	v_mov_b32_e32 v95, v2
	v_pk_add_f32 v[96:97], v[86:87], v[16:17]
	v_pk_add_f32 v[16:17], v[86:87], v[16:17] neg_lo:[0,1] neg_hi:[0,1]
	v_pk_add_f32 v[86:87], v[82:83], v[6:7]
	v_pk_add_f32 v[6:7], v[82:83], v[6:7] neg_lo:[0,1] neg_hi:[0,1]
	v_pk_add_f32 v[2:3], v[10:11], v[94:95]
	v_pk_add_f32 v[10:11], v[10:11], v[94:95] neg_lo:[0,1] neg_hi:[0,1]
	v_pk_add_f32 v[94:95], v[70:71], v[68:69]
	v_pk_add_f32 v[68:69], v[70:71], v[68:69] neg_lo:[0,1] neg_hi:[0,1]
	v_xor_b32_e32 v70, 0x80000000, v9
	v_mov_b32_e32 v71, v8
	v_pk_add_f32 v[82:83], v[24:25], v[78:79]
	v_pk_add_f32 v[24:25], v[24:25], v[78:79] neg_lo:[0,1] neg_hi:[0,1]
	v_pk_add_f32 v[78:79], v[74:75], v[18:19]
	v_pk_add_f32 v[18:19], v[74:75], v[18:19] neg_lo:[0,1] neg_hi:[0,1]
	v_pk_add_f32 v[8:9], v[20:21], v[70:71]
	v_pk_add_f32 v[20:21], v[20:21], v[70:71] neg_lo:[0,1] neg_hi:[0,1]
	v_pk_add_f32 v[70:71], v[96:97], v[86:87]
	v_pk_add_f32 v[86:87], v[96:97], v[86:87] neg_lo:[0,1] neg_hi:[0,1]
	v_xor_b32_e32 v96, 0x80000000, v7
	v_mov_b32_e32 v97, v6
	v_pk_add_f32 v[74:75], v[76:77], v[72:73]
	v_pk_add_f32 v[72:73], v[76:77], v[72:73] neg_lo:[0,1] neg_hi:[0,1]
	v_pk_add_f32 v[76:77], v[130:131], v[14:15]
	v_pk_add_f32 v[14:15], v[130:131], v[14:15] neg_lo:[0,1] neg_hi:[0,1]
	v_pk_add_f32 v[6:7], v[16:17], v[96:97]
	v_pk_add_f32 v[16:17], v[16:17], v[96:97] neg_lo:[0,1] neg_hi:[0,1]
	v_pk_add_f32 v[96:97], v[82:83], v[78:79]
	v_pk_add_f32 v[78:79], v[82:83], v[78:79] neg_lo:[0,1] neg_hi:[0,1]
	v_xor_b32_e32 v82, 0x80000000, v19
	v_mov_b32_e32 v83, v18
	v_pk_add_f32 v[130:131], v[62:63], v[92:93]
	v_pk_add_f32 v[62:63], v[62:63], v[92:93] neg_lo:[0,1] neg_hi:[0,1]
	v_pk_add_f32 v[92:93], v[90:91], v[26:27]
	v_pk_add_f32 v[26:27], v[90:91], v[26:27] neg_lo:[0,1] neg_hi:[0,1]
	v_pk_add_f32 v[18:19], v[24:25], v[82:83]
	v_pk_add_f32 v[24:25], v[24:25], v[82:83] neg_lo:[0,1] neg_hi:[0,1]
	v_pk_add_f32 v[82:83], v[74:75], v[76:77]
	v_pk_add_f32 v[74:75], v[74:75], v[76:77] neg_lo:[0,1] neg_hi:[0,1]
	v_xor_b32_e32 v76, 0x80000000, v15
	v_mov_b32_e32 v77, v14
	v_pk_add_f32 v[90:91], v[84:85], v[88:89]
	v_pk_add_f32 v[84:85], v[84:85], v[88:89] neg_lo:[0,1] neg_hi:[0,1]
	v_pk_add_f32 v[88:89], v[134:135], v[22:23]
	v_pk_add_f32 v[22:23], v[134:135], v[22:23] neg_lo:[0,1] neg_hi:[0,1]
	v_pk_add_f32 v[14:15], v[72:73], v[76:77]
	v_pk_add_f32 v[72:73], v[72:73], v[76:77] neg_lo:[0,1] neg_hi:[0,1]
	v_pk_add_f32 v[76:77], v[130:131], v[92:93]
	v_pk_add_f32 v[92:93], v[130:131], v[92:93] neg_lo:[0,1] neg_hi:[0,1]
	v_xor_b32_e32 v130, 0x80000000, v27
	v_mov_b32_e32 v131, v26
	v_pk_add_f32 v[26:27], v[62:63], v[130:131]
	v_pk_add_f32 v[62:63], v[62:63], v[130:131] neg_lo:[0,1] neg_hi:[0,1]
	v_pk_add_f32 v[130:131], v[90:91], v[88:89]
	v_pk_add_f32 v[88:89], v[90:91], v[88:89] neg_lo:[0,1] neg_hi:[0,1]
	v_xor_b32_e32 v90, 0x80000000, v23
	v_mov_b32_e32 v91, v22
	v_pk_add_f32 v[22:23], v[84:85], v[90:91]
	v_pk_add_f32 v[84:85], v[84:85], v[90:91] neg_lo:[0,1] neg_hi:[0,1]
	v_pk_add_f32 v[90:91], v[132:133], v[64:65]
	v_pk_add_f32 v[64:65], v[132:133], v[64:65] neg_lo:[0,1] neg_hi:[0,1]
	v_pk_mul_f32 v[132:133], v[2:3], s[70:71] op_sel:[1,0] op_sel_hi:[0,0] neg_lo:[1,0]
	v_xor_b32_e32 v134, 0x80000000, v11
	v_pk_fma_f32 v[2:3], v[2:3], s[70:71], v[132:133] op_sel_hi:[1,0,1]
	v_mov_b32_e32 v135, v10
	v_pk_add_f32 v[132:133], v[4:5], v[2:3]
	v_pk_add_f32 v[2:3], v[4:5], v[2:3] neg_lo:[0,1] neg_hi:[0,1]
	v_xor_b32_e32 v4, 0x80000000, v81
	v_mov_b32_e32 v5, v80
	v_pk_add_f32 v[80:81], v[12:13], v[4:5]
	v_pk_add_f32 v[4:5], v[12:13], v[4:5] neg_lo:[0,1] neg_hi:[0,1]
	v_pk_mul_f32 v[12:13], v[10:11], s[70:71] op_sel_hi:[1,0]
	s_nop 0
	v_pk_fma_f32 v[10:11], v[134:135], s[70:71], v[12:13] op_sel_hi:[1,0,1] neg_lo:[0,0,1] neg_hi:[0,0,1]
	v_xor_b32_e32 v134, 0x80000000, v17
	v_pk_add_f32 v[12:13], v[0:1], v[10:11]
	v_pk_add_f32 v[0:1], v[0:1], v[10:11] neg_lo:[0,1] neg_hi:[0,1]
	v_pk_add_f32 v[10:11], v[94:95], v[70:71]
	v_pk_add_f32 v[70:71], v[94:95], v[70:71] neg_lo:[0,1] neg_hi:[0,1]
	v_pk_mul_f32 v[94:95], v[6:7], s[70:71] op_sel:[1,0] op_sel_hi:[0,0] neg_lo:[1,0]
	v_mov_b32_e32 v135, v16
	v_pk_fma_f32 v[6:7], v[6:7], s[70:71], v[94:95] op_sel_hi:[1,0,1]
	s_nop 0
	v_pk_add_f32 v[94:95], v[8:9], v[6:7]
	v_pk_add_f32 v[6:7], v[8:9], v[6:7] neg_lo:[0,1] neg_hi:[0,1]
	v_xor_b32_e32 v8, 0x80000000, v87
	v_mov_b32_e32 v9, v86
	v_pk_add_f32 v[86:87], v[68:69], v[8:9]
	v_pk_add_f32 v[8:9], v[68:69], v[8:9] neg_lo:[0,1] neg_hi:[0,1]
	v_pk_mul_f32 v[68:69], v[16:17], s[70:71] op_sel_hi:[1,0]
	s_nop 0
	v_pk_fma_f32 v[16:17], v[134:135], s[70:71], v[68:69] op_sel_hi:[1,0,1] neg_lo:[0,0,1] neg_hi:[0,0,1]
	v_xor_b32_e32 v134, 0x80000000, v73
	v_pk_add_f32 v[68:69], v[20:21], v[16:17]
	v_pk_add_f32 v[16:17], v[20:21], v[16:17] neg_lo:[0,1] neg_hi:[0,1]
	v_pk_add_f32 v[20:21], v[96:97], v[82:83]
	v_pk_add_f32 v[82:83], v[96:97], v[82:83] neg_lo:[0,1] neg_hi:[0,1]
	v_pk_mul_f32 v[96:97], v[14:15], s[70:71] op_sel:[1,0] op_sel_hi:[0,0] neg_lo:[1,0]
	v_mov_b32_e32 v135, v72
	v_pk_fma_f32 v[14:15], v[14:15], s[70:71], v[96:97] op_sel_hi:[1,0,1]
	s_nop 0
	v_pk_add_f32 v[96:97], v[18:19], v[14:15]
	v_pk_add_f32 v[14:15], v[18:19], v[14:15] neg_lo:[0,1] neg_hi:[0,1]
	v_xor_b32_e32 v18, 0x80000000, v75
	v_mov_b32_e32 v19, v74
	v_pk_add_f32 v[74:75], v[78:79], v[18:19]
	v_pk_add_f32 v[18:19], v[78:79], v[18:19] neg_lo:[0,1] neg_hi:[0,1]
	v_pk_mul_f32 v[78:79], v[72:73], s[70:71] op_sel_hi:[1,0]
	s_nop 0
	v_pk_fma_f32 v[72:73], v[134:135], s[70:71], v[78:79] op_sel_hi:[1,0,1] neg_lo:[0,0,1] neg_hi:[0,0,1]
	v_xor_b32_e32 v134, 0x80000000, v85
	v_pk_add_f32 v[78:79], v[24:25], v[72:73]
	v_pk_add_f32 v[24:25], v[24:25], v[72:73] neg_lo:[0,1] neg_hi:[0,1]
	v_pk_add_f32 v[72:73], v[76:77], v[130:131]
	v_pk_add_f32 v[76:77], v[76:77], v[130:131] neg_lo:[0,1] neg_hi:[0,1]
	v_pk_mul_f32 v[130:131], v[22:23], s[70:71] op_sel:[1,0] op_sel_hi:[0,0] neg_lo:[1,0]
	v_mov_b32_e32 v135, v84
	v_pk_fma_f32 v[22:23], v[22:23], s[70:71], v[130:131] op_sel_hi:[1,0,1]
	s_nop 0
	v_pk_add_f32 v[130:131], v[26:27], v[22:23]
	v_pk_add_f32 v[22:23], v[26:27], v[22:23] neg_lo:[0,1] neg_hi:[0,1]
	v_xor_b32_e32 v26, 0x80000000, v89
	v_mov_b32_e32 v27, v88
	v_pk_add_f32 v[88:89], v[92:93], v[26:27]
	v_pk_add_f32 v[26:27], v[92:93], v[26:27] neg_lo:[0,1] neg_hi:[0,1]
	v_pk_mul_f32 v[92:93], v[84:85], s[70:71] op_sel_hi:[1,0]
	s_nop 0
	v_pk_fma_f32 v[84:85], v[134:135], s[70:71], v[92:93] op_sel_hi:[1,0,1] neg_lo:[0,0,1] neg_hi:[0,0,1]
	v_xor_b32_e32 v134, 0x80000000, v7
	v_pk_add_f32 v[92:93], v[62:63], v[84:85]
	v_pk_add_f32 v[62:63], v[62:63], v[84:85] neg_lo:[0,1] neg_hi:[0,1]
	v_pk_add_f32 v[84:85], v[90:91], v[10:11]
	v_pk_add_f32 v[10:11], v[90:91], v[10:11] neg_lo:[0,1] neg_hi:[0,1]
	v_pk_mul_f32 v[90:91], v[94:95], s[62:63] op_sel:[1,0] op_sel_hi:[0,0] neg_lo:[1,0]
	v_mov_b32_e32 v135, v6
	v_pk_fma_f32 v[90:91], v[94:95], s[60:61], v[90:91] op_sel_hi:[1,0,1]
	s_nop 0
	v_pk_add_f32 v[94:95], v[132:133], v[90:91]
	v_pk_add_f32 v[90:91], v[132:133], v[90:91] neg_lo:[0,1] neg_hi:[0,1]
	v_pk_mul_f32 v[132:133], v[86:87], s[70:71] op_sel:[1,0] op_sel_hi:[0,0] neg_lo:[1,0]
	s_nop 0
	v_pk_fma_f32 v[86:87], v[86:87], s[70:71], v[132:133] op_sel_hi:[1,0,1]
	s_nop 0
	v_pk_add_f32 v[132:133], v[80:81], v[86:87]
	v_pk_add_f32 v[80:81], v[80:81], v[86:87] neg_lo:[0,1] neg_hi:[0,1]
	v_pk_mul_f32 v[86:87], v[68:69], s[60:61] op_sel:[1,0] op_sel_hi:[0,0] neg_lo:[1,0]
	s_nop 0
	v_pk_fma_f32 v[68:69], v[68:69], s[62:63], v[86:87] op_sel_hi:[1,0,1]
	s_nop 0
	v_pk_add_f32 v[86:87], v[12:13], v[68:69]
	v_pk_add_f32 v[12:13], v[12:13], v[68:69] neg_lo:[0,1] neg_hi:[0,1]
	v_xor_b32_e32 v68, 0x80000000, v71
	v_mov_b32_e32 v69, v70
	v_pk_add_f32 v[70:71], v[64:65], v[68:69]
	v_pk_add_f32 v[64:65], v[64:65], v[68:69] neg_lo:[0,1] neg_hi:[0,1]
	v_pk_mul_f32 v[68:69], v[6:7], s[62:63] op_sel_hi:[1,0]
	s_nop 0
	v_pk_fma_f32 v[6:7], v[134:135], s[60:61], v[68:69] op_sel_hi:[1,0,1] neg_lo:[0,0,1] neg_hi:[0,0,1]
	v_xor_b32_e32 v134, 0x80000000, v9
	v_pk_add_f32 v[68:69], v[2:3], v[6:7]
	v_pk_add_f32 v[2:3], v[2:3], v[6:7] neg_lo:[0,1] neg_hi:[0,1]
	v_pk_mul_f32 v[6:7], v[8:9], s[70:71] op_sel_hi:[1,0]
	v_mov_b32_e32 v135, v8
	v_pk_fma_f32 v[6:7], v[134:135], s[70:71], v[6:7] op_sel_hi:[1,0,1] neg_lo:[0,0,1] neg_hi:[0,0,1]
	v_xor_b32_e32 v134, 0x80000000, v17
	v_pk_add_f32 v[8:9], v[4:5], v[6:7]
	v_pk_add_f32 v[4:5], v[4:5], v[6:7] neg_lo:[0,1] neg_hi:[0,1]
	v_pk_mul_f32 v[6:7], v[16:17], s[60:61] op_sel_hi:[1,0]
	v_mov_b32_e32 v135, v16
	v_pk_fma_f32 v[6:7], v[134:135], s[62:63], v[6:7] op_sel_hi:[1,0,1] neg_lo:[0,0,1] neg_hi:[0,0,1]
	v_xor_b32_e32 v134, 0x80000000, v23
	v_pk_add_f32 v[16:17], v[0:1], v[6:7]
	v_pk_add_f32 v[0:1], v[0:1], v[6:7] neg_lo:[0,1] neg_hi:[0,1]
	v_pk_add_f32 v[6:7], v[20:21], v[72:73]
	v_pk_add_f32 v[20:21], v[20:21], v[72:73] neg_lo:[0,1] neg_hi:[0,1]
	v_pk_mul_f32 v[72:73], v[130:131], s[62:63] op_sel:[1,0] op_sel_hi:[0,0] neg_lo:[1,0]
	v_mov_b32_e32 v135, v22
	v_pk_fma_f32 v[72:73], v[130:131], s[60:61], v[72:73] op_sel_hi:[1,0,1]
	s_nop 0
	v_pk_add_f32 v[130:131], v[96:97], v[72:73]
	v_pk_add_f32 v[72:73], v[96:97], v[72:73] neg_lo:[0,1] neg_hi:[0,1]
	v_pk_mul_f32 v[96:97], v[88:89], s[70:71] op_sel:[1,0] op_sel_hi:[0,0] neg_lo:[1,0]
	s_nop 0
	v_pk_fma_f32 v[88:89], v[88:89], s[70:71], v[96:97] op_sel_hi:[1,0,1]
	s_nop 0
	v_pk_add_f32 v[96:97], v[74:75], v[88:89]
	v_pk_add_f32 v[74:75], v[74:75], v[88:89] neg_lo:[0,1] neg_hi:[0,1]
	v_pk_mul_f32 v[88:89], v[92:93], s[60:61] op_sel:[1,0] op_sel_hi:[0,0] neg_lo:[1,0]
	s_nop 0
	v_pk_fma_f32 v[88:89], v[92:93], s[62:63], v[88:89] op_sel_hi:[1,0,1]
	s_nop 0
	v_pk_add_f32 v[92:93], v[78:79], v[88:89]
	v_pk_add_f32 v[78:79], v[78:79], v[88:89] neg_lo:[0,1] neg_hi:[0,1]
	v_xor_b32_e32 v88, 0x80000000, v77
	v_mov_b32_e32 v89, v76
	v_pk_add_f32 v[76:77], v[82:83], v[88:89]
	v_pk_add_f32 v[82:83], v[82:83], v[88:89] neg_lo:[0,1] neg_hi:[0,1]
	v_pk_mul_f32 v[88:89], v[22:23], s[62:63] op_sel_hi:[1,0]
	s_nop 0
	v_pk_fma_f32 v[22:23], v[134:135], s[60:61], v[88:89] op_sel_hi:[1,0,1] neg_lo:[0,0,1] neg_hi:[0,0,1]
	v_xor_b32_e32 v134, 0x80000000, v27
	v_pk_add_f32 v[88:89], v[14:15], v[22:23]
	v_pk_add_f32 v[14:15], v[14:15], v[22:23] neg_lo:[0,1] neg_hi:[0,1]
	v_pk_mul_f32 v[22:23], v[26:27], s[70:71] op_sel_hi:[1,0]
	v_mov_b32_e32 v135, v26
	v_pk_fma_f32 v[22:23], v[134:135], s[70:71], v[22:23] op_sel_hi:[1,0,1] neg_lo:[0,0,1] neg_hi:[0,0,1]
	v_xor_b32_e32 v134, 0x80000000, v63
	v_pk_add_f32 v[26:27], v[18:19], v[22:23]
	v_pk_add_f32 v[18:19], v[18:19], v[22:23] neg_lo:[0,1] neg_hi:[0,1]
	v_pk_mul_f32 v[22:23], v[62:63], s[60:61] op_sel_hi:[1,0]
	v_mov_b32_e32 v135, v62
	v_pk_fma_f32 v[22:23], v[134:135], s[62:63], v[22:23] op_sel_hi:[1,0,1] neg_lo:[0,0,1] neg_hi:[0,0,1]
	v_xor_b32_e32 v134, 0x80000000, v73
	v_pk_add_f32 v[62:63], v[24:25], v[22:23]
	v_pk_add_f32 v[22:23], v[24:25], v[22:23] neg_lo:[0,1] neg_hi:[0,1]
	v_pk_add_f32 v[24:25], v[84:85], v[6:7]
	v_pk_add_f32 v[6:7], v[84:85], v[6:7] neg_lo:[0,1] neg_hi:[0,1]
	v_pk_mul_f32 v[84:85], v[130:131], s[58:59] op_sel:[1,0] op_sel_hi:[0,0] neg_lo:[1,0]
	v_mov_b32_e32 v135, v72
	v_pk_fma_f32 v[84:85], v[130:131], s[46:47], v[84:85] op_sel_hi:[1,0,1]
	s_nop 0
	v_pk_add_f32 v[130:131], v[94:95], v[84:85]
	v_pk_add_f32 v[84:85], v[94:95], v[84:85] neg_lo:[0,1] neg_hi:[0,1]
	v_pk_mul_f32 v[94:95], v[96:97], s[62:63] op_sel:[1,0] op_sel_hi:[0,0] neg_lo:[1,0]
	s_nop 0
	v_pk_fma_f32 v[94:95], v[96:97], s[60:61], v[94:95] op_sel_hi:[1,0,1]
	s_nop 0
	v_pk_add_f32 v[96:97], v[132:133], v[94:95]
	v_pk_add_f32 v[94:95], v[132:133], v[94:95] neg_lo:[0,1] neg_hi:[0,1]
	v_pk_mul_f32 v[132:133], v[92:93], s[66:67] op_sel:[1,0] op_sel_hi:[0,0] neg_lo:[1,0]
	s_nop 0
	v_pk_fma_f32 v[92:93], v[92:93], s[64:65], v[132:133] op_sel_hi:[1,0,1]
	s_nop 0
	v_pk_add_f32 v[132:133], v[86:87], v[92:93]
	v_pk_add_f32 v[86:87], v[86:87], v[92:93] neg_lo:[0,1] neg_hi:[0,1]
	v_pk_mul_f32 v[92:93], v[76:77], s[70:71] op_sel:[1,0] op_sel_hi:[0,0] neg_lo:[1,0]
	s_nop 0
	v_pk_fma_f32 v[76:77], v[76:77], s[70:71], v[92:93] op_sel_hi:[1,0,1]
	s_nop 0
	v_pk_add_f32 v[92:93], v[70:71], v[76:77]
	v_pk_add_f32 v[70:71], v[70:71], v[76:77] neg_lo:[0,1] neg_hi:[0,1]
	v_pk_mul_f32 v[76:77], v[88:89], s[64:65] op_sel:[1,0] op_sel_hi:[0,0] neg_lo:[1,0]
	s_nop 0
	v_pk_fma_f32 v[76:77], v[88:89], s[66:67], v[76:77] op_sel_hi:[1,0,1]
	s_nop 0
	v_pk_add_f32 v[88:89], v[68:69], v[76:77]
	v_pk_add_f32 v[68:69], v[68:69], v[76:77] neg_lo:[0,1] neg_hi:[0,1]
	v_pk_mul_f32 v[76:77], v[26:27], s[60:61] op_sel:[1,0] op_sel_hi:[0,0] neg_lo:[1,0]
	s_nop 0
	v_pk_fma_f32 v[26:27], v[26:27], s[62:63], v[76:77] op_sel_hi:[1,0,1]
	s_nop 0
	v_pk_add_f32 v[76:77], v[8:9], v[26:27]
	v_pk_add_f32 v[8:9], v[8:9], v[26:27] neg_lo:[0,1] neg_hi:[0,1]
	v_pk_mul_f32 v[26:27], v[62:63], s[46:47] op_sel:[1,0] op_sel_hi:[0,0] neg_lo:[1,0]
	s_nop 0
	v_pk_fma_f32 v[26:27], v[62:63], s[58:59], v[26:27] op_sel_hi:[1,0,1]
	s_nop 0
	v_pk_add_f32 v[62:63], v[16:17], v[26:27]
	v_pk_add_f32 v[16:17], v[16:17], v[26:27] neg_lo:[0,1] neg_hi:[0,1]
	v_xor_b32_e32 v26, 0x80000000, v21
	v_mov_b32_e32 v27, v20
	v_pk_add_f32 v[20:21], v[10:11], v[26:27]
	v_pk_add_f32 v[10:11], v[10:11], v[26:27] neg_lo:[0,1] neg_hi:[0,1]
	v_pk_mul_f32 v[26:27], v[72:73], s[58:59] op_sel_hi:[1,0]
	s_nop 0
	v_pk_fma_f32 v[26:27], v[134:135], s[46:47], v[26:27] op_sel_hi:[1,0,1] neg_lo:[0,0,1] neg_hi:[0,0,1]
	v_xor_b32_e32 v134, 0x80000000, v75
	v_pk_add_f32 v[72:73], v[90:91], v[26:27]
	v_pk_add_f32 v[26:27], v[90:91], v[26:27] neg_lo:[0,1] neg_hi:[0,1]
	v_pk_mul_f32 v[90:91], v[74:75], s[62:63] op_sel_hi:[1,0]
	v_mov_b32_e32 v135, v74
	v_pk_fma_f32 v[74:75], v[134:135], s[60:61], v[90:91] op_sel_hi:[1,0,1] neg_lo:[0,0,1] neg_hi:[0,0,1]
	v_xor_b32_e32 v134, 0x80000000, v79
	v_pk_add_f32 v[90:91], v[80:81], v[74:75]
	v_pk_add_f32 v[74:75], v[80:81], v[74:75] neg_lo:[0,1] neg_hi:[0,1]
	v_pk_mul_f32 v[80:81], v[78:79], s[66:67] op_sel_hi:[1,0]
	v_mov_b32_e32 v135, v78
	v_pk_fma_f32 v[78:79], v[134:135], s[64:65], v[80:81] op_sel_hi:[1,0,1] neg_lo:[0,0,1] neg_hi:[0,0,1]
	v_xor_b32_e32 v134, 0x80000000, v83
	v_pk_add_f32 v[80:81], v[12:13], v[78:79]
	v_pk_add_f32 v[12:13], v[12:13], v[78:79] neg_lo:[0,1] neg_hi:[0,1]
	v_pk_mul_f32 v[78:79], v[82:83], s[70:71] op_sel_hi:[1,0]
	v_mov_b32_e32 v135, v82
	v_pk_fma_f32 v[78:79], v[134:135], s[70:71], v[78:79] op_sel_hi:[1,0,1] neg_lo:[0,0,1] neg_hi:[0,0,1]
	v_xor_b32_e32 v134, 0x80000000, v15
	v_pk_add_f32 v[82:83], v[64:65], v[78:79]
	v_pk_add_f32 v[64:65], v[64:65], v[78:79] neg_lo:[0,1] neg_hi:[0,1]
	v_pk_mul_f32 v[78:79], v[14:15], s[64:65] op_sel_hi:[1,0]
	v_mov_b32_e32 v135, v14
	v_pk_fma_f32 v[14:15], v[134:135], s[66:67], v[78:79] op_sel_hi:[1,0,1] neg_lo:[0,0,1] neg_hi:[0,0,1]
	v_xor_b32_e32 v134, 0x80000000, v19
	v_pk_add_f32 v[78:79], v[2:3], v[14:15]
	v_pk_add_f32 v[2:3], v[2:3], v[14:15] neg_lo:[0,1] neg_hi:[0,1]
	v_pk_mul_f32 v[14:15], v[18:19], s[60:61] op_sel_hi:[1,0]
	v_mov_b32_e32 v135, v18
	v_pk_fma_f32 v[14:15], v[134:135], s[62:63], v[14:15] op_sel_hi:[1,0,1] neg_lo:[0,0,1] neg_hi:[0,0,1]
	v_xor_b32_e32 v134, 0x80000000, v23
	v_pk_add_f32 v[18:19], v[4:5], v[14:15]
	v_pk_add_f32 v[4:5], v[4:5], v[14:15] neg_lo:[0,1] neg_hi:[0,1]
	v_pk_mul_f32 v[14:15], v[22:23], s[46:47] op_sel_hi:[1,0]
	v_mov_b32_e32 v135, v22
	v_pk_fma_f32 v[14:15], v[134:135], s[58:59], v[14:15] op_sel_hi:[1,0,1] neg_lo:[0,0,1] neg_hi:[0,0,1]
	s_nop 0
	v_pk_add_f32 v[22:23], v[0:1], v[14:15]
	v_pk_add_f32 v[0:1], v[0:1], v[14:15] neg_lo:[0,1] neg_hi:[0,1]
	ds_write_b64 v67, v[24:25]
	ds_write_b64 v98, v[130:131]
	ds_write_b64 v99, v[96:97] offset:256
	ds_write_b64 v100, v[132:133] offset:256
	ds_write_b64 v101, v[92:93] offset:512
	ds_write_b64 v102, v[88:89] offset:512
	ds_write_b64 v103, v[76:77] offset:768
	ds_write_b64 v104, v[62:63] offset:768
	ds_write_b64 v105, v[20:21] offset:1024
	ds_write_b64 v106, v[72:73] offset:1024
	ds_write_b64 v107, v[90:91] offset:1280
	ds_write_b64 v108, v[80:81] offset:1280
	ds_write_b64 v109, v[82:83] offset:1536
	ds_write_b64 v110, v[78:79] offset:1536
	ds_write_b64 v111, v[18:19] offset:1792
	ds_write_b64 v112, v[22:23] offset:1792
	ds_write_b64 v113, v[6:7] offset:2048
	ds_write_b64 v114, v[84:85] offset:2048
	ds_write_b64 v115, v[94:95] offset:2304
	ds_write_b64 v116, v[86:87] offset:2304
	ds_write_b64 v117, v[70:71] offset:2560
	ds_write_b64 v118, v[68:69] offset:2560
	ds_write_b64 v119, v[8:9] offset:2816
	ds_write_b64 v120, v[16:17] offset:2816
	ds_write_b64 v121, v[10:11] offset:3072
	ds_write_b64 v122, v[26:27] offset:3072
	ds_write_b64 v123, v[74:75] offset:3328
	ds_write_b64 v124, v[12:13] offset:3328
	ds_write_b64 v125, v[64:65] offset:3584
	ds_write_b64 v126, v[2:3] offset:3584
	ds_write_b64 v127, v[4:5] offset:3840
	ds_write_b64 v128, v[0:1] offset:3840
	v_mov_b32_e32 v74, v146
	s_waitcnt lgkmcnt(0)
	s_barrier
	s_nop 0
	v_lshrrev_b32_e32 v0, 5, v74
	v_bfe_u32 v4, v74, 5, 4
	v_bitop3_b32 v0, v0, v74, 15 bitop3:0x6c
	v_bitop3_b32 v4, v4, v74, 16 bitop3:0x36
	v_lshlrev_b32_e32 v66, 3, v0
	v_lshlrev_b32_e32 v67, 3, v4
	v_add_u32_e32 v5, 16, v66
	v_add_u32_e32 v4, 16, v67
	v_add_u32_e32 v62, s47, v66
	v_add_u32_e32 v70, s9, v66
	ds_read2st64_b64 v[0:3], v5 offset1:16
	ds_read2st64_b64 v[16:19], v4 offset0:8 offset1:24
	ds_read2st64_b64 v[24:27], v5 offset0:32 offset1:48
	ds_read2st64_b64 v[8:11], v4 offset0:40 offset1:56
	ds_read2st64_b64 v[92:95], v5 offset0:64 offset1:80
	ds_read2st64_b64 v[12:15], v4 offset0:72 offset1:88
	ds_read2st64_b64 v[20:23], v5 offset0:96 offset1:112
	ds_read2st64_b64 v[4:7], v4 offset0:104 offset1:120
	ds_read_b64 v[68:69], v62
	ds_read_b64 v[72:73], v70
	v_add_u32_e32 v62, s19, v67
	v_add_u32_e32 v70, s8, v67
	ds_read_b64 v[84:85], v62
	ds_read_b64 v[90:91], v70
	v_add_u32_e32 v62, s18, v66
	v_add_u32_e32 v70, s7, v66
	ds_read_b64 v[96:97], v62
	ds_read_b64 v[100:101], v70
	v_add_u32_e32 v62, s17, v67
	v_add_u32_e32 v70, s6, v67
	ds_read_b64 v[64:65], v62
	ds_read_b64 v[70:71], v70
	v_add_u32_e32 v62, s13, v66
	v_add_u32_e32 v75, s5, v66
	ds_read_b64 v[86:87], v62
	ds_read_b64 v[102:103], v75
	v_add_u32_e32 v62, s12, v67
	v_add_u32_e32 v75, s4, v67
	ds_read_b64 v[80:81], v62
	ds_read_b64 v[88:89], v75
	v_add_u32_e32 v62, s11, v66
	v_add_u32_e32 v66, s1, v66
	ds_read_b64 v[98:99], v62
	ds_read_b64 v[104:105], v66
	v_add_u32_e32 v62, s10, v67
	v_add_u32_e32 v66, s0, v67
	ds_read_b64 v[62:63], v62
	ds_read_b64 v[66:67], v66
	s_waitcnt lgkmcnt(14)
	s_nop 0
	v_cvt_f32_i32_e32 v74, v74
	s_nop 0
	s_lshl_b64 s[0:1], s[44:45], 2
	s_add_u32 s0, s24, s0
	v_mul_f32_e32 v74, 0x38800000, v74
	v_cos_f32_e32 v78, v74
	v_sin_f32_e32 v79, v74
	s_addc_u32 s1, s59, s1
	s_and_b64 vcc, s[14:15], exec
	v_add_f32_e32 v76, v78, v78
	v_pk_mul_f32 v[74:75], v[78:79], v[78:79]
	v_mul_f32_e32 v76, v79, v76
	s_nop 0
	s_nop 0
	v_mov_b32_e32 v108, v79
	v_pk_add_f32 v[74:75], v[74:75], v[74:75] op_sel:[0,1] op_sel_hi:[0,1] neg_lo:[0,1] neg_hi:[0,1]
	v_pk_mul_f32 v[82:83], v[78:79], v[76:77] op_sel:[1,0] op_sel_hi:[0,0] neg_lo:[1,0]
	v_pk_mul_f32 v[106:107], v[68:69], v[108:109] op_sel:[1,0] op_sel_hi:[0,0] neg_lo:[1,0]
	v_pk_fma_f32 v[82:83], v[78:79], v[74:75], v[82:83]
	v_pk_fma_f32 v[68:69], v[68:69], v[78:79], v[106:107] op_sel_hi:[1,0,1]
	v_pk_mul_f32 v[78:79], v[76:77], s[48:49] op_sel_hi:[0,1]
	v_pk_fma_f32 v[106:107], v[74:75], s[40:41], v[78:79]
	s_nop 0
	v_pk_mul_f32 v[78:79], v[92:93], v[106:107] op_sel:[1,1] op_sel_hi:[0,1] neg_lo:[1,0]
	s_nop 0
	v_pk_fma_f32 v[78:79], v[92:93], v[106:107], v[78:79] op_sel_hi:[1,0,1]
	v_pk_mul_f32 v[92:93], v[76:77], v[82:83] op_sel:[0,1] op_sel_hi:[0,0] neg_lo:[0,1]
	v_pk_mul_f32 v[108:109], v[72:73], v[82:83] op_sel:[1,1] op_sel_hi:[0,1] neg_lo:[1,0]
	v_pk_fma_f32 v[92:93], v[74:75], v[82:83], v[92:93]
	v_pk_fma_f32 v[72:73], v[72:73], v[82:83], v[108:109] op_sel_hi:[1,0,1]
	v_pk_mul_f32 v[82:83], v[76:77], v[106:107] op_sel:[0,1] op_sel_hi:[0,0] neg_lo:[0,1]
	v_pk_fma_f32 v[106:107], v[74:75], v[106:107], v[82:83]
	s_nop 0
	v_pk_mul_f32 v[82:83], v[24:25], v[106:107] op_sel:[1,1] op_sel_hi:[0,1] neg_lo:[1,0]
	s_nop 0
	v_pk_fma_f32 v[82:83], v[24:25], v[106:107], v[82:83] op_sel_hi:[1,0,1]
	v_pk_mul_f32 v[24:25], v[76:77], v[92:93] op_sel:[0,1] op_sel_hi:[0,0] neg_lo:[0,1]
	v_pk_fma_f32 v[108:109], v[74:75], v[92:93], v[24:25]
	s_waitcnt lgkmcnt(7)
	v_pk_mul_f32 v[24:25], v[86:87], v[92:93] op_sel:[1,1] op_sel_hi:[0,1] neg_lo:[1,0]
	s_nop 0
	v_pk_fma_f32 v[24:25], v[86:87], v[92:93], v[24:25] op_sel_hi:[1,0,1]
	v_pk_mul_f32 v[86:87], v[76:77], v[106:107] op_sel:[0,1] op_sel_hi:[0,0] neg_lo:[0,1]
	v_pk_fma_f32 v[92:93], v[74:75], v[106:107], v[86:87]
	s_nop 0
	v_pk_mul_f32 v[86:87], v[20:21], v[92:93] op_sel:[1,1] op_sel_hi:[0,1] neg_lo:[1,0]
	s_nop 0
	v_pk_fma_f32 v[86:87], v[20:21], v[92:93], v[86:87] op_sel_hi:[1,0,1]
	v_pk_mul_f32 v[20:21], v[76:77], v[108:109] op_sel:[0,1] op_sel_hi:[0,0] neg_lo:[0,1]
	v_pk_fma_f32 v[106:107], v[74:75], v[108:109], v[20:21]
	s_waitcnt lgkmcnt(6)
	v_pk_mul_f32 v[20:21], v[102:103], v[108:109] op_sel:[1,1] op_sel_hi:[0,1] neg_lo:[1,0]
	s_nop 0
	v_pk_fma_f32 v[20:21], v[102:103], v[108:109], v[20:21] op_sel_hi:[1,0,1]
	v_pk_mul_f32 v[102:103], v[76:77], v[92:93] op_sel:[0,1] op_sel_hi:[0,0] neg_lo:[0,1]
	v_pk_fma_f32 v[102:103], v[74:75], v[92:93], v[102:103]
	s_nop 0
	v_pk_mul_f32 v[92:93], v[2:3], v[102:103] op_sel:[1,1] op_sel_hi:[0,1] neg_lo:[1,0]
	s_nop 0
	v_pk_fma_f32 v[92:93], v[2:3], v[102:103], v[92:93] op_sel_hi:[1,0,1]
	v_pk_mul_f32 v[2:3], v[76:77], v[106:107] op_sel:[0,1] op_sel_hi:[0,0] neg_lo:[0,1]
	v_pk_fma_f32 v[108:109], v[74:75], v[106:107], v[2:3]
	v_pk_mul_f32 v[2:3], v[96:97], v[106:107] op_sel:[1,1] op_sel_hi:[0,1] neg_lo:[1,0]
	s_nop 0
	v_pk_fma_f32 v[2:3], v[96:97], v[106:107], v[2:3] op_sel_hi:[1,0,1]
	v_pk_mul_f32 v[96:97], v[76:77], v[102:103] op_sel:[0,1] op_sel_hi:[0,0] neg_lo:[0,1]
	v_pk_fma_f32 v[102:103], v[74:75], v[102:103], v[96:97]
	s_nop 0
	v_pk_mul_f32 v[96:97], v[94:95], v[102:103] op_sel:[1,1] op_sel_hi:[0,1] neg_lo:[1,0]
	s_nop 0
	v_pk_fma_f32 v[96:97], v[94:95], v[102:103], v[96:97] op_sel_hi:[1,0,1]
	v_pk_mul_f32 v[94:95], v[76:77], v[108:109] op_sel:[0,1] op_sel_hi:[0,0] neg_lo:[0,1]
	v_pk_fma_f32 v[106:107], v[74:75], v[108:109], v[94:95]
	v_pk_mul_f32 v[94:95], v[100:101], v[108:109] op_sel:[1,1] op_sel_hi:[0,1] neg_lo:[1,0]
	s_nop 0
	v_pk_fma_f32 v[94:95], v[100:101], v[108:109], v[94:95] op_sel_hi:[1,0,1]
	v_pk_mul_f32 v[100:101], v[76:77], v[102:103] op_sel:[0,1] op_sel_hi:[0,0] neg_lo:[0,1]
	v_pk_fma_f32 v[100:101], v[74:75], v[102:103], v[100:101]
	s_nop 0
	v_pk_mul_f32 v[102:103], v[26:27], v[100:101] op_sel:[1,1] op_sel_hi:[0,1] neg_lo:[1,0]
	s_waitcnt lgkmcnt(3)
	v_pk_fma_f32 v[26:27], v[26:27], v[100:101], v[102:103] op_sel_hi:[1,0,1]
	v_pk_mul_f32 v[102:103], v[76:77], v[106:107] op_sel:[0,1] op_sel_hi:[0,0] neg_lo:[0,1]
	v_pk_mul_f32 v[108:109], v[98:99], v[106:107] op_sel:[1,1] op_sel_hi:[0,1] neg_lo:[1,0]
	v_pk_fma_f32 v[102:103], v[74:75], v[106:107], v[102:103]
	v_pk_fma_f32 v[98:99], v[98:99], v[106:107], v[108:109] op_sel_hi:[1,0,1]
	v_pk_mul_f32 v[106:107], v[76:77], v[100:101] op_sel:[0,1] op_sel_hi:[0,0] neg_lo:[0,1]
	v_pk_fma_f32 v[100:101], v[74:75], v[100:101], v[106:107]
	s_nop 0
	v_pk_mul_f32 v[106:107], v[22:23], v[100:101] op_sel:[1,1] op_sel_hi:[0,1] neg_lo:[1,0]
	s_waitcnt lgkmcnt(2)
	v_pk_fma_f32 v[22:23], v[22:23], v[100:101], v[106:107] op_sel_hi:[1,0,1]
	v_pk_mul_f32 v[106:107], v[76:77], v[102:103] op_sel:[0,1] op_sel_hi:[0,0] neg_lo:[0,1]
	v_pk_mul_f32 v[108:109], v[104:105], v[102:103] op_sel:[1,1] op_sel_hi:[0,1] neg_lo:[1,0]
	v_pk_fma_f32 v[106:107], v[74:75], v[102:103], v[106:107]
	v_pk_fma_f32 v[102:103], v[104:105], v[102:103], v[108:109] op_sel_hi:[1,0,1]
	v_pk_mul_f32 v[104:105], v[76:77], v[100:101] op_sel:[0,1] op_sel_hi:[0,0] neg_lo:[0,1]
	v_pk_fma_f32 v[100:101], v[74:75], v[100:101], v[104:105]
	s_nop 0
	v_pk_mul_f32 v[104:105], v[16:17], v[100:101] op_sel:[1,1] op_sel_hi:[0,1] neg_lo:[1,0]
	s_nop 0
	v_pk_fma_f32 v[16:17], v[16:17], v[100:101], v[104:105] op_sel_hi:[1,0,1]
	v_pk_mul_f32 v[104:105], v[76:77], v[106:107] op_sel:[0,1] op_sel_hi:[0,0] neg_lo:[0,1]
	v_pk_mul_f32 v[108:109], v[84:85], v[106:107] op_sel:[1,1] op_sel_hi:[0,1] neg_lo:[1,0]
	v_pk_fma_f32 v[104:105], v[74:75], v[106:107], v[104:105]
	v_pk_fma_f32 v[84:85], v[84:85], v[106:107], v[108:109] op_sel_hi:[1,0,1]
	v_pk_mul_f32 v[106:107], v[76:77], v[100:101] op_sel:[0,1] op_sel_hi:[0,0] neg_lo:[0,1]
	v_pk_fma_f32 v[100:101], v[74:75], v[100:101], v[106:107]
	s_nop 0
	v_pk_mul_f32 v[106:107], v[12:13], v[100:101] op_sel:[1,1] op_sel_hi:[0,1] neg_lo:[1,0]
	s_nop 0
	v_pk_fma_f32 v[12:13], v[12:13], v[100:101], v[106:107] op_sel_hi:[1,0,1]
	v_pk_mul_f32 v[106:107], v[76:77], v[104:105] op_sel:[0,1] op_sel_hi:[0,0] neg_lo:[0,1]
	v_pk_mul_f32 v[108:109], v[90:91], v[104:105] op_sel:[1,1] op_sel_hi:[0,1] neg_lo:[1,0]
	v_pk_fma_f32 v[106:107], v[74:75], v[104:105], v[106:107]
	v_pk_fma_f32 v[90:91], v[90:91], v[104:105], v[108:109] op_sel_hi:[1,0,1]
	v_pk_mul_f32 v[104:105], v[76:77], v[100:101] op_sel:[0,1] op_sel_hi:[0,0] neg_lo:[0,1]
	v_pk_fma_f32 v[100:101], v[74:75], v[100:101], v[104:105]
	s_nop 0
	v_pk_mul_f32 v[104:105], v[8:9], v[100:101] op_sel:[1,1] op_sel_hi:[0,1] neg_lo:[1,0]
	s_nop 0
	v_pk_fma_f32 v[8:9], v[8:9], v[100:101], v[104:105] op_sel_hi:[1,0,1]
	v_pk_mul_f32 v[104:105], v[76:77], v[106:107] op_sel:[0,1] op_sel_hi:[0,0] neg_lo:[0,1]
	v_pk_mul_f32 v[108:109], v[80:81], v[106:107] op_sel:[1,1] op_sel_hi:[0,1] neg_lo:[1,0]
	v_pk_fma_f32 v[104:105], v[74:75], v[106:107], v[104:105]
	v_pk_fma_f32 v[80:81], v[80:81], v[106:107], v[108:109] op_sel_hi:[1,0,1]
	v_pk_mul_f32 v[106:107], v[76:77], v[100:101] op_sel:[0,1] op_sel_hi:[0,0] neg_lo:[0,1]
	v_pk_fma_f32 v[100:101], v[74:75], v[100:101], v[106:107]
	s_nop 0
	v_pk_mul_f32 v[106:107], v[4:5], v[100:101] op_sel:[1,1] op_sel_hi:[0,1] neg_lo:[1,0]
	s_nop 0
	v_pk_fma_f32 v[4:5], v[4:5], v[100:101], v[106:107] op_sel_hi:[1,0,1]
	v_pk_mul_f32 v[106:107], v[76:77], v[104:105] op_sel:[0,1] op_sel_hi:[0,0] neg_lo:[0,1]
	v_pk_mul_f32 v[108:109], v[88:89], v[104:105] op_sel:[1,1] op_sel_hi:[0,1] neg_lo:[1,0]
	v_pk_fma_f32 v[106:107], v[74:75], v[104:105], v[106:107]
	v_pk_fma_f32 v[88:89], v[88:89], v[104:105], v[108:109] op_sel_hi:[1,0,1]
	v_pk_mul_f32 v[104:105], v[76:77], v[100:101] op_sel:[0,1] op_sel_hi:[0,0] neg_lo:[0,1]
	v_pk_fma_f32 v[100:101], v[74:75], v[100:101], v[104:105]
	s_nop 0
	v_pk_mul_f32 v[104:105], v[18:19], v[100:101] op_sel:[1,1] op_sel_hi:[0,1] neg_lo:[1,0]
	s_nop 0
	v_pk_fma_f32 v[18:19], v[18:19], v[100:101], v[104:105] op_sel_hi:[1,0,1]
	v_pk_mul_f32 v[104:105], v[76:77], v[106:107] op_sel:[0,1] op_sel_hi:[0,0] neg_lo:[0,1]
	v_pk_mul_f32 v[108:109], v[64:65], v[106:107] op_sel:[1,1] op_sel_hi:[0,1] neg_lo:[1,0]
	v_pk_fma_f32 v[104:105], v[74:75], v[106:107], v[104:105]
	v_pk_fma_f32 v[64:65], v[64:65], v[106:107], v[108:109] op_sel_hi:[1,0,1]
	v_pk_mul_f32 v[106:107], v[76:77], v[100:101] op_sel:[0,1] op_sel_hi:[0,0] neg_lo:[0,1]
	v_pk_fma_f32 v[100:101], v[74:75], v[100:101], v[106:107]
	s_nop 0
	v_pk_mul_f32 v[106:107], v[14:15], v[100:101] op_sel:[1,1] op_sel_hi:[0,1] neg_lo:[1,0]
	s_nop 0
	v_pk_fma_f32 v[14:15], v[14:15], v[100:101], v[106:107] op_sel_hi:[1,0,1]
	v_pk_mul_f32 v[106:107], v[76:77], v[104:105] op_sel:[0,1] op_sel_hi:[0,0] neg_lo:[0,1]
	v_pk_mul_f32 v[108:109], v[70:71], v[104:105] op_sel:[1,1] op_sel_hi:[0,1] neg_lo:[1,0]
	v_pk_fma_f32 v[106:107], v[74:75], v[104:105], v[106:107]
	v_pk_fma_f32 v[70:71], v[70:71], v[104:105], v[108:109] op_sel_hi:[1,0,1]
	v_pk_mul_f32 v[104:105], v[76:77], v[100:101] op_sel:[0,1] op_sel_hi:[0,0] neg_lo:[0,1]
	v_pk_fma_f32 v[100:101], v[74:75], v[100:101], v[104:105]
	s_nop 0
	v_pk_mul_f32 v[104:105], v[10:11], v[100:101] op_sel:[1,1] op_sel_hi:[0,1] neg_lo:[1,0]
	s_waitcnt lgkmcnt(1)
	v_pk_fma_f32 v[10:11], v[10:11], v[100:101], v[104:105] op_sel_hi:[1,0,1]
	v_pk_mul_f32 v[104:105], v[76:77], v[106:107] op_sel:[0,1] op_sel_hi:[0,0] neg_lo:[0,1]
	v_pk_mul_f32 v[108:109], v[62:63], v[106:107] op_sel:[1,1] op_sel_hi:[0,1] neg_lo:[1,0]
	v_pk_fma_f32 v[104:105], v[74:75], v[106:107], v[104:105]
	v_pk_fma_f32 v[62:63], v[62:63], v[106:107], v[108:109] op_sel_hi:[1,0,1]
	v_pk_mul_f32 v[76:77], v[76:77], v[100:101] op_sel:[0,1] op_sel_hi:[0,0] neg_lo:[0,1]
	v_pk_fma_f32 v[74:75], v[74:75], v[100:101], v[76:77]
	s_nop 0
	v_pk_mul_f32 v[76:77], v[6:7], v[74:75] op_sel:[1,1] op_sel_hi:[0,1] neg_lo:[1,0]
	s_nop 0
	v_pk_fma_f32 v[6:7], v[6:7], v[74:75], v[76:77] op_sel_hi:[1,0,1]
	s_waitcnt lgkmcnt(0)
	v_pk_mul_f32 v[74:75], v[66:67], v[104:105] op_sel:[1,1] op_sel_hi:[0,1] neg_lo:[1,0]
	v_pk_add_f32 v[76:77], v[82:83], v[8:9]
	v_pk_fma_f32 v[66:67], v[66:67], v[104:105], v[74:75] op_sel_hi:[1,0,1]
	v_pk_add_f32 v[74:75], v[0:1], v[16:17]
	v_pk_add_f32 v[0:1], v[0:1], v[16:17] neg_lo:[0,1] neg_hi:[0,1]
	v_pk_add_f32 v[16:17], v[92:93], v[18:19]
	v_pk_add_f32 v[18:19], v[92:93], v[18:19] neg_lo:[0,1] neg_hi:[0,1]
	v_pk_add_f32 v[8:9], v[82:83], v[8:9] neg_lo:[0,1] neg_hi:[0,1]
	v_pk_add_f32 v[82:83], v[26:27], v[10:11]
	v_pk_add_f32 v[10:11], v[26:27], v[10:11] neg_lo:[0,1] neg_hi:[0,1]
	v_pk_add_f32 v[92:93], v[86:87], v[4:5]
	v_pk_add_f32 v[4:5], v[86:87], v[4:5] neg_lo:[0,1] neg_hi:[0,1]
	v_pk_add_f32 v[86:87], v[22:23], v[6:7]
	v_pk_add_f32 v[6:7], v[22:23], v[6:7] neg_lo:[0,1] neg_hi:[0,1]
	v_pk_add_f32 v[22:23], v[68:69], v[84:85]
	v_pk_add_f32 v[68:69], v[68:69], v[84:85] neg_lo:[0,1] neg_hi:[0,1]
	v_pk_add_f32 v[84:85], v[2:3], v[64:65]
	v_pk_add_f32 v[2:3], v[2:3], v[64:65] neg_lo:[0,1] neg_hi:[0,1]
	v_pk_add_f32 v[64:65], v[24:25], v[80:81]
	v_pk_add_f32 v[24:25], v[24:25], v[80:81] neg_lo:[0,1] neg_hi:[0,1]
	v_pk_add_f32 v[80:81], v[98:99], v[62:63]
	v_pk_add_f32 v[62:63], v[98:99], v[62:63] neg_lo:[0,1] neg_hi:[0,1]
	v_pk_add_f32 v[98:99], v[74:75], v[16:17]
	v_pk_add_f32 v[16:17], v[74:75], v[16:17] neg_lo:[0,1] neg_hi:[0,1]
	v_xor_b32_e32 v74, 0x80000000, v19
	v_mov_b32_e32 v75, v18
	v_pk_add_f32 v[26:27], v[78:79], v[12:13]
	v_pk_add_f32 v[12:13], v[78:79], v[12:13] neg_lo:[0,1] neg_hi:[0,1]
	v_pk_add_f32 v[78:79], v[96:97], v[14:15]
	v_pk_add_f32 v[14:15], v[96:97], v[14:15] neg_lo:[0,1] neg_hi:[0,1]
	v_pk_add_f32 v[18:19], v[0:1], v[74:75]
	v_pk_add_f32 v[0:1], v[0:1], v[74:75] neg_lo:[0,1] neg_hi:[0,1]
	v_pk_add_f32 v[74:75], v[76:77], v[82:83]
	v_pk_add_f32 v[76:77], v[76:77], v[82:83] neg_lo:[0,1] neg_hi:[0,1]
	v_xor_b32_e32 v82, 0x80000000, v11
	v_mov_b32_e32 v83, v10
	v_pk_add_f32 v[10:11], v[8:9], v[82:83]
	v_pk_add_f32 v[8:9], v[8:9], v[82:83] neg_lo:[0,1] neg_hi:[0,1]
	v_pk_add_f32 v[82:83], v[26:27], v[78:79]
	v_pk_add_f32 v[26:27], v[26:27], v[78:79] neg_lo:[0,1] neg_hi:[0,1]
	v_xor_b32_e32 v78, 0x80000000, v15
	v_mov_b32_e32 v79, v14
	v_pk_add_f32 v[14:15], v[12:13], v[78:79]
	v_pk_add_f32 v[12:13], v[12:13], v[78:79] neg_lo:[0,1] neg_hi:[0,1]
	v_pk_add_f32 v[78:79], v[92:93], v[86:87]
	v_pk_add_f32 v[86:87], v[92:93], v[86:87] neg_lo:[0,1] neg_hi:[0,1]
	v_xor_b32_e32 v92, 0x80000000, v7
	v_mov_b32_e32 v93, v6
	v_pk_add_f32 v[6:7], v[4:5], v[92:93]
	v_pk_add_f32 v[4:5], v[4:5], v[92:93] neg_lo:[0,1] neg_hi:[0,1]
	v_pk_add_f32 v[92:93], v[22:23], v[84:85]
	v_pk_add_f32 v[22:23], v[22:23], v[84:85] neg_lo:[0,1] neg_hi:[0,1]
	v_xor_b32_e32 v84, 0x80000000, v3
	v_mov_b32_e32 v85, v2
	v_pk_add_f32 v[96:97], v[72:73], v[90:91]
	v_pk_add_f32 v[72:73], v[72:73], v[90:91] neg_lo:[0,1] neg_hi:[0,1]
	v_pk_add_f32 v[90:91], v[94:95], v[70:71]
	v_pk_add_f32 v[70:71], v[94:95], v[70:71] neg_lo:[0,1] neg_hi:[0,1]
	v_pk_add_f32 v[2:3], v[68:69], v[84:85]
	v_pk_add_f32 v[68:69], v[68:69], v[84:85] neg_lo:[0,1] neg_hi:[0,1]
	v_pk_add_f32 v[84:85], v[64:65], v[80:81]
	v_pk_add_f32 v[64:65], v[64:65], v[80:81] neg_lo:[0,1] neg_hi:[0,1]
	v_xor_b32_e32 v80, 0x80000000, v63
	v_mov_b32_e32 v81, v62
	v_pk_add_f32 v[94:95], v[20:21], v[88:89]
	v_pk_add_f32 v[20:21], v[20:21], v[88:89] neg_lo:[0,1] neg_hi:[0,1]
	v_pk_add_f32 v[88:89], v[102:103], v[66:67]
	v_pk_add_f32 v[66:67], v[102:103], v[66:67] neg_lo:[0,1] neg_hi:[0,1]
	v_pk_add_f32 v[62:63], v[24:25], v[80:81]
	v_pk_add_f32 v[24:25], v[24:25], v[80:81] neg_lo:[0,1] neg_hi:[0,1]
	v_pk_add_f32 v[80:81], v[96:97], v[90:91]
	v_pk_add_f32 v[90:91], v[96:97], v[90:91] neg_lo:[0,1] neg_hi:[0,1]
	v_xor_b32_e32 v96, 0x80000000, v71
	v_mov_b32_e32 v97, v70
	v_pk_add_f32 v[70:71], v[72:73], v[96:97]
	v_pk_add_f32 v[72:73], v[72:73], v[96:97] neg_lo:[0,1] neg_hi:[0,1]
	v_pk_add_f32 v[96:97], v[94:95], v[88:89]
	v_pk_add_f32 v[88:89], v[94:95], v[88:89] neg_lo:[0,1] neg_hi:[0,1]
	v_xor_b32_e32 v94, 0x80000000, v67
	v_mov_b32_e32 v95, v66
	v_pk_add_f32 v[66:67], v[20:21], v[94:95]
	v_pk_add_f32 v[20:21], v[20:21], v[94:95] neg_lo:[0,1] neg_hi:[0,1]
	v_pk_add_f32 v[94:95], v[98:99], v[74:75]
	v_pk_add_f32 v[74:75], v[98:99], v[74:75] neg_lo:[0,1] neg_hi:[0,1]
	v_pk_mul_f32 v[98:99], v[10:11], s[70:71] op_sel:[1,0] op_sel_hi:[0,0] neg_lo:[1,0]
	v_xor_b32_e32 v100, 0x80000000, v9
	v_pk_fma_f32 v[10:11], v[10:11], s[70:71], v[98:99] op_sel_hi:[1,0,1]
	v_mov_b32_e32 v101, v8
	v_pk_add_f32 v[98:99], v[18:19], v[10:11]
	v_pk_add_f32 v[10:11], v[18:19], v[10:11] neg_lo:[0,1] neg_hi:[0,1]
	v_xor_b32_e32 v18, 0x80000000, v77
	v_mov_b32_e32 v19, v76
	v_pk_add_f32 v[76:77], v[16:17], v[18:19]
	v_pk_add_f32 v[16:17], v[16:17], v[18:19] neg_lo:[0,1] neg_hi:[0,1]
	v_pk_mul_f32 v[18:19], v[8:9], s[70:71] op_sel_hi:[1,0]
	s_nop 0
	v_pk_fma_f32 v[8:9], v[100:101], s[70:71], v[18:19] op_sel_hi:[1,0,1] neg_lo:[0,0,1] neg_hi:[0,0,1]
	v_xor_b32_e32 v100, 0x80000000, v5
	v_pk_add_f32 v[18:19], v[0:1], v[8:9]
	v_pk_add_f32 v[0:1], v[0:1], v[8:9] neg_lo:[0,1] neg_hi:[0,1]
	v_pk_add_f32 v[8:9], v[82:83], v[78:79]
	v_pk_add_f32 v[78:79], v[82:83], v[78:79] neg_lo:[0,1] neg_hi:[0,1]
	v_pk_mul_f32 v[82:83], v[6:7], s[70:71] op_sel:[1,0] op_sel_hi:[0,0] neg_lo:[1,0]
	v_mov_b32_e32 v101, v4
	v_pk_fma_f32 v[6:7], v[6:7], s[70:71], v[82:83] op_sel_hi:[1,0,1]
	s_nop 0
	v_pk_add_f32 v[82:83], v[14:15], v[6:7]
	v_pk_add_f32 v[6:7], v[14:15], v[6:7] neg_lo:[0,1] neg_hi:[0,1]
	v_xor_b32_e32 v14, 0x80000000, v87
	v_mov_b32_e32 v15, v86
	v_pk_add_f32 v[86:87], v[26:27], v[14:15]
	v_pk_add_f32 v[14:15], v[26:27], v[14:15] neg_lo:[0,1] neg_hi:[0,1]
	v_pk_mul_f32 v[26:27], v[4:5], s[70:71] op_sel_hi:[1,0]
	s_nop 0
	v_pk_fma_f32 v[4:5], v[100:101], s[70:71], v[26:27] op_sel_hi:[1,0,1] neg_lo:[0,0,1] neg_hi:[0,0,1]
	v_xor_b32_e32 v100, 0x80000000, v25
	v_pk_add_f32 v[26:27], v[12:13], v[4:5]
	v_pk_add_f32 v[4:5], v[12:13], v[4:5] neg_lo:[0,1] neg_hi:[0,1]
	v_pk_add_f32 v[12:13], v[92:93], v[84:85]
	v_pk_add_f32 v[84:85], v[92:93], v[84:85] neg_lo:[0,1] neg_hi:[0,1]
	v_pk_mul_f32 v[92:93], v[62:63], s[70:71] op_sel:[1,0] op_sel_hi:[0,0] neg_lo:[1,0]
	v_mov_b32_e32 v101, v24
	v_pk_fma_f32 v[62:63], v[62:63], s[70:71], v[92:93] op_sel_hi:[1,0,1]
	s_nop 0
	v_pk_add_f32 v[92:93], v[2:3], v[62:63]
	v_pk_add_f32 v[2:3], v[2:3], v[62:63] neg_lo:[0,1] neg_hi:[0,1]
	v_xor_b32_e32 v62, 0x80000000, v65
	v_mov_b32_e32 v63, v64
	v_pk_add_f32 v[64:65], v[22:23], v[62:63]
	v_pk_add_f32 v[22:23], v[22:23], v[62:63] neg_lo:[0,1] neg_hi:[0,1]
	v_pk_mul_f32 v[62:63], v[24:25], s[70:71] op_sel_hi:[1,0]
	s_nop 0
	v_pk_fma_f32 v[24:25], v[100:101], s[70:71], v[62:63] op_sel_hi:[1,0,1] neg_lo:[0,0,1] neg_hi:[0,0,1]
	v_xor_b32_e32 v100, 0x80000000, v21
	v_pk_add_f32 v[62:63], v[68:69], v[24:25]
	v_pk_add_f32 v[24:25], v[68:69], v[24:25] neg_lo:[0,1] neg_hi:[0,1]
	v_pk_add_f32 v[68:69], v[80:81], v[96:97]
	v_pk_add_f32 v[80:81], v[80:81], v[96:97] neg_lo:[0,1] neg_hi:[0,1]
	v_pk_mul_f32 v[96:97], v[66:67], s[70:71] op_sel:[1,0] op_sel_hi:[0,0] neg_lo:[1,0]
	v_mov_b32_e32 v101, v20
	v_pk_fma_f32 v[66:67], v[66:67], s[70:71], v[96:97] op_sel_hi:[1,0,1]
	s_nop 0
	v_pk_add_f32 v[96:97], v[70:71], v[66:67]
	v_pk_add_f32 v[66:67], v[70:71], v[66:67] neg_lo:[0,1] neg_hi:[0,1]
	v_xor_b32_e32 v70, 0x80000000, v89
	v_mov_b32_e32 v71, v88
	v_pk_add_f32 v[88:89], v[90:91], v[70:71]
	v_pk_add_f32 v[70:71], v[90:91], v[70:71] neg_lo:[0,1] neg_hi:[0,1]
	v_pk_mul_f32 v[90:91], v[20:21], s[70:71] op_sel_hi:[1,0]
	s_nop 0
	v_pk_fma_f32 v[20:21], v[100:101], s[70:71], v[90:91] op_sel_hi:[1,0,1] neg_lo:[0,0,1] neg_hi:[0,0,1]
	s_nop 0
	v_pk_add_f32 v[90:91], v[72:73], v[20:21]
	v_pk_add_f32 v[20:21], v[72:73], v[20:21] neg_lo:[0,1] neg_hi:[0,1]
	v_pk_add_f32 v[72:73], v[94:95], v[8:9]
	v_pk_add_f32 v[8:9], v[94:95], v[8:9] neg_lo:[0,1] neg_hi:[0,1]
	v_pk_mul_f32 v[94:95], v[82:83], s[62:63] op_sel:[1,0] op_sel_hi:[0,0] neg_lo:[1,0]
	s_nop 0
	v_pk_fma_f32 v[82:83], v[82:83], s[60:61], v[94:95] op_sel_hi:[1,0,1]
	s_nop 0
	v_pk_add_f32 v[94:95], v[98:99], v[82:83]
	v_pk_add_f32 v[82:83], v[98:99], v[82:83] neg_lo:[0,1] neg_hi:[0,1]
	v_pk_mul_f32 v[98:99], v[86:87], s[70:71] op_sel:[1,0] op_sel_hi:[0,0] neg_lo:[1,0]
	s_nop 0
	v_pk_fma_f32 v[86:87], v[86:87], s[70:71], v[98:99] op_sel_hi:[1,0,1]
	s_nop 0
	v_pk_add_f32 v[98:99], v[76:77], v[86:87]
	v_pk_add_f32 v[86:87], v[76:77], v[86:87] neg_lo:[0,1] neg_hi:[0,1]
	v_pk_mul_f32 v[76:77], v[26:27], s[60:61] op_sel:[1,0] op_sel_hi:[0,0] neg_lo:[1,0]
	s_nop 0
	v_pk_fma_f32 v[26:27], v[26:27], s[62:63], v[76:77] op_sel_hi:[1,0,1]
	v_xor_b32_e32 v76, 0x80000000, v67
	v_pk_add_f32 v[100:101], v[18:19], v[26:27]
	v_pk_add_f32 v[26:27], v[18:19], v[26:27] neg_lo:[0,1] neg_hi:[0,1]
	v_pk_add_f32 v[102:103], v[74:75], v[78:79] op_sel:[0,1] op_sel_hi:[1,0] neg_lo:[0,1]
	v_pk_add_f32 v[104:105], v[74:75], v[78:79] op_sel:[0,1] op_sel_hi:[1,0] neg_hi:[0,1]
	v_pk_mul_f32 v[18:19], v[6:7], s[62:63] op_sel_hi:[1,0]
	v_xor_b32_e32 v74, 0x80000000, v7
	v_mov_b32_e32 v75, v6
	v_pk_fma_f32 v[6:7], v[74:75], s[60:61], v[18:19] op_sel_hi:[1,0,1] neg_lo:[0,0,1] neg_hi:[0,0,1]
	v_xor_b32_e32 v74, 0x80000000, v15
	v_pk_add_f32 v[18:19], v[10:11], v[6:7]
	v_pk_add_f32 v[6:7], v[10:11], v[6:7] neg_lo:[0,1] neg_hi:[0,1]
	v_pk_mul_f32 v[10:11], v[14:15], s[70:71] op_sel_hi:[1,0]
	v_mov_b32_e32 v75, v14
	v_pk_fma_f32 v[10:11], v[74:75], s[70:71], v[10:11] op_sel_hi:[1,0,1] neg_lo:[0,0,1] neg_hi:[0,0,1]
	v_xor_b32_e32 v74, 0x80000000, v5
	v_pk_add_f32 v[14:15], v[16:17], v[10:11]
	v_pk_add_f32 v[10:11], v[16:17], v[10:11] neg_lo:[0,1] neg_hi:[0,1]
	v_pk_mul_f32 v[16:17], v[4:5], s[60:61] op_sel_hi:[1,0]
	v_mov_b32_e32 v75, v4
	v_pk_fma_f32 v[4:5], v[74:75], s[62:63], v[16:17] op_sel_hi:[1,0,1] neg_lo:[0,0,1] neg_hi:[0,0,1]
	v_xor_b32_e32 v74, 0x80000000, v89
	v_pk_add_f32 v[16:17], v[0:1], v[4:5]
	v_pk_add_f32 v[106:107], v[0:1], v[4:5] neg_lo:[0,1] neg_hi:[0,1]
	v_pk_add_f32 v[0:1], v[12:13], v[68:69]
	v_pk_add_f32 v[4:5], v[12:13], v[68:69] neg_lo:[0,1] neg_hi:[0,1]
	v_mov_b32_e32 v75, v88
	v_pk_mul_f32 v[12:13], v[96:97], s[62:63] op_sel:[1,0] op_sel_hi:[0,0] neg_lo:[1,0]
	v_pk_mul_f32 v[74:75], v[74:75], s[70:71] op_sel_hi:[1,0]
	v_pk_fma_f32 v[12:13], v[96:97], s[60:61], v[12:13] op_sel_hi:[1,0,1]
	v_pk_fma_f32 v[74:75], v[88:89], s[70:71], v[74:75] op_sel_hi:[1,0,1]
	v_pk_add_f32 v[68:69], v[92:93], v[12:13]
	v_pk_add_f32 v[12:13], v[92:93], v[12:13] neg_lo:[0,1] neg_hi:[0,1]
	v_pk_add_f32 v[88:89], v[64:65], v[74:75]
	v_pk_add_f32 v[92:93], v[64:65], v[74:75] neg_lo:[0,1] neg_hi:[0,1]
	v_pk_mul_f32 v[64:65], v[90:91], s[60:61] op_sel:[1,0] op_sel_hi:[0,0] neg_lo:[1,0]
	v_pk_add_f32 v[78:79], v[72:73], v[0:1]
	v_pk_fma_f32 v[64:65], v[90:91], s[62:63], v[64:65] op_sel_hi:[1,0,1]
	s_nop 0
	v_pk_add_f32 v[74:75], v[62:63], v[64:65]
	v_pk_add_f32 v[90:91], v[62:63], v[64:65] neg_lo:[0,1] neg_hi:[0,1]
	v_pk_mul_f32 v[0:1], v[68:69], s[58:59] op_sel:[1,0] op_sel_hi:[0,0] neg_lo:[1,0]
	v_pk_add_f32 v[64:65], v[84:85], v[80:81] op_sel:[0,1] op_sel_hi:[1,0] neg_lo:[0,1]
	v_pk_add_f32 v[80:81], v[84:85], v[80:81] op_sel:[0,1] op_sel_hi:[1,0] neg_hi:[0,1]
	v_pk_mul_f32 v[62:63], v[66:67], s[62:63] op_sel_hi:[1,0]
	v_mov_b32_e32 v77, v66
	v_pk_fma_f32 v[0:1], v[68:69], s[46:47], v[0:1] op_sel_hi:[1,0,1]
	v_pk_fma_f32 v[62:63], v[76:77], s[60:61], v[62:63] op_sel_hi:[1,0,1] neg_lo:[0,0,1] neg_hi:[0,0,1]
	v_pk_add_f32 v[76:77], v[94:95], v[0:1]
	v_pk_mul_f32 v[0:1], v[88:89], s[62:63] op_sel:[1,0] op_sel_hi:[0,0] neg_lo:[1,0]
	v_pk_add_f32 v[84:85], v[2:3], v[62:63]
	v_pk_fma_f32 v[0:1], v[88:89], s[60:61], v[0:1] op_sel_hi:[1,0,1]
	v_pk_add_f32 v[2:3], v[2:3], v[62:63] neg_lo:[0,1] neg_hi:[0,1]
	v_pk_add_f32 v[72:73], v[98:99], v[0:1]
	v_pk_mul_f32 v[0:1], v[74:75], s[66:67] op_sel:[1,0] op_sel_hi:[0,0] neg_lo:[1,0]
	v_pk_mul_f32 v[62:63], v[70:71], s[70:71] op_sel_hi:[1,0]
	v_pk_fma_f32 v[0:1], v[74:75], s[64:65], v[0:1] op_sel_hi:[1,0,1]
	v_xor_b32_e32 v66, 0x80000000, v71
	v_pk_add_f32 v[74:75], v[100:101], v[0:1]
	v_pk_mul_f32 v[0:1], v[64:65], s[70:71] op_sel:[1,0] op_sel_hi:[0,0] neg_lo:[1,0]
	v_mov_b32_e32 v67, v70
	v_pk_fma_f32 v[0:1], v[64:65], s[70:71], v[0:1] op_sel_hi:[1,0,1]
	v_pk_fma_f32 v[62:63], v[66:67], s[70:71], v[62:63] op_sel_hi:[1,0,1] neg_lo:[0,0,1] neg_hi:[0,0,1]
	v_pk_add_f32 v[66:67], v[102:103], v[0:1]
	v_pk_mul_f32 v[0:1], v[84:85], s[64:65] op_sel:[1,0] op_sel_hi:[0,0] neg_lo:[1,0]
	v_pk_add_f32 v[70:71], v[22:23], v[62:63]
	v_pk_fma_f32 v[0:1], v[84:85], s[66:67], v[0:1] op_sel_hi:[1,0,1]
	v_pk_add_f32 v[96:97], v[22:23], v[62:63] neg_lo:[0,1] neg_hi:[0,1]
	v_pk_mul_f32 v[22:23], v[20:21], s[60:61] op_sel_hi:[1,0]
	v_pk_add_f32 v[68:69], v[18:19], v[0:1]
	v_pk_fma_f32 v[20:21], v[20:21], s[62:63], v[22:23] op_sel:[1,0,0] op_sel_hi:[0,0,1] neg_lo:[1,0,1] neg_hi:[0,0,1]
	v_pk_mul_f32 v[0:1], v[70:71], s[60:61] op_sel:[1,0] op_sel_hi:[0,0] neg_lo:[1,0]
	v_pk_add_f32 v[22:23], v[24:25], v[20:21]
	v_pk_fma_f32 v[0:1], v[70:71], s[62:63], v[0:1] op_sel_hi:[1,0,1]
	v_pk_add_f32 v[108:109], v[24:25], v[20:21] neg_lo:[0,1] neg_hi:[0,1]
	v_pk_add_f32 v[62:63], v[14:15], v[0:1]
	v_pk_mul_f32 v[0:1], v[22:23], s[46:47] op_sel:[1,0] op_sel_hi:[0,0] neg_lo:[1,0]
	s_nop 0
	v_pk_fma_f32 v[0:1], v[22:23], s[58:59], v[0:1] op_sel_hi:[1,0,1]
	s_nop 0
	v_pk_add_f32 v[64:65], v[16:17], v[0:1]
	v_pk_add_f32 v[22:23], v[8:9], v[4:5] op_sel:[0,1] op_sel_hi:[1,0] neg_lo:[0,1]
	v_pk_mul_f32 v[0:1], v[12:13], s[58:59] op_sel_hi:[1,0]
	v_xor_b32_e32 v4, 0x80000000, v13
	v_mov_b32_e32 v5, v12
	v_pk_fma_f32 v[0:1], v[4:5], s[46:47], v[0:1] op_sel_hi:[1,0,1] neg_lo:[0,0,1] neg_hi:[0,0,1]
	v_xor_b32_e32 v4, 0x80000000, v93
	v_pk_add_f32 v[24:25], v[82:83], v[0:1]
	v_pk_mul_f32 v[0:1], v[92:93], s[62:63] op_sel_hi:[1,0]
	v_mov_b32_e32 v5, v92
	v_pk_fma_f32 v[0:1], v[4:5], s[60:61], v[0:1] op_sel_hi:[1,0,1] neg_lo:[0,0,1] neg_hi:[0,0,1]
	v_xor_b32_e32 v4, 0x80000000, v91
	v_pk_add_f32 v[18:19], v[86:87], v[0:1]
	v_pk_mul_f32 v[0:1], v[90:91], s[66:67] op_sel_hi:[1,0]
	v_mov_b32_e32 v5, v90
	v_pk_fma_f32 v[0:1], v[4:5], s[64:65], v[0:1] op_sel_hi:[1,0,1] neg_lo:[0,0,1] neg_hi:[0,0,1]
	s_nop 0
	v_pk_add_f32 v[20:21], v[26:27], v[0:1]
	v_pk_mul_f32 v[0:1], v[80:81], s[70:71] op_sel_hi:[1,0]
	s_nop 0
	v_pk_fma_f32 v[0:1], v[80:81], s[70:71], v[0:1] op_sel:[1,0,0] op_sel_hi:[0,0,1] neg_lo:[1,0,1] neg_hi:[0,0,1]
	v_xor_b32_e32 v8, 0x80000000, v3
	v_pk_add_f32 v[4:5], v[104:105], v[0:1]
	v_pk_mul_f32 v[0:1], v[2:3], s[64:65] op_sel_hi:[1,0]
	v_mov_b32_e32 v9, v2
	v_pk_fma_f32 v[0:1], v[8:9], s[66:67], v[0:1] op_sel_hi:[1,0,1] neg_lo:[0,0,1] neg_hi:[0,0,1]
	s_nop 0
	v_pk_add_f32 v[6:7], v[6:7], v[0:1]
	v_pk_mul_f32 v[0:1], v[96:97], s[60:61] op_sel_hi:[1,0]
	s_nop 0
	v_pk_fma_f32 v[0:1], v[96:97], s[62:63], v[0:1] op_sel:[1,0,0] op_sel_hi:[0,0,1] neg_lo:[1,0,1] neg_hi:[0,0,1]
	v_pk_mul_f32 v[2:3], v[108:109], s[46:47] op_sel_hi:[1,0]
	v_pk_add_f32 v[0:1], v[10:11], v[0:1]
	v_xor_b32_e32 v8, 0x80000000, v109
	v_mov_b32_e32 v9, v108
	v_mov_b32_e32 v10, v146
	v_pk_fma_f32 v[2:3], v[8:9], s[58:59], v[2:3] op_sel_hi:[1,0,1] neg_lo:[0,0,1] neg_hi:[0,0,1]
	global_load_dword v8, v145, s[0:1]
	s_movk_i32 s0, 0x200
	s_cselect_b32 s4, s0, 0x400
	s_add_i32 s0, s4, s68
	s_ashr_i32 s1, s0, 31
	s_lshl_b32 s6, s4, 2
	s_add_u32 s4, s90, s6
	s_addc_u32 s5, s91, 0
	s_lshl_b64 s[0:1], s[0:1], 14
	v_min_i32_e32 v70, 0x1ffe, v10
	v_mov_b32_e32 v9, s6
	s_add_u32 s36, s26, s0
	v_ashrrev_i32_e32 v11, 31, v10
	v_ashrrev_i32_e32 v71, 31, v70
	global_load_dword v16, v9, s[90:91]
	global_load_dword v14, v153, s[4:5] offset:2048
	global_load_dword v17, v154, s[4:5]
	global_load_dword v12, v9, s[94:95]
	s_addc_u32 s37, s27, s1
	v_max_i32_e32 v9, 1, v10
	v_lshlrev_b64 v[82:83], 1, v[10:11]
	v_lshlrev_b64 v[84:85], 1, v[70:71]
	v_lshl_add_u64 v[26:27], s[36:37], 0, v[82:83]
	v_lshlrev_b32_e32 v9, 1, v9
	v_lshl_add_u64 v[70:71], s[36:37], 0, v[84:85]
	global_load_ushort v13, v[26:27], off
	s_add_u32 s88, s30, s0
	global_load_ushort v70, v[70:71], off offset:2
	s_addc_u32 s89, s31, s1
	global_load_ushort v15, v9, s[36:37] offset:-2
	v_cmp_lt_i32_e64 s[0:1], 0, v10
	v_cmp_gt_i32_e64 s[4:5], s74, v10
	v_pk_add_f32 v[2:3], v[106:107], v[2:3]
	v_cndmask_b32_e64 v81, 0, 1.0, s[0:1]
	v_cndmask_b32_e64 v86, 0, 1.0, s[4:5]
	v_add_u32_e32 v92, 0x200, v10
	v_cmp_lt_i32_e64 s[20:21], s25, v10
	v_cmp_gt_i32_e64 s[18:19], s42, v10
	v_add_u32_e32 v90, 0x400, v10
	v_cmp_lt_i32_e64 s[16:17], s33, v10
	v_cmp_gt_i32_e64 s[0:1], s51, v10
	v_add_u32_e32 v88, 0x600, v10
	v_cmp_lt_i32_e64 s[12:13], s43, v10
	v_cmp_gt_i32_e64 s[10:11], s50, v10
	v_cmp_lt_i32_e64 s[8:9], s2, v10
	v_cmp_gt_i32_e64 s[6:7], s38, v10
	v_cmp_lt_i32_e64 s[4:5], s65, v10
	v_cmp_gt_i32_e64 s[22:23], s34, v10
	s_waitcnt vmcnt(2)
	v_lshlrev_b32_e32 v13, 16, v13
	s_waitcnt vmcnt(1)
	v_lshlrev_b32_e32 v70, 16, v70
	v_mul_f32_e32 v70, v86, v70
	s_waitcnt vmcnt(0)
	v_lshlrev_b32_e32 v15, 16, v15
	v_mul_f32_e32 v15, v81, v15
	v_mul_f32_e32 v15, v16, v15
	v_fmac_f32_e32 v15, v14, v13
	v_fmac_f32_e32 v15, v17, v70
	v_lshl_add_u64 v[70:71], s[88:89], 0, v[82:83]
	v_lshl_add_u64 v[82:83], s[88:89], 0, v[84:85]
	v_add_f32_e32 v80, v12, v15
	global_load_ushort v13, v[70:71], off
	global_load_ushort v15, v[82:83], off offset:2
	v_add_u32_e32 v84, 0x800, v10
	global_load_ushort v9, v9, s[88:89] offset:-2
	v_add_u32_e32 v82, 0xa00, v10
	s_waitcnt vmcnt(2)
	v_lshlrev_b32_e32 v13, 16, v13
	s_waitcnt vmcnt(1)
	v_lshlrev_b32_e32 v15, 16, v15
	v_mul_f32_e32 v15, v86, v15
	s_waitcnt vmcnt(0)
	v_lshlrev_b32_e32 v9, 16, v9
	v_mul_f32_e32 v9, v81, v9
	v_mul_f32_e32 v9, v16, v9
	v_fmac_f32_e32 v9, v14, v13
	v_fmac_f32_e32 v9, v17, v15
	v_add_f32_e32 v86, v12, v9
	s_cbranch_vccnz .LBB0_540
	v_readlane_b32 s98, v252, 56
	s_lshl_b64 s[0:1], s[92:93], 1
	s_add_u32 s4, s0, s30
	s_addc_u32 s5, s1, s31
	s_add_u32 s0, s0, s26
	s_addc_u32 s1, s1, s27
	s_add_u32 s18, s96, 0x800000
	s_addc_u32 s19, s97, 0
	s_cmpk_gt_i32 s98, 0xff
	s_cbranch_scc1 .Lhy_ep1_comb_L0
	v_lshlrev_b32_e32 v109, 1, v10
	v_add_u32_e32 v254, 0x1e00, v10
	v_add_u32_e32 v253, 0x1000, v109
	v_cmp_gt_i32_e32 vcc, 0x1fff, v254
	v_add_u32_e32 v251, 0x2000, v109
	v_add_u32_e32 v250, 0x3000, v109
	v_min_i32_e32 v254, 0x1ffe, v254
	v_cndmask_b32_e64 v255, 0, 1.0, vcc
	v_lshlrev_b32_e32 v254, 1, v254
	global_load_ushort v9, v109, s[0:1]
	global_load_ushort v11, v109, s[4:5]
	global_load_ushort v13, v109, s[36:37] offset:1022
	global_load_ushort v15, v109, s[36:37] offset:1024
	global_load_ushort v81, v109, s[36:37] offset:1026
	global_load_ushort v83, v109, s[88:89] offset:1022
	global_load_ushort v85, v109, s[88:89] offset:1024
	global_load_ushort v87, v109, s[88:89] offset:1026
	global_load_ushort v89, v109, s[0:1] offset:1024
	global_load_ushort v91, v109, s[4:5] offset:1024
	global_load_ushort v93, v109, s[36:37] offset:2046
	global_load_ushort v94, v109, s[36:37] offset:2048
	global_load_ushort v95, v109, s[36:37] offset:2050
	global_load_ushort v96, v109, s[88:89] offset:2046
	global_load_ushort v97, v109, s[88:89] offset:2048
	global_load_ushort v98, v109, s[88:89] offset:2050
	global_load_ushort v99, v109, s[0:1] offset:2048
	global_load_ushort v100, v109, s[4:5] offset:2048
	global_load_ushort v101, v109, s[36:37] offset:3070
	global_load_ushort v102, v109, s[36:37] offset:3072
	global_load_ushort v103, v109, s[36:37] offset:3074
	global_load_ushort v104, v109, s[88:89] offset:3070
	global_load_ushort v105, v109, s[88:89] offset:3072
	global_load_ushort v106, v109, s[88:89] offset:3074
	global_load_ushort v107, v109, s[0:1] offset:3072
	global_load_ushort v108, v109, s[4:5] offset:3072
	global_load_ushort v111, v253, s[36:37] offset:-2
	global_load_ushort v112, v253, s[36:37]
	global_load_ushort v113, v253, s[36:37] offset:2
	global_load_ushort v114, v253, s[88:89] offset:-2
	global_load_ushort v115, v253, s[88:89]
	global_load_ushort v116, v253, s[88:89] offset:2
	global_load_ushort v117, v253, s[0:1]
	global_load_ushort v118, v253, s[4:5]
	global_load_ushort v119, v253, s[36:37] offset:1022
	global_load_ushort v120, v253, s[36:37] offset:1024
	global_load_ushort v121, v253, s[36:37] offset:1026
	global_load_ushort v122, v253, s[88:89] offset:1022
	global_load_ushort v123, v253, s[88:89] offset:1024
	global_load_ushort v124, v253, s[88:89] offset:1026
	global_load_ushort v125, v253, s[0:1] offset:1024
	global_load_ushort v126, v253, s[4:5] offset:1024
	global_load_ushort v127, v253, s[36:37] offset:2046
	global_load_ushort v128, v253, s[36:37] offset:2048
	global_load_ushort v129, v253, s[36:37] offset:2050
	global_load_ushort v130, v253, s[88:89] offset:2046
	global_load_ushort v131, v253, s[88:89] offset:2048
	global_load_ushort v132, v253, s[88:89] offset:2050
	global_load_ushort v133, v253, s[0:1] offset:2048
	global_load_ushort v134, v253, s[4:5] offset:2048
	global_load_ushort v135, v253, s[36:37] offset:3070
	global_load_ushort v136, v253, s[36:37] offset:3072
	global_load_ushort v137, v253, s[36:37] offset:3074
	global_load_ushort v138, v253, s[88:89] offset:3070
	global_load_ushort v139, v253, s[88:89] offset:3072
	global_load_ushort v140, v253, s[88:89] offset:3074
	global_load_ushort v141, v253, s[0:1] offset:3072
	global_load_ushort v142, v253, s[4:5] offset:3072
	global_load_ushort v143, v251, s[36:37] offset:-2
	global_load_ushort v163, v251, s[36:37]
	global_load_ushort v164, v251, s[36:37] offset:2
	global_load_ushort v165, v251, s[88:89] offset:-2
	global_load_ushort v166, v251, s[88:89]
	global_load_ushort v167, v251, s[88:89] offset:2
	global_load_ushort v168, v251, s[0:1]
	global_load_ushort v169, v251, s[4:5]
	global_load_ushort v170, v251, s[36:37] offset:1022
	global_load_ushort v171, v251, s[36:37] offset:1024
	global_load_ushort v172, v251, s[36:37] offset:1026
	global_load_ushort v173, v251, s[88:89] offset:1022
	global_load_ushort v174, v251, s[88:89] offset:1024
	global_load_ushort v175, v251, s[88:89] offset:1026
	global_load_ushort v176, v251, s[0:1] offset:1024
	global_load_ushort v177, v251, s[4:5] offset:1024
	global_load_ushort v178, v251, s[36:37] offset:2046
	global_load_ushort v179, v251, s[36:37] offset:2048
	global_load_ushort v180, v251, s[36:37] offset:2050
	global_load_ushort v181, v251, s[88:89] offset:2046
	global_load_ushort v182, v251, s[88:89] offset:2048
	global_load_ushort v183, v251, s[88:89] offset:2050
	global_load_ushort v184, v251, s[0:1] offset:2048
	global_load_ushort v185, v251, s[4:5] offset:2048
	global_load_ushort v186, v251, s[36:37] offset:3070
	global_load_ushort v187, v251, s[36:37] offset:3072
	global_load_ushort v188, v251, s[36:37] offset:3074
	global_load_ushort v189, v251, s[88:89] offset:3070
	global_load_ushort v190, v251, s[88:89] offset:3072
	global_load_ushort v191, v251, s[88:89] offset:3074
	global_load_ushort v192, v251, s[0:1] offset:3072
	global_load_ushort v193, v251, s[4:5] offset:3072
	global_load_ushort v194, v250, s[36:37] offset:-2
	global_load_ushort v195, v250, s[36:37]
	global_load_ushort v196, v250, s[36:37] offset:2
	global_load_ushort v197, v250, s[88:89] offset:-2
	global_load_ushort v221, v250, s[88:89]
	global_load_ushort v222, v250, s[88:89] offset:2
	global_load_ushort v223, v250, s[0:1]
	global_load_ushort v224, v250, s[4:5]
	global_load_ushort v225, v250, s[36:37] offset:1022
	global_load_ushort v226, v250, s[36:37] offset:1024
	global_load_ushort v227, v250, s[36:37] offset:1026
	global_load_ushort v228, v250, s[88:89] offset:1022
	global_load_ushort v229, v250, s[88:89] offset:1024
	global_load_ushort v230, v250, s[88:89] offset:1026
	global_load_ushort v231, v250, s[0:1] offset:1024
	global_load_ushort v232, v250, s[4:5] offset:1024
	global_load_ushort v233, v250, s[36:37] offset:2046
	global_load_ushort v234, v250, s[36:37] offset:2048
	global_load_ushort v235, v250, s[36:37] offset:2050
	global_load_ushort v236, v250, s[88:89] offset:2046
	global_load_ushort v237, v250, s[88:89] offset:2048
	global_load_ushort v238, v250, s[88:89] offset:2050
	global_load_ushort v239, v250, s[0:1] offset:2048
	global_load_ushort v240, v250, s[4:5] offset:2048
	global_load_ushort v241, v250, s[36:37] offset:3070
	global_load_ushort v242, v250, s[36:37] offset:3072
	global_load_ushort v243, v254, s[36:37] offset:2
	global_load_ushort v244, v250, s[88:89] offset:3070
	global_load_ushort v245, v250, s[88:89] offset:3072
	global_load_ushort v246, v254, s[88:89] offset:2
	global_load_ushort v247, v250, s[0:1] offset:3072
	global_load_ushort v248, v250, s[4:5] offset:3072
	s_waitcnt vmcnt(63)
	v_fma_f32 v27, v32, v8, v78
	v_mul_f32_e32 v70, v80, v27
	v_lshlrev_b32_e32 v9, 16, v9
	v_mul_f32_e32 v84, 0xbfb8aa3b, v9
	v_exp_f32_e32 v84, v84
	s_nop 0
	v_add_f32_e32 v84, 1.0, v84
	v_div_scale_f32 v71, s[28:29], v84, v84, v9
	v_rcp_f32_e32 v82, v71
	s_nop 0
	v_fma_f32 v92, -v71, v82, 1.0
	v_fmac_f32_e32 v82, v92, v82
	v_div_scale_f32 v88, vcc, v9, v84, v9
	v_mul_f32_e32 v90, v88, v82
	v_fma_f32 v92, -v71, v90, v88
	v_fmac_f32_e32 v90, v92, v82
	v_fma_f32 v71, -v71, v90, v88
	v_div_fmas_f32 v71, v71, v82, v90
	v_div_fixup_f32 v9, v71, v84, v9
	v_mul_f32_e32 v70, v70, v9
	v_fma_f32 v27, v34, v8, v79
	v_mul_f32_e32 v110, v86, v27
	v_lshlrev_b32_e32 v11, 16, v11
	v_mul_f32_e32 v84, 0xbfb8aa3b, v11
	v_exp_f32_e32 v84, v84
	s_nop 0
	v_add_f32_e32 v84, 1.0, v84
	v_div_scale_f32 v71, s[28:29], v84, v84, v11
	v_rcp_f32_e32 v82, v71
	s_nop 0
	v_fma_f32 v92, -v71, v82, 1.0
	v_fmac_f32_e32 v82, v92, v82
	v_div_scale_f32 v88, vcc, v11, v84, v11
	v_mul_f32_e32 v90, v88, v82
	v_fma_f32 v92, -v71, v90, v88
	v_fmac_f32_e32 v90, v92, v82
	v_fma_f32 v71, -v71, v90, v88
	v_div_fmas_f32 v71, v71, v82, v90
	v_div_fixup_f32 v11, v71, v84, v11
	v_mul_f32_e32 v110, v110, v11
	v_cvt_pk_bf16_f32 v198, v70, v110
	v_lshlrev_b32_e32 v15, 16, v15
	v_lshlrev_b32_e32 v81, 16, v81
	v_lshlrev_b32_e32 v13, 16, v13
	v_mul_f32_e32 v13, v16, v13
	v_fmac_f32_e32 v13, v14, v15
	v_fmac_f32_e32 v13, v17, v81
	v_add_f32_e32 v13, v12, v13
	v_fma_f32 v27, v33, v8, v76
	v_mul_f32_e32 v70, v27, v13
	v_lshlrev_b32_e32 v89, 16, v89
	v_mul_f32_e32 v84, 0xbfb8aa3b, v89
	v_exp_f32_e32 v84, v84
	s_nop 0
	v_add_f32_e32 v84, 1.0, v84
	v_div_scale_f32 v71, s[28:29], v84, v84, v89
	v_rcp_f32_e32 v82, v71
	s_nop 0
	v_fma_f32 v92, -v71, v82, 1.0
	v_fmac_f32_e32 v82, v92, v82
	v_div_scale_f32 v88, vcc, v89, v84, v89
	v_mul_f32_e32 v90, v88, v82
	v_fma_f32 v92, -v71, v90, v88
	v_fmac_f32_e32 v90, v92, v82
	v_fma_f32 v71, -v71, v90, v88
	v_div_fmas_f32 v71, v71, v82, v90
	v_div_fixup_f32 v89, v71, v84, v89
	v_mul_f32_e32 v70, v70, v89
	v_lshlrev_b32_e32 v85, 16, v85
	v_lshlrev_b32_e32 v87, 16, v87
	v_lshlrev_b32_e32 v83, 16, v83
	v_mul_f32_e32 v83, v16, v83
	v_fmac_f32_e32 v83, v14, v85
	v_fmac_f32_e32 v83, v17, v87
	v_add_f32_e32 v83, v12, v83
	v_fma_f32 v27, v35, v8, v77
	v_mul_f32_e32 v110, v27, v83
	v_lshlrev_b32_e32 v91, 16, v91
	v_mul_f32_e32 v84, 0xbfb8aa3b, v91
	v_exp_f32_e32 v84, v84
	s_nop 0
	v_add_f32_e32 v84, 1.0, v84
	v_div_scale_f32 v71, s[28:29], v84, v84, v91
	v_rcp_f32_e32 v82, v71
	s_nop 0
	v_fma_f32 v92, -v71, v82, 1.0
	v_fmac_f32_e32 v82, v92, v82
	v_div_scale_f32 v88, vcc, v91, v84, v91
	v_mul_f32_e32 v90, v88, v82
	v_fma_f32 v92, -v71, v90, v88
	v_fmac_f32_e32 v90, v92, v82
	v_fma_f32 v71, -v71, v90, v88
	v_div_fmas_f32 v71, v71, v82, v90
	v_div_fixup_f32 v91, v71, v84, v91
	v_mul_f32_e32 v110, v110, v91
	v_cvt_pk_bf16_f32 v199, v70, v110
	v_lshlrev_b32_e32 v94, 16, v94
	v_lshlrev_b32_e32 v95, 16, v95
	v_lshlrev_b32_e32 v93, 16, v93
	v_mul_f32_e32 v93, v16, v93
	v_fmac_f32_e32 v93, v14, v94
	v_fmac_f32_e32 v93, v17, v95
	v_add_f32_e32 v93, v12, v93
	v_fma_f32 v27, v37, v8, v72
	v_mul_f32_e32 v70, v27, v93
	v_lshlrev_b32_e32 v99, 16, v99
	v_mul_f32_e32 v84, 0xbfb8aa3b, v99
	v_exp_f32_e32 v84, v84
	s_nop 0
	v_add_f32_e32 v84, 1.0, v84
	v_div_scale_f32 v71, s[28:29], v84, v84, v99
	v_rcp_f32_e32 v82, v71
	s_nop 0
	v_fma_f32 v92, -v71, v82, 1.0
	v_fmac_f32_e32 v82, v92, v82
	v_div_scale_f32 v88, vcc, v99, v84, v99
	v_mul_f32_e32 v90, v88, v82
	v_fma_f32 v92, -v71, v90, v88
	v_fmac_f32_e32 v90, v92, v82
	v_fma_f32 v71, -v71, v90, v88
	v_div_fmas_f32 v71, v71, v82, v90
	v_div_fixup_f32 v99, v71, v84, v99
	v_mul_f32_e32 v70, v70, v99
	v_lshlrev_b32_e32 v97, 16, v97
	v_lshlrev_b32_e32 v98, 16, v98
	v_lshlrev_b32_e32 v96, 16, v96
	v_mul_f32_e32 v96, v16, v96
	v_fmac_f32_e32 v96, v14, v97
	v_fmac_f32_e32 v96, v17, v98
	v_add_f32_e32 v96, v12, v96
	v_fma_f32 v27, v31, v8, v73
	v_mul_f32_e32 v110, v27, v96
	v_lshlrev_b32_e32 v100, 16, v100
	v_mul_f32_e32 v84, 0xbfb8aa3b, v100
	v_exp_f32_e32 v84, v84
	s_nop 0
	v_add_f32_e32 v84, 1.0, v84
	v_div_scale_f32 v71, s[28:29], v84, v84, v100
	v_rcp_f32_e32 v82, v71
	s_nop 0
	v_fma_f32 v92, -v71, v82, 1.0
	v_fmac_f32_e32 v82, v92, v82
	v_div_scale_f32 v88, vcc, v100, v84, v100
	v_mul_f32_e32 v90, v88, v82
	v_fma_f32 v92, -v71, v90, v88
	v_fmac_f32_e32 v90, v92, v82
	v_fma_f32 v71, -v71, v90, v88
	v_div_fmas_f32 v71, v71, v82, v90
	v_div_fixup_f32 v100, v71, v84, v100
	v_mul_f32_e32 v110, v110, v100
	v_cvt_pk_bf16_f32 v200, v70, v110
	v_lshlrev_b32_e32 v102, 16, v102
	v_lshlrev_b32_e32 v103, 16, v103
	v_lshlrev_b32_e32 v101, 16, v101
	v_mul_f32_e32 v101, v16, v101
	v_fmac_f32_e32 v101, v14, v102
	v_fmac_f32_e32 v101, v17, v103
	v_add_f32_e32 v101, v12, v101
	v_fma_f32 v27, v36, v8, v74
	v_mul_f32_e32 v70, v27, v101
	v_lshlrev_b32_e32 v107, 16, v107
	v_mul_f32_e32 v84, 0xbfb8aa3b, v107
	v_exp_f32_e32 v84, v84
	s_nop 0
	v_add_f32_e32 v84, 1.0, v84
	v_div_scale_f32 v71, s[28:29], v84, v84, v107
	v_rcp_f32_e32 v82, v71
	s_nop 0
	v_fma_f32 v92, -v71, v82, 1.0
	v_fmac_f32_e32 v82, v92, v82
	v_div_scale_f32 v88, vcc, v107, v84, v107
	v_mul_f32_e32 v90, v88, v82
	v_fma_f32 v92, -v71, v90, v88
	v_fmac_f32_e32 v90, v92, v82
	v_fma_f32 v71, -v71, v90, v88
	v_div_fmas_f32 v71, v71, v82, v90
	v_div_fixup_f32 v107, v71, v84, v107
	v_mul_f32_e32 v70, v70, v107
	v_lshlrev_b32_e32 v105, 16, v105
	v_lshlrev_b32_e32 v106, 16, v106
	v_lshlrev_b32_e32 v104, 16, v104
	v_mul_f32_e32 v104, v16, v104
	v_fmac_f32_e32 v104, v14, v105
	v_fmac_f32_e32 v104, v17, v106
	v_add_f32_e32 v104, v12, v104
	v_fma_f32 v27, v30, v8, v75
	v_mul_f32_e32 v110, v27, v104
	v_lshlrev_b32_e32 v108, 16, v108
	v_mul_f32_e32 v84, 0xbfb8aa3b, v108
	v_exp_f32_e32 v84, v84
	s_nop 0
	v_add_f32_e32 v84, 1.0, v84
	v_div_scale_f32 v71, s[28:29], v84, v84, v108
	v_rcp_f32_e32 v82, v71
	s_nop 0
	v_fma_f32 v92, -v71, v82, 1.0
	v_fmac_f32_e32 v82, v92, v82
	v_div_scale_f32 v88, vcc, v108, v84, v108
	v_mul_f32_e32 v90, v88, v82
	v_fma_f32 v92, -v71, v90, v88
	v_fmac_f32_e32 v90, v92, v82
	v_fma_f32 v71, -v71, v90, v88
	v_div_fmas_f32 v71, v71, v82, v90
	v_div_fixup_f32 v108, v71, v84, v108
	v_mul_f32_e32 v110, v110, v108
	v_cvt_pk_bf16_f32 v201, v70, v110
	s_waitcnt vmcnt(63)
	v_lshlrev_b32_e32 v112, 16, v112
	v_lshlrev_b32_e32 v113, 16, v113
	v_lshlrev_b32_e32 v111, 16, v111
	v_mul_f32_e32 v111, v16, v111
	v_fmac_f32_e32 v111, v14, v112
	v_fmac_f32_e32 v111, v17, v113
	v_add_f32_e32 v111, v12, v111
	v_fma_f32 v27, v39, v8, v66
	v_mul_f32_e32 v70, v27, v111
	v_lshlrev_b32_e32 v117, 16, v117
	v_mul_f32_e32 v84, 0xbfb8aa3b, v117
	v_exp_f32_e32 v84, v84
	s_nop 0
	v_add_f32_e32 v84, 1.0, v84
	v_div_scale_f32 v71, s[28:29], v84, v84, v117
	v_rcp_f32_e32 v82, v71
	s_nop 0
	v_fma_f32 v92, -v71, v82, 1.0
	v_fmac_f32_e32 v82, v92, v82
	v_div_scale_f32 v88, vcc, v117, v84, v117
	v_mul_f32_e32 v90, v88, v82
	v_fma_f32 v92, -v71, v90, v88
	v_fmac_f32_e32 v90, v92, v82
	v_fma_f32 v71, -v71, v90, v88
	v_div_fmas_f32 v71, v71, v82, v90
	v_div_fixup_f32 v117, v71, v84, v117
	v_mul_f32_e32 v70, v70, v117
	v_lshlrev_b32_e32 v115, 16, v115
	v_lshlrev_b32_e32 v116, 16, v116
	v_lshlrev_b32_e32 v114, 16, v114
	v_mul_f32_e32 v114, v16, v114
	v_fmac_f32_e32 v114, v14, v115
	v_fmac_f32_e32 v114, v17, v116
	v_add_f32_e32 v114, v12, v114
	v_fma_f32 v27, v41, v8, v67
	v_mul_f32_e32 v110, v27, v114
	v_lshlrev_b32_e32 v118, 16, v118
	v_mul_f32_e32 v84, 0xbfb8aa3b, v118
	v_exp_f32_e32 v84, v84
	s_nop 0
	v_add_f32_e32 v84, 1.0, v84
	v_div_scale_f32 v71, s[28:29], v84, v84, v118
	v_rcp_f32_e32 v82, v71
	s_nop 0
	v_fma_f32 v92, -v71, v82, 1.0
	v_fmac_f32_e32 v82, v92, v82
	v_div_scale_f32 v88, vcc, v118, v84, v118
	v_mul_f32_e32 v90, v88, v82
	v_fma_f32 v92, -v71, v90, v88
	v_fmac_f32_e32 v90, v92, v82
	v_fma_f32 v71, -v71, v90, v88
	v_div_fmas_f32 v71, v71, v82, v90
	v_div_fixup_f32 v118, v71, v84, v118
	v_mul_f32_e32 v110, v110, v118
	v_cvt_pk_bf16_f32 v202, v70, v110
	v_lshlrev_b32_e32 v120, 16, v120
	v_lshlrev_b32_e32 v121, 16, v121
	v_lshlrev_b32_e32 v119, 16, v119
	v_mul_f32_e32 v119, v16, v119
	v_fmac_f32_e32 v119, v14, v120
	v_fmac_f32_e32 v119, v17, v121
	v_add_f32_e32 v119, v12, v119
	v_fma_f32 v27, v38, v8, v68
	v_mul_f32_e32 v70, v27, v119
	v_lshlrev_b32_e32 v125, 16, v125
	v_mul_f32_e32 v84, 0xbfb8aa3b, v125
	v_exp_f32_e32 v84, v84
	s_nop 0
	v_add_f32_e32 v84, 1.0, v84
	v_div_scale_f32 v71, s[28:29], v84, v84, v125
	v_rcp_f32_e32 v82, v71
	s_nop 0
	v_fma_f32 v92, -v71, v82, 1.0
	v_fmac_f32_e32 v82, v92, v82
	v_div_scale_f32 v88, vcc, v125, v84, v125
	v_mul_f32_e32 v90, v88, v82
	v_fma_f32 v92, -v71, v90, v88
	v_fmac_f32_e32 v90, v92, v82
	v_fma_f32 v71, -v71, v90, v88
	v_div_fmas_f32 v71, v71, v82, v90
	v_div_fixup_f32 v125, v71, v84, v125
	v_mul_f32_e32 v70, v70, v125
	v_lshlrev_b32_e32 v123, 16, v123
	v_lshlrev_b32_e32 v124, 16, v124
	v_lshlrev_b32_e32 v122, 16, v122
	v_mul_f32_e32 v122, v16, v122
	v_fmac_f32_e32 v122, v14, v123
	v_fmac_f32_e32 v122, v17, v124
	v_add_f32_e32 v122, v12, v122
	v_fma_f32 v27, v40, v8, v69
	v_mul_f32_e32 v110, v27, v122
	v_lshlrev_b32_e32 v126, 16, v126
	v_mul_f32_e32 v84, 0xbfb8aa3b, v126
	v_exp_f32_e32 v84, v84
	s_nop 0
	v_add_f32_e32 v84, 1.0, v84
	v_div_scale_f32 v71, s[28:29], v84, v84, v126
	v_rcp_f32_e32 v82, v71
	s_nop 0
	v_fma_f32 v92, -v71, v82, 1.0
	v_fmac_f32_e32 v82, v92, v82
	v_div_scale_f32 v88, vcc, v126, v84, v126
	v_mul_f32_e32 v90, v88, v82
	v_fma_f32 v92, -v71, v90, v88
	v_fmac_f32_e32 v90, v92, v82
	v_fma_f32 v71, -v71, v90, v88
	v_div_fmas_f32 v71, v71, v82, v90
	v_div_fixup_f32 v126, v71, v84, v126
	v_mul_f32_e32 v110, v110, v126
	v_cvt_pk_bf16_f32 v203, v70, v110
	v_lshlrev_b32_e32 v128, 16, v128
	v_lshlrev_b32_e32 v129, 16, v129
	v_lshlrev_b32_e32 v127, 16, v127
	v_mul_f32_e32 v127, v16, v127
	v_fmac_f32_e32 v127, v14, v128
	v_fmac_f32_e32 v127, v17, v129
	v_add_f32_e32 v127, v12, v127
	v_fma_f32 v27, v43, v8, v62
	v_mul_f32_e32 v70, v27, v127
	v_lshlrev_b32_e32 v133, 16, v133
	v_mul_f32_e32 v84, 0xbfb8aa3b, v133
	v_exp_f32_e32 v84, v84
	s_nop 0
	v_add_f32_e32 v84, 1.0, v84
	v_div_scale_f32 v71, s[28:29], v84, v84, v133
	v_rcp_f32_e32 v82, v71
	s_nop 0
	v_fma_f32 v92, -v71, v82, 1.0
	v_fmac_f32_e32 v82, v92, v82
	v_div_scale_f32 v88, vcc, v133, v84, v133
	v_mul_f32_e32 v90, v88, v82
	v_fma_f32 v92, -v71, v90, v88
	v_fmac_f32_e32 v90, v92, v82
	v_fma_f32 v71, -v71, v90, v88
	v_div_fmas_f32 v71, v71, v82, v90
	v_div_fixup_f32 v133, v71, v84, v133
	v_mul_f32_e32 v70, v70, v133
	v_lshlrev_b32_e32 v131, 16, v131
	v_lshlrev_b32_e32 v132, 16, v132
	v_lshlrev_b32_e32 v130, 16, v130
	v_mul_f32_e32 v130, v16, v130
	v_fmac_f32_e32 v130, v14, v131
	v_fmac_f32_e32 v130, v17, v132
	v_add_f32_e32 v130, v12, v130
	v_fma_f32 v27, v45, v8, v63
	v_mul_f32_e32 v110, v27, v130
	v_lshlrev_b32_e32 v134, 16, v134
	v_mul_f32_e32 v84, 0xbfb8aa3b, v134
	v_exp_f32_e32 v84, v84
	s_nop 0
	v_add_f32_e32 v84, 1.0, v84
	v_div_scale_f32 v71, s[28:29], v84, v84, v134
	v_rcp_f32_e32 v82, v71
	s_nop 0
	v_fma_f32 v92, -v71, v82, 1.0
	v_fmac_f32_e32 v82, v92, v82
	v_div_scale_f32 v88, vcc, v134, v84, v134
	v_mul_f32_e32 v90, v88, v82
	v_fma_f32 v92, -v71, v90, v88
	v_fmac_f32_e32 v90, v92, v82
	v_fma_f32 v71, -v71, v90, v88
	v_div_fmas_f32 v71, v71, v82, v90
	v_div_fixup_f32 v134, v71, v84, v134
	v_mul_f32_e32 v110, v110, v134
	v_cvt_pk_bf16_f32 v204, v70, v110
	v_lshlrev_b32_e32 v136, 16, v136
	v_lshlrev_b32_e32 v137, 16, v137
	v_lshlrev_b32_e32 v135, 16, v135
	v_mul_f32_e32 v135, v16, v135
	v_fmac_f32_e32 v135, v14, v136
	v_fmac_f32_e32 v135, v17, v137
	v_add_f32_e32 v135, v12, v135
	v_fma_f32 v27, v42, v8, v64
	v_mul_f32_e32 v70, v27, v135
	v_lshlrev_b32_e32 v141, 16, v141
	v_mul_f32_e32 v84, 0xbfb8aa3b, v141
	v_exp_f32_e32 v84, v84
	s_nop 0
	v_add_f32_e32 v84, 1.0, v84
	v_div_scale_f32 v71, s[28:29], v84, v84, v141
	v_rcp_f32_e32 v82, v71
	s_nop 0
	v_fma_f32 v92, -v71, v82, 1.0
	v_fmac_f32_e32 v82, v92, v82
	v_div_scale_f32 v88, vcc, v141, v84, v141
	v_mul_f32_e32 v90, v88, v82
	v_fma_f32 v92, -v71, v90, v88
	v_fmac_f32_e32 v90, v92, v82
	v_fma_f32 v71, -v71, v90, v88
	v_div_fmas_f32 v71, v71, v82, v90
	v_div_fixup_f32 v141, v71, v84, v141
	v_mul_f32_e32 v70, v70, v141
	v_lshlrev_b32_e32 v139, 16, v139
	v_lshlrev_b32_e32 v140, 16, v140
	v_lshlrev_b32_e32 v138, 16, v138
	v_mul_f32_e32 v138, v16, v138
	v_fmac_f32_e32 v138, v14, v139
	v_fmac_f32_e32 v138, v17, v140
	v_add_f32_e32 v138, v12, v138
	v_fma_f32 v27, v44, v8, v65
	v_mul_f32_e32 v110, v27, v138
	v_lshlrev_b32_e32 v142, 16, v142
	v_mul_f32_e32 v84, 0xbfb8aa3b, v142
	v_exp_f32_e32 v84, v84
	s_nop 0
	v_add_f32_e32 v84, 1.0, v84
	v_div_scale_f32 v71, s[28:29], v84, v84, v142
	v_rcp_f32_e32 v82, v71
	s_nop 0
	v_fma_f32 v92, -v71, v82, 1.0
	v_fmac_f32_e32 v82, v92, v82
	v_div_scale_f32 v88, vcc, v142, v84, v142
	v_mul_f32_e32 v90, v88, v82
	v_fma_f32 v92, -v71, v90, v88
	v_fmac_f32_e32 v90, v92, v82
	v_fma_f32 v71, -v71, v90, v88
	v_div_fmas_f32 v71, v71, v82, v90
	v_div_fixup_f32 v142, v71, v84, v142
	v_mul_f32_e32 v110, v110, v142
	v_cvt_pk_bf16_f32 v205, v70, v110
	s_waitcnt vmcnt(32)
	v_lshlrev_b32_e32 v163, 16, v163
	v_lshlrev_b32_e32 v164, 16, v164
	v_lshlrev_b32_e32 v143, 16, v143
	v_mul_f32_e32 v143, v16, v143
	v_fmac_f32_e32 v143, v14, v163
	v_fmac_f32_e32 v143, v17, v164
	v_add_f32_e32 v143, v12, v143
	v_fma_f32 v27, v47, v8, v22
	v_mul_f32_e32 v70, v27, v143
	v_lshlrev_b32_e32 v168, 16, v168
	v_mul_f32_e32 v84, 0xbfb8aa3b, v168
	v_exp_f32_e32 v84, v84
	s_nop 0
	v_add_f32_e32 v84, 1.0, v84
	v_div_scale_f32 v71, s[28:29], v84, v84, v168
	v_rcp_f32_e32 v82, v71
	s_nop 0
	v_fma_f32 v92, -v71, v82, 1.0
	v_fmac_f32_e32 v82, v92, v82
	v_div_scale_f32 v88, vcc, v168, v84, v168
	v_mul_f32_e32 v90, v88, v82
	v_fma_f32 v92, -v71, v90, v88
	v_fmac_f32_e32 v90, v92, v82
	v_fma_f32 v71, -v71, v90, v88
	v_div_fmas_f32 v71, v71, v82, v90
	v_div_fixup_f32 v168, v71, v84, v168
	v_mul_f32_e32 v70, v70, v168
	v_lshlrev_b32_e32 v166, 16, v166
	v_lshlrev_b32_e32 v167, 16, v167
	v_lshlrev_b32_e32 v165, 16, v165
	v_mul_f32_e32 v165, v16, v165
	v_fmac_f32_e32 v165, v14, v166
	v_fmac_f32_e32 v165, v17, v167
	v_add_f32_e32 v165, v12, v165
	v_fma_f32 v27, v49, v8, v23
	v_mul_f32_e32 v110, v27, v165
	v_lshlrev_b32_e32 v169, 16, v169
	v_mul_f32_e32 v84, 0xbfb8aa3b, v169
	v_exp_f32_e32 v84, v84
	s_nop 0
	v_add_f32_e32 v84, 1.0, v84
	v_div_scale_f32 v71, s[28:29], v84, v84, v169
	v_rcp_f32_e32 v82, v71
	s_nop 0
	v_fma_f32 v92, -v71, v82, 1.0
	v_fmac_f32_e32 v82, v92, v82
	v_div_scale_f32 v88, vcc, v169, v84, v169
	v_mul_f32_e32 v90, v88, v82
	v_fma_f32 v92, -v71, v90, v88
	v_fmac_f32_e32 v90, v92, v82
	v_fma_f32 v71, -v71, v90, v88
	v_div_fmas_f32 v71, v71, v82, v90
	v_div_fixup_f32 v169, v71, v84, v169
	v_mul_f32_e32 v110, v110, v169
	v_cvt_pk_bf16_f32 v206, v70, v110
	v_lshlrev_b32_e32 v171, 16, v171
	v_lshlrev_b32_e32 v172, 16, v172
	v_lshlrev_b32_e32 v170, 16, v170
	v_mul_f32_e32 v170, v16, v170
	v_fmac_f32_e32 v170, v14, v171
	v_fmac_f32_e32 v170, v17, v172
	v_add_f32_e32 v170, v12, v170
	v_fma_f32 v27, v46, v8, v24
	v_mul_f32_e32 v70, v27, v170
	v_lshlrev_b32_e32 v176, 16, v176
	v_mul_f32_e32 v84, 0xbfb8aa3b, v176
	v_exp_f32_e32 v84, v84
	s_nop 0
	v_add_f32_e32 v84, 1.0, v84
	v_div_scale_f32 v71, s[28:29], v84, v84, v176
	v_rcp_f32_e32 v82, v71
	s_nop 0
	v_fma_f32 v92, -v71, v82, 1.0
	v_fmac_f32_e32 v82, v92, v82
	v_div_scale_f32 v88, vcc, v176, v84, v176
	v_mul_f32_e32 v90, v88, v82
	v_fma_f32 v92, -v71, v90, v88
	v_fmac_f32_e32 v90, v92, v82
	v_fma_f32 v71, -v71, v90, v88
	v_div_fmas_f32 v71, v71, v82, v90
	v_div_fixup_f32 v176, v71, v84, v176
	v_mul_f32_e32 v70, v70, v176
	v_lshlrev_b32_e32 v174, 16, v174
	v_lshlrev_b32_e32 v175, 16, v175
	v_lshlrev_b32_e32 v173, 16, v173
	v_mul_f32_e32 v173, v16, v173
	v_fmac_f32_e32 v173, v14, v174
	v_fmac_f32_e32 v173, v17, v175
	v_add_f32_e32 v173, v12, v173
	v_fma_f32 v27, v48, v8, v25
	v_mul_f32_e32 v110, v27, v173
	v_lshlrev_b32_e32 v177, 16, v177
	v_mul_f32_e32 v84, 0xbfb8aa3b, v177
	v_exp_f32_e32 v84, v84
	s_nop 0
	v_add_f32_e32 v84, 1.0, v84
	v_div_scale_f32 v71, s[28:29], v84, v84, v177
	v_rcp_f32_e32 v82, v71
	s_nop 0
	v_fma_f32 v92, -v71, v82, 1.0
	v_fmac_f32_e32 v82, v92, v82
	v_div_scale_f32 v88, vcc, v177, v84, v177
	v_mul_f32_e32 v90, v88, v82
	v_fma_f32 v92, -v71, v90, v88
	v_fmac_f32_e32 v90, v92, v82
	v_fma_f32 v71, -v71, v90, v88
	v_div_fmas_f32 v71, v71, v82, v90
	v_div_fixup_f32 v177, v71, v84, v177
	v_mul_f32_e32 v110, v110, v177
	v_cvt_pk_bf16_f32 v207, v70, v110
	v_lshlrev_b32_e32 v179, 16, v179
	v_lshlrev_b32_e32 v180, 16, v180
	v_lshlrev_b32_e32 v178, 16, v178
	v_mul_f32_e32 v178, v16, v178
	v_fmac_f32_e32 v178, v14, v179
	v_fmac_f32_e32 v178, v17, v180
	v_add_f32_e32 v178, v12, v178
	v_fma_f32 v27, v51, v8, v18
	v_mul_f32_e32 v70, v27, v178
	v_lshlrev_b32_e32 v184, 16, v184
	v_mul_f32_e32 v84, 0xbfb8aa3b, v184
	v_exp_f32_e32 v84, v84
	s_nop 0
	v_add_f32_e32 v84, 1.0, v84
	v_div_scale_f32 v71, s[28:29], v84, v84, v184
	v_rcp_f32_e32 v82, v71
	s_nop 0
	v_fma_f32 v92, -v71, v82, 1.0
	v_fmac_f32_e32 v82, v92, v82
	v_div_scale_f32 v88, vcc, v184, v84, v184
	v_mul_f32_e32 v90, v88, v82
	v_fma_f32 v92, -v71, v90, v88
	v_fmac_f32_e32 v90, v92, v82
	v_fma_f32 v71, -v71, v90, v88
	v_div_fmas_f32 v71, v71, v82, v90
	v_div_fixup_f32 v184, v71, v84, v184
	v_mul_f32_e32 v70, v70, v184
	v_lshlrev_b32_e32 v182, 16, v182
	v_lshlrev_b32_e32 v183, 16, v183
	v_lshlrev_b32_e32 v181, 16, v181
	v_mul_f32_e32 v181, v16, v181
	v_fmac_f32_e32 v181, v14, v182
	v_fmac_f32_e32 v181, v17, v183
	v_add_f32_e32 v181, v12, v181
	v_fma_f32 v27, v53, v8, v19
	v_mul_f32_e32 v110, v27, v181
	v_lshlrev_b32_e32 v185, 16, v185
	v_mul_f32_e32 v84, 0xbfb8aa3b, v185
	v_exp_f32_e32 v84, v84
	s_nop 0
	v_add_f32_e32 v84, 1.0, v84
	v_div_scale_f32 v71, s[28:29], v84, v84, v185
	v_rcp_f32_e32 v82, v71
	s_nop 0
	v_fma_f32 v92, -v71, v82, 1.0
	v_fmac_f32_e32 v82, v92, v82
	v_div_scale_f32 v88, vcc, v185, v84, v185
	v_mul_f32_e32 v90, v88, v82
	v_fma_f32 v92, -v71, v90, v88
	v_fmac_f32_e32 v90, v92, v82
	v_fma_f32 v71, -v71, v90, v88
	v_div_fmas_f32 v71, v71, v82, v90
	v_div_fixup_f32 v185, v71, v84, v185
	v_mul_f32_e32 v110, v110, v185
	v_cvt_pk_bf16_f32 v208, v70, v110
	v_lshlrev_b32_e32 v187, 16, v187
	v_lshlrev_b32_e32 v188, 16, v188
	v_lshlrev_b32_e32 v186, 16, v186
	v_mul_f32_e32 v186, v16, v186
	v_fmac_f32_e32 v186, v14, v187
	v_fmac_f32_e32 v186, v17, v188
	v_add_f32_e32 v186, v12, v186
	v_fma_f32 v27, v50, v8, v20
	v_mul_f32_e32 v70, v27, v186
	v_lshlrev_b32_e32 v192, 16, v192
	v_mul_f32_e32 v84, 0xbfb8aa3b, v192
	v_exp_f32_e32 v84, v84
	s_nop 0
	v_add_f32_e32 v84, 1.0, v84
	v_div_scale_f32 v71, s[28:29], v84, v84, v192
	v_rcp_f32_e32 v82, v71
	s_nop 0
	v_fma_f32 v92, -v71, v82, 1.0
	v_fmac_f32_e32 v82, v92, v82
	v_div_scale_f32 v88, vcc, v192, v84, v192
	v_mul_f32_e32 v90, v88, v82
	v_fma_f32 v92, -v71, v90, v88
	v_fmac_f32_e32 v90, v92, v82
	v_fma_f32 v71, -v71, v90, v88
	v_div_fmas_f32 v71, v71, v82, v90
	v_div_fixup_f32 v192, v71, v84, v192
	v_mul_f32_e32 v70, v70, v192
	v_lshlrev_b32_e32 v190, 16, v190
	v_lshlrev_b32_e32 v191, 16, v191
	v_lshlrev_b32_e32 v189, 16, v189
	v_mul_f32_e32 v189, v16, v189
	v_fmac_f32_e32 v189, v14, v190
	v_fmac_f32_e32 v189, v17, v191
	v_add_f32_e32 v189, v12, v189
	v_fma_f32 v27, v52, v8, v21
	v_mul_f32_e32 v110, v27, v189
	v_lshlrev_b32_e32 v193, 16, v193
	v_mul_f32_e32 v84, 0xbfb8aa3b, v193
	v_exp_f32_e32 v84, v84
	s_nop 0
	v_add_f32_e32 v84, 1.0, v84
	v_div_scale_f32 v71, s[28:29], v84, v84, v193
	v_rcp_f32_e32 v82, v71
	s_nop 0
	v_fma_f32 v92, -v71, v82, 1.0
	v_fmac_f32_e32 v82, v92, v82
	v_div_scale_f32 v88, vcc, v193, v84, v193
	v_mul_f32_e32 v90, v88, v82
	v_fma_f32 v92, -v71, v90, v88
	v_fmac_f32_e32 v90, v92, v82
	v_fma_f32 v71, -v71, v90, v88
	v_div_fmas_f32 v71, v71, v82, v90
	v_div_fixup_f32 v193, v71, v84, v193
	v_mul_f32_e32 v110, v110, v193
	v_cvt_pk_bf16_f32 v209, v70, v110
	s_waitcnt vmcnt(0)
	v_lshlrev_b32_e32 v195, 16, v195
	v_lshlrev_b32_e32 v196, 16, v196
	v_lshlrev_b32_e32 v194, 16, v194
	v_mul_f32_e32 v194, v16, v194
	v_fmac_f32_e32 v194, v14, v195
	v_fmac_f32_e32 v194, v17, v196
	v_add_f32_e32 v194, v12, v194
	v_fma_f32 v27, v55, v8, v4
	v_mul_f32_e32 v70, v27, v194
	v_lshlrev_b32_e32 v223, 16, v223
	v_mul_f32_e32 v84, 0xbfb8aa3b, v223
	v_exp_f32_e32 v84, v84
	s_nop 0
	v_add_f32_e32 v84, 1.0, v84
	v_div_scale_f32 v71, s[28:29], v84, v84, v223
	v_rcp_f32_e32 v82, v71
	s_nop 0
	v_fma_f32 v92, -v71, v82, 1.0
	v_fmac_f32_e32 v82, v92, v82
	v_div_scale_f32 v88, vcc, v223, v84, v223
	v_mul_f32_e32 v90, v88, v82
	v_fma_f32 v92, -v71, v90, v88
	v_fmac_f32_e32 v90, v92, v82
	v_fma_f32 v71, -v71, v90, v88
	v_div_fmas_f32 v71, v71, v82, v90
	v_div_fixup_f32 v223, v71, v84, v223
	v_mul_f32_e32 v70, v70, v223
	v_lshlrev_b32_e32 v221, 16, v221
	v_lshlrev_b32_e32 v222, 16, v222
	v_lshlrev_b32_e32 v197, 16, v197
	v_mul_f32_e32 v197, v16, v197
	v_fmac_f32_e32 v197, v14, v221
	v_fmac_f32_e32 v197, v17, v222
	v_add_f32_e32 v197, v12, v197
	v_fma_f32 v27, v57, v8, v5
	v_mul_f32_e32 v110, v27, v197
	v_lshlrev_b32_e32 v224, 16, v224
	v_mul_f32_e32 v84, 0xbfb8aa3b, v224
	v_exp_f32_e32 v84, v84
	s_nop 0
	v_add_f32_e32 v84, 1.0, v84
	v_div_scale_f32 v71, s[28:29], v84, v84, v224
	v_rcp_f32_e32 v82, v71
	s_nop 0
	v_fma_f32 v92, -v71, v82, 1.0
	v_fmac_f32_e32 v82, v92, v82
	v_div_scale_f32 v88, vcc, v224, v84, v224
	v_mul_f32_e32 v90, v88, v82
	v_fma_f32 v92, -v71, v90, v88
	v_fmac_f32_e32 v90, v92, v82
	v_fma_f32 v71, -v71, v90, v88
	v_div_fmas_f32 v71, v71, v82, v90
	v_div_fixup_f32 v224, v71, v84, v224
	v_mul_f32_e32 v110, v110, v224
	v_cvt_pk_bf16_f32 v210, v70, v110
	v_lshlrev_b32_e32 v226, 16, v226
	v_lshlrev_b32_e32 v227, 16, v227
	v_lshlrev_b32_e32 v225, 16, v225
	v_mul_f32_e32 v225, v16, v225
	v_fmac_f32_e32 v225, v14, v226
	v_fmac_f32_e32 v225, v17, v227
	v_add_f32_e32 v225, v12, v225
	v_fma_f32 v27, v54, v8, v6
	v_mul_f32_e32 v70, v27, v225
	v_lshlrev_b32_e32 v231, 16, v231
	v_mul_f32_e32 v84, 0xbfb8aa3b, v231
	v_exp_f32_e32 v84, v84
	s_nop 0
	v_add_f32_e32 v84, 1.0, v84
	v_div_scale_f32 v71, s[28:29], v84, v84, v231
	v_rcp_f32_e32 v82, v71
	s_nop 0
	v_fma_f32 v92, -v71, v82, 1.0
	v_fmac_f32_e32 v82, v92, v82
	v_div_scale_f32 v88, vcc, v231, v84, v231
	v_mul_f32_e32 v90, v88, v82
	v_fma_f32 v92, -v71, v90, v88
	v_fmac_f32_e32 v90, v92, v82
	v_fma_f32 v71, -v71, v90, v88
	v_div_fmas_f32 v71, v71, v82, v90
	v_div_fixup_f32 v231, v71, v84, v231
	v_mul_f32_e32 v70, v70, v231
	v_lshlrev_b32_e32 v229, 16, v229
	v_lshlrev_b32_e32 v230, 16, v230
	v_lshlrev_b32_e32 v228, 16, v228
	v_mul_f32_e32 v228, v16, v228
	v_fmac_f32_e32 v228, v14, v229
	v_fmac_f32_e32 v228, v17, v230
	v_add_f32_e32 v228, v12, v228
	v_fma_f32 v27, v56, v8, v7
	v_mul_f32_e32 v110, v27, v228
	v_lshlrev_b32_e32 v232, 16, v232
	v_mul_f32_e32 v84, 0xbfb8aa3b, v232
	v_exp_f32_e32 v84, v84
	s_nop 0
	v_add_f32_e32 v84, 1.0, v84
	v_div_scale_f32 v71, s[28:29], v84, v84, v232
	v_rcp_f32_e32 v82, v71
	s_nop 0
	v_fma_f32 v92, -v71, v82, 1.0
	v_fmac_f32_e32 v82, v92, v82
	v_div_scale_f32 v88, vcc, v232, v84, v232
	v_mul_f32_e32 v90, v88, v82
	v_fma_f32 v92, -v71, v90, v88
	v_fmac_f32_e32 v90, v92, v82
	v_fma_f32 v71, -v71, v90, v88
	v_div_fmas_f32 v71, v71, v82, v90
	v_div_fixup_f32 v232, v71, v84, v232
	v_mul_f32_e32 v110, v110, v232
	v_cvt_pk_bf16_f32 v211, v70, v110
	v_lshlrev_b32_e32 v234, 16, v234
	v_lshlrev_b32_e32 v235, 16, v235
	v_lshlrev_b32_e32 v233, 16, v233
	v_mul_f32_e32 v233, v16, v233
	v_fmac_f32_e32 v233, v14, v234
	v_fmac_f32_e32 v233, v17, v235
	v_add_f32_e32 v233, v12, v233
	v_fma_f32 v27, v59, v8, v0
	v_mul_f32_e32 v70, v27, v233
	v_lshlrev_b32_e32 v239, 16, v239
	v_mul_f32_e32 v84, 0xbfb8aa3b, v239
	v_exp_f32_e32 v84, v84
	s_nop 0
	v_add_f32_e32 v84, 1.0, v84
	v_div_scale_f32 v71, s[28:29], v84, v84, v239
	v_rcp_f32_e32 v82, v71
	s_nop 0
	v_fma_f32 v92, -v71, v82, 1.0
	v_fmac_f32_e32 v82, v92, v82
	v_div_scale_f32 v88, vcc, v239, v84, v239
	v_mul_f32_e32 v90, v88, v82
	v_fma_f32 v92, -v71, v90, v88
	v_fmac_f32_e32 v90, v92, v82
	v_fma_f32 v71, -v71, v90, v88
	v_div_fmas_f32 v71, v71, v82, v90
	v_div_fixup_f32 v239, v71, v84, v239
	v_mul_f32_e32 v70, v70, v239
	v_lshlrev_b32_e32 v237, 16, v237
	v_lshlrev_b32_e32 v238, 16, v238
	v_lshlrev_b32_e32 v236, 16, v236
	v_mul_f32_e32 v236, v16, v236
	v_fmac_f32_e32 v236, v14, v237
	v_fmac_f32_e32 v236, v17, v238
	v_add_f32_e32 v236, v12, v236
	v_fma_f32 v27, v61, v8, v1
	v_mul_f32_e32 v110, v27, v236
	v_lshlrev_b32_e32 v240, 16, v240
	v_mul_f32_e32 v84, 0xbfb8aa3b, v240
	v_exp_f32_e32 v84, v84
	s_nop 0
	v_add_f32_e32 v84, 1.0, v84
	v_div_scale_f32 v71, s[28:29], v84, v84, v240
	v_rcp_f32_e32 v82, v71
	s_nop 0
	v_fma_f32 v92, -v71, v82, 1.0
	v_fmac_f32_e32 v82, v92, v82
	v_div_scale_f32 v88, vcc, v240, v84, v240
	v_mul_f32_e32 v90, v88, v82
	v_fma_f32 v92, -v71, v90, v88
	v_fmac_f32_e32 v90, v92, v82
	v_fma_f32 v71, -v71, v90, v88
	v_div_fmas_f32 v71, v71, v82, v90
	v_div_fixup_f32 v240, v71, v84, v240
	v_mul_f32_e32 v110, v110, v240
	v_cvt_pk_bf16_f32 v212, v70, v110
	v_lshlrev_b32_e32 v242, 16, v242
	v_lshlrev_b32_e32 v243, 16, v243
	v_lshlrev_b32_e32 v241, 16, v241
	v_mul_f32_e32 v241, v16, v241
	v_mul_f32_e32 v243, v255, v243
	v_fmac_f32_e32 v241, v14, v242
	v_fmac_f32_e32 v241, v17, v243
	v_add_f32_e32 v241, v12, v241
	v_fma_f32 v27, v58, v8, v2
	v_mul_f32_e32 v70, v27, v241
	v_lshlrev_b32_e32 v247, 16, v247
	v_mul_f32_e32 v84, 0xbfb8aa3b, v247
	v_exp_f32_e32 v84, v84
	s_nop 0
	v_add_f32_e32 v84, 1.0, v84
	v_div_scale_f32 v71, s[28:29], v84, v84, v247
	v_rcp_f32_e32 v82, v71
	s_nop 0
	v_fma_f32 v92, -v71, v82, 1.0
	v_fmac_f32_e32 v82, v92, v82
	v_div_scale_f32 v88, vcc, v247, v84, v247
	v_mul_f32_e32 v90, v88, v82
	v_fma_f32 v92, -v71, v90, v88
	v_fmac_f32_e32 v90, v92, v82
	v_fma_f32 v71, -v71, v90, v88
	v_div_fmas_f32 v71, v71, v82, v90
	v_div_fixup_f32 v247, v71, v84, v247
	v_mul_f32_e32 v70, v70, v247
	v_lshlrev_b32_e32 v245, 16, v245
	v_lshlrev_b32_e32 v246, 16, v246
	v_lshlrev_b32_e32 v244, 16, v244
	v_mul_f32_e32 v244, v16, v244
	v_mul_f32_e32 v246, v255, v246
	v_fmac_f32_e32 v244, v14, v245
	v_fmac_f32_e32 v244, v17, v246
	v_add_f32_e32 v244, v12, v244
	v_fma_f32 v27, v60, v8, v3
	v_mul_f32_e32 v110, v27, v244
	v_lshlrev_b32_e32 v248, 16, v248
	v_mul_f32_e32 v84, 0xbfb8aa3b, v248
	v_exp_f32_e32 v84, v84
	s_nop 0
	v_add_f32_e32 v84, 1.0, v84
	v_div_scale_f32 v71, s[28:29], v84, v84, v248
	v_rcp_f32_e32 v82, v71
	s_nop 0
	v_fma_f32 v92, -v71, v82, 1.0
	v_fmac_f32_e32 v82, v92, v82
	v_div_scale_f32 v88, vcc, v248, v84, v248
	v_mul_f32_e32 v90, v88, v82
	v_fma_f32 v92, -v71, v90, v88
	v_fmac_f32_e32 v90, v92, v82
	v_fma_f32 v71, -v71, v90, v88
	v_div_fmas_f32 v71, v71, v82, v90
	v_div_fixup_f32 v248, v71, v84, v248
	v_mul_f32_e32 v110, v110, v248
	v_cvt_pk_bf16_f32 v213, v70, v110
	s_branch .Lhy_ep1_done_L0
.Lhy_ep1_comb_L0:
	s_mov_b32 s98, 0x5040100
	s_mov_b32 s99, 0x7060302
	v_lshlrev_b32_e32 v109, 1, v10
	v_add_u32_e32 v254, 0x1e00, v10
	v_add_u32_e32 v253, 0x1000, v109
	v_cmp_gt_i32_e32 vcc, 0x1fff, v254
	v_add_u32_e32 v251, 0x2000, v109
	v_add_u32_e32 v250, 0x3000, v109
	v_min_i32_e32 v254, 0x1ffe, v254
	v_cndmask_b32_e64 v255, 0, 1.0, vcc
	v_lshlrev_b32_e32 v254, 1, v254
	global_load_ushort v9, v109, s[0:1]
	global_load_ushort v11, v109, s[4:5]
	global_load_ushort v13, v109, s[36:37] offset:1022
	global_load_ushort v15, v109, s[36:37] offset:1024
	global_load_ushort v81, v109, s[36:37] offset:1026
	global_load_ushort v83, v109, s[88:89] offset:1022
	global_load_ushort v85, v109, s[88:89] offset:1024
	global_load_ushort v87, v109, s[88:89] offset:1026
	global_load_ushort v89, v109, s[0:1] offset:1024
	global_load_ushort v91, v109, s[4:5] offset:1024
	global_load_ushort v93, v109, s[36:37] offset:2046
	global_load_ushort v94, v109, s[36:37] offset:2048
	global_load_ushort v95, v109, s[36:37] offset:2050
	global_load_ushort v96, v109, s[88:89] offset:2046
	global_load_ushort v97, v109, s[88:89] offset:2048
	global_load_ushort v98, v109, s[88:89] offset:2050
	global_load_ushort v99, v109, s[0:1] offset:2048
	global_load_ushort v100, v109, s[4:5] offset:2048
	global_load_ushort v101, v109, s[36:37] offset:3070
	global_load_ushort v102, v109, s[36:37] offset:3072
	global_load_ushort v103, v109, s[36:37] offset:3074
	global_load_ushort v104, v109, s[88:89] offset:3070
	global_load_ushort v105, v109, s[88:89] offset:3072
	global_load_ushort v106, v109, s[88:89] offset:3074
	global_load_ushort v107, v109, s[0:1] offset:3072
	global_load_ushort v108, v109, s[4:5] offset:3072
	global_load_ushort v111, v253, s[36:37] offset:-2
	global_load_ushort v112, v253, s[36:37]
	global_load_ushort v113, v253, s[36:37] offset:2
	global_load_ushort v114, v253, s[88:89] offset:-2
	global_load_ushort v115, v253, s[88:89]
	global_load_ushort v116, v253, s[88:89] offset:2
	global_load_ushort v117, v253, s[0:1]
	global_load_ushort v118, v253, s[4:5]
	global_load_ushort v119, v253, s[36:37] offset:1022
	global_load_ushort v120, v253, s[36:37] offset:1024
	global_load_ushort v121, v253, s[36:37] offset:1026
	global_load_ushort v122, v253, s[88:89] offset:1022
	global_load_ushort v123, v253, s[88:89] offset:1024
	global_load_ushort v124, v253, s[88:89] offset:1026
	global_load_ushort v125, v253, s[0:1] offset:1024
	global_load_ushort v126, v253, s[4:5] offset:1024
	global_load_ushort v127, v253, s[36:37] offset:2046
	global_load_ushort v128, v253, s[36:37] offset:2048
	global_load_ushort v129, v253, s[36:37] offset:2050
	global_load_ushort v130, v253, s[88:89] offset:2046
	global_load_ushort v131, v253, s[88:89] offset:2048
	global_load_ushort v132, v253, s[88:89] offset:2050
	global_load_ushort v133, v253, s[0:1] offset:2048
	global_load_ushort v134, v253, s[4:5] offset:2048
	global_load_ushort v135, v253, s[36:37] offset:3070
	global_load_ushort v136, v253, s[36:37] offset:3072
	global_load_ushort v137, v253, s[36:37] offset:3074
	global_load_ushort v138, v253, s[88:89] offset:3070
	global_load_ushort v139, v253, s[88:89] offset:3072
	global_load_ushort v140, v253, s[88:89] offset:3074
	global_load_ushort v141, v253, s[0:1] offset:3072
	global_load_ushort v142, v253, s[4:5] offset:3072
	global_load_ushort v143, v251, s[36:37] offset:-2
	global_load_ushort v163, v251, s[36:37]
	global_load_ushort v164, v251, s[36:37] offset:2
	global_load_ushort v165, v251, s[88:89] offset:-2
	global_load_ushort v166, v251, s[88:89]
	global_load_ushort v167, v251, s[88:89] offset:2
	global_load_ushort v168, v251, s[0:1]
	global_load_ushort v169, v251, s[4:5]
	global_load_ushort v170, v251, s[36:37] offset:1022
	global_load_ushort v171, v251, s[36:37] offset:1024
	global_load_ushort v172, v251, s[36:37] offset:1026
	global_load_ushort v173, v251, s[88:89] offset:1022
	global_load_ushort v174, v251, s[88:89] offset:1024
	global_load_ushort v175, v251, s[88:89] offset:1026
	global_load_ushort v176, v251, s[0:1] offset:1024
	global_load_ushort v177, v251, s[4:5] offset:1024
	global_load_ushort v178, v251, s[36:37] offset:2046
	global_load_ushort v179, v251, s[36:37] offset:2048
	global_load_ushort v180, v251, s[36:37] offset:2050
	global_load_ushort v181, v251, s[88:89] offset:2046
	global_load_ushort v182, v251, s[88:89] offset:2048
	global_load_ushort v183, v251, s[88:89] offset:2050
	global_load_ushort v184, v251, s[0:1] offset:2048
	global_load_ushort v185, v251, s[4:5] offset:2048
	global_load_ushort v186, v251, s[36:37] offset:3070
	global_load_ushort v187, v251, s[36:37] offset:3072
	global_load_ushort v188, v251, s[36:37] offset:3074
	global_load_ushort v189, v251, s[88:89] offset:3070
	global_load_ushort v190, v251, s[88:89] offset:3072
	global_load_ushort v191, v251, s[88:89] offset:3074
	global_load_ushort v192, v251, s[0:1] offset:3072
	global_load_ushort v193, v251, s[4:5] offset:3072
	global_load_ushort v194, v250, s[36:37] offset:-2
	global_load_ushort v195, v250, s[36:37]
	global_load_ushort v196, v250, s[36:37] offset:2
	global_load_ushort v197, v250, s[88:89] offset:-2
	global_load_ushort v221, v250, s[88:89]
	global_load_ushort v222, v250, s[88:89] offset:2
	global_load_ushort v223, v250, s[0:1]
	global_load_ushort v224, v250, s[4:5]
	global_load_ushort v225, v250, s[36:37] offset:1022
	global_load_ushort v226, v250, s[36:37] offset:1024
	global_load_ushort v227, v250, s[36:37] offset:1026
	global_load_ushort v228, v250, s[88:89] offset:1022
	global_load_ushort v229, v250, s[88:89] offset:1024
	global_load_ushort v230, v250, s[88:89] offset:1026
	global_load_ushort v231, v250, s[0:1] offset:1024
	global_load_ushort v232, v250, s[4:5] offset:1024
	global_load_ushort v233, v250, s[36:37] offset:2046
	global_load_ushort v234, v250, s[36:37] offset:2048
	global_load_ushort v235, v250, s[36:37] offset:2050
	global_load_ushort v236, v250, s[88:89] offset:2046
	global_load_ushort v237, v250, s[88:89] offset:2048
	global_load_ushort v238, v250, s[88:89] offset:2050
	global_load_ushort v239, v250, s[0:1] offset:2048
	global_load_ushort v240, v250, s[4:5] offset:2048
	global_load_ushort v241, v250, s[36:37] offset:3070
	global_load_ushort v242, v250, s[36:37] offset:3072
	global_load_ushort v243, v254, s[36:37] offset:2
	global_load_ushort v244, v250, s[88:89] offset:3070
	global_load_ushort v245, v250, s[88:89] offset:3072
	global_load_ushort v246, v254, s[88:89] offset:2
	global_load_ushort v247, v250, s[0:1] offset:3072
	global_load_ushort v248, v250, s[4:5] offset:3072
	s_waitcnt vmcnt(63)
	v_lshlrev_b32_e32 v26, 10, v10
	v_fma_f32 v27, v32, v8, v78
	v_mul_f32_e32 v70, v80, v27
	v_lshlrev_b32_e32 v9, 16, v9
	v_mul_f32_e32 v84, 0xbfb8aa3b, v9
	v_exp_f32_e32 v84, v84
	s_nop 0
	v_add_f32_e32 v84, 1.0, v84
	v_div_scale_f32 v71, s[28:29], v84, v84, v9
	v_rcp_f32_e32 v82, v71
	s_nop 0
	v_fma_f32 v92, -v71, v82, 1.0
	v_fmac_f32_e32 v82, v92, v82
	v_div_scale_f32 v88, vcc, v9, v84, v9
	v_mul_f32_e32 v90, v88, v82
	v_fma_f32 v92, -v71, v90, v88
	v_fmac_f32_e32 v90, v92, v82
	v_fma_f32 v71, -v71, v90, v88
	v_div_fmas_f32 v71, v71, v82, v90
	v_div_fixup_f32 v9, v71, v84, v9
	v_mul_f32_e32 v70, v70, v9
	v_fma_f32 v27, v34, v8, v79
	v_mul_f32_e32 v110, v86, v27
	v_lshlrev_b32_e32 v11, 16, v11
	v_mul_f32_e32 v84, 0xbfb8aa3b, v11
	v_exp_f32_e32 v84, v84
	s_nop 0
	v_add_f32_e32 v84, 1.0, v84
	v_div_scale_f32 v71, s[28:29], v84, v84, v11
	v_rcp_f32_e32 v82, v71
	s_nop 0
	v_fma_f32 v92, -v71, v82, 1.0
	v_fmac_f32_e32 v82, v92, v82
	v_div_scale_f32 v88, vcc, v11, v84, v11
	v_mul_f32_e32 v90, v88, v82
	v_fma_f32 v92, -v71, v90, v88
	v_fmac_f32_e32 v90, v92, v82
	v_fma_f32 v71, -v71, v90, v88
	v_div_fmas_f32 v71, v71, v82, v90
	v_div_fixup_f32 v11, v71, v84, v11
	v_mul_f32_e32 v110, v110, v11
	v_cvt_pk_bf16_f32 v70, v70, v110
	v_perm_b32 v110, v70, v198, s98
	v_perm_b32 v70, v70, v198, s99
	global_store_dword v26, v110, s[96:97] offset:-2
	global_store_dword v26, v70, s[18:19] offset:-2
	v_add_u32_e32 v26, 0x80000, v26
	v_lshlrev_b32_e32 v15, 16, v15
	v_lshlrev_b32_e32 v81, 16, v81
	v_lshlrev_b32_e32 v13, 16, v13
	v_mul_f32_e32 v13, v16, v13
	v_fmac_f32_e32 v13, v14, v15
	v_fmac_f32_e32 v13, v17, v81
	v_add_f32_e32 v13, v12, v13
	v_fma_f32 v27, v33, v8, v76
	v_mul_f32_e32 v70, v27, v13
	v_lshlrev_b32_e32 v89, 16, v89
	v_mul_f32_e32 v84, 0xbfb8aa3b, v89
	v_exp_f32_e32 v84, v84
	s_nop 0
	v_add_f32_e32 v84, 1.0, v84
	v_div_scale_f32 v71, s[28:29], v84, v84, v89
	v_rcp_f32_e32 v82, v71
	s_nop 0
	v_fma_f32 v92, -v71, v82, 1.0
	v_fmac_f32_e32 v82, v92, v82
	v_div_scale_f32 v88, vcc, v89, v84, v89
	v_mul_f32_e32 v90, v88, v82
	v_fma_f32 v92, -v71, v90, v88
	v_fmac_f32_e32 v90, v92, v82
	v_fma_f32 v71, -v71, v90, v88
	v_div_fmas_f32 v71, v71, v82, v90
	v_div_fixup_f32 v89, v71, v84, v89
	v_mul_f32_e32 v70, v70, v89
	v_lshlrev_b32_e32 v85, 16, v85
	v_lshlrev_b32_e32 v87, 16, v87
	v_lshlrev_b32_e32 v83, 16, v83
	v_mul_f32_e32 v83, v16, v83
	v_fmac_f32_e32 v83, v14, v85
	v_fmac_f32_e32 v83, v17, v87
	v_add_f32_e32 v83, v12, v83
	v_fma_f32 v27, v35, v8, v77
	v_mul_f32_e32 v110, v27, v83
	v_lshlrev_b32_e32 v91, 16, v91
	v_mul_f32_e32 v84, 0xbfb8aa3b, v91
	v_exp_f32_e32 v84, v84
	s_nop 0
	v_add_f32_e32 v84, 1.0, v84
	v_div_scale_f32 v71, s[28:29], v84, v84, v91
	v_rcp_f32_e32 v82, v71
	s_nop 0
	v_fma_f32 v92, -v71, v82, 1.0
	v_fmac_f32_e32 v82, v92, v82
	v_div_scale_f32 v88, vcc, v91, v84, v91
	v_mul_f32_e32 v90, v88, v82
	v_fma_f32 v92, -v71, v90, v88
	v_fmac_f32_e32 v90, v92, v82
	v_fma_f32 v71, -v71, v90, v88
	v_div_fmas_f32 v71, v71, v82, v90
	v_div_fixup_f32 v91, v71, v84, v91
	v_mul_f32_e32 v110, v110, v91
	v_cvt_pk_bf16_f32 v70, v70, v110
	v_perm_b32 v110, v70, v199, s98
	v_perm_b32 v70, v70, v199, s99
	global_store_dword v26, v110, s[96:97] offset:-2
	global_store_dword v26, v70, s[18:19] offset:-2
	v_add_u32_e32 v26, 0x80000, v26
	v_lshlrev_b32_e32 v94, 16, v94
	v_lshlrev_b32_e32 v95, 16, v95
	v_lshlrev_b32_e32 v93, 16, v93
	v_mul_f32_e32 v93, v16, v93
	v_fmac_f32_e32 v93, v14, v94
	v_fmac_f32_e32 v93, v17, v95
	v_add_f32_e32 v93, v12, v93
	v_fma_f32 v27, v37, v8, v72
	v_mul_f32_e32 v70, v27, v93
	v_lshlrev_b32_e32 v99, 16, v99
	v_mul_f32_e32 v84, 0xbfb8aa3b, v99
	v_exp_f32_e32 v84, v84
	s_nop 0
	v_add_f32_e32 v84, 1.0, v84
	v_div_scale_f32 v71, s[28:29], v84, v84, v99
	v_rcp_f32_e32 v82, v71
	s_nop 0
	v_fma_f32 v92, -v71, v82, 1.0
	v_fmac_f32_e32 v82, v92, v82
	v_div_scale_f32 v88, vcc, v99, v84, v99
	v_mul_f32_e32 v90, v88, v82
	v_fma_f32 v92, -v71, v90, v88
	v_fmac_f32_e32 v90, v92, v82
	v_fma_f32 v71, -v71, v90, v88
	v_div_fmas_f32 v71, v71, v82, v90
	v_div_fixup_f32 v99, v71, v84, v99
	v_mul_f32_e32 v70, v70, v99
	v_lshlrev_b32_e32 v97, 16, v97
	v_lshlrev_b32_e32 v98, 16, v98
	v_lshlrev_b32_e32 v96, 16, v96
	v_mul_f32_e32 v96, v16, v96
	v_fmac_f32_e32 v96, v14, v97
	v_fmac_f32_e32 v96, v17, v98
	v_add_f32_e32 v96, v12, v96
	v_fma_f32 v27, v31, v8, v73
	v_mul_f32_e32 v110, v27, v96
	v_lshlrev_b32_e32 v100, 16, v100
	v_mul_f32_e32 v84, 0xbfb8aa3b, v100
	v_exp_f32_e32 v84, v84
	s_nop 0
	v_add_f32_e32 v84, 1.0, v84
	v_div_scale_f32 v71, s[28:29], v84, v84, v100
	v_rcp_f32_e32 v82, v71
	s_nop 0
	v_fma_f32 v92, -v71, v82, 1.0
	v_fmac_f32_e32 v82, v92, v82
	v_div_scale_f32 v88, vcc, v100, v84, v100
	v_mul_f32_e32 v90, v88, v82
	v_fma_f32 v92, -v71, v90, v88
	v_fmac_f32_e32 v90, v92, v82
	v_fma_f32 v71, -v71, v90, v88
	v_div_fmas_f32 v71, v71, v82, v90
	v_div_fixup_f32 v100, v71, v84, v100
	v_mul_f32_e32 v110, v110, v100
	v_cvt_pk_bf16_f32 v70, v70, v110
	v_perm_b32 v110, v70, v200, s98
	v_perm_b32 v70, v70, v200, s99
	global_store_dword v26, v110, s[96:97] offset:-2
	global_store_dword v26, v70, s[18:19] offset:-2
	v_add_u32_e32 v26, 0x80000, v26
	v_lshlrev_b32_e32 v102, 16, v102
	v_lshlrev_b32_e32 v103, 16, v103
	v_lshlrev_b32_e32 v101, 16, v101
	v_mul_f32_e32 v101, v16, v101
	v_fmac_f32_e32 v101, v14, v102
	v_fmac_f32_e32 v101, v17, v103
	v_add_f32_e32 v101, v12, v101
	v_fma_f32 v27, v36, v8, v74
	v_mul_f32_e32 v70, v27, v101
	v_lshlrev_b32_e32 v107, 16, v107
	v_mul_f32_e32 v84, 0xbfb8aa3b, v107
	v_exp_f32_e32 v84, v84
	s_nop 0
	v_add_f32_e32 v84, 1.0, v84
	v_div_scale_f32 v71, s[28:29], v84, v84, v107
	v_rcp_f32_e32 v82, v71
	s_nop 0
	v_fma_f32 v92, -v71, v82, 1.0
	v_fmac_f32_e32 v82, v92, v82
	v_div_scale_f32 v88, vcc, v107, v84, v107
	v_mul_f32_e32 v90, v88, v82
	v_fma_f32 v92, -v71, v90, v88
	v_fmac_f32_e32 v90, v92, v82
	v_fma_f32 v71, -v71, v90, v88
	v_div_fmas_f32 v71, v71, v82, v90
	v_div_fixup_f32 v107, v71, v84, v107
	v_mul_f32_e32 v70, v70, v107
	v_lshlrev_b32_e32 v105, 16, v105
	v_lshlrev_b32_e32 v106, 16, v106
	v_lshlrev_b32_e32 v104, 16, v104
	v_mul_f32_e32 v104, v16, v104
	v_fmac_f32_e32 v104, v14, v105
	v_fmac_f32_e32 v104, v17, v106
	v_add_f32_e32 v104, v12, v104
	v_fma_f32 v27, v30, v8, v75
	v_mul_f32_e32 v110, v27, v104
	v_lshlrev_b32_e32 v108, 16, v108
	v_mul_f32_e32 v84, 0xbfb8aa3b, v108
	v_exp_f32_e32 v84, v84
	s_nop 0
	v_add_f32_e32 v84, 1.0, v84
	v_div_scale_f32 v71, s[28:29], v84, v84, v108
	v_rcp_f32_e32 v82, v71
	s_nop 0
	v_fma_f32 v92, -v71, v82, 1.0
	v_fmac_f32_e32 v82, v92, v82
	v_div_scale_f32 v88, vcc, v108, v84, v108
	v_mul_f32_e32 v90, v88, v82
	v_fma_f32 v92, -v71, v90, v88
	v_fmac_f32_e32 v90, v92, v82
	v_fma_f32 v71, -v71, v90, v88
	v_div_fmas_f32 v71, v71, v82, v90
	v_div_fixup_f32 v108, v71, v84, v108
	v_mul_f32_e32 v110, v110, v108
	v_cvt_pk_bf16_f32 v70, v70, v110
	v_perm_b32 v110, v70, v201, s98
	v_perm_b32 v70, v70, v201, s99
	global_store_dword v26, v110, s[96:97] offset:-2
	global_store_dword v26, v70, s[18:19] offset:-2
	s_waitcnt vmcnt(63)
	v_add_u32_e32 v26, 0x80000, v26
	v_lshlrev_b32_e32 v112, 16, v112
	v_lshlrev_b32_e32 v113, 16, v113
	v_lshlrev_b32_e32 v111, 16, v111
	v_mul_f32_e32 v111, v16, v111
	v_fmac_f32_e32 v111, v14, v112
	v_fmac_f32_e32 v111, v17, v113
	v_add_f32_e32 v111, v12, v111
	v_fma_f32 v27, v39, v8, v66
	v_mul_f32_e32 v70, v27, v111
	v_lshlrev_b32_e32 v117, 16, v117
	v_mul_f32_e32 v84, 0xbfb8aa3b, v117
	v_exp_f32_e32 v84, v84
	s_nop 0
	v_add_f32_e32 v84, 1.0, v84
	v_div_scale_f32 v71, s[28:29], v84, v84, v117
	v_rcp_f32_e32 v82, v71
	s_nop 0
	v_fma_f32 v92, -v71, v82, 1.0
	v_fmac_f32_e32 v82, v92, v82
	v_div_scale_f32 v88, vcc, v117, v84, v117
	v_mul_f32_e32 v90, v88, v82
	v_fma_f32 v92, -v71, v90, v88
	v_fmac_f32_e32 v90, v92, v82
	v_fma_f32 v71, -v71, v90, v88
	v_div_fmas_f32 v71, v71, v82, v90
	v_div_fixup_f32 v117, v71, v84, v117
	v_mul_f32_e32 v70, v70, v117
	v_lshlrev_b32_e32 v115, 16, v115
	v_lshlrev_b32_e32 v116, 16, v116
	v_lshlrev_b32_e32 v114, 16, v114
	v_mul_f32_e32 v114, v16, v114
	v_fmac_f32_e32 v114, v14, v115
	v_fmac_f32_e32 v114, v17, v116
	v_add_f32_e32 v114, v12, v114
	v_fma_f32 v27, v41, v8, v67
	v_mul_f32_e32 v110, v27, v114
	v_lshlrev_b32_e32 v118, 16, v118
	v_mul_f32_e32 v84, 0xbfb8aa3b, v118
	v_exp_f32_e32 v84, v84
	s_nop 0
	v_add_f32_e32 v84, 1.0, v84
	v_div_scale_f32 v71, s[28:29], v84, v84, v118
	v_rcp_f32_e32 v82, v71
	s_nop 0
	v_fma_f32 v92, -v71, v82, 1.0
	v_fmac_f32_e32 v82, v92, v82
	v_div_scale_f32 v88, vcc, v118, v84, v118
	v_mul_f32_e32 v90, v88, v82
	v_fma_f32 v92, -v71, v90, v88
	v_fmac_f32_e32 v90, v92, v82
	v_fma_f32 v71, -v71, v90, v88
	v_div_fmas_f32 v71, v71, v82, v90
	v_div_fixup_f32 v118, v71, v84, v118
	v_mul_f32_e32 v110, v110, v118
	v_cvt_pk_bf16_f32 v70, v70, v110
	v_perm_b32 v110, v70, v202, s98
	v_perm_b32 v70, v70, v202, s99
	global_store_dword v26, v110, s[96:97] offset:-2
	global_store_dword v26, v70, s[18:19] offset:-2
	v_add_u32_e32 v26, 0x80000, v26
	v_lshlrev_b32_e32 v120, 16, v120
	v_lshlrev_b32_e32 v121, 16, v121
	v_lshlrev_b32_e32 v119, 16, v119
	v_mul_f32_e32 v119, v16, v119
	v_fmac_f32_e32 v119, v14, v120
	v_fmac_f32_e32 v119, v17, v121
	v_add_f32_e32 v119, v12, v119
	v_fma_f32 v27, v38, v8, v68
	v_mul_f32_e32 v70, v27, v119
	v_lshlrev_b32_e32 v125, 16, v125
	v_mul_f32_e32 v84, 0xbfb8aa3b, v125
	v_exp_f32_e32 v84, v84
	s_nop 0
	v_add_f32_e32 v84, 1.0, v84
	v_div_scale_f32 v71, s[28:29], v84, v84, v125
	v_rcp_f32_e32 v82, v71
	s_nop 0
	v_fma_f32 v92, -v71, v82, 1.0
	v_fmac_f32_e32 v82, v92, v82
	v_div_scale_f32 v88, vcc, v125, v84, v125
	v_mul_f32_e32 v90, v88, v82
	v_fma_f32 v92, -v71, v90, v88
	v_fmac_f32_e32 v90, v92, v82
	v_fma_f32 v71, -v71, v90, v88
	v_div_fmas_f32 v71, v71, v82, v90
	v_div_fixup_f32 v125, v71, v84, v125
	v_mul_f32_e32 v70, v70, v125
	v_lshlrev_b32_e32 v123, 16, v123
	v_lshlrev_b32_e32 v124, 16, v124
	v_lshlrev_b32_e32 v122, 16, v122
	v_mul_f32_e32 v122, v16, v122
	v_fmac_f32_e32 v122, v14, v123
	v_fmac_f32_e32 v122, v17, v124
	v_add_f32_e32 v122, v12, v122
	v_fma_f32 v27, v40, v8, v69
	v_mul_f32_e32 v110, v27, v122
	v_lshlrev_b32_e32 v126, 16, v126
	v_mul_f32_e32 v84, 0xbfb8aa3b, v126
	v_exp_f32_e32 v84, v84
	s_nop 0
	v_add_f32_e32 v84, 1.0, v84
	v_div_scale_f32 v71, s[28:29], v84, v84, v126
	v_rcp_f32_e32 v82, v71
	s_nop 0
	v_fma_f32 v92, -v71, v82, 1.0
	v_fmac_f32_e32 v82, v92, v82
	v_div_scale_f32 v88, vcc, v126, v84, v126
	v_mul_f32_e32 v90, v88, v82
	v_fma_f32 v92, -v71, v90, v88
	v_fmac_f32_e32 v90, v92, v82
	v_fma_f32 v71, -v71, v90, v88
	v_div_fmas_f32 v71, v71, v82, v90
	v_div_fixup_f32 v126, v71, v84, v126
	v_mul_f32_e32 v110, v110, v126
	v_cvt_pk_bf16_f32 v70, v70, v110
	v_perm_b32 v110, v70, v203, s98
	v_perm_b32 v70, v70, v203, s99
	global_store_dword v26, v110, s[96:97] offset:-2
	global_store_dword v26, v70, s[18:19] offset:-2
	v_add_u32_e32 v26, 0x80000, v26
	v_lshlrev_b32_e32 v128, 16, v128
	v_lshlrev_b32_e32 v129, 16, v129
	v_lshlrev_b32_e32 v127, 16, v127
	v_mul_f32_e32 v127, v16, v127
	v_fmac_f32_e32 v127, v14, v128
	v_fmac_f32_e32 v127, v17, v129
	v_add_f32_e32 v127, v12, v127
	v_fma_f32 v27, v43, v8, v62
	v_mul_f32_e32 v70, v27, v127
	v_lshlrev_b32_e32 v133, 16, v133
	v_mul_f32_e32 v84, 0xbfb8aa3b, v133
	v_exp_f32_e32 v84, v84
	s_nop 0
	v_add_f32_e32 v84, 1.0, v84
	v_div_scale_f32 v71, s[28:29], v84, v84, v133
	v_rcp_f32_e32 v82, v71
	s_nop 0
	v_fma_f32 v92, -v71, v82, 1.0
	v_fmac_f32_e32 v82, v92, v82
	v_div_scale_f32 v88, vcc, v133, v84, v133
	v_mul_f32_e32 v90, v88, v82
	v_fma_f32 v92, -v71, v90, v88
	v_fmac_f32_e32 v90, v92, v82
	v_fma_f32 v71, -v71, v90, v88
	v_div_fmas_f32 v71, v71, v82, v90
	v_div_fixup_f32 v133, v71, v84, v133
	v_mul_f32_e32 v70, v70, v133
	v_lshlrev_b32_e32 v131, 16, v131
	v_lshlrev_b32_e32 v132, 16, v132
	v_lshlrev_b32_e32 v130, 16, v130
	v_mul_f32_e32 v130, v16, v130
	v_fmac_f32_e32 v130, v14, v131
	v_fmac_f32_e32 v130, v17, v132
	v_add_f32_e32 v130, v12, v130
	v_fma_f32 v27, v45, v8, v63
	v_mul_f32_e32 v110, v27, v130
	v_lshlrev_b32_e32 v134, 16, v134
	v_mul_f32_e32 v84, 0xbfb8aa3b, v134
	v_exp_f32_e32 v84, v84
	s_nop 0
	v_add_f32_e32 v84, 1.0, v84
	v_div_scale_f32 v71, s[28:29], v84, v84, v134
	v_rcp_f32_e32 v82, v71
	s_nop 0
	v_fma_f32 v92, -v71, v82, 1.0
	v_fmac_f32_e32 v82, v92, v82
	v_div_scale_f32 v88, vcc, v134, v84, v134
	v_mul_f32_e32 v90, v88, v82
	v_fma_f32 v92, -v71, v90, v88
	v_fmac_f32_e32 v90, v92, v82
	v_fma_f32 v71, -v71, v90, v88
	v_div_fmas_f32 v71, v71, v82, v90
	v_div_fixup_f32 v134, v71, v84, v134
	v_mul_f32_e32 v110, v110, v134
	v_cvt_pk_bf16_f32 v70, v70, v110
	v_perm_b32 v110, v70, v204, s98
	v_perm_b32 v70, v70, v204, s99
	global_store_dword v26, v110, s[96:97] offset:-2
	global_store_dword v26, v70, s[18:19] offset:-2
	v_add_u32_e32 v26, 0x80000, v26
	v_lshlrev_b32_e32 v136, 16, v136
	v_lshlrev_b32_e32 v137, 16, v137
	v_lshlrev_b32_e32 v135, 16, v135
	v_mul_f32_e32 v135, v16, v135
	v_fmac_f32_e32 v135, v14, v136
	v_fmac_f32_e32 v135, v17, v137
	v_add_f32_e32 v135, v12, v135
	v_fma_f32 v27, v42, v8, v64
	v_mul_f32_e32 v70, v27, v135
	v_lshlrev_b32_e32 v141, 16, v141
	v_mul_f32_e32 v84, 0xbfb8aa3b, v141
	v_exp_f32_e32 v84, v84
	s_nop 0
	v_add_f32_e32 v84, 1.0, v84
	v_div_scale_f32 v71, s[28:29], v84, v84, v141
	v_rcp_f32_e32 v82, v71
	s_nop 0
	v_fma_f32 v92, -v71, v82, 1.0
	v_fmac_f32_e32 v82, v92, v82
	v_div_scale_f32 v88, vcc, v141, v84, v141
	v_mul_f32_e32 v90, v88, v82
	v_fma_f32 v92, -v71, v90, v88
	v_fmac_f32_e32 v90, v92, v82
	v_fma_f32 v71, -v71, v90, v88
	v_div_fmas_f32 v71, v71, v82, v90
	v_div_fixup_f32 v141, v71, v84, v141
	v_mul_f32_e32 v70, v70, v141
	v_lshlrev_b32_e32 v139, 16, v139
	v_lshlrev_b32_e32 v140, 16, v140
	v_lshlrev_b32_e32 v138, 16, v138
	v_mul_f32_e32 v138, v16, v138
	v_fmac_f32_e32 v138, v14, v139
	v_fmac_f32_e32 v138, v17, v140
	v_add_f32_e32 v138, v12, v138
	v_fma_f32 v27, v44, v8, v65
	v_mul_f32_e32 v110, v27, v138
	v_lshlrev_b32_e32 v142, 16, v142
	v_mul_f32_e32 v84, 0xbfb8aa3b, v142
	v_exp_f32_e32 v84, v84
	s_nop 0
	v_add_f32_e32 v84, 1.0, v84
	v_div_scale_f32 v71, s[28:29], v84, v84, v142
	v_rcp_f32_e32 v82, v71
	s_nop 0
	v_fma_f32 v92, -v71, v82, 1.0
	v_fmac_f32_e32 v82, v92, v82
	v_div_scale_f32 v88, vcc, v142, v84, v142
	v_mul_f32_e32 v90, v88, v82
	v_fma_f32 v92, -v71, v90, v88
	v_fmac_f32_e32 v90, v92, v82
	v_fma_f32 v71, -v71, v90, v88
	v_div_fmas_f32 v71, v71, v82, v90
	v_div_fixup_f32 v142, v71, v84, v142
	v_mul_f32_e32 v110, v110, v142
	v_cvt_pk_bf16_f32 v70, v70, v110
	v_perm_b32 v110, v70, v205, s98
	v_perm_b32 v70, v70, v205, s99
	global_store_dword v26, v110, s[96:97] offset:-2
	global_store_dword v26, v70, s[18:19] offset:-2
	s_waitcnt vmcnt(48)
	v_add_u32_e32 v26, 0x80000, v26
	v_lshlrev_b32_e32 v163, 16, v163
	v_lshlrev_b32_e32 v164, 16, v164
	v_lshlrev_b32_e32 v143, 16, v143
	v_mul_f32_e32 v143, v16, v143
	v_fmac_f32_e32 v143, v14, v163
	v_fmac_f32_e32 v143, v17, v164
	v_add_f32_e32 v143, v12, v143
	v_fma_f32 v27, v47, v8, v22
	v_mul_f32_e32 v70, v27, v143
	v_lshlrev_b32_e32 v168, 16, v168
	v_mul_f32_e32 v84, 0xbfb8aa3b, v168
	v_exp_f32_e32 v84, v84
	s_nop 0
	v_add_f32_e32 v84, 1.0, v84
	v_div_scale_f32 v71, s[28:29], v84, v84, v168
	v_rcp_f32_e32 v82, v71
	s_nop 0
	v_fma_f32 v92, -v71, v82, 1.0
	v_fmac_f32_e32 v82, v92, v82
	v_div_scale_f32 v88, vcc, v168, v84, v168
	v_mul_f32_e32 v90, v88, v82
	v_fma_f32 v92, -v71, v90, v88
	v_fmac_f32_e32 v90, v92, v82
	v_fma_f32 v71, -v71, v90, v88
	v_div_fmas_f32 v71, v71, v82, v90
	v_div_fixup_f32 v168, v71, v84, v168
	v_mul_f32_e32 v70, v70, v168
	v_lshlrev_b32_e32 v166, 16, v166
	v_lshlrev_b32_e32 v167, 16, v167
	v_lshlrev_b32_e32 v165, 16, v165
	v_mul_f32_e32 v165, v16, v165
	v_fmac_f32_e32 v165, v14, v166
	v_fmac_f32_e32 v165, v17, v167
	v_add_f32_e32 v165, v12, v165
	v_fma_f32 v27, v49, v8, v23
	v_mul_f32_e32 v110, v27, v165
	v_lshlrev_b32_e32 v169, 16, v169
	v_mul_f32_e32 v84, 0xbfb8aa3b, v169
	v_exp_f32_e32 v84, v84
	s_nop 0
	v_add_f32_e32 v84, 1.0, v84
	v_div_scale_f32 v71, s[28:29], v84, v84, v169
	v_rcp_f32_e32 v82, v71
	s_nop 0
	v_fma_f32 v92, -v71, v82, 1.0
	v_fmac_f32_e32 v82, v92, v82
	v_div_scale_f32 v88, vcc, v169, v84, v169
	v_mul_f32_e32 v90, v88, v82
	v_fma_f32 v92, -v71, v90, v88
	v_fmac_f32_e32 v90, v92, v82
	v_fma_f32 v71, -v71, v90, v88
	v_div_fmas_f32 v71, v71, v82, v90
	v_div_fixup_f32 v169, v71, v84, v169
	v_mul_f32_e32 v110, v110, v169
	v_cvt_pk_bf16_f32 v70, v70, v110
	v_perm_b32 v110, v70, v206, s98
	v_perm_b32 v70, v70, v206, s99
	global_store_dword v26, v110, s[96:97] offset:-2
	global_store_dword v26, v70, s[18:19] offset:-2
	v_add_u32_e32 v26, 0x80000, v26
	v_lshlrev_b32_e32 v171, 16, v171
	v_lshlrev_b32_e32 v172, 16, v172
	v_lshlrev_b32_e32 v170, 16, v170
	v_mul_f32_e32 v170, v16, v170
	v_fmac_f32_e32 v170, v14, v171
	v_fmac_f32_e32 v170, v17, v172
	v_add_f32_e32 v170, v12, v170
	v_fma_f32 v27, v46, v8, v24
	v_mul_f32_e32 v70, v27, v170
	v_lshlrev_b32_e32 v176, 16, v176
	v_mul_f32_e32 v84, 0xbfb8aa3b, v176
	v_exp_f32_e32 v84, v84
	s_nop 0
	v_add_f32_e32 v84, 1.0, v84
	v_div_scale_f32 v71, s[28:29], v84, v84, v176
	v_rcp_f32_e32 v82, v71
	s_nop 0
	v_fma_f32 v92, -v71, v82, 1.0
	v_fmac_f32_e32 v82, v92, v82
	v_div_scale_f32 v88, vcc, v176, v84, v176
	v_mul_f32_e32 v90, v88, v82
	v_fma_f32 v92, -v71, v90, v88
	v_fmac_f32_e32 v90, v92, v82
	v_fma_f32 v71, -v71, v90, v88
	v_div_fmas_f32 v71, v71, v82, v90
	v_div_fixup_f32 v176, v71, v84, v176
	v_mul_f32_e32 v70, v70, v176
	v_lshlrev_b32_e32 v174, 16, v174
	v_lshlrev_b32_e32 v175, 16, v175
	v_lshlrev_b32_e32 v173, 16, v173
	v_mul_f32_e32 v173, v16, v173
	v_fmac_f32_e32 v173, v14, v174
	v_fmac_f32_e32 v173, v17, v175
	v_add_f32_e32 v173, v12, v173
	v_fma_f32 v27, v48, v8, v25
	v_mul_f32_e32 v110, v27, v173
	v_lshlrev_b32_e32 v177, 16, v177
	v_mul_f32_e32 v84, 0xbfb8aa3b, v177
	v_exp_f32_e32 v84, v84
	s_nop 0
	v_add_f32_e32 v84, 1.0, v84
	v_div_scale_f32 v71, s[28:29], v84, v84, v177
	v_rcp_f32_e32 v82, v71
	s_nop 0
	v_fma_f32 v92, -v71, v82, 1.0
	v_fmac_f32_e32 v82, v92, v82
	v_div_scale_f32 v88, vcc, v177, v84, v177
	v_mul_f32_e32 v90, v88, v82
	v_fma_f32 v92, -v71, v90, v88
	v_fmac_f32_e32 v90, v92, v82
	v_fma_f32 v71, -v71, v90, v88
	v_div_fmas_f32 v71, v71, v82, v90
	v_div_fixup_f32 v177, v71, v84, v177
	v_mul_f32_e32 v110, v110, v177
	v_cvt_pk_bf16_f32 v70, v70, v110
	v_perm_b32 v110, v70, v207, s98
	v_perm_b32 v70, v70, v207, s99
	global_store_dword v26, v110, s[96:97] offset:-2
	global_store_dword v26, v70, s[18:19] offset:-2
	v_add_u32_e32 v26, 0x80000, v26
	v_lshlrev_b32_e32 v179, 16, v179
	v_lshlrev_b32_e32 v180, 16, v180
	v_lshlrev_b32_e32 v178, 16, v178
	v_mul_f32_e32 v178, v16, v178
	v_fmac_f32_e32 v178, v14, v179
	v_fmac_f32_e32 v178, v17, v180
	v_add_f32_e32 v178, v12, v178
	v_fma_f32 v27, v51, v8, v18
	v_mul_f32_e32 v70, v27, v178
	v_lshlrev_b32_e32 v184, 16, v184
	v_mul_f32_e32 v84, 0xbfb8aa3b, v184
	v_exp_f32_e32 v84, v84
	s_nop 0
	v_add_f32_e32 v84, 1.0, v84
	v_div_scale_f32 v71, s[28:29], v84, v84, v184
	v_rcp_f32_e32 v82, v71
	s_nop 0
	v_fma_f32 v92, -v71, v82, 1.0
	v_fmac_f32_e32 v82, v92, v82
	v_div_scale_f32 v88, vcc, v184, v84, v184
	v_mul_f32_e32 v90, v88, v82
	v_fma_f32 v92, -v71, v90, v88
	v_fmac_f32_e32 v90, v92, v82
	v_fma_f32 v71, -v71, v90, v88
	v_div_fmas_f32 v71, v71, v82, v90
	v_div_fixup_f32 v184, v71, v84, v184
	v_mul_f32_e32 v70, v70, v184
	v_lshlrev_b32_e32 v182, 16, v182
	v_lshlrev_b32_e32 v183, 16, v183
	v_lshlrev_b32_e32 v181, 16, v181
	v_mul_f32_e32 v181, v16, v181
	v_fmac_f32_e32 v181, v14, v182
	v_fmac_f32_e32 v181, v17, v183
	v_add_f32_e32 v181, v12, v181
	v_fma_f32 v27, v53, v8, v19
	v_mul_f32_e32 v110, v27, v181
	v_lshlrev_b32_e32 v185, 16, v185
	v_mul_f32_e32 v84, 0xbfb8aa3b, v185
	v_exp_f32_e32 v84, v84
	s_nop 0
	v_add_f32_e32 v84, 1.0, v84
	v_div_scale_f32 v71, s[28:29], v84, v84, v185
	v_rcp_f32_e32 v82, v71
	s_nop 0
	v_fma_f32 v92, -v71, v82, 1.0
	v_fmac_f32_e32 v82, v92, v82
	v_div_scale_f32 v88, vcc, v185, v84, v185
	v_mul_f32_e32 v90, v88, v82
	v_fma_f32 v92, -v71, v90, v88
	v_fmac_f32_e32 v90, v92, v82
	v_fma_f32 v71, -v71, v90, v88
	v_div_fmas_f32 v71, v71, v82, v90
	v_div_fixup_f32 v185, v71, v84, v185
	v_mul_f32_e32 v110, v110, v185
	v_cvt_pk_bf16_f32 v70, v70, v110
	v_perm_b32 v110, v70, v208, s98
	v_perm_b32 v70, v70, v208, s99
	global_store_dword v26, v110, s[96:97] offset:-2
	global_store_dword v26, v70, s[18:19] offset:-2
	v_add_u32_e32 v26, 0x80000, v26
	v_lshlrev_b32_e32 v187, 16, v187
	v_lshlrev_b32_e32 v188, 16, v188
	v_lshlrev_b32_e32 v186, 16, v186
	v_mul_f32_e32 v186, v16, v186
	v_fmac_f32_e32 v186, v14, v187
	v_fmac_f32_e32 v186, v17, v188
	v_add_f32_e32 v186, v12, v186
	v_fma_f32 v27, v50, v8, v20
	v_mul_f32_e32 v70, v27, v186
	v_lshlrev_b32_e32 v192, 16, v192
	v_mul_f32_e32 v84, 0xbfb8aa3b, v192
	v_exp_f32_e32 v84, v84
	s_nop 0
	v_add_f32_e32 v84, 1.0, v84
	v_div_scale_f32 v71, s[28:29], v84, v84, v192
	v_rcp_f32_e32 v82, v71
	s_nop 0
	v_fma_f32 v92, -v71, v82, 1.0
	v_fmac_f32_e32 v82, v92, v82
	v_div_scale_f32 v88, vcc, v192, v84, v192
	v_mul_f32_e32 v90, v88, v82
	v_fma_f32 v92, -v71, v90, v88
	v_fmac_f32_e32 v90, v92, v82
	v_fma_f32 v71, -v71, v90, v88
	v_div_fmas_f32 v71, v71, v82, v90
	v_div_fixup_f32 v192, v71, v84, v192
	v_mul_f32_e32 v70, v70, v192
	v_lshlrev_b32_e32 v190, 16, v190
	v_lshlrev_b32_e32 v191, 16, v191
	v_lshlrev_b32_e32 v189, 16, v189
	v_mul_f32_e32 v189, v16, v189
	v_fmac_f32_e32 v189, v14, v190
	v_fmac_f32_e32 v189, v17, v191
	v_add_f32_e32 v189, v12, v189
	v_fma_f32 v27, v52, v8, v21
	v_mul_f32_e32 v110, v27, v189
	v_lshlrev_b32_e32 v193, 16, v193
	v_mul_f32_e32 v84, 0xbfb8aa3b, v193
	v_exp_f32_e32 v84, v84
	s_nop 0
	v_add_f32_e32 v84, 1.0, v84
	v_div_scale_f32 v71, s[28:29], v84, v84, v193
	v_rcp_f32_e32 v82, v71
	s_nop 0
	v_fma_f32 v92, -v71, v82, 1.0
	v_fmac_f32_e32 v82, v92, v82
	v_div_scale_f32 v88, vcc, v193, v84, v193
	v_mul_f32_e32 v90, v88, v82
	v_fma_f32 v92, -v71, v90, v88
	v_fmac_f32_e32 v90, v92, v82
	v_fma_f32 v71, -v71, v90, v88
	v_div_fmas_f32 v71, v71, v82, v90
	v_div_fixup_f32 v193, v71, v84, v193
	v_mul_f32_e32 v110, v110, v193
	v_cvt_pk_bf16_f32 v70, v70, v110
	v_perm_b32 v110, v70, v209, s98
	v_perm_b32 v70, v70, v209, s99
	global_store_dword v26, v110, s[96:97] offset:-2
	global_store_dword v26, v70, s[18:19] offset:-2
	s_waitcnt vmcnt(24)
	v_add_u32_e32 v26, 0x80000, v26
	v_lshlrev_b32_e32 v195, 16, v195
	v_lshlrev_b32_e32 v196, 16, v196
	v_lshlrev_b32_e32 v194, 16, v194
	v_mul_f32_e32 v194, v16, v194
	v_fmac_f32_e32 v194, v14, v195
	v_fmac_f32_e32 v194, v17, v196
	v_add_f32_e32 v194, v12, v194
	v_fma_f32 v27, v55, v8, v4
	v_mul_f32_e32 v70, v27, v194
	v_lshlrev_b32_e32 v223, 16, v223
	v_mul_f32_e32 v84, 0xbfb8aa3b, v223
	v_exp_f32_e32 v84, v84
	s_nop 0
	v_add_f32_e32 v84, 1.0, v84
	v_div_scale_f32 v71, s[28:29], v84, v84, v223
	v_rcp_f32_e32 v82, v71
	s_nop 0
	v_fma_f32 v92, -v71, v82, 1.0
	v_fmac_f32_e32 v82, v92, v82
	v_div_scale_f32 v88, vcc, v223, v84, v223
	v_mul_f32_e32 v90, v88, v82
	v_fma_f32 v92, -v71, v90, v88
	v_fmac_f32_e32 v90, v92, v82
	v_fma_f32 v71, -v71, v90, v88
	v_div_fmas_f32 v71, v71, v82, v90
	v_div_fixup_f32 v223, v71, v84, v223
	v_mul_f32_e32 v70, v70, v223
	v_lshlrev_b32_e32 v221, 16, v221
	v_lshlrev_b32_e32 v222, 16, v222
	v_lshlrev_b32_e32 v197, 16, v197
	v_mul_f32_e32 v197, v16, v197
	v_fmac_f32_e32 v197, v14, v221
	v_fmac_f32_e32 v197, v17, v222
	v_add_f32_e32 v197, v12, v197
	v_fma_f32 v27, v57, v8, v5
	v_mul_f32_e32 v110, v27, v197
	v_lshlrev_b32_e32 v224, 16, v224
	v_mul_f32_e32 v84, 0xbfb8aa3b, v224
	v_exp_f32_e32 v84, v84
	s_nop 0
	v_add_f32_e32 v84, 1.0, v84
	v_div_scale_f32 v71, s[28:29], v84, v84, v224
	v_rcp_f32_e32 v82, v71
	s_nop 0
	v_fma_f32 v92, -v71, v82, 1.0
	v_fmac_f32_e32 v82, v92, v82
	v_div_scale_f32 v88, vcc, v224, v84, v224
	v_mul_f32_e32 v90, v88, v82
	v_fma_f32 v92, -v71, v90, v88
	v_fmac_f32_e32 v90, v92, v82
	v_fma_f32 v71, -v71, v90, v88
	v_div_fmas_f32 v71, v71, v82, v90
	v_div_fixup_f32 v224, v71, v84, v224
	v_mul_f32_e32 v110, v110, v224
	v_cvt_pk_bf16_f32 v70, v70, v110
	v_perm_b32 v110, v70, v210, s98
	v_perm_b32 v70, v70, v210, s99
	global_store_dword v26, v110, s[96:97] offset:-2
	global_store_dword v26, v70, s[18:19] offset:-2
	v_add_u32_e32 v26, 0x80000, v26
	v_lshlrev_b32_e32 v226, 16, v226
	v_lshlrev_b32_e32 v227, 16, v227
	v_lshlrev_b32_e32 v225, 16, v225
	v_mul_f32_e32 v225, v16, v225
	v_fmac_f32_e32 v225, v14, v226
	v_fmac_f32_e32 v225, v17, v227
	v_add_f32_e32 v225, v12, v225
	v_fma_f32 v27, v54, v8, v6
	v_mul_f32_e32 v70, v27, v225
	v_lshlrev_b32_e32 v231, 16, v231
	v_mul_f32_e32 v84, 0xbfb8aa3b, v231
	v_exp_f32_e32 v84, v84
	s_nop 0
	v_add_f32_e32 v84, 1.0, v84
	v_div_scale_f32 v71, s[28:29], v84, v84, v231
	v_rcp_f32_e32 v82, v71
	s_nop 0
	v_fma_f32 v92, -v71, v82, 1.0
	v_fmac_f32_e32 v82, v92, v82
	v_div_scale_f32 v88, vcc, v231, v84, v231
	v_mul_f32_e32 v90, v88, v82
	v_fma_f32 v92, -v71, v90, v88
	v_fmac_f32_e32 v90, v92, v82
	v_fma_f32 v71, -v71, v90, v88
	v_div_fmas_f32 v71, v71, v82, v90
	v_div_fixup_f32 v231, v71, v84, v231
	v_mul_f32_e32 v70, v70, v231
	v_lshlrev_b32_e32 v229, 16, v229
	v_lshlrev_b32_e32 v230, 16, v230
	v_lshlrev_b32_e32 v228, 16, v228
	v_mul_f32_e32 v228, v16, v228
	v_fmac_f32_e32 v228, v14, v229
	v_fmac_f32_e32 v228, v17, v230
	v_add_f32_e32 v228, v12, v228
	v_fma_f32 v27, v56, v8, v7
	v_mul_f32_e32 v110, v27, v228
	v_lshlrev_b32_e32 v232, 16, v232
	v_mul_f32_e32 v84, 0xbfb8aa3b, v232
	v_exp_f32_e32 v84, v84
	s_nop 0
	v_add_f32_e32 v84, 1.0, v84
	v_div_scale_f32 v71, s[28:29], v84, v84, v232
	v_rcp_f32_e32 v82, v71
	s_nop 0
	v_fma_f32 v92, -v71, v82, 1.0
	v_fmac_f32_e32 v82, v92, v82
	v_div_scale_f32 v88, vcc, v232, v84, v232
	v_mul_f32_e32 v90, v88, v82
	v_fma_f32 v92, -v71, v90, v88
	v_fmac_f32_e32 v90, v92, v82
	v_fma_f32 v71, -v71, v90, v88
	v_div_fmas_f32 v71, v71, v82, v90
	v_div_fixup_f32 v232, v71, v84, v232
	v_mul_f32_e32 v110, v110, v232
	v_cvt_pk_bf16_f32 v70, v70, v110
	v_perm_b32 v110, v70, v211, s98
	v_perm_b32 v70, v70, v211, s99
	global_store_dword v26, v110, s[96:97] offset:-2
	global_store_dword v26, v70, s[18:19] offset:-2
	v_add_u32_e32 v26, 0x80000, v26
	v_lshlrev_b32_e32 v234, 16, v234
	v_lshlrev_b32_e32 v235, 16, v235
	v_lshlrev_b32_e32 v233, 16, v233
	v_mul_f32_e32 v233, v16, v233
	v_fmac_f32_e32 v233, v14, v234
	v_fmac_f32_e32 v233, v17, v235
	v_add_f32_e32 v233, v12, v233
	v_fma_f32 v27, v59, v8, v0
	v_mul_f32_e32 v70, v27, v233
	v_lshlrev_b32_e32 v239, 16, v239
	v_mul_f32_e32 v84, 0xbfb8aa3b, v239
	v_exp_f32_e32 v84, v84
	s_nop 0
	v_add_f32_e32 v84, 1.0, v84
	v_div_scale_f32 v71, s[28:29], v84, v84, v239
	v_rcp_f32_e32 v82, v71
	s_nop 0
	v_fma_f32 v92, -v71, v82, 1.0
	v_fmac_f32_e32 v82, v92, v82
	v_div_scale_f32 v88, vcc, v239, v84, v239
	v_mul_f32_e32 v90, v88, v82
	v_fma_f32 v92, -v71, v90, v88
	v_fmac_f32_e32 v90, v92, v82
	v_fma_f32 v71, -v71, v90, v88
	v_div_fmas_f32 v71, v71, v82, v90
	v_div_fixup_f32 v239, v71, v84, v239
	v_mul_f32_e32 v70, v70, v239
	v_lshlrev_b32_e32 v237, 16, v237
	v_lshlrev_b32_e32 v238, 16, v238
	v_lshlrev_b32_e32 v236, 16, v236
	v_mul_f32_e32 v236, v16, v236
	v_fmac_f32_e32 v236, v14, v237
	v_fmac_f32_e32 v236, v17, v238
	v_add_f32_e32 v236, v12, v236
	v_fma_f32 v27, v61, v8, v1
	v_mul_f32_e32 v110, v27, v236
	v_lshlrev_b32_e32 v240, 16, v240
	v_mul_f32_e32 v84, 0xbfb8aa3b, v240
	v_exp_f32_e32 v84, v84
	s_nop 0
	v_add_f32_e32 v84, 1.0, v84
	v_div_scale_f32 v71, s[28:29], v84, v84, v240
	v_rcp_f32_e32 v82, v71
	s_nop 0
	v_fma_f32 v92, -v71, v82, 1.0
	v_fmac_f32_e32 v82, v92, v82
	v_div_scale_f32 v88, vcc, v240, v84, v240
	v_mul_f32_e32 v90, v88, v82
	v_fma_f32 v92, -v71, v90, v88
	v_fmac_f32_e32 v90, v92, v82
	v_fma_f32 v71, -v71, v90, v88
	v_div_fmas_f32 v71, v71, v82, v90
	v_div_fixup_f32 v240, v71, v84, v240
	v_mul_f32_e32 v110, v110, v240
	v_cvt_pk_bf16_f32 v70, v70, v110
	v_perm_b32 v110, v70, v212, s98
	v_perm_b32 v70, v70, v212, s99
	global_store_dword v26, v110, s[96:97] offset:-2
	global_store_dword v26, v70, s[18:19] offset:-2
	v_add_u32_e32 v26, 0x80000, v26
	v_lshlrev_b32_e32 v242, 16, v242
	v_lshlrev_b32_e32 v243, 16, v243
	v_lshlrev_b32_e32 v241, 16, v241
	v_mul_f32_e32 v241, v16, v241
	v_mul_f32_e32 v243, v255, v243
	v_fmac_f32_e32 v241, v14, v242
	v_fmac_f32_e32 v241, v17, v243
	v_add_f32_e32 v241, v12, v241
	v_fma_f32 v27, v58, v8, v2
	v_mul_f32_e32 v70, v27, v241
	v_lshlrev_b32_e32 v247, 16, v247
	v_mul_f32_e32 v84, 0xbfb8aa3b, v247
	v_exp_f32_e32 v84, v84
	s_nop 0
	v_add_f32_e32 v84, 1.0, v84
	v_div_scale_f32 v71, s[28:29], v84, v84, v247
	v_rcp_f32_e32 v82, v71
	s_nop 0
	v_fma_f32 v92, -v71, v82, 1.0
	v_fmac_f32_e32 v82, v92, v82
	v_div_scale_f32 v88, vcc, v247, v84, v247
	v_mul_f32_e32 v90, v88, v82
	v_fma_f32 v92, -v71, v90, v88
	v_fmac_f32_e32 v90, v92, v82
	v_fma_f32 v71, -v71, v90, v88
	v_div_fmas_f32 v71, v71, v82, v90
	v_div_fixup_f32 v247, v71, v84, v247
	v_mul_f32_e32 v70, v70, v247
	v_lshlrev_b32_e32 v245, 16, v245
	v_lshlrev_b32_e32 v246, 16, v246
	v_lshlrev_b32_e32 v244, 16, v244
	v_mul_f32_e32 v244, v16, v244
	v_mul_f32_e32 v246, v255, v246
	v_fmac_f32_e32 v244, v14, v245
	v_fmac_f32_e32 v244, v17, v246
	v_add_f32_e32 v244, v12, v244
	v_fma_f32 v27, v60, v8, v3
	v_mul_f32_e32 v110, v27, v244
	v_lshlrev_b32_e32 v248, 16, v248
	v_mul_f32_e32 v84, 0xbfb8aa3b, v248
	v_exp_f32_e32 v84, v84
	s_nop 0
	v_add_f32_e32 v84, 1.0, v84
	v_div_scale_f32 v71, s[28:29], v84, v84, v248
	v_rcp_f32_e32 v82, v71
	s_nop 0
	v_fma_f32 v92, -v71, v82, 1.0
	v_fmac_f32_e32 v82, v92, v82
	v_div_scale_f32 v88, vcc, v248, v84, v248
	v_mul_f32_e32 v90, v88, v82
	v_fma_f32 v92, -v71, v90, v88
	v_fmac_f32_e32 v90, v92, v82
	v_fma_f32 v71, -v71, v90, v88
	v_div_fmas_f32 v71, v71, v82, v90
	v_div_fixup_f32 v248, v71, v84, v248
	v_mul_f32_e32 v110, v110, v248
	v_cvt_pk_bf16_f32 v70, v70, v110
	v_perm_b32 v110, v70, v213, s98
	v_perm_b32 v70, v70, v213, s99
	global_store_dword v26, v110, s[96:97] offset:-2
	global_store_dword v26, v70, s[18:19] offset:-2

.LBB0_540:
	s_andn2_b64 vcc, exec, s[28:29]
	s_cbranch_vccnz .LBB0_537
	v_lshlrev_b32_e32 v109, 1, v10
	v_add_u32_e32 v254, 0x1e00, v10
	v_add_u32_e32 v253, 0x1000, v109
	v_cmp_gt_i32_e32 vcc, 0x1fff, v254
	v_add_u32_e32 v251, 0x2000, v109
	v_add_u32_e32 v250, 0x3000, v109
	v_min_i32_e32 v254, 0x1ffe, v254
	v_cndmask_b32_e64 v255, 0, 1.0, vcc
	v_lshlrev_b32_e32 v254, 1, v254
	global_load_ushort v9, v109, s[36:37] offset:1022
	global_load_ushort v11, v109, s[36:37] offset:1024
	global_load_ushort v13, v109, s[36:37] offset:1026
	global_load_ushort v15, v109, s[88:89] offset:1022
	global_load_ushort v81, v109, s[88:89] offset:1024
	global_load_ushort v83, v109, s[88:89] offset:1026
	global_load_ushort v85, v109, s[36:37] offset:2046
	global_load_ushort v87, v109, s[36:37] offset:2048
	global_load_ushort v89, v109, s[36:37] offset:2050
	global_load_ushort v91, v109, s[88:89] offset:2046
	global_load_ushort v93, v109, s[88:89] offset:2048
	global_load_ushort v94, v109, s[88:89] offset:2050
	global_load_ushort v95, v109, s[36:37] offset:3070
	global_load_ushort v96, v109, s[36:37] offset:3072
	global_load_ushort v97, v109, s[36:37] offset:3074
	global_load_ushort v98, v109, s[88:89] offset:3070
	global_load_ushort v99, v109, s[88:89] offset:3072
	global_load_ushort v100, v109, s[88:89] offset:3074
	global_load_ushort v101, v253, s[36:37] offset:-2
	global_load_ushort v102, v253, s[36:37]
	global_load_ushort v103, v253, s[36:37] offset:2
	global_load_ushort v104, v253, s[88:89] offset:-2
	global_load_ushort v105, v253, s[88:89]
	global_load_ushort v106, v253, s[88:89] offset:2
	global_load_ushort v107, v253, s[36:37] offset:1022
	global_load_ushort v108, v253, s[36:37] offset:1024
	global_load_ushort v111, v253, s[36:37] offset:1026
	global_load_ushort v112, v253, s[88:89] offset:1022
	global_load_ushort v113, v253, s[88:89] offset:1024
	global_load_ushort v114, v253, s[88:89] offset:1026
	global_load_ushort v115, v253, s[36:37] offset:2046
	global_load_ushort v116, v253, s[36:37] offset:2048
	global_load_ushort v117, v253, s[36:37] offset:2050
	global_load_ushort v118, v253, s[88:89] offset:2046
	global_load_ushort v119, v253, s[88:89] offset:2048
	global_load_ushort v120, v253, s[88:89] offset:2050
	global_load_ushort v121, v253, s[36:37] offset:3070
	global_load_ushort v122, v253, s[36:37] offset:3072
	global_load_ushort v123, v253, s[36:37] offset:3074
	global_load_ushort v124, v253, s[88:89] offset:3070
	global_load_ushort v125, v253, s[88:89] offset:3072
	global_load_ushort v126, v253, s[88:89] offset:3074
	global_load_ushort v127, v251, s[36:37] offset:-2
	global_load_ushort v128, v251, s[36:37]
	global_load_ushort v129, v251, s[36:37] offset:2
	global_load_ushort v130, v251, s[88:89] offset:-2
	global_load_ushort v131, v251, s[88:89]
	global_load_ushort v132, v251, s[88:89] offset:2
	global_load_ushort v133, v251, s[36:37] offset:1022
	global_load_ushort v134, v251, s[36:37] offset:1024
	global_load_ushort v135, v251, s[36:37] offset:1026
	global_load_ushort v136, v251, s[88:89] offset:1022
	global_load_ushort v137, v251, s[88:89] offset:1024
	global_load_ushort v138, v251, s[88:89] offset:1026
	global_load_ushort v139, v251, s[36:37] offset:2046
	global_load_ushort v140, v251, s[36:37] offset:2048
	global_load_ushort v141, v251, s[36:37] offset:2050
	global_load_ushort v142, v251, s[88:89] offset:2046
	global_load_ushort v143, v251, s[88:89] offset:2048
	global_load_ushort v163, v251, s[88:89] offset:2050
	global_load_ushort v164, v251, s[36:37] offset:3070
	global_load_ushort v165, v251, s[36:37] offset:3072
	global_load_ushort v166, v251, s[36:37] offset:3074
	global_load_ushort v167, v251, s[88:89] offset:3070
	global_load_ushort v168, v251, s[88:89] offset:3072
	global_load_ushort v169, v251, s[88:89] offset:3074
	global_load_ushort v170, v250, s[36:37] offset:-2
	global_load_ushort v171, v250, s[36:37]
	global_load_ushort v172, v250, s[36:37] offset:2
	global_load_ushort v173, v250, s[88:89] offset:-2
	global_load_ushort v174, v250, s[88:89]
	global_load_ushort v175, v250, s[88:89] offset:2
	global_load_ushort v176, v250, s[36:37] offset:1022
	global_load_ushort v177, v250, s[36:37] offset:1024
	global_load_ushort v178, v250, s[36:37] offset:1026
	global_load_ushort v179, v250, s[88:89] offset:1022
	global_load_ushort v180, v250, s[88:89] offset:1024
	global_load_ushort v181, v250, s[88:89] offset:1026
	global_load_ushort v182, v250, s[36:37] offset:2046
	global_load_ushort v183, v250, s[36:37] offset:2048
	global_load_ushort v184, v250, s[36:37] offset:2050
	global_load_ushort v185, v250, s[88:89] offset:2046
	global_load_ushort v186, v250, s[88:89] offset:2048
	global_load_ushort v187, v250, s[88:89] offset:2050
	global_load_ushort v188, v250, s[36:37] offset:3070
	global_load_ushort v189, v250, s[36:37] offset:3072
	global_load_ushort v190, v254, s[36:37] offset:2
	global_load_ushort v191, v250, s[88:89] offset:3070
	global_load_ushort v192, v250, s[88:89] offset:3072
	global_load_ushort v193, v254, s[88:89] offset:2
	s_waitcnt vmcnt(63)
	v_fma_f32 v27, v32, v8, v78
	v_mul_f32_e32 v32, v80, v27
	v_fma_f32 v27, v34, v8, v79
	v_mul_f32_e32 v34, v86, v27
	v_lshlrev_b32_e32 v11, 16, v11
	v_lshlrev_b32_e32 v13, 16, v13
	v_lshlrev_b32_e32 v9, 16, v9
	v_mul_f32_e32 v9, v16, v9
	v_fmac_f32_e32 v9, v14, v11
	v_fmac_f32_e32 v9, v17, v13
	v_add_f32_e32 v9, v12, v9
	v_fma_f32 v27, v33, v8, v76
	v_mul_f32_e32 v33, v9, v27
	v_lshlrev_b32_e32 v81, 16, v81
	v_lshlrev_b32_e32 v83, 16, v83
	v_lshlrev_b32_e32 v15, 16, v15
	v_mul_f32_e32 v15, v16, v15
	v_fmac_f32_e32 v15, v14, v81
	v_fmac_f32_e32 v15, v17, v83
	v_add_f32_e32 v15, v12, v15
	v_fma_f32 v27, v35, v8, v77
	v_mul_f32_e32 v35, v15, v27
	v_lshlrev_b32_e32 v87, 16, v87
	v_lshlrev_b32_e32 v89, 16, v89
	v_lshlrev_b32_e32 v85, 16, v85
	v_mul_f32_e32 v85, v16, v85
	v_fmac_f32_e32 v85, v14, v87
	v_fmac_f32_e32 v85, v17, v89
	v_add_f32_e32 v85, v12, v85
	v_fma_f32 v27, v37, v8, v72
	v_mul_f32_e32 v37, v85, v27
	v_lshlrev_b32_e32 v93, 16, v93
	v_lshlrev_b32_e32 v94, 16, v94
	v_lshlrev_b32_e32 v91, 16, v91
	v_mul_f32_e32 v91, v16, v91
	v_fmac_f32_e32 v91, v14, v93
	v_fmac_f32_e32 v91, v17, v94
	v_add_f32_e32 v91, v12, v91
	v_fma_f32 v27, v31, v8, v73
	v_mul_f32_e32 v31, v91, v27
	v_lshlrev_b32_e32 v96, 16, v96
	v_lshlrev_b32_e32 v97, 16, v97
	v_lshlrev_b32_e32 v95, 16, v95
	v_mul_f32_e32 v95, v16, v95
	v_fmac_f32_e32 v95, v14, v96
	v_fmac_f32_e32 v95, v17, v97
	v_add_f32_e32 v95, v12, v95
	v_fma_f32 v27, v36, v8, v74
	v_mul_f32_e32 v36, v95, v27
	v_lshlrev_b32_e32 v99, 16, v99
	v_lshlrev_b32_e32 v100, 16, v100
	v_lshlrev_b32_e32 v98, 16, v98
	v_mul_f32_e32 v98, v16, v98
	v_fmac_f32_e32 v98, v14, v99
	v_fmac_f32_e32 v98, v17, v100
	v_add_f32_e32 v98, v12, v98
	v_fma_f32 v27, v30, v8, v75
	v_mul_f32_e32 v30, v98, v27
	s_waitcnt vmcnt(48)
	v_lshlrev_b32_e32 v102, 16, v102
	v_lshlrev_b32_e32 v103, 16, v103
	v_lshlrev_b32_e32 v101, 16, v101
	v_mul_f32_e32 v101, v16, v101
	v_fmac_f32_e32 v101, v14, v102
	v_fmac_f32_e32 v101, v17, v103
	v_add_f32_e32 v101, v12, v101
	v_fma_f32 v27, v39, v8, v66
	v_mul_f32_e32 v39, v101, v27
	v_lshlrev_b32_e32 v105, 16, v105
	v_lshlrev_b32_e32 v106, 16, v106
	v_lshlrev_b32_e32 v104, 16, v104
	v_mul_f32_e32 v104, v16, v104
	v_fmac_f32_e32 v104, v14, v105
	v_fmac_f32_e32 v104, v17, v106
	v_add_f32_e32 v104, v12, v104
	v_fma_f32 v27, v41, v8, v67
	v_mul_f32_e32 v41, v104, v27
	v_lshlrev_b32_e32 v108, 16, v108
	v_lshlrev_b32_e32 v111, 16, v111
	v_lshlrev_b32_e32 v107, 16, v107
	v_mul_f32_e32 v107, v16, v107
	v_fmac_f32_e32 v107, v14, v108
	v_fmac_f32_e32 v107, v17, v111
	v_add_f32_e32 v107, v12, v107
	v_fma_f32 v27, v38, v8, v68
	v_mul_f32_e32 v38, v107, v27
	v_lshlrev_b32_e32 v113, 16, v113
	v_lshlrev_b32_e32 v114, 16, v114
	v_lshlrev_b32_e32 v112, 16, v112
	v_mul_f32_e32 v112, v16, v112
	v_fmac_f32_e32 v112, v14, v113
	v_fmac_f32_e32 v112, v17, v114
	v_add_f32_e32 v112, v12, v112
	v_fma_f32 v27, v40, v8, v69
	v_mul_f32_e32 v40, v112, v27
	v_lshlrev_b32_e32 v116, 16, v116
	v_lshlrev_b32_e32 v117, 16, v117
	v_lshlrev_b32_e32 v115, 16, v115
	v_mul_f32_e32 v115, v16, v115
	v_fmac_f32_e32 v115, v14, v116
	v_fmac_f32_e32 v115, v17, v117
	v_add_f32_e32 v115, v12, v115
	v_fma_f32 v27, v43, v8, v62
	v_mul_f32_e32 v43, v115, v27
	v_lshlrev_b32_e32 v119, 16, v119
	v_lshlrev_b32_e32 v120, 16, v120
	v_lshlrev_b32_e32 v118, 16, v118
	v_mul_f32_e32 v118, v16, v118
	v_fmac_f32_e32 v118, v14, v119
	v_fmac_f32_e32 v118, v17, v120
	v_add_f32_e32 v118, v12, v118
	v_fma_f32 v27, v45, v8, v63
	v_mul_f32_e32 v45, v118, v27
	v_lshlrev_b32_e32 v122, 16, v122
	v_lshlrev_b32_e32 v123, 16, v123
	v_lshlrev_b32_e32 v121, 16, v121
	v_mul_f32_e32 v121, v16, v121
	v_fmac_f32_e32 v121, v14, v122
	v_fmac_f32_e32 v121, v17, v123
	v_add_f32_e32 v121, v12, v121
	v_fma_f32 v27, v42, v8, v64
	v_mul_f32_e32 v42, v121, v27
	v_lshlrev_b32_e32 v125, 16, v125
	v_lshlrev_b32_e32 v126, 16, v126
	v_lshlrev_b32_e32 v124, 16, v124
	v_mul_f32_e32 v124, v16, v124
	v_fmac_f32_e32 v124, v14, v125
	v_fmac_f32_e32 v124, v17, v126
	v_add_f32_e32 v124, v12, v124
	v_fma_f32 v27, v44, v8, v65
	v_mul_f32_e32 v44, v124, v27
	s_waitcnt vmcnt(24)
	v_lshlrev_b32_e32 v128, 16, v128
	v_lshlrev_b32_e32 v129, 16, v129
	v_lshlrev_b32_e32 v127, 16, v127
	v_mul_f32_e32 v127, v16, v127
	v_fmac_f32_e32 v127, v14, v128
	v_fmac_f32_e32 v127, v17, v129
	v_add_f32_e32 v127, v12, v127
	v_fma_f32 v27, v47, v8, v22
	v_mul_f32_e32 v47, v127, v27
	v_lshlrev_b32_e32 v131, 16, v131
	v_lshlrev_b32_e32 v132, 16, v132
	v_lshlrev_b32_e32 v130, 16, v130
	v_mul_f32_e32 v130, v16, v130
	v_fmac_f32_e32 v130, v14, v131
	v_fmac_f32_e32 v130, v17, v132
	v_add_f32_e32 v130, v12, v130
	v_fma_f32 v27, v49, v8, v23
	v_mul_f32_e32 v49, v130, v27
	v_lshlrev_b32_e32 v134, 16, v134
	v_lshlrev_b32_e32 v135, 16, v135
	v_lshlrev_b32_e32 v133, 16, v133
	v_mul_f32_e32 v133, v16, v133
	v_fmac_f32_e32 v133, v14, v134
	v_fmac_f32_e32 v133, v17, v135
	v_add_f32_e32 v133, v12, v133
	v_fma_f32 v27, v46, v8, v24
	v_mul_f32_e32 v46, v133, v27
	v_lshlrev_b32_e32 v137, 16, v137
	v_lshlrev_b32_e32 v138, 16, v138
	v_lshlrev_b32_e32 v136, 16, v136
	v_mul_f32_e32 v136, v16, v136
	v_fmac_f32_e32 v136, v14, v137
	v_fmac_f32_e32 v136, v17, v138
	v_add_f32_e32 v136, v12, v136
	v_fma_f32 v27, v48, v8, v25
	v_mul_f32_e32 v48, v136, v27
	v_lshlrev_b32_e32 v140, 16, v140
	v_lshlrev_b32_e32 v141, 16, v141
	v_lshlrev_b32_e32 v139, 16, v139
	v_mul_f32_e32 v139, v16, v139
	v_fmac_f32_e32 v139, v14, v140
	v_fmac_f32_e32 v139, v17, v141
	v_add_f32_e32 v139, v12, v139
	v_fma_f32 v27, v51, v8, v18
	v_mul_f32_e32 v51, v139, v27
	v_lshlrev_b32_e32 v143, 16, v143
	v_lshlrev_b32_e32 v163, 16, v163
	v_lshlrev_b32_e32 v142, 16, v142
	v_mul_f32_e32 v142, v16, v142
	v_fmac_f32_e32 v142, v14, v143
	v_fmac_f32_e32 v142, v17, v163
	v_add_f32_e32 v142, v12, v142
	v_fma_f32 v27, v53, v8, v19
	v_mul_f32_e32 v53, v142, v27
	v_lshlrev_b32_e32 v165, 16, v165
	v_lshlrev_b32_e32 v166, 16, v166
	v_lshlrev_b32_e32 v164, 16, v164
	v_mul_f32_e32 v164, v16, v164
	v_fmac_f32_e32 v164, v14, v165
	v_fmac_f32_e32 v164, v17, v166
	v_add_f32_e32 v164, v12, v164
	v_fma_f32 v27, v50, v8, v20
	v_mul_f32_e32 v50, v164, v27
	v_lshlrev_b32_e32 v168, 16, v168
	v_lshlrev_b32_e32 v169, 16, v169
	v_lshlrev_b32_e32 v167, 16, v167
	v_mul_f32_e32 v167, v16, v167
	v_fmac_f32_e32 v167, v14, v168
	v_fmac_f32_e32 v167, v17, v169
	v_add_f32_e32 v167, v12, v167
	v_fma_f32 v27, v52, v8, v21
	v_mul_f32_e32 v52, v167, v27
	s_waitcnt vmcnt(0)
	v_lshlrev_b32_e32 v171, 16, v171
	v_lshlrev_b32_e32 v172, 16, v172
	v_lshlrev_b32_e32 v170, 16, v170
	v_mul_f32_e32 v170, v16, v170
	v_fmac_f32_e32 v170, v14, v171
	v_fmac_f32_e32 v170, v17, v172
	v_add_f32_e32 v170, v12, v170
	v_fma_f32 v27, v55, v8, v4
	v_mul_f32_e32 v55, v170, v27
	v_lshlrev_b32_e32 v174, 16, v174
	v_lshlrev_b32_e32 v175, 16, v175
	v_lshlrev_b32_e32 v173, 16, v173
	v_mul_f32_e32 v173, v16, v173
	v_fmac_f32_e32 v173, v14, v174
	v_fmac_f32_e32 v173, v17, v175
	v_add_f32_e32 v173, v12, v173
	v_fma_f32 v27, v57, v8, v5
	v_mul_f32_e32 v57, v173, v27
	v_lshlrev_b32_e32 v177, 16, v177
	v_lshlrev_b32_e32 v178, 16, v178
	v_lshlrev_b32_e32 v176, 16, v176
	v_mul_f32_e32 v176, v16, v176
	v_fmac_f32_e32 v176, v14, v177
	v_fmac_f32_e32 v176, v17, v178
	v_add_f32_e32 v176, v12, v176
	v_fma_f32 v27, v54, v8, v6
	v_mul_f32_e32 v54, v176, v27
	v_lshlrev_b32_e32 v180, 16, v180
	v_lshlrev_b32_e32 v181, 16, v181
	v_lshlrev_b32_e32 v179, 16, v179
	v_mul_f32_e32 v179, v16, v179
	v_fmac_f32_e32 v179, v14, v180
	v_fmac_f32_e32 v179, v17, v181
	v_add_f32_e32 v179, v12, v179
	v_fma_f32 v27, v56, v8, v7
	v_mul_f32_e32 v56, v179, v27
	v_lshlrev_b32_e32 v183, 16, v183
	v_lshlrev_b32_e32 v184, 16, v184
	v_lshlrev_b32_e32 v182, 16, v182
	v_mul_f32_e32 v182, v16, v182
	v_fmac_f32_e32 v182, v14, v183
	v_fmac_f32_e32 v182, v17, v184
	v_add_f32_e32 v182, v12, v182
	v_fma_f32 v27, v59, v8, v0
	v_mul_f32_e32 v59, v182, v27
	v_lshlrev_b32_e32 v186, 16, v186
	v_lshlrev_b32_e32 v187, 16, v187
	v_lshlrev_b32_e32 v185, 16, v185
	v_mul_f32_e32 v185, v16, v185
	v_fmac_f32_e32 v185, v14, v186
	v_fmac_f32_e32 v185, v17, v187
	v_add_f32_e32 v185, v12, v185
	v_fma_f32 v27, v61, v8, v1
	v_mul_f32_e32 v61, v185, v27
	v_lshlrev_b32_e32 v189, 16, v189
	v_lshlrev_b32_e32 v190, 16, v190
	v_lshlrev_b32_e32 v188, 16, v188
	v_mul_f32_e32 v188, v16, v188
	v_mul_f32_e32 v190, v255, v190
	v_fmac_f32_e32 v188, v14, v189
	v_fmac_f32_e32 v188, v17, v190
	v_add_f32_e32 v188, v12, v188
	v_fma_f32 v27, v58, v8, v2
	v_mul_f32_e32 v58, v188, v27
	v_lshlrev_b32_e32 v192, 16, v192
	v_lshlrev_b32_e32 v193, 16, v193
	v_lshlrev_b32_e32 v191, 16, v191
	v_mul_f32_e32 v191, v16, v191
	v_mul_f32_e32 v193, v255, v193
	v_fmac_f32_e32 v191, v14, v192
	v_fmac_f32_e32 v191, v17, v193
	v_add_f32_e32 v191, v12, v191
	v_fma_f32 v27, v60, v8, v3
	v_mul_f32_e32 v60, v191, v27
	s_branch .LBB0_537

.LBB0_910:
	s_lshl_b32 s98, s16, 16
	s_mov_b32 s99, 0
	v_lshl_add_u64 v[196:197], s[98:99], 0, v[28:29]
	global_load_dwordx4 v[164:167], v[196:197], off offset:-4096
	global_load_dwordx4 v[168:171], v[196:197], off offset:-3072
	global_load_dwordx4 v[172:175], v[196:197], off offset:-2048
	global_load_dwordx4 v[176:179], v[196:197], off offset:-1024
	global_load_dwordx4 v[180:183], v[196:197], off
	global_load_dwordx4 v[184:187], v[196:197], off offset:1024
	global_load_dwordx4 v[188:191], v[196:197], off offset:2048
	global_load_dwordx4 v[192:195], v[196:197], off offset:3072
	v_mov_b32_e32 v20, v46
	v_mov_b32_e32 v21, v48
	v_mov_b32_e32 v22, v51
	v_mov_b32_e32 v23, v53
	v_pk_add_f32 v[88:89], v[20:21], 0 op_sel_hi:[1,0]
	v_pk_mul_f32 v[20:21], v[20:21], s[48:49] op_sel_hi:[1,0]
	v_xor_b32_e32 v91, 0x80000000, v46
	v_mov_b32_e32 v90, v48
	v_pk_add_f32 v[92:93], v[50:51], 0 neg_lo:[1,1] neg_hi:[1,1]
	v_mov_b32_e32 v24, v50
	v_mov_b32_e32 v25, v52
	v_pk_fma_f32 v[20:21], v[90:91], s[44:45], v[20:21] op_sel_hi:[1,0,1] neg_lo:[0,0,1] neg_hi:[0,0,1]
	v_pk_add_f32 v[90:91], v[22:23], 0 op_sel_hi:[1,0]
	v_pk_mul_f32 v[22:23], v[22:23], s[54:55] op_sel_hi:[1,0]
	v_mov_b32_e32 v92, v53
	v_mov_b32_e32 v26, v55
	v_mov_b32_e32 v27, v57
	v_pk_fma_f32 v[22:23], v[92:93], s[52:53], v[22:23] op_sel_hi:[1,0,1] neg_lo:[0,0,1] neg_hi:[0,0,1]
	v_pk_add_f32 v[92:93], v[24:25], 0 op_sel_hi:[1,0]
	v_pk_mul_f32 v[24:25], v[24:25], s[58:59] op_sel_hi:[1,0]
	v_xor_b32_e32 v95, 0x80000000, v50
	v_mov_b32_e32 v94, v52
	v_pk_add_f32 v[96:97], v[54:55], 0 neg_lo:[1,1] neg_hi:[1,1]
	v_mov_b32_e32 v64, v54
	v_mov_b32_e32 v65, v56
	v_pk_fma_f32 v[24:25], v[94:95], s[56:57], v[24:25] op_sel_hi:[1,0,1] neg_lo:[0,0,1] neg_hi:[0,0,1]
	v_pk_add_f32 v[94:95], v[26:27], 0 op_sel_hi:[1,0]
	v_pk_mul_f32 v[26:27], v[26:27], s[60:61] op_sel_hi:[1,0]
	v_mov_b32_e32 v96, v57
	v_mov_b32_e32 v66, v59
	v_mov_b32_e32 v67, v61
	v_pk_fma_f32 v[26:27], v[96:97], s[60:61], v[26:27] op_sel_hi:[1,0,1] neg_lo:[0,0,1] neg_hi:[0,0,1]
	v_pk_add_f32 v[96:97], v[64:65], 0 op_sel_hi:[1,0]
	v_pk_mul_f32 v[64:65], v[64:65], s[56:57] op_sel_hi:[1,0]
	v_xor_b32_e32 v99, 0x80000000, v54
	v_mov_b32_e32 v98, v56
	v_pk_add_f32 v[100:101], v[58:59], 0 neg_lo:[1,1] neg_hi:[1,1]
	v_mov_b32_e32 v2, v32
	v_mov_b32_e32 v3, v34
	v_mov_b32_e32 v4, v33
	v_mov_b32_e32 v5, v35
	v_mov_b32_e32 v18, v47
	v_mov_b32_e32 v19, v49
	v_mov_b32_e32 v68, v58
	v_mov_b32_e32 v69, v60
	v_pk_fma_f32 v[64:65], v[98:99], s[58:59], v[64:65] op_sel_hi:[1,0,1] neg_lo:[0,0,1] neg_hi:[0,0,1]
	v_pk_add_f32 v[98:99], v[66:67], 0 op_sel_hi:[1,0]
	v_pk_mul_f32 v[66:67], v[66:67], s[52:53] op_sel_hi:[1,0]
	v_mov_b32_e32 v100, v61
	v_pk_add_f32 v[70:71], v[2:3], 0 op_sel_hi:[1,0]
	v_pk_add_f32 v[72:73], v[4:5], 0 op_sel_hi:[1,0]
	v_pk_add_f32 v[74:75], v[32:33], 0 neg_lo:[1,1] neg_hi:[1,1]
	v_pk_add_f32 v[18:19], v[18:19], 0 op_sel_hi:[1,0]
	v_pk_fma_f32 v[66:67], v[100:101], s[54:55], v[66:67] op_sel_hi:[1,0,1] neg_lo:[0,0,1] neg_hi:[0,0,1]
	v_pk_add_f32 v[100:101], v[68:69], 0 op_sel_hi:[1,0]
	v_pk_mul_f32 v[68:69], v[68:69], s[44:45] op_sel_hi:[1,0]
	v_xor_b32_e32 v103, 0x80000000, v58
	v_mov_b32_e32 v102, v60
	v_mov_b32_e32 v74, v35
	v_pk_fma_f32 v[68:69], v[102:103], s[48:49], v[68:69] op_sel_hi:[1,0,1] neg_lo:[0,0,1] neg_hi:[0,0,1]
	v_pk_add_f32 v[102:103], v[18:19], v[70:71]
	v_pk_add_f32 v[18:19], v[70:71], v[18:19] neg_lo:[0,1] neg_hi:[0,1]
	v_pk_add_f32 v[70:71], v[88:89], v[72:73]
	v_pk_add_f32 v[72:73], v[72:73], v[88:89] neg_lo:[0,1] neg_hi:[0,1]
	v_mov_b32_e32 v6, v37
	v_mov_b32_e32 v7, v31
	v_pk_mul_f32 v[74:75], v[74:75], s[48:49] op_sel_hi:[1,0]
	s_nop 0
	v_pk_fma_f32 v[4:5], v[4:5], s[44:45], v[74:75] op_sel_hi:[1,0,1]
	v_pk_add_f32 v[74:75], v[6:7], 0 op_sel_hi:[1,0]
	v_pk_add_f32 v[76:77], v[36:37], 0 neg_lo:[1,1] neg_hi:[1,1]
	v_pk_mul_f32 v[88:89], v[72:73], s[54:55] op_sel:[1,0] op_sel_hi:[0,0] neg_hi:[1,0]
	v_mov_b32_e32 v76, v31
	v_pk_fma_f32 v[72:73], v[72:73], s[52:53], v[88:89] op_sel_hi:[1,0,1]
	v_pk_add_f32 v[88:89], v[90:91], v[74:75]
	v_pk_add_f32 v[74:75], v[74:75], v[90:91] neg_lo:[0,1] neg_hi:[0,1]
	v_mov_b32_e32 v8, v36
	v_mov_b32_e32 v9, v30
	v_pk_mul_f32 v[76:77], v[76:77], s[54:55] op_sel_hi:[1,0]
	s_nop 0
	v_pk_fma_f32 v[6:7], v[6:7], s[52:53], v[76:77] op_sel_hi:[1,0,1]
	v_pk_add_f32 v[76:77], v[8:9], 0 op_sel_hi:[1,0]
	v_pk_mul_f32 v[90:91], v[74:75], s[60:61] op_sel:[1,0] op_sel_hi:[0,0] neg_hi:[1,0]
	v_xor_b32_e32 v79, 0x80000000, v36
	v_mov_b32_e32 v78, v30
	v_pk_add_f32 v[80:81], v[38:39], 0 neg_lo:[1,1] neg_hi:[1,1]
	v_pk_fma_f32 v[74:75], v[74:75], s[60:61], v[90:91] op_sel_hi:[1,0,1]
	v_pk_add_f32 v[90:91], v[92:93], v[76:77]
	v_pk_add_f32 v[76:77], v[76:77], v[92:93] neg_lo:[0,1] neg_hi:[0,1]
	v_mov_b32_e32 v10, v39
	v_mov_b32_e32 v11, v41
	v_pk_mul_f32 v[78:79], v[78:79], s[58:59] op_sel_hi:[1,0]
	v_mov_b32_e32 v80, v41
	v_mov_b32_e32 v12, v38
	v_mov_b32_e32 v13, v40
	v_pk_fma_f32 v[8:9], v[8:9], s[56:57], v[78:79] op_sel_hi:[1,0,1]
	v_pk_add_f32 v[78:79], v[10:11], 0 op_sel_hi:[1,0]
	v_pk_mul_f32 v[80:81], v[80:81], s[60:61] op_sel_hi:[1,0]
	v_pk_mul_f32 v[92:93], v[76:77], s[52:53] op_sel:[1,0] op_sel_hi:[0,0] neg_hi:[1,0]
	v_pk_fma_f32 v[10:11], v[10:11], s[60:61], v[80:81] op_sel_hi:[1,0,1]
	v_pk_add_f32 v[80:81], v[12:13], 0 op_sel_hi:[1,0]
	v_xor_b32_e32 v83, 0x80000000, v38
	v_mov_b32_e32 v82, v40
	v_pk_fma_f32 v[76:77], v[76:77], s[54:55], v[92:93] op_sel_hi:[1,0,1]
	v_pk_add_f32 v[92:93], v[94:95], v[78:79]
	v_pk_add_f32 v[78:79], v[78:79], v[94:95] neg_lo:[0,1] neg_hi:[0,1]
	v_mov_b32_e32 v14, v43
	v_mov_b32_e32 v15, v45
	v_pk_mul_f32 v[82:83], v[82:83], s[56:57] op_sel_hi:[1,0]
	v_pk_add_f32 v[84:85], v[42:43], 0 neg_lo:[1,1] neg_hi:[1,1]
	v_xor_b32_e32 v95, 0x80000000, v78
	v_mov_b32_e32 v94, v79
	v_pk_add_f32 v[78:79], v[96:97], v[80:81]
	v_pk_add_f32 v[80:81], v[80:81], v[96:97] neg_lo:[0,1] neg_hi:[0,1]
	v_pk_fma_f32 v[12:13], v[12:13], s[58:59], v[82:83] op_sel_hi:[1,0,1]
	v_pk_add_f32 v[82:83], v[14:15], 0 op_sel_hi:[1,0]
	v_mov_b32_e32 v84, v45
	v_pk_mul_f32 v[96:97], v[80:81], s[54:55] op_sel_hi:[1,0]
	v_xor_b32_e32 v105, 0x80000000, v80
	v_mov_b32_e32 v104, v81
	v_mov_b32_e32 v16, v42
	v_mov_b32_e32 v17, v44
	v_pk_mul_f32 v[84:85], v[84:85], s[52:53] op_sel_hi:[1,0]
	v_xor_b32_e32 v87, 0x80000000, v42
	v_mov_b32_e32 v86, v44
	v_pk_fma_f32 v[80:81], v[104:105], s[52:53], v[96:97] op_sel_hi:[1,0,1] neg_lo:[0,0,1] neg_hi:[0,0,1]
	v_pk_add_f32 v[96:97], v[98:99], v[82:83]
	v_pk_add_f32 v[82:83], v[82:83], v[98:99] neg_lo:[0,1] neg_hi:[0,1]
	v_pk_fma_f32 v[14:15], v[14:15], s[54:55], v[84:85] op_sel_hi:[1,0,1]
	v_pk_add_f32 v[84:85], v[16:17], 0 op_sel_hi:[1,0]
	v_pk_mul_f32 v[86:87], v[86:87], s[44:45] op_sel_hi:[1,0]
	v_pk_mul_f32 v[98:99], v[82:83], s[60:61] op_sel_hi:[1,0]
	v_xor_b32_e32 v105, 0x80000000, v82
	v_mov_b32_e32 v104, v83
	v_pk_fma_f32 v[16:17], v[16:17], s[48:49], v[86:87] op_sel_hi:[1,0,1]
	v_pk_add_f32 v[86:87], v[46:47], 0 neg_lo:[1,1] neg_hi:[1,1]
	v_pk_fma_f32 v[82:83], v[104:105], s[60:61], v[98:99] op_sel_hi:[1,0,1] neg_lo:[0,0,1] neg_hi:[0,0,1]
	v_pk_add_f32 v[98:99], v[100:101], v[84:85]
	v_pk_add_f32 v[84:85], v[84:85], v[100:101] neg_lo:[0,1] neg_hi:[0,1]
	v_mov_b32_e32 v86, v49
	v_pk_mul_f32 v[100:101], v[84:85], s[52:53] op_sel_hi:[1,0]
	v_xor_b32_e32 v105, 0x80000000, v84
	v_mov_b32_e32 v104, v85
	v_pk_fma_f32 v[84:85], v[104:105], s[54:55], v[100:101] op_sel_hi:[1,0,1] neg_lo:[0,0,1] neg_hi:[0,0,1]
	v_pk_add_f32 v[100:101], v[86:87], v[2:3]
	v_pk_add_f32 v[2:3], v[2:3], v[86:87] neg_lo:[0,1] neg_hi:[0,1]
	v_pk_add_f32 v[86:87], v[20:21], v[4:5]
	v_pk_add_f32 v[4:5], v[4:5], v[20:21] neg_lo:[0,1] neg_hi:[0,1]
	v_mov_b32_e32 v63, v146
	v_pk_mul_f32 v[20:21], v[4:5], s[54:55] op_sel:[1,0] op_sel_hi:[0,0] neg_hi:[1,0]
	s_nop 0
	v_pk_fma_f32 v[4:5], v[4:5], s[52:53], v[20:21] op_sel_hi:[1,0,1]
	v_pk_add_f32 v[20:21], v[22:23], v[6:7]
	v_pk_add_f32 v[6:7], v[6:7], v[22:23] neg_lo:[0,1] neg_hi:[0,1]
	s_barrier
	v_pk_mul_f32 v[22:23], v[6:7], s[60:61] op_sel:[1,0] op_sel_hi:[0,0] neg_hi:[1,0]
	s_nop 0
	v_pk_fma_f32 v[6:7], v[6:7], s[60:61], v[22:23] op_sel_hi:[1,0,1]
	v_pk_add_f32 v[22:23], v[24:25], v[8:9]
	v_pk_add_f32 v[8:9], v[8:9], v[24:25] neg_lo:[0,1] neg_hi:[0,1]
	s_add_i32 s19, 16, 0x11000
	v_pk_mul_f32 v[24:25], v[8:9], s[52:53] op_sel:[1,0] op_sel_hi:[0,0] neg_hi:[1,0]
	s_add_i32 s18, 16, 0x12000
	v_pk_fma_f32 v[8:9], v[8:9], s[54:55], v[24:25] op_sel_hi:[1,0,1]
	v_pk_add_f32 v[24:25], v[26:27], v[10:11]
	v_pk_add_f32 v[10:11], v[10:11], v[26:27] neg_lo:[0,1] neg_hi:[0,1]
	s_add_i32 s17, 16, 0x13000
	v_xor_b32_e32 v27, 0x80000000, v10
	v_mov_b32_e32 v26, v11
	v_pk_add_f32 v[10:11], v[64:65], v[12:13]
	v_pk_add_f32 v[12:13], v[12:13], v[64:65] neg_lo:[0,1] neg_hi:[0,1]
	s_add_i32 s13, 16, 0x14000
	v_pk_mul_f32 v[64:65], v[12:13], s[54:55] op_sel_hi:[1,0]
	v_xor_b32_e32 v105, 0x80000000, v12
	v_mov_b32_e32 v104, v13
	v_pk_fma_f32 v[12:13], v[104:105], s[52:53], v[64:65] op_sel_hi:[1,0,1] neg_lo:[0,0,1] neg_hi:[0,0,1]
	v_pk_add_f32 v[64:65], v[66:67], v[14:15]
	v_pk_add_f32 v[14:15], v[14:15], v[66:67] neg_lo:[0,1] neg_hi:[0,1]
	s_add_i32 s12, 16, 0x15000
	v_pk_mul_f32 v[66:67], v[14:15], s[60:61] op_sel_hi:[1,0]
	v_xor_b32_e32 v105, 0x80000000, v14
	v_mov_b32_e32 v104, v15
	v_pk_fma_f32 v[14:15], v[104:105], s[60:61], v[66:67] op_sel_hi:[1,0,1] neg_lo:[0,0,1] neg_hi:[0,0,1]
	v_pk_add_f32 v[66:67], v[68:69], v[16:17]
	v_pk_add_f32 v[16:17], v[16:17], v[68:69] neg_lo:[0,1] neg_hi:[0,1]
	s_add_i32 s11, 16, 0x16000
	v_pk_mul_f32 v[68:69], v[16:17], s[52:53] op_sel_hi:[1,0]
	v_xor_b32_e32 v105, 0x80000000, v16
	v_mov_b32_e32 v104, v17
	v_pk_fma_f32 v[16:17], v[104:105], s[54:55], v[68:69] op_sel_hi:[1,0,1] neg_lo:[0,0,1] neg_hi:[0,0,1]
	v_pk_add_f32 v[68:69], v[92:93], v[102:103]
	v_pk_add_f32 v[92:93], v[102:103], v[92:93] neg_lo:[0,1] neg_hi:[0,1]
	v_pk_add_f32 v[102:103], v[78:79], v[70:71]
	v_pk_add_f32 v[70:71], v[70:71], v[78:79] neg_lo:[0,1] neg_hi:[0,1]
	s_add_i32 s10, 16, 0x17000
	v_pk_mul_f32 v[78:79], v[70:71], s[60:61] op_sel:[1,0] op_sel_hi:[0,0] neg_hi:[1,0]
	s_add_i32 s9, 16, 0x18000
	v_pk_fma_f32 v[70:71], v[70:71], s[60:61], v[78:79] op_sel_hi:[1,0,1]
	v_pk_add_f32 v[78:79], v[96:97], v[88:89]
	v_pk_add_f32 v[88:89], v[88:89], v[96:97] neg_lo:[0,1] neg_hi:[0,1]
	s_add_i32 s8, 16, 0x19000
	v_xor_b32_e32 v97, 0x80000000, v88
	v_mov_b32_e32 v96, v89
	v_pk_add_f32 v[88:89], v[98:99], v[90:91]
	v_pk_add_f32 v[90:91], v[90:91], v[98:99] neg_lo:[0,1] neg_hi:[0,1]
	s_add_i32 s7, 16, 0x1a000
	v_pk_mul_f32 v[98:99], v[90:91], s[60:61] op_sel_hi:[1,0]
	v_xor_b32_e32 v105, 0x80000000, v90
	v_mov_b32_e32 v104, v91
	v_pk_fma_f32 v[90:91], v[104:105], s[60:61], v[98:99] op_sel_hi:[1,0,1] neg_lo:[0,0,1] neg_hi:[0,0,1]
	v_pk_add_f32 v[98:99], v[94:95], v[18:19]
	v_pk_add_f32 v[18:19], v[18:19], v[94:95] neg_lo:[0,1] neg_hi:[0,1]
	v_pk_add_f32 v[94:95], v[80:81], v[72:73]
	v_pk_add_f32 v[72:73], v[72:73], v[80:81] neg_lo:[0,1] neg_hi:[0,1]
	s_add_i32 s6, 16, 0x1b000
	v_pk_mul_f32 v[80:81], v[72:73], s[60:61] op_sel:[1,0] op_sel_hi:[0,0] neg_hi:[1,0]
	s_add_i32 s5, 16, 0x1c000
	v_pk_fma_f32 v[72:73], v[72:73], s[60:61], v[80:81] op_sel_hi:[1,0,1]
	v_pk_add_f32 v[80:81], v[82:83], v[74:75]
	v_pk_add_f32 v[74:75], v[74:75], v[82:83] neg_lo:[0,1] neg_hi:[0,1]
	s_add_i32 s4, 16, 0x1d000
	v_xor_b32_e32 v83, 0x80000000, v74
	v_mov_b32_e32 v82, v75
	v_pk_add_f32 v[74:75], v[84:85], v[76:77]
	v_pk_add_f32 v[76:77], v[76:77], v[84:85] neg_lo:[0,1] neg_hi:[0,1]
	v_pk_add_f32 v[106:107], v[18:19], v[82:83]
	v_pk_mul_f32 v[84:85], v[76:77], s[60:61] op_sel_hi:[1,0]
	v_xor_b32_e32 v105, 0x80000000, v76
	v_mov_b32_e32 v104, v77
	v_pk_fma_f32 v[76:77], v[104:105], s[60:61], v[84:85] op_sel_hi:[1,0,1] neg_lo:[0,0,1] neg_hi:[0,0,1]
	v_pk_add_f32 v[84:85], v[24:25], v[100:101]
	v_pk_add_f32 v[24:25], v[100:101], v[24:25] neg_lo:[0,1] neg_hi:[0,1]
	v_pk_add_f32 v[100:101], v[10:11], v[86:87]
	v_pk_add_f32 v[10:11], v[86:87], v[10:11] neg_lo:[0,1] neg_hi:[0,1]
	v_pk_add_f32 v[18:19], v[18:19], v[82:83] neg_lo:[0,1] neg_hi:[0,1]
	v_pk_mul_f32 v[86:87], v[10:11], s[60:61] op_sel:[1,0] op_sel_hi:[0,0] neg_hi:[1,0]
	v_pk_add_f32 v[82:83], v[76:77], v[72:73]
	v_pk_fma_f32 v[10:11], v[10:11], s[60:61], v[86:87] op_sel_hi:[1,0,1]
	v_pk_add_f32 v[86:87], v[64:65], v[20:21]
	v_pk_add_f32 v[20:21], v[20:21], v[64:65] neg_lo:[0,1] neg_hi:[0,1]
	v_pk_add_f32 v[72:73], v[72:73], v[76:77] neg_lo:[0,1] neg_hi:[0,1]
	v_xor_b32_e32 v65, 0x80000000, v20
	v_mov_b32_e32 v64, v21
	v_pk_add_f32 v[20:21], v[66:67], v[22:23]
	v_pk_add_f32 v[22:23], v[22:23], v[66:67] neg_lo:[0,1] neg_hi:[0,1]
	v_xor_b32_e32 v77, 0x80000000, v72
	v_pk_mul_f32 v[66:67], v[22:23], s[60:61] op_sel_hi:[1,0]
	v_xor_b32_e32 v105, 0x80000000, v22
	v_mov_b32_e32 v104, v23
	v_pk_fma_f32 v[22:23], v[104:105], s[60:61], v[66:67] op_sel_hi:[1,0,1] neg_lo:[0,0,1] neg_hi:[0,0,1]
	v_pk_add_f32 v[66:67], v[2:3], v[26:27]
	v_pk_add_f32 v[2:3], v[2:3], v[26:27] neg_lo:[0,1] neg_hi:[0,1]
	v_pk_add_f32 v[26:27], v[12:13], v[4:5]
	v_pk_add_f32 v[4:5], v[4:5], v[12:13] neg_lo:[0,1] neg_hi:[0,1]
	v_mov_b32_e32 v76, v73
	v_pk_mul_f32 v[12:13], v[4:5], s[60:61] op_sel:[1,0] op_sel_hi:[0,0] neg_hi:[1,0]
	v_pk_add_f32 v[72:73], v[84:85], v[86:87]
	v_pk_fma_f32 v[4:5], v[4:5], s[60:61], v[12:13] op_sel_hi:[1,0,1]
	v_pk_add_f32 v[12:13], v[14:15], v[6:7]
	v_pk_add_f32 v[6:7], v[6:7], v[14:15] neg_lo:[0,1] neg_hi:[0,1]
	v_pk_add_f32 v[84:85], v[84:85], v[86:87] neg_lo:[0,1] neg_hi:[0,1]
	v_xor_b32_e32 v15, 0x80000000, v6
	v_mov_b32_e32 v14, v7
	v_pk_add_f32 v[6:7], v[16:17], v[8:9]
	v_pk_add_f32 v[8:9], v[8:9], v[16:17] neg_lo:[0,1] neg_hi:[0,1]
	v_pk_add_f32 v[86:87], v[20:21], v[100:101]
	v_pk_mul_f32 v[16:17], v[8:9], s[60:61] op_sel_hi:[1,0]
	s_nop 0
	v_pk_fma_f32 v[8:9], v[8:9], s[60:61], v[16:17] op_sel:[1,0,0] op_sel_hi:[0,0,1] neg_lo:[0,0,1] neg_hi:[1,0,1]
	v_pk_add_f32 v[104:105], v[92:93], v[96:97]
	v_pk_add_f32 v[92:93], v[92:93], v[96:97] neg_lo:[0,1] neg_hi:[0,1]
	v_pk_add_f32 v[96:97], v[90:91], v[70:71]
	v_pk_add_f32 v[70:71], v[70:71], v[90:91] neg_lo:[0,1] neg_hi:[0,1]
	v_pk_add_f32 v[16:17], v[78:79], v[68:69]
	v_pk_add_f32 v[68:69], v[68:69], v[78:79] neg_lo:[0,1] neg_hi:[0,1]
	v_pk_add_f32 v[78:79], v[88:89], v[102:103]
	v_pk_add_f32 v[88:89], v[102:103], v[88:89] neg_lo:[0,1] neg_hi:[0,1]
	v_xor_b32_e32 v91, 0x80000000, v70
	v_mov_b32_e32 v90, v71
	v_pk_add_f32 v[70:71], v[98:99], v[80:81]
	v_pk_add_f32 v[98:99], v[98:99], v[80:81] neg_lo:[0,1] neg_hi:[0,1]
	v_pk_add_f32 v[80:81], v[74:75], v[94:95]
	v_pk_add_f32 v[74:75], v[94:95], v[74:75] neg_lo:[0,1] neg_hi:[0,1]
	v_pk_add_f32 v[20:21], v[100:101], v[20:21] neg_lo:[0,1] neg_hi:[0,1]
	v_pk_add_f32 v[108:109], v[24:25], v[64:65]
	v_pk_add_f32 v[24:25], v[24:25], v[64:65] neg_lo:[0,1] neg_hi:[0,1]
	v_pk_add_f32 v[64:65], v[22:23], v[10:11]
	v_pk_add_f32 v[10:11], v[10:11], v[22:23] neg_lo:[0,1] neg_hi:[0,1]
	v_pk_add_f32 v[114:115], v[6:7], v[26:27]
	v_pk_add_f32 v[6:7], v[26:27], v[6:7] neg_lo:[0,1] neg_hi:[0,1]
	v_xor_b32_e32 v103, 0x80000000, v88
	v_mov_b32_e32 v102, v89
	v_xor_b32_e32 v95, 0x80000000, v74
	v_mov_b32_e32 v94, v75
	v_xor_b32_e32 v101, 0x80000000, v20
	v_mov_b32_e32 v100, v21
	v_xor_b32_e32 v27, 0x80000000, v6
	v_mov_b32_e32 v26, v7
	v_pk_add_f32 v[6:7], v[2:3], v[14:15]
	v_pk_add_f32 v[116:117], v[2:3], v[14:15] neg_lo:[0,1] neg_hi:[0,1]
	v_pk_add_f32 v[2:3], v[4:5], v[8:9] neg_lo:[0,1] neg_hi:[0,1]
	v_pk_add_f32 v[112:113], v[66:67], v[12:13]
	v_pk_add_f32 v[66:67], v[66:67], v[12:13] neg_lo:[0,1] neg_hi:[0,1]
	v_pk_add_f32 v[118:119], v[8:9], v[4:5]
	v_xor_b32_e32 v121, 0x80000000, v2
	v_mov_b32_e32 v120, v3
	v_pk_add_f32 v[2:3], v[78:79], v[16:17]
	v_pk_add_f32 v[88:89], v[16:17], v[78:79] neg_lo:[0,1] neg_hi:[0,1]
	v_pk_add_f32 v[122:123], v[68:69], v[102:103]
	v_pk_add_f32 v[20:21], v[68:69], v[102:103] neg_lo:[0,1] neg_hi:[0,1]
	v_pk_add_f32 v[78:79], v[104:105], v[96:97]
	v_pk_add_f32 v[74:75], v[104:105], v[96:97] neg_lo:[0,1] neg_hi:[0,1]
	v_pk_add_f32 v[96:97], v[92:93], v[90:91]
	v_pk_add_f32 v[8:9], v[92:93], v[90:91] neg_lo:[0,1] neg_hi:[0,1]
	v_pk_add_f32 v[102:103], v[98:99], v[94:95]
	v_pk_add_f32 v[12:13], v[98:99], v[94:95] neg_lo:[0,1] neg_hi:[0,1]
	v_pk_add_f32 v[98:99], v[18:19], v[76:77]
	v_pk_add_f32 v[4:5], v[18:19], v[76:77] neg_lo:[0,1] neg_hi:[0,1]
	v_pk_add_f32 v[18:19], v[72:73], v[86:87]
	v_pk_add_f32 v[92:93], v[72:73], v[86:87] neg_lo:[0,1] neg_hi:[0,1]
	v_pk_add_f32 v[86:87], v[84:85], v[100:101]
	v_pk_add_f32 v[22:23], v[84:85], v[100:101] neg_lo:[0,1] neg_hi:[0,1]
	v_pk_add_f32 v[100:101], v[24:25], v[10:11] op_sel:[0,1] op_sel_hi:[1,0] neg_hi:[0,1]
	v_pk_add_f32 v[10:11], v[24:25], v[10:11] op_sel:[0,1] op_sel_hi:[1,0] neg_lo:[0,1]
	v_mov_b32_e32 v24, v63
	v_pk_add_f32 v[84:85], v[108:109], v[64:65]
	v_cvt_f32_i32_e32 v24, v24
	v_pk_add_f32 v[76:77], v[108:109], v[64:65] neg_lo:[0,1] neg_hi:[0,1]
	v_pk_add_f32 v[104:105], v[66:67], v[26:27]
	v_pk_add_f32 v[14:15], v[66:67], v[26:27] neg_lo:[0,1] neg_hi:[0,1]
	v_mul_f32_e32 v25, 0x38800000, v24
	v_cos_f32_e32 v24, v25
	v_sin_f32_e32 v25, v25
	s_nop 0
	s_nop 0
	v_add_f32_e32 v62, v24, v24
	v_pk_mul_f32 v[26:27], v[24:25], v[24:25]
	v_mul_f32_e32 v62, v25, v62
	s_nop 0
	s_nop 0
	v_mov_b32_e32 v108, v25
	v_pk_add_f32 v[26:27], v[26:27], v[26:27] op_sel:[0,1] op_sel_hi:[0,1] neg_lo:[0,1] neg_hi:[0,1]
	v_pk_mul_f32 v[72:73], v[24:25], v[62:63] op_sel:[1,0] op_sel_hi:[0,0] neg_lo:[1,0]
	v_pk_mul_f32 v[94:95], v[18:19], v[108:109] op_sel:[1,0] op_sel_hi:[0,0] neg_hi:[1,0]
	v_pk_add_f32 v[16:17], v[70:71], v[80:81]
	v_pk_fma_f32 v[72:73], v[24:25], v[26:27], v[72:73]
	v_pk_fma_f32 v[18:19], v[18:19], v[24:25], v[94:95] op_sel_hi:[1,0,1]
	v_pk_mul_f32 v[24:25], v[62:63], s[46:47] op_sel_hi:[0,1]
	v_pk_fma_f32 v[94:95], v[26:27], s[40:41], v[24:25]
	s_nop 0
	v_pk_mul_f32 v[24:25], v[16:17], v[94:95] op_sel:[1,1] op_sel_hi:[0,1] neg_hi:[1,0]
	v_pk_add_f32 v[64:65], v[112:113], v[114:115]
	v_pk_fma_f32 v[24:25], v[16:17], v[94:95], v[24:25] op_sel_hi:[1,0,1]
	v_pk_mul_f32 v[16:17], v[62:63], v[72:73] op_sel:[0,1] op_sel_hi:[0,0] neg_lo:[0,1]
	v_pk_fma_f32 v[108:109], v[26:27], v[72:73], v[16:17]
	v_pk_mul_f32 v[16:17], v[64:65], v[72:73] op_sel:[1,1] op_sel_hi:[0,1] neg_hi:[1,0]
	v_pk_add_f32 v[90:91], v[106:107], v[82:83]
	v_pk_fma_f32 v[16:17], v[64:65], v[72:73], v[16:17] op_sel_hi:[1,0,1]
	v_pk_mul_f32 v[64:65], v[62:63], v[94:95] op_sel:[0,1] op_sel_hi:[0,0] neg_lo:[0,1]
	v_pk_fma_f32 v[94:95], v[26:27], v[94:95], v[64:65]
	s_nop 0
	v_pk_mul_f32 v[64:65], v[78:79], v[94:95] op_sel:[1,1] op_sel_hi:[0,1] neg_hi:[1,0]
	v_pk_add_f32 v[66:67], v[6:7], v[118:119]
	v_pk_fma_f32 v[72:73], v[78:79], v[94:95], v[64:65] op_sel_hi:[1,0,1]
	v_pk_mul_f32 v[64:65], v[62:63], v[108:109] op_sel:[0,1] op_sel_hi:[0,0] neg_lo:[0,1]
	v_pk_fma_f32 v[110:111], v[26:27], v[108:109], v[64:65]
	v_pk_mul_f32 v[64:65], v[84:85], v[108:109] op_sel:[1,1] op_sel_hi:[0,1] neg_hi:[1,0]
	v_pk_mul_f32 v[78:79], v[62:63], v[94:95] op_sel:[0,1] op_sel_hi:[0,0] neg_lo:[0,1]
	v_pk_fma_f32 v[64:65], v[84:85], v[108:109], v[64:65] op_sel_hi:[1,0,1]
	v_pk_fma_f32 v[84:85], v[26:27], v[94:95], v[78:79]
	s_nop 0
	v_pk_mul_f32 v[78:79], v[90:91], v[84:85] op_sel:[1,1] op_sel_hi:[0,1] neg_hi:[1,0]
	v_pk_add_f32 v[68:69], v[106:107], v[82:83] neg_lo:[0,1] neg_hi:[0,1]
	v_pk_fma_f32 v[78:79], v[90:91], v[84:85], v[78:79] op_sel_hi:[1,0,1]
	v_pk_mul_f32 v[90:91], v[62:63], v[110:111] op_sel:[0,1] op_sel_hi:[0,0] neg_lo:[0,1]
	v_pk_fma_f32 v[94:95], v[26:27], v[110:111], v[90:91]
	v_pk_mul_f32 v[90:91], v[66:67], v[110:111] op_sel:[1,1] op_sel_hi:[0,1] neg_hi:[1,0]
	v_pk_add_f32 v[106:107], v[116:117], v[120:121]
	v_pk_fma_f32 v[66:67], v[66:67], v[110:111], v[90:91] op_sel_hi:[1,0,1]
	v_pk_mul_f32 v[90:91], v[62:63], v[84:85] op_sel:[0,1] op_sel_hi:[0,0] neg_lo:[0,1]
	v_pk_fma_f32 v[108:109], v[26:27], v[84:85], v[90:91]
	s_nop 0
	v_pk_mul_f32 v[84:85], v[122:123], v[108:109] op_sel:[1,1] op_sel_hi:[0,1] neg_hi:[1,0]
	v_pk_add_f32 v[80:81], v[70:71], v[80:81] neg_lo:[0,1] neg_hi:[0,1]
	v_pk_fma_f32 v[90:91], v[122:123], v[108:109], v[84:85] op_sel_hi:[1,0,1]
	v_pk_mul_f32 v[84:85], v[62:63], v[94:95] op_sel:[0,1] op_sel_hi:[0,0] neg_lo:[0,1]
	v_pk_fma_f32 v[110:111], v[26:27], v[94:95], v[84:85]
	v_pk_mul_f32 v[84:85], v[86:87], v[94:95] op_sel:[1,1] op_sel_hi:[0,1] neg_hi:[1,0]
	v_pk_add_f32 v[82:83], v[112:113], v[114:115] neg_lo:[0,1] neg_hi:[0,1]
	v_pk_fma_f32 v[84:85], v[86:87], v[94:95], v[84:85] op_sel_hi:[1,0,1]
	v_pk_mul_f32 v[86:87], v[62:63], v[108:109] op_sel:[0,1] op_sel_hi:[0,0] neg_lo:[0,1]
	v_pk_fma_f32 v[108:109], v[26:27], v[108:109], v[86:87]
	s_nop 0
	v_pk_mul_f32 v[86:87], v[102:103], v[108:109] op_sel:[1,1] op_sel_hi:[0,1] neg_hi:[1,0]
	v_pk_add_f32 v[70:71], v[6:7], v[118:119] neg_lo:[0,1] neg_hi:[0,1]
	v_pk_fma_f32 v[94:95], v[102:103], v[108:109], v[86:87] op_sel_hi:[1,0,1]
	v_pk_mul_f32 v[86:87], v[62:63], v[110:111] op_sel:[0,1] op_sel_hi:[0,0] neg_lo:[0,1]
	v_pk_fma_f32 v[102:103], v[26:27], v[110:111], v[86:87]
	v_pk_mul_f32 v[86:87], v[104:105], v[110:111] op_sel:[1,1] op_sel_hi:[0,1] neg_hi:[1,0]
	v_pk_add_f32 v[6:7], v[116:117], v[120:121] neg_lo:[0,1] neg_hi:[0,1]
	v_pk_fma_f32 v[86:87], v[104:105], v[110:111], v[86:87] op_sel_hi:[1,0,1]
	v_pk_mul_f32 v[104:105], v[62:63], v[108:109] op_sel:[0,1] op_sel_hi:[0,0] neg_lo:[0,1]
	v_pk_fma_f32 v[104:105], v[26:27], v[108:109], v[104:105]
	s_nop 0
	v_pk_mul_f32 v[108:109], v[96:97], v[104:105] op_sel:[1,1] op_sel_hi:[0,1] neg_hi:[1,0]
	s_nop 0
	v_pk_fma_f32 v[96:97], v[96:97], v[104:105], v[108:109] op_sel_hi:[1,0,1]
	v_pk_mul_f32 v[108:109], v[62:63], v[102:103] op_sel:[0,1] op_sel_hi:[0,0] neg_lo:[0,1]
	v_pk_mul_f32 v[110:111], v[100:101], v[102:103] op_sel:[1,1] op_sel_hi:[0,1] neg_hi:[1,0]
	v_pk_fma_f32 v[108:109], v[26:27], v[102:103], v[108:109]
	v_pk_fma_f32 v[100:101], v[100:101], v[102:103], v[110:111] op_sel_hi:[1,0,1]
	v_pk_mul_f32 v[102:103], v[62:63], v[104:105] op_sel:[0,1] op_sel_hi:[0,0] neg_lo:[0,1]
	v_pk_fma_f32 v[102:103], v[26:27], v[104:105], v[102:103]
	s_nop 0
	v_pk_mul_f32 v[104:105], v[98:99], v[102:103] op_sel:[1,1] op_sel_hi:[0,1] neg_hi:[1,0]
	s_nop 0
	v_pk_fma_f32 v[98:99], v[98:99], v[102:103], v[104:105] op_sel_hi:[1,0,1]
	v_pk_mul_f32 v[104:105], v[62:63], v[108:109] op_sel:[0,1] op_sel_hi:[0,0] neg_lo:[0,1]
	v_pk_mul_f32 v[110:111], v[106:107], v[108:109] op_sel:[1,1] op_sel_hi:[0,1] neg_hi:[1,0]
	v_pk_fma_f32 v[104:105], v[26:27], v[108:109], v[104:105]
	v_pk_fma_f32 v[106:107], v[106:107], v[108:109], v[110:111] op_sel_hi:[1,0,1]
	v_pk_mul_f32 v[108:109], v[62:63], v[102:103] op_sel:[0,1] op_sel_hi:[0,0] neg_lo:[0,1]
	v_pk_fma_f32 v[102:103], v[26:27], v[102:103], v[108:109]
	s_nop 0
	v_pk_mul_f32 v[108:109], v[88:89], v[102:103] op_sel:[1,1] op_sel_hi:[0,1] neg_hi:[1,0]
	s_nop 0
	v_pk_fma_f32 v[88:89], v[88:89], v[102:103], v[108:109] op_sel_hi:[1,0,1]
	v_pk_mul_f32 v[108:109], v[62:63], v[104:105] op_sel:[0,1] op_sel_hi:[0,0] neg_lo:[0,1]
	v_pk_mul_f32 v[110:111], v[92:93], v[104:105] op_sel:[1,1] op_sel_hi:[0,1] neg_hi:[1,0]
	v_pk_fma_f32 v[108:109], v[26:27], v[104:105], v[108:109]
	v_pk_fma_f32 v[92:93], v[92:93], v[104:105], v[110:111] op_sel_hi:[1,0,1]
	v_pk_mul_f32 v[104:105], v[62:63], v[102:103] op_sel:[0,1] op_sel_hi:[0,0] neg_lo:[0,1]
	v_pk_fma_f32 v[102:103], v[26:27], v[102:103], v[104:105]
	s_nop 0
	v_pk_mul_f32 v[104:105], v[80:81], v[102:103] op_sel:[1,1] op_sel_hi:[0,1] neg_hi:[1,0]
	s_nop 0
	v_pk_fma_f32 v[80:81], v[80:81], v[102:103], v[104:105] op_sel_hi:[1,0,1]
	v_pk_mul_f32 v[104:105], v[62:63], v[108:109] op_sel:[0,1] op_sel_hi:[0,0] neg_lo:[0,1]
	v_pk_mul_f32 v[110:111], v[82:83], v[108:109] op_sel:[1,1] op_sel_hi:[0,1] neg_hi:[1,0]
	v_pk_fma_f32 v[104:105], v[26:27], v[108:109], v[104:105]
	v_pk_fma_f32 v[82:83], v[82:83], v[108:109], v[110:111] op_sel_hi:[1,0,1]
	v_pk_mul_f32 v[108:109], v[62:63], v[102:103] op_sel:[0,1] op_sel_hi:[0,0] neg_lo:[0,1]
	v_pk_fma_f32 v[102:103], v[26:27], v[102:103], v[108:109]
	s_nop 0
	v_pk_mul_f32 v[108:109], v[74:75], v[102:103] op_sel:[1,1] op_sel_hi:[0,1] neg_hi:[1,0]
	s_nop 0
	v_pk_fma_f32 v[74:75], v[74:75], v[102:103], v[108:109] op_sel_hi:[1,0,1]
	v_pk_mul_f32 v[108:109], v[62:63], v[104:105] op_sel:[0,1] op_sel_hi:[0,0] neg_lo:[0,1]
	v_pk_mul_f32 v[110:111], v[76:77], v[104:105] op_sel:[1,1] op_sel_hi:[0,1] neg_hi:[1,0]
	v_pk_fma_f32 v[108:109], v[26:27], v[104:105], v[108:109]
	v_pk_fma_f32 v[76:77], v[76:77], v[104:105], v[110:111] op_sel_hi:[1,0,1]
	v_pk_mul_f32 v[104:105], v[62:63], v[102:103] op_sel:[0,1] op_sel_hi:[0,0] neg_lo:[0,1]
	v_pk_fma_f32 v[102:103], v[26:27], v[102:103], v[104:105]
	s_nop 0
	v_pk_mul_f32 v[104:105], v[68:69], v[102:103] op_sel:[1,1] op_sel_hi:[0,1] neg_hi:[1,0]
	s_nop 0
	v_pk_fma_f32 v[68:69], v[68:69], v[102:103], v[104:105] op_sel_hi:[1,0,1]
	v_pk_mul_f32 v[104:105], v[62:63], v[108:109] op_sel:[0,1] op_sel_hi:[0,0] neg_lo:[0,1]
	v_pk_mul_f32 v[110:111], v[70:71], v[108:109] op_sel:[1,1] op_sel_hi:[0,1] neg_hi:[1,0]
	v_pk_fma_f32 v[104:105], v[26:27], v[108:109], v[104:105]
	v_pk_fma_f32 v[70:71], v[70:71], v[108:109], v[110:111] op_sel_hi:[1,0,1]
	v_pk_mul_f32 v[108:109], v[62:63], v[102:103] op_sel:[0,1] op_sel_hi:[0,0] neg_lo:[0,1]
	v_pk_fma_f32 v[102:103], v[26:27], v[102:103], v[108:109]
	s_nop 0
	v_pk_mul_f32 v[108:109], v[20:21], v[102:103] op_sel:[1,1] op_sel_hi:[0,1] neg_hi:[1,0]
	s_nop 0
	v_pk_fma_f32 v[20:21], v[20:21], v[102:103], v[108:109] op_sel_hi:[1,0,1]
	v_pk_mul_f32 v[108:109], v[62:63], v[104:105] op_sel:[0,1] op_sel_hi:[0,0] neg_lo:[0,1]
	v_pk_mul_f32 v[110:111], v[22:23], v[104:105] op_sel:[1,1] op_sel_hi:[0,1] neg_hi:[1,0]
	v_pk_fma_f32 v[108:109], v[26:27], v[104:105], v[108:109]
	v_pk_fma_f32 v[22:23], v[22:23], v[104:105], v[110:111] op_sel_hi:[1,0,1]
	v_pk_mul_f32 v[104:105], v[62:63], v[102:103] op_sel:[0,1] op_sel_hi:[0,0] neg_lo:[0,1]
	v_pk_fma_f32 v[102:103], v[26:27], v[102:103], v[104:105]
	s_nop 0
	v_pk_mul_f32 v[104:105], v[12:13], v[102:103] op_sel:[1,1] op_sel_hi:[0,1] neg_hi:[1,0]
	s_nop 0
	v_pk_fma_f32 v[12:13], v[12:13], v[102:103], v[104:105] op_sel_hi:[1,0,1]
	v_pk_mul_f32 v[104:105], v[62:63], v[108:109] op_sel:[0,1] op_sel_hi:[0,0] neg_lo:[0,1]
	v_pk_mul_f32 v[110:111], v[14:15], v[108:109] op_sel:[1,1] op_sel_hi:[0,1] neg_hi:[1,0]
	v_pk_fma_f32 v[104:105], v[26:27], v[108:109], v[104:105]
	v_pk_fma_f32 v[14:15], v[14:15], v[108:109], v[110:111] op_sel_hi:[1,0,1]
	v_pk_mul_f32 v[108:109], v[62:63], v[102:103] op_sel:[0,1] op_sel_hi:[0,0] neg_lo:[0,1]
	v_pk_fma_f32 v[102:103], v[26:27], v[102:103], v[108:109]
	s_nop 0
	v_pk_mul_f32 v[108:109], v[8:9], v[102:103] op_sel:[1,1] op_sel_hi:[0,1] neg_hi:[1,0]
	s_nop 0
	v_pk_fma_f32 v[8:9], v[8:9], v[102:103], v[108:109] op_sel_hi:[1,0,1]
	v_pk_mul_f32 v[108:109], v[62:63], v[104:105] op_sel:[0,1] op_sel_hi:[0,0] neg_lo:[0,1]
	v_pk_mul_f32 v[110:111], v[10:11], v[104:105] op_sel:[1,1] op_sel_hi:[0,1] neg_hi:[1,0]
	v_pk_fma_f32 v[108:109], v[26:27], v[104:105], v[108:109]
	v_pk_fma_f32 v[10:11], v[10:11], v[104:105], v[110:111] op_sel_hi:[1,0,1]
	v_pk_mul_f32 v[104:105], v[62:63], v[102:103] op_sel:[0,1] op_sel_hi:[0,0] neg_lo:[0,1]
	v_pk_fma_f32 v[26:27], v[26:27], v[102:103], v[104:105]
	s_nop 0
	v_pk_mul_f32 v[102:103], v[4:5], v[26:27] op_sel:[1,1] op_sel_hi:[0,1] neg_hi:[1,0]
	s_add_i32 s1, 16, 0x1e000
	v_pk_fma_f32 v[4:5], v[4:5], v[26:27], v[102:103] op_sel_hi:[1,0,1]
	s_nop 0
	s_nop 0
	v_pk_mul_f32 v[26:27], v[6:7], v[108:109] op_sel:[1,1] op_sel_hi:[0,1] neg_hi:[1,0]
	s_add_i32 s0, 16, 0x1f000
	v_pk_fma_f32 v[6:7], v[6:7], v[108:109], v[26:27] op_sel_hi:[1,0,1]
	v_lshrrev_b32_e32 v26, 5, v63
	v_bitop3_b32 v26, v26, v63, 15 bitop3:0x6c
	v_lshlrev_b32_e32 v26, 3, v26
	v_bfe_u32 v27, v63, 5, 4
	v_add_u32_e32 v62, 16, v26
	ds_write_b64 v62, v[2:3]
	v_bitop3_b32 v2, v27, v63, 16 bitop3:0x36
	v_lshlrev_b32_e32 v2, 3, v2
	v_add_u32_e32 v3, 16, v2
	ds_write_b64 v3, v[88:89] offset:4096
	ds_write_b64 v62, v[90:91] offset:8192
	ds_write_b64 v3, v[20:21] offset:12288
	ds_write_b64 v62, v[72:73] offset:16384
	ds_write_b64 v3, v[74:75] offset:20480
	ds_write_b64 v62, v[96:97] offset:24576
	ds_write_b64 v3, v[8:9] offset:28672
	ds_write_b64 v62, v[24:25] offset:32768
	ds_write_b64 v3, v[80:81] offset:36864
	ds_write_b64 v62, v[94:95] offset:40960
	ds_write_b64 v3, v[12:13] offset:45056
	ds_write_b64 v62, v[78:79] offset:49152
	ds_write_b64 v3, v[68:69] offset:53248
	ds_write_b64 v62, v[98:99] offset:57344
	ds_write_b64 v3, v[4:5] offset:61440
	v_add_u32_e32 v3, s79, v26
	ds_write_b64 v3, v[18:19]
	v_add_u32_e32 v3, s19, v2
	ds_write_b64 v3, v[92:93]
	v_add_u32_e32 v3, s18, v26
	ds_write_b64 v3, v[84:85]
	v_add_u32_e32 v3, s17, v2
	ds_write_b64 v3, v[22:23]
	v_add_u32_e32 v3, s13, v26
	ds_write_b64 v3, v[64:65]
	v_add_u32_e32 v3, s12, v2
	ds_write_b64 v3, v[76:77]
	v_add_u32_e32 v3, s11, v26
	ds_write_b64 v3, v[100:101]
	v_add_u32_e32 v3, s10, v2
	ds_write_b64 v3, v[10:11]
	v_add_u32_e32 v3, s9, v26
	ds_write_b64 v3, v[16:17]
	v_add_u32_e32 v3, s8, v2
	ds_write_b64 v3, v[82:83]
	v_add_u32_e32 v3, s7, v26
	ds_write_b64 v3, v[86:87]
	v_add_u32_e32 v3, s6, v2
	ds_write_b64 v3, v[14:15]
	v_add_u32_e32 v3, s5, v26
	ds_write_b64 v3, v[66:67]
	v_add_u32_e32 v3, s4, v2
	ds_write_b64 v3, v[70:71]
	v_add_u32_e32 v3, s1, v26
	v_add_u32_e32 v2, s0, v2
	v_mov_b32_e32 v21, v146
	ds_write_b64 v3, v[106:107]
	ds_write_b64 v2, v[6:7]
	s_waitcnt lgkmcnt(0)
	s_barrier
	s_lshl_b32 s42, s16, 14
	v_lshlrev_b32_e32 v2, 5, v21
	v_and_b32_e32 v4, 0xfffffe00, v2
	v_and_b32_e32 v20, 15, v21
	v_and_or_b32 v2, v21, 16, v4
	v_bitop3_b32 v4, v4, 16, v21 bitop3:0x34
	v_bitop3_b32 v72, v21, 8, 15 bitop3:0x6c
	v_lshl_add_u32 v26, v2, 3, 16
	v_lshlrev_b32_e32 v5, 3, v20
	v_lshl_add_u32 v126, v4, 3, 16
	v_lshlrev_b32_e32 v74, 3, v72
	v_add_u32_e32 v27, v26, v5
	v_add_u32_e32 v96, v126, v5
	v_add_u32_e32 v111, v26, v74
	v_add_u32_e32 v112, v126, v74
	ds_read_b64 v[2:3], v27
	ds_read_b64 v[4:5], v96
	v_bitop3_b32 v6, v21, 1, 15 bitop3:0x6c
	ds_read_b64 v[72:73], v111 offset:2048
	ds_read_b64 v[74:75], v112 offset:2048
	v_bitop3_b32 v76, v21, 9, 15 bitop3:0x6c
	v_lshlrev_b32_e32 v8, 3, v6
	v_lshlrev_b32_e32 v78, 3, v76
	v_add_u32_e32 v97, v26, v8
	v_add_u32_e32 v113, v26, v78
	ds_read_b64 v[6:7], v97 offset:256
	ds_read_b64 v[76:77], v113 offset:2304
	v_add_u32_e32 v98, v126, v8
	v_add_u32_e32 v114, v126, v78
	ds_read_b64 v[8:9], v98 offset:256
	ds_read_b64 v[78:79], v114 offset:2304
	s_waitcnt lgkmcnt(5)
	v_pk_add_f32 v[136:137], v[2:3], v[72:73]
	v_pk_add_f32 v[2:3], v[2:3], v[72:73] neg_lo:[0,1] neg_hi:[0,1]
	s_waitcnt lgkmcnt(4)
	v_pk_add_f32 v[72:73], v[4:5], v[74:75]
	v_pk_add_f32 v[4:5], v[4:5], v[74:75] neg_lo:[0,1] neg_hi:[0,1]
	v_bitop3_b32 v10, v21, 2, 15 bitop3:0x6c
	v_bitop3_b32 v80, v21, 10, 15 bitop3:0x6c
	v_lshlrev_b32_e32 v12, 3, v10
	v_lshlrev_b32_e32 v82, 3, v80
	v_pk_mul_f32 v[74:75], v[4:5], s[48:49] op_sel:[1,0] op_sel_hi:[0,0] neg_hi:[1,0]
	v_add_u32_e32 v99, v26, v12
	v_add_u32_e32 v115, v26, v82
	v_pk_fma_f32 v[4:5], v[4:5], s[44:45], v[74:75] op_sel_hi:[1,0,1]
	s_waitcnt lgkmcnt(2)
	v_pk_add_f32 v[74:75], v[6:7], v[76:77]
	v_pk_add_f32 v[6:7], v[6:7], v[76:77] neg_lo:[0,1] neg_hi:[0,1]
	ds_read_b64 v[10:11], v99 offset:512
	ds_read_b64 v[80:81], v115 offset:2560
	v_pk_mul_f32 v[76:77], v[6:7], s[54:55] op_sel:[1,0] op_sel_hi:[0,0] neg_hi:[1,0]
	v_add_u32_e32 v100, v126, v12
	v_bitop3_b32 v14, v21, 3, 15 bitop3:0x6c
	v_add_u32_e32 v116, v126, v82
	v_bitop3_b32 v84, v21, 11, 15 bitop3:0x6c
	v_pk_fma_f32 v[6:7], v[6:7], s[52:53], v[76:77] op_sel_hi:[1,0,1]
	s_waitcnt lgkmcnt(2)
	v_pk_add_f32 v[76:77], v[8:9], v[78:79]
	v_pk_add_f32 v[8:9], v[8:9], v[78:79] neg_lo:[0,1] neg_hi:[0,1]
	ds_read_b64 v[12:13], v100 offset:512
	v_lshlrev_b32_e32 v16, 3, v14
	ds_read_b64 v[82:83], v116 offset:2560
	v_lshlrev_b32_e32 v86, 3, v84
	v_add_u32_e32 v101, v26, v16
	v_add_u32_e32 v102, v126, v16
	v_add_u32_e32 v117, v26, v86
	v_add_u32_e32 v118, v126, v86
	v_pk_mul_f32 v[78:79], v[8:9], s[58:59] op_sel:[1,0] op_sel_hi:[0,0] neg_hi:[1,0]
	ds_read_b64 v[14:15], v101 offset:768
	ds_read_b64 v[16:17], v102 offset:768
	ds_read_b64 v[84:85], v117 offset:2816
	ds_read_b64 v[86:87], v118 offset:2816
	v_pk_fma_f32 v[8:9], v[8:9], s[56:57], v[78:79] op_sel_hi:[1,0,1]
	s_waitcnt lgkmcnt(6)
	v_pk_add_f32 v[78:79], v[10:11], v[80:81]
	v_pk_add_f32 v[10:11], v[10:11], v[80:81] neg_lo:[0,1] neg_hi:[0,1]
	v_bitop3_b32 v18, v21, 4, 15 bitop3:0x6c
	v_pk_mul_f32 v[80:81], v[10:11], s[60:61] op_sel:[1,0] op_sel_hi:[0,0] neg_hi:[1,0]
	v_bitop3_b32 v88, v21, 12, 15 bitop3:0x6c
	v_pk_fma_f32 v[10:11], v[10:11], s[60:61], v[80:81] op_sel_hi:[1,0,1]
	s_waitcnt lgkmcnt(4)
	v_pk_add_f32 v[80:81], v[12:13], v[82:83]
	v_pk_add_f32 v[12:13], v[12:13], v[82:83] neg_lo:[0,1] neg_hi:[0,1]
	v_lshlrev_b32_e32 v22, 3, v18
	v_lshlrev_b32_e32 v90, 3, v88
	v_pk_mul_f32 v[82:83], v[12:13], s[56:57] op_sel:[1,0] op_sel_hi:[0,0] neg_hi:[1,0]
	v_add_u32_e32 v103, v26, v22
	v_add_u32_e32 v119, v26, v90
	v_pk_fma_f32 v[12:13], v[12:13], s[58:59], v[82:83] op_sel_hi:[1,0,1]
	s_waitcnt lgkmcnt(1)
	v_pk_add_f32 v[82:83], v[14:15], v[84:85]
	v_pk_add_f32 v[14:15], v[14:15], v[84:85] neg_lo:[0,1] neg_hi:[0,1]
	ds_read_b64 v[18:19], v103 offset:1024
	v_add_u32_e32 v104, v126, v22
	v_bitop3_b32 v24, v21, 5, 15 bitop3:0x6c
	ds_read_b64 v[88:89], v119 offset:3072
	v_add_u32_e32 v120, v126, v90
	v_bitop3_b32 v92, v21, 13, 15 bitop3:0x6c
	ds_read_b64 v[22:23], v104 offset:1024
	v_lshlrev_b32_e32 v62, 3, v24
	ds_read_b64 v[90:91], v120 offset:3072
	v_lshlrev_b32_e32 v94, 3, v92
	v_pk_mul_f32 v[84:85], v[14:15], s[52:53] op_sel:[1,0] op_sel_hi:[0,0] neg_hi:[1,0]
	v_add_u32_e32 v105, v26, v62
	v_add_u32_e32 v121, v26, v94
	v_pk_fma_f32 v[14:15], v[14:15], s[54:55], v[84:85] op_sel_hi:[1,0,1]
	s_waitcnt lgkmcnt(4)
	v_pk_add_f32 v[84:85], v[16:17], v[86:87]
	v_pk_add_f32 v[16:17], v[16:17], v[86:87] neg_lo:[0,1] neg_hi:[0,1]
	ds_read_b64 v[24:25], v105 offset:1280
	ds_read_b64 v[92:93], v121 offset:3328
	v_add_u32_e32 v106, v126, v62
	v_bitop3_b32 v64, v21, 6, 15 bitop3:0x6c
	v_add_u32_e32 v122, v126, v94
	v_bitop3_b32 v123, v21, 14, 15 bitop3:0x6c
	v_pk_mul_f32 v[86:87], v[16:17], s[44:45] op_sel:[1,0] op_sel_hi:[0,0] neg_hi:[1,0]
	ds_read_b64 v[62:63], v106 offset:1280
	v_lshlrev_b32_e32 v66, 3, v64
	ds_read_b64 v[94:95], v122 offset:3328
	v_lshlrev_b32_e32 v124, 3, v123
	v_pk_fma_f32 v[16:17], v[16:17], s[48:49], v[86:87] op_sel_hi:[1,0,1]
	s_waitcnt lgkmcnt(6)
	v_pk_add_f32 v[86:87], v[18:19], v[88:89]
	v_pk_add_f32 v[18:19], v[18:19], v[88:89] neg_lo:[0,1] neg_hi:[0,1]
	v_add_u32_e32 v107, v26, v66
	v_add_u32_e32 v123, v26, v124
	v_xor_b32_e32 v89, 0x80000000, v18
	v_mov_b32_e32 v88, v19
	s_waitcnt lgkmcnt(4)
	v_pk_add_f32 v[18:19], v[22:23], v[90:91]
	v_pk_add_f32 v[22:23], v[22:23], v[90:91] neg_lo:[0,1] neg_hi:[0,1]
	ds_read_b64 v[64:65], v107 offset:1536
	ds_read_b64 v[128:129], v123 offset:3584
	v_pk_mul_f32 v[90:91], v[22:23], s[48:49] op_sel_hi:[1,0]
	v_xor_b32_e32 v139, 0x80000000, v22
	v_mov_b32_e32 v138, v23
	v_add_u32_e32 v108, v126, v66
	v_bitop3_b32 v68, v21, 7, 15 bitop3:0x6c
	v_add_u32_e32 v124, v126, v124
	v_bitop3_b32 v21, v21, 15, v21 bitop3:0xc
	v_pk_fma_f32 v[22:23], v[138:139], s[44:45], v[90:91] op_sel_hi:[1,0,1] neg_lo:[0,0,1] neg_hi:[0,0,1]
	s_waitcnt lgkmcnt(4)
	v_pk_add_f32 v[90:91], v[24:25], v[92:93]
	v_pk_add_f32 v[24:25], v[24:25], v[92:93] neg_lo:[0,1] neg_hi:[0,1]
	ds_read_b64 v[66:67], v108 offset:1536
	v_lshlrev_b32_e32 v70, 3, v68
	ds_read_b64 v[130:131], v124 offset:3584
	v_lshlrev_b32_e32 v21, 3, v21
	v_pk_mul_f32 v[92:93], v[24:25], s[54:55] op_sel_hi:[1,0]
	v_xor_b32_e32 v139, 0x80000000, v24
	v_mov_b32_e32 v138, v25
	v_add_u32_e32 v109, v26, v70
	v_add_u32_e32 v125, v26, v21
	v_pk_fma_f32 v[24:25], v[138:139], s[52:53], v[92:93] op_sel_hi:[1,0,1] neg_lo:[0,0,1] neg_hi:[0,0,1]
	s_waitcnt lgkmcnt(4)
	v_pk_add_f32 v[92:93], v[62:63], v[94:95]
	v_pk_add_f32 v[62:63], v[62:63], v[94:95] neg_lo:[0,1] neg_hi:[0,1]
	ds_read_b64 v[68:69], v109 offset:1792
	v_add_u32_e32 v110, v126, v70
	ds_read_b64 v[132:133], v125 offset:3840
	v_add_u32_e32 v126, v126, v21
	v_pk_mul_f32 v[94:95], v[62:63], s[58:59] op_sel_hi:[1,0]
	v_xor_b32_e32 v139, 0x80000000, v62
	v_mov_b32_e32 v138, v63
	ds_read_b64 v[70:71], v110 offset:1792
	ds_read_b64 v[134:135], v126 offset:3840
	v_pk_fma_f32 v[62:63], v[138:139], s[56:57], v[94:95] op_sel_hi:[1,0,1] neg_lo:[0,0,1] neg_hi:[0,0,1]
	s_waitcnt lgkmcnt(6)
	v_pk_add_f32 v[94:95], v[64:65], v[128:129]
	v_pk_add_f32 v[64:65], v[64:65], v[128:129] neg_lo:[0,1] neg_hi:[0,1]
	v_lshl_add_u64 v[0:1], s[42:43], 2, v[28:29]
	v_pk_mul_f32 v[128:129], v[64:65], s[60:61] op_sel_hi:[1,0]
	v_xor_b32_e32 v139, 0x80000000, v64
	v_mov_b32_e32 v138, v65
	v_pk_fma_f32 v[64:65], v[138:139], s[60:61], v[128:129] op_sel_hi:[1,0,1] neg_lo:[0,0,1] neg_hi:[0,0,1]
	s_waitcnt lgkmcnt(4)
	v_pk_add_f32 v[128:129], v[66:67], v[130:131]
	v_pk_add_f32 v[66:67], v[66:67], v[130:131] neg_lo:[0,1] neg_hi:[0,1]
	v_cvt_f32_i32_e32 v20, v20
	v_pk_mul_f32 v[130:131], v[66:67], s[56:57] op_sel_hi:[1,0]
	v_xor_b32_e32 v139, 0x80000000, v66
	v_mov_b32_e32 v138, v67
	v_pk_fma_f32 v[66:67], v[138:139], s[58:59], v[130:131] op_sel_hi:[1,0,1] neg_lo:[0,0,1] neg_hi:[0,0,1]
	s_waitcnt lgkmcnt(2)
	v_pk_add_f32 v[130:131], v[68:69], v[132:133]
	v_pk_add_f32 v[68:69], v[68:69], v[132:133] neg_lo:[0,1] neg_hi:[0,1]
	v_mul_f32_e32 v21, 0x3b000000, v20
	v_pk_mul_f32 v[132:133], v[68:69], s[52:53] op_sel_hi:[1,0]
	v_xor_b32_e32 v139, 0x80000000, v68
	v_mov_b32_e32 v138, v69
	v_pk_fma_f32 v[68:69], v[138:139], s[54:55], v[132:133] op_sel_hi:[1,0,1] neg_lo:[0,0,1] neg_hi:[0,0,1]
	s_waitcnt lgkmcnt(0)
	v_pk_add_f32 v[132:133], v[70:71], v[134:135]
	v_pk_add_f32 v[70:71], v[70:71], v[134:135] neg_lo:[0,1] neg_hi:[0,1]
	v_cos_f32_e32 v20, v21
	v_pk_mul_f32 v[134:135], v[70:71], s[44:45] op_sel_hi:[1,0]
	v_xor_b32_e32 v139, 0x80000000, v70
	v_mov_b32_e32 v138, v71
	v_pk_fma_f32 v[70:71], v[138:139], s[48:49], v[134:135] op_sel_hi:[1,0,1] neg_lo:[0,0,1] neg_hi:[0,0,1]
	v_pk_add_f32 v[134:135], v[136:137], v[86:87]
	v_pk_add_f32 v[86:87], v[136:137], v[86:87] neg_lo:[0,1] neg_hi:[0,1]
	v_pk_add_f32 v[136:137], v[72:73], v[18:19]
	v_pk_add_f32 v[18:19], v[72:73], v[18:19] neg_lo:[0,1] neg_hi:[0,1]
	v_sin_f32_e32 v21, v21
	s_nop 0
	s_nop 0
	v_pk_mul_f32 v[72:73], v[18:19], s[54:55] op_sel:[1,0] op_sel_hi:[0,0] neg_hi:[1,0]
	v_add_f32_e32 v26, v20, v20
	v_pk_fma_f32 v[18:19], v[18:19], s[52:53], v[72:73] op_sel_hi:[1,0,1]
	v_pk_add_f32 v[72:73], v[74:75], v[90:91]
	v_pk_add_f32 v[74:75], v[74:75], v[90:91] neg_lo:[0,1] neg_hi:[0,1]
	v_mul_f32_e32 v26, v21, v26
	s_nop 0
	s_nop 0
	v_pk_mul_f32 v[90:91], v[74:75], s[60:61] op_sel:[1,0] op_sel_hi:[0,0] neg_hi:[1,0]
	s_lshl_b32 s42, s16, 9
	v_pk_fma_f32 v[74:75], v[74:75], s[60:61], v[90:91] op_sel_hi:[1,0,1]
	v_pk_add_f32 v[90:91], v[76:77], v[92:93]
	v_pk_add_f32 v[76:77], v[76:77], v[92:93] neg_lo:[0,1] neg_hi:[0,1]
	s_mov_b64 s[74:75], -1
	s_nop 0
	s_nop 0
	v_pk_mul_f32 v[92:93], v[76:77], s[52:53] op_sel:[1,0] op_sel_hi:[0,0] neg_hi:[1,0]
	s_nop 0
	v_pk_fma_f32 v[76:77], v[76:77], s[54:55], v[92:93] op_sel_hi:[1,0,1]
	v_pk_add_f32 v[92:93], v[78:79], v[94:95]
	v_pk_add_f32 v[78:79], v[78:79], v[94:95] neg_lo:[0,1] neg_hi:[0,1]
	s_nop 0
	v_xor_b32_e32 v95, 0x80000000, v78
	v_mov_b32_e32 v94, v79
	v_pk_add_f32 v[78:79], v[80:81], v[128:129]
	v_pk_add_f32 v[80:81], v[80:81], v[128:129] neg_lo:[0,1] neg_hi:[0,1]
	s_nop 0
	v_pk_mul_f32 v[128:129], v[80:81], s[54:55] op_sel_hi:[1,0]
	v_xor_b32_e32 v139, 0x80000000, v80
	v_mov_b32_e32 v138, v81
	v_pk_fma_f32 v[80:81], v[138:139], s[52:53], v[128:129] op_sel_hi:[1,0,1] neg_lo:[0,0,1] neg_hi:[0,0,1]
	v_pk_add_f32 v[128:129], v[82:83], v[130:131]
	v_pk_add_f32 v[82:83], v[82:83], v[130:131] neg_lo:[0,1] neg_hi:[0,1]
	s_nop 0
	v_pk_mul_f32 v[130:131], v[82:83], s[60:61] op_sel_hi:[1,0]
	v_xor_b32_e32 v139, 0x80000000, v82
	v_mov_b32_e32 v138, v83
	v_pk_fma_f32 v[82:83], v[138:139], s[60:61], v[130:131] op_sel_hi:[1,0,1] neg_lo:[0,0,1] neg_hi:[0,0,1]
	v_pk_add_f32 v[130:131], v[84:85], v[132:133]
	v_pk_add_f32 v[84:85], v[84:85], v[132:133] neg_lo:[0,1] neg_hi:[0,1]
	s_nop 0
	v_pk_mul_f32 v[132:133], v[84:85], s[52:53] op_sel_hi:[1,0]
	v_xor_b32_e32 v139, 0x80000000, v84
	v_mov_b32_e32 v138, v85
	v_pk_fma_f32 v[84:85], v[138:139], s[54:55], v[132:133] op_sel_hi:[1,0,1] neg_lo:[0,0,1] neg_hi:[0,0,1]
	v_pk_add_f32 v[132:133], v[2:3], v[88:89]
	v_pk_add_f32 v[2:3], v[2:3], v[88:89] neg_lo:[0,1] neg_hi:[0,1]
	v_pk_add_f32 v[88:89], v[4:5], v[22:23]
	v_pk_add_f32 v[4:5], v[4:5], v[22:23] neg_lo:[0,1] neg_hi:[0,1]
	s_nop 0
	v_pk_mul_f32 v[22:23], v[4:5], s[54:55] op_sel:[1,0] op_sel_hi:[0,0] neg_hi:[1,0]
	s_nop 0
	v_pk_fma_f32 v[4:5], v[4:5], s[52:53], v[22:23] op_sel_hi:[1,0,1]
	v_pk_add_f32 v[22:23], v[6:7], v[24:25]
	v_pk_add_f32 v[6:7], v[6:7], v[24:25] neg_lo:[0,1] neg_hi:[0,1]
	s_nop 0
	v_pk_mul_f32 v[24:25], v[6:7], s[60:61] op_sel:[1,0] op_sel_hi:[0,0] neg_hi:[1,0]
	s_nop 0
	v_pk_fma_f32 v[6:7], v[6:7], s[60:61], v[24:25] op_sel_hi:[1,0,1]
	v_pk_add_f32 v[24:25], v[8:9], v[62:63]
	v_pk_add_f32 v[8:9], v[8:9], v[62:63] neg_lo:[0,1] neg_hi:[0,1]
	s_nop 0
	v_pk_mul_f32 v[62:63], v[8:9], s[52:53] op_sel:[1,0] op_sel_hi:[0,0] neg_hi:[1,0]
	s_nop 0
	v_pk_fma_f32 v[8:9], v[8:9], s[54:55], v[62:63] op_sel_hi:[1,0,1]
	v_pk_add_f32 v[62:63], v[10:11], v[64:65]
	v_pk_add_f32 v[10:11], v[10:11], v[64:65] neg_lo:[0,1] neg_hi:[0,1]
	s_nop 0
	v_xor_b32_e32 v65, 0x80000000, v10
	v_mov_b32_e32 v64, v11
	v_pk_add_f32 v[10:11], v[12:13], v[66:67]
	v_pk_add_f32 v[12:13], v[12:13], v[66:67] neg_lo:[0,1] neg_hi:[0,1]
	s_nop 0
	v_pk_mul_f32 v[66:67], v[12:13], s[54:55] op_sel_hi:[1,0]
	v_xor_b32_e32 v139, 0x80000000, v12
	v_mov_b32_e32 v138, v13
	v_pk_fma_f32 v[12:13], v[138:139], s[52:53], v[66:67] op_sel_hi:[1,0,1] neg_lo:[0,0,1] neg_hi:[0,0,1]
	v_pk_add_f32 v[66:67], v[14:15], v[68:69]
	v_pk_add_f32 v[14:15], v[14:15], v[68:69] neg_lo:[0,1] neg_hi:[0,1]
	s_nop 0
	v_pk_mul_f32 v[68:69], v[14:15], s[60:61] op_sel_hi:[1,0]
	v_xor_b32_e32 v139, 0x80000000, v14
	v_mov_b32_e32 v138, v15
	v_pk_fma_f32 v[14:15], v[138:139], s[60:61], v[68:69] op_sel_hi:[1,0,1] neg_lo:[0,0,1] neg_hi:[0,0,1]
	v_pk_add_f32 v[68:69], v[16:17], v[70:71]
	v_pk_add_f32 v[16:17], v[16:17], v[70:71] neg_lo:[0,1] neg_hi:[0,1]
	s_nop 0
	v_pk_mul_f32 v[70:71], v[16:17], s[52:53] op_sel_hi:[1,0]
	v_xor_b32_e32 v139, 0x80000000, v16
	v_mov_b32_e32 v138, v17
	v_pk_fma_f32 v[16:17], v[138:139], s[54:55], v[70:71] op_sel_hi:[1,0,1] neg_lo:[0,0,1] neg_hi:[0,0,1]
	v_pk_add_f32 v[70:71], v[134:135], v[92:93]
	v_pk_add_f32 v[92:93], v[134:135], v[92:93] neg_lo:[0,1] neg_hi:[0,1]
	v_pk_add_f32 v[134:135], v[136:137], v[78:79]
	v_pk_add_f32 v[78:79], v[136:137], v[78:79] neg_lo:[0,1] neg_hi:[0,1]
	s_nop 0
	v_pk_mul_f32 v[136:137], v[78:79], s[60:61] op_sel:[1,0] op_sel_hi:[0,0] neg_hi:[1,0]
	s_nop 0
	v_pk_fma_f32 v[78:79], v[78:79], s[60:61], v[136:137] op_sel_hi:[1,0,1]
	v_pk_add_f32 v[136:137], v[72:73], v[128:129]
	v_pk_add_f32 v[72:73], v[72:73], v[128:129] neg_lo:[0,1] neg_hi:[0,1]
	s_nop 0
	v_xor_b32_e32 v129, 0x80000000, v72
	v_mov_b32_e32 v128, v73
	v_pk_add_f32 v[72:73], v[90:91], v[130:131]
	v_pk_add_f32 v[90:91], v[90:91], v[130:131] neg_lo:[0,1] neg_hi:[0,1]
	s_nop 0
	v_pk_mul_f32 v[130:131], v[90:91], s[60:61] op_sel_hi:[1,0]
	v_xor_b32_e32 v139, 0x80000000, v90
	v_mov_b32_e32 v138, v91
	v_pk_fma_f32 v[90:91], v[138:139], s[60:61], v[130:131] op_sel_hi:[1,0,1] neg_lo:[0,0,1] neg_hi:[0,0,1]
	v_pk_add_f32 v[130:131], v[86:87], v[94:95]
	v_pk_add_f32 v[86:87], v[86:87], v[94:95] neg_lo:[0,1] neg_hi:[0,1]
	v_pk_add_f32 v[94:95], v[18:19], v[80:81]
	v_pk_add_f32 v[18:19], v[18:19], v[80:81] neg_lo:[0,1] neg_hi:[0,1]
	s_nop 0
	v_pk_mul_f32 v[80:81], v[18:19], s[60:61] op_sel:[1,0] op_sel_hi:[0,0] neg_hi:[1,0]
	s_nop 0
	v_pk_fma_f32 v[18:19], v[18:19], s[60:61], v[80:81] op_sel_hi:[1,0,1]
	v_pk_add_f32 v[80:81], v[74:75], v[82:83]
	v_pk_add_f32 v[74:75], v[74:75], v[82:83] neg_lo:[0,1] neg_hi:[0,1]
	s_nop 0
	v_xor_b32_e32 v83, 0x80000000, v74
	v_mov_b32_e32 v82, v75
	v_pk_add_f32 v[74:75], v[76:77], v[84:85]
	v_pk_add_f32 v[76:77], v[76:77], v[84:85] neg_lo:[0,1] neg_hi:[0,1]
	s_nop 0
	v_pk_mul_f32 v[84:85], v[76:77], s[60:61] op_sel_hi:[1,0]
	v_xor_b32_e32 v139, 0x80000000, v76
	v_mov_b32_e32 v138, v77
	v_pk_fma_f32 v[76:77], v[138:139], s[60:61], v[84:85] op_sel_hi:[1,0,1] neg_lo:[0,0,1] neg_hi:[0,0,1]
	v_pk_add_f32 v[84:85], v[132:133], v[62:63]
	v_pk_add_f32 v[62:63], v[132:133], v[62:63] neg_lo:[0,1] neg_hi:[0,1]
	v_pk_add_f32 v[132:133], v[88:89], v[10:11]
	v_pk_add_f32 v[10:11], v[88:89], v[10:11] neg_lo:[0,1] neg_hi:[0,1]
	s_nop 0
	v_pk_mul_f32 v[88:89], v[10:11], s[60:61] op_sel:[1,0] op_sel_hi:[0,0] neg_hi:[1,0]
	s_nop 0
	v_pk_fma_f32 v[10:11], v[10:11], s[60:61], v[88:89] op_sel_hi:[1,0,1]
	v_pk_add_f32 v[88:89], v[22:23], v[66:67]
	v_pk_add_f32 v[22:23], v[22:23], v[66:67] neg_lo:[0,1] neg_hi:[0,1]
	s_nop 0
	v_xor_b32_e32 v67, 0x80000000, v22
	v_mov_b32_e32 v66, v23
	v_pk_add_f32 v[22:23], v[24:25], v[68:69]
	v_pk_add_f32 v[24:25], v[24:25], v[68:69] neg_lo:[0,1] neg_hi:[0,1]
	s_nop 0
	v_pk_mul_f32 v[68:69], v[24:25], s[60:61] op_sel_hi:[1,0]
	v_xor_b32_e32 v139, 0x80000000, v24
	v_mov_b32_e32 v138, v25
	v_pk_fma_f32 v[24:25], v[138:139], s[60:61], v[68:69] op_sel_hi:[1,0,1] neg_lo:[0,0,1] neg_hi:[0,0,1]
	v_pk_add_f32 v[68:69], v[2:3], v[64:65]
	v_pk_add_f32 v[2:3], v[2:3], v[64:65] neg_lo:[0,1] neg_hi:[0,1]
	v_pk_add_f32 v[64:65], v[4:5], v[12:13]
	v_pk_add_f32 v[4:5], v[4:5], v[12:13] neg_lo:[0,1] neg_hi:[0,1]
	s_nop 0
	v_pk_mul_f32 v[12:13], v[4:5], s[60:61] op_sel:[1,0] op_sel_hi:[0,0] neg_hi:[1,0]
	s_nop 0
	v_pk_fma_f32 v[4:5], v[4:5], s[60:61], v[12:13] op_sel_hi:[1,0,1]
	v_pk_add_f32 v[12:13], v[6:7], v[14:15]
	v_pk_add_f32 v[6:7], v[6:7], v[14:15] neg_lo:[0,1] neg_hi:[0,1]
	v_pk_add_f32 v[140:141], v[68:69], v[12:13]
	v_xor_b32_e32 v15, 0x80000000, v6
	v_mov_b32_e32 v14, v7
	v_pk_add_f32 v[6:7], v[8:9], v[16:17]
	v_pk_add_f32 v[8:9], v[8:9], v[16:17] neg_lo:[0,1] neg_hi:[0,1]
	v_pk_add_f32 v[142:143], v[64:65], v[6:7]
	v_pk_mul_f32 v[16:17], v[8:9], s[60:61] op_sel_hi:[1,0]
	s_nop 0
	v_pk_fma_f32 v[8:9], v[8:9], s[60:61], v[16:17] op_sel:[1,0,0] op_sel_hi:[0,0,1] neg_lo:[0,0,1] neg_hi:[1,0,1]
	v_pk_add_f32 v[16:17], v[70:71], v[136:137]
	v_pk_add_f32 v[70:71], v[70:71], v[136:137] neg_lo:[0,1] neg_hi:[0,1]
	v_pk_add_f32 v[136:137], v[134:135], v[72:73]
	v_pk_add_f32 v[72:73], v[134:135], v[72:73] neg_lo:[0,1] neg_hi:[0,1]
	v_pk_add_f32 v[138:139], v[84:85], v[88:89] neg_lo:[0,1] neg_hi:[0,1]
	v_xor_b32_e32 v135, 0x80000000, v72
	v_mov_b32_e32 v134, v73
	v_pk_add_f32 v[72:73], v[92:93], v[128:129]
	v_pk_add_f32 v[92:93], v[92:93], v[128:129] neg_lo:[0,1] neg_hi:[0,1]
	v_pk_add_f32 v[128:129], v[78:79], v[90:91]
	v_pk_add_f32 v[78:79], v[78:79], v[90:91] neg_lo:[0,1] neg_hi:[0,1]
	v_pk_add_f32 v[6:7], v[64:65], v[6:7] neg_lo:[0,1] neg_hi:[0,1]
	v_xor_b32_e32 v91, 0x80000000, v78
	v_mov_b32_e32 v90, v79
	v_pk_add_f32 v[78:79], v[130:131], v[80:81]
	v_pk_add_f32 v[130:131], v[130:131], v[80:81] neg_lo:[0,1] neg_hi:[0,1]
	v_pk_add_f32 v[80:81], v[94:95], v[74:75]
	v_pk_add_f32 v[74:75], v[94:95], v[74:75] neg_lo:[0,1] neg_hi:[0,1]
	v_xor_b32_e32 v149, 0x80000000, v6
	v_xor_b32_e32 v95, 0x80000000, v74
	v_mov_b32_e32 v94, v75
	v_pk_add_f32 v[74:75], v[86:87], v[82:83]
	v_pk_add_f32 v[82:83], v[86:87], v[82:83] neg_lo:[0,1] neg_hi:[0,1]
	v_pk_add_f32 v[86:87], v[18:19], v[76:77]
	v_pk_add_f32 v[18:19], v[18:19], v[76:77] neg_lo:[0,1] neg_hi:[0,1]
	v_mov_b32_e32 v148, v7
	v_xor_b32_e32 v77, 0x80000000, v18
	v_mov_b32_e32 v76, v19
	v_pk_add_f32 v[18:19], v[84:85], v[88:89]
	v_pk_add_f32 v[88:89], v[132:133], v[22:23]
	v_pk_add_f32 v[22:23], v[132:133], v[22:23] neg_lo:[0,1] neg_hi:[0,1]
	v_pk_add_f32 v[6:7], v[2:3], v[14:15]
	v_xor_b32_e32 v133, 0x80000000, v22
	v_mov_b32_e32 v132, v23
	v_pk_add_f32 v[22:23], v[62:63], v[66:67]
	v_pk_add_f32 v[62:63], v[62:63], v[66:67] neg_lo:[0,1] neg_hi:[0,1]
	v_pk_add_f32 v[66:67], v[10:11], v[24:25]
	v_pk_add_f32 v[10:11], v[10:11], v[24:25] neg_lo:[0,1] neg_hi:[0,1]
	v_pk_add_f32 v[154:155], v[2:3], v[14:15] neg_lo:[0,1] neg_hi:[0,1]
	v_pk_add_f32 v[2:3], v[4:5], v[8:9] neg_lo:[0,1] neg_hi:[0,1]
	v_pk_add_f32 v[68:69], v[68:69], v[12:13] neg_lo:[0,1] neg_hi:[0,1]
	v_pk_add_f32 v[156:157], v[4:5], v[8:9]
	v_xor_b32_e32 v159, 0x80000000, v2
	v_mov_b32_e32 v158, v3
	v_pk_add_f32 v[2:3], v[16:17], v[136:137]
	v_pk_add_f32 v[84:85], v[16:17], v[136:137] neg_lo:[0,1] neg_hi:[0,1]
	v_pk_add_f32 v[136:137], v[70:71], v[134:135]
	v_pk_add_f32 v[16:17], v[70:71], v[134:135] neg_lo:[0,1] neg_hi:[0,1]
	v_pk_add_f32 v[134:135], v[72:73], v[128:129]
	v_pk_add_f32 v[70:71], v[72:73], v[128:129] neg_lo:[0,1] neg_hi:[0,1]
	v_pk_add_f32 v[128:129], v[92:93], v[90:91]
	v_pk_add_f32 v[8:9], v[92:93], v[90:91] neg_lo:[0,1] neg_hi:[0,1]
	v_pk_add_f32 v[72:73], v[78:79], v[80:81]
	v_pk_add_f32 v[80:81], v[78:79], v[80:81] neg_lo:[0,1] neg_hi:[0,1]
	v_pk_add_f32 v[92:93], v[130:131], v[94:95]
	v_pk_add_f32 v[12:13], v[130:131], v[94:95] neg_lo:[0,1] neg_hi:[0,1]
	v_pk_add_f32 v[78:79], v[74:75], v[86:87]
	v_pk_add_f32 v[64:65], v[74:75], v[86:87] neg_lo:[0,1] neg_hi:[0,1]
	v_pk_add_f32 v[130:131], v[82:83], v[76:77]
	v_pk_add_f32 v[4:5], v[82:83], v[76:77] neg_lo:[0,1] neg_hi:[0,1]
	v_pk_add_f32 v[76:77], v[18:19], v[88:89]
	v_pk_add_f32 v[88:89], v[18:19], v[88:89] neg_lo:[0,1] neg_hi:[0,1]
	v_pk_add_f32 v[86:87], v[138:139], v[132:133]
	v_pk_add_f32 v[18:19], v[138:139], v[132:133] neg_lo:[0,1] neg_hi:[0,1]
	v_pk_add_f32 v[132:133], v[62:63], v[10:11] op_sel:[0,1] op_sel_hi:[1,0] neg_hi:[0,1]
	v_pk_add_f32 v[10:11], v[62:63], v[10:11] op_sel:[0,1] op_sel_hi:[1,0] neg_lo:[0,1]
	v_pk_mul_f32 v[24:25], v[20:21], v[20:21]
	s_nop 0
	v_pk_add_f32 v[24:25], v[24:25], v[24:25] op_sel:[0,1] op_sel_hi:[0,1] neg_lo:[0,1] neg_hi:[0,1]
	v_pk_mul_f32 v[62:63], v[20:21], v[26:27] op_sel:[1,0] op_sel_hi:[0,0] neg_lo:[1,0]
	v_pk_add_f32 v[90:91], v[22:23], v[66:67]
	v_pk_add_f32 v[74:75], v[22:23], v[66:67] neg_lo:[0,1] neg_hi:[0,1]
	v_pk_add_f32 v[22:23], v[140:141], v[142:143]
	v_pk_add_f32 v[82:83], v[140:141], v[142:143] neg_lo:[0,1] neg_hi:[0,1]
	v_pk_add_f32 v[138:139], v[68:69], v[148:149]
	v_pk_add_f32 v[14:15], v[68:69], v[148:149] neg_lo:[0,1] neg_hi:[0,1]
	v_pk_fma_f32 v[68:69], v[20:21], v[24:25], v[62:63]
	v_mov_b32_e32 v142, v21
	s_nop 0
	v_pk_mul_f32 v[62:63], v[142:143], v[76:77] op_sel:[0,1] op_sel_hi:[0,0] neg_hi:[0,1]
	v_pk_fma_f32 v[20:21], v[20:21], v[76:77], v[62:63] op_sel_hi:[0,1,1]
	v_pk_mul_f32 v[62:63], v[26:27], s[46:47] op_sel_hi:[0,1]
	v_pk_fma_f32 v[76:77], v[24:25], s[40:41], v[62:63]
	s_nop 0
	v_pk_mul_f32 v[62:63], v[76:77], v[72:73] op_sel:[1,1] op_sel_hi:[1,0] neg_hi:[0,1]
	v_pk_add_f32 v[94:95], v[6:7], v[156:157]
	v_pk_fma_f32 v[62:63], v[72:73], v[76:77], v[62:63] op_sel_hi:[1,0,1]
	v_pk_mul_f32 v[72:73], v[26:27], v[68:69] op_sel:[0,1] op_sel_hi:[0,0] neg_lo:[0,1]
	v_pk_fma_f32 v[142:143], v[24:25], v[68:69], v[72:73]
	v_pk_mul_f32 v[72:73], v[68:69], v[22:23] op_sel:[1,1] op_sel_hi:[1,0] neg_hi:[0,1]
	v_pk_add_f32 v[140:141], v[154:155], v[158:159]
	v_pk_fma_f32 v[22:23], v[68:69], v[22:23], v[72:73] op_sel_hi:[0,1,1]
	v_pk_mul_f32 v[68:69], v[26:27], v[76:77] op_sel:[0,1] op_sel_hi:[0,0] neg_lo:[0,1]
	v_pk_fma_f32 v[76:77], v[24:25], v[76:77], v[68:69]
	s_nop 0
	v_pk_mul_f32 v[68:69], v[134:135], v[76:77] op_sel:[1,1] op_sel_hi:[0,1] neg_hi:[1,0]
	v_pk_add_f32 v[66:67], v[6:7], v[156:157] neg_lo:[0,1] neg_hi:[0,1]
	v_pk_fma_f32 v[72:73], v[134:135], v[76:77], v[68:69] op_sel_hi:[1,0,1]
	v_pk_mul_f32 v[68:69], v[26:27], v[142:143] op_sel:[0,1] op_sel_hi:[0,0] neg_lo:[0,1]
	v_pk_fma_f32 v[134:135], v[24:25], v[142:143], v[68:69]
	v_pk_mul_f32 v[68:69], v[142:143], v[90:91] op_sel:[1,1] op_sel_hi:[1,0] neg_hi:[0,1]
	v_pk_add_f32 v[6:7], v[154:155], v[158:159] neg_lo:[0,1] neg_hi:[0,1]
	v_pk_fma_f32 v[68:69], v[90:91], v[142:143], v[68:69] op_sel_hi:[1,0,1]
	v_pk_mul_f32 v[90:91], v[26:27], v[76:77] op_sel:[0,1] op_sel_hi:[0,0] neg_lo:[0,1]
	v_pk_fma_f32 v[90:91], v[24:25], v[76:77], v[90:91]
	s_nop 0
	v_pk_mul_f32 v[76:77], v[78:79], v[90:91] op_sel:[1,1] op_sel_hi:[0,1] neg_hi:[1,0]
	s_nop 0
	v_pk_fma_f32 v[78:79], v[78:79], v[90:91], v[76:77] op_sel_hi:[1,0,1]
	v_pk_mul_f32 v[76:77], v[26:27], v[134:135] op_sel:[0,1] op_sel_hi:[0,0] neg_lo:[0,1]
	v_pk_fma_f32 v[142:143], v[24:25], v[134:135], v[76:77]
	v_pk_mul_f32 v[76:77], v[134:135], v[94:95] op_sel:[1,1] op_sel_hi:[1,0] neg_hi:[0,1]
	s_nop 0
	v_pk_fma_f32 v[76:77], v[94:95], v[134:135], v[76:77] op_sel_hi:[1,0,1]
	v_pk_mul_f32 v[94:95], v[26:27], v[90:91] op_sel:[0,1] op_sel_hi:[0,0] neg_lo:[0,1]
	v_pk_fma_f32 v[94:95], v[24:25], v[90:91], v[94:95]
	s_nop 0
	v_pk_mul_f32 v[90:91], v[136:137], v[94:95] op_sel:[1,1] op_sel_hi:[0,1] neg_hi:[1,0]
	v_xor_b32_e32 v134, 0x80000000, v143
	v_pk_fma_f32 v[90:91], v[136:137], v[94:95], v[90:91] op_sel_hi:[1,0,1]
	v_pk_mul_f32 v[136:137], v[86:87], v[142:143] op_sel:[1,1] op_sel_hi:[0,1] neg_hi:[1,0]
	v_mov_b32_e32 v135, v142
	v_pk_fma_f32 v[86:87], v[86:87], v[142:143], v[136:137] op_sel_hi:[1,0,1]
	v_pk_mul_f32 v[136:137], v[26:27], v[94:95] op_sel:[0,1] op_sel_hi:[0,0] neg_lo:[0,1]
	v_pk_mul_f32 v[134:135], v[26:27], v[134:135] op_sel_hi:[0,1]
	v_pk_fma_f32 v[136:137], v[24:25], v[94:95], v[136:137]
	v_pk_fma_f32 v[134:135], v[24:25], v[142:143], v[134:135]
	v_pk_mul_f32 v[94:95], v[92:93], v[136:137] op_sel:[1,1] op_sel_hi:[0,1] neg_hi:[1,0]
	s_nop 0
	v_pk_fma_f32 v[94:95], v[92:93], v[136:137], v[94:95] op_sel_hi:[1,0,1]
	v_pk_mul_f32 v[92:93], v[26:27], v[134:135] op_sel:[0,1] op_sel_hi:[0,0] neg_lo:[0,1]
	v_pk_fma_f32 v[142:143], v[24:25], v[134:135], v[92:93]
	v_pk_mul_f32 v[92:93], v[138:139], v[134:135] op_sel:[1,1] op_sel_hi:[0,1] neg_hi:[1,0]
	s_nop 0
	v_pk_fma_f32 v[92:93], v[138:139], v[134:135], v[92:93] op_sel_hi:[1,0,1]
	v_pk_mul_f32 v[134:135], v[26:27], v[136:137] op_sel:[0,1] op_sel_hi:[0,0] neg_lo:[0,1]
	s_nop 0
	v_pk_fma_f32 v[134:135], v[24:25], v[136:137], v[134:135]
	v_pk_mul_f32 v[138:139], v[132:133], v[142:143] op_sel:[1,1] op_sel_hi:[0,1] neg_hi:[1,0]
	v_pk_mul_f32 v[136:137], v[128:129], v[134:135] op_sel:[1,1] op_sel_hi:[0,1] neg_hi:[1,0]
	v_pk_fma_f32 v[132:133], v[132:133], v[142:143], v[138:139] op_sel_hi:[1,0,1]
	v_pk_fma_f32 v[128:129], v[128:129], v[134:135], v[136:137] op_sel_hi:[1,0,1]
	v_pk_mul_f32 v[138:139], v[26:27], v[134:135] op_sel:[0,1] op_sel_hi:[0,0] neg_lo:[0,1]
	v_pk_mul_f32 v[136:137], v[26:27], v[142:143] op_sel:[0,1] op_sel_hi:[0,0] neg_lo:[0,1]
	v_pk_fma_f32 v[134:135], v[24:25], v[134:135], v[138:139]
	v_pk_fma_f32 v[136:137], v[24:25], v[142:143], v[136:137]
	v_pk_mul_f32 v[138:139], v[130:131], v[134:135] op_sel:[1,1] op_sel_hi:[0,1] neg_hi:[1,0]
	s_nop 0
	v_pk_fma_f32 v[130:131], v[130:131], v[134:135], v[138:139] op_sel_hi:[1,0,1]
	v_pk_mul_f32 v[138:139], v[26:27], v[136:137] op_sel:[0,1] op_sel_hi:[0,0] neg_lo:[0,1]
	v_pk_mul_f32 v[142:143], v[140:141], v[136:137] op_sel:[1,1] op_sel_hi:[0,1] neg_hi:[1,0]
	v_pk_fma_f32 v[138:139], v[24:25], v[136:137], v[138:139]
	v_pk_fma_f32 v[136:137], v[140:141], v[136:137], v[142:143] op_sel_hi:[1,0,1]
	v_pk_mul_f32 v[140:141], v[26:27], v[134:135] op_sel:[0,1] op_sel_hi:[0,0] neg_lo:[0,1]
	v_pk_fma_f32 v[134:135], v[24:25], v[134:135], v[140:141]
	s_nop 0
	v_pk_mul_f32 v[140:141], v[84:85], v[134:135] op_sel:[1,1] op_sel_hi:[0,1] neg_hi:[1,0]
	s_nop 0
	v_pk_fma_f32 v[84:85], v[84:85], v[134:135], v[140:141] op_sel_hi:[1,0,1]
	v_pk_mul_f32 v[140:141], v[26:27], v[138:139] op_sel:[0,1] op_sel_hi:[0,0] neg_lo:[0,1]
	v_pk_mul_f32 v[142:143], v[88:89], v[138:139] op_sel:[1,1] op_sel_hi:[0,1] neg_hi:[1,0]
	v_pk_fma_f32 v[140:141], v[24:25], v[138:139], v[140:141]
	v_pk_fma_f32 v[88:89], v[88:89], v[138:139], v[142:143] op_sel_hi:[1,0,1]
	v_pk_mul_f32 v[138:139], v[26:27], v[134:135] op_sel:[0,1] op_sel_hi:[0,0] neg_lo:[0,1]
	v_pk_fma_f32 v[134:135], v[24:25], v[134:135], v[138:139]
	s_nop 0
	v_pk_mul_f32 v[138:139], v[80:81], v[134:135] op_sel:[1,1] op_sel_hi:[0,1] neg_hi:[1,0]
	s_nop 0
	v_pk_fma_f32 v[80:81], v[80:81], v[134:135], v[138:139] op_sel_hi:[1,0,1]
	v_pk_mul_f32 v[138:139], v[26:27], v[140:141] op_sel:[0,1] op_sel_hi:[0,0] neg_lo:[0,1]
	v_pk_mul_f32 v[142:143], v[82:83], v[140:141] op_sel:[1,1] op_sel_hi:[0,1] neg_hi:[1,0]
	v_pk_fma_f32 v[138:139], v[24:25], v[140:141], v[138:139]
	v_pk_fma_f32 v[82:83], v[82:83], v[140:141], v[142:143] op_sel_hi:[1,0,1]
	v_pk_mul_f32 v[140:141], v[26:27], v[134:135] op_sel:[0,1] op_sel_hi:[0,0] neg_lo:[0,1]
	v_pk_fma_f32 v[134:135], v[24:25], v[134:135], v[140:141]
	s_nop 0
	v_pk_mul_f32 v[140:141], v[70:71], v[134:135] op_sel:[1,1] op_sel_hi:[0,1] neg_hi:[1,0]
	s_nop 0
	v_pk_fma_f32 v[70:71], v[70:71], v[134:135], v[140:141] op_sel_hi:[1,0,1]
	v_pk_mul_f32 v[140:141], v[26:27], v[138:139] op_sel:[0,1] op_sel_hi:[0,0] neg_lo:[0,1]
	v_pk_mul_f32 v[142:143], v[74:75], v[138:139] op_sel:[1,1] op_sel_hi:[0,1] neg_hi:[1,0]
	v_pk_fma_f32 v[140:141], v[24:25], v[138:139], v[140:141]
	v_pk_fma_f32 v[74:75], v[74:75], v[138:139], v[142:143] op_sel_hi:[1,0,1]
	v_pk_mul_f32 v[138:139], v[26:27], v[134:135] op_sel:[0,1] op_sel_hi:[0,0] neg_lo:[0,1]
	v_pk_fma_f32 v[134:135], v[24:25], v[134:135], v[138:139]
	s_nop 0
	v_pk_mul_f32 v[138:139], v[64:65], v[134:135] op_sel:[1,1] op_sel_hi:[0,1] neg_hi:[1,0]
	s_nop 0
	v_pk_fma_f32 v[64:65], v[64:65], v[134:135], v[138:139] op_sel_hi:[1,0,1]
	v_pk_mul_f32 v[138:139], v[26:27], v[140:141] op_sel:[0,1] op_sel_hi:[0,0] neg_lo:[0,1]
	v_pk_mul_f32 v[142:143], v[66:67], v[140:141] op_sel:[1,1] op_sel_hi:[0,1] neg_hi:[1,0]
	v_pk_fma_f32 v[138:139], v[24:25], v[140:141], v[138:139]
	v_pk_fma_f32 v[66:67], v[66:67], v[140:141], v[142:143] op_sel_hi:[1,0,1]
	v_pk_mul_f32 v[140:141], v[26:27], v[134:135] op_sel:[0,1] op_sel_hi:[0,0] neg_lo:[0,1]
	v_pk_fma_f32 v[134:135], v[24:25], v[134:135], v[140:141]
	s_nop 0
	v_pk_mul_f32 v[140:141], v[16:17], v[134:135] op_sel:[1,1] op_sel_hi:[0,1] neg_hi:[1,0]
	s_nop 0
	v_pk_fma_f32 v[16:17], v[16:17], v[134:135], v[140:141] op_sel_hi:[1,0,1]
	v_pk_mul_f32 v[140:141], v[26:27], v[138:139] op_sel:[0,1] op_sel_hi:[0,0] neg_lo:[0,1]
	v_pk_mul_f32 v[142:143], v[18:19], v[138:139] op_sel:[1,1] op_sel_hi:[0,1] neg_hi:[1,0]
	v_pk_fma_f32 v[140:141], v[24:25], v[138:139], v[140:141]
	v_pk_fma_f32 v[18:19], v[18:19], v[138:139], v[142:143] op_sel_hi:[1,0,1]
	v_pk_mul_f32 v[138:139], v[26:27], v[134:135] op_sel:[0,1] op_sel_hi:[0,0] neg_lo:[0,1]
	v_pk_fma_f32 v[134:135], v[24:25], v[134:135], v[138:139]
	s_nop 0
	v_pk_mul_f32 v[138:139], v[12:13], v[134:135] op_sel:[1,1] op_sel_hi:[0,1] neg_hi:[1,0]
	s_nop 0
	v_pk_fma_f32 v[12:13], v[12:13], v[134:135], v[138:139] op_sel_hi:[1,0,1]
	v_pk_mul_f32 v[138:139], v[26:27], v[140:141] op_sel:[0,1] op_sel_hi:[0,0] neg_lo:[0,1]
	v_pk_mul_f32 v[142:143], v[14:15], v[140:141] op_sel:[1,1] op_sel_hi:[0,1] neg_hi:[1,0]
	v_pk_fma_f32 v[138:139], v[24:25], v[140:141], v[138:139]
	v_pk_fma_f32 v[14:15], v[14:15], v[140:141], v[142:143] op_sel_hi:[1,0,1]
	v_pk_mul_f32 v[140:141], v[26:27], v[134:135] op_sel:[0,1] op_sel_hi:[0,0] neg_lo:[0,1]
	v_pk_fma_f32 v[134:135], v[24:25], v[134:135], v[140:141]
	s_nop 0
	v_pk_mul_f32 v[140:141], v[8:9], v[134:135] op_sel:[1,1] op_sel_hi:[0,1] neg_hi:[1,0]
	s_nop 0
	v_pk_fma_f32 v[8:9], v[8:9], v[134:135], v[140:141] op_sel_hi:[1,0,1]
	v_pk_mul_f32 v[140:141], v[26:27], v[138:139] op_sel:[0,1] op_sel_hi:[0,0] neg_lo:[0,1]
	v_pk_mul_f32 v[142:143], v[10:11], v[138:139] op_sel:[1,1] op_sel_hi:[0,1] neg_hi:[1,0]
	v_pk_fma_f32 v[140:141], v[24:25], v[138:139], v[140:141]
	v_pk_fma_f32 v[10:11], v[10:11], v[138:139], v[142:143] op_sel_hi:[1,0,1]
	v_pk_mul_f32 v[138:139], v[26:27], v[134:135] op_sel:[0,1] op_sel_hi:[0,0] neg_lo:[0,1]
	v_pk_fma_f32 v[24:25], v[24:25], v[134:135], v[138:139]
	s_nop 0
	v_pk_mul_f32 v[134:135], v[4:5], v[24:25] op_sel:[1,1] op_sel_hi:[0,1] neg_hi:[1,0]
	s_nop 0
	v_pk_fma_f32 v[4:5], v[4:5], v[24:25], v[134:135] op_sel_hi:[1,0,1]
	v_pk_mul_f32 v[24:25], v[6:7], v[140:141] op_sel:[1,1] op_sel_hi:[0,1] neg_hi:[1,0]
	s_nop 0
	v_pk_fma_f32 v[6:7], v[6:7], v[140:141], v[24:25] op_sel_hi:[1,0,1]
	ds_write_b64 v27, v[2:3]
	ds_write_b64 v96, v[84:85]
	ds_write_b64 v97, v[90:91] offset:256
	ds_write_b64 v98, v[16:17] offset:256
	ds_write_b64 v99, v[72:73] offset:512
	ds_write_b64 v100, v[70:71] offset:512
	ds_write_b64 v101, v[128:129] offset:768
	ds_write_b64 v102, v[8:9] offset:768
	ds_write_b64 v103, v[62:63] offset:1024
	ds_write_b64 v104, v[80:81] offset:1024
	ds_write_b64 v105, v[94:95] offset:1280
	ds_write_b64 v106, v[12:13] offset:1280
	ds_write_b64 v107, v[78:79] offset:1536
	ds_write_b64 v108, v[64:65] offset:1536
	ds_write_b64 v109, v[130:131] offset:1792
	ds_write_b64 v110, v[4:5] offset:1792
	ds_write_b64 v111, v[20:21] offset:2048
	ds_write_b64 v112, v[88:89] offset:2048
	ds_write_b64 v113, v[86:87] offset:2304
	ds_write_b64 v114, v[18:19] offset:2304
	ds_write_b64 v115, v[68:69] offset:2560
	ds_write_b64 v116, v[74:75] offset:2560
	ds_write_b64 v117, v[132:133] offset:2816
	ds_write_b64 v118, v[10:11] offset:2816
	ds_write_b64 v119, v[22:23] offset:3072
	ds_write_b64 v120, v[82:83] offset:3072
	ds_write_b64 v121, v[92:93] offset:3328
	ds_write_b64 v122, v[14:15] offset:3328
	ds_write_b64 v123, v[76:77] offset:3584
	ds_write_b64 v124, v[66:67] offset:3584
	ds_write_b64 v125, v[136:137] offset:3840
	ds_write_b64 v126, v[6:7] offset:3840
	v_mov_b32_e32 v2, v146
	s_waitcnt lgkmcnt(0)
	s_barrier
	s_nop 0
	v_lshlrev_b32_e32 v3, 4, v2
	v_lshrrev_b32_e32 v4, 1, v2
	v_bfe_u32 v2, v2, 1, 4
	v_bitop3_b32 v5, v4, v3, 16 bitop3:0x6c
	v_lshl_add_u32 v5, v5, 3, 16
	v_lshlrev_b32_e32 v2, 3, v2
	v_add_u32_e32 v6, v5, v2
	ds_read_b64 v[12:13], v6
	v_bitop3_b32 v6, v4, 1, 15 bitop3:0x6c
	v_lshlrev_b32_e32 v8, 3, v6
	v_add_u32_e32 v6, v5, v8
	ds_read_b64 v[14:15], v6
	v_bitop3_b32 v6, v4, 2, 15 bitop3:0x6c
	v_lshlrev_b32_e32 v9, 3, v6
	v_add_u32_e32 v6, v5, v9
	ds_read_b64 v[16:17], v6
	v_bitop3_b32 v6, v4, 3, 15 bitop3:0x6c
	v_lshlrev_b32_e32 v10, 3, v6
	v_add_u32_e32 v6, v5, v10
	ds_read_b64 v[18:19], v6
	v_bitop3_b32 v6, v4, 4, 15 bitop3:0x6c
	v_lshlrev_b32_e32 v11, 3, v6
	v_add_u32_e32 v6, v5, v11
	ds_read_b64 v[20:21], v6
	v_bitop3_b32 v6, v4, 5, 15 bitop3:0x6c
	v_lshlrev_b32_e32 v82, 3, v6
	v_add_u32_e32 v6, v5, v82
	ds_read_b64 v[22:23], v6
	v_bitop3_b32 v6, v4, 6, 15 bitop3:0x6c
	v_lshlrev_b32_e32 v83, 3, v6
	v_add_u32_e32 v6, v5, v83
	ds_read_b64 v[24:25], v6
	v_bitop3_b32 v6, v4, 7, 15 bitop3:0x6c
	v_lshlrev_b32_e32 v84, 3, v6
	v_add_u32_e32 v6, v5, v84
	ds_read_b64 v[26:27], v6
	v_bitop3_b32 v6, v4, 8, 15 bitop3:0x6c
	v_lshlrev_b32_e32 v85, 3, v6
	v_add_u32_e32 v6, v5, v85
	ds_read_b64 v[62:63], v6
	v_bitop3_b32 v6, v4, 9, 15 bitop3:0x6c
	v_lshlrev_b32_e32 v86, 3, v6
	v_add_u32_e32 v6, v5, v86
	ds_read_b64 v[64:65], v6
	v_bitop3_b32 v6, v4, 10, 15 bitop3:0x6c
	v_lshlrev_b32_e32 v87, 3, v6
	v_add_u32_e32 v6, v5, v87
	ds_read_b64 v[66:67], v6
	v_bitop3_b32 v6, v4, 11, 15 bitop3:0x6c
	v_lshlrev_b32_e32 v88, 3, v6
	v_add_u32_e32 v6, v5, v88
	ds_read_b64 v[68:69], v6
	v_bitop3_b32 v6, v4, 12, 15 bitop3:0x6c
	v_lshlrev_b32_e32 v89, 3, v6
	v_add_u32_e32 v6, v5, v89
	ds_read_b64 v[70:71], v6
	v_bitop3_b32 v6, v4, 13, 15 bitop3:0x6c
	v_lshlrev_b32_e32 v90, 3, v6
	v_add_u32_e32 v6, v5, v90
	ds_read_b64 v[72:73], v6
	v_bitop3_b32 v6, v4, 14, 15 bitop3:0x6c
	v_lshlrev_b32_e32 v91, 3, v6
	v_add_u32_e32 v6, v5, v91
	v_add_u32_e32 v3, 0x2000, v3
	ds_read_b64 v[74:75], v6
	v_bitop3_b32 v6, v4, 15, v4 bitop3:0xc
	v_bitop3_b32 v3, v3, v4, 16 bitop3:0x78
	v_lshlrev_b32_e32 v106, 3, v6
	v_lshl_add_u32 v107, v3, 3, 16
	v_add_u32_e32 v5, v5, v106
	v_add_u32_e32 v2, v107, v2
	ds_read_b64 v[76:77], v5
	ds_read_b64 v[6:7], v2
	v_add_u32_e32 v2, v107, v8
	ds_read_b64 v[78:79], v2
	v_add_u32_e32 v2, v107, v9
	ds_read_b64 v[8:9], v2
	v_add_u32_e32 v2, v107, v10
	ds_read_b64 v[80:81], v2
	v_add_u32_e32 v2, v107, v11
	ds_read_b64 v[10:11], v2
	v_add_u32_e32 v2, v107, v82
	v_add_u32_e32 v82, v107, v84
	v_add_u32_e32 v84, v107, v85
	ds_read_b64 v[4:5], v2
	ds_read_b64 v[92:93], v84
	v_add_u32_e32 v2, v107, v83
	v_add_u32_e32 v84, v107, v86
	ds_read_b64 v[2:3], v2
	ds_read_b64 v[82:83], v82
	ds_read_b64 v[94:95], v84
	v_add_u32_e32 v84, v107, v87
	ds_read_b64 v[96:97], v84
	v_add_u32_e32 v84, v107, v88
	ds_read_b64 v[98:99], v84
	v_add_u32_e32 v84, v107, v89
	ds_read_b64 v[100:101], v84
	v_add_u32_e32 v84, v107, v90
	ds_read_b64 v[102:103], v84
	v_add_u32_e32 v84, v107, v91
	ds_read_b64 v[104:105], v84
	v_add_u32_e32 v84, v107, v106
	ds_read_b64 v[106:107], v84
	s_waitcnt lgkmcnt(14)
	v_pk_add_f32 v[84:85], v[12:13], v[62:63]
	v_pk_add_f32 v[12:13], v[12:13], v[62:63] neg_lo:[0,1] neg_hi:[0,1]
	v_pk_add_f32 v[62:63], v[14:15], v[64:65]
	v_pk_add_f32 v[14:15], v[14:15], v[64:65] neg_lo:[0,1] neg_hi:[0,1]
	s_nop 0
	v_pk_mul_f32 v[64:65], v[14:15], s[54:55] op_sel:[1,0] op_sel_hi:[0,0] neg_hi:[1,0]
	s_nop 0
	v_pk_fma_f32 v[14:15], v[14:15], s[52:53], v[64:65] op_sel_hi:[1,0,1]
	v_pk_add_f32 v[64:65], v[16:17], v[66:67]
	v_pk_add_f32 v[16:17], v[16:17], v[66:67] neg_lo:[0,1] neg_hi:[0,1]
	s_nop 0
	v_pk_mul_f32 v[66:67], v[16:17], s[60:61] op_sel:[1,0] op_sel_hi:[0,0] neg_hi:[1,0]
	s_nop 0
	v_pk_fma_f32 v[16:17], v[16:17], s[60:61], v[66:67] op_sel_hi:[1,0,1]
	v_pk_add_f32 v[66:67], v[18:19], v[68:69]
	v_pk_add_f32 v[18:19], v[18:19], v[68:69] neg_lo:[0,1] neg_hi:[0,1]
	s_nop 0
	v_pk_mul_f32 v[68:69], v[18:19], s[52:53] op_sel:[1,0] op_sel_hi:[0,0] neg_hi:[1,0]
	s_nop 0
	v_pk_fma_f32 v[18:19], v[18:19], s[54:55], v[68:69] op_sel_hi:[1,0,1]
	v_pk_add_f32 v[68:69], v[20:21], v[70:71]
	v_pk_add_f32 v[20:21], v[20:21], v[70:71] neg_lo:[0,1] neg_hi:[0,1]
	s_nop 0
	v_xor_b32_e32 v71, 0x80000000, v20
	v_mov_b32_e32 v70, v21
	v_pk_add_f32 v[20:21], v[22:23], v[72:73]
	v_pk_add_f32 v[22:23], v[22:23], v[72:73] neg_lo:[0,1] neg_hi:[0,1]
	s_nop 0
	v_pk_mul_f32 v[72:73], v[22:23], s[54:55] op_sel_hi:[1,0]
	v_xor_b32_e32 v87, 0x80000000, v22
	v_mov_b32_e32 v86, v23
	v_pk_fma_f32 v[22:23], v[86:87], s[52:53], v[72:73] op_sel_hi:[1,0,1] neg_lo:[0,0,1] neg_hi:[0,0,1]
	v_pk_add_f32 v[72:73], v[24:25], v[74:75]
	v_pk_add_f32 v[24:25], v[24:25], v[74:75] neg_lo:[0,1] neg_hi:[0,1]
	s_nop 0
	v_pk_mul_f32 v[74:75], v[24:25], s[60:61] op_sel_hi:[1,0]
	v_xor_b32_e32 v87, 0x80000000, v24
	v_mov_b32_e32 v86, v25
	v_pk_fma_f32 v[24:25], v[86:87], s[60:61], v[74:75] op_sel_hi:[1,0,1] neg_lo:[0,0,1] neg_hi:[0,0,1]
	v_pk_add_f32 v[74:75], v[26:27], v[76:77]
	v_pk_add_f32 v[26:27], v[26:27], v[76:77] neg_lo:[0,1] neg_hi:[0,1]
	s_nop 0
	v_pk_mul_f32 v[76:77], v[26:27], s[52:53] op_sel_hi:[1,0]
	v_xor_b32_e32 v87, 0x80000000, v26
	v_mov_b32_e32 v86, v27
	v_pk_fma_f32 v[26:27], v[86:87], s[54:55], v[76:77] op_sel_hi:[1,0,1] neg_lo:[0,0,1] neg_hi:[0,0,1]
	v_pk_add_f32 v[76:77], v[84:85], v[68:69]
	v_pk_add_f32 v[68:69], v[84:85], v[68:69] neg_lo:[0,1] neg_hi:[0,1]
	v_pk_add_f32 v[84:85], v[62:63], v[20:21]
	v_pk_add_f32 v[20:21], v[62:63], v[20:21] neg_lo:[0,1] neg_hi:[0,1]
	s_nop 0
	v_pk_mul_f32 v[62:63], v[20:21], s[60:61] op_sel:[1,0] op_sel_hi:[0,0] neg_hi:[1,0]
	s_nop 0
	v_pk_fma_f32 v[20:21], v[20:21], s[60:61], v[62:63] op_sel_hi:[1,0,1]
	v_pk_add_f32 v[62:63], v[64:65], v[72:73]
	v_pk_add_f32 v[64:65], v[64:65], v[72:73] neg_lo:[0,1] neg_hi:[0,1]
	s_nop 0
	v_xor_b32_e32 v73, 0x80000000, v64
	v_mov_b32_e32 v72, v65
	v_pk_add_f32 v[64:65], v[66:67], v[74:75]
	v_pk_add_f32 v[66:67], v[66:67], v[74:75] neg_lo:[0,1] neg_hi:[0,1]
	s_nop 0
	v_pk_mul_f32 v[74:75], v[66:67], s[60:61] op_sel_hi:[1,0]
	v_xor_b32_e32 v87, 0x80000000, v66
	v_mov_b32_e32 v86, v67
	v_pk_fma_f32 v[66:67], v[86:87], s[60:61], v[74:75] op_sel_hi:[1,0,1] neg_lo:[0,0,1] neg_hi:[0,0,1]
	v_pk_add_f32 v[74:75], v[12:13], v[70:71]
	v_pk_add_f32 v[12:13], v[12:13], v[70:71] neg_lo:[0,1] neg_hi:[0,1]
	v_pk_add_f32 v[70:71], v[14:15], v[22:23]
	v_pk_add_f32 v[14:15], v[14:15], v[22:23] neg_lo:[0,1] neg_hi:[0,1]
	s_nop 0
	v_pk_mul_f32 v[22:23], v[14:15], s[60:61] op_sel:[1,0] op_sel_hi:[0,0] neg_hi:[1,0]
	s_nop 0
	v_pk_fma_f32 v[14:15], v[14:15], s[60:61], v[22:23] op_sel_hi:[1,0,1]
	v_pk_add_f32 v[22:23], v[16:17], v[24:25]
	v_pk_add_f32 v[16:17], v[16:17], v[24:25] neg_lo:[0,1] neg_hi:[0,1]
	s_nop 0
	v_xor_b32_e32 v25, 0x80000000, v16
	v_mov_b32_e32 v24, v17
	v_pk_add_f32 v[16:17], v[18:19], v[26:27]
	v_pk_add_f32 v[18:19], v[18:19], v[26:27] neg_lo:[0,1] neg_hi:[0,1]
	v_pk_add_f32 v[108:109], v[12:13], v[24:25]
	v_pk_mul_f32 v[26:27], v[18:19], s[60:61] op_sel_hi:[1,0]
	s_nop 0
	v_pk_fma_f32 v[18:19], v[18:19], s[60:61], v[26:27] op_sel:[1,0,0] op_sel_hi:[0,0,1] neg_lo:[0,0,1] neg_hi:[1,0,1]
	v_pk_add_f32 v[26:27], v[76:77], v[62:63]
	v_pk_add_f32 v[62:63], v[76:77], v[62:63] neg_lo:[0,1] neg_hi:[0,1]
	v_pk_add_f32 v[76:77], v[84:85], v[64:65]
	v_pk_add_f32 v[64:65], v[84:85], v[64:65] neg_lo:[0,1] neg_hi:[0,1]
	v_pk_add_f32 v[110:111], v[12:13], v[24:25] neg_lo:[0,1] neg_hi:[0,1]
	v_xor_b32_e32 v85, 0x80000000, v64
	v_mov_b32_e32 v84, v65
	v_pk_add_f32 v[64:65], v[68:69], v[72:73]
	v_pk_add_f32 v[68:69], v[68:69], v[72:73] neg_lo:[0,1] neg_hi:[0,1]
	v_pk_add_f32 v[72:73], v[20:21], v[66:67]
	v_pk_add_f32 v[20:21], v[20:21], v[66:67] neg_lo:[0,1] neg_hi:[0,1]
	v_pk_add_f32 v[12:13], v[14:15], v[18:19] neg_lo:[0,1] neg_hi:[0,1]
	v_pk_add_f32 v[112:113], v[14:15], v[18:19]
	v_xor_b32_e32 v115, 0x80000000, v12
	v_mov_b32_e32 v114, v13
	v_pk_add_f32 v[12:13], v[26:27], v[76:77]
	v_pk_add_f32 v[14:15], v[26:27], v[76:77] neg_lo:[0,1] neg_hi:[0,1]
	v_pk_add_f32 v[24:25], v[68:69], v[20:21] op_sel:[0,1] op_sel_hi:[1,0] neg_hi:[0,1]
	v_pk_add_f32 v[26:27], v[68:69], v[20:21] op_sel:[0,1] op_sel_hi:[1,0] neg_lo:[0,1]
	s_waitcnt lgkmcnt(6)
	v_pk_add_f32 v[66:67], v[78:79], v[94:95] neg_lo:[0,1] neg_hi:[0,1]
	v_pk_add_f32 v[86:87], v[74:75], v[22:23]
	v_pk_mul_f32 v[76:77], v[66:67], s[54:55] op_sel:[1,0] op_sel_hi:[0,0] neg_hi:[1,0]
	v_pk_add_f32 v[74:75], v[74:75], v[22:23] neg_lo:[0,1] neg_hi:[0,1]
	v_pk_fma_f32 v[66:67], v[66:67], s[52:53], v[76:77] op_sel_hi:[1,0,1]
	s_waitcnt lgkmcnt(5)
	v_pk_add_f32 v[76:77], v[8:9], v[96:97]
	v_pk_add_f32 v[8:9], v[8:9], v[96:97] neg_lo:[0,1] neg_hi:[0,1]
	v_pk_add_f32 v[20:21], v[64:65], v[72:73]
	v_pk_add_f32 v[22:23], v[64:65], v[72:73] neg_lo:[0,1] neg_hi:[0,1]
	v_pk_add_f32 v[64:65], v[78:79], v[94:95]
	v_pk_mul_f32 v[78:79], v[8:9], s[60:61] op_sel:[1,0] op_sel_hi:[0,0] neg_hi:[1,0]
	v_pk_add_f32 v[88:89], v[70:71], v[16:17]
	v_pk_add_f32 v[16:17], v[70:71], v[16:17] neg_lo:[0,1] neg_hi:[0,1]
	v_pk_fma_f32 v[8:9], v[8:9], s[60:61], v[78:79] op_sel_hi:[1,0,1]
	s_waitcnt lgkmcnt(4)
	v_pk_add_f32 v[78:79], v[80:81], v[98:99]
	v_pk_add_f32 v[80:81], v[80:81], v[98:99] neg_lo:[0,1] neg_hi:[0,1]
	v_xor_b32_e32 v91, 0x80000000, v16
	v_mov_b32_e32 v90, v17
	v_pk_add_f32 v[16:17], v[62:63], v[84:85]
	v_pk_add_f32 v[18:19], v[62:63], v[84:85] neg_lo:[0,1] neg_hi:[0,1]
	v_pk_add_f32 v[62:63], v[6:7], v[92:93]
	v_pk_add_f32 v[6:7], v[6:7], v[92:93] neg_lo:[0,1] neg_hi:[0,1]
	v_pk_mul_f32 v[92:93], v[80:81], s[52:53] op_sel:[1,0] op_sel_hi:[0,0] neg_hi:[1,0]
	v_pk_add_f32 v[68:69], v[86:87], v[88:89]
	v_pk_fma_f32 v[80:81], v[80:81], s[54:55], v[92:93] op_sel_hi:[1,0,1]
	s_waitcnt lgkmcnt(3)
	v_pk_add_f32 v[92:93], v[10:11], v[100:101]
	v_pk_add_f32 v[10:11], v[10:11], v[100:101] neg_lo:[0,1] neg_hi:[0,1]
	v_pk_add_f32 v[70:71], v[86:87], v[88:89] neg_lo:[0,1] neg_hi:[0,1]
	v_xor_b32_e32 v95, 0x80000000, v10
	v_mov_b32_e32 v94, v11
	s_waitcnt lgkmcnt(2)
	v_pk_add_f32 v[10:11], v[4:5], v[102:103]
	v_pk_add_f32 v[4:5], v[4:5], v[102:103] neg_lo:[0,1] neg_hi:[0,1]
	v_pk_add_f32 v[84:85], v[108:109], v[112:113]
	v_pk_mul_f32 v[96:97], v[4:5], s[54:55] op_sel_hi:[1,0]
	s_nop 0
	v_pk_fma_f32 v[4:5], v[4:5], s[52:53], v[96:97] op_sel:[1,0,0] op_sel_hi:[0,0,1] neg_lo:[0,0,1] neg_hi:[1,0,1]
	s_waitcnt lgkmcnt(1)
	v_pk_add_f32 v[96:97], v[2:3], v[104:105]
	v_pk_add_f32 v[2:3], v[2:3], v[104:105] neg_lo:[0,1] neg_hi:[0,1]
	v_pk_add_f32 v[86:87], v[108:109], v[112:113] neg_lo:[0,1] neg_hi:[0,1]
	v_pk_mul_f32 v[98:99], v[2:3], s[60:61] op_sel_hi:[1,0]
	s_nop 0
	v_pk_fma_f32 v[2:3], v[2:3], s[60:61], v[98:99] op_sel:[1,0,0] op_sel_hi:[0,0,1] neg_lo:[0,0,1] neg_hi:[1,0,1]
	s_waitcnt lgkmcnt(0)
	v_pk_add_f32 v[98:99], v[82:83], v[106:107]
	v_pk_add_f32 v[82:83], v[82:83], v[106:107] neg_lo:[0,1] neg_hi:[0,1]
	v_pk_add_f32 v[72:73], v[74:75], v[90:91]
	v_pk_mul_f32 v[100:101], v[82:83], s[52:53] op_sel_hi:[1,0]
	v_xor_b32_e32 v103, 0x80000000, v82
	v_mov_b32_e32 v102, v83
	v_pk_fma_f32 v[82:83], v[102:103], s[54:55], v[100:101] op_sel_hi:[1,0,1] neg_lo:[0,0,1] neg_hi:[0,0,1]
	v_pk_add_f32 v[100:101], v[62:63], v[92:93]
	v_pk_add_f32 v[62:63], v[62:63], v[92:93] neg_lo:[0,1] neg_hi:[0,1]
	v_pk_add_f32 v[92:93], v[64:65], v[10:11]
	v_pk_add_f32 v[10:11], v[64:65], v[10:11] neg_lo:[0,1] neg_hi:[0,1]
	v_pk_add_f32 v[74:75], v[74:75], v[90:91] neg_lo:[0,1] neg_hi:[0,1]
	v_pk_mul_f32 v[64:65], v[10:11], s[60:61] op_sel:[1,0] op_sel_hi:[0,0] neg_hi:[1,0]
	v_pk_add_f32 v[88:89], v[110:111], v[114:115]
	v_pk_fma_f32 v[10:11], v[10:11], s[60:61], v[64:65] op_sel_hi:[1,0,1]
	v_pk_add_f32 v[64:65], v[76:77], v[96:97]
	v_pk_add_f32 v[76:77], v[76:77], v[96:97] neg_lo:[0,1] neg_hi:[0,1]
	v_pk_add_f32 v[90:91], v[110:111], v[114:115] neg_lo:[0,1] neg_hi:[0,1]
	v_xor_b32_e32 v97, 0x80000000, v76
	v_mov_b32_e32 v96, v77
	v_pk_add_f32 v[76:77], v[78:79], v[98:99]
	v_pk_add_f32 v[78:79], v[78:79], v[98:99] neg_lo:[0,1] neg_hi:[0,1]
	s_nop 0
	v_pk_mul_f32 v[98:99], v[78:79], s[60:61] op_sel_hi:[1,0]
	v_xor_b32_e32 v103, 0x80000000, v78
	v_mov_b32_e32 v102, v79
	v_pk_fma_f32 v[78:79], v[102:103], s[60:61], v[98:99] op_sel_hi:[1,0,1] neg_lo:[0,0,1] neg_hi:[0,0,1]
	v_pk_add_f32 v[98:99], v[6:7], v[94:95]
	v_pk_add_f32 v[6:7], v[6:7], v[94:95] neg_lo:[0,1] neg_hi:[0,1]
	v_pk_add_f32 v[94:95], v[66:67], v[4:5]
	v_pk_add_f32 v[4:5], v[66:67], v[4:5] neg_lo:[0,1] neg_hi:[0,1]
	s_nop 0
	v_pk_mul_f32 v[66:67], v[4:5], s[60:61] op_sel:[1,0] op_sel_hi:[0,0] neg_hi:[1,0]
	s_nop 0
	v_pk_fma_f32 v[4:5], v[4:5], s[60:61], v[66:67] op_sel_hi:[1,0,1]
	v_pk_add_f32 v[66:67], v[8:9], v[2:3]
	v_pk_add_f32 v[2:3], v[8:9], v[2:3] neg_lo:[0,1] neg_hi:[0,1]
	v_pk_add_f32 v[106:107], v[98:99], v[66:67] neg_lo:[0,1] neg_hi:[0,1]
	v_xor_b32_e32 v9, 0x80000000, v2
	v_mov_b32_e32 v8, v3
	v_pk_add_f32 v[2:3], v[80:81], v[82:83]
	v_pk_add_f32 v[80:81], v[80:81], v[82:83] neg_lo:[0,1] neg_hi:[0,1]
	v_pk_add_f32 v[108:109], v[94:95], v[2:3]
	v_pk_mul_f32 v[82:83], v[80:81], s[60:61] op_sel_hi:[1,0]
	s_nop 0
	v_pk_fma_f32 v[80:81], v[80:81], s[60:61], v[82:83] op_sel:[1,0,0] op_sel_hi:[0,0,1] neg_lo:[0,0,1] neg_hi:[1,0,1]
	v_pk_add_f32 v[82:83], v[100:101], v[64:65]
	v_pk_add_f32 v[64:65], v[100:101], v[64:65] neg_lo:[0,1] neg_hi:[0,1]
	v_pk_add_f32 v[100:101], v[92:93], v[76:77]
	v_pk_add_f32 v[76:77], v[92:93], v[76:77] neg_lo:[0,1] neg_hi:[0,1]
	v_pk_add_f32 v[102:103], v[10:11], v[78:79]
	v_xor_b32_e32 v93, 0x80000000, v76
	v_mov_b32_e32 v92, v77
	v_pk_add_f32 v[76:77], v[62:63], v[96:97]
	v_pk_add_f32 v[10:11], v[10:11], v[78:79] neg_lo:[0,1] neg_hi:[0,1]
	v_pk_add_f32 v[2:3], v[94:95], v[2:3] neg_lo:[0,1] neg_hi:[0,1]
	v_pk_add_f32 v[62:63], v[62:63], v[96:97] neg_lo:[0,1] neg_hi:[0,1]
	v_xor_b32_e32 v105, 0x80000000, v10
	v_mov_b32_e32 v104, v11
	v_pk_add_f32 v[10:11], v[98:99], v[66:67]
	v_xor_b32_e32 v111, 0x80000000, v2
	v_mov_b32_e32 v110, v3
	v_pk_add_f32 v[112:113], v[6:7], v[8:9]
	v_pk_add_f32 v[114:115], v[6:7], v[8:9] neg_lo:[0,1] neg_hi:[0,1]
	v_pk_add_f32 v[6:7], v[4:5], v[80:81]
	v_pk_add_f32 v[2:3], v[4:5], v[80:81] neg_lo:[0,1] neg_hi:[0,1]
	v_pk_add_f32 v[98:99], v[82:83], v[100:101]
	v_pk_add_f32 v[96:97], v[82:83], v[100:101] neg_lo:[0,1] neg_hi:[0,1]
	v_pk_add_f32 v[82:83], v[76:77], v[102:103]
	v_pk_add_f32 v[80:81], v[76:77], v[102:103] neg_lo:[0,1] neg_hi:[0,1]
	s_waitcnt vmcnt(7)
	v_mov_b64 v[100:101], v[164:165]
	v_mov_b64 v[102:103], v[166:167]
	v_pk_add_f32 v[78:79], v[62:63], v[104:105]
	v_pk_add_f32 v[76:77], v[62:63], v[104:105] neg_lo:[0,1] neg_hi:[0,1]
	v_xor_b32_e32 v5, 0x80000000, v2
	v_mov_b32_e32 v4, v3
	v_pk_add_f32 v[62:63], v[106:107], v[110:111]
	v_pk_add_f32 v[2:3], v[106:107], v[110:111] neg_lo:[0,1] neg_hi:[0,1]
	v_pk_add_f32 v[94:95], v[64:65], v[92:93]
	v_pk_add_f32 v[92:93], v[64:65], v[92:93] neg_lo:[0,1] neg_hi:[0,1]
	v_pk_add_f32 v[66:67], v[10:11], v[108:109]
	v_pk_add_f32 v[64:65], v[10:11], v[108:109] neg_lo:[0,1] neg_hi:[0,1]
	v_pk_add_f32 v[10:11], v[112:113], v[6:7]
	v_pk_add_f32 v[8:9], v[112:113], v[6:7] neg_lo:[0,1] neg_hi:[0,1]
	v_pk_add_f32 v[6:7], v[114:115], v[4:5]
	v_pk_add_f32 v[4:5], v[114:115], v[4:5] neg_lo:[0,1] neg_hi:[0,1]
	v_cvt_f32_f16_e32 v104, v100
	v_cvt_f32_f16_sdwa v100, v100 dst_sel:DWORD dst_unused:UNUSED_PAD src0_sel:WORD_1
	v_mul_f32_e32 v104, 0x38800000, v104
	v_mul_f32_e32 v100, 0x38800000, v100
	s_nop 0
	v_pk_mul_f32 v[106:107], v[12:13], v[100:101] op_sel:[1,0] op_sel_hi:[0,0] neg_lo:[1,0]
	v_cvt_f32_f16_e32 v100, v101
	v_cvt_f32_f16_sdwa v101, v101 dst_sel:DWORD dst_unused:UNUSED_PAD src0_sel:WORD_1
	v_pk_fma_f32 v[12:13], v[12:13], v[104:105], v[106:107] op_sel_hi:[1,0,1]
	v_xor_b32_e32 v106, 0x80000000, v15
	v_mov_b32_e32 v107, v14
	v_mul_f32_e32 v104, 0x38800000, v101
	v_mul_f32_e32 v100, 0x38800000, v100
	v_pk_mul_f32 v[104:105], v[106:107], v[104:105] op_sel_hi:[1,0]
	v_xor_b32_e32 v106, 0x80000000, v21
	v_pk_fma_f32 v[14:15], v[14:15], v[100:101], v[104:105] op_sel_hi:[1,0,1]
	v_cvt_f32_f16_sdwa v101, v102 dst_sel:DWORD dst_unused:UNUSED_PAD src0_sel:WORD_1
	v_cvt_f32_f16_e32 v100, v102
	s_nop 0
	s_nop 0
	v_mul_f32_e32 v102, 0x38800000, v101
	v_mul_f32_e32 v100, 0x38800000, v100
	v_pk_mul_f32 v[104:105], v[16:17], v[102:103] op_sel:[1,0] op_sel_hi:[0,0] neg_lo:[1,0]
	v_mov_b32_e32 v107, v20
	v_pk_fma_f32 v[16:17], v[16:17], v[100:101], v[104:105] op_sel_hi:[1,0,1]
	v_cvt_f32_f16_sdwa v101, v103 dst_sel:DWORD dst_unused:UNUSED_PAD src0_sel:WORD_1
	v_cvt_f32_f16_e32 v100, v103
	v_xor_b32_e32 v104, 0x80000000, v19
	v_mov_b32_e32 v105, v18
	v_mul_f32_e32 v102, 0x38800000, v101
	v_mul_f32_e32 v100, 0x38800000, v100
	v_pk_mul_f32 v[102:103], v[104:105], v[102:103] op_sel_hi:[1,0]
	s_nop 0
	v_pk_fma_f32 v[18:19], v[18:19], v[100:101], v[102:103] op_sel_hi:[1,0,1]
	s_waitcnt vmcnt(6)
	v_mov_b64 v[100:101], v[168:169]
	v_mov_b64 v[102:103], v[170:171]
	v_cvt_f32_f16_e32 v104, v100
	v_cvt_f32_f16_sdwa v100, v100 dst_sel:DWORD dst_unused:UNUSED_PAD src0_sel:WORD_1
	v_mul_f32_e32 v104, 0x38800000, v104
	v_mul_f32_e32 v100, 0x38800000, v100
	v_pk_mul_f32 v[106:107], v[106:107], v[100:101] op_sel_hi:[1,0]
	v_cvt_f32_f16_e32 v100, v101
	v_cvt_f32_f16_sdwa v101, v101 dst_sel:DWORD dst_unused:UNUSED_PAD src0_sel:WORD_1
	v_pk_fma_f32 v[20:21], v[20:21], v[104:105], v[106:107] op_sel_hi:[1,0,1]
	v_xor_b32_e32 v106, 0x80000000, v23
	v_mov_b32_e32 v107, v22
	v_mul_f32_e32 v104, 0x38800000, v101
	v_mul_f32_e32 v100, 0x38800000, v100
	v_pk_mul_f32 v[104:105], v[106:107], v[104:105] op_sel_hi:[1,0]
	v_xor_b32_e32 v106, 0x80000000, v69
	v_pk_fma_f32 v[22:23], v[22:23], v[100:101], v[104:105] op_sel_hi:[1,0,1]
	v_cvt_f32_f16_sdwa v101, v102 dst_sel:DWORD dst_unused:UNUSED_PAD src0_sel:WORD_1
	v_cvt_f32_f16_e32 v100, v102
	s_nop 0
	s_nop 0
	v_mul_f32_e32 v102, 0x38800000, v101
	v_mul_f32_e32 v100, 0x38800000, v100
	v_pk_mul_f32 v[104:105], v[24:25], v[102:103] op_sel:[1,0] op_sel_hi:[0,0] neg_lo:[1,0]
	v_mov_b32_e32 v107, v68
	v_pk_fma_f32 v[24:25], v[24:25], v[100:101], v[104:105] op_sel_hi:[1,0,1]
	v_cvt_f32_f16_sdwa v101, v103 dst_sel:DWORD dst_unused:UNUSED_PAD src0_sel:WORD_1
	v_cvt_f32_f16_e32 v100, v103
	v_xor_b32_e32 v104, 0x80000000, v27
	v_mov_b32_e32 v105, v26
	v_mul_f32_e32 v102, 0x38800000, v101
	v_mul_f32_e32 v100, 0x38800000, v100
	v_pk_mul_f32 v[102:103], v[104:105], v[102:103] op_sel_hi:[1,0]
	s_nop 0
	v_pk_fma_f32 v[26:27], v[26:27], v[100:101], v[102:103] op_sel_hi:[1,0,1]
	s_waitcnt vmcnt(5)
	v_mov_b64 v[100:101], v[172:173]
	v_mov_b64 v[102:103], v[174:175]
	v_cvt_f32_f16_e32 v104, v100
	v_cvt_f32_f16_sdwa v100, v100 dst_sel:DWORD dst_unused:UNUSED_PAD src0_sel:WORD_1
	v_mul_f32_e32 v104, 0x38800000, v104
	v_mul_f32_e32 v100, 0x38800000, v100
	v_pk_mul_f32 v[106:107], v[106:107], v[100:101] op_sel_hi:[1,0]
	v_cvt_f32_f16_e32 v100, v101
	v_cvt_f32_f16_sdwa v101, v101 dst_sel:DWORD dst_unused:UNUSED_PAD src0_sel:WORD_1
	v_pk_fma_f32 v[68:69], v[68:69], v[104:105], v[106:107] op_sel_hi:[1,0,1]
	v_xor_b32_e32 v106, 0x80000000, v71
	v_mov_b32_e32 v107, v70
	v_mul_f32_e32 v104, 0x38800000, v101
	v_mul_f32_e32 v100, 0x38800000, v100
	v_pk_mul_f32 v[104:105], v[106:107], v[104:105] op_sel_hi:[1,0]
	v_xor_b32_e32 v106, 0x80000000, v85
	v_pk_fma_f32 v[70:71], v[70:71], v[100:101], v[104:105] op_sel_hi:[1,0,1]
	v_cvt_f32_f16_sdwa v101, v102 dst_sel:DWORD dst_unused:UNUSED_PAD src0_sel:WORD_1
	v_cvt_f32_f16_e32 v100, v102
	s_nop 0
	s_nop 0
	v_mul_f32_e32 v102, 0x38800000, v101
	v_mul_f32_e32 v100, 0x38800000, v100
	v_pk_mul_f32 v[104:105], v[72:73], v[102:103] op_sel:[1,0] op_sel_hi:[0,0] neg_lo:[1,0]
	v_mov_b32_e32 v107, v84
	v_pk_fma_f32 v[72:73], v[72:73], v[100:101], v[104:105] op_sel_hi:[1,0,1]
	v_cvt_f32_f16_sdwa v101, v103 dst_sel:DWORD dst_unused:UNUSED_PAD src0_sel:WORD_1
	v_cvt_f32_f16_e32 v100, v103
	v_xor_b32_e32 v104, 0x80000000, v75
	v_mov_b32_e32 v105, v74
	v_mul_f32_e32 v102, 0x38800000, v101
	v_mul_f32_e32 v100, 0x38800000, v100
	v_pk_mul_f32 v[102:103], v[104:105], v[102:103] op_sel_hi:[1,0]
	s_nop 0
	v_pk_fma_f32 v[74:75], v[74:75], v[100:101], v[102:103] op_sel_hi:[1,0,1]
	s_waitcnt vmcnt(4)
	v_mov_b64 v[100:101], v[176:177]
	v_mov_b64 v[102:103], v[178:179]
	v_cvt_f32_f16_e32 v104, v100
	v_cvt_f32_f16_sdwa v100, v100 dst_sel:DWORD dst_unused:UNUSED_PAD src0_sel:WORD_1
	v_mul_f32_e32 v104, 0x38800000, v104
	v_mul_f32_e32 v100, 0x38800000, v100
	v_pk_mul_f32 v[106:107], v[106:107], v[100:101] op_sel_hi:[1,0]
	v_cvt_f32_f16_e32 v100, v101
	v_cvt_f32_f16_sdwa v101, v101 dst_sel:DWORD dst_unused:UNUSED_PAD src0_sel:WORD_1
	v_pk_fma_f32 v[84:85], v[84:85], v[104:105], v[106:107] op_sel_hi:[1,0,1]
	v_xor_b32_e32 v106, 0x80000000, v87
	v_mov_b32_e32 v107, v86
	v_mul_f32_e32 v104, 0x38800000, v101
	v_mul_f32_e32 v100, 0x38800000, v100
	v_pk_mul_f32 v[104:105], v[106:107], v[104:105] op_sel_hi:[1,0]
	v_xor_b32_e32 v106, 0x80000000, v99
	v_pk_fma_f32 v[86:87], v[86:87], v[100:101], v[104:105] op_sel_hi:[1,0,1]
	v_cvt_f32_f16_sdwa v101, v102 dst_sel:DWORD dst_unused:UNUSED_PAD src0_sel:WORD_1
	v_cvt_f32_f16_e32 v100, v102
	s_nop 0
	s_nop 0
	v_mul_f32_e32 v102, 0x38800000, v101
	v_mul_f32_e32 v100, 0x38800000, v100
	v_pk_mul_f32 v[104:105], v[88:89], v[102:103] op_sel:[1,0] op_sel_hi:[0,0] neg_lo:[1,0]
	v_mov_b32_e32 v107, v98
	v_pk_fma_f32 v[88:89], v[88:89], v[100:101], v[104:105] op_sel_hi:[1,0,1]
	v_cvt_f32_f16_sdwa v101, v103 dst_sel:DWORD dst_unused:UNUSED_PAD src0_sel:WORD_1
	v_cvt_f32_f16_e32 v100, v103
	v_xor_b32_e32 v104, 0x80000000, v91
	v_mov_b32_e32 v105, v90
	v_mul_f32_e32 v102, 0x38800000, v101
	v_mul_f32_e32 v100, 0x38800000, v100
	v_pk_mul_f32 v[102:103], v[104:105], v[102:103] op_sel_hi:[1,0]
	s_nop 0
	v_pk_fma_f32 v[90:91], v[90:91], v[100:101], v[102:103] op_sel_hi:[1,0,1]
	s_waitcnt vmcnt(3)
	v_mov_b64 v[100:101], v[180:181]
	v_mov_b64 v[102:103], v[182:183]
	v_cvt_f32_f16_e32 v104, v100
	v_cvt_f32_f16_sdwa v100, v100 dst_sel:DWORD dst_unused:UNUSED_PAD src0_sel:WORD_1
	v_mul_f32_e32 v104, 0x38800000, v104
	v_mul_f32_e32 v100, 0x38800000, v100
	v_pk_mul_f32 v[106:107], v[106:107], v[100:101] op_sel_hi:[1,0]
	v_cvt_f32_f16_e32 v100, v101
	v_cvt_f32_f16_sdwa v101, v101 dst_sel:DWORD dst_unused:UNUSED_PAD src0_sel:WORD_1
	v_pk_fma_f32 v[98:99], v[98:99], v[104:105], v[106:107] op_sel_hi:[1,0,1]
	v_xor_b32_e32 v106, 0x80000000, v97
	v_mov_b32_e32 v107, v96
	v_mul_f32_e32 v104, 0x38800000, v101
	v_mul_f32_e32 v100, 0x38800000, v100
	v_pk_mul_f32 v[104:105], v[106:107], v[104:105] op_sel_hi:[1,0]
	v_xor_b32_e32 v106, 0x80000000, v83
	v_pk_fma_f32 v[96:97], v[96:97], v[100:101], v[104:105] op_sel_hi:[1,0,1]
	v_cvt_f32_f16_sdwa v101, v102 dst_sel:DWORD dst_unused:UNUSED_PAD src0_sel:WORD_1
	v_cvt_f32_f16_e32 v100, v102
	s_nop 0
	s_nop 0
	v_mul_f32_e32 v102, 0x38800000, v101
	v_mul_f32_e32 v100, 0x38800000, v100
	v_pk_mul_f32 v[104:105], v[94:95], v[102:103] op_sel:[1,0] op_sel_hi:[0,0] neg_lo:[1,0]
	v_mov_b32_e32 v107, v82
	v_pk_fma_f32 v[94:95], v[94:95], v[100:101], v[104:105] op_sel_hi:[1,0,1]
	v_cvt_f32_f16_sdwa v101, v103 dst_sel:DWORD dst_unused:UNUSED_PAD src0_sel:WORD_1
	v_cvt_f32_f16_e32 v100, v103
	v_xor_b32_e32 v104, 0x80000000, v93
	v_mov_b32_e32 v105, v92
	v_mul_f32_e32 v102, 0x38800000, v101
	v_mul_f32_e32 v100, 0x38800000, v100
	v_pk_mul_f32 v[102:103], v[104:105], v[102:103] op_sel_hi:[1,0]
	s_nop 0
	v_pk_fma_f32 v[92:93], v[92:93], v[100:101], v[102:103] op_sel_hi:[1,0,1]
	s_waitcnt vmcnt(2)
	v_mov_b64 v[100:101], v[184:185]
	v_mov_b64 v[102:103], v[186:187]
	v_cvt_f32_f16_e32 v104, v100
	v_cvt_f32_f16_sdwa v100, v100 dst_sel:DWORD dst_unused:UNUSED_PAD src0_sel:WORD_1
	v_mul_f32_e32 v104, 0x38800000, v104
	v_mul_f32_e32 v100, 0x38800000, v100
	v_pk_mul_f32 v[106:107], v[106:107], v[100:101] op_sel_hi:[1,0]
	v_cvt_f32_f16_e32 v100, v101
	v_cvt_f32_f16_sdwa v101, v101 dst_sel:DWORD dst_unused:UNUSED_PAD src0_sel:WORD_1
	v_pk_fma_f32 v[82:83], v[82:83], v[104:105], v[106:107] op_sel_hi:[1,0,1]
	v_xor_b32_e32 v106, 0x80000000, v81
	v_mov_b32_e32 v107, v80
	v_mul_f32_e32 v104, 0x38800000, v101
	v_mul_f32_e32 v100, 0x38800000, v100
	v_pk_mul_f32 v[104:105], v[106:107], v[104:105] op_sel_hi:[1,0]
	v_xor_b32_e32 v106, 0x80000000, v67
	v_pk_fma_f32 v[80:81], v[80:81], v[100:101], v[104:105] op_sel_hi:[1,0,1]
	v_cvt_f32_f16_sdwa v101, v102 dst_sel:DWORD dst_unused:UNUSED_PAD src0_sel:WORD_1
	v_cvt_f32_f16_e32 v100, v102
	s_nop 0
	s_nop 0
	v_mul_f32_e32 v102, 0x38800000, v101
	v_mul_f32_e32 v100, 0x38800000, v100
	v_pk_mul_f32 v[104:105], v[78:79], v[102:103] op_sel:[1,0] op_sel_hi:[0,0] neg_lo:[1,0]
	v_mov_b32_e32 v107, v66
	v_pk_fma_f32 v[78:79], v[78:79], v[100:101], v[104:105] op_sel_hi:[1,0,1]
	v_cvt_f32_f16_sdwa v101, v103 dst_sel:DWORD dst_unused:UNUSED_PAD src0_sel:WORD_1
	v_cvt_f32_f16_e32 v100, v103
	v_xor_b32_e32 v104, 0x80000000, v77
	v_mov_b32_e32 v105, v76
	v_mul_f32_e32 v102, 0x38800000, v101
	v_mul_f32_e32 v100, 0x38800000, v100
	v_pk_mul_f32 v[102:103], v[104:105], v[102:103] op_sel_hi:[1,0]
	s_nop 0
	v_pk_fma_f32 v[76:77], v[76:77], v[100:101], v[102:103] op_sel_hi:[1,0,1]
	s_waitcnt vmcnt(1)
	v_mov_b64 v[100:101], v[188:189]
	v_mov_b64 v[102:103], v[190:191]
	v_cvt_f32_f16_e32 v104, v100
	v_cvt_f32_f16_sdwa v100, v100 dst_sel:DWORD dst_unused:UNUSED_PAD src0_sel:WORD_1
	v_mul_f32_e32 v104, 0x38800000, v104
	v_mul_f32_e32 v100, 0x38800000, v100
	v_pk_mul_f32 v[106:107], v[106:107], v[100:101] op_sel_hi:[1,0]
	v_cvt_f32_f16_e32 v100, v101
	v_cvt_f32_f16_sdwa v101, v101 dst_sel:DWORD dst_unused:UNUSED_PAD src0_sel:WORD_1
	v_pk_fma_f32 v[66:67], v[66:67], v[104:105], v[106:107] op_sel_hi:[1,0,1]
	v_xor_b32_e32 v106, 0x80000000, v65
	v_mov_b32_e32 v107, v64
	v_mul_f32_e32 v104, 0x38800000, v101
	v_mul_f32_e32 v100, 0x38800000, v100
	v_pk_mul_f32 v[104:105], v[106:107], v[104:105] op_sel_hi:[1,0]
	s_nop 0
	v_pk_fma_f32 v[64:65], v[64:65], v[100:101], v[104:105] op_sel_hi:[1,0,1]
	v_cvt_f32_f16_sdwa v101, v102 dst_sel:DWORD dst_unused:UNUSED_PAD src0_sel:WORD_1
	v_cvt_f32_f16_e32 v100, v102
	s_nop 0
	s_nop 0
	v_mul_f32_e32 v102, 0x38800000, v101
	v_mul_f32_e32 v100, 0x38800000, v100
	v_pk_mul_f32 v[104:105], v[62:63], v[102:103] op_sel:[1,0] op_sel_hi:[0,0] neg_lo:[1,0]
	s_nop 0
	v_pk_fma_f32 v[62:63], v[62:63], v[100:101], v[104:105] op_sel_hi:[1,0,1]
	v_cvt_f32_f16_sdwa v101, v103 dst_sel:DWORD dst_unused:UNUSED_PAD src0_sel:WORD_1
	v_cvt_f32_f16_e32 v100, v103
	v_xor_b32_e32 v104, 0x80000000, v3
	v_mov_b32_e32 v105, v2
	v_mul_f32_e32 v102, 0x38800000, v101
	v_mul_f32_e32 v100, 0x38800000, v100
	v_pk_mul_f32 v[102:103], v[104:105], v[102:103] op_sel_hi:[1,0]
	v_xor_b32_e32 v104, 0x80000000, v11
	v_pk_fma_f32 v[100:101], v[2:3], v[100:101], v[102:103] op_sel_hi:[1,0,1]
	s_waitcnt vmcnt(0)
	v_mov_b64 v[0:1], v[192:193]
	v_mov_b64 v[2:3], v[194:195]
	v_mov_b32_e32 v105, v10
	v_cvt_f32_f16_e32 v102, v0
	v_cvt_f32_f16_sdwa v0, v0 dst_sel:DWORD dst_unused:UNUSED_PAD src0_sel:WORD_1
	v_mul_f32_e32 v102, 0x38800000, v102
	v_mul_f32_e32 v0, 0x38800000, v0
	v_pk_mul_f32 v[104:105], v[104:105], v[0:1] op_sel_hi:[1,0]
	v_cvt_f32_f16_e32 v0, v1
	v_cvt_f32_f16_sdwa v1, v1 dst_sel:DWORD dst_unused:UNUSED_PAD src0_sel:WORD_1
	v_pk_fma_f32 v[10:11], v[10:11], v[102:103], v[104:105] op_sel_hi:[1,0,1]
	v_xor_b32_e32 v104, 0x80000000, v9
	v_mov_b32_e32 v105, v8
	v_mul_f32_e32 v102, 0x38800000, v1
	v_mul_f32_e32 v0, 0x38800000, v0
	v_pk_mul_f32 v[102:103], v[104:105], v[102:103] op_sel_hi:[1,0]
	s_nop 0
	v_pk_fma_f32 v[0:1], v[8:9], v[0:1], v[102:103] op_sel_hi:[1,0,1]
	v_cvt_f32_f16_e32 v8, v2
	v_cvt_f32_f16_sdwa v2, v2 dst_sel:DWORD dst_unused:UNUSED_PAD src0_sel:WORD_1
	s_nop 0
	s_nop 0
	v_mul_f32_e32 v8, 0x38800000, v8
	v_mul_f32_e32 v2, 0x38800000, v2
	s_nop 0
	v_pk_mul_f32 v[102:103], v[6:7], v[2:3] op_sel:[1,0] op_sel_hi:[0,0] neg_lo:[1,0]
	v_cvt_f32_f16_e32 v2, v3
	v_cvt_f32_f16_sdwa v3, v3 dst_sel:DWORD dst_unused:UNUSED_PAD src0_sel:WORD_1
	v_pk_fma_f32 v[6:7], v[6:7], v[8:9], v[102:103] op_sel_hi:[1,0,1]
	v_xor_b32_e32 v102, 0x80000000, v5
	v_mov_b32_e32 v103, v4
	v_mul_f32_e32 v8, 0x38800000, v3
	v_mul_f32_e32 v2, 0x38800000, v2
	v_pk_mul_f32 v[8:9], v[102:103], v[8:9] op_sel_hi:[1,0]
	v_mov_b32_e32 v102, v146
	v_pk_fma_f32 v[2:3], v[4:5], v[2:3], v[8:9] op_sel_hi:[1,0,1]
	v_pk_add_f32 v[4:5], v[12:13], v[14:15]
	v_pk_add_f32 v[8:9], v[12:13], v[14:15] neg_lo:[0,1] neg_hi:[0,1]
	v_pk_add_f32 v[12:13], v[16:17], v[18:19]
	v_pk_add_f32 v[14:15], v[16:17], v[18:19] neg_lo:[0,1] neg_hi:[0,1]
	v_pk_add_f32 v[16:17], v[20:21], v[22:23]
	v_pk_add_f32 v[18:19], v[20:21], v[22:23] neg_lo:[0,1] neg_hi:[0,1]
	v_pk_add_f32 v[20:21], v[24:25], v[26:27]
	v_pk_add_f32 v[22:23], v[24:25], v[26:27] neg_lo:[0,1] neg_hi:[0,1]
	v_pk_add_f32 v[24:25], v[68:69], v[70:71]
	v_pk_add_f32 v[26:27], v[68:69], v[70:71] neg_lo:[0,1] neg_hi:[0,1]
	v_pk_add_f32 v[68:69], v[72:73], v[74:75]
	v_pk_add_f32 v[70:71], v[72:73], v[74:75] neg_lo:[0,1] neg_hi:[0,1]
	v_pk_add_f32 v[72:73], v[84:85], v[86:87]
	v_pk_add_f32 v[74:75], v[84:85], v[86:87] neg_lo:[0,1] neg_hi:[0,1]
	v_pk_add_f32 v[84:85], v[88:89], v[90:91]
	v_pk_add_f32 v[86:87], v[88:89], v[90:91] neg_lo:[0,1] neg_hi:[0,1]
	v_pk_add_f32 v[88:89], v[4:5], v[12:13]
	v_pk_add_f32 v[4:5], v[4:5], v[12:13] neg_lo:[0,1] neg_hi:[0,1]
	v_xor_b32_e32 v12, 0x80000000, v15
	v_mov_b32_e32 v13, v14
	v_pk_add_f32 v[14:15], v[8:9], v[12:13]
	v_pk_add_f32 v[8:9], v[8:9], v[12:13] neg_lo:[0,1] neg_hi:[0,1]
	v_pk_add_f32 v[12:13], v[16:17], v[20:21]
	v_pk_add_f32 v[16:17], v[16:17], v[20:21] neg_lo:[0,1] neg_hi:[0,1]
	v_xor_b32_e32 v20, 0x80000000, v23
	v_mov_b32_e32 v21, v22
	v_pk_add_f32 v[22:23], v[18:19], v[20:21]
	v_pk_add_f32 v[18:19], v[18:19], v[20:21] neg_lo:[0,1] neg_hi:[0,1]
	v_pk_add_f32 v[20:21], v[24:25], v[68:69]
	v_pk_add_f32 v[24:25], v[24:25], v[68:69] neg_lo:[0,1] neg_hi:[0,1]
	v_xor_b32_e32 v68, 0x80000000, v71
	v_mov_b32_e32 v69, v70
	v_pk_add_f32 v[70:71], v[26:27], v[68:69]
	v_pk_add_f32 v[26:27], v[26:27], v[68:69] neg_lo:[0,1] neg_hi:[0,1]
	v_pk_add_f32 v[68:69], v[72:73], v[84:85]
	v_pk_add_f32 v[72:73], v[72:73], v[84:85] neg_lo:[0,1] neg_hi:[0,1]
	v_xor_b32_e32 v84, 0x80000000, v87
	v_mov_b32_e32 v85, v86
	v_pk_add_f32 v[86:87], v[74:75], v[84:85]
	v_pk_add_f32 v[74:75], v[74:75], v[84:85] neg_lo:[0,1] neg_hi:[0,1]
	v_pk_add_f32 v[84:85], v[88:89], v[12:13]
	v_pk_add_f32 v[12:13], v[88:89], v[12:13] neg_lo:[0,1] neg_hi:[0,1]
	v_pk_mul_f32 v[88:89], v[22:23], s[60:61] op_sel:[1,0] op_sel_hi:[0,0] neg_lo:[1,0]
	v_xor_b32_e32 v90, 0x80000000, v19
	v_pk_fma_f32 v[22:23], v[22:23], s[60:61], v[88:89] op_sel_hi:[1,0,1]
	v_mov_b32_e32 v91, v18
	v_pk_add_f32 v[88:89], v[14:15], v[22:23]
	v_pk_add_f32 v[14:15], v[14:15], v[22:23] neg_lo:[0,1] neg_hi:[0,1]
	v_xor_b32_e32 v22, 0x80000000, v17
	v_mov_b32_e32 v23, v16
	v_pk_add_f32 v[16:17], v[4:5], v[22:23]
	v_pk_add_f32 v[4:5], v[4:5], v[22:23] neg_lo:[0,1] neg_hi:[0,1]
	v_pk_mul_f32 v[22:23], v[18:19], s[60:61] op_sel_hi:[1,0]
	s_nop 0
	v_pk_fma_f32 v[18:19], v[90:91], s[60:61], v[22:23] op_sel_hi:[1,0,1] neg_lo:[0,0,1] neg_hi:[0,0,1]
	v_xor_b32_e32 v90, 0x80000000, v75
	v_pk_add_f32 v[22:23], v[8:9], v[18:19]
	v_pk_add_f32 v[8:9], v[8:9], v[18:19] neg_lo:[0,1] neg_hi:[0,1]
	v_pk_add_f32 v[18:19], v[20:21], v[68:69]
	v_pk_add_f32 v[20:21], v[20:21], v[68:69] neg_lo:[0,1] neg_hi:[0,1]
	v_pk_mul_f32 v[68:69], v[86:87], s[60:61] op_sel:[1,0] op_sel_hi:[0,0] neg_lo:[1,0]
	v_mov_b32_e32 v91, v74
	v_pk_fma_f32 v[68:69], v[86:87], s[60:61], v[68:69] op_sel_hi:[1,0,1]
	s_nop 0
	v_pk_add_f32 v[86:87], v[70:71], v[68:69]
	v_pk_add_f32 v[68:69], v[70:71], v[68:69] neg_lo:[0,1] neg_hi:[0,1]
	v_xor_b32_e32 v70, 0x80000000, v73
	v_mov_b32_e32 v71, v72
	v_pk_add_f32 v[72:73], v[24:25], v[70:71]
	v_pk_add_f32 v[24:25], v[24:25], v[70:71] neg_lo:[0,1] neg_hi:[0,1]
	v_pk_mul_f32 v[70:71], v[74:75], s[60:61] op_sel_hi:[1,0]
	s_nop 0
	v_pk_fma_f32 v[70:71], v[90:91], s[60:61], v[70:71] op_sel_hi:[1,0,1] neg_lo:[0,0,1] neg_hi:[0,0,1]
	v_xor_b32_e32 v90, 0x80000000, v69
	v_pk_add_f32 v[74:75], v[26:27], v[70:71]
	v_pk_add_f32 v[26:27], v[26:27], v[70:71] neg_lo:[0,1] neg_hi:[0,1]
	v_pk_add_f32 v[70:71], v[84:85], v[18:19]
	v_pk_add_f32 v[18:19], v[84:85], v[18:19] neg_lo:[0,1] neg_hi:[0,1]
	v_pk_mul_f32 v[84:85], v[86:87], s[54:55] op_sel:[1,0] op_sel_hi:[0,0] neg_lo:[1,0]
	v_mov_b32_e32 v91, v68
	v_pk_fma_f32 v[84:85], v[86:87], s[52:53], v[84:85] op_sel_hi:[1,0,1]
	s_nop 0
	v_pk_add_f32 v[86:87], v[88:89], v[84:85]
	v_pk_add_f32 v[84:85], v[88:89], v[84:85] neg_lo:[0,1] neg_hi:[0,1]
	v_pk_mul_f32 v[88:89], v[72:73], s[60:61] op_sel:[1,0] op_sel_hi:[0,0] neg_lo:[1,0]
	s_nop 0
	v_pk_fma_f32 v[72:73], v[72:73], s[60:61], v[88:89] op_sel_hi:[1,0,1]
	s_nop 0
	v_pk_add_f32 v[88:89], v[16:17], v[72:73]
	v_pk_add_f32 v[16:17], v[16:17], v[72:73] neg_lo:[0,1] neg_hi:[0,1]
	v_pk_mul_f32 v[72:73], v[74:75], s[52:53] op_sel:[1,0] op_sel_hi:[0,0] neg_lo:[1,0]
	s_nop 0
	v_pk_fma_f32 v[72:73], v[74:75], s[54:55], v[72:73] op_sel_hi:[1,0,1]
	s_nop 0
	v_pk_add_f32 v[74:75], v[22:23], v[72:73]
	v_pk_add_f32 v[22:23], v[22:23], v[72:73] neg_lo:[0,1] neg_hi:[0,1]
	v_xor_b32_e32 v72, 0x80000000, v21
	v_mov_b32_e32 v73, v20
	v_pk_add_f32 v[20:21], v[12:13], v[72:73]
	v_pk_add_f32 v[12:13], v[12:13], v[72:73] neg_lo:[0,1] neg_hi:[0,1]
	v_pk_mul_f32 v[72:73], v[68:69], s[54:55] op_sel_hi:[1,0]
	s_nop 0
	v_pk_fma_f32 v[68:69], v[90:91], s[52:53], v[72:73] op_sel_hi:[1,0,1] neg_lo:[0,0,1] neg_hi:[0,0,1]
	v_xor_b32_e32 v90, 0x80000000, v25
	v_pk_add_f32 v[72:73], v[14:15], v[68:69]
	v_pk_add_f32 v[14:15], v[14:15], v[68:69] neg_lo:[0,1] neg_hi:[0,1]
	v_pk_mul_f32 v[68:69], v[24:25], s[60:61] op_sel_hi:[1,0]
	v_mov_b32_e32 v91, v24
	v_pk_fma_f32 v[24:25], v[90:91], s[60:61], v[68:69] op_sel_hi:[1,0,1] neg_lo:[0,0,1] neg_hi:[0,0,1]
	s_nop 0
	v_pk_add_f32 v[68:69], v[4:5], v[24:25]
	v_pk_add_f32 v[4:5], v[4:5], v[24:25] neg_lo:[0,1] neg_hi:[0,1]
	v_pk_mul_f32 v[24:25], v[26:27], s[52:53] op_sel_hi:[1,0]
	s_nop 0
	v_pk_fma_f32 v[24:25], v[26:27], s[54:55], v[24:25] op_sel:[1,0,0] op_sel_hi:[0,0,1] neg_lo:[1,0,1] neg_hi:[0,0,1]
	v_pk_add_f32 v[90:91], v[98:99], v[96:97] neg_lo:[0,1] neg_hi:[0,1]
	v_pk_add_f32 v[26:27], v[8:9], v[24:25]
	v_pk_add_f32 v[8:9], v[8:9], v[24:25] neg_lo:[0,1] neg_hi:[0,1]
	v_pk_add_f32 v[24:25], v[98:99], v[96:97]
	v_pk_add_f32 v[96:97], v[94:95], v[92:93]
	v_pk_add_f32 v[92:93], v[94:95], v[92:93] neg_lo:[0,1] neg_hi:[0,1]
	v_pk_add_f32 v[94:95], v[82:83], v[80:81]
	v_pk_add_f32 v[80:81], v[82:83], v[80:81] neg_lo:[0,1] neg_hi:[0,1]
	v_pk_add_f32 v[82:83], v[78:79], v[76:77]
	v_pk_add_f32 v[76:77], v[78:79], v[76:77] neg_lo:[0,1] neg_hi:[0,1]
	v_pk_add_f32 v[98:99], v[10:11], v[0:1]
	v_pk_add_f32 v[0:1], v[10:11], v[0:1] neg_lo:[0,1] neg_hi:[0,1]
	v_pk_add_f32 v[10:11], v[6:7], v[2:3]
	v_pk_add_f32 v[2:3], v[6:7], v[2:3] neg_lo:[0,1] neg_hi:[0,1]
	v_pk_add_f32 v[6:7], v[24:25], v[96:97]
	v_pk_add_f32 v[24:25], v[24:25], v[96:97] neg_lo:[0,1] neg_hi:[0,1]
	v_xor_b32_e32 v96, 0x80000000, v93
	v_mov_b32_e32 v97, v92
	v_pk_add_f32 v[78:79], v[66:67], v[64:65]
	v_pk_add_f32 v[64:65], v[66:67], v[64:65] neg_lo:[0,1] neg_hi:[0,1]
	v_pk_add_f32 v[66:67], v[62:63], v[100:101]
	v_pk_add_f32 v[62:63], v[62:63], v[100:101] neg_lo:[0,1] neg_hi:[0,1]
	v_pk_add_f32 v[92:93], v[90:91], v[96:97]
	v_pk_add_f32 v[90:91], v[90:91], v[96:97] neg_lo:[0,1] neg_hi:[0,1]
	v_pk_add_f32 v[96:97], v[94:95], v[82:83]
	v_pk_add_f32 v[82:83], v[94:95], v[82:83] neg_lo:[0,1] neg_hi:[0,1]
	v_xor_b32_e32 v94, 0x80000000, v77
	v_mov_b32_e32 v95, v76
	v_pk_add_f32 v[76:77], v[80:81], v[94:95]
	v_pk_add_f32 v[80:81], v[80:81], v[94:95] neg_lo:[0,1] neg_hi:[0,1]
	v_pk_add_f32 v[94:95], v[78:79], v[66:67]
	v_pk_add_f32 v[66:67], v[78:79], v[66:67] neg_lo:[0,1] neg_hi:[0,1]
	v_xor_b32_e32 v78, 0x80000000, v63
	v_mov_b32_e32 v79, v62
	v_pk_add_f32 v[62:63], v[64:65], v[78:79]
	v_pk_add_f32 v[64:65], v[64:65], v[78:79] neg_lo:[0,1] neg_hi:[0,1]
	v_pk_add_f32 v[78:79], v[98:99], v[10:11]
	v_pk_add_f32 v[10:11], v[98:99], v[10:11] neg_lo:[0,1] neg_hi:[0,1]
	v_xor_b32_e32 v98, 0x80000000, v3
	v_mov_b32_e32 v99, v2
	v_pk_add_f32 v[2:3], v[0:1], v[98:99]
	v_pk_add_f32 v[0:1], v[0:1], v[98:99] neg_lo:[0,1] neg_hi:[0,1]
	v_pk_add_f32 v[98:99], v[6:7], v[96:97]
	v_pk_add_f32 v[6:7], v[6:7], v[96:97] neg_lo:[0,1] neg_hi:[0,1]
	v_pk_mul_f32 v[96:97], v[76:77], s[60:61] op_sel:[1,0] op_sel_hi:[0,0] neg_lo:[1,0]
	v_xor_b32_e32 v100, 0x80000000, v81
	v_pk_fma_f32 v[76:77], v[76:77], s[60:61], v[96:97] op_sel_hi:[1,0,1]
	v_mov_b32_e32 v101, v80
	v_pk_add_f32 v[96:97], v[92:93], v[76:77]
	v_pk_add_f32 v[76:77], v[92:93], v[76:77] neg_lo:[0,1] neg_hi:[0,1]
	v_xor_b32_e32 v92, 0x80000000, v83
	v_mov_b32_e32 v93, v82
	v_pk_add_f32 v[82:83], v[24:25], v[92:93]
	v_pk_add_f32 v[24:25], v[24:25], v[92:93] neg_lo:[0,1] neg_hi:[0,1]
	v_pk_mul_f32 v[92:93], v[80:81], s[60:61] op_sel_hi:[1,0]
	s_nop 0
	v_pk_fma_f32 v[80:81], v[100:101], s[60:61], v[92:93] op_sel_hi:[1,0,1] neg_lo:[0,0,1] neg_hi:[0,0,1]
	v_xor_b32_e32 v100, 0x80000000, v1
	v_pk_add_f32 v[92:93], v[90:91], v[80:81]
	v_pk_add_f32 v[80:81], v[90:91], v[80:81] neg_lo:[0,1] neg_hi:[0,1]
	v_pk_add_f32 v[90:91], v[94:95], v[78:79]
	v_pk_add_f32 v[78:79], v[94:95], v[78:79] neg_lo:[0,1] neg_hi:[0,1]
	v_pk_mul_f32 v[94:95], v[2:3], s[60:61] op_sel:[1,0] op_sel_hi:[0,0] neg_lo:[1,0]
	v_mov_b32_e32 v101, v0
	v_pk_fma_f32 v[2:3], v[2:3], s[60:61], v[94:95] op_sel_hi:[1,0,1]
	s_nop 0
	v_pk_add_f32 v[94:95], v[62:63], v[2:3]
	v_pk_add_f32 v[2:3], v[62:63], v[2:3] neg_lo:[0,1] neg_hi:[0,1]
	v_xor_b32_e32 v62, 0x80000000, v11
	v_mov_b32_e32 v63, v10
	v_pk_add_f32 v[10:11], v[66:67], v[62:63]
	v_pk_add_f32 v[62:63], v[66:67], v[62:63] neg_lo:[0,1] neg_hi:[0,1]
	v_pk_mul_f32 v[66:67], v[0:1], s[60:61] op_sel_hi:[1,0]
	s_nop 0
	v_pk_fma_f32 v[0:1], v[100:101], s[60:61], v[66:67] op_sel_hi:[1,0,1] neg_lo:[0,0,1] neg_hi:[0,0,1]
	v_xor_b32_e32 v100, 0x80000000, v3
	v_pk_add_f32 v[66:67], v[64:65], v[0:1]
	v_pk_add_f32 v[0:1], v[64:65], v[0:1] neg_lo:[0,1] neg_hi:[0,1]
	v_pk_add_f32 v[64:65], v[98:99], v[90:91]
	v_pk_add_f32 v[90:91], v[98:99], v[90:91] neg_lo:[0,1] neg_hi:[0,1]
	v_pk_mul_f32 v[98:99], v[94:95], s[54:55] op_sel:[1,0] op_sel_hi:[0,0] neg_lo:[1,0]
	v_mov_b32_e32 v101, v2
	v_pk_fma_f32 v[94:95], v[94:95], s[52:53], v[98:99] op_sel_hi:[1,0,1]
	s_nop 0
	v_pk_add_f32 v[98:99], v[96:97], v[94:95]
	v_pk_add_f32 v[94:95], v[96:97], v[94:95] neg_lo:[0,1] neg_hi:[0,1]
	v_pk_mul_f32 v[96:97], v[10:11], s[60:61] op_sel:[1,0] op_sel_hi:[0,0] neg_lo:[1,0]
	s_nop 0
	v_pk_fma_f32 v[10:11], v[10:11], s[60:61], v[96:97] op_sel_hi:[1,0,1]
	s_nop 0
	v_pk_add_f32 v[96:97], v[82:83], v[10:11]
	v_pk_add_f32 v[10:11], v[82:83], v[10:11] neg_lo:[0,1] neg_hi:[0,1]
	v_pk_mul_f32 v[82:83], v[66:67], s[52:53] op_sel:[1,0] op_sel_hi:[0,0] neg_lo:[1,0]
	s_nop 0
	v_pk_fma_f32 v[66:67], v[66:67], s[54:55], v[82:83] op_sel_hi:[1,0,1]
	s_nop 0
	v_pk_add_f32 v[82:83], v[92:93], v[66:67]
	v_pk_add_f32 v[66:67], v[92:93], v[66:67] neg_lo:[0,1] neg_hi:[0,1]
	v_xor_b32_e32 v92, 0x80000000, v79
	v_mov_b32_e32 v93, v78
	v_pk_add_f32 v[78:79], v[6:7], v[92:93]
	v_pk_add_f32 v[6:7], v[6:7], v[92:93] neg_lo:[0,1] neg_hi:[0,1]
	v_pk_mul_f32 v[92:93], v[2:3], s[54:55] op_sel_hi:[1,0]
	s_nop 0
	v_pk_fma_f32 v[2:3], v[100:101], s[52:53], v[92:93] op_sel_hi:[1,0,1] neg_lo:[0,0,1] neg_hi:[0,0,1]
	v_xor_b32_e32 v100, 0x80000000, v63
	v_pk_add_f32 v[92:93], v[76:77], v[2:3]
	v_pk_add_f32 v[2:3], v[76:77], v[2:3] neg_lo:[0,1] neg_hi:[0,1]
	v_pk_mul_f32 v[76:77], v[62:63], s[60:61] op_sel_hi:[1,0]
	v_mov_b32_e32 v101, v62
	v_pk_fma_f32 v[62:63], v[100:101], s[60:61], v[76:77] op_sel_hi:[1,0,1] neg_lo:[0,0,1] neg_hi:[0,0,1]
	v_xor_b32_e32 v100, 0x80000000, v1
	v_pk_add_f32 v[76:77], v[24:25], v[62:63]
	v_pk_add_f32 v[24:25], v[24:25], v[62:63] neg_lo:[0,1] neg_hi:[0,1]
	v_pk_mul_f32 v[62:63], v[0:1], s[52:53] op_sel_hi:[1,0]
	v_mov_b32_e32 v101, v0
	v_pk_fma_f32 v[0:1], v[100:101], s[54:55], v[62:63] op_sel_hi:[1,0,1] neg_lo:[0,0,1] neg_hi:[0,0,1]
	v_bfe_u32 v100, v102, 1, 4
	v_pk_add_f32 v[62:63], v[80:81], v[0:1]
	v_pk_add_f32 v[0:1], v[80:81], v[0:1] neg_lo:[0,1] neg_hi:[0,1]
	v_lshlrev_b32_e32 v80, 4, v102
	v_lshrrev_b32_e32 v81, 1, v102
	v_bitop3_b32 v101, v81, v80, 16 bitop3:0x6c
	v_lshl_add_u32 v101, v101, 3, 16
	v_lshlrev_b32_e32 v100, 3, v100
	v_add_u32_e32 v102, v101, v100
	ds_write_b64 v102, v[70:71]
	v_bitop3_b32 v70, v81, 1, 15 bitop3:0x6c
	v_lshlrev_b32_e32 v70, 3, v70
	v_add_u32_e32 v71, v101, v70
	ds_write_b64 v71, v[86:87]
	v_bitop3_b32 v71, v81, 2, 15 bitop3:0x6c
	v_lshlrev_b32_e32 v71, 3, v71
	v_add_u32_e32 v86, v101, v71
	ds_write_b64 v86, v[88:89]
	v_bitop3_b32 v86, v81, 3, 15 bitop3:0x6c
	v_lshlrev_b32_e32 v86, 3, v86
	v_add_u32_e32 v87, v101, v86
	ds_write_b64 v87, v[74:75]
	v_bitop3_b32 v74, v81, 4, 15 bitop3:0x6c
	v_lshlrev_b32_e32 v74, 3, v74
	v_add_u32_e32 v75, v101, v74
	ds_write_b64 v75, v[20:21]
	v_bitop3_b32 v20, v81, 5, 15 bitop3:0x6c
	v_lshlrev_b32_e32 v20, 3, v20
	v_add_u32_e32 v21, v101, v20
	ds_write_b64 v21, v[72:73]
	v_bitop3_b32 v21, v81, 6, 15 bitop3:0x6c
	v_lshlrev_b32_e32 v21, 3, v21
	v_add_u32_e32 v72, v101, v21
	ds_write_b64 v72, v[68:69]
	v_bitop3_b32 v68, v81, 7, 15 bitop3:0x6c
	v_lshlrev_b32_e32 v68, 3, v68
	v_add_u32_e32 v69, v101, v68
	ds_write_b64 v69, v[26:27]
	v_bitop3_b32 v26, v81, 8, 15 bitop3:0x6c
	v_lshlrev_b32_e32 v26, 3, v26
	v_add_u32_e32 v27, v101, v26
	ds_write_b64 v27, v[18:19]
	v_bitop3_b32 v18, v81, 9, 15 bitop3:0x6c
	v_lshlrev_b32_e32 v18, 3, v18
	v_add_u32_e32 v19, v101, v18
	ds_write_b64 v19, v[84:85]
	v_bitop3_b32 v19, v81, 10, 15 bitop3:0x6c
	v_lshlrev_b32_e32 v19, 3, v19
	v_add_u32_e32 v27, v101, v19
	ds_write_b64 v27, v[16:17]
	v_bitop3_b32 v16, v81, 11, 15 bitop3:0x6c
	v_lshlrev_b32_e32 v16, 3, v16
	v_add_u32_e32 v17, v101, v16
	ds_write_b64 v17, v[22:23]
	v_bitop3_b32 v17, v81, 12, 15 bitop3:0x6c
	v_lshlrev_b32_e32 v17, 3, v17
	v_add_u32_e32 v22, v101, v17
	ds_write_b64 v22, v[12:13]
	v_bitop3_b32 v12, v81, 13, 15 bitop3:0x6c
	v_lshlrev_b32_e32 v12, 3, v12
	v_add_u32_e32 v13, v101, v12
	ds_write_b64 v13, v[14:15]
	v_bitop3_b32 v13, v81, 14, 15 bitop3:0x6c
	v_lshlrev_b32_e32 v13, 3, v13
	v_add_u32_e32 v14, v101, v13
	ds_write_b64 v14, v[4:5]
	v_bitop3_b32 v4, v81, 15, v81 bitop3:0xc
	v_lshlrev_b32_e32 v4, 3, v4
	v_add_u32_e32 v5, v101, v4
	ds_write_b64 v5, v[8:9]
	v_add_u32_e32 v5, 0x2000, v80
	v_bitop3_b32 v5, v5, v81, 16 bitop3:0x78
	v_lshl_add_u32 v5, v5, 3, 16
	v_add_u32_e32 v8, v5, v100
	ds_write_b64 v8, v[64:65]
	v_add_u32_e32 v8, v5, v70
	ds_write_b64 v8, v[98:99]
	v_add_u32_e32 v8, v5, v71
	ds_write_b64 v8, v[96:97]
	v_add_u32_e32 v8, v5, v86
	ds_write_b64 v8, v[82:83]
	v_add_u32_e32 v8, v5, v74
	ds_write_b64 v8, v[78:79]
	v_add_u32_e32 v8, v5, v20
	ds_write_b64 v8, v[92:93]
	v_add_u32_e32 v8, v5, v21
	ds_write_b64 v8, v[76:77]
	v_add_u32_e32 v8, v5, v68
	ds_write_b64 v8, v[62:63]
	v_add_u32_e32 v8, v5, v26
	ds_write_b64 v8, v[90:91]
	v_add_u32_e32 v8, v5, v18
	ds_write_b64 v8, v[94:95]
	v_add_u32_e32 v8, v5, v19
	ds_write_b64 v8, v[10:11]
	v_add_u32_e32 v8, v5, v16
	ds_write_b64 v8, v[66:67]
	v_add_u32_e32 v8, v5, v17
	ds_write_b64 v8, v[6:7]
	v_add_u32_e32 v6, v5, v12
	ds_write_b64 v6, v[2:3]
	v_add_u32_e32 v2, v5, v13
	ds_write_b64 v2, v[24:25]
	v_add_u32_e32 v2, v5, v4
	v_mov_b32_e32 v22, v146
	ds_write_b64 v2, v[0:1]
	s_waitcnt lgkmcnt(0)
	s_barrier
	s_nop 0
	v_lshlrev_b32_e32 v0, 5, v22
	v_and_b32_e32 v2, 0xfffffe00, v0
	v_and_or_b32 v0, v22, 16, v2
	v_bitop3_b32 v2, v2, 16, v22 bitop3:0x34
	v_bitop3_b32 v6, v22, 4, 15 bitop3:0x6c
	v_bitop3_b32 v14, v22, 8, 15 bitop3:0x6c
	v_lshl_add_u32 v23, v0, 3, 16
	v_lshl_add_u32 v65, v2, 3, 16
	v_lshlrev_b32_e32 v6, 3, v6
	v_lshlrev_b32_e32 v14, 3, v14
	v_bitop3_b32 v2, v22, 1, 15 bitop3:0x6c
	v_add_u32_e32 v105, v23, v6
	v_add_u32_e32 v106, v65, v6
	v_bitop3_b32 v6, v22, 5, 15 bitop3:0x6c
	v_add_u32_e32 v113, v23, v14
	v_add_u32_e32 v114, v65, v14
	v_bitop3_b32 v14, v22, 9, 15 bitop3:0x6c
	v_lshlrev_b32_e32 v2, 3, v2
	v_lshlrev_b32_e32 v6, 3, v6
	v_lshlrev_b32_e32 v14, 3, v14
	v_add_u32_e32 v99, v23, v2
	v_add_u32_e32 v100, v65, v2
	v_bitop3_b32 v2, v22, 2, 15 bitop3:0x6c
	v_add_u32_e32 v107, v23, v6
	v_add_u32_e32 v108, v65, v6
	v_bitop3_b32 v6, v22, 6, 15 bitop3:0x6c
	v_add_u32_e32 v115, v23, v14
	v_add_u32_e32 v116, v65, v14
	v_bitop3_b32 v14, v22, 10, 15 bitop3:0x6c
	v_bitop3_b32 v26, v22, 12, 15 bitop3:0x6c
	v_lshlrev_b32_e32 v2, 3, v2
	v_lshlrev_b32_e32 v6, 3, v6
	v_lshlrev_b32_e32 v14, 3, v14
	v_lshlrev_b32_e32 v26, 3, v26
	v_and_b32_e32 v64, 15, v22
	v_add_u32_e32 v101, v23, v2
	v_add_u32_e32 v102, v65, v2
	v_bitop3_b32 v2, v22, 3, 15 bitop3:0x6c
	v_add_u32_e32 v109, v23, v6
	v_add_u32_e32 v110, v65, v6
	v_bitop3_b32 v6, v22, 7, 15 bitop3:0x6c
	v_add_u32_e32 v117, v23, v14
	v_add_u32_e32 v118, v65, v14
	v_bitop3_b32 v14, v22, 11, 15 bitop3:0x6c
	v_add_u32_e32 v121, v23, v26
	v_add_u32_e32 v122, v65, v26
	v_bitop3_b32 v26, v22, 13, 15 bitop3:0x6c
	v_bitop3_b32 v66, v22, 14, 15 bitop3:0x6c
	v_bitop3_b32 v22, v22, 15, v22 bitop3:0xc
	v_lshlrev_b32_e32 v3, 3, v64
	v_lshlrev_b32_e32 v2, 3, v2
	v_lshlrev_b32_e32 v6, 3, v6
	v_lshlrev_b32_e32 v14, 3, v14
	v_lshlrev_b32_e32 v26, 3, v26
	v_lshlrev_b32_e32 v66, 3, v66
	v_lshlrev_b32_e32 v22, 3, v22
	v_add_u32_e32 v67, v23, v3
	v_add_u32_e32 v98, v65, v3
	v_add_u32_e32 v103, v23, v2
	v_add_u32_e32 v104, v65, v2
	v_add_u32_e32 v111, v23, v6
	v_add_u32_e32 v112, v65, v6
	v_add_u32_e32 v119, v23, v14
	v_add_u32_e32 v120, v65, v14
	v_add_u32_e32 v123, v23, v26
	v_add_u32_e32 v124, v65, v26
	v_add_u32_e32 v125, v23, v66
	v_add_u32_e32 v126, v65, v66
	v_add_u32_e32 v127, v23, v22
	v_add_u32_e32 v128, v65, v22
	ds_read_b64 v[0:1], v67
	ds_read_b64 v[12:13], v98
	ds_read_b64 v[74:75], v99 offset:256
	ds_read_b64 v[4:5], v100 offset:256
	ds_read_b64 v[76:77], v101 offset:512
	ds_read_b64 v[10:11], v102 offset:512
	ds_read_b64 v[70:71], v103 offset:768
	ds_read_b64 v[2:3], v104 offset:768
	ds_read_b64 v[62:63], v105 offset:1024
	ds_read_b64 v[20:21], v106 offset:1024
	ds_read_b64 v[90:91], v107 offset:1280
	ds_read_b64 v[8:9], v108 offset:1280
	ds_read_b64 v[84:85], v109 offset:1536
	ds_read_b64 v[16:17], v110 offset:1536
	ds_read_b64 v[82:83], v111 offset:1792
	ds_read_b64 v[6:7], v112 offset:1792
	ds_read_b64 v[24:25], v113 offset:2048
	ds_read_b64 v[78:79], v114 offset:2048
	ds_read_b64 v[96:97], v115 offset:2304
	ds_read_b64 v[18:19], v116 offset:2304
	ds_read_b64 v[86:87], v117 offset:2560
	ds_read_b64 v[72:73], v118 offset:2560
	ds_read_b64 v[130:131], v119 offset:2816
	ds_read_b64 v[14:15], v120 offset:2816
	ds_read_b64 v[80:81], v121 offset:3072
	ds_read_b64 v[92:93], v122 offset:3072
	ds_read_b64 v[132:133], v123 offset:3328
	ds_read_b64 v[26:27], v124 offset:3328
	ds_read_b64 v[94:95], v125 offset:3584
	ds_read_b64 v[88:89], v126 offset:3584
	ds_read_b64 v[134:135], v127 offset:3840
	ds_read_b64 v[22:23], v128 offset:3840
	s_waitcnt lgkmcnt(14)
	s_nop 0
	v_cvt_f32_i32_e32 v64, v64
	s_nop 0
	v_mul_f32_e32 v64, 0x3b000000, v64
	v_cos_f32_e32 v68, v64
	v_sin_f32_e32 v69, v64
	v_add_f32_e32 v66, v68, v68
	v_pk_mul_f32 v[64:65], v[68:69], v[68:69]
	v_mul_f32_e32 v66, v69, v66
	s_nop 0
	s_nop 0
	v_mov_b32_e32 v140, v69
	v_pk_add_f32 v[64:65], v[64:65], v[64:65] op_sel:[0,1] op_sel_hi:[0,1] neg_lo:[0,1] neg_hi:[0,1]
	v_pk_mul_f32 v[136:137], v[68:69], v[66:67] op_sel:[1,0] op_sel_hi:[0,0] neg_lo:[1,0]
	v_pk_mul_f32 v[138:139], v[24:25], v[140:141] op_sel:[1,0] op_sel_hi:[0,0] neg_lo:[1,0]
	v_pk_fma_f32 v[136:137], v[68:69], v[64:65], v[136:137]
	v_pk_fma_f32 v[24:25], v[24:25], v[68:69], v[138:139] op_sel_hi:[1,0,1]
	v_pk_mul_f32 v[68:69], v[66:67], s[46:47] op_sel_hi:[0,1]
	v_pk_fma_f32 v[138:139], v[64:65], s[40:41], v[68:69]
	s_nop 0
	v_pk_mul_f32 v[68:69], v[62:63], v[138:139] op_sel:[1,1] op_sel_hi:[0,1] neg_lo:[1,0]
	s_nop 0
	v_pk_fma_f32 v[68:69], v[62:63], v[138:139], v[68:69] op_sel_hi:[1,0,1]
	v_pk_mul_f32 v[62:63], v[66:67], v[136:137] op_sel:[0,1] op_sel_hi:[0,0] neg_lo:[0,1]
	v_pk_fma_f32 v[140:141], v[64:65], v[136:137], v[62:63]
	s_waitcnt lgkmcnt(7)
	v_pk_mul_f32 v[62:63], v[80:81], v[136:137] op_sel:[1,1] op_sel_hi:[0,1] neg_lo:[1,0]
	s_nop 0
	v_pk_fma_f32 v[62:63], v[80:81], v[136:137], v[62:63] op_sel_hi:[1,0,1]
	v_pk_mul_f32 v[80:81], v[66:67], v[138:139] op_sel:[0,1] op_sel_hi:[0,0] neg_lo:[0,1]
	v_pk_fma_f32 v[136:137], v[64:65], v[138:139], v[80:81]
	s_nop 0
	v_pk_mul_f32 v[80:81], v[76:77], v[136:137] op_sel:[1,1] op_sel_hi:[0,1] neg_lo:[1,0]
	s_nop 0
	v_pk_fma_f32 v[80:81], v[76:77], v[136:137], v[80:81] op_sel_hi:[1,0,1]
	v_pk_mul_f32 v[76:77], v[66:67], v[140:141] op_sel:[0,1] op_sel_hi:[0,0] neg_lo:[0,1]
	v_pk_fma_f32 v[138:139], v[64:65], v[140:141], v[76:77]
	v_pk_mul_f32 v[76:77], v[86:87], v[140:141] op_sel:[1,1] op_sel_hi:[0,1] neg_lo:[1,0]
	s_nop 0
	v_pk_fma_f32 v[76:77], v[86:87], v[140:141], v[76:77] op_sel_hi:[1,0,1]
	v_pk_mul_f32 v[86:87], v[66:67], v[136:137] op_sel:[0,1] op_sel_hi:[0,0] neg_lo:[0,1]
	v_pk_fma_f32 v[136:137], v[64:65], v[136:137], v[86:87]
	s_nop 0
	v_pk_mul_f32 v[86:87], v[84:85], v[136:137] op_sel:[1,1] op_sel_hi:[0,1] neg_lo:[1,0]
	s_nop 0
	v_pk_fma_f32 v[86:87], v[84:85], v[136:137], v[86:87] op_sel_hi:[1,0,1]
	v_pk_mul_f32 v[84:85], v[66:67], v[138:139] op_sel:[0,1] op_sel_hi:[0,0] neg_lo:[0,1]
	v_pk_fma_f32 v[140:141], v[64:65], v[138:139], v[84:85]
	s_waitcnt lgkmcnt(3)
	v_pk_mul_f32 v[84:85], v[94:95], v[138:139] op_sel:[1,1] op_sel_hi:[0,1] neg_lo:[1,0]
	s_nop 0
	v_pk_fma_f32 v[84:85], v[94:95], v[138:139], v[84:85] op_sel_hi:[1,0,1]
	v_pk_mul_f32 v[94:95], v[66:67], v[136:137] op_sel:[0,1] op_sel_hi:[0,0] neg_lo:[0,1]
	v_pk_fma_f32 v[136:137], v[64:65], v[136:137], v[94:95]
	s_nop 0
	v_pk_mul_f32 v[94:95], v[74:75], v[136:137] op_sel:[1,1] op_sel_hi:[0,1] neg_lo:[1,0]
	s_nop 0
	v_pk_fma_f32 v[94:95], v[74:75], v[136:137], v[94:95] op_sel_hi:[1,0,1]
	v_pk_mul_f32 v[74:75], v[66:67], v[140:141] op_sel:[0,1] op_sel_hi:[0,0] neg_lo:[0,1]
	v_pk_fma_f32 v[138:139], v[64:65], v[140:141], v[74:75]
	v_pk_mul_f32 v[74:75], v[96:97], v[140:141] op_sel:[1,1] op_sel_hi:[0,1] neg_lo:[1,0]
	s_nop 0
	v_pk_fma_f32 v[74:75], v[96:97], v[140:141], v[74:75] op_sel_hi:[1,0,1]
	v_pk_mul_f32 v[96:97], v[66:67], v[136:137] op_sel:[0,1] op_sel_hi:[0,0] neg_lo:[0,1]
	v_pk_fma_f32 v[136:137], v[64:65], v[136:137], v[96:97]
	s_nop 0
	v_pk_mul_f32 v[96:97], v[90:91], v[136:137] op_sel:[1,1] op_sel_hi:[0,1] neg_lo:[1,0]
	s_nop 0
	v_pk_fma_f32 v[96:97], v[90:91], v[136:137], v[96:97] op_sel_hi:[1,0,1]
	v_pk_mul_f32 v[90:91], v[66:67], v[138:139] op_sel:[0,1] op_sel_hi:[0,0] neg_lo:[0,1]
	v_pk_fma_f32 v[140:141], v[64:65], v[138:139], v[90:91]
	v_pk_mul_f32 v[90:91], v[132:133], v[138:139] op_sel:[1,1] op_sel_hi:[0,1] neg_lo:[1,0]
	s_nop 0
	v_pk_fma_f32 v[90:91], v[132:133], v[138:139], v[90:91] op_sel_hi:[1,0,1]
	v_pk_mul_f32 v[132:133], v[66:67], v[136:137] op_sel:[0,1] op_sel_hi:[0,0] neg_lo:[0,1]
	s_nop 0
	v_pk_fma_f32 v[132:133], v[64:65], v[136:137], v[132:133]
	v_pk_mul_f32 v[138:139], v[130:131], v[140:141] op_sel:[1,1] op_sel_hi:[0,1] neg_lo:[1,0]
	v_pk_mul_f32 v[136:137], v[70:71], v[132:133] op_sel:[1,1] op_sel_hi:[0,1] neg_lo:[1,0]
	v_pk_fma_f32 v[130:131], v[130:131], v[140:141], v[138:139] op_sel_hi:[1,0,1]
	v_pk_fma_f32 v[70:71], v[70:71], v[132:133], v[136:137] op_sel_hi:[1,0,1]
	v_pk_mul_f32 v[138:139], v[66:67], v[132:133] op_sel:[0,1] op_sel_hi:[0,0] neg_lo:[0,1]
	v_pk_mul_f32 v[136:137], v[66:67], v[140:141] op_sel:[0,1] op_sel_hi:[0,0] neg_lo:[0,1]
	v_pk_fma_f32 v[132:133], v[64:65], v[132:133], v[138:139]
	v_pk_fma_f32 v[136:137], v[64:65], v[140:141], v[136:137]
	v_pk_mul_f32 v[138:139], v[82:83], v[132:133] op_sel:[1,1] op_sel_hi:[0,1] neg_lo:[1,0]
	s_waitcnt lgkmcnt(1)
	v_pk_fma_f32 v[82:83], v[82:83], v[132:133], v[138:139] op_sel_hi:[1,0,1]
	v_pk_mul_f32 v[138:139], v[66:67], v[136:137] op_sel:[0,1] op_sel_hi:[0,0] neg_lo:[0,1]
	v_pk_mul_f32 v[140:141], v[134:135], v[136:137] op_sel:[1,1] op_sel_hi:[0,1] neg_lo:[1,0]
	v_pk_fma_f32 v[138:139], v[64:65], v[136:137], v[138:139]
	v_pk_fma_f32 v[134:135], v[134:135], v[136:137], v[140:141] op_sel_hi:[1,0,1]
	v_pk_mul_f32 v[136:137], v[66:67], v[132:133] op_sel:[0,1] op_sel_hi:[0,0] neg_lo:[0,1]
	v_pk_fma_f32 v[132:133], v[64:65], v[132:133], v[136:137]
	s_nop 0
	v_pk_mul_f32 v[136:137], v[12:13], v[132:133] op_sel:[1,1] op_sel_hi:[0,1] neg_lo:[1,0]
	s_nop 0
	v_pk_fma_f32 v[12:13], v[12:13], v[132:133], v[136:137] op_sel_hi:[1,0,1]
	v_pk_mul_f32 v[136:137], v[66:67], v[138:139] op_sel:[0,1] op_sel_hi:[0,0] neg_lo:[0,1]
	v_pk_mul_f32 v[140:141], v[78:79], v[138:139] op_sel:[1,1] op_sel_hi:[0,1] neg_lo:[1,0]
	v_pk_fma_f32 v[136:137], v[64:65], v[138:139], v[136:137]
	v_pk_fma_f32 v[78:79], v[78:79], v[138:139], v[140:141] op_sel_hi:[1,0,1]
	v_pk_mul_f32 v[138:139], v[66:67], v[132:133] op_sel:[0,1] op_sel_hi:[0,0] neg_lo:[0,1]
	v_pk_fma_f32 v[132:133], v[64:65], v[132:133], v[138:139]
	s_nop 0
	v_pk_mul_f32 v[138:139], v[20:21], v[132:133] op_sel:[1,1] op_sel_hi:[0,1] neg_lo:[1,0]
	s_nop 0
	v_pk_fma_f32 v[20:21], v[20:21], v[132:133], v[138:139] op_sel_hi:[1,0,1]
	v_pk_mul_f32 v[138:139], v[66:67], v[136:137] op_sel:[0,1] op_sel_hi:[0,0] neg_lo:[0,1]
	v_pk_mul_f32 v[140:141], v[92:93], v[136:137] op_sel:[1,1] op_sel_hi:[0,1] neg_lo:[1,0]
	v_pk_fma_f32 v[138:139], v[64:65], v[136:137], v[138:139]
	v_pk_fma_f32 v[92:93], v[92:93], v[136:137], v[140:141] op_sel_hi:[1,0,1]
	v_pk_mul_f32 v[136:137], v[66:67], v[132:133] op_sel:[0,1] op_sel_hi:[0,0] neg_lo:[0,1]
	v_pk_fma_f32 v[132:133], v[64:65], v[132:133], v[136:137]
	s_nop 0
	v_pk_mul_f32 v[136:137], v[10:11], v[132:133] op_sel:[1,1] op_sel_hi:[0,1] neg_lo:[1,0]
	s_nop 0
	v_pk_fma_f32 v[10:11], v[10:11], v[132:133], v[136:137] op_sel_hi:[1,0,1]
	v_pk_mul_f32 v[136:137], v[66:67], v[138:139] op_sel:[0,1] op_sel_hi:[0,0] neg_lo:[0,1]
	v_pk_mul_f32 v[140:141], v[72:73], v[138:139] op_sel:[1,1] op_sel_hi:[0,1] neg_lo:[1,0]
	v_pk_fma_f32 v[136:137], v[64:65], v[138:139], v[136:137]
	v_pk_fma_f32 v[72:73], v[72:73], v[138:139], v[140:141] op_sel_hi:[1,0,1]
	v_pk_mul_f32 v[138:139], v[66:67], v[132:133] op_sel:[0,1] op_sel_hi:[0,0] neg_lo:[0,1]
	v_pk_fma_f32 v[132:133], v[64:65], v[132:133], v[138:139]
	s_nop 0
	v_pk_mul_f32 v[138:139], v[16:17], v[132:133] op_sel:[1,1] op_sel_hi:[0,1] neg_lo:[1,0]
	s_nop 0
	v_pk_fma_f32 v[16:17], v[16:17], v[132:133], v[138:139] op_sel_hi:[1,0,1]
	v_pk_mul_f32 v[138:139], v[66:67], v[136:137] op_sel:[0,1] op_sel_hi:[0,0] neg_lo:[0,1]
	v_pk_mul_f32 v[140:141], v[88:89], v[136:137] op_sel:[1,1] op_sel_hi:[0,1] neg_lo:[1,0]
	v_pk_fma_f32 v[138:139], v[64:65], v[136:137], v[138:139]
	v_pk_fma_f32 v[88:89], v[88:89], v[136:137], v[140:141] op_sel_hi:[1,0,1]
	v_pk_mul_f32 v[136:137], v[66:67], v[132:133] op_sel:[0,1] op_sel_hi:[0,0] neg_lo:[0,1]
	v_pk_fma_f32 v[132:133], v[64:65], v[132:133], v[136:137]
	s_nop 0
	v_pk_mul_f32 v[136:137], v[4:5], v[132:133] op_sel:[1,1] op_sel_hi:[0,1] neg_lo:[1,0]
	s_nop 0
	v_pk_fma_f32 v[4:5], v[4:5], v[132:133], v[136:137] op_sel_hi:[1,0,1]
	v_pk_mul_f32 v[136:137], v[66:67], v[138:139] op_sel:[0,1] op_sel_hi:[0,0] neg_lo:[0,1]
	v_pk_mul_f32 v[140:141], v[18:19], v[138:139] op_sel:[1,1] op_sel_hi:[0,1] neg_lo:[1,0]
	v_pk_fma_f32 v[136:137], v[64:65], v[138:139], v[136:137]
	v_pk_fma_f32 v[18:19], v[18:19], v[138:139], v[140:141] op_sel_hi:[1,0,1]
	v_pk_mul_f32 v[138:139], v[66:67], v[132:133] op_sel:[0,1] op_sel_hi:[0,0] neg_lo:[0,1]
	v_pk_fma_f32 v[132:133], v[64:65], v[132:133], v[138:139]
	s_nop 0
	v_pk_mul_f32 v[138:139], v[8:9], v[132:133] op_sel:[1,1] op_sel_hi:[0,1] neg_lo:[1,0]
	s_nop 0
	v_pk_fma_f32 v[8:9], v[8:9], v[132:133], v[138:139] op_sel_hi:[1,0,1]
	v_pk_mul_f32 v[138:139], v[66:67], v[136:137] op_sel:[0,1] op_sel_hi:[0,0] neg_lo:[0,1]
	v_pk_mul_f32 v[140:141], v[26:27], v[136:137] op_sel:[1,1] op_sel_hi:[0,1] neg_lo:[1,0]
	v_pk_fma_f32 v[138:139], v[64:65], v[136:137], v[138:139]
	v_pk_fma_f32 v[26:27], v[26:27], v[136:137], v[140:141] op_sel_hi:[1,0,1]
	v_pk_mul_f32 v[136:137], v[66:67], v[132:133] op_sel:[0,1] op_sel_hi:[0,0] neg_lo:[0,1]
	v_pk_fma_f32 v[132:133], v[64:65], v[132:133], v[136:137]
	s_nop 0
	v_pk_mul_f32 v[136:137], v[2:3], v[132:133] op_sel:[1,1] op_sel_hi:[0,1] neg_lo:[1,0]
	s_nop 0
	v_pk_fma_f32 v[2:3], v[2:3], v[132:133], v[136:137] op_sel_hi:[1,0,1]
	v_pk_mul_f32 v[136:137], v[66:67], v[138:139] op_sel:[0,1] op_sel_hi:[0,0] neg_lo:[0,1]
	v_pk_mul_f32 v[140:141], v[14:15], v[138:139] op_sel:[1,1] op_sel_hi:[0,1] neg_lo:[1,0]
	v_pk_fma_f32 v[136:137], v[64:65], v[138:139], v[136:137]
	v_pk_fma_f32 v[14:15], v[14:15], v[138:139], v[140:141] op_sel_hi:[1,0,1]
	v_pk_mul_f32 v[138:139], v[66:67], v[132:133] op_sel:[0,1] op_sel_hi:[0,0] neg_lo:[0,1]
	v_pk_fma_f32 v[64:65], v[64:65], v[132:133], v[138:139]
	s_nop 0
	v_pk_mul_f32 v[132:133], v[6:7], v[64:65] op_sel:[1,1] op_sel_hi:[0,1] neg_lo:[1,0]
	s_nop 0
	v_pk_fma_f32 v[6:7], v[6:7], v[64:65], v[132:133] op_sel_hi:[1,0,1]
	s_waitcnt lgkmcnt(0)
	v_pk_mul_f32 v[64:65], v[22:23], v[136:137] op_sel:[1,1] op_sel_hi:[0,1] neg_lo:[1,0]
	s_nop 0
	v_pk_fma_f32 v[22:23], v[22:23], v[136:137], v[64:65] op_sel_hi:[1,0,1]
	v_pk_add_f32 v[64:65], v[0:1], v[12:13]
	v_pk_add_f32 v[0:1], v[0:1], v[12:13] neg_lo:[0,1] neg_hi:[0,1]
	v_pk_add_f32 v[12:13], v[94:95], v[4:5]
	v_pk_add_f32 v[4:5], v[94:95], v[4:5] neg_lo:[0,1] neg_hi:[0,1]
	v_pk_add_f32 v[94:95], v[80:81], v[10:11]
	v_pk_add_f32 v[10:11], v[80:81], v[10:11] neg_lo:[0,1] neg_hi:[0,1]
	v_pk_add_f32 v[80:81], v[70:71], v[2:3]
	v_pk_add_f32 v[2:3], v[70:71], v[2:3] neg_lo:[0,1] neg_hi:[0,1]
	v_pk_add_f32 v[132:133], v[64:65], v[12:13]
	v_pk_add_f32 v[12:13], v[64:65], v[12:13] neg_lo:[0,1] neg_hi:[0,1]
	v_xor_b32_e32 v64, 0x80000000, v5
	v_mov_b32_e32 v65, v4
	v_pk_add_f32 v[70:71], v[68:69], v[20:21]
	v_pk_add_f32 v[20:21], v[68:69], v[20:21] neg_lo:[0,1] neg_hi:[0,1]
	v_pk_add_f32 v[68:69], v[96:97], v[8:9]
	v_pk_add_f32 v[8:9], v[96:97], v[8:9] neg_lo:[0,1] neg_hi:[0,1]
	v_pk_add_f32 v[4:5], v[0:1], v[64:65]
	v_pk_add_f32 v[0:1], v[0:1], v[64:65] neg_lo:[0,1] neg_hi:[0,1]
	v_pk_add_f32 v[64:65], v[94:95], v[80:81]
	v_pk_add_f32 v[80:81], v[94:95], v[80:81] neg_lo:[0,1] neg_hi:[0,1]
	v_xor_b32_e32 v94, 0x80000000, v3
	v_mov_b32_e32 v95, v2
	v_pk_add_f32 v[96:97], v[86:87], v[16:17]
	v_pk_add_f32 v[16:17], v[86:87], v[16:17] neg_lo:[0,1] neg_hi:[0,1]
	v_pk_add_f32 v[86:87], v[82:83], v[6:7]
	v_pk_add_f32 v[6:7], v[82:83], v[6:7] neg_lo:[0,1] neg_hi:[0,1]
	v_pk_add_f32 v[2:3], v[10:11], v[94:95]
	v_pk_add_f32 v[10:11], v[10:11], v[94:95] neg_lo:[0,1] neg_hi:[0,1]
	v_pk_add_f32 v[94:95], v[70:71], v[68:69]
	v_pk_add_f32 v[68:69], v[70:71], v[68:69] neg_lo:[0,1] neg_hi:[0,1]
	v_xor_b32_e32 v70, 0x80000000, v9
	v_mov_b32_e32 v71, v8
	v_pk_add_f32 v[82:83], v[24:25], v[78:79]
	v_pk_add_f32 v[24:25], v[24:25], v[78:79] neg_lo:[0,1] neg_hi:[0,1]
	v_pk_add_f32 v[78:79], v[74:75], v[18:19]
	v_pk_add_f32 v[18:19], v[74:75], v[18:19] neg_lo:[0,1] neg_hi:[0,1]
	v_pk_add_f32 v[8:9], v[20:21], v[70:71]
	v_pk_add_f32 v[20:21], v[20:21], v[70:71] neg_lo:[0,1] neg_hi:[0,1]
	v_pk_add_f32 v[70:71], v[96:97], v[86:87]
	v_pk_add_f32 v[86:87], v[96:97], v[86:87] neg_lo:[0,1] neg_hi:[0,1]
	v_xor_b32_e32 v96, 0x80000000, v7
	v_mov_b32_e32 v97, v6
	v_pk_add_f32 v[74:75], v[76:77], v[72:73]
	v_pk_add_f32 v[72:73], v[76:77], v[72:73] neg_lo:[0,1] neg_hi:[0,1]
	v_pk_add_f32 v[76:77], v[130:131], v[14:15]
	v_pk_add_f32 v[14:15], v[130:131], v[14:15] neg_lo:[0,1] neg_hi:[0,1]
	v_pk_add_f32 v[6:7], v[16:17], v[96:97]
	v_pk_add_f32 v[16:17], v[16:17], v[96:97] neg_lo:[0,1] neg_hi:[0,1]
	v_pk_add_f32 v[96:97], v[82:83], v[78:79]
	v_pk_add_f32 v[78:79], v[82:83], v[78:79] neg_lo:[0,1] neg_hi:[0,1]
	v_xor_b32_e32 v82, 0x80000000, v19
	v_mov_b32_e32 v83, v18
	v_pk_add_f32 v[130:131], v[62:63], v[92:93]
	v_pk_add_f32 v[62:63], v[62:63], v[92:93] neg_lo:[0,1] neg_hi:[0,1]
	v_pk_add_f32 v[92:93], v[90:91], v[26:27]
	v_pk_add_f32 v[26:27], v[90:91], v[26:27] neg_lo:[0,1] neg_hi:[0,1]
	v_pk_add_f32 v[18:19], v[24:25], v[82:83]
	v_pk_add_f32 v[24:25], v[24:25], v[82:83] neg_lo:[0,1] neg_hi:[0,1]
	v_pk_add_f32 v[82:83], v[74:75], v[76:77]
	v_pk_add_f32 v[74:75], v[74:75], v[76:77] neg_lo:[0,1] neg_hi:[0,1]
	v_xor_b32_e32 v76, 0x80000000, v15
	v_mov_b32_e32 v77, v14
	v_pk_add_f32 v[90:91], v[84:85], v[88:89]
	v_pk_add_f32 v[84:85], v[84:85], v[88:89] neg_lo:[0,1] neg_hi:[0,1]
	v_pk_add_f32 v[88:89], v[134:135], v[22:23]
	v_pk_add_f32 v[22:23], v[134:135], v[22:23] neg_lo:[0,1] neg_hi:[0,1]
	v_pk_add_f32 v[14:15], v[72:73], v[76:77]
	v_pk_add_f32 v[72:73], v[72:73], v[76:77] neg_lo:[0,1] neg_hi:[0,1]
	v_pk_add_f32 v[76:77], v[130:131], v[92:93]
	v_pk_add_f32 v[92:93], v[130:131], v[92:93] neg_lo:[0,1] neg_hi:[0,1]
	v_xor_b32_e32 v130, 0x80000000, v27
	v_mov_b32_e32 v131, v26
	v_pk_add_f32 v[26:27], v[62:63], v[130:131]
	v_pk_add_f32 v[62:63], v[62:63], v[130:131] neg_lo:[0,1] neg_hi:[0,1]
	v_pk_add_f32 v[130:131], v[90:91], v[88:89]
	v_pk_add_f32 v[88:89], v[90:91], v[88:89] neg_lo:[0,1] neg_hi:[0,1]
	v_xor_b32_e32 v90, 0x80000000, v23
	v_mov_b32_e32 v91, v22
	v_pk_add_f32 v[22:23], v[84:85], v[90:91]
	v_pk_add_f32 v[84:85], v[84:85], v[90:91] neg_lo:[0,1] neg_hi:[0,1]
	v_pk_add_f32 v[90:91], v[132:133], v[64:65]
	v_pk_add_f32 v[64:65], v[132:133], v[64:65] neg_lo:[0,1] neg_hi:[0,1]
	v_pk_mul_f32 v[132:133], v[2:3], s[60:61] op_sel:[1,0] op_sel_hi:[0,0] neg_lo:[1,0]
	v_xor_b32_e32 v134, 0x80000000, v11
	v_pk_fma_f32 v[2:3], v[2:3], s[60:61], v[132:133] op_sel_hi:[1,0,1]
	v_mov_b32_e32 v135, v10
	v_pk_add_f32 v[132:133], v[4:5], v[2:3]
	v_pk_add_f32 v[2:3], v[4:5], v[2:3] neg_lo:[0,1] neg_hi:[0,1]
	v_xor_b32_e32 v4, 0x80000000, v81
	v_mov_b32_e32 v5, v80
	v_pk_add_f32 v[80:81], v[12:13], v[4:5]
	v_pk_add_f32 v[4:5], v[12:13], v[4:5] neg_lo:[0,1] neg_hi:[0,1]
	v_pk_mul_f32 v[12:13], v[10:11], s[60:61] op_sel_hi:[1,0]
	s_nop 0
	v_pk_fma_f32 v[10:11], v[134:135], s[60:61], v[12:13] op_sel_hi:[1,0,1] neg_lo:[0,0,1] neg_hi:[0,0,1]
	v_xor_b32_e32 v134, 0x80000000, v17
	v_pk_add_f32 v[12:13], v[0:1], v[10:11]
	v_pk_add_f32 v[0:1], v[0:1], v[10:11] neg_lo:[0,1] neg_hi:[0,1]
	v_pk_add_f32 v[10:11], v[94:95], v[70:71]
	v_pk_add_f32 v[70:71], v[94:95], v[70:71] neg_lo:[0,1] neg_hi:[0,1]
	v_pk_mul_f32 v[94:95], v[6:7], s[60:61] op_sel:[1,0] op_sel_hi:[0,0] neg_lo:[1,0]
	v_mov_b32_e32 v135, v16
	v_pk_fma_f32 v[6:7], v[6:7], s[60:61], v[94:95] op_sel_hi:[1,0,1]
	s_nop 0
	v_pk_add_f32 v[94:95], v[8:9], v[6:7]
	v_pk_add_f32 v[6:7], v[8:9], v[6:7] neg_lo:[0,1] neg_hi:[0,1]
	v_xor_b32_e32 v8, 0x80000000, v87
	v_mov_b32_e32 v9, v86
	v_pk_add_f32 v[86:87], v[68:69], v[8:9]
	v_pk_add_f32 v[8:9], v[68:69], v[8:9] neg_lo:[0,1] neg_hi:[0,1]
	v_pk_mul_f32 v[68:69], v[16:17], s[60:61] op_sel_hi:[1,0]
	s_nop 0
	v_pk_fma_f32 v[16:17], v[134:135], s[60:61], v[68:69] op_sel_hi:[1,0,1] neg_lo:[0,0,1] neg_hi:[0,0,1]
	v_xor_b32_e32 v134, 0x80000000, v73
	v_pk_add_f32 v[68:69], v[20:21], v[16:17]
	v_pk_add_f32 v[16:17], v[20:21], v[16:17] neg_lo:[0,1] neg_hi:[0,1]
	v_pk_add_f32 v[20:21], v[96:97], v[82:83]
	v_pk_add_f32 v[82:83], v[96:97], v[82:83] neg_lo:[0,1] neg_hi:[0,1]
	v_pk_mul_f32 v[96:97], v[14:15], s[60:61] op_sel:[1,0] op_sel_hi:[0,0] neg_lo:[1,0]
	v_mov_b32_e32 v135, v72
	v_pk_fma_f32 v[14:15], v[14:15], s[60:61], v[96:97] op_sel_hi:[1,0,1]
	s_nop 0
	v_pk_add_f32 v[96:97], v[18:19], v[14:15]
	v_pk_add_f32 v[14:15], v[18:19], v[14:15] neg_lo:[0,1] neg_hi:[0,1]
	v_xor_b32_e32 v18, 0x80000000, v75
	v_mov_b32_e32 v19, v74
	v_pk_add_f32 v[74:75], v[78:79], v[18:19]
	v_pk_add_f32 v[18:19], v[78:79], v[18:19] neg_lo:[0,1] neg_hi:[0,1]
	v_pk_mul_f32 v[78:79], v[72:73], s[60:61] op_sel_hi:[1,0]
	s_nop 0
	v_pk_fma_f32 v[72:73], v[134:135], s[60:61], v[78:79] op_sel_hi:[1,0,1] neg_lo:[0,0,1] neg_hi:[0,0,1]
	v_xor_b32_e32 v134, 0x80000000, v85
	v_pk_add_f32 v[78:79], v[24:25], v[72:73]
	v_pk_add_f32 v[24:25], v[24:25], v[72:73] neg_lo:[0,1] neg_hi:[0,1]
	v_pk_add_f32 v[72:73], v[76:77], v[130:131]
	v_pk_add_f32 v[76:77], v[76:77], v[130:131] neg_lo:[0,1] neg_hi:[0,1]
	v_pk_mul_f32 v[130:131], v[22:23], s[60:61] op_sel:[1,0] op_sel_hi:[0,0] neg_lo:[1,0]
	v_mov_b32_e32 v135, v84
	v_pk_fma_f32 v[22:23], v[22:23], s[60:61], v[130:131] op_sel_hi:[1,0,1]
	s_nop 0
	v_pk_add_f32 v[130:131], v[26:27], v[22:23]
	v_pk_add_f32 v[22:23], v[26:27], v[22:23] neg_lo:[0,1] neg_hi:[0,1]
	v_xor_b32_e32 v26, 0x80000000, v89
	v_mov_b32_e32 v27, v88
	v_pk_add_f32 v[88:89], v[92:93], v[26:27]
	v_pk_add_f32 v[26:27], v[92:93], v[26:27] neg_lo:[0,1] neg_hi:[0,1]
	v_pk_mul_f32 v[92:93], v[84:85], s[60:61] op_sel_hi:[1,0]
	s_nop 0
	v_pk_fma_f32 v[84:85], v[134:135], s[60:61], v[92:93] op_sel_hi:[1,0,1] neg_lo:[0,0,1] neg_hi:[0,0,1]
	v_xor_b32_e32 v134, 0x80000000, v7
	v_pk_add_f32 v[92:93], v[62:63], v[84:85]
	v_pk_add_f32 v[62:63], v[62:63], v[84:85] neg_lo:[0,1] neg_hi:[0,1]
	v_pk_add_f32 v[84:85], v[90:91], v[10:11]
	v_pk_add_f32 v[10:11], v[90:91], v[10:11] neg_lo:[0,1] neg_hi:[0,1]
	v_pk_mul_f32 v[90:91], v[94:95], s[54:55] op_sel:[1,0] op_sel_hi:[0,0] neg_lo:[1,0]
	v_mov_b32_e32 v135, v6
	v_pk_fma_f32 v[90:91], v[94:95], s[52:53], v[90:91] op_sel_hi:[1,0,1]
	s_nop 0
	v_pk_add_f32 v[94:95], v[132:133], v[90:91]
	v_pk_add_f32 v[90:91], v[132:133], v[90:91] neg_lo:[0,1] neg_hi:[0,1]
	v_pk_mul_f32 v[132:133], v[86:87], s[60:61] op_sel:[1,0] op_sel_hi:[0,0] neg_lo:[1,0]
	s_nop 0
	v_pk_fma_f32 v[86:87], v[86:87], s[60:61], v[132:133] op_sel_hi:[1,0,1]
	s_nop 0
	v_pk_add_f32 v[132:133], v[80:81], v[86:87]
	v_pk_add_f32 v[80:81], v[80:81], v[86:87] neg_lo:[0,1] neg_hi:[0,1]
	v_pk_mul_f32 v[86:87], v[68:69], s[52:53] op_sel:[1,0] op_sel_hi:[0,0] neg_lo:[1,0]
	s_nop 0
	v_pk_fma_f32 v[68:69], v[68:69], s[54:55], v[86:87] op_sel_hi:[1,0,1]
	s_nop 0
	v_pk_add_f32 v[86:87], v[12:13], v[68:69]
	v_pk_add_f32 v[12:13], v[12:13], v[68:69] neg_lo:[0,1] neg_hi:[0,1]
	v_xor_b32_e32 v68, 0x80000000, v71
	v_mov_b32_e32 v69, v70
	v_pk_add_f32 v[70:71], v[64:65], v[68:69]
	v_pk_add_f32 v[64:65], v[64:65], v[68:69] neg_lo:[0,1] neg_hi:[0,1]
	v_pk_mul_f32 v[68:69], v[6:7], s[54:55] op_sel_hi:[1,0]
	s_nop 0
	v_pk_fma_f32 v[6:7], v[134:135], s[52:53], v[68:69] op_sel_hi:[1,0,1] neg_lo:[0,0,1] neg_hi:[0,0,1]
	v_xor_b32_e32 v134, 0x80000000, v9
	v_pk_add_f32 v[68:69], v[2:3], v[6:7]
	v_pk_add_f32 v[2:3], v[2:3], v[6:7] neg_lo:[0,1] neg_hi:[0,1]
	v_pk_mul_f32 v[6:7], v[8:9], s[60:61] op_sel_hi:[1,0]
	v_mov_b32_e32 v135, v8
	v_pk_fma_f32 v[6:7], v[134:135], s[60:61], v[6:7] op_sel_hi:[1,0,1] neg_lo:[0,0,1] neg_hi:[0,0,1]
	v_xor_b32_e32 v134, 0x80000000, v17
	v_pk_add_f32 v[8:9], v[4:5], v[6:7]
	v_pk_add_f32 v[4:5], v[4:5], v[6:7] neg_lo:[0,1] neg_hi:[0,1]
	v_pk_mul_f32 v[6:7], v[16:17], s[52:53] op_sel_hi:[1,0]
	v_mov_b32_e32 v135, v16
	v_pk_fma_f32 v[6:7], v[134:135], s[54:55], v[6:7] op_sel_hi:[1,0,1] neg_lo:[0,0,1] neg_hi:[0,0,1]
	v_xor_b32_e32 v134, 0x80000000, v23
	v_pk_add_f32 v[16:17], v[0:1], v[6:7]
	v_pk_add_f32 v[0:1], v[0:1], v[6:7] neg_lo:[0,1] neg_hi:[0,1]
	v_pk_add_f32 v[6:7], v[20:21], v[72:73]
	v_pk_add_f32 v[20:21], v[20:21], v[72:73] neg_lo:[0,1] neg_hi:[0,1]
	v_pk_mul_f32 v[72:73], v[130:131], s[54:55] op_sel:[1,0] op_sel_hi:[0,0] neg_lo:[1,0]
	v_mov_b32_e32 v135, v22
	v_pk_fma_f32 v[72:73], v[130:131], s[52:53], v[72:73] op_sel_hi:[1,0,1]
	s_nop 0
	v_pk_add_f32 v[130:131], v[96:97], v[72:73]
	v_pk_add_f32 v[72:73], v[96:97], v[72:73] neg_lo:[0,1] neg_hi:[0,1]
	v_pk_mul_f32 v[96:97], v[88:89], s[60:61] op_sel:[1,0] op_sel_hi:[0,0] neg_lo:[1,0]
	s_nop 0
	v_pk_fma_f32 v[88:89], v[88:89], s[60:61], v[96:97] op_sel_hi:[1,0,1]
	s_nop 0
	v_pk_add_f32 v[96:97], v[74:75], v[88:89]
	v_pk_add_f32 v[74:75], v[74:75], v[88:89] neg_lo:[0,1] neg_hi:[0,1]
	v_pk_mul_f32 v[88:89], v[92:93], s[52:53] op_sel:[1,0] op_sel_hi:[0,0] neg_lo:[1,0]
	s_nop 0
	v_pk_fma_f32 v[88:89], v[92:93], s[54:55], v[88:89] op_sel_hi:[1,0,1]
	s_nop 0
	v_pk_add_f32 v[92:93], v[78:79], v[88:89]
	v_pk_add_f32 v[78:79], v[78:79], v[88:89] neg_lo:[0,1] neg_hi:[0,1]
	v_xor_b32_e32 v88, 0x80000000, v77
	v_mov_b32_e32 v89, v76
	v_pk_add_f32 v[76:77], v[82:83], v[88:89]
	v_pk_add_f32 v[82:83], v[82:83], v[88:89] neg_lo:[0,1] neg_hi:[0,1]
	v_pk_mul_f32 v[88:89], v[22:23], s[54:55] op_sel_hi:[1,0]
	s_nop 0
	v_pk_fma_f32 v[22:23], v[134:135], s[52:53], v[88:89] op_sel_hi:[1,0,1] neg_lo:[0,0,1] neg_hi:[0,0,1]
	v_xor_b32_e32 v134, 0x80000000, v27
	v_pk_add_f32 v[88:89], v[14:15], v[22:23]
	v_pk_add_f32 v[14:15], v[14:15], v[22:23] neg_lo:[0,1] neg_hi:[0,1]
	v_pk_mul_f32 v[22:23], v[26:27], s[60:61] op_sel_hi:[1,0]
	v_mov_b32_e32 v135, v26
	v_pk_fma_f32 v[22:23], v[134:135], s[60:61], v[22:23] op_sel_hi:[1,0,1] neg_lo:[0,0,1] neg_hi:[0,0,1]
	v_xor_b32_e32 v134, 0x80000000, v63
	v_pk_add_f32 v[26:27], v[18:19], v[22:23]
	v_pk_add_f32 v[18:19], v[18:19], v[22:23] neg_lo:[0,1] neg_hi:[0,1]
	v_pk_mul_f32 v[22:23], v[62:63], s[52:53] op_sel_hi:[1,0]
	v_mov_b32_e32 v135, v62
	v_pk_fma_f32 v[22:23], v[134:135], s[54:55], v[22:23] op_sel_hi:[1,0,1] neg_lo:[0,0,1] neg_hi:[0,0,1]
	v_xor_b32_e32 v134, 0x80000000, v73
	v_pk_add_f32 v[62:63], v[24:25], v[22:23]
	v_pk_add_f32 v[22:23], v[24:25], v[22:23] neg_lo:[0,1] neg_hi:[0,1]
	v_pk_add_f32 v[24:25], v[84:85], v[6:7]
	v_pk_add_f32 v[6:7], v[84:85], v[6:7] neg_lo:[0,1] neg_hi:[0,1]
	v_pk_mul_f32 v[84:85], v[130:131], s[48:49] op_sel:[1,0] op_sel_hi:[0,0] neg_lo:[1,0]
	v_mov_b32_e32 v135, v72
	v_pk_fma_f32 v[84:85], v[130:131], s[44:45], v[84:85] op_sel_hi:[1,0,1]
	s_nop 0
	v_pk_add_f32 v[130:131], v[94:95], v[84:85]
	v_pk_add_f32 v[84:85], v[94:95], v[84:85] neg_lo:[0,1] neg_hi:[0,1]
	v_pk_mul_f32 v[94:95], v[96:97], s[54:55] op_sel:[1,0] op_sel_hi:[0,0] neg_lo:[1,0]
	s_nop 0
	v_pk_fma_f32 v[94:95], v[96:97], s[52:53], v[94:95] op_sel_hi:[1,0,1]
	s_nop 0
	v_pk_add_f32 v[96:97], v[132:133], v[94:95]
	v_pk_add_f32 v[94:95], v[132:133], v[94:95] neg_lo:[0,1] neg_hi:[0,1]
	v_pk_mul_f32 v[132:133], v[92:93], s[58:59] op_sel:[1,0] op_sel_hi:[0,0] neg_lo:[1,0]
	s_nop 0
	v_pk_fma_f32 v[92:93], v[92:93], s[56:57], v[132:133] op_sel_hi:[1,0,1]
	s_nop 0
	v_pk_add_f32 v[132:133], v[86:87], v[92:93]
	v_pk_add_f32 v[86:87], v[86:87], v[92:93] neg_lo:[0,1] neg_hi:[0,1]
	v_pk_mul_f32 v[92:93], v[76:77], s[60:61] op_sel:[1,0] op_sel_hi:[0,0] neg_lo:[1,0]
	s_nop 0
	v_pk_fma_f32 v[76:77], v[76:77], s[60:61], v[92:93] op_sel_hi:[1,0,1]
	s_nop 0
	v_pk_add_f32 v[92:93], v[70:71], v[76:77]
	v_pk_add_f32 v[70:71], v[70:71], v[76:77] neg_lo:[0,1] neg_hi:[0,1]
	v_pk_mul_f32 v[76:77], v[88:89], s[56:57] op_sel:[1,0] op_sel_hi:[0,0] neg_lo:[1,0]
	s_nop 0
	v_pk_fma_f32 v[76:77], v[88:89], s[58:59], v[76:77] op_sel_hi:[1,0,1]
	s_nop 0
	v_pk_add_f32 v[88:89], v[68:69], v[76:77]
	v_pk_add_f32 v[68:69], v[68:69], v[76:77] neg_lo:[0,1] neg_hi:[0,1]
	v_pk_mul_f32 v[76:77], v[26:27], s[52:53] op_sel:[1,0] op_sel_hi:[0,0] neg_lo:[1,0]
	s_nop 0
	v_pk_fma_f32 v[26:27], v[26:27], s[54:55], v[76:77] op_sel_hi:[1,0,1]
	s_nop 0
	v_pk_add_f32 v[76:77], v[8:9], v[26:27]
	v_pk_add_f32 v[8:9], v[8:9], v[26:27] neg_lo:[0,1] neg_hi:[0,1]
	v_pk_mul_f32 v[26:27], v[62:63], s[44:45] op_sel:[1,0] op_sel_hi:[0,0] neg_lo:[1,0]
	s_nop 0
	v_pk_fma_f32 v[26:27], v[62:63], s[48:49], v[26:27] op_sel_hi:[1,0,1]
	s_nop 0
	v_pk_add_f32 v[62:63], v[16:17], v[26:27]
	v_pk_add_f32 v[16:17], v[16:17], v[26:27] neg_lo:[0,1] neg_hi:[0,1]
	v_xor_b32_e32 v26, 0x80000000, v21
	v_mov_b32_e32 v27, v20
	v_pk_add_f32 v[20:21], v[10:11], v[26:27]
	v_pk_add_f32 v[10:11], v[10:11], v[26:27] neg_lo:[0,1] neg_hi:[0,1]
	v_pk_mul_f32 v[26:27], v[72:73], s[48:49] op_sel_hi:[1,0]
	s_nop 0
	v_pk_fma_f32 v[26:27], v[134:135], s[44:45], v[26:27] op_sel_hi:[1,0,1] neg_lo:[0,0,1] neg_hi:[0,0,1]
	v_xor_b32_e32 v134, 0x80000000, v75
	v_pk_add_f32 v[72:73], v[90:91], v[26:27]
	v_pk_add_f32 v[26:27], v[90:91], v[26:27] neg_lo:[0,1] neg_hi:[0,1]
	v_pk_mul_f32 v[90:91], v[74:75], s[54:55] op_sel_hi:[1,0]
	v_mov_b32_e32 v135, v74
	v_pk_fma_f32 v[74:75], v[134:135], s[52:53], v[90:91] op_sel_hi:[1,0,1] neg_lo:[0,0,1] neg_hi:[0,0,1]
	v_xor_b32_e32 v134, 0x80000000, v79
	v_pk_add_f32 v[90:91], v[80:81], v[74:75]
	v_pk_add_f32 v[74:75], v[80:81], v[74:75] neg_lo:[0,1] neg_hi:[0,1]
	v_pk_mul_f32 v[80:81], v[78:79], s[58:59] op_sel_hi:[1,0]
	v_mov_b32_e32 v135, v78
	v_pk_fma_f32 v[78:79], v[134:135], s[56:57], v[80:81] op_sel_hi:[1,0,1] neg_lo:[0,0,1] neg_hi:[0,0,1]
	v_xor_b32_e32 v134, 0x80000000, v83
	v_pk_add_f32 v[80:81], v[12:13], v[78:79]
	v_pk_add_f32 v[12:13], v[12:13], v[78:79] neg_lo:[0,1] neg_hi:[0,1]
	v_pk_mul_f32 v[78:79], v[82:83], s[60:61] op_sel_hi:[1,0]
	v_mov_b32_e32 v135, v82
	v_pk_fma_f32 v[78:79], v[134:135], s[60:61], v[78:79] op_sel_hi:[1,0,1] neg_lo:[0,0,1] neg_hi:[0,0,1]
	v_xor_b32_e32 v134, 0x80000000, v15
	v_pk_add_f32 v[82:83], v[64:65], v[78:79]
	v_pk_add_f32 v[64:65], v[64:65], v[78:79] neg_lo:[0,1] neg_hi:[0,1]
	v_pk_mul_f32 v[78:79], v[14:15], s[56:57] op_sel_hi:[1,0]
	v_mov_b32_e32 v135, v14
	v_pk_fma_f32 v[14:15], v[134:135], s[58:59], v[78:79] op_sel_hi:[1,0,1] neg_lo:[0,0,1] neg_hi:[0,0,1]
	v_xor_b32_e32 v134, 0x80000000, v19
	v_pk_add_f32 v[78:79], v[2:3], v[14:15]
	v_pk_add_f32 v[2:3], v[2:3], v[14:15] neg_lo:[0,1] neg_hi:[0,1]
	v_pk_mul_f32 v[14:15], v[18:19], s[52:53] op_sel_hi:[1,0]
	v_mov_b32_e32 v135, v18
	v_pk_fma_f32 v[14:15], v[134:135], s[54:55], v[14:15] op_sel_hi:[1,0,1] neg_lo:[0,0,1] neg_hi:[0,0,1]
	v_xor_b32_e32 v134, 0x80000000, v23
	v_pk_add_f32 v[18:19], v[4:5], v[14:15]
	v_pk_add_f32 v[4:5], v[4:5], v[14:15] neg_lo:[0,1] neg_hi:[0,1]
	v_pk_mul_f32 v[14:15], v[22:23], s[44:45] op_sel_hi:[1,0]
	v_mov_b32_e32 v135, v22
	v_pk_fma_f32 v[14:15], v[134:135], s[48:49], v[14:15] op_sel_hi:[1,0,1] neg_lo:[0,0,1] neg_hi:[0,0,1]
	s_nop 0
	v_pk_add_f32 v[22:23], v[0:1], v[14:15]
	v_pk_add_f32 v[0:1], v[0:1], v[14:15] neg_lo:[0,1] neg_hi:[0,1]
	ds_write_b64 v67, v[24:25]
	ds_write_b64 v98, v[130:131]
	ds_write_b64 v99, v[96:97] offset:256
	ds_write_b64 v100, v[132:133] offset:256
	ds_write_b64 v101, v[92:93] offset:512
	ds_write_b64 v102, v[88:89] offset:512
	ds_write_b64 v103, v[76:77] offset:768
	ds_write_b64 v104, v[62:63] offset:768
	ds_write_b64 v105, v[20:21] offset:1024
	ds_write_b64 v106, v[72:73] offset:1024
	ds_write_b64 v107, v[90:91] offset:1280
	ds_write_b64 v108, v[80:81] offset:1280
	ds_write_b64 v109, v[82:83] offset:1536
	ds_write_b64 v110, v[78:79] offset:1536
	ds_write_b64 v111, v[18:19] offset:1792
	ds_write_b64 v112, v[22:23] offset:1792
	ds_write_b64 v113, v[6:7] offset:2048
	ds_write_b64 v114, v[84:85] offset:2048
	ds_write_b64 v115, v[94:95] offset:2304
	ds_write_b64 v116, v[86:87] offset:2304
	ds_write_b64 v117, v[70:71] offset:2560
	ds_write_b64 v118, v[68:69] offset:2560
	ds_write_b64 v119, v[8:9] offset:2816
	ds_write_b64 v120, v[16:17] offset:2816
	ds_write_b64 v121, v[10:11] offset:3072
	ds_write_b64 v122, v[26:27] offset:3072
	ds_write_b64 v123, v[74:75] offset:3328
	ds_write_b64 v124, v[12:13] offset:3328
	ds_write_b64 v125, v[64:65] offset:3584
	ds_write_b64 v126, v[2:3] offset:3584
	ds_write_b64 v127, v[4:5] offset:3840
	ds_write_b64 v128, v[0:1] offset:3840
	v_mov_b32_e32 v74, v146
	s_waitcnt lgkmcnt(0)
	s_barrier
	s_nop 0
	v_lshrrev_b32_e32 v0, 5, v74
	v_bfe_u32 v4, v74, 5, 4
	v_bitop3_b32 v0, v0, v74, 15 bitop3:0x6c
	v_bitop3_b32 v4, v4, v74, 16 bitop3:0x36
	v_lshlrev_b32_e32 v66, 3, v0
	v_lshlrev_b32_e32 v67, 3, v4
	v_add_u32_e32 v5, 16, v66
	v_add_u32_e32 v4, 16, v67
	v_add_u32_e32 v62, s79, v66
	v_add_u32_e32 v70, s9, v66
	ds_read2st64_b64 v[0:3], v5 offset1:16
	ds_read2st64_b64 v[16:19], v4 offset0:8 offset1:24
	ds_read2st64_b64 v[24:27], v5 offset0:32 offset1:48
	ds_read2st64_b64 v[8:11], v4 offset0:40 offset1:56
	ds_read2st64_b64 v[92:95], v5 offset0:64 offset1:80
	ds_read2st64_b64 v[12:15], v4 offset0:72 offset1:88
	ds_read2st64_b64 v[20:23], v5 offset0:96 offset1:112
	ds_read2st64_b64 v[4:7], v4 offset0:104 offset1:120
	ds_read_b64 v[68:69], v62
	ds_read_b64 v[72:73], v70
	v_add_u32_e32 v62, s19, v67
	v_add_u32_e32 v70, s8, v67
	ds_read_b64 v[84:85], v62
	ds_read_b64 v[90:91], v70
	v_add_u32_e32 v62, s18, v66
	v_add_u32_e32 v70, s7, v66
	ds_read_b64 v[96:97], v62
	ds_read_b64 v[100:101], v70
	v_add_u32_e32 v62, s17, v67
	v_add_u32_e32 v70, s6, v67
	ds_read_b64 v[64:65], v62
	ds_read_b64 v[70:71], v70
	v_add_u32_e32 v62, s13, v66
	v_add_u32_e32 v75, s5, v66
	ds_read_b64 v[86:87], v62
	ds_read_b64 v[102:103], v75
	v_add_u32_e32 v62, s12, v67
	v_add_u32_e32 v75, s4, v67
	ds_read_b64 v[80:81], v62
	ds_read_b64 v[88:89], v75
	v_add_u32_e32 v62, s11, v66
	v_add_u32_e32 v66, s1, v66
	ds_read_b64 v[98:99], v62
	ds_read_b64 v[104:105], v66
	v_add_u32_e32 v62, s10, v67
	v_add_u32_e32 v66, s0, v67
	ds_read_b64 v[62:63], v62
	ds_read_b64 v[66:67], v66
	s_waitcnt lgkmcnt(14)
	s_nop 0
	v_cvt_f32_i32_e32 v74, v74
	s_nop 0
	s_lshl_b64 s[0:1], s[42:43], 2
	s_add_u32 s0, s45, s0
	v_mul_f32_e32 v74, 0x38800000, v74
	v_cos_f32_e32 v78, v74
	v_sin_f32_e32 v79, v74
	s_addc_u32 s1, s24, s1
	s_and_b64 vcc, s[14:15], exec
	v_add_f32_e32 v76, v78, v78
	v_pk_mul_f32 v[74:75], v[78:79], v[78:79]
	v_mul_f32_e32 v76, v79, v76
	s_nop 0
	s_nop 0
	v_mov_b32_e32 v108, v79
	v_pk_add_f32 v[74:75], v[74:75], v[74:75] op_sel:[0,1] op_sel_hi:[0,1] neg_lo:[0,1] neg_hi:[0,1]
	v_pk_mul_f32 v[82:83], v[78:79], v[76:77] op_sel:[1,0] op_sel_hi:[0,0] neg_lo:[1,0]
	v_pk_mul_f32 v[106:107], v[68:69], v[108:109] op_sel:[1,0] op_sel_hi:[0,0] neg_lo:[1,0]
	v_pk_fma_f32 v[82:83], v[78:79], v[74:75], v[82:83]
	v_pk_fma_f32 v[68:69], v[68:69], v[78:79], v[106:107] op_sel_hi:[1,0,1]
	v_pk_mul_f32 v[78:79], v[76:77], s[46:47] op_sel_hi:[0,1]
	v_pk_fma_f32 v[106:107], v[74:75], s[40:41], v[78:79]
	s_nop 0
	v_pk_mul_f32 v[78:79], v[92:93], v[106:107] op_sel:[1,1] op_sel_hi:[0,1] neg_lo:[1,0]
	s_nop 0
	v_pk_fma_f32 v[78:79], v[92:93], v[106:107], v[78:79] op_sel_hi:[1,0,1]
	v_pk_mul_f32 v[92:93], v[76:77], v[82:83] op_sel:[0,1] op_sel_hi:[0,0] neg_lo:[0,1]
	v_pk_mul_f32 v[108:109], v[72:73], v[82:83] op_sel:[1,1] op_sel_hi:[0,1] neg_lo:[1,0]
	v_pk_fma_f32 v[92:93], v[74:75], v[82:83], v[92:93]
	v_pk_fma_f32 v[72:73], v[72:73], v[82:83], v[108:109] op_sel_hi:[1,0,1]
	v_pk_mul_f32 v[82:83], v[76:77], v[106:107] op_sel:[0,1] op_sel_hi:[0,0] neg_lo:[0,1]
	v_pk_fma_f32 v[106:107], v[74:75], v[106:107], v[82:83]
	s_nop 0
	v_pk_mul_f32 v[82:83], v[24:25], v[106:107] op_sel:[1,1] op_sel_hi:[0,1] neg_lo:[1,0]
	s_nop 0
	v_pk_fma_f32 v[82:83], v[24:25], v[106:107], v[82:83] op_sel_hi:[1,0,1]
	v_pk_mul_f32 v[24:25], v[76:77], v[92:93] op_sel:[0,1] op_sel_hi:[0,0] neg_lo:[0,1]
	v_pk_fma_f32 v[108:109], v[74:75], v[92:93], v[24:25]
	s_waitcnt lgkmcnt(7)
	v_pk_mul_f32 v[24:25], v[86:87], v[92:93] op_sel:[1,1] op_sel_hi:[0,1] neg_lo:[1,0]
	s_nop 0
	v_pk_fma_f32 v[24:25], v[86:87], v[92:93], v[24:25] op_sel_hi:[1,0,1]
	v_pk_mul_f32 v[86:87], v[76:77], v[106:107] op_sel:[0,1] op_sel_hi:[0,0] neg_lo:[0,1]
	v_pk_fma_f32 v[92:93], v[74:75], v[106:107], v[86:87]
	s_nop 0
	v_pk_mul_f32 v[86:87], v[20:21], v[92:93] op_sel:[1,1] op_sel_hi:[0,1] neg_lo:[1,0]
	s_nop 0
	v_pk_fma_f32 v[86:87], v[20:21], v[92:93], v[86:87] op_sel_hi:[1,0,1]
	v_pk_mul_f32 v[20:21], v[76:77], v[108:109] op_sel:[0,1] op_sel_hi:[0,0] neg_lo:[0,1]
	v_pk_fma_f32 v[106:107], v[74:75], v[108:109], v[20:21]
	s_waitcnt lgkmcnt(6)
	v_pk_mul_f32 v[20:21], v[102:103], v[108:109] op_sel:[1,1] op_sel_hi:[0,1] neg_lo:[1,0]
	s_nop 0
	v_pk_fma_f32 v[20:21], v[102:103], v[108:109], v[20:21] op_sel_hi:[1,0,1]
	v_pk_mul_f32 v[102:103], v[76:77], v[92:93] op_sel:[0,1] op_sel_hi:[0,0] neg_lo:[0,1]
	v_pk_fma_f32 v[102:103], v[74:75], v[92:93], v[102:103]
	s_nop 0
	v_pk_mul_f32 v[92:93], v[2:3], v[102:103] op_sel:[1,1] op_sel_hi:[0,1] neg_lo:[1,0]
	s_nop 0
	v_pk_fma_f32 v[92:93], v[2:3], v[102:103], v[92:93] op_sel_hi:[1,0,1]
	v_pk_mul_f32 v[2:3], v[76:77], v[106:107] op_sel:[0,1] op_sel_hi:[0,0] neg_lo:[0,1]
	v_pk_fma_f32 v[108:109], v[74:75], v[106:107], v[2:3]
	v_pk_mul_f32 v[2:3], v[96:97], v[106:107] op_sel:[1,1] op_sel_hi:[0,1] neg_lo:[1,0]
	s_nop 0
	v_pk_fma_f32 v[2:3], v[96:97], v[106:107], v[2:3] op_sel_hi:[1,0,1]
	v_pk_mul_f32 v[96:97], v[76:77], v[102:103] op_sel:[0,1] op_sel_hi:[0,0] neg_lo:[0,1]
	v_pk_fma_f32 v[102:103], v[74:75], v[102:103], v[96:97]
	s_nop 0
	v_pk_mul_f32 v[96:97], v[94:95], v[102:103] op_sel:[1,1] op_sel_hi:[0,1] neg_lo:[1,0]
	s_nop 0
	v_pk_fma_f32 v[96:97], v[94:95], v[102:103], v[96:97] op_sel_hi:[1,0,1]
	v_pk_mul_f32 v[94:95], v[76:77], v[108:109] op_sel:[0,1] op_sel_hi:[0,0] neg_lo:[0,1]
	v_pk_fma_f32 v[106:107], v[74:75], v[108:109], v[94:95]
	v_pk_mul_f32 v[94:95], v[100:101], v[108:109] op_sel:[1,1] op_sel_hi:[0,1] neg_lo:[1,0]
	s_nop 0
	v_pk_fma_f32 v[94:95], v[100:101], v[108:109], v[94:95] op_sel_hi:[1,0,1]
	v_pk_mul_f32 v[100:101], v[76:77], v[102:103] op_sel:[0,1] op_sel_hi:[0,0] neg_lo:[0,1]
	v_pk_fma_f32 v[100:101], v[74:75], v[102:103], v[100:101]
	s_nop 0
	v_pk_mul_f32 v[102:103], v[26:27], v[100:101] op_sel:[1,1] op_sel_hi:[0,1] neg_lo:[1,0]
	s_waitcnt lgkmcnt(3)
	v_pk_fma_f32 v[26:27], v[26:27], v[100:101], v[102:103] op_sel_hi:[1,0,1]
	v_pk_mul_f32 v[102:103], v[76:77], v[106:107] op_sel:[0,1] op_sel_hi:[0,0] neg_lo:[0,1]
	v_pk_mul_f32 v[108:109], v[98:99], v[106:107] op_sel:[1,1] op_sel_hi:[0,1] neg_lo:[1,0]
	v_pk_fma_f32 v[102:103], v[74:75], v[106:107], v[102:103]
	v_pk_fma_f32 v[98:99], v[98:99], v[106:107], v[108:109] op_sel_hi:[1,0,1]
	v_pk_mul_f32 v[106:107], v[76:77], v[100:101] op_sel:[0,1] op_sel_hi:[0,0] neg_lo:[0,1]
	v_pk_fma_f32 v[100:101], v[74:75], v[100:101], v[106:107]
	s_nop 0
	v_pk_mul_f32 v[106:107], v[22:23], v[100:101] op_sel:[1,1] op_sel_hi:[0,1] neg_lo:[1,0]
	s_waitcnt lgkmcnt(2)
	v_pk_fma_f32 v[22:23], v[22:23], v[100:101], v[106:107] op_sel_hi:[1,0,1]
	v_pk_mul_f32 v[106:107], v[76:77], v[102:103] op_sel:[0,1] op_sel_hi:[0,0] neg_lo:[0,1]
	v_pk_mul_f32 v[108:109], v[104:105], v[102:103] op_sel:[1,1] op_sel_hi:[0,1] neg_lo:[1,0]
	v_pk_fma_f32 v[106:107], v[74:75], v[102:103], v[106:107]
	v_pk_fma_f32 v[102:103], v[104:105], v[102:103], v[108:109] op_sel_hi:[1,0,1]
	v_pk_mul_f32 v[104:105], v[76:77], v[100:101] op_sel:[0,1] op_sel_hi:[0,0] neg_lo:[0,1]
	v_pk_fma_f32 v[100:101], v[74:75], v[100:101], v[104:105]
	s_nop 0
	v_pk_mul_f32 v[104:105], v[16:17], v[100:101] op_sel:[1,1] op_sel_hi:[0,1] neg_lo:[1,0]
	s_nop 0
	v_pk_fma_f32 v[16:17], v[16:17], v[100:101], v[104:105] op_sel_hi:[1,0,1]
	v_pk_mul_f32 v[104:105], v[76:77], v[106:107] op_sel:[0,1] op_sel_hi:[0,0] neg_lo:[0,1]
	v_pk_mul_f32 v[108:109], v[84:85], v[106:107] op_sel:[1,1] op_sel_hi:[0,1] neg_lo:[1,0]
	v_pk_fma_f32 v[104:105], v[74:75], v[106:107], v[104:105]
	v_pk_fma_f32 v[84:85], v[84:85], v[106:107], v[108:109] op_sel_hi:[1,0,1]
	v_pk_mul_f32 v[106:107], v[76:77], v[100:101] op_sel:[0,1] op_sel_hi:[0,0] neg_lo:[0,1]
	v_pk_fma_f32 v[100:101], v[74:75], v[100:101], v[106:107]
	s_nop 0
	v_pk_mul_f32 v[106:107], v[12:13], v[100:101] op_sel:[1,1] op_sel_hi:[0,1] neg_lo:[1,0]
	s_nop 0
	v_pk_fma_f32 v[12:13], v[12:13], v[100:101], v[106:107] op_sel_hi:[1,0,1]
	v_pk_mul_f32 v[106:107], v[76:77], v[104:105] op_sel:[0,1] op_sel_hi:[0,0] neg_lo:[0,1]
	v_pk_mul_f32 v[108:109], v[90:91], v[104:105] op_sel:[1,1] op_sel_hi:[0,1] neg_lo:[1,0]
	v_pk_fma_f32 v[106:107], v[74:75], v[104:105], v[106:107]
	v_pk_fma_f32 v[90:91], v[90:91], v[104:105], v[108:109] op_sel_hi:[1,0,1]
	v_pk_mul_f32 v[104:105], v[76:77], v[100:101] op_sel:[0,1] op_sel_hi:[0,0] neg_lo:[0,1]
	v_pk_fma_f32 v[100:101], v[74:75], v[100:101], v[104:105]
	s_nop 0
	v_pk_mul_f32 v[104:105], v[8:9], v[100:101] op_sel:[1,1] op_sel_hi:[0,1] neg_lo:[1,0]
	s_nop 0
	v_pk_fma_f32 v[8:9], v[8:9], v[100:101], v[104:105] op_sel_hi:[1,0,1]
	v_pk_mul_f32 v[104:105], v[76:77], v[106:107] op_sel:[0,1] op_sel_hi:[0,0] neg_lo:[0,1]
	v_pk_mul_f32 v[108:109], v[80:81], v[106:107] op_sel:[1,1] op_sel_hi:[0,1] neg_lo:[1,0]
	v_pk_fma_f32 v[104:105], v[74:75], v[106:107], v[104:105]
	v_pk_fma_f32 v[80:81], v[80:81], v[106:107], v[108:109] op_sel_hi:[1,0,1]
	v_pk_mul_f32 v[106:107], v[76:77], v[100:101] op_sel:[0,1] op_sel_hi:[0,0] neg_lo:[0,1]
	v_pk_fma_f32 v[100:101], v[74:75], v[100:101], v[106:107]
	s_nop 0
	v_pk_mul_f32 v[106:107], v[4:5], v[100:101] op_sel:[1,1] op_sel_hi:[0,1] neg_lo:[1,0]
	s_nop 0
	v_pk_fma_f32 v[4:5], v[4:5], v[100:101], v[106:107] op_sel_hi:[1,0,1]
	v_pk_mul_f32 v[106:107], v[76:77], v[104:105] op_sel:[0,1] op_sel_hi:[0,0] neg_lo:[0,1]
	v_pk_mul_f32 v[108:109], v[88:89], v[104:105] op_sel:[1,1] op_sel_hi:[0,1] neg_lo:[1,0]
	v_pk_fma_f32 v[106:107], v[74:75], v[104:105], v[106:107]
	v_pk_fma_f32 v[88:89], v[88:89], v[104:105], v[108:109] op_sel_hi:[1,0,1]
	v_pk_mul_f32 v[104:105], v[76:77], v[100:101] op_sel:[0,1] op_sel_hi:[0,0] neg_lo:[0,1]
	v_pk_fma_f32 v[100:101], v[74:75], v[100:101], v[104:105]
	s_nop 0
	v_pk_mul_f32 v[104:105], v[18:19], v[100:101] op_sel:[1,1] op_sel_hi:[0,1] neg_lo:[1,0]
	s_nop 0
	v_pk_fma_f32 v[18:19], v[18:19], v[100:101], v[104:105] op_sel_hi:[1,0,1]
	v_pk_mul_f32 v[104:105], v[76:77], v[106:107] op_sel:[0,1] op_sel_hi:[0,0] neg_lo:[0,1]
	v_pk_mul_f32 v[108:109], v[64:65], v[106:107] op_sel:[1,1] op_sel_hi:[0,1] neg_lo:[1,0]
	v_pk_fma_f32 v[104:105], v[74:75], v[106:107], v[104:105]
	v_pk_fma_f32 v[64:65], v[64:65], v[106:107], v[108:109] op_sel_hi:[1,0,1]
	v_pk_mul_f32 v[106:107], v[76:77], v[100:101] op_sel:[0,1] op_sel_hi:[0,0] neg_lo:[0,1]
	v_pk_fma_f32 v[100:101], v[74:75], v[100:101], v[106:107]
	s_nop 0
	v_pk_mul_f32 v[106:107], v[14:15], v[100:101] op_sel:[1,1] op_sel_hi:[0,1] neg_lo:[1,0]
	s_nop 0
	v_pk_fma_f32 v[14:15], v[14:15], v[100:101], v[106:107] op_sel_hi:[1,0,1]
	v_pk_mul_f32 v[106:107], v[76:77], v[104:105] op_sel:[0,1] op_sel_hi:[0,0] neg_lo:[0,1]
	v_pk_mul_f32 v[108:109], v[70:71], v[104:105] op_sel:[1,1] op_sel_hi:[0,1] neg_lo:[1,0]
	v_pk_fma_f32 v[106:107], v[74:75], v[104:105], v[106:107]
	v_pk_fma_f32 v[70:71], v[70:71], v[104:105], v[108:109] op_sel_hi:[1,0,1]
	v_pk_mul_f32 v[104:105], v[76:77], v[100:101] op_sel:[0,1] op_sel_hi:[0,0] neg_lo:[0,1]
	v_pk_fma_f32 v[100:101], v[74:75], v[100:101], v[104:105]
	s_nop 0
	v_pk_mul_f32 v[104:105], v[10:11], v[100:101] op_sel:[1,1] op_sel_hi:[0,1] neg_lo:[1,0]
	s_waitcnt lgkmcnt(1)
	v_pk_fma_f32 v[10:11], v[10:11], v[100:101], v[104:105] op_sel_hi:[1,0,1]
	v_pk_mul_f32 v[104:105], v[76:77], v[106:107] op_sel:[0,1] op_sel_hi:[0,0] neg_lo:[0,1]
	v_pk_mul_f32 v[108:109], v[62:63], v[106:107] op_sel:[1,1] op_sel_hi:[0,1] neg_lo:[1,0]
	v_pk_fma_f32 v[104:105], v[74:75], v[106:107], v[104:105]
	v_pk_fma_f32 v[62:63], v[62:63], v[106:107], v[108:109] op_sel_hi:[1,0,1]
	v_pk_mul_f32 v[76:77], v[76:77], v[100:101] op_sel:[0,1] op_sel_hi:[0,0] neg_lo:[0,1]
	v_pk_fma_f32 v[74:75], v[74:75], v[100:101], v[76:77]
	s_nop 0
	v_pk_mul_f32 v[76:77], v[6:7], v[74:75] op_sel:[1,1] op_sel_hi:[0,1] neg_lo:[1,0]
	s_nop 0
	v_pk_fma_f32 v[6:7], v[6:7], v[74:75], v[76:77] op_sel_hi:[1,0,1]
	s_waitcnt lgkmcnt(0)
	v_pk_mul_f32 v[74:75], v[66:67], v[104:105] op_sel:[1,1] op_sel_hi:[0,1] neg_lo:[1,0]
	v_pk_add_f32 v[76:77], v[82:83], v[8:9]
	v_pk_fma_f32 v[66:67], v[66:67], v[104:105], v[74:75] op_sel_hi:[1,0,1]
	v_pk_add_f32 v[74:75], v[0:1], v[16:17]
	v_pk_add_f32 v[0:1], v[0:1], v[16:17] neg_lo:[0,1] neg_hi:[0,1]
	v_pk_add_f32 v[16:17], v[92:93], v[18:19]
	v_pk_add_f32 v[18:19], v[92:93], v[18:19] neg_lo:[0,1] neg_hi:[0,1]
	v_pk_add_f32 v[8:9], v[82:83], v[8:9] neg_lo:[0,1] neg_hi:[0,1]
	v_pk_add_f32 v[82:83], v[26:27], v[10:11]
	v_pk_add_f32 v[10:11], v[26:27], v[10:11] neg_lo:[0,1] neg_hi:[0,1]
	v_pk_add_f32 v[92:93], v[86:87], v[4:5]
	v_pk_add_f32 v[4:5], v[86:87], v[4:5] neg_lo:[0,1] neg_hi:[0,1]
	v_pk_add_f32 v[86:87], v[22:23], v[6:7]
	v_pk_add_f32 v[6:7], v[22:23], v[6:7] neg_lo:[0,1] neg_hi:[0,1]
	v_pk_add_f32 v[22:23], v[68:69], v[84:85]
	v_pk_add_f32 v[68:69], v[68:69], v[84:85] neg_lo:[0,1] neg_hi:[0,1]
	v_pk_add_f32 v[84:85], v[2:3], v[64:65]
	v_pk_add_f32 v[2:3], v[2:3], v[64:65] neg_lo:[0,1] neg_hi:[0,1]
	v_pk_add_f32 v[64:65], v[24:25], v[80:81]
	v_pk_add_f32 v[24:25], v[24:25], v[80:81] neg_lo:[0,1] neg_hi:[0,1]
	v_pk_add_f32 v[80:81], v[98:99], v[62:63]
	v_pk_add_f32 v[62:63], v[98:99], v[62:63] neg_lo:[0,1] neg_hi:[0,1]
	v_pk_add_f32 v[98:99], v[74:75], v[16:17]
	v_pk_add_f32 v[16:17], v[74:75], v[16:17] neg_lo:[0,1] neg_hi:[0,1]
	v_xor_b32_e32 v74, 0x80000000, v19
	v_mov_b32_e32 v75, v18
	v_pk_add_f32 v[26:27], v[78:79], v[12:13]
	v_pk_add_f32 v[12:13], v[78:79], v[12:13] neg_lo:[0,1] neg_hi:[0,1]
	v_pk_add_f32 v[78:79], v[96:97], v[14:15]
	v_pk_add_f32 v[14:15], v[96:97], v[14:15] neg_lo:[0,1] neg_hi:[0,1]
	v_pk_add_f32 v[18:19], v[0:1], v[74:75]
	v_pk_add_f32 v[0:1], v[0:1], v[74:75] neg_lo:[0,1] neg_hi:[0,1]
	v_pk_add_f32 v[74:75], v[76:77], v[82:83]
	v_pk_add_f32 v[76:77], v[76:77], v[82:83] neg_lo:[0,1] neg_hi:[0,1]
	v_xor_b32_e32 v82, 0x80000000, v11
	v_mov_b32_e32 v83, v10
	v_pk_add_f32 v[10:11], v[8:9], v[82:83]
	v_pk_add_f32 v[8:9], v[8:9], v[82:83] neg_lo:[0,1] neg_hi:[0,1]
	v_pk_add_f32 v[82:83], v[26:27], v[78:79]
	v_pk_add_f32 v[26:27], v[26:27], v[78:79] neg_lo:[0,1] neg_hi:[0,1]
	v_xor_b32_e32 v78, 0x80000000, v15
	v_mov_b32_e32 v79, v14
	v_pk_add_f32 v[14:15], v[12:13], v[78:79]
	v_pk_add_f32 v[12:13], v[12:13], v[78:79] neg_lo:[0,1] neg_hi:[0,1]
	v_pk_add_f32 v[78:79], v[92:93], v[86:87]
	v_pk_add_f32 v[86:87], v[92:93], v[86:87] neg_lo:[0,1] neg_hi:[0,1]
	v_xor_b32_e32 v92, 0x80000000, v7
	v_mov_b32_e32 v93, v6
	v_pk_add_f32 v[6:7], v[4:5], v[92:93]
	v_pk_add_f32 v[4:5], v[4:5], v[92:93] neg_lo:[0,1] neg_hi:[0,1]
	v_pk_add_f32 v[92:93], v[22:23], v[84:85]
	v_pk_add_f32 v[22:23], v[22:23], v[84:85] neg_lo:[0,1] neg_hi:[0,1]
	v_xor_b32_e32 v84, 0x80000000, v3
	v_mov_b32_e32 v85, v2
	v_pk_add_f32 v[96:97], v[72:73], v[90:91]
	v_pk_add_f32 v[72:73], v[72:73], v[90:91] neg_lo:[0,1] neg_hi:[0,1]
	v_pk_add_f32 v[90:91], v[94:95], v[70:71]
	v_pk_add_f32 v[70:71], v[94:95], v[70:71] neg_lo:[0,1] neg_hi:[0,1]
	v_pk_add_f32 v[2:3], v[68:69], v[84:85]
	v_pk_add_f32 v[68:69], v[68:69], v[84:85] neg_lo:[0,1] neg_hi:[0,1]
	v_pk_add_f32 v[84:85], v[64:65], v[80:81]
	v_pk_add_f32 v[64:65], v[64:65], v[80:81] neg_lo:[0,1] neg_hi:[0,1]
	v_xor_b32_e32 v80, 0x80000000, v63
	v_mov_b32_e32 v81, v62
	v_pk_add_f32 v[94:95], v[20:21], v[88:89]
	v_pk_add_f32 v[20:21], v[20:21], v[88:89] neg_lo:[0,1] neg_hi:[0,1]
	v_pk_add_f32 v[88:89], v[102:103], v[66:67]
	v_pk_add_f32 v[66:67], v[102:103], v[66:67] neg_lo:[0,1] neg_hi:[0,1]
	v_pk_add_f32 v[62:63], v[24:25], v[80:81]
	v_pk_add_f32 v[24:25], v[24:25], v[80:81] neg_lo:[0,1] neg_hi:[0,1]
	v_pk_add_f32 v[80:81], v[96:97], v[90:91]
	v_pk_add_f32 v[90:91], v[96:97], v[90:91] neg_lo:[0,1] neg_hi:[0,1]
	v_xor_b32_e32 v96, 0x80000000, v71
	v_mov_b32_e32 v97, v70
	v_pk_add_f32 v[70:71], v[72:73], v[96:97]
	v_pk_add_f32 v[72:73], v[72:73], v[96:97] neg_lo:[0,1] neg_hi:[0,1]
	v_pk_add_f32 v[96:97], v[94:95], v[88:89]
	v_pk_add_f32 v[88:89], v[94:95], v[88:89] neg_lo:[0,1] neg_hi:[0,1]
	v_xor_b32_e32 v94, 0x80000000, v67
	v_mov_b32_e32 v95, v66
	v_pk_add_f32 v[66:67], v[20:21], v[94:95]
	v_pk_add_f32 v[20:21], v[20:21], v[94:95] neg_lo:[0,1] neg_hi:[0,1]
	v_pk_add_f32 v[94:95], v[98:99], v[74:75]
	v_pk_add_f32 v[74:75], v[98:99], v[74:75] neg_lo:[0,1] neg_hi:[0,1]
	v_pk_mul_f32 v[98:99], v[10:11], s[60:61] op_sel:[1,0] op_sel_hi:[0,0] neg_lo:[1,0]
	v_xor_b32_e32 v100, 0x80000000, v9
	v_pk_fma_f32 v[10:11], v[10:11], s[60:61], v[98:99] op_sel_hi:[1,0,1]
	v_mov_b32_e32 v101, v8
	v_pk_add_f32 v[98:99], v[18:19], v[10:11]
	v_pk_add_f32 v[10:11], v[18:19], v[10:11] neg_lo:[0,1] neg_hi:[0,1]
	v_xor_b32_e32 v18, 0x80000000, v77
	v_mov_b32_e32 v19, v76
	v_pk_add_f32 v[76:77], v[16:17], v[18:19]
	v_pk_add_f32 v[16:17], v[16:17], v[18:19] neg_lo:[0,1] neg_hi:[0,1]
	v_pk_mul_f32 v[18:19], v[8:9], s[60:61] op_sel_hi:[1,0]
	s_nop 0
	v_pk_fma_f32 v[8:9], v[100:101], s[60:61], v[18:19] op_sel_hi:[1,0,1] neg_lo:[0,0,1] neg_hi:[0,0,1]
	v_xor_b32_e32 v100, 0x80000000, v5
	v_pk_add_f32 v[18:19], v[0:1], v[8:9]
	v_pk_add_f32 v[0:1], v[0:1], v[8:9] neg_lo:[0,1] neg_hi:[0,1]
	v_pk_add_f32 v[8:9], v[82:83], v[78:79]
	v_pk_add_f32 v[78:79], v[82:83], v[78:79] neg_lo:[0,1] neg_hi:[0,1]
	v_pk_mul_f32 v[82:83], v[6:7], s[60:61] op_sel:[1,0] op_sel_hi:[0,0] neg_lo:[1,0]
	v_mov_b32_e32 v101, v4
	v_pk_fma_f32 v[6:7], v[6:7], s[60:61], v[82:83] op_sel_hi:[1,0,1]
	s_nop 0
	v_pk_add_f32 v[82:83], v[14:15], v[6:7]
	v_pk_add_f32 v[6:7], v[14:15], v[6:7] neg_lo:[0,1] neg_hi:[0,1]
	v_xor_b32_e32 v14, 0x80000000, v87
	v_mov_b32_e32 v15, v86
	v_pk_add_f32 v[86:87], v[26:27], v[14:15]
	v_pk_add_f32 v[14:15], v[26:27], v[14:15] neg_lo:[0,1] neg_hi:[0,1]
	v_pk_mul_f32 v[26:27], v[4:5], s[60:61] op_sel_hi:[1,0]
	s_nop 0
	v_pk_fma_f32 v[4:5], v[100:101], s[60:61], v[26:27] op_sel_hi:[1,0,1] neg_lo:[0,0,1] neg_hi:[0,0,1]
	v_xor_b32_e32 v100, 0x80000000, v25
	v_pk_add_f32 v[26:27], v[12:13], v[4:5]
	v_pk_add_f32 v[4:5], v[12:13], v[4:5] neg_lo:[0,1] neg_hi:[0,1]
	v_pk_add_f32 v[12:13], v[92:93], v[84:85]
	v_pk_add_f32 v[84:85], v[92:93], v[84:85] neg_lo:[0,1] neg_hi:[0,1]
	v_pk_mul_f32 v[92:93], v[62:63], s[60:61] op_sel:[1,0] op_sel_hi:[0,0] neg_lo:[1,0]
	v_mov_b32_e32 v101, v24
	v_pk_fma_f32 v[62:63], v[62:63], s[60:61], v[92:93] op_sel_hi:[1,0,1]
	s_nop 0
	v_pk_add_f32 v[92:93], v[2:3], v[62:63]
	v_pk_add_f32 v[2:3], v[2:3], v[62:63] neg_lo:[0,1] neg_hi:[0,1]
	v_xor_b32_e32 v62, 0x80000000, v65
	v_mov_b32_e32 v63, v64
	v_pk_add_f32 v[64:65], v[22:23], v[62:63]
	v_pk_add_f32 v[22:23], v[22:23], v[62:63] neg_lo:[0,1] neg_hi:[0,1]
	v_pk_mul_f32 v[62:63], v[24:25], s[60:61] op_sel_hi:[1,0]
	s_nop 0
	v_pk_fma_f32 v[24:25], v[100:101], s[60:61], v[62:63] op_sel_hi:[1,0,1] neg_lo:[0,0,1] neg_hi:[0,0,1]
	v_xor_b32_e32 v100, 0x80000000, v21
	v_pk_add_f32 v[62:63], v[68:69], v[24:25]
	v_pk_add_f32 v[24:25], v[68:69], v[24:25] neg_lo:[0,1] neg_hi:[0,1]
	v_pk_add_f32 v[68:69], v[80:81], v[96:97]
	v_pk_add_f32 v[80:81], v[80:81], v[96:97] neg_lo:[0,1] neg_hi:[0,1]
	v_pk_mul_f32 v[96:97], v[66:67], s[60:61] op_sel:[1,0] op_sel_hi:[0,0] neg_lo:[1,0]
	v_mov_b32_e32 v101, v20
	v_pk_fma_f32 v[66:67], v[66:67], s[60:61], v[96:97] op_sel_hi:[1,0,1]
	s_nop 0
	v_pk_add_f32 v[96:97], v[70:71], v[66:67]
	v_pk_add_f32 v[66:67], v[70:71], v[66:67] neg_lo:[0,1] neg_hi:[0,1]
	v_xor_b32_e32 v70, 0x80000000, v89
	v_mov_b32_e32 v71, v88
	v_pk_add_f32 v[88:89], v[90:91], v[70:71]
	v_pk_add_f32 v[70:71], v[90:91], v[70:71] neg_lo:[0,1] neg_hi:[0,1]
	v_pk_mul_f32 v[90:91], v[20:21], s[60:61] op_sel_hi:[1,0]
	s_nop 0
	v_pk_fma_f32 v[20:21], v[100:101], s[60:61], v[90:91] op_sel_hi:[1,0,1] neg_lo:[0,0,1] neg_hi:[0,0,1]
	s_nop 0
	v_pk_add_f32 v[90:91], v[72:73], v[20:21]
	v_pk_add_f32 v[20:21], v[72:73], v[20:21] neg_lo:[0,1] neg_hi:[0,1]
	v_pk_add_f32 v[72:73], v[94:95], v[8:9]
	v_pk_add_f32 v[8:9], v[94:95], v[8:9] neg_lo:[0,1] neg_hi:[0,1]
	v_pk_mul_f32 v[94:95], v[82:83], s[54:55] op_sel:[1,0] op_sel_hi:[0,0] neg_lo:[1,0]
	s_nop 0
	v_pk_fma_f32 v[82:83], v[82:83], s[52:53], v[94:95] op_sel_hi:[1,0,1]
	s_nop 0
	v_pk_add_f32 v[94:95], v[98:99], v[82:83]
	v_pk_add_f32 v[82:83], v[98:99], v[82:83] neg_lo:[0,1] neg_hi:[0,1]
	v_pk_mul_f32 v[98:99], v[86:87], s[60:61] op_sel:[1,0] op_sel_hi:[0,0] neg_lo:[1,0]
	s_nop 0
	v_pk_fma_f32 v[86:87], v[86:87], s[60:61], v[98:99] op_sel_hi:[1,0,1]
	s_nop 0
	v_pk_add_f32 v[98:99], v[76:77], v[86:87]
	v_pk_add_f32 v[86:87], v[76:77], v[86:87] neg_lo:[0,1] neg_hi:[0,1]
	v_pk_mul_f32 v[76:77], v[26:27], s[52:53] op_sel:[1,0] op_sel_hi:[0,0] neg_lo:[1,0]
	s_nop 0
	v_pk_fma_f32 v[26:27], v[26:27], s[54:55], v[76:77] op_sel_hi:[1,0,1]
	v_xor_b32_e32 v76, 0x80000000, v67
	v_pk_add_f32 v[100:101], v[18:19], v[26:27]
	v_pk_add_f32 v[26:27], v[18:19], v[26:27] neg_lo:[0,1] neg_hi:[0,1]
	v_pk_add_f32 v[102:103], v[74:75], v[78:79] op_sel:[0,1] op_sel_hi:[1,0] neg_lo:[0,1]
	v_pk_add_f32 v[104:105], v[74:75], v[78:79] op_sel:[0,1] op_sel_hi:[1,0] neg_hi:[0,1]
	v_pk_mul_f32 v[18:19], v[6:7], s[54:55] op_sel_hi:[1,0]
	v_xor_b32_e32 v74, 0x80000000, v7
	v_mov_b32_e32 v75, v6
	v_pk_fma_f32 v[6:7], v[74:75], s[52:53], v[18:19] op_sel_hi:[1,0,1] neg_lo:[0,0,1] neg_hi:[0,0,1]
	v_xor_b32_e32 v74, 0x80000000, v15
	v_pk_add_f32 v[18:19], v[10:11], v[6:7]
	v_pk_add_f32 v[6:7], v[10:11], v[6:7] neg_lo:[0,1] neg_hi:[0,1]
	v_pk_mul_f32 v[10:11], v[14:15], s[60:61] op_sel_hi:[1,0]
	v_mov_b32_e32 v75, v14
	v_pk_fma_f32 v[10:11], v[74:75], s[60:61], v[10:11] op_sel_hi:[1,0,1] neg_lo:[0,0,1] neg_hi:[0,0,1]
	v_xor_b32_e32 v74, 0x80000000, v5
	v_pk_add_f32 v[14:15], v[16:17], v[10:11]
	v_pk_add_f32 v[10:11], v[16:17], v[10:11] neg_lo:[0,1] neg_hi:[0,1]
	v_pk_mul_f32 v[16:17], v[4:5], s[52:53] op_sel_hi:[1,0]
	v_mov_b32_e32 v75, v4
	v_pk_fma_f32 v[4:5], v[74:75], s[54:55], v[16:17] op_sel_hi:[1,0,1] neg_lo:[0,0,1] neg_hi:[0,0,1]
	v_xor_b32_e32 v74, 0x80000000, v89
	v_pk_add_f32 v[16:17], v[0:1], v[4:5]
	v_pk_add_f32 v[106:107], v[0:1], v[4:5] neg_lo:[0,1] neg_hi:[0,1]
	v_pk_add_f32 v[0:1], v[12:13], v[68:69]
	v_pk_add_f32 v[4:5], v[12:13], v[68:69] neg_lo:[0,1] neg_hi:[0,1]
	v_mov_b32_e32 v75, v88
	v_pk_mul_f32 v[12:13], v[96:97], s[54:55] op_sel:[1,0] op_sel_hi:[0,0] neg_lo:[1,0]
	v_pk_mul_f32 v[74:75], v[74:75], s[60:61] op_sel_hi:[1,0]
	v_pk_fma_f32 v[12:13], v[96:97], s[52:53], v[12:13] op_sel_hi:[1,0,1]
	v_pk_fma_f32 v[74:75], v[88:89], s[60:61], v[74:75] op_sel_hi:[1,0,1]
	v_pk_add_f32 v[68:69], v[92:93], v[12:13]
	v_pk_add_f32 v[12:13], v[92:93], v[12:13] neg_lo:[0,1] neg_hi:[0,1]
	v_pk_add_f32 v[88:89], v[64:65], v[74:75]
	v_pk_add_f32 v[92:93], v[64:65], v[74:75] neg_lo:[0,1] neg_hi:[0,1]
	v_pk_mul_f32 v[64:65], v[90:91], s[52:53] op_sel:[1,0] op_sel_hi:[0,0] neg_lo:[1,0]
	v_pk_add_f32 v[78:79], v[72:73], v[0:1]
	v_pk_fma_f32 v[64:65], v[90:91], s[54:55], v[64:65] op_sel_hi:[1,0,1]
	s_nop 0
	v_pk_add_f32 v[74:75], v[62:63], v[64:65]
	v_pk_add_f32 v[90:91], v[62:63], v[64:65] neg_lo:[0,1] neg_hi:[0,1]
	v_pk_mul_f32 v[0:1], v[68:69], s[48:49] op_sel:[1,0] op_sel_hi:[0,0] neg_lo:[1,0]
	v_pk_add_f32 v[64:65], v[84:85], v[80:81] op_sel:[0,1] op_sel_hi:[1,0] neg_lo:[0,1]
	v_pk_add_f32 v[80:81], v[84:85], v[80:81] op_sel:[0,1] op_sel_hi:[1,0] neg_hi:[0,1]
	v_pk_mul_f32 v[62:63], v[66:67], s[54:55] op_sel_hi:[1,0]
	v_mov_b32_e32 v77, v66
	v_pk_fma_f32 v[0:1], v[68:69], s[44:45], v[0:1] op_sel_hi:[1,0,1]
	v_pk_fma_f32 v[62:63], v[76:77], s[52:53], v[62:63] op_sel_hi:[1,0,1] neg_lo:[0,0,1] neg_hi:[0,0,1]
	v_pk_add_f32 v[76:77], v[94:95], v[0:1]
	v_pk_mul_f32 v[0:1], v[88:89], s[54:55] op_sel:[1,0] op_sel_hi:[0,0] neg_lo:[1,0]
	v_pk_add_f32 v[84:85], v[2:3], v[62:63]
	v_pk_fma_f32 v[0:1], v[88:89], s[52:53], v[0:1] op_sel_hi:[1,0,1]
	v_pk_add_f32 v[2:3], v[2:3], v[62:63] neg_lo:[0,1] neg_hi:[0,1]
	v_pk_add_f32 v[72:73], v[98:99], v[0:1]
	v_pk_mul_f32 v[0:1], v[74:75], s[58:59] op_sel:[1,0] op_sel_hi:[0,0] neg_lo:[1,0]
	v_pk_mul_f32 v[62:63], v[70:71], s[60:61] op_sel_hi:[1,0]
	v_pk_fma_f32 v[0:1], v[74:75], s[56:57], v[0:1] op_sel_hi:[1,0,1]
	v_xor_b32_e32 v66, 0x80000000, v71
	v_pk_add_f32 v[74:75], v[100:101], v[0:1]
	v_pk_mul_f32 v[0:1], v[64:65], s[60:61] op_sel:[1,0] op_sel_hi:[0,0] neg_lo:[1,0]
	v_mov_b32_e32 v67, v70
	v_pk_fma_f32 v[0:1], v[64:65], s[60:61], v[0:1] op_sel_hi:[1,0,1]
	v_pk_fma_f32 v[62:63], v[66:67], s[60:61], v[62:63] op_sel_hi:[1,0,1] neg_lo:[0,0,1] neg_hi:[0,0,1]
	v_pk_add_f32 v[66:67], v[102:103], v[0:1]
	v_pk_mul_f32 v[0:1], v[84:85], s[56:57] op_sel:[1,0] op_sel_hi:[0,0] neg_lo:[1,0]
	v_pk_add_f32 v[70:71], v[22:23], v[62:63]
	v_pk_fma_f32 v[0:1], v[84:85], s[58:59], v[0:1] op_sel_hi:[1,0,1]
	v_pk_add_f32 v[96:97], v[22:23], v[62:63] neg_lo:[0,1] neg_hi:[0,1]
	v_pk_mul_f32 v[22:23], v[20:21], s[52:53] op_sel_hi:[1,0]
	v_pk_add_f32 v[68:69], v[18:19], v[0:1]
	v_pk_fma_f32 v[20:21], v[20:21], s[54:55], v[22:23] op_sel:[1,0,0] op_sel_hi:[0,0,1] neg_lo:[1,0,1] neg_hi:[0,0,1]
	v_pk_mul_f32 v[0:1], v[70:71], s[52:53] op_sel:[1,0] op_sel_hi:[0,0] neg_lo:[1,0]
	v_pk_add_f32 v[22:23], v[24:25], v[20:21]
	v_pk_fma_f32 v[0:1], v[70:71], s[54:55], v[0:1] op_sel_hi:[1,0,1]
	v_pk_add_f32 v[108:109], v[24:25], v[20:21] neg_lo:[0,1] neg_hi:[0,1]
	v_pk_add_f32 v[62:63], v[14:15], v[0:1]
	v_pk_mul_f32 v[0:1], v[22:23], s[44:45] op_sel:[1,0] op_sel_hi:[0,0] neg_lo:[1,0]
	s_nop 0
	v_pk_fma_f32 v[0:1], v[22:23], s[48:49], v[0:1] op_sel_hi:[1,0,1]
	s_nop 0
	v_pk_add_f32 v[64:65], v[16:17], v[0:1]
	v_pk_add_f32 v[22:23], v[8:9], v[4:5] op_sel:[0,1] op_sel_hi:[1,0] neg_lo:[0,1]
	v_pk_mul_f32 v[0:1], v[12:13], s[48:49] op_sel_hi:[1,0]
	v_xor_b32_e32 v4, 0x80000000, v13
	v_mov_b32_e32 v5, v12
	v_pk_fma_f32 v[0:1], v[4:5], s[44:45], v[0:1] op_sel_hi:[1,0,1] neg_lo:[0,0,1] neg_hi:[0,0,1]
	v_xor_b32_e32 v4, 0x80000000, v93
	v_pk_add_f32 v[24:25], v[82:83], v[0:1]
	v_pk_mul_f32 v[0:1], v[92:93], s[54:55] op_sel_hi:[1,0]
	v_mov_b32_e32 v5, v92
	v_pk_fma_f32 v[0:1], v[4:5], s[52:53], v[0:1] op_sel_hi:[1,0,1] neg_lo:[0,0,1] neg_hi:[0,0,1]
	v_xor_b32_e32 v4, 0x80000000, v91
	v_pk_add_f32 v[18:19], v[86:87], v[0:1]
	v_pk_mul_f32 v[0:1], v[90:91], s[58:59] op_sel_hi:[1,0]
	v_mov_b32_e32 v5, v90
	v_pk_fma_f32 v[0:1], v[4:5], s[56:57], v[0:1] op_sel_hi:[1,0,1] neg_lo:[0,0,1] neg_hi:[0,0,1]
	s_nop 0
	v_pk_add_f32 v[20:21], v[26:27], v[0:1]
	v_pk_mul_f32 v[0:1], v[80:81], s[60:61] op_sel_hi:[1,0]
	s_nop 0
	v_pk_fma_f32 v[0:1], v[80:81], s[60:61], v[0:1] op_sel:[1,0,0] op_sel_hi:[0,0,1] neg_lo:[1,0,1] neg_hi:[0,0,1]
	v_xor_b32_e32 v8, 0x80000000, v3
	v_pk_add_f32 v[4:5], v[104:105], v[0:1]
	v_pk_mul_f32 v[0:1], v[2:3], s[56:57] op_sel_hi:[1,0]
	v_mov_b32_e32 v9, v2
	v_pk_fma_f32 v[0:1], v[8:9], s[58:59], v[0:1] op_sel_hi:[1,0,1] neg_lo:[0,0,1] neg_hi:[0,0,1]
	s_nop 0
	v_pk_add_f32 v[6:7], v[6:7], v[0:1]
	v_pk_mul_f32 v[0:1], v[96:97], s[52:53] op_sel_hi:[1,0]
	s_nop 0
	v_pk_fma_f32 v[0:1], v[96:97], s[54:55], v[0:1] op_sel:[1,0,0] op_sel_hi:[0,0,1] neg_lo:[1,0,1] neg_hi:[0,0,1]
	v_pk_mul_f32 v[2:3], v[108:109], s[44:45] op_sel_hi:[1,0]
	v_pk_add_f32 v[0:1], v[10:11], v[0:1]
	v_xor_b32_e32 v8, 0x80000000, v109
	v_mov_b32_e32 v9, v108
	v_mov_b32_e32 v10, v146
	v_pk_fma_f32 v[2:3], v[8:9], s[48:49], v[2:3] op_sel_hi:[1,0,1] neg_lo:[0,0,1] neg_hi:[0,0,1]
	global_load_dword v8, v145, s[0:1]
	s_movk_i32 s0, 0x200
	s_cselect_b32 s4, s0, 0x400
	s_add_i32 s0, s4, s62
	s_ashr_i32 s1, s0, 31
	s_lshl_b32 s6, s4, 2
	s_add_u32 s4, s64, s6
	s_addc_u32 s5, s65, 0
	s_lshl_b64 s[0:1], s[0:1], 14
	v_min_i32_e32 v70, 0x1ffe, v10
	v_mov_b32_e32 v9, s6
	s_add_u32 s36, s26, s0
	v_ashrrev_i32_e32 v11, 31, v10
	v_ashrrev_i32_e32 v71, 31, v70
	global_load_dword v16, v9, s[64:65]
	global_load_dword v14, v151, s[4:5] offset:2048
	global_load_dword v17, v152, s[4:5]
	global_load_dword v12, v9, s[68:69]
	s_addc_u32 s37, s27, s1
	v_max_i32_e32 v9, 1, v10
	v_lshlrev_b64 v[82:83], 1, v[10:11]
	v_lshlrev_b64 v[84:85], 1, v[70:71]
	v_lshl_add_u64 v[26:27], s[36:37], 0, v[82:83]
	v_lshlrev_b32_e32 v9, 1, v9
	v_lshl_add_u64 v[70:71], s[36:37], 0, v[84:85]
	global_load_ushort v13, v[26:27], off
	s_add_u32 s72, s30, s0
	global_load_ushort v70, v[70:71], off offset:2
	s_addc_u32 s73, s31, s1
	global_load_ushort v15, v9, s[36:37] offset:-2
	v_cmp_lt_i32_e64 s[0:1], 0, v10
	v_cmp_gt_i32_e64 s[4:5], s88, v10
	v_pk_add_f32 v[2:3], v[106:107], v[2:3]
	v_cndmask_b32_e64 v81, 0, 1.0, s[0:1]
	v_cndmask_b32_e64 v86, 0, 1.0, s[4:5]
	v_add_u32_e32 v92, 0x200, v10
	v_cmp_lt_i32_e64 s[20:21], s33, v10
	v_cmp_gt_i32_e64 s[18:19], s92, v10
	v_add_u32_e32 v90, 0x400, v10
	v_cmp_lt_i32_e64 s[16:17], s81, v10
	v_cmp_gt_i32_e64 s[0:1], s38, v10
	v_add_u32_e32 v88, 0x600, v10
	v_cmp_lt_i32_e64 s[12:13], s93, v10
	v_cmp_gt_i32_e64 s[10:11], s3, v10
	v_cmp_lt_i32_e64 s[8:9], s50, v10
	v_cmp_gt_i32_e64 s[6:7], s90, v10
	v_cmp_lt_i32_e64 s[4:5], s39, v10
	v_cmp_gt_i32_e64 s[22:23], s51, v10
	s_waitcnt vmcnt(2)
	v_lshlrev_b32_e32 v13, 16, v13
	s_waitcnt vmcnt(1)
	v_lshlrev_b32_e32 v70, 16, v70
	v_mul_f32_e32 v70, v86, v70
	s_waitcnt vmcnt(0)
	v_lshlrev_b32_e32 v15, 16, v15
	v_mul_f32_e32 v15, v81, v15
	v_mul_f32_e32 v15, v16, v15
	v_fmac_f32_e32 v15, v14, v13
	v_fmac_f32_e32 v15, v17, v70
	v_lshl_add_u64 v[70:71], s[72:73], 0, v[82:83]
	v_lshl_add_u64 v[82:83], s[72:73], 0, v[84:85]
	v_add_f32_e32 v80, v12, v15
	global_load_ushort v13, v[70:71], off
	global_load_ushort v15, v[82:83], off offset:2
	v_add_u32_e32 v84, 0x800, v10
	global_load_ushort v9, v9, s[72:73] offset:-2
	v_add_u32_e32 v82, 0xa00, v10
	s_waitcnt vmcnt(2)
	v_lshlrev_b32_e32 v13, 16, v13
	s_waitcnt vmcnt(1)
	v_lshlrev_b32_e32 v15, 16, v15
	v_mul_f32_e32 v15, v86, v15
	s_waitcnt vmcnt(0)
	v_lshlrev_b32_e32 v9, 16, v9
	v_mul_f32_e32 v9, v81, v9
	v_mul_f32_e32 v9, v16, v9
	v_fmac_f32_e32 v9, v14, v13
	v_fmac_f32_e32 v9, v17, v15
	v_add_f32_e32 v86, v12, v9
	s_cbranch_vccnz .LBB0_912
	s_mov_b32 s98, s29
	s_lshl_b64 s[0:1], s[66:67], 1
	s_add_u32 s4, s0, s30
	s_addc_u32 s5, s1, s31
	s_add_u32 s0, s0, s26
	s_addc_u32 s1, s1, s27
	s_add_u32 s18, s70, 0x800000
	s_addc_u32 s19, s71, 0
	s_cmpk_gt_i32 s98, 0xff
	s_cbranch_scc1 .Lhy_ep1_comb_L1
	v_lshlrev_b32_e32 v109, 1, v10
	v_add_u32_e32 v254, 0x1e00, v10
	v_add_u32_e32 v253, 0x1000, v109
	v_cmp_gt_i32_e32 vcc, 0x1fff, v254
	v_add_u32_e32 v251, 0x2000, v109
	v_add_u32_e32 v250, 0x3000, v109
	v_min_i32_e32 v254, 0x1ffe, v254
	v_cndmask_b32_e64 v255, 0, 1.0, vcc
	v_lshlrev_b32_e32 v254, 1, v254
	global_load_ushort v9, v109, s[0:1]
	global_load_ushort v11, v109, s[4:5]
	global_load_ushort v13, v109, s[36:37] offset:1022
	global_load_ushort v15, v109, s[36:37] offset:1024
	global_load_ushort v81, v109, s[36:37] offset:1026
	global_load_ushort v83, v109, s[72:73] offset:1022
	global_load_ushort v85, v109, s[72:73] offset:1024
	global_load_ushort v87, v109, s[72:73] offset:1026
	global_load_ushort v89, v109, s[0:1] offset:1024
	global_load_ushort v91, v109, s[4:5] offset:1024
	global_load_ushort v93, v109, s[36:37] offset:2046
	global_load_ushort v94, v109, s[36:37] offset:2048
	global_load_ushort v95, v109, s[36:37] offset:2050
	global_load_ushort v96, v109, s[72:73] offset:2046
	global_load_ushort v97, v109, s[72:73] offset:2048
	global_load_ushort v98, v109, s[72:73] offset:2050
	global_load_ushort v99, v109, s[0:1] offset:2048
	global_load_ushort v100, v109, s[4:5] offset:2048
	global_load_ushort v101, v109, s[36:37] offset:3070
	global_load_ushort v102, v109, s[36:37] offset:3072
	global_load_ushort v103, v109, s[36:37] offset:3074
	global_load_ushort v104, v109, s[72:73] offset:3070
	global_load_ushort v105, v109, s[72:73] offset:3072
	global_load_ushort v106, v109, s[72:73] offset:3074
	global_load_ushort v107, v109, s[0:1] offset:3072
	global_load_ushort v108, v109, s[4:5] offset:3072
	global_load_ushort v111, v253, s[36:37] offset:-2
	global_load_ushort v112, v253, s[36:37]
	global_load_ushort v113, v253, s[36:37] offset:2
	global_load_ushort v114, v253, s[72:73] offset:-2
	global_load_ushort v115, v253, s[72:73]
	global_load_ushort v116, v253, s[72:73] offset:2
	global_load_ushort v117, v253, s[0:1]
	global_load_ushort v118, v253, s[4:5]
	global_load_ushort v119, v253, s[36:37] offset:1022
	global_load_ushort v120, v253, s[36:37] offset:1024
	global_load_ushort v121, v253, s[36:37] offset:1026
	global_load_ushort v122, v253, s[72:73] offset:1022
	global_load_ushort v123, v253, s[72:73] offset:1024
	global_load_ushort v124, v253, s[72:73] offset:1026
	global_load_ushort v125, v253, s[0:1] offset:1024
	global_load_ushort v126, v253, s[4:5] offset:1024
	global_load_ushort v127, v253, s[36:37] offset:2046
	global_load_ushort v128, v253, s[36:37] offset:2048
	global_load_ushort v129, v253, s[36:37] offset:2050
	global_load_ushort v130, v253, s[72:73] offset:2046
	global_load_ushort v131, v253, s[72:73] offset:2048
	global_load_ushort v132, v253, s[72:73] offset:2050
	global_load_ushort v133, v253, s[0:1] offset:2048
	global_load_ushort v134, v253, s[4:5] offset:2048
	global_load_ushort v135, v253, s[36:37] offset:3070
	global_load_ushort v136, v253, s[36:37] offset:3072
	global_load_ushort v137, v253, s[36:37] offset:3074
	global_load_ushort v138, v253, s[72:73] offset:3070
	global_load_ushort v139, v253, s[72:73] offset:3072
	global_load_ushort v140, v253, s[72:73] offset:3074
	global_load_ushort v141, v253, s[0:1] offset:3072
	global_load_ushort v142, v253, s[4:5] offset:3072
	global_load_ushort v143, v251, s[36:37] offset:-2
	global_load_ushort v163, v251, s[36:37]
	global_load_ushort v164, v251, s[36:37] offset:2
	global_load_ushort v165, v251, s[72:73] offset:-2
	global_load_ushort v166, v251, s[72:73]
	global_load_ushort v167, v251, s[72:73] offset:2
	global_load_ushort v168, v251, s[0:1]
	global_load_ushort v169, v251, s[4:5]
	global_load_ushort v170, v251, s[36:37] offset:1022
	global_load_ushort v171, v251, s[36:37] offset:1024
	global_load_ushort v172, v251, s[36:37] offset:1026
	global_load_ushort v173, v251, s[72:73] offset:1022
	global_load_ushort v174, v251, s[72:73] offset:1024
	global_load_ushort v175, v251, s[72:73] offset:1026
	global_load_ushort v176, v251, s[0:1] offset:1024
	global_load_ushort v177, v251, s[4:5] offset:1024
	global_load_ushort v178, v251, s[36:37] offset:2046
	global_load_ushort v179, v251, s[36:37] offset:2048
	global_load_ushort v180, v251, s[36:37] offset:2050
	global_load_ushort v181, v251, s[72:73] offset:2046
	global_load_ushort v182, v251, s[72:73] offset:2048
	global_load_ushort v183, v251, s[72:73] offset:2050
	global_load_ushort v184, v251, s[0:1] offset:2048
	global_load_ushort v185, v251, s[4:5] offset:2048
	global_load_ushort v186, v251, s[36:37] offset:3070
	global_load_ushort v187, v251, s[36:37] offset:3072
	global_load_ushort v188, v251, s[36:37] offset:3074
	global_load_ushort v189, v251, s[72:73] offset:3070
	global_load_ushort v190, v251, s[72:73] offset:3072
	global_load_ushort v191, v251, s[72:73] offset:3074
	global_load_ushort v192, v251, s[0:1] offset:3072
	global_load_ushort v193, v251, s[4:5] offset:3072
	global_load_ushort v194, v250, s[36:37] offset:-2
	global_load_ushort v195, v250, s[36:37]
	global_load_ushort v196, v250, s[36:37] offset:2
	global_load_ushort v197, v250, s[72:73] offset:-2
	global_load_ushort v221, v250, s[72:73]
	global_load_ushort v222, v250, s[72:73] offset:2
	global_load_ushort v223, v250, s[0:1]
	global_load_ushort v224, v250, s[4:5]
	global_load_ushort v225, v250, s[36:37] offset:1022
	global_load_ushort v226, v250, s[36:37] offset:1024
	global_load_ushort v227, v250, s[36:37] offset:1026
	global_load_ushort v228, v250, s[72:73] offset:1022
	global_load_ushort v229, v250, s[72:73] offset:1024
	global_load_ushort v230, v250, s[72:73] offset:1026
	global_load_ushort v231, v250, s[0:1] offset:1024
	global_load_ushort v232, v250, s[4:5] offset:1024
	global_load_ushort v233, v250, s[36:37] offset:2046
	global_load_ushort v234, v250, s[36:37] offset:2048
	global_load_ushort v235, v250, s[36:37] offset:2050
	global_load_ushort v236, v250, s[72:73] offset:2046
	global_load_ushort v237, v250, s[72:73] offset:2048
	global_load_ushort v238, v250, s[72:73] offset:2050
	global_load_ushort v239, v250, s[0:1] offset:2048
	global_load_ushort v240, v250, s[4:5] offset:2048
	global_load_ushort v241, v250, s[36:37] offset:3070
	global_load_ushort v242, v250, s[36:37] offset:3072
	global_load_ushort v243, v254, s[36:37] offset:2
	global_load_ushort v244, v250, s[72:73] offset:3070
	global_load_ushort v245, v250, s[72:73] offset:3072
	global_load_ushort v246, v254, s[72:73] offset:2
	global_load_ushort v247, v250, s[0:1] offset:3072
	global_load_ushort v248, v250, s[4:5] offset:3072
	s_waitcnt vmcnt(63)
	v_fma_f32 v27, v32, v8, v78
	v_mul_f32_e32 v70, v80, v27
	v_lshlrev_b32_e32 v9, 16, v9
	v_mul_f32_e32 v84, 0xbfb8aa3b, v9
	v_exp_f32_e32 v84, v84
	s_nop 0
	v_add_f32_e32 v84, 1.0, v84
	v_div_scale_f32 v71, s[74:75], v84, v84, v9
	v_rcp_f32_e32 v82, v71
	s_nop 0
	v_fma_f32 v92, -v71, v82, 1.0
	v_fmac_f32_e32 v82, v92, v82
	v_div_scale_f32 v88, vcc, v9, v84, v9
	v_mul_f32_e32 v90, v88, v82
	v_fma_f32 v92, -v71, v90, v88
	v_fmac_f32_e32 v90, v92, v82
	v_fma_f32 v71, -v71, v90, v88
	v_div_fmas_f32 v71, v71, v82, v90
	v_div_fixup_f32 v9, v71, v84, v9
	v_mul_f32_e32 v70, v70, v9
	v_fma_f32 v27, v34, v8, v79
	v_mul_f32_e32 v110, v86, v27
	v_lshlrev_b32_e32 v11, 16, v11
	v_mul_f32_e32 v84, 0xbfb8aa3b, v11
	v_exp_f32_e32 v84, v84
	s_nop 0
	v_add_f32_e32 v84, 1.0, v84
	v_div_scale_f32 v71, s[74:75], v84, v84, v11
	v_rcp_f32_e32 v82, v71
	s_nop 0
	v_fma_f32 v92, -v71, v82, 1.0
	v_fmac_f32_e32 v82, v92, v82
	v_div_scale_f32 v88, vcc, v11, v84, v11
	v_mul_f32_e32 v90, v88, v82
	v_fma_f32 v92, -v71, v90, v88
	v_fmac_f32_e32 v90, v92, v82
	v_fma_f32 v71, -v71, v90, v88
	v_div_fmas_f32 v71, v71, v82, v90
	v_div_fixup_f32 v11, v71, v84, v11
	v_mul_f32_e32 v110, v110, v11
	v_cvt_pk_bf16_f32 v198, v70, v110
	v_lshlrev_b32_e32 v15, 16, v15
	v_lshlrev_b32_e32 v81, 16, v81
	v_lshlrev_b32_e32 v13, 16, v13
	v_mul_f32_e32 v13, v16, v13
	v_fmac_f32_e32 v13, v14, v15
	v_fmac_f32_e32 v13, v17, v81
	v_add_f32_e32 v13, v12, v13
	v_fma_f32 v27, v33, v8, v76
	v_mul_f32_e32 v70, v27, v13
	v_lshlrev_b32_e32 v89, 16, v89
	v_mul_f32_e32 v84, 0xbfb8aa3b, v89
	v_exp_f32_e32 v84, v84
	s_nop 0
	v_add_f32_e32 v84, 1.0, v84
	v_div_scale_f32 v71, s[74:75], v84, v84, v89
	v_rcp_f32_e32 v82, v71
	s_nop 0
	v_fma_f32 v92, -v71, v82, 1.0
	v_fmac_f32_e32 v82, v92, v82
	v_div_scale_f32 v88, vcc, v89, v84, v89
	v_mul_f32_e32 v90, v88, v82
	v_fma_f32 v92, -v71, v90, v88
	v_fmac_f32_e32 v90, v92, v82
	v_fma_f32 v71, -v71, v90, v88
	v_div_fmas_f32 v71, v71, v82, v90
	v_div_fixup_f32 v89, v71, v84, v89
	v_mul_f32_e32 v70, v70, v89
	v_lshlrev_b32_e32 v85, 16, v85
	v_lshlrev_b32_e32 v87, 16, v87
	v_lshlrev_b32_e32 v83, 16, v83
	v_mul_f32_e32 v83, v16, v83
	v_fmac_f32_e32 v83, v14, v85
	v_fmac_f32_e32 v83, v17, v87
	v_add_f32_e32 v83, v12, v83
	v_fma_f32 v27, v35, v8, v77
	v_mul_f32_e32 v110, v27, v83
	v_lshlrev_b32_e32 v91, 16, v91
	v_mul_f32_e32 v84, 0xbfb8aa3b, v91
	v_exp_f32_e32 v84, v84
	s_nop 0
	v_add_f32_e32 v84, 1.0, v84
	v_div_scale_f32 v71, s[74:75], v84, v84, v91
	v_rcp_f32_e32 v82, v71
	s_nop 0
	v_fma_f32 v92, -v71, v82, 1.0
	v_fmac_f32_e32 v82, v92, v82
	v_div_scale_f32 v88, vcc, v91, v84, v91
	v_mul_f32_e32 v90, v88, v82
	v_fma_f32 v92, -v71, v90, v88
	v_fmac_f32_e32 v90, v92, v82
	v_fma_f32 v71, -v71, v90, v88
	v_div_fmas_f32 v71, v71, v82, v90
	v_div_fixup_f32 v91, v71, v84, v91
	v_mul_f32_e32 v110, v110, v91
	v_cvt_pk_bf16_f32 v199, v70, v110
	v_lshlrev_b32_e32 v94, 16, v94
	v_lshlrev_b32_e32 v95, 16, v95
	v_lshlrev_b32_e32 v93, 16, v93
	v_mul_f32_e32 v93, v16, v93
	v_fmac_f32_e32 v93, v14, v94
	v_fmac_f32_e32 v93, v17, v95
	v_add_f32_e32 v93, v12, v93
	v_fma_f32 v27, v37, v8, v72
	v_mul_f32_e32 v70, v27, v93
	v_lshlrev_b32_e32 v99, 16, v99
	v_mul_f32_e32 v84, 0xbfb8aa3b, v99
	v_exp_f32_e32 v84, v84
	s_nop 0
	v_add_f32_e32 v84, 1.0, v84
	v_div_scale_f32 v71, s[74:75], v84, v84, v99
	v_rcp_f32_e32 v82, v71
	s_nop 0
	v_fma_f32 v92, -v71, v82, 1.0
	v_fmac_f32_e32 v82, v92, v82
	v_div_scale_f32 v88, vcc, v99, v84, v99
	v_mul_f32_e32 v90, v88, v82
	v_fma_f32 v92, -v71, v90, v88
	v_fmac_f32_e32 v90, v92, v82
	v_fma_f32 v71, -v71, v90, v88
	v_div_fmas_f32 v71, v71, v82, v90
	v_div_fixup_f32 v99, v71, v84, v99
	v_mul_f32_e32 v70, v70, v99
	v_lshlrev_b32_e32 v97, 16, v97
	v_lshlrev_b32_e32 v98, 16, v98
	v_lshlrev_b32_e32 v96, 16, v96
	v_mul_f32_e32 v96, v16, v96
	v_fmac_f32_e32 v96, v14, v97
	v_fmac_f32_e32 v96, v17, v98
	v_add_f32_e32 v96, v12, v96
	v_fma_f32 v27, v31, v8, v73
	v_mul_f32_e32 v110, v27, v96
	v_lshlrev_b32_e32 v100, 16, v100
	v_mul_f32_e32 v84, 0xbfb8aa3b, v100
	v_exp_f32_e32 v84, v84
	s_nop 0
	v_add_f32_e32 v84, 1.0, v84
	v_div_scale_f32 v71, s[74:75], v84, v84, v100
	v_rcp_f32_e32 v82, v71
	s_nop 0
	v_fma_f32 v92, -v71, v82, 1.0
	v_fmac_f32_e32 v82, v92, v82
	v_div_scale_f32 v88, vcc, v100, v84, v100
	v_mul_f32_e32 v90, v88, v82
	v_fma_f32 v92, -v71, v90, v88
	v_fmac_f32_e32 v90, v92, v82
	v_fma_f32 v71, -v71, v90, v88
	v_div_fmas_f32 v71, v71, v82, v90
	v_div_fixup_f32 v100, v71, v84, v100
	v_mul_f32_e32 v110, v110, v100
	v_cvt_pk_bf16_f32 v200, v70, v110
	v_lshlrev_b32_e32 v102, 16, v102
	v_lshlrev_b32_e32 v103, 16, v103
	v_lshlrev_b32_e32 v101, 16, v101
	v_mul_f32_e32 v101, v16, v101
	v_fmac_f32_e32 v101, v14, v102
	v_fmac_f32_e32 v101, v17, v103
	v_add_f32_e32 v101, v12, v101
	v_fma_f32 v27, v36, v8, v74
	v_mul_f32_e32 v70, v27, v101
	v_lshlrev_b32_e32 v107, 16, v107
	v_mul_f32_e32 v84, 0xbfb8aa3b, v107
	v_exp_f32_e32 v84, v84
	s_nop 0
	v_add_f32_e32 v84, 1.0, v84
	v_div_scale_f32 v71, s[74:75], v84, v84, v107
	v_rcp_f32_e32 v82, v71
	s_nop 0
	v_fma_f32 v92, -v71, v82, 1.0
	v_fmac_f32_e32 v82, v92, v82
	v_div_scale_f32 v88, vcc, v107, v84, v107
	v_mul_f32_e32 v90, v88, v82
	v_fma_f32 v92, -v71, v90, v88
	v_fmac_f32_e32 v90, v92, v82
	v_fma_f32 v71, -v71, v90, v88
	v_div_fmas_f32 v71, v71, v82, v90
	v_div_fixup_f32 v107, v71, v84, v107
	v_mul_f32_e32 v70, v70, v107
	v_lshlrev_b32_e32 v105, 16, v105
	v_lshlrev_b32_e32 v106, 16, v106
	v_lshlrev_b32_e32 v104, 16, v104
	v_mul_f32_e32 v104, v16, v104
	v_fmac_f32_e32 v104, v14, v105
	v_fmac_f32_e32 v104, v17, v106
	v_add_f32_e32 v104, v12, v104
	v_fma_f32 v27, v30, v8, v75
	v_mul_f32_e32 v110, v27, v104
	v_lshlrev_b32_e32 v108, 16, v108
	v_mul_f32_e32 v84, 0xbfb8aa3b, v108
	v_exp_f32_e32 v84, v84
	s_nop 0
	v_add_f32_e32 v84, 1.0, v84
	v_div_scale_f32 v71, s[74:75], v84, v84, v108
	v_rcp_f32_e32 v82, v71
	s_nop 0
	v_fma_f32 v92, -v71, v82, 1.0
	v_fmac_f32_e32 v82, v92, v82
	v_div_scale_f32 v88, vcc, v108, v84, v108
	v_mul_f32_e32 v90, v88, v82
	v_fma_f32 v92, -v71, v90, v88
	v_fmac_f32_e32 v90, v92, v82
	v_fma_f32 v71, -v71, v90, v88
	v_div_fmas_f32 v71, v71, v82, v90
	v_div_fixup_f32 v108, v71, v84, v108
	v_mul_f32_e32 v110, v110, v108
	v_cvt_pk_bf16_f32 v201, v70, v110
	s_waitcnt vmcnt(63)
	v_lshlrev_b32_e32 v112, 16, v112
	v_lshlrev_b32_e32 v113, 16, v113
	v_lshlrev_b32_e32 v111, 16, v111
	v_mul_f32_e32 v111, v16, v111
	v_fmac_f32_e32 v111, v14, v112
	v_fmac_f32_e32 v111, v17, v113
	v_add_f32_e32 v111, v12, v111
	v_fma_f32 v27, v39, v8, v66
	v_mul_f32_e32 v70, v27, v111
	v_lshlrev_b32_e32 v117, 16, v117
	v_mul_f32_e32 v84, 0xbfb8aa3b, v117
	v_exp_f32_e32 v84, v84
	s_nop 0
	v_add_f32_e32 v84, 1.0, v84
	v_div_scale_f32 v71, s[74:75], v84, v84, v117
	v_rcp_f32_e32 v82, v71
	s_nop 0
	v_fma_f32 v92, -v71, v82, 1.0
	v_fmac_f32_e32 v82, v92, v82
	v_div_scale_f32 v88, vcc, v117, v84, v117
	v_mul_f32_e32 v90, v88, v82
	v_fma_f32 v92, -v71, v90, v88
	v_fmac_f32_e32 v90, v92, v82
	v_fma_f32 v71, -v71, v90, v88
	v_div_fmas_f32 v71, v71, v82, v90
	v_div_fixup_f32 v117, v71, v84, v117
	v_mul_f32_e32 v70, v70, v117
	v_lshlrev_b32_e32 v115, 16, v115
	v_lshlrev_b32_e32 v116, 16, v116
	v_lshlrev_b32_e32 v114, 16, v114
	v_mul_f32_e32 v114, v16, v114
	v_fmac_f32_e32 v114, v14, v115
	v_fmac_f32_e32 v114, v17, v116
	v_add_f32_e32 v114, v12, v114
	v_fma_f32 v27, v41, v8, v67
	v_mul_f32_e32 v110, v27, v114
	v_lshlrev_b32_e32 v118, 16, v118
	v_mul_f32_e32 v84, 0xbfb8aa3b, v118
	v_exp_f32_e32 v84, v84
	s_nop 0
	v_add_f32_e32 v84, 1.0, v84
	v_div_scale_f32 v71, s[74:75], v84, v84, v118
	v_rcp_f32_e32 v82, v71
	s_nop 0
	v_fma_f32 v92, -v71, v82, 1.0
	v_fmac_f32_e32 v82, v92, v82
	v_div_scale_f32 v88, vcc, v118, v84, v118
	v_mul_f32_e32 v90, v88, v82
	v_fma_f32 v92, -v71, v90, v88
	v_fmac_f32_e32 v90, v92, v82
	v_fma_f32 v71, -v71, v90, v88
	v_div_fmas_f32 v71, v71, v82, v90
	v_div_fixup_f32 v118, v71, v84, v118
	v_mul_f32_e32 v110, v110, v118
	v_cvt_pk_bf16_f32 v202, v70, v110
	v_lshlrev_b32_e32 v120, 16, v120
	v_lshlrev_b32_e32 v121, 16, v121
	v_lshlrev_b32_e32 v119, 16, v119
	v_mul_f32_e32 v119, v16, v119
	v_fmac_f32_e32 v119, v14, v120
	v_fmac_f32_e32 v119, v17, v121
	v_add_f32_e32 v119, v12, v119
	v_fma_f32 v27, v38, v8, v68
	v_mul_f32_e32 v70, v27, v119
	v_lshlrev_b32_e32 v125, 16, v125
	v_mul_f32_e32 v84, 0xbfb8aa3b, v125
	v_exp_f32_e32 v84, v84
	s_nop 0
	v_add_f32_e32 v84, 1.0, v84
	v_div_scale_f32 v71, s[74:75], v84, v84, v125
	v_rcp_f32_e32 v82, v71
	s_nop 0
	v_fma_f32 v92, -v71, v82, 1.0
	v_fmac_f32_e32 v82, v92, v82
	v_div_scale_f32 v88, vcc, v125, v84, v125
	v_mul_f32_e32 v90, v88, v82
	v_fma_f32 v92, -v71, v90, v88
	v_fmac_f32_e32 v90, v92, v82
	v_fma_f32 v71, -v71, v90, v88
	v_div_fmas_f32 v71, v71, v82, v90
	v_div_fixup_f32 v125, v71, v84, v125
	v_mul_f32_e32 v70, v70, v125
	v_lshlrev_b32_e32 v123, 16, v123
	v_lshlrev_b32_e32 v124, 16, v124
	v_lshlrev_b32_e32 v122, 16, v122
	v_mul_f32_e32 v122, v16, v122
	v_fmac_f32_e32 v122, v14, v123
	v_fmac_f32_e32 v122, v17, v124
	v_add_f32_e32 v122, v12, v122
	v_fma_f32 v27, v40, v8, v69
	v_mul_f32_e32 v110, v27, v122
	v_lshlrev_b32_e32 v126, 16, v126
	v_mul_f32_e32 v84, 0xbfb8aa3b, v126
	v_exp_f32_e32 v84, v84
	s_nop 0
	v_add_f32_e32 v84, 1.0, v84
	v_div_scale_f32 v71, s[74:75], v84, v84, v126
	v_rcp_f32_e32 v82, v71
	s_nop 0
	v_fma_f32 v92, -v71, v82, 1.0
	v_fmac_f32_e32 v82, v92, v82
	v_div_scale_f32 v88, vcc, v126, v84, v126
	v_mul_f32_e32 v90, v88, v82
	v_fma_f32 v92, -v71, v90, v88
	v_fmac_f32_e32 v90, v92, v82
	v_fma_f32 v71, -v71, v90, v88
	v_div_fmas_f32 v71, v71, v82, v90
	v_div_fixup_f32 v126, v71, v84, v126
	v_mul_f32_e32 v110, v110, v126
	v_cvt_pk_bf16_f32 v203, v70, v110
	v_lshlrev_b32_e32 v128, 16, v128
	v_lshlrev_b32_e32 v129, 16, v129
	v_lshlrev_b32_e32 v127, 16, v127
	v_mul_f32_e32 v127, v16, v127
	v_fmac_f32_e32 v127, v14, v128
	v_fmac_f32_e32 v127, v17, v129
	v_add_f32_e32 v127, v12, v127
	v_fma_f32 v27, v43, v8, v62
	v_mul_f32_e32 v70, v27, v127
	v_lshlrev_b32_e32 v133, 16, v133
	v_mul_f32_e32 v84, 0xbfb8aa3b, v133
	v_exp_f32_e32 v84, v84
	s_nop 0
	v_add_f32_e32 v84, 1.0, v84
	v_div_scale_f32 v71, s[74:75], v84, v84, v133
	v_rcp_f32_e32 v82, v71
	s_nop 0
	v_fma_f32 v92, -v71, v82, 1.0
	v_fmac_f32_e32 v82, v92, v82
	v_div_scale_f32 v88, vcc, v133, v84, v133
	v_mul_f32_e32 v90, v88, v82
	v_fma_f32 v92, -v71, v90, v88
	v_fmac_f32_e32 v90, v92, v82
	v_fma_f32 v71, -v71, v90, v88
	v_div_fmas_f32 v71, v71, v82, v90
	v_div_fixup_f32 v133, v71, v84, v133
	v_mul_f32_e32 v70, v70, v133
	v_lshlrev_b32_e32 v131, 16, v131
	v_lshlrev_b32_e32 v132, 16, v132
	v_lshlrev_b32_e32 v130, 16, v130
	v_mul_f32_e32 v130, v16, v130
	v_fmac_f32_e32 v130, v14, v131
	v_fmac_f32_e32 v130, v17, v132
	v_add_f32_e32 v130, v12, v130
	v_fma_f32 v27, v45, v8, v63
	v_mul_f32_e32 v110, v27, v130
	v_lshlrev_b32_e32 v134, 16, v134
	v_mul_f32_e32 v84, 0xbfb8aa3b, v134
	v_exp_f32_e32 v84, v84
	s_nop 0
	v_add_f32_e32 v84, 1.0, v84
	v_div_scale_f32 v71, s[74:75], v84, v84, v134
	v_rcp_f32_e32 v82, v71
	s_nop 0
	v_fma_f32 v92, -v71, v82, 1.0
	v_fmac_f32_e32 v82, v92, v82
	v_div_scale_f32 v88, vcc, v134, v84, v134
	v_mul_f32_e32 v90, v88, v82
	v_fma_f32 v92, -v71, v90, v88
	v_fmac_f32_e32 v90, v92, v82
	v_fma_f32 v71, -v71, v90, v88
	v_div_fmas_f32 v71, v71, v82, v90
	v_div_fixup_f32 v134, v71, v84, v134
	v_mul_f32_e32 v110, v110, v134
	v_cvt_pk_bf16_f32 v204, v70, v110
	v_lshlrev_b32_e32 v136, 16, v136
	v_lshlrev_b32_e32 v137, 16, v137
	v_lshlrev_b32_e32 v135, 16, v135
	v_mul_f32_e32 v135, v16, v135
	v_fmac_f32_e32 v135, v14, v136
	v_fmac_f32_e32 v135, v17, v137
	v_add_f32_e32 v135, v12, v135
	v_fma_f32 v27, v42, v8, v64
	v_mul_f32_e32 v70, v27, v135
	v_lshlrev_b32_e32 v141, 16, v141
	v_mul_f32_e32 v84, 0xbfb8aa3b, v141
	v_exp_f32_e32 v84, v84
	s_nop 0
	v_add_f32_e32 v84, 1.0, v84
	v_div_scale_f32 v71, s[74:75], v84, v84, v141
	v_rcp_f32_e32 v82, v71
	s_nop 0
	v_fma_f32 v92, -v71, v82, 1.0
	v_fmac_f32_e32 v82, v92, v82
	v_div_scale_f32 v88, vcc, v141, v84, v141
	v_mul_f32_e32 v90, v88, v82
	v_fma_f32 v92, -v71, v90, v88
	v_fmac_f32_e32 v90, v92, v82
	v_fma_f32 v71, -v71, v90, v88
	v_div_fmas_f32 v71, v71, v82, v90
	v_div_fixup_f32 v141, v71, v84, v141
	v_mul_f32_e32 v70, v70, v141
	v_lshlrev_b32_e32 v139, 16, v139
	v_lshlrev_b32_e32 v140, 16, v140
	v_lshlrev_b32_e32 v138, 16, v138
	v_mul_f32_e32 v138, v16, v138
	v_fmac_f32_e32 v138, v14, v139
	v_fmac_f32_e32 v138, v17, v140
	v_add_f32_e32 v138, v12, v138
	v_fma_f32 v27, v44, v8, v65
	v_mul_f32_e32 v110, v27, v138
	v_lshlrev_b32_e32 v142, 16, v142
	v_mul_f32_e32 v84, 0xbfb8aa3b, v142
	v_exp_f32_e32 v84, v84
	s_nop 0
	v_add_f32_e32 v84, 1.0, v84
	v_div_scale_f32 v71, s[74:75], v84, v84, v142
	v_rcp_f32_e32 v82, v71
	s_nop 0
	v_fma_f32 v92, -v71, v82, 1.0
	v_fmac_f32_e32 v82, v92, v82
	v_div_scale_f32 v88, vcc, v142, v84, v142
	v_mul_f32_e32 v90, v88, v82
	v_fma_f32 v92, -v71, v90, v88
	v_fmac_f32_e32 v90, v92, v82
	v_fma_f32 v71, -v71, v90, v88
	v_div_fmas_f32 v71, v71, v82, v90
	v_div_fixup_f32 v142, v71, v84, v142
	v_mul_f32_e32 v110, v110, v142
	v_cvt_pk_bf16_f32 v205, v70, v110
	s_waitcnt vmcnt(32)
	v_lshlrev_b32_e32 v163, 16, v163
	v_lshlrev_b32_e32 v164, 16, v164
	v_lshlrev_b32_e32 v143, 16, v143
	v_mul_f32_e32 v143, v16, v143
	v_fmac_f32_e32 v143, v14, v163
	v_fmac_f32_e32 v143, v17, v164
	v_add_f32_e32 v143, v12, v143
	v_fma_f32 v27, v47, v8, v22
	v_mul_f32_e32 v70, v27, v143
	v_lshlrev_b32_e32 v168, 16, v168
	v_mul_f32_e32 v84, 0xbfb8aa3b, v168
	v_exp_f32_e32 v84, v84
	s_nop 0
	v_add_f32_e32 v84, 1.0, v84
	v_div_scale_f32 v71, s[74:75], v84, v84, v168
	v_rcp_f32_e32 v82, v71
	s_nop 0
	v_fma_f32 v92, -v71, v82, 1.0
	v_fmac_f32_e32 v82, v92, v82
	v_div_scale_f32 v88, vcc, v168, v84, v168
	v_mul_f32_e32 v90, v88, v82
	v_fma_f32 v92, -v71, v90, v88
	v_fmac_f32_e32 v90, v92, v82
	v_fma_f32 v71, -v71, v90, v88
	v_div_fmas_f32 v71, v71, v82, v90
	v_div_fixup_f32 v168, v71, v84, v168
	v_mul_f32_e32 v70, v70, v168
	v_lshlrev_b32_e32 v166, 16, v166
	v_lshlrev_b32_e32 v167, 16, v167
	v_lshlrev_b32_e32 v165, 16, v165
	v_mul_f32_e32 v165, v16, v165
	v_fmac_f32_e32 v165, v14, v166
	v_fmac_f32_e32 v165, v17, v167
	v_add_f32_e32 v165, v12, v165
	v_fma_f32 v27, v49, v8, v23
	v_mul_f32_e32 v110, v27, v165
	v_lshlrev_b32_e32 v169, 16, v169
	v_mul_f32_e32 v84, 0xbfb8aa3b, v169
	v_exp_f32_e32 v84, v84
	s_nop 0
	v_add_f32_e32 v84, 1.0, v84
	v_div_scale_f32 v71, s[74:75], v84, v84, v169
	v_rcp_f32_e32 v82, v71
	s_nop 0
	v_fma_f32 v92, -v71, v82, 1.0
	v_fmac_f32_e32 v82, v92, v82
	v_div_scale_f32 v88, vcc, v169, v84, v169
	v_mul_f32_e32 v90, v88, v82
	v_fma_f32 v92, -v71, v90, v88
	v_fmac_f32_e32 v90, v92, v82
	v_fma_f32 v71, -v71, v90, v88
	v_div_fmas_f32 v71, v71, v82, v90
	v_div_fixup_f32 v169, v71, v84, v169
	v_mul_f32_e32 v110, v110, v169
	v_cvt_pk_bf16_f32 v206, v70, v110
	v_lshlrev_b32_e32 v171, 16, v171
	v_lshlrev_b32_e32 v172, 16, v172
	v_lshlrev_b32_e32 v170, 16, v170
	v_mul_f32_e32 v170, v16, v170
	v_fmac_f32_e32 v170, v14, v171
	v_fmac_f32_e32 v170, v17, v172
	v_add_f32_e32 v170, v12, v170
	v_fma_f32 v27, v46, v8, v24
	v_mul_f32_e32 v70, v27, v170
	v_lshlrev_b32_e32 v176, 16, v176
	v_mul_f32_e32 v84, 0xbfb8aa3b, v176
	v_exp_f32_e32 v84, v84
	s_nop 0
	v_add_f32_e32 v84, 1.0, v84
	v_div_scale_f32 v71, s[74:75], v84, v84, v176
	v_rcp_f32_e32 v82, v71
	s_nop 0
	v_fma_f32 v92, -v71, v82, 1.0
	v_fmac_f32_e32 v82, v92, v82
	v_div_scale_f32 v88, vcc, v176, v84, v176
	v_mul_f32_e32 v90, v88, v82
	v_fma_f32 v92, -v71, v90, v88
	v_fmac_f32_e32 v90, v92, v82
	v_fma_f32 v71, -v71, v90, v88
	v_div_fmas_f32 v71, v71, v82, v90
	v_div_fixup_f32 v176, v71, v84, v176
	v_mul_f32_e32 v70, v70, v176
	v_lshlrev_b32_e32 v174, 16, v174
	v_lshlrev_b32_e32 v175, 16, v175
	v_lshlrev_b32_e32 v173, 16, v173
	v_mul_f32_e32 v173, v16, v173
	v_fmac_f32_e32 v173, v14, v174
	v_fmac_f32_e32 v173, v17, v175
	v_add_f32_e32 v173, v12, v173
	v_fma_f32 v27, v48, v8, v25
	v_mul_f32_e32 v110, v27, v173
	v_lshlrev_b32_e32 v177, 16, v177
	v_mul_f32_e32 v84, 0xbfb8aa3b, v177
	v_exp_f32_e32 v84, v84
	s_nop 0
	v_add_f32_e32 v84, 1.0, v84
	v_div_scale_f32 v71, s[74:75], v84, v84, v177
	v_rcp_f32_e32 v82, v71
	s_nop 0
	v_fma_f32 v92, -v71, v82, 1.0
	v_fmac_f32_e32 v82, v92, v82
	v_div_scale_f32 v88, vcc, v177, v84, v177
	v_mul_f32_e32 v90, v88, v82
	v_fma_f32 v92, -v71, v90, v88
	v_fmac_f32_e32 v90, v92, v82
	v_fma_f32 v71, -v71, v90, v88
	v_div_fmas_f32 v71, v71, v82, v90
	v_div_fixup_f32 v177, v71, v84, v177
	v_mul_f32_e32 v110, v110, v177
	v_cvt_pk_bf16_f32 v207, v70, v110
	v_lshlrev_b32_e32 v179, 16, v179
	v_lshlrev_b32_e32 v180, 16, v180
	v_lshlrev_b32_e32 v178, 16, v178
	v_mul_f32_e32 v178, v16, v178
	v_fmac_f32_e32 v178, v14, v179
	v_fmac_f32_e32 v178, v17, v180
	v_add_f32_e32 v178, v12, v178
	v_fma_f32 v27, v51, v8, v18
	v_mul_f32_e32 v70, v27, v178
	v_lshlrev_b32_e32 v184, 16, v184
	v_mul_f32_e32 v84, 0xbfb8aa3b, v184
	v_exp_f32_e32 v84, v84
	s_nop 0
	v_add_f32_e32 v84, 1.0, v84
	v_div_scale_f32 v71, s[74:75], v84, v84, v184
	v_rcp_f32_e32 v82, v71
	s_nop 0
	v_fma_f32 v92, -v71, v82, 1.0
	v_fmac_f32_e32 v82, v92, v82
	v_div_scale_f32 v88, vcc, v184, v84, v184
	v_mul_f32_e32 v90, v88, v82
	v_fma_f32 v92, -v71, v90, v88
	v_fmac_f32_e32 v90, v92, v82
	v_fma_f32 v71, -v71, v90, v88
	v_div_fmas_f32 v71, v71, v82, v90
	v_div_fixup_f32 v184, v71, v84, v184
	v_mul_f32_e32 v70, v70, v184
	v_lshlrev_b32_e32 v182, 16, v182
	v_lshlrev_b32_e32 v183, 16, v183
	v_lshlrev_b32_e32 v181, 16, v181
	v_mul_f32_e32 v181, v16, v181
	v_fmac_f32_e32 v181, v14, v182
	v_fmac_f32_e32 v181, v17, v183
	v_add_f32_e32 v181, v12, v181
	v_fma_f32 v27, v53, v8, v19
	v_mul_f32_e32 v110, v27, v181
	v_lshlrev_b32_e32 v185, 16, v185
	v_mul_f32_e32 v84, 0xbfb8aa3b, v185
	v_exp_f32_e32 v84, v84
	s_nop 0
	v_add_f32_e32 v84, 1.0, v84
	v_div_scale_f32 v71, s[74:75], v84, v84, v185
	v_rcp_f32_e32 v82, v71
	s_nop 0
	v_fma_f32 v92, -v71, v82, 1.0
	v_fmac_f32_e32 v82, v92, v82
	v_div_scale_f32 v88, vcc, v185, v84, v185
	v_mul_f32_e32 v90, v88, v82
	v_fma_f32 v92, -v71, v90, v88
	v_fmac_f32_e32 v90, v92, v82
	v_fma_f32 v71, -v71, v90, v88
	v_div_fmas_f32 v71, v71, v82, v90
	v_div_fixup_f32 v185, v71, v84, v185
	v_mul_f32_e32 v110, v110, v185
	v_cvt_pk_bf16_f32 v208, v70, v110
	v_lshlrev_b32_e32 v187, 16, v187
	v_lshlrev_b32_e32 v188, 16, v188
	v_lshlrev_b32_e32 v186, 16, v186
	v_mul_f32_e32 v186, v16, v186
	v_fmac_f32_e32 v186, v14, v187
	v_fmac_f32_e32 v186, v17, v188
	v_add_f32_e32 v186, v12, v186
	v_fma_f32 v27, v50, v8, v20
	v_mul_f32_e32 v70, v27, v186
	v_lshlrev_b32_e32 v192, 16, v192
	v_mul_f32_e32 v84, 0xbfb8aa3b, v192
	v_exp_f32_e32 v84, v84
	s_nop 0
	v_add_f32_e32 v84, 1.0, v84
	v_div_scale_f32 v71, s[74:75], v84, v84, v192
	v_rcp_f32_e32 v82, v71
	s_nop 0
	v_fma_f32 v92, -v71, v82, 1.0
	v_fmac_f32_e32 v82, v92, v82
	v_div_scale_f32 v88, vcc, v192, v84, v192
	v_mul_f32_e32 v90, v88, v82
	v_fma_f32 v92, -v71, v90, v88
	v_fmac_f32_e32 v90, v92, v82
	v_fma_f32 v71, -v71, v90, v88
	v_div_fmas_f32 v71, v71, v82, v90
	v_div_fixup_f32 v192, v71, v84, v192
	v_mul_f32_e32 v70, v70, v192
	v_lshlrev_b32_e32 v190, 16, v190
	v_lshlrev_b32_e32 v191, 16, v191
	v_lshlrev_b32_e32 v189, 16, v189
	v_mul_f32_e32 v189, v16, v189
	v_fmac_f32_e32 v189, v14, v190
	v_fmac_f32_e32 v189, v17, v191
	v_add_f32_e32 v189, v12, v189
	v_fma_f32 v27, v52, v8, v21
	v_mul_f32_e32 v110, v27, v189
	v_lshlrev_b32_e32 v193, 16, v193
	v_mul_f32_e32 v84, 0xbfb8aa3b, v193
	v_exp_f32_e32 v84, v84
	s_nop 0
	v_add_f32_e32 v84, 1.0, v84
	v_div_scale_f32 v71, s[74:75], v84, v84, v193
	v_rcp_f32_e32 v82, v71
	s_nop 0
	v_fma_f32 v92, -v71, v82, 1.0
	v_fmac_f32_e32 v82, v92, v82
	v_div_scale_f32 v88, vcc, v193, v84, v193
	v_mul_f32_e32 v90, v88, v82
	v_fma_f32 v92, -v71, v90, v88
	v_fmac_f32_e32 v90, v92, v82
	v_fma_f32 v71, -v71, v90, v88
	v_div_fmas_f32 v71, v71, v82, v90
	v_div_fixup_f32 v193, v71, v84, v193
	v_mul_f32_e32 v110, v110, v193
	v_cvt_pk_bf16_f32 v209, v70, v110
	s_waitcnt vmcnt(0)
	v_lshlrev_b32_e32 v195, 16, v195
	v_lshlrev_b32_e32 v196, 16, v196
	v_lshlrev_b32_e32 v194, 16, v194
	v_mul_f32_e32 v194, v16, v194
	v_fmac_f32_e32 v194, v14, v195
	v_fmac_f32_e32 v194, v17, v196
	v_add_f32_e32 v194, v12, v194
	v_fma_f32 v27, v55, v8, v4
	v_mul_f32_e32 v70, v27, v194
	v_lshlrev_b32_e32 v223, 16, v223
	v_mul_f32_e32 v84, 0xbfb8aa3b, v223
	v_exp_f32_e32 v84, v84
	s_nop 0
	v_add_f32_e32 v84, 1.0, v84
	v_div_scale_f32 v71, s[74:75], v84, v84, v223
	v_rcp_f32_e32 v82, v71
	s_nop 0
	v_fma_f32 v92, -v71, v82, 1.0
	v_fmac_f32_e32 v82, v92, v82
	v_div_scale_f32 v88, vcc, v223, v84, v223
	v_mul_f32_e32 v90, v88, v82
	v_fma_f32 v92, -v71, v90, v88
	v_fmac_f32_e32 v90, v92, v82
	v_fma_f32 v71, -v71, v90, v88
	v_div_fmas_f32 v71, v71, v82, v90
	v_div_fixup_f32 v223, v71, v84, v223
	v_mul_f32_e32 v70, v70, v223
	v_lshlrev_b32_e32 v221, 16, v221
	v_lshlrev_b32_e32 v222, 16, v222
	v_lshlrev_b32_e32 v197, 16, v197
	v_mul_f32_e32 v197, v16, v197
	v_fmac_f32_e32 v197, v14, v221
	v_fmac_f32_e32 v197, v17, v222
	v_add_f32_e32 v197, v12, v197
	v_fma_f32 v27, v57, v8, v5
	v_mul_f32_e32 v110, v27, v197
	v_lshlrev_b32_e32 v224, 16, v224
	v_mul_f32_e32 v84, 0xbfb8aa3b, v224
	v_exp_f32_e32 v84, v84
	s_nop 0
	v_add_f32_e32 v84, 1.0, v84
	v_div_scale_f32 v71, s[74:75], v84, v84, v224
	v_rcp_f32_e32 v82, v71
	s_nop 0
	v_fma_f32 v92, -v71, v82, 1.0
	v_fmac_f32_e32 v82, v92, v82
	v_div_scale_f32 v88, vcc, v224, v84, v224
	v_mul_f32_e32 v90, v88, v82
	v_fma_f32 v92, -v71, v90, v88
	v_fmac_f32_e32 v90, v92, v82
	v_fma_f32 v71, -v71, v90, v88
	v_div_fmas_f32 v71, v71, v82, v90
	v_div_fixup_f32 v224, v71, v84, v224
	v_mul_f32_e32 v110, v110, v224
	v_cvt_pk_bf16_f32 v210, v70, v110
	v_lshlrev_b32_e32 v226, 16, v226
	v_lshlrev_b32_e32 v227, 16, v227
	v_lshlrev_b32_e32 v225, 16, v225
	v_mul_f32_e32 v225, v16, v225
	v_fmac_f32_e32 v225, v14, v226
	v_fmac_f32_e32 v225, v17, v227
	v_add_f32_e32 v225, v12, v225
	v_fma_f32 v27, v54, v8, v6
	v_mul_f32_e32 v70, v27, v225
	v_lshlrev_b32_e32 v231, 16, v231
	v_mul_f32_e32 v84, 0xbfb8aa3b, v231
	v_exp_f32_e32 v84, v84
	s_nop 0
	v_add_f32_e32 v84, 1.0, v84
	v_div_scale_f32 v71, s[74:75], v84, v84, v231
	v_rcp_f32_e32 v82, v71
	s_nop 0
	v_fma_f32 v92, -v71, v82, 1.0
	v_fmac_f32_e32 v82, v92, v82
	v_div_scale_f32 v88, vcc, v231, v84, v231
	v_mul_f32_e32 v90, v88, v82
	v_fma_f32 v92, -v71, v90, v88
	v_fmac_f32_e32 v90, v92, v82
	v_fma_f32 v71, -v71, v90, v88
	v_div_fmas_f32 v71, v71, v82, v90
	v_div_fixup_f32 v231, v71, v84, v231
	v_mul_f32_e32 v70, v70, v231
	v_lshlrev_b32_e32 v229, 16, v229
	v_lshlrev_b32_e32 v230, 16, v230
	v_lshlrev_b32_e32 v228, 16, v228
	v_mul_f32_e32 v228, v16, v228
	v_fmac_f32_e32 v228, v14, v229
	v_fmac_f32_e32 v228, v17, v230
	v_add_f32_e32 v228, v12, v228
	v_fma_f32 v27, v56, v8, v7
	v_mul_f32_e32 v110, v27, v228
	v_lshlrev_b32_e32 v232, 16, v232
	v_mul_f32_e32 v84, 0xbfb8aa3b, v232
	v_exp_f32_e32 v84, v84
	s_nop 0
	v_add_f32_e32 v84, 1.0, v84
	v_div_scale_f32 v71, s[74:75], v84, v84, v232
	v_rcp_f32_e32 v82, v71
	s_nop 0
	v_fma_f32 v92, -v71, v82, 1.0
	v_fmac_f32_e32 v82, v92, v82
	v_div_scale_f32 v88, vcc, v232, v84, v232
	v_mul_f32_e32 v90, v88, v82
	v_fma_f32 v92, -v71, v90, v88
	v_fmac_f32_e32 v90, v92, v82
	v_fma_f32 v71, -v71, v90, v88
	v_div_fmas_f32 v71, v71, v82, v90
	v_div_fixup_f32 v232, v71, v84, v232
	v_mul_f32_e32 v110, v110, v232
	v_cvt_pk_bf16_f32 v211, v70, v110
	v_lshlrev_b32_e32 v234, 16, v234
	v_lshlrev_b32_e32 v235, 16, v235
	v_lshlrev_b32_e32 v233, 16, v233
	v_mul_f32_e32 v233, v16, v233
	v_fmac_f32_e32 v233, v14, v234
	v_fmac_f32_e32 v233, v17, v235
	v_add_f32_e32 v233, v12, v233
	v_fma_f32 v27, v59, v8, v0
	v_mul_f32_e32 v70, v27, v233
	v_lshlrev_b32_e32 v239, 16, v239
	v_mul_f32_e32 v84, 0xbfb8aa3b, v239
	v_exp_f32_e32 v84, v84
	s_nop 0
	v_add_f32_e32 v84, 1.0, v84
	v_div_scale_f32 v71, s[74:75], v84, v84, v239
	v_rcp_f32_e32 v82, v71
	s_nop 0
	v_fma_f32 v92, -v71, v82, 1.0
	v_fmac_f32_e32 v82, v92, v82
	v_div_scale_f32 v88, vcc, v239, v84, v239
	v_mul_f32_e32 v90, v88, v82
	v_fma_f32 v92, -v71, v90, v88
	v_fmac_f32_e32 v90, v92, v82
	v_fma_f32 v71, -v71, v90, v88
	v_div_fmas_f32 v71, v71, v82, v90
	v_div_fixup_f32 v239, v71, v84, v239
	v_mul_f32_e32 v70, v70, v239
	v_lshlrev_b32_e32 v237, 16, v237
	v_lshlrev_b32_e32 v238, 16, v238
	v_lshlrev_b32_e32 v236, 16, v236
	v_mul_f32_e32 v236, v16, v236
	v_fmac_f32_e32 v236, v14, v237
	v_fmac_f32_e32 v236, v17, v238
	v_add_f32_e32 v236, v12, v236
	v_fma_f32 v27, v61, v8, v1
	v_mul_f32_e32 v110, v27, v236
	v_lshlrev_b32_e32 v240, 16, v240
	v_mul_f32_e32 v84, 0xbfb8aa3b, v240
	v_exp_f32_e32 v84, v84
	s_nop 0
	v_add_f32_e32 v84, 1.0, v84
	v_div_scale_f32 v71, s[74:75], v84, v84, v240
	v_rcp_f32_e32 v82, v71
	s_nop 0
	v_fma_f32 v92, -v71, v82, 1.0
	v_fmac_f32_e32 v82, v92, v82
	v_div_scale_f32 v88, vcc, v240, v84, v240
	v_mul_f32_e32 v90, v88, v82
	v_fma_f32 v92, -v71, v90, v88
	v_fmac_f32_e32 v90, v92, v82
	v_fma_f32 v71, -v71, v90, v88
	v_div_fmas_f32 v71, v71, v82, v90
	v_div_fixup_f32 v240, v71, v84, v240
	v_mul_f32_e32 v110, v110, v240
	v_cvt_pk_bf16_f32 v212, v70, v110
	v_lshlrev_b32_e32 v242, 16, v242
	v_lshlrev_b32_e32 v243, 16, v243
	v_lshlrev_b32_e32 v241, 16, v241
	v_mul_f32_e32 v241, v16, v241
	v_mul_f32_e32 v243, v255, v243
	v_fmac_f32_e32 v241, v14, v242
	v_fmac_f32_e32 v241, v17, v243
	v_add_f32_e32 v241, v12, v241
	v_fma_f32 v27, v58, v8, v2
	v_mul_f32_e32 v70, v27, v241
	v_lshlrev_b32_e32 v247, 16, v247
	v_mul_f32_e32 v84, 0xbfb8aa3b, v247
	v_exp_f32_e32 v84, v84
	s_nop 0
	v_add_f32_e32 v84, 1.0, v84
	v_div_scale_f32 v71, s[74:75], v84, v84, v247
	v_rcp_f32_e32 v82, v71
	s_nop 0
	v_fma_f32 v92, -v71, v82, 1.0
	v_fmac_f32_e32 v82, v92, v82
	v_div_scale_f32 v88, vcc, v247, v84, v247
	v_mul_f32_e32 v90, v88, v82
	v_fma_f32 v92, -v71, v90, v88
	v_fmac_f32_e32 v90, v92, v82
	v_fma_f32 v71, -v71, v90, v88
	v_div_fmas_f32 v71, v71, v82, v90
	v_div_fixup_f32 v247, v71, v84, v247
	v_mul_f32_e32 v70, v70, v247
	v_lshlrev_b32_e32 v245, 16, v245
	v_lshlrev_b32_e32 v246, 16, v246
	v_lshlrev_b32_e32 v244, 16, v244
	v_mul_f32_e32 v244, v16, v244
	v_mul_f32_e32 v246, v255, v246
	v_fmac_f32_e32 v244, v14, v245
	v_fmac_f32_e32 v244, v17, v246
	v_add_f32_e32 v244, v12, v244
	v_fma_f32 v27, v60, v8, v3
	v_mul_f32_e32 v110, v27, v244
	v_lshlrev_b32_e32 v248, 16, v248
	v_mul_f32_e32 v84, 0xbfb8aa3b, v248
	v_exp_f32_e32 v84, v84
	s_nop 0
	v_add_f32_e32 v84, 1.0, v84
	v_div_scale_f32 v71, s[74:75], v84, v84, v248
	v_rcp_f32_e32 v82, v71
	s_nop 0
	v_fma_f32 v92, -v71, v82, 1.0
	v_fmac_f32_e32 v82, v92, v82
	v_div_scale_f32 v88, vcc, v248, v84, v248
	v_mul_f32_e32 v90, v88, v82
	v_fma_f32 v92, -v71, v90, v88
	v_fmac_f32_e32 v90, v92, v82
	v_fma_f32 v71, -v71, v90, v88
	v_div_fmas_f32 v71, v71, v82, v90
	v_div_fixup_f32 v248, v71, v84, v248
	v_mul_f32_e32 v110, v110, v248
	v_cvt_pk_bf16_f32 v213, v70, v110
	s_branch .Lhy_ep1_done_L1
.Lhy_ep1_comb_L1:
	s_mov_b32 s98, 0x5040100
	s_mov_b32 s99, 0x7060302
	v_lshlrev_b32_e32 v109, 1, v10
	v_add_u32_e32 v254, 0x1e00, v10
	v_add_u32_e32 v253, 0x1000, v109
	v_cmp_gt_i32_e32 vcc, 0x1fff, v254
	v_add_u32_e32 v251, 0x2000, v109
	v_add_u32_e32 v250, 0x3000, v109
	v_min_i32_e32 v254, 0x1ffe, v254
	v_cndmask_b32_e64 v255, 0, 1.0, vcc
	v_lshlrev_b32_e32 v254, 1, v254
	global_load_ushort v9, v109, s[0:1]
	global_load_ushort v11, v109, s[4:5]
	global_load_ushort v13, v109, s[36:37] offset:1022
	global_load_ushort v15, v109, s[36:37] offset:1024
	global_load_ushort v81, v109, s[36:37] offset:1026
	global_load_ushort v83, v109, s[72:73] offset:1022
	global_load_ushort v85, v109, s[72:73] offset:1024
	global_load_ushort v87, v109, s[72:73] offset:1026
	global_load_ushort v89, v109, s[0:1] offset:1024
	global_load_ushort v91, v109, s[4:5] offset:1024
	global_load_ushort v93, v109, s[36:37] offset:2046
	global_load_ushort v94, v109, s[36:37] offset:2048
	global_load_ushort v95, v109, s[36:37] offset:2050
	global_load_ushort v96, v109, s[72:73] offset:2046
	global_load_ushort v97, v109, s[72:73] offset:2048
	global_load_ushort v98, v109, s[72:73] offset:2050
	global_load_ushort v99, v109, s[0:1] offset:2048
	global_load_ushort v100, v109, s[4:5] offset:2048
	global_load_ushort v101, v109, s[36:37] offset:3070
	global_load_ushort v102, v109, s[36:37] offset:3072
	global_load_ushort v103, v109, s[36:37] offset:3074
	global_load_ushort v104, v109, s[72:73] offset:3070
	global_load_ushort v105, v109, s[72:73] offset:3072
	global_load_ushort v106, v109, s[72:73] offset:3074
	global_load_ushort v107, v109, s[0:1] offset:3072
	global_load_ushort v108, v109, s[4:5] offset:3072
	global_load_ushort v111, v253, s[36:37] offset:-2
	global_load_ushort v112, v253, s[36:37]
	global_load_ushort v113, v253, s[36:37] offset:2
	global_load_ushort v114, v253, s[72:73] offset:-2
	global_load_ushort v115, v253, s[72:73]
	global_load_ushort v116, v253, s[72:73] offset:2
	global_load_ushort v117, v253, s[0:1]
	global_load_ushort v118, v253, s[4:5]
	global_load_ushort v119, v253, s[36:37] offset:1022
	global_load_ushort v120, v253, s[36:37] offset:1024
	global_load_ushort v121, v253, s[36:37] offset:1026
	global_load_ushort v122, v253, s[72:73] offset:1022
	global_load_ushort v123, v253, s[72:73] offset:1024
	global_load_ushort v124, v253, s[72:73] offset:1026
	global_load_ushort v125, v253, s[0:1] offset:1024
	global_load_ushort v126, v253, s[4:5] offset:1024
	global_load_ushort v127, v253, s[36:37] offset:2046
	global_load_ushort v128, v253, s[36:37] offset:2048
	global_load_ushort v129, v253, s[36:37] offset:2050
	global_load_ushort v130, v253, s[72:73] offset:2046
	global_load_ushort v131, v253, s[72:73] offset:2048
	global_load_ushort v132, v253, s[72:73] offset:2050
	global_load_ushort v133, v253, s[0:1] offset:2048
	global_load_ushort v134, v253, s[4:5] offset:2048
	global_load_ushort v135, v253, s[36:37] offset:3070
	global_load_ushort v136, v253, s[36:37] offset:3072
	global_load_ushort v137, v253, s[36:37] offset:3074
	global_load_ushort v138, v253, s[72:73] offset:3070
	global_load_ushort v139, v253, s[72:73] offset:3072
	global_load_ushort v140, v253, s[72:73] offset:3074
	global_load_ushort v141, v253, s[0:1] offset:3072
	global_load_ushort v142, v253, s[4:5] offset:3072
	global_load_ushort v143, v251, s[36:37] offset:-2
	global_load_ushort v163, v251, s[36:37]
	global_load_ushort v164, v251, s[36:37] offset:2
	global_load_ushort v165, v251, s[72:73] offset:-2
	global_load_ushort v166, v251, s[72:73]
	global_load_ushort v167, v251, s[72:73] offset:2
	global_load_ushort v168, v251, s[0:1]
	global_load_ushort v169, v251, s[4:5]
	global_load_ushort v170, v251, s[36:37] offset:1022
	global_load_ushort v171, v251, s[36:37] offset:1024
	global_load_ushort v172, v251, s[36:37] offset:1026
	global_load_ushort v173, v251, s[72:73] offset:1022
	global_load_ushort v174, v251, s[72:73] offset:1024
	global_load_ushort v175, v251, s[72:73] offset:1026
	global_load_ushort v176, v251, s[0:1] offset:1024
	global_load_ushort v177, v251, s[4:5] offset:1024
	global_load_ushort v178, v251, s[36:37] offset:2046
	global_load_ushort v179, v251, s[36:37] offset:2048
	global_load_ushort v180, v251, s[36:37] offset:2050
	global_load_ushort v181, v251, s[72:73] offset:2046
	global_load_ushort v182, v251, s[72:73] offset:2048
	global_load_ushort v183, v251, s[72:73] offset:2050
	global_load_ushort v184, v251, s[0:1] offset:2048
	global_load_ushort v185, v251, s[4:5] offset:2048
	global_load_ushort v186, v251, s[36:37] offset:3070
	global_load_ushort v187, v251, s[36:37] offset:3072
	global_load_ushort v188, v251, s[36:37] offset:3074
	global_load_ushort v189, v251, s[72:73] offset:3070
	global_load_ushort v190, v251, s[72:73] offset:3072
	global_load_ushort v191, v251, s[72:73] offset:3074
	global_load_ushort v192, v251, s[0:1] offset:3072
	global_load_ushort v193, v251, s[4:5] offset:3072
	global_load_ushort v194, v250, s[36:37] offset:-2
	global_load_ushort v195, v250, s[36:37]
	global_load_ushort v196, v250, s[36:37] offset:2
	global_load_ushort v197, v250, s[72:73] offset:-2
	global_load_ushort v221, v250, s[72:73]
	global_load_ushort v222, v250, s[72:73] offset:2
	global_load_ushort v223, v250, s[0:1]
	global_load_ushort v224, v250, s[4:5]
	global_load_ushort v225, v250, s[36:37] offset:1022
	global_load_ushort v226, v250, s[36:37] offset:1024
	global_load_ushort v227, v250, s[36:37] offset:1026
	global_load_ushort v228, v250, s[72:73] offset:1022
	global_load_ushort v229, v250, s[72:73] offset:1024
	global_load_ushort v230, v250, s[72:73] offset:1026
	global_load_ushort v231, v250, s[0:1] offset:1024
	global_load_ushort v232, v250, s[4:5] offset:1024
	global_load_ushort v233, v250, s[36:37] offset:2046
	global_load_ushort v234, v250, s[36:37] offset:2048
	global_load_ushort v235, v250, s[36:37] offset:2050
	global_load_ushort v236, v250, s[72:73] offset:2046
	global_load_ushort v237, v250, s[72:73] offset:2048
	global_load_ushort v238, v250, s[72:73] offset:2050
	global_load_ushort v239, v250, s[0:1] offset:2048
	global_load_ushort v240, v250, s[4:5] offset:2048
	global_load_ushort v241, v250, s[36:37] offset:3070
	global_load_ushort v242, v250, s[36:37] offset:3072
	global_load_ushort v243, v254, s[36:37] offset:2
	global_load_ushort v244, v250, s[72:73] offset:3070
	global_load_ushort v245, v250, s[72:73] offset:3072
	global_load_ushort v246, v254, s[72:73] offset:2
	global_load_ushort v247, v250, s[0:1] offset:3072
	global_load_ushort v248, v250, s[4:5] offset:3072
	s_waitcnt vmcnt(63)
	v_lshlrev_b32_e32 v26, 10, v10
	v_fma_f32 v27, v32, v8, v78
	v_mul_f32_e32 v70, v80, v27
	v_lshlrev_b32_e32 v9, 16, v9
	v_mul_f32_e32 v84, 0xbfb8aa3b, v9
	v_exp_f32_e32 v84, v84
	s_nop 0
	v_add_f32_e32 v84, 1.0, v84
	v_div_scale_f32 v71, s[74:75], v84, v84, v9
	v_rcp_f32_e32 v82, v71
	s_nop 0
	v_fma_f32 v92, -v71, v82, 1.0
	v_fmac_f32_e32 v82, v92, v82
	v_div_scale_f32 v88, vcc, v9, v84, v9
	v_mul_f32_e32 v90, v88, v82
	v_fma_f32 v92, -v71, v90, v88
	v_fmac_f32_e32 v90, v92, v82
	v_fma_f32 v71, -v71, v90, v88
	v_div_fmas_f32 v71, v71, v82, v90
	v_div_fixup_f32 v9, v71, v84, v9
	v_mul_f32_e32 v70, v70, v9
	v_fma_f32 v27, v34, v8, v79
	v_mul_f32_e32 v110, v86, v27
	v_lshlrev_b32_e32 v11, 16, v11
	v_mul_f32_e32 v84, 0xbfb8aa3b, v11
	v_exp_f32_e32 v84, v84
	s_nop 0
	v_add_f32_e32 v84, 1.0, v84
	v_div_scale_f32 v71, s[74:75], v84, v84, v11
	v_rcp_f32_e32 v82, v71
	s_nop 0
	v_fma_f32 v92, -v71, v82, 1.0
	v_fmac_f32_e32 v82, v92, v82
	v_div_scale_f32 v88, vcc, v11, v84, v11
	v_mul_f32_e32 v90, v88, v82
	v_fma_f32 v92, -v71, v90, v88
	v_fmac_f32_e32 v90, v92, v82
	v_fma_f32 v71, -v71, v90, v88
	v_div_fmas_f32 v71, v71, v82, v90
	v_div_fixup_f32 v11, v71, v84, v11
	v_mul_f32_e32 v110, v110, v11
	v_cvt_pk_bf16_f32 v70, v70, v110
	v_perm_b32 v110, v70, v198, s98
	v_perm_b32 v70, v70, v198, s99
	global_store_dword v26, v110, s[70:71] offset:-2
	global_store_dword v26, v70, s[18:19] offset:-2
	v_add_u32_e32 v26, 0x80000, v26
	v_lshlrev_b32_e32 v15, 16, v15
	v_lshlrev_b32_e32 v81, 16, v81
	v_lshlrev_b32_e32 v13, 16, v13
	v_mul_f32_e32 v13, v16, v13
	v_fmac_f32_e32 v13, v14, v15
	v_fmac_f32_e32 v13, v17, v81
	v_add_f32_e32 v13, v12, v13
	v_fma_f32 v27, v33, v8, v76
	v_mul_f32_e32 v70, v27, v13
	v_lshlrev_b32_e32 v89, 16, v89
	v_mul_f32_e32 v84, 0xbfb8aa3b, v89
	v_exp_f32_e32 v84, v84
	s_nop 0
	v_add_f32_e32 v84, 1.0, v84
	v_div_scale_f32 v71, s[74:75], v84, v84, v89
	v_rcp_f32_e32 v82, v71
	s_nop 0
	v_fma_f32 v92, -v71, v82, 1.0
	v_fmac_f32_e32 v82, v92, v82
	v_div_scale_f32 v88, vcc, v89, v84, v89
	v_mul_f32_e32 v90, v88, v82
	v_fma_f32 v92, -v71, v90, v88
	v_fmac_f32_e32 v90, v92, v82
	v_fma_f32 v71, -v71, v90, v88
	v_div_fmas_f32 v71, v71, v82, v90
	v_div_fixup_f32 v89, v71, v84, v89
	v_mul_f32_e32 v70, v70, v89
	v_lshlrev_b32_e32 v85, 16, v85
	v_lshlrev_b32_e32 v87, 16, v87
	v_lshlrev_b32_e32 v83, 16, v83
	v_mul_f32_e32 v83, v16, v83
	v_fmac_f32_e32 v83, v14, v85
	v_fmac_f32_e32 v83, v17, v87
	v_add_f32_e32 v83, v12, v83
	v_fma_f32 v27, v35, v8, v77
	v_mul_f32_e32 v110, v27, v83
	v_lshlrev_b32_e32 v91, 16, v91
	v_mul_f32_e32 v84, 0xbfb8aa3b, v91
	v_exp_f32_e32 v84, v84
	s_nop 0
	v_add_f32_e32 v84, 1.0, v84
	v_div_scale_f32 v71, s[74:75], v84, v84, v91
	v_rcp_f32_e32 v82, v71
	s_nop 0
	v_fma_f32 v92, -v71, v82, 1.0
	v_fmac_f32_e32 v82, v92, v82
	v_div_scale_f32 v88, vcc, v91, v84, v91
	v_mul_f32_e32 v90, v88, v82
	v_fma_f32 v92, -v71, v90, v88
	v_fmac_f32_e32 v90, v92, v82
	v_fma_f32 v71, -v71, v90, v88
	v_div_fmas_f32 v71, v71, v82, v90
	v_div_fixup_f32 v91, v71, v84, v91
	v_mul_f32_e32 v110, v110, v91
	v_cvt_pk_bf16_f32 v70, v70, v110
	v_perm_b32 v110, v70, v199, s98
	v_perm_b32 v70, v70, v199, s99
	global_store_dword v26, v110, s[70:71] offset:-2
	global_store_dword v26, v70, s[18:19] offset:-2
	v_add_u32_e32 v26, 0x80000, v26
	v_lshlrev_b32_e32 v94, 16, v94
	v_lshlrev_b32_e32 v95, 16, v95
	v_lshlrev_b32_e32 v93, 16, v93
	v_mul_f32_e32 v93, v16, v93
	v_fmac_f32_e32 v93, v14, v94
	v_fmac_f32_e32 v93, v17, v95
	v_add_f32_e32 v93, v12, v93
	v_fma_f32 v27, v37, v8, v72
	v_mul_f32_e32 v70, v27, v93
	v_lshlrev_b32_e32 v99, 16, v99
	v_mul_f32_e32 v84, 0xbfb8aa3b, v99
	v_exp_f32_e32 v84, v84
	s_nop 0
	v_add_f32_e32 v84, 1.0, v84
	v_div_scale_f32 v71, s[74:75], v84, v84, v99
	v_rcp_f32_e32 v82, v71
	s_nop 0
	v_fma_f32 v92, -v71, v82, 1.0
	v_fmac_f32_e32 v82, v92, v82
	v_div_scale_f32 v88, vcc, v99, v84, v99
	v_mul_f32_e32 v90, v88, v82
	v_fma_f32 v92, -v71, v90, v88
	v_fmac_f32_e32 v90, v92, v82
	v_fma_f32 v71, -v71, v90, v88
	v_div_fmas_f32 v71, v71, v82, v90
	v_div_fixup_f32 v99, v71, v84, v99
	v_mul_f32_e32 v70, v70, v99
	v_lshlrev_b32_e32 v97, 16, v97
	v_lshlrev_b32_e32 v98, 16, v98
	v_lshlrev_b32_e32 v96, 16, v96
	v_mul_f32_e32 v96, v16, v96
	v_fmac_f32_e32 v96, v14, v97
	v_fmac_f32_e32 v96, v17, v98
	v_add_f32_e32 v96, v12, v96
	v_fma_f32 v27, v31, v8, v73
	v_mul_f32_e32 v110, v27, v96
	v_lshlrev_b32_e32 v100, 16, v100
	v_mul_f32_e32 v84, 0xbfb8aa3b, v100
	v_exp_f32_e32 v84, v84
	s_nop 0
	v_add_f32_e32 v84, 1.0, v84
	v_div_scale_f32 v71, s[74:75], v84, v84, v100
	v_rcp_f32_e32 v82, v71
	s_nop 0
	v_fma_f32 v92, -v71, v82, 1.0
	v_fmac_f32_e32 v82, v92, v82
	v_div_scale_f32 v88, vcc, v100, v84, v100
	v_mul_f32_e32 v90, v88, v82
	v_fma_f32 v92, -v71, v90, v88
	v_fmac_f32_e32 v90, v92, v82
	v_fma_f32 v71, -v71, v90, v88
	v_div_fmas_f32 v71, v71, v82, v90
	v_div_fixup_f32 v100, v71, v84, v100
	v_mul_f32_e32 v110, v110, v100
	v_cvt_pk_bf16_f32 v70, v70, v110
	v_perm_b32 v110, v70, v200, s98
	v_perm_b32 v70, v70, v200, s99
	global_store_dword v26, v110, s[70:71] offset:-2
	global_store_dword v26, v70, s[18:19] offset:-2
	v_add_u32_e32 v26, 0x80000, v26
	v_lshlrev_b32_e32 v102, 16, v102
	v_lshlrev_b32_e32 v103, 16, v103
	v_lshlrev_b32_e32 v101, 16, v101
	v_mul_f32_e32 v101, v16, v101
	v_fmac_f32_e32 v101, v14, v102
	v_fmac_f32_e32 v101, v17, v103
	v_add_f32_e32 v101, v12, v101
	v_fma_f32 v27, v36, v8, v74
	v_mul_f32_e32 v70, v27, v101
	v_lshlrev_b32_e32 v107, 16, v107
	v_mul_f32_e32 v84, 0xbfb8aa3b, v107
	v_exp_f32_e32 v84, v84
	s_nop 0
	v_add_f32_e32 v84, 1.0, v84
	v_div_scale_f32 v71, s[74:75], v84, v84, v107
	v_rcp_f32_e32 v82, v71
	s_nop 0
	v_fma_f32 v92, -v71, v82, 1.0
	v_fmac_f32_e32 v82, v92, v82
	v_div_scale_f32 v88, vcc, v107, v84, v107
	v_mul_f32_e32 v90, v88, v82
	v_fma_f32 v92, -v71, v90, v88
	v_fmac_f32_e32 v90, v92, v82
	v_fma_f32 v71, -v71, v90, v88
	v_div_fmas_f32 v71, v71, v82, v90
	v_div_fixup_f32 v107, v71, v84, v107
	v_mul_f32_e32 v70, v70, v107
	v_lshlrev_b32_e32 v105, 16, v105
	v_lshlrev_b32_e32 v106, 16, v106
	v_lshlrev_b32_e32 v104, 16, v104
	v_mul_f32_e32 v104, v16, v104
	v_fmac_f32_e32 v104, v14, v105
	v_fmac_f32_e32 v104, v17, v106
	v_add_f32_e32 v104, v12, v104
	v_fma_f32 v27, v30, v8, v75
	v_mul_f32_e32 v110, v27, v104
	v_lshlrev_b32_e32 v108, 16, v108
	v_mul_f32_e32 v84, 0xbfb8aa3b, v108
	v_exp_f32_e32 v84, v84
	s_nop 0
	v_add_f32_e32 v84, 1.0, v84
	v_div_scale_f32 v71, s[74:75], v84, v84, v108
	v_rcp_f32_e32 v82, v71
	s_nop 0
	v_fma_f32 v92, -v71, v82, 1.0
	v_fmac_f32_e32 v82, v92, v82
	v_div_scale_f32 v88, vcc, v108, v84, v108
	v_mul_f32_e32 v90, v88, v82
	v_fma_f32 v92, -v71, v90, v88
	v_fmac_f32_e32 v90, v92, v82
	v_fma_f32 v71, -v71, v90, v88
	v_div_fmas_f32 v71, v71, v82, v90
	v_div_fixup_f32 v108, v71, v84, v108
	v_mul_f32_e32 v110, v110, v108
	v_cvt_pk_bf16_f32 v70, v70, v110
	v_perm_b32 v110, v70, v201, s98
	v_perm_b32 v70, v70, v201, s99
	global_store_dword v26, v110, s[70:71] offset:-2
	global_store_dword v26, v70, s[18:19] offset:-2
	s_waitcnt vmcnt(63)
	v_add_u32_e32 v26, 0x80000, v26
	v_lshlrev_b32_e32 v112, 16, v112
	v_lshlrev_b32_e32 v113, 16, v113
	v_lshlrev_b32_e32 v111, 16, v111
	v_mul_f32_e32 v111, v16, v111
	v_fmac_f32_e32 v111, v14, v112
	v_fmac_f32_e32 v111, v17, v113
	v_add_f32_e32 v111, v12, v111
	v_fma_f32 v27, v39, v8, v66
	v_mul_f32_e32 v70, v27, v111
	v_lshlrev_b32_e32 v117, 16, v117
	v_mul_f32_e32 v84, 0xbfb8aa3b, v117
	v_exp_f32_e32 v84, v84
	s_nop 0
	v_add_f32_e32 v84, 1.0, v84
	v_div_scale_f32 v71, s[74:75], v84, v84, v117
	v_rcp_f32_e32 v82, v71
	s_nop 0
	v_fma_f32 v92, -v71, v82, 1.0
	v_fmac_f32_e32 v82, v92, v82
	v_div_scale_f32 v88, vcc, v117, v84, v117
	v_mul_f32_e32 v90, v88, v82
	v_fma_f32 v92, -v71, v90, v88
	v_fmac_f32_e32 v90, v92, v82
	v_fma_f32 v71, -v71, v90, v88
	v_div_fmas_f32 v71, v71, v82, v90
	v_div_fixup_f32 v117, v71, v84, v117
	v_mul_f32_e32 v70, v70, v117
	v_lshlrev_b32_e32 v115, 16, v115
	v_lshlrev_b32_e32 v116, 16, v116
	v_lshlrev_b32_e32 v114, 16, v114
	v_mul_f32_e32 v114, v16, v114
	v_fmac_f32_e32 v114, v14, v115
	v_fmac_f32_e32 v114, v17, v116
	v_add_f32_e32 v114, v12, v114
	v_fma_f32 v27, v41, v8, v67
	v_mul_f32_e32 v110, v27, v114
	v_lshlrev_b32_e32 v118, 16, v118
	v_mul_f32_e32 v84, 0xbfb8aa3b, v118
	v_exp_f32_e32 v84, v84
	s_nop 0
	v_add_f32_e32 v84, 1.0, v84
	v_div_scale_f32 v71, s[74:75], v84, v84, v118
	v_rcp_f32_e32 v82, v71
	s_nop 0
	v_fma_f32 v92, -v71, v82, 1.0
	v_fmac_f32_e32 v82, v92, v82
	v_div_scale_f32 v88, vcc, v118, v84, v118
	v_mul_f32_e32 v90, v88, v82
	v_fma_f32 v92, -v71, v90, v88
	v_fmac_f32_e32 v90, v92, v82
	v_fma_f32 v71, -v71, v90, v88
	v_div_fmas_f32 v71, v71, v82, v90
	v_div_fixup_f32 v118, v71, v84, v118
	v_mul_f32_e32 v110, v110, v118
	v_cvt_pk_bf16_f32 v70, v70, v110
	v_perm_b32 v110, v70, v202, s98
	v_perm_b32 v70, v70, v202, s99
	global_store_dword v26, v110, s[70:71] offset:-2
	global_store_dword v26, v70, s[18:19] offset:-2
	v_add_u32_e32 v26, 0x80000, v26
	v_lshlrev_b32_e32 v120, 16, v120
	v_lshlrev_b32_e32 v121, 16, v121
	v_lshlrev_b32_e32 v119, 16, v119
	v_mul_f32_e32 v119, v16, v119
	v_fmac_f32_e32 v119, v14, v120
	v_fmac_f32_e32 v119, v17, v121
	v_add_f32_e32 v119, v12, v119
	v_fma_f32 v27, v38, v8, v68
	v_mul_f32_e32 v70, v27, v119
	v_lshlrev_b32_e32 v125, 16, v125
	v_mul_f32_e32 v84, 0xbfb8aa3b, v125
	v_exp_f32_e32 v84, v84
	s_nop 0
	v_add_f32_e32 v84, 1.0, v84
	v_div_scale_f32 v71, s[74:75], v84, v84, v125
	v_rcp_f32_e32 v82, v71
	s_nop 0
	v_fma_f32 v92, -v71, v82, 1.0
	v_fmac_f32_e32 v82, v92, v82
	v_div_scale_f32 v88, vcc, v125, v84, v125
	v_mul_f32_e32 v90, v88, v82
	v_fma_f32 v92, -v71, v90, v88
	v_fmac_f32_e32 v90, v92, v82
	v_fma_f32 v71, -v71, v90, v88
	v_div_fmas_f32 v71, v71, v82, v90
	v_div_fixup_f32 v125, v71, v84, v125
	v_mul_f32_e32 v70, v70, v125
	v_lshlrev_b32_e32 v123, 16, v123
	v_lshlrev_b32_e32 v124, 16, v124
	v_lshlrev_b32_e32 v122, 16, v122
	v_mul_f32_e32 v122, v16, v122
	v_fmac_f32_e32 v122, v14, v123
	v_fmac_f32_e32 v122, v17, v124
	v_add_f32_e32 v122, v12, v122
	v_fma_f32 v27, v40, v8, v69
	v_mul_f32_e32 v110, v27, v122
	v_lshlrev_b32_e32 v126, 16, v126
	v_mul_f32_e32 v84, 0xbfb8aa3b, v126
	v_exp_f32_e32 v84, v84
	s_nop 0
	v_add_f32_e32 v84, 1.0, v84
	v_div_scale_f32 v71, s[74:75], v84, v84, v126
	v_rcp_f32_e32 v82, v71
	s_nop 0
	v_fma_f32 v92, -v71, v82, 1.0
	v_fmac_f32_e32 v82, v92, v82
	v_div_scale_f32 v88, vcc, v126, v84, v126
	v_mul_f32_e32 v90, v88, v82
	v_fma_f32 v92, -v71, v90, v88
	v_fmac_f32_e32 v90, v92, v82
	v_fma_f32 v71, -v71, v90, v88
	v_div_fmas_f32 v71, v71, v82, v90
	v_div_fixup_f32 v126, v71, v84, v126
	v_mul_f32_e32 v110, v110, v126
	v_cvt_pk_bf16_f32 v70, v70, v110
	v_perm_b32 v110, v70, v203, s98
	v_perm_b32 v70, v70, v203, s99
	global_store_dword v26, v110, s[70:71] offset:-2
	global_store_dword v26, v70, s[18:19] offset:-2
	v_add_u32_e32 v26, 0x80000, v26
	v_lshlrev_b32_e32 v128, 16, v128
	v_lshlrev_b32_e32 v129, 16, v129
	v_lshlrev_b32_e32 v127, 16, v127
	v_mul_f32_e32 v127, v16, v127
	v_fmac_f32_e32 v127, v14, v128
	v_fmac_f32_e32 v127, v17, v129
	v_add_f32_e32 v127, v12, v127
	v_fma_f32 v27, v43, v8, v62
	v_mul_f32_e32 v70, v27, v127
	v_lshlrev_b32_e32 v133, 16, v133
	v_mul_f32_e32 v84, 0xbfb8aa3b, v133
	v_exp_f32_e32 v84, v84
	s_nop 0
	v_add_f32_e32 v84, 1.0, v84
	v_div_scale_f32 v71, s[74:75], v84, v84, v133
	v_rcp_f32_e32 v82, v71
	s_nop 0
	v_fma_f32 v92, -v71, v82, 1.0
	v_fmac_f32_e32 v82, v92, v82
	v_div_scale_f32 v88, vcc, v133, v84, v133
	v_mul_f32_e32 v90, v88, v82
	v_fma_f32 v92, -v71, v90, v88
	v_fmac_f32_e32 v90, v92, v82
	v_fma_f32 v71, -v71, v90, v88
	v_div_fmas_f32 v71, v71, v82, v90
	v_div_fixup_f32 v133, v71, v84, v133
	v_mul_f32_e32 v70, v70, v133
	v_lshlrev_b32_e32 v131, 16, v131
	v_lshlrev_b32_e32 v132, 16, v132
	v_lshlrev_b32_e32 v130, 16, v130
	v_mul_f32_e32 v130, v16, v130
	v_fmac_f32_e32 v130, v14, v131
	v_fmac_f32_e32 v130, v17, v132
	v_add_f32_e32 v130, v12, v130
	v_fma_f32 v27, v45, v8, v63
	v_mul_f32_e32 v110, v27, v130
	v_lshlrev_b32_e32 v134, 16, v134
	v_mul_f32_e32 v84, 0xbfb8aa3b, v134
	v_exp_f32_e32 v84, v84
	s_nop 0
	v_add_f32_e32 v84, 1.0, v84
	v_div_scale_f32 v71, s[74:75], v84, v84, v134
	v_rcp_f32_e32 v82, v71
	s_nop 0
	v_fma_f32 v92, -v71, v82, 1.0
	v_fmac_f32_e32 v82, v92, v82
	v_div_scale_f32 v88, vcc, v134, v84, v134
	v_mul_f32_e32 v90, v88, v82
	v_fma_f32 v92, -v71, v90, v88
	v_fmac_f32_e32 v90, v92, v82
	v_fma_f32 v71, -v71, v90, v88
	v_div_fmas_f32 v71, v71, v82, v90
	v_div_fixup_f32 v134, v71, v84, v134
	v_mul_f32_e32 v110, v110, v134
	v_cvt_pk_bf16_f32 v70, v70, v110
	v_perm_b32 v110, v70, v204, s98
	v_perm_b32 v70, v70, v204, s99
	global_store_dword v26, v110, s[70:71] offset:-2
	global_store_dword v26, v70, s[18:19] offset:-2
	v_add_u32_e32 v26, 0x80000, v26
	v_lshlrev_b32_e32 v136, 16, v136
	v_lshlrev_b32_e32 v137, 16, v137
	v_lshlrev_b32_e32 v135, 16, v135
	v_mul_f32_e32 v135, v16, v135
	v_fmac_f32_e32 v135, v14, v136
	v_fmac_f32_e32 v135, v17, v137
	v_add_f32_e32 v135, v12, v135
	v_fma_f32 v27, v42, v8, v64
	v_mul_f32_e32 v70, v27, v135
	v_lshlrev_b32_e32 v141, 16, v141
	v_mul_f32_e32 v84, 0xbfb8aa3b, v141
	v_exp_f32_e32 v84, v84
	s_nop 0
	v_add_f32_e32 v84, 1.0, v84
	v_div_scale_f32 v71, s[74:75], v84, v84, v141
	v_rcp_f32_e32 v82, v71
	s_nop 0
	v_fma_f32 v92, -v71, v82, 1.0
	v_fmac_f32_e32 v82, v92, v82
	v_div_scale_f32 v88, vcc, v141, v84, v141
	v_mul_f32_e32 v90, v88, v82
	v_fma_f32 v92, -v71, v90, v88
	v_fmac_f32_e32 v90, v92, v82
	v_fma_f32 v71, -v71, v90, v88
	v_div_fmas_f32 v71, v71, v82, v90
	v_div_fixup_f32 v141, v71, v84, v141
	v_mul_f32_e32 v70, v70, v141
	v_lshlrev_b32_e32 v139, 16, v139
	v_lshlrev_b32_e32 v140, 16, v140
	v_lshlrev_b32_e32 v138, 16, v138
	v_mul_f32_e32 v138, v16, v138
	v_fmac_f32_e32 v138, v14, v139
	v_fmac_f32_e32 v138, v17, v140
	v_add_f32_e32 v138, v12, v138
	v_fma_f32 v27, v44, v8, v65
	v_mul_f32_e32 v110, v27, v138
	v_lshlrev_b32_e32 v142, 16, v142
	v_mul_f32_e32 v84, 0xbfb8aa3b, v142
	v_exp_f32_e32 v84, v84
	s_nop 0
	v_add_f32_e32 v84, 1.0, v84
	v_div_scale_f32 v71, s[74:75], v84, v84, v142
	v_rcp_f32_e32 v82, v71
	s_nop 0
	v_fma_f32 v92, -v71, v82, 1.0
	v_fmac_f32_e32 v82, v92, v82
	v_div_scale_f32 v88, vcc, v142, v84, v142
	v_mul_f32_e32 v90, v88, v82
	v_fma_f32 v92, -v71, v90, v88
	v_fmac_f32_e32 v90, v92, v82
	v_fma_f32 v71, -v71, v90, v88
	v_div_fmas_f32 v71, v71, v82, v90
	v_div_fixup_f32 v142, v71, v84, v142
	v_mul_f32_e32 v110, v110, v142
	v_cvt_pk_bf16_f32 v70, v70, v110
	v_perm_b32 v110, v70, v205, s98
	v_perm_b32 v70, v70, v205, s99
	global_store_dword v26, v110, s[70:71] offset:-2
	global_store_dword v26, v70, s[18:19] offset:-2
	s_waitcnt vmcnt(48)
	v_add_u32_e32 v26, 0x80000, v26
	v_lshlrev_b32_e32 v163, 16, v163
	v_lshlrev_b32_e32 v164, 16, v164
	v_lshlrev_b32_e32 v143, 16, v143
	v_mul_f32_e32 v143, v16, v143
	v_fmac_f32_e32 v143, v14, v163
	v_fmac_f32_e32 v143, v17, v164
	v_add_f32_e32 v143, v12, v143
	v_fma_f32 v27, v47, v8, v22
	v_mul_f32_e32 v70, v27, v143
	v_lshlrev_b32_e32 v168, 16, v168
	v_mul_f32_e32 v84, 0xbfb8aa3b, v168
	v_exp_f32_e32 v84, v84
	s_nop 0
	v_add_f32_e32 v84, 1.0, v84
	v_div_scale_f32 v71, s[74:75], v84, v84, v168
	v_rcp_f32_e32 v82, v71
	s_nop 0
	v_fma_f32 v92, -v71, v82, 1.0
	v_fmac_f32_e32 v82, v92, v82
	v_div_scale_f32 v88, vcc, v168, v84, v168
	v_mul_f32_e32 v90, v88, v82
	v_fma_f32 v92, -v71, v90, v88
	v_fmac_f32_e32 v90, v92, v82
	v_fma_f32 v71, -v71, v90, v88
	v_div_fmas_f32 v71, v71, v82, v90
	v_div_fixup_f32 v168, v71, v84, v168
	v_mul_f32_e32 v70, v70, v168
	v_lshlrev_b32_e32 v166, 16, v166
	v_lshlrev_b32_e32 v167, 16, v167
	v_lshlrev_b32_e32 v165, 16, v165
	v_mul_f32_e32 v165, v16, v165
	v_fmac_f32_e32 v165, v14, v166
	v_fmac_f32_e32 v165, v17, v167
	v_add_f32_e32 v165, v12, v165
	v_fma_f32 v27, v49, v8, v23
	v_mul_f32_e32 v110, v27, v165
	v_lshlrev_b32_e32 v169, 16, v169
	v_mul_f32_e32 v84, 0xbfb8aa3b, v169
	v_exp_f32_e32 v84, v84
	s_nop 0
	v_add_f32_e32 v84, 1.0, v84
	v_div_scale_f32 v71, s[74:75], v84, v84, v169
	v_rcp_f32_e32 v82, v71
	s_nop 0
	v_fma_f32 v92, -v71, v82, 1.0
	v_fmac_f32_e32 v82, v92, v82
	v_div_scale_f32 v88, vcc, v169, v84, v169
	v_mul_f32_e32 v90, v88, v82
	v_fma_f32 v92, -v71, v90, v88
	v_fmac_f32_e32 v90, v92, v82
	v_fma_f32 v71, -v71, v90, v88
	v_div_fmas_f32 v71, v71, v82, v90
	v_div_fixup_f32 v169, v71, v84, v169
	v_mul_f32_e32 v110, v110, v169
	v_cvt_pk_bf16_f32 v70, v70, v110
	v_perm_b32 v110, v70, v206, s98
	v_perm_b32 v70, v70, v206, s99
	global_store_dword v26, v110, s[70:71] offset:-2
	global_store_dword v26, v70, s[18:19] offset:-2
	v_add_u32_e32 v26, 0x80000, v26
	v_lshlrev_b32_e32 v171, 16, v171
	v_lshlrev_b32_e32 v172, 16, v172
	v_lshlrev_b32_e32 v170, 16, v170
	v_mul_f32_e32 v170, v16, v170
	v_fmac_f32_e32 v170, v14, v171
	v_fmac_f32_e32 v170, v17, v172
	v_add_f32_e32 v170, v12, v170
	v_fma_f32 v27, v46, v8, v24
	v_mul_f32_e32 v70, v27, v170
	v_lshlrev_b32_e32 v176, 16, v176
	v_mul_f32_e32 v84, 0xbfb8aa3b, v176
	v_exp_f32_e32 v84, v84
	s_nop 0
	v_add_f32_e32 v84, 1.0, v84
	v_div_scale_f32 v71, s[74:75], v84, v84, v176
	v_rcp_f32_e32 v82, v71
	s_nop 0
	v_fma_f32 v92, -v71, v82, 1.0
	v_fmac_f32_e32 v82, v92, v82
	v_div_scale_f32 v88, vcc, v176, v84, v176
	v_mul_f32_e32 v90, v88, v82
	v_fma_f32 v92, -v71, v90, v88
	v_fmac_f32_e32 v90, v92, v82
	v_fma_f32 v71, -v71, v90, v88
	v_div_fmas_f32 v71, v71, v82, v90
	v_div_fixup_f32 v176, v71, v84, v176
	v_mul_f32_e32 v70, v70, v176
	v_lshlrev_b32_e32 v174, 16, v174
	v_lshlrev_b32_e32 v175, 16, v175
	v_lshlrev_b32_e32 v173, 16, v173
	v_mul_f32_e32 v173, v16, v173
	v_fmac_f32_e32 v173, v14, v174
	v_fmac_f32_e32 v173, v17, v175
	v_add_f32_e32 v173, v12, v173
	v_fma_f32 v27, v48, v8, v25
	v_mul_f32_e32 v110, v27, v173
	v_lshlrev_b32_e32 v177, 16, v177
	v_mul_f32_e32 v84, 0xbfb8aa3b, v177
	v_exp_f32_e32 v84, v84
	s_nop 0
	v_add_f32_e32 v84, 1.0, v84
	v_div_scale_f32 v71, s[74:75], v84, v84, v177
	v_rcp_f32_e32 v82, v71
	s_nop 0
	v_fma_f32 v92, -v71, v82, 1.0
	v_fmac_f32_e32 v82, v92, v82
	v_div_scale_f32 v88, vcc, v177, v84, v177
	v_mul_f32_e32 v90, v88, v82
	v_fma_f32 v92, -v71, v90, v88
	v_fmac_f32_e32 v90, v92, v82
	v_fma_f32 v71, -v71, v90, v88
	v_div_fmas_f32 v71, v71, v82, v90
	v_div_fixup_f32 v177, v71, v84, v177
	v_mul_f32_e32 v110, v110, v177
	v_cvt_pk_bf16_f32 v70, v70, v110
	v_perm_b32 v110, v70, v207, s98
	v_perm_b32 v70, v70, v207, s99
	global_store_dword v26, v110, s[70:71] offset:-2
	global_store_dword v26, v70, s[18:19] offset:-2
	v_add_u32_e32 v26, 0x80000, v26
	v_lshlrev_b32_e32 v179, 16, v179
	v_lshlrev_b32_e32 v180, 16, v180
	v_lshlrev_b32_e32 v178, 16, v178
	v_mul_f32_e32 v178, v16, v178
	v_fmac_f32_e32 v178, v14, v179
	v_fmac_f32_e32 v178, v17, v180
	v_add_f32_e32 v178, v12, v178
	v_fma_f32 v27, v51, v8, v18
	v_mul_f32_e32 v70, v27, v178
	v_lshlrev_b32_e32 v184, 16, v184
	v_mul_f32_e32 v84, 0xbfb8aa3b, v184
	v_exp_f32_e32 v84, v84
	s_nop 0
	v_add_f32_e32 v84, 1.0, v84
	v_div_scale_f32 v71, s[74:75], v84, v84, v184
	v_rcp_f32_e32 v82, v71
	s_nop 0
	v_fma_f32 v92, -v71, v82, 1.0
	v_fmac_f32_e32 v82, v92, v82
	v_div_scale_f32 v88, vcc, v184, v84, v184
	v_mul_f32_e32 v90, v88, v82
	v_fma_f32 v92, -v71, v90, v88
	v_fmac_f32_e32 v90, v92, v82
	v_fma_f32 v71, -v71, v90, v88
	v_div_fmas_f32 v71, v71, v82, v90
	v_div_fixup_f32 v184, v71, v84, v184
	v_mul_f32_e32 v70, v70, v184
	v_lshlrev_b32_e32 v182, 16, v182
	v_lshlrev_b32_e32 v183, 16, v183
	v_lshlrev_b32_e32 v181, 16, v181
	v_mul_f32_e32 v181, v16, v181
	v_fmac_f32_e32 v181, v14, v182
	v_fmac_f32_e32 v181, v17, v183
	v_add_f32_e32 v181, v12, v181
	v_fma_f32 v27, v53, v8, v19
	v_mul_f32_e32 v110, v27, v181
	v_lshlrev_b32_e32 v185, 16, v185
	v_mul_f32_e32 v84, 0xbfb8aa3b, v185
	v_exp_f32_e32 v84, v84
	s_nop 0
	v_add_f32_e32 v84, 1.0, v84
	v_div_scale_f32 v71, s[74:75], v84, v84, v185
	v_rcp_f32_e32 v82, v71
	s_nop 0
	v_fma_f32 v92, -v71, v82, 1.0
	v_fmac_f32_e32 v82, v92, v82
	v_div_scale_f32 v88, vcc, v185, v84, v185
	v_mul_f32_e32 v90, v88, v82
	v_fma_f32 v92, -v71, v90, v88
	v_fmac_f32_e32 v90, v92, v82
	v_fma_f32 v71, -v71, v90, v88
	v_div_fmas_f32 v71, v71, v82, v90
	v_div_fixup_f32 v185, v71, v84, v185
	v_mul_f32_e32 v110, v110, v185
	v_cvt_pk_bf16_f32 v70, v70, v110
	v_perm_b32 v110, v70, v208, s98
	v_perm_b32 v70, v70, v208, s99
	global_store_dword v26, v110, s[70:71] offset:-2
	global_store_dword v26, v70, s[18:19] offset:-2
	v_add_u32_e32 v26, 0x80000, v26
	v_lshlrev_b32_e32 v187, 16, v187
	v_lshlrev_b32_e32 v188, 16, v188
	v_lshlrev_b32_e32 v186, 16, v186
	v_mul_f32_e32 v186, v16, v186
	v_fmac_f32_e32 v186, v14, v187
	v_fmac_f32_e32 v186, v17, v188
	v_add_f32_e32 v186, v12, v186
	v_fma_f32 v27, v50, v8, v20
	v_mul_f32_e32 v70, v27, v186
	v_lshlrev_b32_e32 v192, 16, v192
	v_mul_f32_e32 v84, 0xbfb8aa3b, v192
	v_exp_f32_e32 v84, v84
	s_nop 0
	v_add_f32_e32 v84, 1.0, v84
	v_div_scale_f32 v71, s[74:75], v84, v84, v192
	v_rcp_f32_e32 v82, v71
	s_nop 0
	v_fma_f32 v92, -v71, v82, 1.0
	v_fmac_f32_e32 v82, v92, v82
	v_div_scale_f32 v88, vcc, v192, v84, v192
	v_mul_f32_e32 v90, v88, v82
	v_fma_f32 v92, -v71, v90, v88
	v_fmac_f32_e32 v90, v92, v82
	v_fma_f32 v71, -v71, v90, v88
	v_div_fmas_f32 v71, v71, v82, v90
	v_div_fixup_f32 v192, v71, v84, v192
	v_mul_f32_e32 v70, v70, v192
	v_lshlrev_b32_e32 v190, 16, v190
	v_lshlrev_b32_e32 v191, 16, v191
	v_lshlrev_b32_e32 v189, 16, v189
	v_mul_f32_e32 v189, v16, v189
	v_fmac_f32_e32 v189, v14, v190
	v_fmac_f32_e32 v189, v17, v191
	v_add_f32_e32 v189, v12, v189
	v_fma_f32 v27, v52, v8, v21
	v_mul_f32_e32 v110, v27, v189
	v_lshlrev_b32_e32 v193, 16, v193
	v_mul_f32_e32 v84, 0xbfb8aa3b, v193
	v_exp_f32_e32 v84, v84
	s_nop 0
	v_add_f32_e32 v84, 1.0, v84
	v_div_scale_f32 v71, s[74:75], v84, v84, v193
	v_rcp_f32_e32 v82, v71
	s_nop 0
	v_fma_f32 v92, -v71, v82, 1.0
	v_fmac_f32_e32 v82, v92, v82
	v_div_scale_f32 v88, vcc, v193, v84, v193
	v_mul_f32_e32 v90, v88, v82
	v_fma_f32 v92, -v71, v90, v88
	v_fmac_f32_e32 v90, v92, v82
	v_fma_f32 v71, -v71, v90, v88
	v_div_fmas_f32 v71, v71, v82, v90
	v_div_fixup_f32 v193, v71, v84, v193
	v_mul_f32_e32 v110, v110, v193
	v_cvt_pk_bf16_f32 v70, v70, v110
	v_perm_b32 v110, v70, v209, s98
	v_perm_b32 v70, v70, v209, s99
	global_store_dword v26, v110, s[70:71] offset:-2
	global_store_dword v26, v70, s[18:19] offset:-2
	s_waitcnt vmcnt(24)
	v_add_u32_e32 v26, 0x80000, v26
	v_lshlrev_b32_e32 v195, 16, v195
	v_lshlrev_b32_e32 v196, 16, v196
	v_lshlrev_b32_e32 v194, 16, v194
	v_mul_f32_e32 v194, v16, v194
	v_fmac_f32_e32 v194, v14, v195
	v_fmac_f32_e32 v194, v17, v196
	v_add_f32_e32 v194, v12, v194
	v_fma_f32 v27, v55, v8, v4
	v_mul_f32_e32 v70, v27, v194
	v_lshlrev_b32_e32 v223, 16, v223
	v_mul_f32_e32 v84, 0xbfb8aa3b, v223
	v_exp_f32_e32 v84, v84
	s_nop 0
	v_add_f32_e32 v84, 1.0, v84
	v_div_scale_f32 v71, s[74:75], v84, v84, v223
	v_rcp_f32_e32 v82, v71
	s_nop 0
	v_fma_f32 v92, -v71, v82, 1.0
	v_fmac_f32_e32 v82, v92, v82
	v_div_scale_f32 v88, vcc, v223, v84, v223
	v_mul_f32_e32 v90, v88, v82
	v_fma_f32 v92, -v71, v90, v88
	v_fmac_f32_e32 v90, v92, v82
	v_fma_f32 v71, -v71, v90, v88
	v_div_fmas_f32 v71, v71, v82, v90
	v_div_fixup_f32 v223, v71, v84, v223
	v_mul_f32_e32 v70, v70, v223
	v_lshlrev_b32_e32 v221, 16, v221
	v_lshlrev_b32_e32 v222, 16, v222
	v_lshlrev_b32_e32 v197, 16, v197
	v_mul_f32_e32 v197, v16, v197
	v_fmac_f32_e32 v197, v14, v221
	v_fmac_f32_e32 v197, v17, v222
	v_add_f32_e32 v197, v12, v197
	v_fma_f32 v27, v57, v8, v5
	v_mul_f32_e32 v110, v27, v197
	v_lshlrev_b32_e32 v224, 16, v224
	v_mul_f32_e32 v84, 0xbfb8aa3b, v224
	v_exp_f32_e32 v84, v84
	s_nop 0
	v_add_f32_e32 v84, 1.0, v84
	v_div_scale_f32 v71, s[74:75], v84, v84, v224
	v_rcp_f32_e32 v82, v71
	s_nop 0
	v_fma_f32 v92, -v71, v82, 1.0
	v_fmac_f32_e32 v82, v92, v82
	v_div_scale_f32 v88, vcc, v224, v84, v224
	v_mul_f32_e32 v90, v88, v82
	v_fma_f32 v92, -v71, v90, v88
	v_fmac_f32_e32 v90, v92, v82
	v_fma_f32 v71, -v71, v90, v88
	v_div_fmas_f32 v71, v71, v82, v90
	v_div_fixup_f32 v224, v71, v84, v224
	v_mul_f32_e32 v110, v110, v224
	v_cvt_pk_bf16_f32 v70, v70, v110
	v_perm_b32 v110, v70, v210, s98
	v_perm_b32 v70, v70, v210, s99
	global_store_dword v26, v110, s[70:71] offset:-2
	global_store_dword v26, v70, s[18:19] offset:-2
	v_add_u32_e32 v26, 0x80000, v26
	v_lshlrev_b32_e32 v226, 16, v226
	v_lshlrev_b32_e32 v227, 16, v227
	v_lshlrev_b32_e32 v225, 16, v225
	v_mul_f32_e32 v225, v16, v225
	v_fmac_f32_e32 v225, v14, v226
	v_fmac_f32_e32 v225, v17, v227
	v_add_f32_e32 v225, v12, v225
	v_fma_f32 v27, v54, v8, v6
	v_mul_f32_e32 v70, v27, v225
	v_lshlrev_b32_e32 v231, 16, v231
	v_mul_f32_e32 v84, 0xbfb8aa3b, v231
	v_exp_f32_e32 v84, v84
	s_nop 0
	v_add_f32_e32 v84, 1.0, v84
	v_div_scale_f32 v71, s[74:75], v84, v84, v231
	v_rcp_f32_e32 v82, v71
	s_nop 0
	v_fma_f32 v92, -v71, v82, 1.0
	v_fmac_f32_e32 v82, v92, v82
	v_div_scale_f32 v88, vcc, v231, v84, v231
	v_mul_f32_e32 v90, v88, v82
	v_fma_f32 v92, -v71, v90, v88
	v_fmac_f32_e32 v90, v92, v82
	v_fma_f32 v71, -v71, v90, v88
	v_div_fmas_f32 v71, v71, v82, v90
	v_div_fixup_f32 v231, v71, v84, v231
	v_mul_f32_e32 v70, v70, v231
	v_lshlrev_b32_e32 v229, 16, v229
	v_lshlrev_b32_e32 v230, 16, v230
	v_lshlrev_b32_e32 v228, 16, v228
	v_mul_f32_e32 v228, v16, v228
	v_fmac_f32_e32 v228, v14, v229
	v_fmac_f32_e32 v228, v17, v230
	v_add_f32_e32 v228, v12, v228
	v_fma_f32 v27, v56, v8, v7
	v_mul_f32_e32 v110, v27, v228
	v_lshlrev_b32_e32 v232, 16, v232
	v_mul_f32_e32 v84, 0xbfb8aa3b, v232
	v_exp_f32_e32 v84, v84
	s_nop 0
	v_add_f32_e32 v84, 1.0, v84
	v_div_scale_f32 v71, s[74:75], v84, v84, v232
	v_rcp_f32_e32 v82, v71
	s_nop 0
	v_fma_f32 v92, -v71, v82, 1.0
	v_fmac_f32_e32 v82, v92, v82
	v_div_scale_f32 v88, vcc, v232, v84, v232
	v_mul_f32_e32 v90, v88, v82
	v_fma_f32 v92, -v71, v90, v88
	v_fmac_f32_e32 v90, v92, v82
	v_fma_f32 v71, -v71, v90, v88
	v_div_fmas_f32 v71, v71, v82, v90
	v_div_fixup_f32 v232, v71, v84, v232
	v_mul_f32_e32 v110, v110, v232
	v_cvt_pk_bf16_f32 v70, v70, v110
	v_perm_b32 v110, v70, v211, s98
	v_perm_b32 v70, v70, v211, s99
	global_store_dword v26, v110, s[70:71] offset:-2
	global_store_dword v26, v70, s[18:19] offset:-2
	v_add_u32_e32 v26, 0x80000, v26
	v_lshlrev_b32_e32 v234, 16, v234
	v_lshlrev_b32_e32 v235, 16, v235
	v_lshlrev_b32_e32 v233, 16, v233
	v_mul_f32_e32 v233, v16, v233
	v_fmac_f32_e32 v233, v14, v234
	v_fmac_f32_e32 v233, v17, v235
	v_add_f32_e32 v233, v12, v233
	v_fma_f32 v27, v59, v8, v0
	v_mul_f32_e32 v70, v27, v233
	v_lshlrev_b32_e32 v239, 16, v239
	v_mul_f32_e32 v84, 0xbfb8aa3b, v239
	v_exp_f32_e32 v84, v84
	s_nop 0
	v_add_f32_e32 v84, 1.0, v84
	v_div_scale_f32 v71, s[74:75], v84, v84, v239
	v_rcp_f32_e32 v82, v71
	s_nop 0
	v_fma_f32 v92, -v71, v82, 1.0
	v_fmac_f32_e32 v82, v92, v82
	v_div_scale_f32 v88, vcc, v239, v84, v239
	v_mul_f32_e32 v90, v88, v82
	v_fma_f32 v92, -v71, v90, v88
	v_fmac_f32_e32 v90, v92, v82
	v_fma_f32 v71, -v71, v90, v88
	v_div_fmas_f32 v71, v71, v82, v90
	v_div_fixup_f32 v239, v71, v84, v239
	v_mul_f32_e32 v70, v70, v239
	v_lshlrev_b32_e32 v237, 16, v237
	v_lshlrev_b32_e32 v238, 16, v238
	v_lshlrev_b32_e32 v236, 16, v236
	v_mul_f32_e32 v236, v16, v236
	v_fmac_f32_e32 v236, v14, v237
	v_fmac_f32_e32 v236, v17, v238
	v_add_f32_e32 v236, v12, v236
	v_fma_f32 v27, v61, v8, v1
	v_mul_f32_e32 v110, v27, v236
	v_lshlrev_b32_e32 v240, 16, v240
	v_mul_f32_e32 v84, 0xbfb8aa3b, v240
	v_exp_f32_e32 v84, v84
	s_nop 0
	v_add_f32_e32 v84, 1.0, v84
	v_div_scale_f32 v71, s[74:75], v84, v84, v240
	v_rcp_f32_e32 v82, v71
	s_nop 0
	v_fma_f32 v92, -v71, v82, 1.0
	v_fmac_f32_e32 v82, v92, v82
	v_div_scale_f32 v88, vcc, v240, v84, v240
	v_mul_f32_e32 v90, v88, v82
	v_fma_f32 v92, -v71, v90, v88
	v_fmac_f32_e32 v90, v92, v82
	v_fma_f32 v71, -v71, v90, v88
	v_div_fmas_f32 v71, v71, v82, v90
	v_div_fixup_f32 v240, v71, v84, v240
	v_mul_f32_e32 v110, v110, v240
	v_cvt_pk_bf16_f32 v70, v70, v110
	v_perm_b32 v110, v70, v212, s98
	v_perm_b32 v70, v70, v212, s99
	global_store_dword v26, v110, s[70:71] offset:-2
	global_store_dword v26, v70, s[18:19] offset:-2
	v_add_u32_e32 v26, 0x80000, v26
	v_lshlrev_b32_e32 v242, 16, v242
	v_lshlrev_b32_e32 v243, 16, v243
	v_lshlrev_b32_e32 v241, 16, v241
	v_mul_f32_e32 v241, v16, v241
	v_mul_f32_e32 v243, v255, v243
	v_fmac_f32_e32 v241, v14, v242
	v_fmac_f32_e32 v241, v17, v243
	v_add_f32_e32 v241, v12, v241
	v_fma_f32 v27, v58, v8, v2
	v_mul_f32_e32 v70, v27, v241
	v_lshlrev_b32_e32 v247, 16, v247
	v_mul_f32_e32 v84, 0xbfb8aa3b, v247
	v_exp_f32_e32 v84, v84
	s_nop 0
	v_add_f32_e32 v84, 1.0, v84
	v_div_scale_f32 v71, s[74:75], v84, v84, v247
	v_rcp_f32_e32 v82, v71
	s_nop 0
	v_fma_f32 v92, -v71, v82, 1.0
	v_fmac_f32_e32 v82, v92, v82
	v_div_scale_f32 v88, vcc, v247, v84, v247
	v_mul_f32_e32 v90, v88, v82
	v_fma_f32 v92, -v71, v90, v88
	v_fmac_f32_e32 v90, v92, v82
	v_fma_f32 v71, -v71, v90, v88
	v_div_fmas_f32 v71, v71, v82, v90
	v_div_fixup_f32 v247, v71, v84, v247
	v_mul_f32_e32 v70, v70, v247
	v_lshlrev_b32_e32 v245, 16, v245
	v_lshlrev_b32_e32 v246, 16, v246
	v_lshlrev_b32_e32 v244, 16, v244
	v_mul_f32_e32 v244, v16, v244
	v_mul_f32_e32 v246, v255, v246
	v_fmac_f32_e32 v244, v14, v245
	v_fmac_f32_e32 v244, v17, v246
	v_add_f32_e32 v244, v12, v244
	v_fma_f32 v27, v60, v8, v3
	v_mul_f32_e32 v110, v27, v244
	v_lshlrev_b32_e32 v248, 16, v248
	v_mul_f32_e32 v84, 0xbfb8aa3b, v248
	v_exp_f32_e32 v84, v84
	s_nop 0
	v_add_f32_e32 v84, 1.0, v84
	v_div_scale_f32 v71, s[74:75], v84, v84, v248
	v_rcp_f32_e32 v82, v71
	s_nop 0
	v_fma_f32 v92, -v71, v82, 1.0
	v_fmac_f32_e32 v82, v92, v82
	v_div_scale_f32 v88, vcc, v248, v84, v248
	v_mul_f32_e32 v90, v88, v82
	v_fma_f32 v92, -v71, v90, v88
	v_fmac_f32_e32 v90, v92, v82
	v_fma_f32 v71, -v71, v90, v88
	v_div_fmas_f32 v71, v71, v82, v90
	v_div_fixup_f32 v248, v71, v84, v248
	v_mul_f32_e32 v110, v110, v248
	v_cvt_pk_bf16_f32 v70, v70, v110
	v_perm_b32 v110, v70, v213, s98
	v_perm_b32 v70, v70, v213, s99
	global_store_dword v26, v110, s[70:71] offset:-2
	global_store_dword v26, v70, s[18:19] offset:-2

.LBB0_912:
	s_andn2_b64 vcc, exec, s[74:75]
	s_cbranch_vccnz .LBB0_909
	v_lshlrev_b32_e32 v109, 1, v10
	v_add_u32_e32 v254, 0x1e00, v10
	v_add_u32_e32 v253, 0x1000, v109
	v_cmp_gt_i32_e32 vcc, 0x1fff, v254
	v_add_u32_e32 v251, 0x2000, v109
	v_add_u32_e32 v250, 0x3000, v109
	v_min_i32_e32 v254, 0x1ffe, v254
	v_cndmask_b32_e64 v255, 0, 1.0, vcc
	v_lshlrev_b32_e32 v254, 1, v254
	global_load_ushort v9, v109, s[36:37] offset:1022
	global_load_ushort v11, v109, s[36:37] offset:1024
	global_load_ushort v13, v109, s[36:37] offset:1026
	global_load_ushort v15, v109, s[72:73] offset:1022
	global_load_ushort v81, v109, s[72:73] offset:1024
	global_load_ushort v83, v109, s[72:73] offset:1026
	global_load_ushort v85, v109, s[36:37] offset:2046
	global_load_ushort v87, v109, s[36:37] offset:2048
	global_load_ushort v89, v109, s[36:37] offset:2050
	global_load_ushort v91, v109, s[72:73] offset:2046
	global_load_ushort v93, v109, s[72:73] offset:2048
	global_load_ushort v94, v109, s[72:73] offset:2050
	global_load_ushort v95, v109, s[36:37] offset:3070
	global_load_ushort v96, v109, s[36:37] offset:3072
	global_load_ushort v97, v109, s[36:37] offset:3074
	global_load_ushort v98, v109, s[72:73] offset:3070
	global_load_ushort v99, v109, s[72:73] offset:3072
	global_load_ushort v100, v109, s[72:73] offset:3074
	global_load_ushort v101, v253, s[36:37] offset:-2
	global_load_ushort v102, v253, s[36:37]
	global_load_ushort v103, v253, s[36:37] offset:2
	global_load_ushort v104, v253, s[72:73] offset:-2
	global_load_ushort v105, v253, s[72:73]
	global_load_ushort v106, v253, s[72:73] offset:2
	global_load_ushort v107, v253, s[36:37] offset:1022
	global_load_ushort v108, v253, s[36:37] offset:1024
	global_load_ushort v111, v253, s[36:37] offset:1026
	global_load_ushort v112, v253, s[72:73] offset:1022
	global_load_ushort v113, v253, s[72:73] offset:1024
	global_load_ushort v114, v253, s[72:73] offset:1026
	global_load_ushort v115, v253, s[36:37] offset:2046
	global_load_ushort v116, v253, s[36:37] offset:2048
	global_load_ushort v117, v253, s[36:37] offset:2050
	global_load_ushort v118, v253, s[72:73] offset:2046
	global_load_ushort v119, v253, s[72:73] offset:2048
	global_load_ushort v120, v253, s[72:73] offset:2050
	global_load_ushort v121, v253, s[36:37] offset:3070
	global_load_ushort v122, v253, s[36:37] offset:3072
	global_load_ushort v123, v253, s[36:37] offset:3074
	global_load_ushort v124, v253, s[72:73] offset:3070
	global_load_ushort v125, v253, s[72:73] offset:3072
	global_load_ushort v126, v253, s[72:73] offset:3074
	global_load_ushort v127, v251, s[36:37] offset:-2
	global_load_ushort v128, v251, s[36:37]
	global_load_ushort v129, v251, s[36:37] offset:2
	global_load_ushort v130, v251, s[72:73] offset:-2
	global_load_ushort v131, v251, s[72:73]
	global_load_ushort v132, v251, s[72:73] offset:2
	global_load_ushort v133, v251, s[36:37] offset:1022
	global_load_ushort v134, v251, s[36:37] offset:1024
	global_load_ushort v135, v251, s[36:37] offset:1026
	global_load_ushort v136, v251, s[72:73] offset:1022
	global_load_ushort v137, v251, s[72:73] offset:1024
	global_load_ushort v138, v251, s[72:73] offset:1026
	global_load_ushort v139, v251, s[36:37] offset:2046
	global_load_ushort v140, v251, s[36:37] offset:2048
	global_load_ushort v141, v251, s[36:37] offset:2050
	global_load_ushort v142, v251, s[72:73] offset:2046
	global_load_ushort v143, v251, s[72:73] offset:2048
	global_load_ushort v163, v251, s[72:73] offset:2050
	global_load_ushort v164, v251, s[36:37] offset:3070
	global_load_ushort v165, v251, s[36:37] offset:3072
	global_load_ushort v166, v251, s[36:37] offset:3074
	global_load_ushort v167, v251, s[72:73] offset:3070
	global_load_ushort v168, v251, s[72:73] offset:3072
	global_load_ushort v169, v251, s[72:73] offset:3074
	global_load_ushort v170, v250, s[36:37] offset:-2
	global_load_ushort v171, v250, s[36:37]
	global_load_ushort v172, v250, s[36:37] offset:2
	global_load_ushort v173, v250, s[72:73] offset:-2
	global_load_ushort v174, v250, s[72:73]
	global_load_ushort v175, v250, s[72:73] offset:2
	global_load_ushort v176, v250, s[36:37] offset:1022
	global_load_ushort v177, v250, s[36:37] offset:1024
	global_load_ushort v178, v250, s[36:37] offset:1026
	global_load_ushort v179, v250, s[72:73] offset:1022
	global_load_ushort v180, v250, s[72:73] offset:1024
	global_load_ushort v181, v250, s[72:73] offset:1026
	global_load_ushort v182, v250, s[36:37] offset:2046
	global_load_ushort v183, v250, s[36:37] offset:2048
	global_load_ushort v184, v250, s[36:37] offset:2050
	global_load_ushort v185, v250, s[72:73] offset:2046
	global_load_ushort v186, v250, s[72:73] offset:2048
	global_load_ushort v187, v250, s[72:73] offset:2050
	global_load_ushort v188, v250, s[36:37] offset:3070
	global_load_ushort v189, v250, s[36:37] offset:3072
	global_load_ushort v190, v254, s[36:37] offset:2
	global_load_ushort v191, v250, s[72:73] offset:3070
	global_load_ushort v192, v250, s[72:73] offset:3072
	global_load_ushort v193, v254, s[72:73] offset:2
	s_waitcnt vmcnt(63)
	v_fma_f32 v27, v32, v8, v78
	v_mul_f32_e32 v32, v80, v27
	v_fma_f32 v27, v34, v8, v79
	v_mul_f32_e32 v34, v86, v27
	v_lshlrev_b32_e32 v11, 16, v11
	v_lshlrev_b32_e32 v13, 16, v13
	v_lshlrev_b32_e32 v9, 16, v9
	v_mul_f32_e32 v9, v16, v9
	v_fmac_f32_e32 v9, v14, v11
	v_fmac_f32_e32 v9, v17, v13
	v_add_f32_e32 v9, v12, v9
	v_fma_f32 v27, v33, v8, v76
	v_mul_f32_e32 v33, v9, v27
	v_lshlrev_b32_e32 v81, 16, v81
	v_lshlrev_b32_e32 v83, 16, v83
	v_lshlrev_b32_e32 v15, 16, v15
	v_mul_f32_e32 v15, v16, v15
	v_fmac_f32_e32 v15, v14, v81
	v_fmac_f32_e32 v15, v17, v83
	v_add_f32_e32 v15, v12, v15
	v_fma_f32 v27, v35, v8, v77
	v_mul_f32_e32 v35, v15, v27
	v_lshlrev_b32_e32 v87, 16, v87
	v_lshlrev_b32_e32 v89, 16, v89
	v_lshlrev_b32_e32 v85, 16, v85
	v_mul_f32_e32 v85, v16, v85
	v_fmac_f32_e32 v85, v14, v87
	v_fmac_f32_e32 v85, v17, v89
	v_add_f32_e32 v85, v12, v85
	v_fma_f32 v27, v37, v8, v72
	v_mul_f32_e32 v37, v85, v27
	v_lshlrev_b32_e32 v93, 16, v93
	v_lshlrev_b32_e32 v94, 16, v94
	v_lshlrev_b32_e32 v91, 16, v91
	v_mul_f32_e32 v91, v16, v91
	v_fmac_f32_e32 v91, v14, v93
	v_fmac_f32_e32 v91, v17, v94
	v_add_f32_e32 v91, v12, v91
	v_fma_f32 v27, v31, v8, v73
	v_mul_f32_e32 v31, v91, v27
	v_lshlrev_b32_e32 v96, 16, v96
	v_lshlrev_b32_e32 v97, 16, v97
	v_lshlrev_b32_e32 v95, 16, v95
	v_mul_f32_e32 v95, v16, v95
	v_fmac_f32_e32 v95, v14, v96
	v_fmac_f32_e32 v95, v17, v97
	v_add_f32_e32 v95, v12, v95
	v_fma_f32 v27, v36, v8, v74
	v_mul_f32_e32 v36, v95, v27
	v_lshlrev_b32_e32 v99, 16, v99
	v_lshlrev_b32_e32 v100, 16, v100
	v_lshlrev_b32_e32 v98, 16, v98
	v_mul_f32_e32 v98, v16, v98
	v_fmac_f32_e32 v98, v14, v99
	v_fmac_f32_e32 v98, v17, v100
	v_add_f32_e32 v98, v12, v98
	v_fma_f32 v27, v30, v8, v75
	v_mul_f32_e32 v30, v98, v27
	s_waitcnt vmcnt(48)
	v_lshlrev_b32_e32 v102, 16, v102
	v_lshlrev_b32_e32 v103, 16, v103
	v_lshlrev_b32_e32 v101, 16, v101
	v_mul_f32_e32 v101, v16, v101
	v_fmac_f32_e32 v101, v14, v102
	v_fmac_f32_e32 v101, v17, v103
	v_add_f32_e32 v101, v12, v101
	v_fma_f32 v27, v39, v8, v66
	v_mul_f32_e32 v39, v101, v27
	v_lshlrev_b32_e32 v105, 16, v105
	v_lshlrev_b32_e32 v106, 16, v106
	v_lshlrev_b32_e32 v104, 16, v104
	v_mul_f32_e32 v104, v16, v104
	v_fmac_f32_e32 v104, v14, v105
	v_fmac_f32_e32 v104, v17, v106
	v_add_f32_e32 v104, v12, v104
	v_fma_f32 v27, v41, v8, v67
	v_mul_f32_e32 v41, v104, v27
	v_lshlrev_b32_e32 v108, 16, v108
	v_lshlrev_b32_e32 v111, 16, v111
	v_lshlrev_b32_e32 v107, 16, v107
	v_mul_f32_e32 v107, v16, v107
	v_fmac_f32_e32 v107, v14, v108
	v_fmac_f32_e32 v107, v17, v111
	v_add_f32_e32 v107, v12, v107
	v_fma_f32 v27, v38, v8, v68
	v_mul_f32_e32 v38, v107, v27
	v_lshlrev_b32_e32 v113, 16, v113
	v_lshlrev_b32_e32 v114, 16, v114
	v_lshlrev_b32_e32 v112, 16, v112
	v_mul_f32_e32 v112, v16, v112
	v_fmac_f32_e32 v112, v14, v113
	v_fmac_f32_e32 v112, v17, v114
	v_add_f32_e32 v112, v12, v112
	v_fma_f32 v27, v40, v8, v69
	v_mul_f32_e32 v40, v112, v27
	v_lshlrev_b32_e32 v116, 16, v116
	v_lshlrev_b32_e32 v117, 16, v117
	v_lshlrev_b32_e32 v115, 16, v115
	v_mul_f32_e32 v115, v16, v115
	v_fmac_f32_e32 v115, v14, v116
	v_fmac_f32_e32 v115, v17, v117
	v_add_f32_e32 v115, v12, v115
	v_fma_f32 v27, v43, v8, v62
	v_mul_f32_e32 v43, v115, v27
	v_lshlrev_b32_e32 v119, 16, v119
	v_lshlrev_b32_e32 v120, 16, v120
	v_lshlrev_b32_e32 v118, 16, v118
	v_mul_f32_e32 v118, v16, v118
	v_fmac_f32_e32 v118, v14, v119
	v_fmac_f32_e32 v118, v17, v120
	v_add_f32_e32 v118, v12, v118
	v_fma_f32 v27, v45, v8, v63
	v_mul_f32_e32 v45, v118, v27
	v_lshlrev_b32_e32 v122, 16, v122
	v_lshlrev_b32_e32 v123, 16, v123
	v_lshlrev_b32_e32 v121, 16, v121
	v_mul_f32_e32 v121, v16, v121
	v_fmac_f32_e32 v121, v14, v122
	v_fmac_f32_e32 v121, v17, v123
	v_add_f32_e32 v121, v12, v121
	v_fma_f32 v27, v42, v8, v64
	v_mul_f32_e32 v42, v121, v27
	v_lshlrev_b32_e32 v125, 16, v125
	v_lshlrev_b32_e32 v126, 16, v126
	v_lshlrev_b32_e32 v124, 16, v124
	v_mul_f32_e32 v124, v16, v124
	v_fmac_f32_e32 v124, v14, v125
	v_fmac_f32_e32 v124, v17, v126
	v_add_f32_e32 v124, v12, v124
	v_fma_f32 v27, v44, v8, v65
	v_mul_f32_e32 v44, v124, v27
	s_waitcnt vmcnt(24)
	v_lshlrev_b32_e32 v128, 16, v128
	v_lshlrev_b32_e32 v129, 16, v129
	v_lshlrev_b32_e32 v127, 16, v127
	v_mul_f32_e32 v127, v16, v127
	v_fmac_f32_e32 v127, v14, v128
	v_fmac_f32_e32 v127, v17, v129
	v_add_f32_e32 v127, v12, v127
	v_fma_f32 v27, v47, v8, v22
	v_mul_f32_e32 v47, v127, v27
	v_lshlrev_b32_e32 v131, 16, v131
	v_lshlrev_b32_e32 v132, 16, v132
	v_lshlrev_b32_e32 v130, 16, v130
	v_mul_f32_e32 v130, v16, v130
	v_fmac_f32_e32 v130, v14, v131
	v_fmac_f32_e32 v130, v17, v132
	v_add_f32_e32 v130, v12, v130
	v_fma_f32 v27, v49, v8, v23
	v_mul_f32_e32 v49, v130, v27
	v_lshlrev_b32_e32 v134, 16, v134
	v_lshlrev_b32_e32 v135, 16, v135
	v_lshlrev_b32_e32 v133, 16, v133
	v_mul_f32_e32 v133, v16, v133
	v_fmac_f32_e32 v133, v14, v134
	v_fmac_f32_e32 v133, v17, v135
	v_add_f32_e32 v133, v12, v133
	v_fma_f32 v27, v46, v8, v24
	v_mul_f32_e32 v46, v133, v27
	v_lshlrev_b32_e32 v137, 16, v137
	v_lshlrev_b32_e32 v138, 16, v138
	v_lshlrev_b32_e32 v136, 16, v136
	v_mul_f32_e32 v136, v16, v136
	v_fmac_f32_e32 v136, v14, v137
	v_fmac_f32_e32 v136, v17, v138
	v_add_f32_e32 v136, v12, v136
	v_fma_f32 v27, v48, v8, v25
	v_mul_f32_e32 v48, v136, v27
	v_lshlrev_b32_e32 v140, 16, v140
	v_lshlrev_b32_e32 v141, 16, v141
	v_lshlrev_b32_e32 v139, 16, v139
	v_mul_f32_e32 v139, v16, v139
	v_fmac_f32_e32 v139, v14, v140
	v_fmac_f32_e32 v139, v17, v141
	v_add_f32_e32 v139, v12, v139
	v_fma_f32 v27, v51, v8, v18
	v_mul_f32_e32 v51, v139, v27
	v_lshlrev_b32_e32 v143, 16, v143
	v_lshlrev_b32_e32 v163, 16, v163
	v_lshlrev_b32_e32 v142, 16, v142
	v_mul_f32_e32 v142, v16, v142
	v_fmac_f32_e32 v142, v14, v143
	v_fmac_f32_e32 v142, v17, v163
	v_add_f32_e32 v142, v12, v142
	v_fma_f32 v27, v53, v8, v19
	v_mul_f32_e32 v53, v142, v27
	v_lshlrev_b32_e32 v165, 16, v165
	v_lshlrev_b32_e32 v166, 16, v166
	v_lshlrev_b32_e32 v164, 16, v164
	v_mul_f32_e32 v164, v16, v164
	v_fmac_f32_e32 v164, v14, v165
	v_fmac_f32_e32 v164, v17, v166
	v_add_f32_e32 v164, v12, v164
	v_fma_f32 v27, v50, v8, v20
	v_mul_f32_e32 v50, v164, v27
	v_lshlrev_b32_e32 v168, 16, v168
	v_lshlrev_b32_e32 v169, 16, v169
	v_lshlrev_b32_e32 v167, 16, v167
	v_mul_f32_e32 v167, v16, v167
	v_fmac_f32_e32 v167, v14, v168
	v_fmac_f32_e32 v167, v17, v169
	v_add_f32_e32 v167, v12, v167
	v_fma_f32 v27, v52, v8, v21
	v_mul_f32_e32 v52, v167, v27
	s_waitcnt vmcnt(0)
	v_lshlrev_b32_e32 v171, 16, v171
	v_lshlrev_b32_e32 v172, 16, v172
	v_lshlrev_b32_e32 v170, 16, v170
	v_mul_f32_e32 v170, v16, v170
	v_fmac_f32_e32 v170, v14, v171
	v_fmac_f32_e32 v170, v17, v172
	v_add_f32_e32 v170, v12, v170
	v_fma_f32 v27, v55, v8, v4
	v_mul_f32_e32 v55, v170, v27
	v_lshlrev_b32_e32 v174, 16, v174
	v_lshlrev_b32_e32 v175, 16, v175
	v_lshlrev_b32_e32 v173, 16, v173
	v_mul_f32_e32 v173, v16, v173
	v_fmac_f32_e32 v173, v14, v174
	v_fmac_f32_e32 v173, v17, v175
	v_add_f32_e32 v173, v12, v173
	v_fma_f32 v27, v57, v8, v5
	v_mul_f32_e32 v57, v173, v27
	v_lshlrev_b32_e32 v177, 16, v177
	v_lshlrev_b32_e32 v178, 16, v178
	v_lshlrev_b32_e32 v176, 16, v176
	v_mul_f32_e32 v176, v16, v176
	v_fmac_f32_e32 v176, v14, v177
	v_fmac_f32_e32 v176, v17, v178
	v_add_f32_e32 v176, v12, v176
	v_fma_f32 v27, v54, v8, v6
	v_mul_f32_e32 v54, v176, v27
	v_lshlrev_b32_e32 v180, 16, v180
	v_lshlrev_b32_e32 v181, 16, v181
	v_lshlrev_b32_e32 v179, 16, v179
	v_mul_f32_e32 v179, v16, v179
	v_fmac_f32_e32 v179, v14, v180
	v_fmac_f32_e32 v179, v17, v181
	v_add_f32_e32 v179, v12, v179
	v_fma_f32 v27, v56, v8, v7
	v_mul_f32_e32 v56, v179, v27
	v_lshlrev_b32_e32 v183, 16, v183
	v_lshlrev_b32_e32 v184, 16, v184
	v_lshlrev_b32_e32 v182, 16, v182
	v_mul_f32_e32 v182, v16, v182
	v_fmac_f32_e32 v182, v14, v183
	v_fmac_f32_e32 v182, v17, v184
	v_add_f32_e32 v182, v12, v182
	v_fma_f32 v27, v59, v8, v0
	v_mul_f32_e32 v59, v182, v27
	v_lshlrev_b32_e32 v186, 16, v186
	v_lshlrev_b32_e32 v187, 16, v187
	v_lshlrev_b32_e32 v185, 16, v185
	v_mul_f32_e32 v185, v16, v185
	v_fmac_f32_e32 v185, v14, v186
	v_fmac_f32_e32 v185, v17, v187
	v_add_f32_e32 v185, v12, v185
	v_fma_f32 v27, v61, v8, v1
	v_mul_f32_e32 v61, v185, v27
	v_lshlrev_b32_e32 v189, 16, v189
	v_lshlrev_b32_e32 v190, 16, v190
	v_lshlrev_b32_e32 v188, 16, v188
	v_mul_f32_e32 v188, v16, v188
	v_mul_f32_e32 v190, v255, v190
	v_fmac_f32_e32 v188, v14, v189
	v_fmac_f32_e32 v188, v17, v190
	v_add_f32_e32 v188, v12, v188
	v_fma_f32 v27, v58, v8, v2
	v_mul_f32_e32 v58, v188, v27
	v_lshlrev_b32_e32 v192, 16, v192
	v_lshlrev_b32_e32 v193, 16, v193
	v_lshlrev_b32_e32 v191, 16, v191
	v_mul_f32_e32 v191, v16, v191
	v_mul_f32_e32 v193, v255, v193
	v_fmac_f32_e32 v191, v14, v192
	v_fmac_f32_e32 v191, v17, v193
	v_add_f32_e32 v191, v12, v191
	v_fma_f32 v27, v60, v8, v3
	v_mul_f32_e32 v60, v191, v27
	s_branch .LBB0_909
